# 948 more f32->bf16 bit-trick packs (bfe/add3/lshr/and_or, 6 VALU) replaced by v_cvt_pk_bf16_f32 with s_nop fill (same RNE rounding)
# speedup vs baseline: 1.0053x; 1.0001x over previous
; #define LAS __attribute__((address_space(3)))
; #define LDS_WAIT() asm volatile("s_waitcnt lgkmcnt(0)" ::: "memory")
; __device__ __forceinline__ unsigned pk2(float lo, float hi) { return f2bf(lo) | (f2bf(hi) << 16); }
;     ...
;         const int kb = it / nblk, nb = it % nblk, k0 = 64 * kb, n0 = 64 * nb, nq = (lane & 15) * 4, kr = lane >> 4; const bool ok = (n0 + nq) < N;
;         f32x4 v[16];
; #pragma unroll
;         for (int i = 0; i < 16; ++i) v[i] = ok ? __builtin_nontemporal_load((const f32x4*)(W + (size_t)(k0 + 4 * i + kr) * N + n0 + nq)) : (f32x4){0.f, 0.f, 0.f, 0.f};
;         if (gain) {
; #pragma unroll
;             for (int i = 0; i < 16; ++i) v[i] *= gain[k0 + 4 * i + kr]; }
; #pragma unroll
;         for (int i = 0; i < 16; ++i) { LAS float* d = scr + (4 * i + kr) * 65 + nq; d[0] = v[i].x; d[1] = v[i].y; d[2] = v[i].z; d[3] = v[i].w; }
;         LDS_WAIT(); asm volatile("" ::: "memory");
;         const int c8 = lane & 7; int d0 = n0;
;         if (ffnmap) { const int bj = n0 >= FFH ? 1 : 0, chn = n0 - FFH * bj; d0 = 256 * (chn >> 7) + 128 * bj + (chn & 127); }
; #pragma unroll
;         for (int j = 0; j < 8; ++j) { const int n = (lane >> 3) + 8 * j; const LAS float* sp = scr + (8 * c8) * 65 + n;
;             v4u o; o.x = pk2(sp[0 * 65], sp[1 * 65]); o.y = pk2(sp[2 * 65], sp[3 * 65]); o.z = pk2(sp[4 * 65], sp[5 * 65]); o.w = pk2(sp[6 * 65], sp[7 * 65]);
;             *(v4u*)(WT + (size_t)(d0 + n) * K + k0 + 8 * c8) = o; }
.LBB0_10:
	v_add_u32_e32 v3, 0x410, v81
	s_waitcnt vmcnt(0)
	ds_write2_b32 v81, v6, v7 offset1:1
	ds_write2_b32 v81, v8, v9 offset0:2 offset1:3
	ds_write2_b32 v3, v10, v11 offset1:1
	v_add_u32_e32 v3, 0x418, v81
	ds_write2_b32 v3, v12, v13 offset1:1
	v_add_u32_e32 v3, 0x820, v81
	ds_write2_b32 v3, v14, v15 offset1:1
	v_add_u32_e32 v3, 0x828, v81
	ds_write2_b32 v3, v16, v17 offset1:1
	v_add_u32_e32 v3, 0xc30, v81
	ds_write2_b32 v3, v18, v19 offset1:1
	v_add_u32_e32 v3, 0xc38, v81
	ds_write2_b32 v3, v20, v21 offset1:1
	v_add_u32_e32 v3, 0x1040, v81
	ds_write2_b32 v3, v22, v23 offset1:1
	v_add_u32_e32 v3, 0x1048, v81
	ds_write2_b32 v3, v24, v25 offset1:1
	v_add_u32_e32 v3, 0x1450, v81
	ds_write2_b32 v3, v26, v27 offset1:1
	v_add_u32_e32 v3, 0x1458, v81
	ds_write2_b32 v3, v28, v29 offset1:1
	v_add_u32_e32 v3, 0x1860, v81
	ds_write2_b32 v3, v30, v31 offset1:1
	v_add_u32_e32 v3, 0x1868, v81
	ds_write2_b32 v3, v32, v33 offset1:1
	v_add_u32_e32 v3, 0x1c70, v81
	ds_write2_b32 v3, v34, v35 offset1:1
	v_add_u32_e32 v3, 0x1c78, v81
	ds_write2_b32 v3, v36, v37 offset1:1
	v_add_u32_e32 v3, 0x2080, v81
	ds_write2_b32 v3, v38, v39 offset1:1
	v_add_u32_e32 v3, 0x2088, v81
	ds_write2_b32 v3, v40, v41 offset1:1
	v_add_u32_e32 v3, 0x2490, v81
	ds_write2_b32 v3, v42, v43 offset1:1
	v_add_u32_e32 v3, 0x2498, v81
	ds_write2_b32 v3, v44, v45 offset1:1
	v_add_u32_e32 v3, 0x28a0, v81
	ds_write2_b32 v3, v46, v47 offset1:1
	v_add_u32_e32 v3, 0x28a8, v81
	ds_write2_b32 v3, v48, v49 offset1:1
	v_add_u32_e32 v3, 0x2cb0, v81
	ds_write2_b32 v3, v50, v51 offset1:1
	v_add_u32_e32 v3, 0x2cb8, v81
	ds_write2_b32 v3, v52, v53 offset1:1
	v_add_u32_e32 v3, 0x30c0, v81
	ds_write2_b32 v3, v54, v55 offset1:1
	v_add_u32_e32 v3, 0x30c8, v81
	ds_write2_b32 v3, v56, v57 offset1:1
	v_add_u32_e32 v3, 0x34d0, v81
	ds_write2_b32 v3, v58, v59 offset1:1
	v_add_u32_e32 v3, 0x34d8, v81
	ds_write2_b32 v3, v60, v61 offset1:1
	v_add_u32_e32 v3, 0x38e0, v81
	ds_write2_b32 v3, v62, v63 offset1:1
	v_add_u32_e32 v3, 0x38e8, v81
	ds_write2_b32 v3, v64, v65 offset1:1
	v_add_u32_e32 v3, 0x3cf0, v81
	ds_write2_b32 v3, v66, v67 offset1:1
	v_add_u32_e32 v3, 0x3cf8, v81
	ds_write2_b32 v3, v68, v69 offset1:1
	s_waitcnt lgkmcnt(0)
	ds_read2_b32 v[12:13], v80 offset1:8
	ds_read2_b32 v[14:15], v80 offset0:65 offset1:73
	ds_read2_b32 v[16:17], v80 offset0:130 offset1:138
	ds_read2_b32 v[18:19], v80 offset0:195 offset1:203
	v_add_u32_e32 v30, 0x400, v80
	s_waitcnt lgkmcnt(3)
	s_nop 1
	s_waitcnt lgkmcnt(2)
	s_nop 0
	ds_read2_b32 v[20:21], v30 offset0:4 offset1:12
	s_nop 1
	ds_read2_b32 v[22:23], v30 offset0:69 offset1:77
	v_cvt_pk_bf16_f32 v8, v12, v14
	s_waitcnt lgkmcnt(3)
	s_nop 1
	s_waitcnt lgkmcnt(2)
	s_nop 0
	ds_read2_b32 v[24:25], v30 offset0:134 offset1:142
	s_nop 1
	ds_read2_b32 v[26:27], v30 offset0:199 offset1:207
	v_cvt_pk_bf16_f32 v9, v16, v18
	s_waitcnt lgkmcnt(3)
	s_nop 1
	s_waitcnt lgkmcnt(2)
	s_nop 2
	v_cvt_pk_bf16_f32 v10, v20, v22
	s_waitcnt lgkmcnt(1)
	s_nop 1
	s_waitcnt lgkmcnt(0)
	s_nop 2
	v_cvt_pk_bf16_f32 v11, v24, v26
	v_add_u32_e32 v6, s6, v79
	s_ashr_i32 s9, s8, 31
	v_ashrrev_i32_e32 v7, 31, v6
	v_bfe_u32 v3, v13, 16, 1
	v_lshl_add_u64 v[4:5], s[8:9], 1, v[72:73]
	v_lshlrev_b64 v[28:29], 12, v[6:7]
	v_add3_u32 v3, v13, v3, s13
	v_bfe_u32 v7, v15, 16, 1
	v_lshl_add_u64 v[28:29], v[4:5], 0, v[28:29]
	v_lshrrev_b32_e32 v3, 16, v3
	v_add3_u32 v7, v15, v7, s13
	global_store_dwordx4 v[28:29], v[8:11], off
	v_add_u32_e32 v12, 8, v6
	v_ashrrev_i32_e32 v13, 31, v12
	v_and_or_b32 v8, v7, s14, v3
	s_nop 4
	v_cvt_pk_bf16_f32 v9, v17, v19
	s_nop 4
	v_cvt_pk_bf16_f32 v10, v21, v23
	s_nop 4
	v_lshlrev_b64 v[12:13], 12, v[12:13]
	v_cvt_pk_bf16_f32 v11, v25, v27
	ds_read2_b32 v[14:15], v80 offset0:16 offset1:24
	v_lshl_add_u64 v[12:13], v[4:5], 0, v[12:13]
	global_store_dwordx4 v[12:13], v[8:11], off
	ds_read2_b32 v[12:13], v80 offset0:81 offset1:89
	ds_read2_b32 v[16:17], v80 offset0:146 offset1:154
	ds_read2_b32 v[18:19], v80 offset0:211 offset1:219
	s_waitcnt lgkmcnt(3)
	s_nop 1
	s_waitcnt lgkmcnt(2)
	s_nop 0
	ds_read2_b32 v[20:21], v30 offset0:20 offset1:28
	s_nop 1
	ds_read2_b32 v[22:23], v30 offset0:85 offset1:93
	v_cvt_pk_bf16_f32 v8, v14, v12
	s_waitcnt lgkmcnt(3)
; #define LAS __attribute__((address_space(3)))
; #define LDS_WAIT() asm volatile("s_waitcnt lgkmcnt(0)" ::: "memory")
; __device__ __forceinline__ unsigned pk2(float lo, float hi) { return f2bf(lo) | (f2bf(hi) << 16); }
;     ...
;         for (int i = 0; i < 16; ++i) { LAS float* d = scr + (4 * i + kr) * 65 + nq; d[0] = v[i].x; d[1] = v[i].y; d[2] = v[i].z; d[3] = v[i].w; }
;         LDS_WAIT(); asm volatile("" ::: "memory");
;         const int c8 = lane & 7; int d0 = n0;
;         if (ffnmap) { const int bj = n0 >= FFH ? 1 : 0, chn = n0 - FFH * bj; d0 = 256 * (chn >> 7) + 128 * bj + (chn & 127); }
; #pragma unroll
;         for (int j = 0; j < 8; ++j) { const int n = (lane >> 3) + 8 * j; const LAS float* sp = scr + (8 * c8) * 65 + n;
;             v4u o; o.x = pk2(sp[0 * 65], sp[1 * 65]); o.y = pk2(sp[2 * 65], sp[3 * 65]); o.z = pk2(sp[4 * 65], sp[5 * 65]); o.w = pk2(sp[6 * 65], sp[7 * 65]);
;             *(v4u*)(WT + (size_t)(d0 + n) * K + k0 + 8 * c8) = o; }
	s_nop 1
	s_waitcnt lgkmcnt(2)
	s_nop 0
	ds_read2_b32 v[24:25], v30 offset0:150 offset1:158
	s_nop 1
	ds_read2_b32 v[26:27], v30 offset0:215 offset1:223
	v_cvt_pk_bf16_f32 v9, v16, v18
	s_waitcnt lgkmcnt(3)
	s_nop 1
	s_waitcnt lgkmcnt(2)
	s_nop 2
	v_cvt_pk_bf16_f32 v10, v20, v22
	s_waitcnt lgkmcnt(1)
	s_nop 1
	s_waitcnt lgkmcnt(0)
	s_nop 2
	v_add_u32_e32 v28, 16, v6
	v_cvt_pk_bf16_f32 v11, v24, v26
	v_ashrrev_i32_e32 v29, 31, v28
	v_bfe_u32 v3, v15, 16, 1
	v_lshlrev_b64 v[28:29], 12, v[28:29]
	v_add3_u32 v3, v15, v3, s13
	v_bfe_u32 v7, v13, 16, 1
	v_lshl_add_u64 v[28:29], v[4:5], 0, v[28:29]
	v_lshrrev_b32_e32 v3, 16, v3
	v_add3_u32 v7, v13, v7, s13
	global_store_dwordx4 v[28:29], v[8:11], off
	v_add_u32_e32 v12, 24, v6
	v_ashrrev_i32_e32 v13, 31, v12
	v_and_or_b32 v8, v7, s14, v3
	s_nop 4
	v_cvt_pk_bf16_f32 v9, v17, v19
	s_nop 4
	v_cvt_pk_bf16_f32 v10, v21, v23
	s_nop 4
	v_lshlrev_b64 v[12:13], 12, v[12:13]
	v_cvt_pk_bf16_f32 v11, v25, v27
	ds_read2_b32 v[14:15], v80 offset0:32 offset1:40
	v_lshl_add_u64 v[12:13], v[4:5], 0, v[12:13]
	global_store_dwordx4 v[12:13], v[8:11], off
	ds_read2_b32 v[12:13], v80 offset0:97 offset1:105
	ds_read2_b32 v[16:17], v80 offset0:162 offset1:170
	ds_read2_b32 v[18:19], v80 offset0:227 offset1:235
	s_waitcnt lgkmcnt(3)
	s_nop 1
	s_waitcnt lgkmcnt(2)
	s_nop 0
	ds_read2_b32 v[20:21], v30 offset0:36 offset1:44
	s_nop 1
	ds_read2_b32 v[22:23], v30 offset0:101 offset1:109
	v_cvt_pk_bf16_f32 v8, v14, v12
	s_waitcnt lgkmcnt(3)
	s_nop 1
	s_waitcnt lgkmcnt(2)
	s_nop 0
	ds_read2_b32 v[24:25], v30 offset0:166 offset1:174
	s_nop 1
	ds_read2_b32 v[26:27], v30 offset0:231 offset1:239
	v_cvt_pk_bf16_f32 v9, v16, v18
	s_waitcnt lgkmcnt(3)
	s_nop 1
	s_waitcnt lgkmcnt(2)
	s_nop 2
	v_cvt_pk_bf16_f32 v10, v20, v22
	s_waitcnt lgkmcnt(1)
	s_nop 1
	s_waitcnt lgkmcnt(0)
	s_nop 2
	v_add_u32_e32 v28, 32, v6
	v_cvt_pk_bf16_f32 v11, v24, v26
	v_ashrrev_i32_e32 v29, 31, v28
	v_bfe_u32 v3, v15, 16, 1
	v_lshlrev_b64 v[28:29], 12, v[28:29]
	v_add3_u32 v3, v15, v3, s13
	v_bfe_u32 v7, v13, 16, 1
	v_lshl_add_u64 v[28:29], v[4:5], 0, v[28:29]
	v_lshrrev_b32_e32 v3, 16, v3
	v_add3_u32 v7, v13, v7, s13
	global_store_dwordx4 v[28:29], v[8:11], off
	v_add_u32_e32 v12, 40, v6
	v_ashrrev_i32_e32 v13, 31, v12
	v_and_or_b32 v8, v7, s14, v3
	s_nop 4
	v_cvt_pk_bf16_f32 v9, v17, v19
	s_nop 4
	v_cvt_pk_bf16_f32 v10, v21, v23
	s_nop 4
	v_lshlrev_b64 v[12:13], 12, v[12:13]
	v_cvt_pk_bf16_f32 v11, v25, v27
	ds_read2_b32 v[14:15], v80 offset0:48 offset1:56
	v_lshl_add_u64 v[12:13], v[4:5], 0, v[12:13]
	global_store_dwordx4 v[12:13], v[8:11], off
	ds_read2_b32 v[12:13], v80 offset0:113 offset1:121
	ds_read2_b32 v[16:17], v80 offset0:178 offset1:186
	ds_read2_b32 v[18:19], v80 offset0:243 offset1:251
	s_waitcnt lgkmcnt(3)
	s_nop 1
	s_waitcnt lgkmcnt(2)
	s_nop 0
	ds_read2_b32 v[20:21], v30 offset0:52 offset1:60
	s_nop 1
	ds_read2_b32 v[22:23], v30 offset0:117 offset1:125
	v_cvt_pk_bf16_f32 v8, v14, v12
	s_waitcnt lgkmcnt(3)
	s_nop 1
	s_waitcnt lgkmcnt(2)
	s_nop 0
	ds_read2_b32 v[24:25], v30 offset0:182 offset1:190
	s_nop 1
	ds_read2_b32 v[26:27], v30 offset0:247 offset1:255
	v_cvt_pk_bf16_f32 v9, v16, v18
	s_waitcnt lgkmcnt(3)
	s_nop 1
	s_waitcnt lgkmcnt(2)
	s_nop 2
	v_cvt_pk_bf16_f32 v10, v20, v22
	s_waitcnt lgkmcnt(1)
	s_nop 1
	s_waitcnt lgkmcnt(0)
	s_nop 2
	v_add_u32_e32 v28, 48, v6
	v_cvt_pk_bf16_f32 v11, v24, v26
	v_ashrrev_i32_e32 v29, 31, v28
	v_bfe_u32 v3, v15, 16, 1
	v_lshlrev_b64 v[28:29], 12, v[28:29]
	v_add3_u32 v3, v15, v3, s13
	v_bfe_u32 v7, v13, 16, 1
	v_lshl_add_u64 v[28:29], v[4:5], 0, v[28:29]
	v_lshrrev_b32_e32 v3, 16, v3
	v_add3_u32 v7, v13, v7, s13
	global_store_dwordx4 v[28:29], v[8:11], off
	v_add_u32_e32 v6, 56, v6
	s_add_i32 s15, s15, s86
	v_and_or_b32 v8, v7, s14, v3
	s_nop 4
	v_cvt_pk_bf16_f32 v9, v17, v19
	s_nop 4
	v_cvt_pk_bf16_f32 v10, v21, v23
	s_nop 4
	v_cvt_pk_bf16_f32 v11, v25, v27
	v_ashrrev_i32_e32 v7, 31, v6
	v_lshlrev_b64 v[6:7], 12, v[6:7]
	v_lshl_add_u64 v[4:5], v[4:5], 0, v[6:7]
	global_store_dwordx4 v[4:5], v[8:11], off
	s_waitcnt lgkmcnt(0)
	s_add_i32 s0, s0, s1
	s_cmpk_lt_i32 s15, 0x1480
	s_cbranch_scc0 .LBB0_45

; #define LAS __attribute__((address_space(3)))
; #define LDS_WAIT() asm volatile("s_waitcnt lgkmcnt(0)" ::: "memory")
; __device__ __forceinline__ unsigned pk2(float lo, float hi) { return f2bf(lo) | (f2bf(hi) << 16); }
;     ...
;     for (int it = gw0; it < items; it += ngw) {
;         const int kb = it / nblk, nb = it % nblk, k0 = 64 * kb, n0 = 64 * nb, nq = (lane & 15) * 4, kr = lane >> 4; const bool ok = (n0 + nq) < N;
;         f32x4 v[16];
; #pragma unroll
;         for (int i = 0; i < 16; ++i) v[i] = ok ? __builtin_nontemporal_load((const f32x4*)(W + (size_t)(k0 + 4 * i + kr) * N + n0 + nq)) : (f32x4){0.f, 0.f, 0.f, 0.f};
;         if (gain) {
; #pragma unroll
;             for (int i = 0; i < 16; ++i) v[i] *= gain[k0 + 4 * i + kr]; }
; #pragma unroll
;         for (int i = 0; i < 16; ++i) { LAS float* d = scr + (4 * i + kr) * 65 + nq; d[0] = v[i].x; d[1] = v[i].y; d[2] = v[i].z; d[3] = v[i].w; }
;         LDS_WAIT(); asm volatile("" ::: "memory");
;         const int c8 = lane & 7; int d0 = n0;
;         if (ffnmap) { const int bj = n0 >= FFH ? 1 : 0, chn = n0 - FFH * bj; d0 = 256 * (chn >> 7) + 128 * bj + (chn & 127); }
; #pragma unroll
;         for (int j = 0; j < 8; ++j) { const int n = (lane >> 3) + 8 * j; const LAS float* sp = scr + (8 * c8) * 65 + n;
;             v4u o; o.x = pk2(sp[0 * 65], sp[1 * 65]); o.y = pk2(sp[2 * 65], sp[3 * 65]); o.z = pk2(sp[4 * 65], sp[5 * 65]); o.w = pk2(sp[6 * 65], sp[7 * 65]);
;             *(v4u*)(WT + (size_t)(d0 + n) * K + k0 + 8 * c8) = o; }
.LBB0_47:
	s_or_b64 exec, exec, s[6:7]
	s_waitcnt vmcnt(0)
	ds_write2_b32 v77, v2, v3 offset1:1
	ds_write2_b32 v77, v4, v5 offset0:2 offset1:3
	v_add_u32_e32 v2, 0x410, v77
	ds_write2_b32 v2, v10, v11 offset1:1
	v_add_u32_e32 v2, 0x418, v77
	ds_write2_b32 v2, v12, v13 offset1:1
	v_add_u32_e32 v2, 0x820, v77
	ds_write2_b32 v2, v6, v7 offset1:1
	v_add_u32_e32 v2, 0x828, v77
	ds_write2_b32 v2, v8, v9 offset1:1
	v_add_u32_e32 v2, 0xc30, v77
	ds_write2_b32 v2, v18, v19 offset1:1
	v_add_u32_e32 v2, 0xc38, v77
	ds_write2_b32 v2, v20, v21 offset1:1
	v_add_u32_e32 v2, 0x1040, v77
	ds_write2_b32 v2, v14, v15 offset1:1
	v_add_u32_e32 v2, 0x1048, v77
	ds_write2_b32 v2, v16, v17 offset1:1
	v_add_u32_e32 v2, 0x1450, v77
	ds_write2_b32 v2, v26, v27 offset1:1
	v_add_u32_e32 v2, 0x1458, v77
	ds_write2_b32 v2, v28, v29 offset1:1
	v_add_u32_e32 v2, 0x1860, v77
	ds_write2_b32 v2, v22, v23 offset1:1
	v_add_u32_e32 v2, 0x1868, v77
	ds_write2_b32 v2, v24, v25 offset1:1
	v_add_u32_e32 v2, 0x1c70, v77
	ds_write2_b32 v2, v34, v35 offset1:1
	v_add_u32_e32 v2, 0x1c78, v77
	ds_write2_b32 v2, v36, v37 offset1:1
	v_add_u32_e32 v2, 0x2080, v77
	ds_write2_b32 v2, v30, v31 offset1:1
	v_add_u32_e32 v2, 0x2088, v77
	ds_write2_b32 v2, v32, v33 offset1:1
	v_add_u32_e32 v2, 0x2490, v77
	ds_write2_b32 v2, v42, v43 offset1:1
	v_add_u32_e32 v2, 0x2498, v77
	ds_write2_b32 v2, v44, v45 offset1:1
	v_add_u32_e32 v2, 0x28a0, v77
	ds_write2_b32 v2, v38, v39 offset1:1
	v_add_u32_e32 v2, 0x28a8, v77
	ds_write2_b32 v2, v40, v41 offset1:1
	v_add_u32_e32 v2, 0x2cb0, v77
	ds_write2_b32 v2, v50, v51 offset1:1
	v_add_u32_e32 v2, 0x2cb8, v77
	ds_write2_b32 v2, v52, v53 offset1:1
	v_add_u32_e32 v2, 0x30c0, v77
	ds_write2_b32 v2, v46, v47 offset1:1
	v_add_u32_e32 v2, 0x30c8, v77
	ds_write2_b32 v2, v48, v49 offset1:1
	v_add_u32_e32 v2, 0x34d0, v77
	ds_write2_b32 v2, v58, v59 offset1:1
	v_add_u32_e32 v2, 0x34d8, v77
	ds_write2_b32 v2, v60, v61 offset1:1
	v_add_u32_e32 v2, 0x38e0, v77
	ds_write2_b32 v2, v54, v55 offset1:1
	v_add_u32_e32 v2, 0x38e8, v77
	ds_write2_b32 v2, v56, v57 offset1:1
	v_add_u32_e32 v2, 0x3cf0, v77
	ds_write2_b32 v2, v62, v63 offset1:1
	v_add_u32_e32 v2, 0x3cf8, v77
	ds_write2_b32 v2, v64, v65 offset1:1
	s_waitcnt lgkmcnt(0)
	ds_read2_b32 v[10:11], v76 offset1:8
	ds_read2_b32 v[12:13], v76 offset0:65 offset1:73
	ds_read2_b32 v[14:15], v76 offset0:130 offset1:138
	ds_read2_b32 v[16:17], v76 offset0:195 offset1:203
	v_add_u32_e32 v28, 0x400, v76
	s_waitcnt lgkmcnt(3)
	s_nop 1
	s_waitcnt lgkmcnt(2)
	s_nop 0
	ds_read2_b32 v[18:19], v28 offset0:4 offset1:12
	s_nop 1
	ds_read2_b32 v[20:21], v28 offset0:69 offset1:77
	v_cvt_pk_bf16_f32 v6, v10, v12
	s_waitcnt lgkmcnt(3)
	s_nop 1
	s_waitcnt lgkmcnt(2)
	s_nop 0
	ds_read2_b32 v[22:23], v28 offset0:134 offset1:142
	s_nop 1
	ds_read2_b32 v[24:25], v28 offset0:199 offset1:207
	v_cvt_pk_bf16_f32 v7, v14, v16
	s_waitcnt lgkmcnt(3)
	s_nop 1
	s_waitcnt lgkmcnt(2)
	s_nop 2
	v_cvt_pk_bf16_f32 v8, v18, v20
	s_waitcnt lgkmcnt(1)
	s_nop 1
	s_waitcnt lgkmcnt(0)
	s_nop 2
	s_add_i32 s12, s12, s0
	v_cvt_pk_bf16_f32 v9, v22, v24
	v_add_u32_e32 v4, s12, v75
	s_ashr_i32 s3, s2, 31
	v_ashrrev_i32_e32 v5, 31, v4
	v_lshl_add_u64 v[2:3], s[2:3], 1, v[68:69]
	v_lshlrev_b64 v[26:27], 13, v[4:5]
	v_lshl_add_u64 v[26:27], v[2:3], 0, v[26:27]
	v_bfe_u32 v5, v11, 16, 1
	global_store_dwordx4 v[26:27], v[6:9], off
	v_add3_u32 v5, v11, v5, s9
	v_lshrrev_b32_e32 v5, 16, v5
	v_bfe_u32 v6, v13, 16, 1
	v_add3_u32 v6, v13, v6, s9
	v_and_or_b32 v6, v6, s10, v5
	s_nop 4
	v_cvt_pk_bf16_f32 v7, v15, v17
	s_nop 4
	v_cvt_pk_bf16_f32 v8, v19, v21
	s_nop 0
	v_add_u32_e32 v10, 8, v4
	s_nop 1
	v_ashrrev_i32_e32 v11, 31, v10
	s_nop 1
	v_lshlrev_b64 v[10:11], 13, v[10:11]
	v_cvt_pk_bf16_f32 v9, v23, v25
	ds_read2_b32 v[12:13], v76 offset0:16 offset1:24
	v_lshl_add_u64 v[10:11], v[2:3], 0, v[10:11]
	global_store_dwordx4 v[10:11], v[6:9], off
	ds_read2_b32 v[10:11], v76 offset0:81 offset1:89
	ds_read2_b32 v[14:15], v76 offset0:146 offset1:154
	ds_read2_b32 v[16:17], v76 offset0:211 offset1:219
	s_waitcnt lgkmcnt(3)
	s_nop 1
	s_waitcnt lgkmcnt(2)
	s_nop 0
	ds_read2_b32 v[18:19], v28 offset0:20 offset1:28
	s_nop 1
	ds_read2_b32 v[20:21], v28 offset0:85 offset1:93
	v_cvt_pk_bf16_f32 v6, v12, v10
	s_waitcnt lgkmcnt(3)
; #define LAS __attribute__((address_space(3)))
; #define LDS_WAIT() asm volatile("s_waitcnt lgkmcnt(0)" ::: "memory")
; __device__ __forceinline__ unsigned pk2(float lo, float hi) { return f2bf(lo) | (f2bf(hi) << 16); }
;     ...
;         for (int i = 0; i < 16; ++i) { LAS float* d = scr + (4 * i + kr) * 65 + nq; d[0] = v[i].x; d[1] = v[i].y; d[2] = v[i].z; d[3] = v[i].w; }
;         LDS_WAIT(); asm volatile("" ::: "memory");
;         const int c8 = lane & 7; int d0 = n0;
;         if (ffnmap) { const int bj = n0 >= FFH ? 1 : 0, chn = n0 - FFH * bj; d0 = 256 * (chn >> 7) + 128 * bj + (chn & 127); }
; #pragma unroll
;         for (int j = 0; j < 8; ++j) { const int n = (lane >> 3) + 8 * j; const LAS float* sp = scr + (8 * c8) * 65 + n;
;             v4u o; o.x = pk2(sp[0 * 65], sp[1 * 65]); o.y = pk2(sp[2 * 65], sp[3 * 65]); o.z = pk2(sp[4 * 65], sp[5 * 65]); o.w = pk2(sp[6 * 65], sp[7 * 65]);
;             *(v4u*)(WT + (size_t)(d0 + n) * K + k0 + 8 * c8) = o; }
	s_nop 1
	s_waitcnt lgkmcnt(2)
	s_nop 0
	ds_read2_b32 v[22:23], v28 offset0:150 offset1:158
	s_nop 1
	ds_read2_b32 v[24:25], v28 offset0:215 offset1:223
	v_cvt_pk_bf16_f32 v7, v14, v16
	s_waitcnt lgkmcnt(3)
	s_nop 1
	s_waitcnt lgkmcnt(2)
	s_nop 2
	v_cvt_pk_bf16_f32 v8, v18, v20
	s_waitcnt lgkmcnt(1)
	s_nop 0
	v_add_u32_e32 v26, 16, v4
	s_nop 0
	s_waitcnt lgkmcnt(0)
	s_nop 0
	v_ashrrev_i32_e32 v27, 31, v26
	s_nop 1
	v_lshlrev_b64 v[26:27], 13, v[26:27]
	v_cvt_pk_bf16_f32 v9, v22, v24
	v_lshl_add_u64 v[26:27], v[2:3], 0, v[26:27]
	v_bfe_u32 v5, v13, 16, 1
	global_store_dwordx4 v[26:27], v[6:9], off
	v_add3_u32 v5, v13, v5, s9
	v_lshrrev_b32_e32 v5, 16, v5
	v_bfe_u32 v6, v11, 16, 1
	v_add3_u32 v6, v11, v6, s9
	v_and_or_b32 v6, v6, s10, v5
	s_nop 4
	v_cvt_pk_bf16_f32 v7, v15, v17
	s_nop 4
	v_cvt_pk_bf16_f32 v8, v19, v21
	s_nop 0
	v_add_u32_e32 v10, 24, v4
	s_nop 1
	v_ashrrev_i32_e32 v11, 31, v10
	s_nop 1
	v_lshlrev_b64 v[10:11], 13, v[10:11]
	v_cvt_pk_bf16_f32 v9, v23, v25
	ds_read2_b32 v[12:13], v76 offset0:32 offset1:40
	v_lshl_add_u64 v[10:11], v[2:3], 0, v[10:11]
	global_store_dwordx4 v[10:11], v[6:9], off
	ds_read2_b32 v[10:11], v76 offset0:97 offset1:105
	ds_read2_b32 v[14:15], v76 offset0:162 offset1:170
	ds_read2_b32 v[16:17], v76 offset0:227 offset1:235
	s_waitcnt lgkmcnt(3)
	s_nop 1
	s_waitcnt lgkmcnt(2)
	s_nop 0
	ds_read2_b32 v[18:19], v28 offset0:36 offset1:44
	s_nop 1
	ds_read2_b32 v[20:21], v28 offset0:101 offset1:109
	v_cvt_pk_bf16_f32 v6, v12, v10
	s_waitcnt lgkmcnt(3)
	s_nop 1
	s_waitcnt lgkmcnt(2)
	s_nop 0
	ds_read2_b32 v[22:23], v28 offset0:166 offset1:174
	s_nop 1
	ds_read2_b32 v[24:25], v28 offset0:231 offset1:239
	v_cvt_pk_bf16_f32 v7, v14, v16
	s_waitcnt lgkmcnt(3)
	s_nop 1
	s_waitcnt lgkmcnt(2)
	s_nop 2
	v_cvt_pk_bf16_f32 v8, v18, v20
	s_waitcnt lgkmcnt(1)
	s_nop 0
	v_add_u32_e32 v26, 32, v4
	s_nop 0
	s_waitcnt lgkmcnt(0)
	s_nop 0
	v_ashrrev_i32_e32 v27, 31, v26
	s_nop 1
	v_lshlrev_b64 v[26:27], 13, v[26:27]
	v_cvt_pk_bf16_f32 v9, v22, v24
	v_lshl_add_u64 v[26:27], v[2:3], 0, v[26:27]
	v_bfe_u32 v5, v13, 16, 1
	global_store_dwordx4 v[26:27], v[6:9], off
	v_add3_u32 v5, v13, v5, s9
	v_lshrrev_b32_e32 v5, 16, v5
	v_bfe_u32 v6, v11, 16, 1
	v_add3_u32 v6, v11, v6, s9
	v_and_or_b32 v6, v6, s10, v5
	s_nop 4
	v_cvt_pk_bf16_f32 v7, v15, v17
	s_nop 4
	v_cvt_pk_bf16_f32 v8, v19, v21
	s_nop 0
	v_add_u32_e32 v10, 40, v4
	s_nop 1
	v_ashrrev_i32_e32 v11, 31, v10
	s_nop 1
	v_lshlrev_b64 v[10:11], 13, v[10:11]
	v_cvt_pk_bf16_f32 v9, v23, v25
	ds_read2_b32 v[12:13], v76 offset0:48 offset1:56
	v_lshl_add_u64 v[10:11], v[2:3], 0, v[10:11]
	global_store_dwordx4 v[10:11], v[6:9], off
	ds_read2_b32 v[10:11], v76 offset0:113 offset1:121
	ds_read2_b32 v[14:15], v76 offset0:178 offset1:186
	ds_read2_b32 v[16:17], v76 offset0:243 offset1:251
	s_waitcnt lgkmcnt(3)
	s_nop 1
	s_waitcnt lgkmcnt(2)
	s_nop 0
	ds_read2_b32 v[18:19], v28 offset0:52 offset1:60
	s_nop 1
	ds_read2_b32 v[20:21], v28 offset0:117 offset1:125
	v_cvt_pk_bf16_f32 v6, v12, v10
	s_waitcnt lgkmcnt(3)
	s_nop 1
	s_waitcnt lgkmcnt(2)
	s_nop 0
	ds_read2_b32 v[22:23], v28 offset0:182 offset1:190
	s_nop 1
	ds_read2_b32 v[24:25], v28 offset0:247 offset1:255
	v_cvt_pk_bf16_f32 v7, v14, v16
	s_waitcnt lgkmcnt(3)
	s_nop 1
	s_waitcnt lgkmcnt(2)
	s_nop 2
	v_cvt_pk_bf16_f32 v8, v18, v20
	s_waitcnt lgkmcnt(1)
	s_nop 0
	v_add_u32_e32 v26, 48, v4
	s_nop 0
	s_waitcnt lgkmcnt(0)
	s_nop 0
	v_ashrrev_i32_e32 v27, 31, v26
	s_nop 1
	v_lshlrev_b64 v[26:27], 13, v[26:27]
	v_cvt_pk_bf16_f32 v9, v22, v24
	v_lshl_add_u64 v[26:27], v[2:3], 0, v[26:27]
	v_bfe_u32 v5, v13, 16, 1
	global_store_dwordx4 v[26:27], v[6:9], off
	v_add3_u32 v5, v13, v5, s9
	v_lshrrev_b32_e32 v5, 16, v5
	v_bfe_u32 v6, v11, 16, 1
	v_add3_u32 v6, v11, v6, s9
	v_and_or_b32 v6, v6, s10, v5
	s_nop 4
	v_cvt_pk_bf16_f32 v7, v15, v17
	s_nop 4
	v_cvt_pk_bf16_f32 v8, v19, v21
	s_nop 4
	v_add_u32_e32 v4, 56, v4
	v_cvt_pk_bf16_f32 v9, v23, v25
	v_ashrrev_i32_e32 v5, 31, v4
	v_lshlrev_b64 v[4:5], 13, v[4:5]
	v_lshl_add_u64 v[2:3], v[2:3], 0, v[4:5]
	global_store_dwordx4 v[2:3], v[6:9], off
	s_waitcnt lgkmcnt(0)
	s_add_i32 s11, s11, s86
	s_add_i32 s0, s0, s1
	s_cmpk_lt_i32 s11, 0x800
	s_cbranch_scc0 .LBB0_80

; #define LAS __attribute__((address_space(3)))
; #define LDS_WAIT() asm volatile("s_waitcnt lgkmcnt(0)" ::: "memory")
;     ...
;         const int kb = it / nblk, nb = it % nblk, k0 = 64 * kb, n0 = 64 * nb, nq = (lane & 15) * 4, kr = lane >> 4; const bool ok = (n0 + nq) < N;
;         f32x4 v[16];
; #pragma unroll
;         for (int i = 0; i < 16; ++i) v[i] = ok ? __builtin_nontemporal_load((const f32x4*)(W + (size_t)(k0 + 4 * i + kr) * N + n0 + nq)) : (f32x4){0.f, 0.f, 0.f, 0.f};
;         if (gain) {
; #pragma unroll
;             for (int i = 0; i < 16; ++i) v[i] *= gain[k0 + 4 * i + kr]; }
; #pragma unroll
;         for (int i = 0; i < 16; ++i) { LAS float* d = scr + (4 * i + kr) * 65 + nq; d[0] = v[i].x; d[1] = v[i].y; d[2] = v[i].z; d[3] = v[i].w; }
;         LDS_WAIT(); asm volatile("" ::: "memory");
.LBB0_82:
	s_or_b64 exec, exec, s[8:9]
	v_lshl_add_u64 v[70:71], v[70:71], 2, s[2:3]
	global_load_dword v72, v[70:71], off
	global_load_dword v80, v[70:71], off offset:16
	global_load_dword v82, v[70:71], off offset:32
	global_load_dword v84, v[70:71], off offset:48
	global_load_dword v86, v[70:71], off offset:64
	global_load_dword v88, v[70:71], off offset:80
	global_load_dword v90, v[70:71], off offset:96
	global_load_dword v92, v[70:71], off offset:112
	global_load_dword v94, v[70:71], off offset:128
	global_load_dword v96, v[70:71], off offset:144
	global_load_dword v98, v[70:71], off offset:160
	global_load_dword v100, v[70:71], off offset:176
	global_load_dword v102, v[70:71], off offset:192
	global_load_dword v104, v[70:71], off offset:208
	s_nop 0
	global_load_dword v70, v[70:71], off offset:224
	v_lshl_add_u64 v[74:75], v[74:75], 2, s[2:3]
	global_load_dword v74, v[74:75], off
	v_add_u32_e32 v73, 0x418, v79
	v_add_u32_e32 v81, 0x828, v79
	v_add_u32_e32 v83, 0xc30, v79
	v_add_u32_e32 v85, 0xc38, v79
	v_add_u32_e32 v87, 0x1040, v79
	v_add_u32_e32 v89, 0x1048, v79
	v_add_u32_e32 v91, 0x1450, v79
	v_add_u32_e32 v93, 0x1458, v79
	v_add_u32_e32 v95, 0x1860, v79
	v_add_u32_e32 v97, 0x1868, v79
	v_add_u32_e32 v71, 0x410, v79
	v_add_u32_e32 v75, 0x820, v79
	v_add_u32_e32 v99, 0x1c70, v79
	v_add_u32_e32 v101, 0x1c78, v79
	v_add_u32_e32 v103, 0x2080, v79
	v_add_u32_e32 v105, 0x2088, v79
	s_add_i32 s14, s14, s0
	s_ashr_i32 s7, s6, 31
	s_add_i32 s13, s13, s86
	s_add_i32 s0, s0, s1
	s_cmpk_lt_i32 s13, 0x100
	s_waitcnt vmcnt(15)
	v_pk_mul_f32 v[2:3], v[2:3], v[72:73] op_sel_hi:[1,0]
	v_pk_mul_f32 v[4:5], v[4:5], v[72:73] op_sel_hi:[1,0]
	s_waitcnt vmcnt(14)
	v_pk_mul_f32 v[12:13], v[12:13], v[80:81] op_sel_hi:[1,0]
	v_pk_mul_f32 v[10:11], v[10:11], v[80:81] op_sel_hi:[1,0]
	s_waitcnt vmcnt(13)
	v_pk_mul_f32 v[8:9], v[8:9], v[82:83] op_sel_hi:[1,0]
	v_pk_mul_f32 v[6:7], v[6:7], v[82:83] op_sel_hi:[1,0]
	s_waitcnt vmcnt(12)
	v_pk_mul_f32 v[20:21], v[20:21], v[84:85] op_sel_hi:[1,0]
	v_pk_mul_f32 v[18:19], v[18:19], v[84:85] op_sel_hi:[1,0]
	s_waitcnt vmcnt(11)
	v_pk_mul_f32 v[16:17], v[16:17], v[86:87] op_sel_hi:[1,0]
	v_pk_mul_f32 v[14:15], v[14:15], v[86:87] op_sel_hi:[1,0]
	s_waitcnt vmcnt(10)
	v_pk_mul_f32 v[28:29], v[28:29], v[88:89] op_sel_hi:[1,0]
	v_pk_mul_f32 v[26:27], v[26:27], v[88:89] op_sel_hi:[1,0]
	s_waitcnt vmcnt(9)
	v_pk_mul_f32 v[24:25], v[24:25], v[90:91] op_sel_hi:[1,0]
	v_pk_mul_f32 v[22:23], v[22:23], v[90:91] op_sel_hi:[1,0]
	s_waitcnt vmcnt(8)
	v_pk_mul_f32 v[36:37], v[36:37], v[92:93] op_sel_hi:[1,0]
	v_pk_mul_f32 v[34:35], v[34:35], v[92:93] op_sel_hi:[1,0]
	s_waitcnt vmcnt(7)
	v_pk_mul_f32 v[32:33], v[32:33], v[94:95] op_sel_hi:[1,0]
	v_pk_mul_f32 v[30:31], v[30:31], v[94:95] op_sel_hi:[1,0]
	s_waitcnt vmcnt(6)
	v_pk_mul_f32 v[42:43], v[42:43], v[96:97] op_sel_hi:[1,0]
	ds_write2_b32 v79, v2, v3 offset1:1
	ds_write2_b32 v79, v4, v5 offset0:2 offset1:3
	ds_write2_b32 v71, v10, v11 offset1:1
	ds_write2_b32 v73, v12, v13 offset1:1
	ds_write2_b32 v75, v6, v7 offset1:1
	ds_write2_b32 v81, v8, v9 offset1:1
	ds_write2_b32 v83, v18, v19 offset1:1
	ds_write2_b32 v85, v20, v21 offset1:1
	ds_write2_b32 v87, v14, v15 offset1:1
	ds_write2_b32 v89, v16, v17 offset1:1
	ds_write2_b32 v91, v26, v27 offset1:1
	ds_write2_b32 v93, v28, v29 offset1:1
	ds_write2_b32 v95, v22, v23 offset1:1
	ds_write2_b32 v97, v24, v25 offset1:1
	ds_write2_b32 v99, v34, v35 offset1:1
	ds_write2_b32 v101, v36, v37 offset1:1
	ds_write2_b32 v103, v30, v31 offset1:1
	ds_write2_b32 v105, v32, v33 offset1:1
	v_add_u32_e32 v2, 0x2490, v79
	v_pk_mul_f32 v[44:45], v[44:45], v[96:97] op_sel_hi:[1,0]
	ds_write2_b32 v2, v42, v43 offset1:1
	v_add_u32_e32 v2, 0x2498, v79
	s_waitcnt vmcnt(5)
	v_pk_mul_f32 v[38:39], v[38:39], v[98:99] op_sel_hi:[1,0]
	ds_write2_b32 v2, v44, v45 offset1:1
	v_add_u32_e32 v2, 0x28a0, v79
	v_pk_mul_f32 v[40:41], v[40:41], v[98:99] op_sel_hi:[1,0]
	ds_write2_b32 v2, v38, v39 offset1:1
	v_add_u32_e32 v2, 0x28a8, v79
	s_waitcnt vmcnt(4)
	v_pk_mul_f32 v[50:51], v[50:51], v[100:101] op_sel_hi:[1,0]
	ds_write2_b32 v2, v40, v41 offset1:1
	v_add_u32_e32 v2, 0x2cb0, v79
	v_pk_mul_f32 v[52:53], v[52:53], v[100:101] op_sel_hi:[1,0]
	ds_write2_b32 v2, v50, v51 offset1:1
	v_add_u32_e32 v2, 0x2cb8, v79
	s_waitcnt vmcnt(3)
	v_pk_mul_f32 v[46:47], v[46:47], v[102:103] op_sel_hi:[1,0]
	ds_write2_b32 v2, v52, v53 offset1:1
	v_add_u32_e32 v2, 0x30c0, v79
	v_pk_mul_f32 v[48:49], v[48:49], v[102:103] op_sel_hi:[1,0]
	ds_write2_b32 v2, v46, v47 offset1:1
	v_add_u32_e32 v2, 0x30c8, v79
	s_waitcnt vmcnt(2)
	v_pk_mul_f32 v[58:59], v[58:59], v[104:105] op_sel_hi:[1,0]
	ds_write2_b32 v2, v48, v49 offset1:1
	v_add_u32_e32 v2, 0x34d0, v79
	v_pk_mul_f32 v[60:61], v[60:61], v[104:105] op_sel_hi:[1,0]
	ds_write2_b32 v2, v58, v59 offset1:1
	v_add_u32_e32 v2, 0x34d8, v79
	s_waitcnt vmcnt(1)
	v_pk_mul_f32 v[54:55], v[54:55], v[70:71] op_sel_hi:[1,0]
	ds_write2_b32 v2, v60, v61 offset1:1
	v_add_u32_e32 v2, 0x38e0, v79
	v_pk_mul_f32 v[56:57], v[56:57], v[70:71] op_sel_hi:[1,0]
	ds_write2_b32 v2, v54, v55 offset1:1
	v_add_u32_e32 v2, 0x38e8, v79
	s_waitcnt vmcnt(0)
	v_pk_mul_f32 v[62:63], v[62:63], v[74:75] op_sel_hi:[1,0]
	ds_write2_b32 v2, v56, v57 offset1:1
	v_add_u32_e32 v2, 0x3cf0, v79
	v_pk_mul_f32 v[64:65], v[64:65], v[74:75] op_sel_hi:[1,0]
	ds_write2_b32 v2, v62, v63 offset1:1
	v_add_u32_e32 v2, 0x3cf8, v79
	ds_write2_b32 v2, v64, v65 offset1:1
	s_waitcnt lgkmcnt(0)
	ds_read2_b32 v[10:11], v78 offset1:8
	ds_read2_b32 v[12:13], v78 offset0:65 offset1:73
	ds_read2_b32 v[14:15], v78 offset0:130 offset1:138
	ds_read2_b32 v[16:17], v78 offset0:195 offset1:203
	v_add_u32_e32 v28, 0x400, v78
	s_waitcnt lgkmcnt(3)
; #define LAS __attribute__((address_space(3)))
; #define LDS_WAIT() asm volatile("s_waitcnt lgkmcnt(0)" ::: "memory")
; __device__ __forceinline__ unsigned pk2(float lo, float hi) { return f2bf(lo) | (f2bf(hi) << 16); }
;     ...
;         for (int i = 0; i < 16; ++i) { LAS float* d = scr + (4 * i + kr) * 65 + nq; d[0] = v[i].x; d[1] = v[i].y; d[2] = v[i].z; d[3] = v[i].w; }
;         LDS_WAIT(); asm volatile("" ::: "memory");
;         const int c8 = lane & 7; int d0 = n0;
;         if (ffnmap) { const int bj = n0 >= FFH ? 1 : 0, chn = n0 - FFH * bj; d0 = 256 * (chn >> 7) + 128 * bj + (chn & 127); }
; #pragma unroll
;         for (int j = 0; j < 8; ++j) { const int n = (lane >> 3) + 8 * j; const LAS float* sp = scr + (8 * c8) * 65 + n;
;             v4u o; o.x = pk2(sp[0 * 65], sp[1 * 65]); o.y = pk2(sp[2 * 65], sp[3 * 65]); o.z = pk2(sp[4 * 65], sp[5 * 65]); o.w = pk2(sp[6 * 65], sp[7 * 65]);
;             *(v4u*)(WT + (size_t)(d0 + n) * K + k0 + 8 * c8) = o; }
	s_nop 1
	s_waitcnt lgkmcnt(2)
	s_nop 0
	ds_read2_b32 v[18:19], v28 offset0:4 offset1:12
	s_nop 1
	ds_read2_b32 v[20:21], v28 offset0:69 offset1:77
	v_cvt_pk_bf16_f32 v6, v10, v12
	s_waitcnt lgkmcnt(3)
	s_nop 1
	s_waitcnt lgkmcnt(2)
	s_nop 0
	ds_read2_b32 v[22:23], v28 offset0:134 offset1:142
	s_nop 1
	ds_read2_b32 v[24:25], v28 offset0:199 offset1:207
	v_cvt_pk_bf16_f32 v7, v14, v16
	s_waitcnt lgkmcnt(3)
	s_nop 1
	s_waitcnt lgkmcnt(2)
	s_nop 2
	v_cvt_pk_bf16_f32 v8, v18, v20
	s_waitcnt lgkmcnt(1)
	s_nop 1
	s_waitcnt lgkmcnt(0)
	s_nop 2
	v_cvt_pk_bf16_f32 v9, v22, v24
	v_add_u32_e32 v4, s14, v77
	v_ashrrev_i32_e32 v5, 31, v4
	v_lshl_add_u64 v[2:3], s[6:7], 1, v[68:69]
	v_lshlrev_b64 v[26:27], 12, v[4:5]
	v_lshl_add_u64 v[26:27], v[2:3], 0, v[26:27]
	v_bfe_u32 v5, v11, 16, 1
	global_store_dwordx4 v[26:27], v[6:9], off
	v_add3_u32 v5, v11, v5, s11
	v_lshrrev_b32_e32 v5, 16, v5
	v_bfe_u32 v6, v13, 16, 1
	v_add3_u32 v6, v13, v6, s11
	v_and_or_b32 v6, v6, s12, v5
	s_nop 4
	v_cvt_pk_bf16_f32 v7, v15, v17
	s_nop 4
	v_cvt_pk_bf16_f32 v8, v19, v21
	s_nop 0
	v_add_u32_e32 v10, 8, v4
	s_nop 1
	v_ashrrev_i32_e32 v11, 31, v10
	s_nop 1
	v_lshlrev_b64 v[10:11], 12, v[10:11]
	v_cvt_pk_bf16_f32 v9, v23, v25
	ds_read2_b32 v[12:13], v78 offset0:16 offset1:24
	v_lshl_add_u64 v[10:11], v[2:3], 0, v[10:11]
	global_store_dwordx4 v[10:11], v[6:9], off
	ds_read2_b32 v[10:11], v78 offset0:81 offset1:89
	ds_read2_b32 v[14:15], v78 offset0:146 offset1:154
	ds_read2_b32 v[16:17], v78 offset0:211 offset1:219
	s_waitcnt lgkmcnt(3)
	s_nop 1
	s_waitcnt lgkmcnt(2)
	s_nop 0
	ds_read2_b32 v[18:19], v28 offset0:20 offset1:28
	s_nop 1
	ds_read2_b32 v[20:21], v28 offset0:85 offset1:93
	v_cvt_pk_bf16_f32 v6, v12, v10
	s_waitcnt lgkmcnt(3)
	s_nop 1
	s_waitcnt lgkmcnt(2)
	s_nop 0
	ds_read2_b32 v[22:23], v28 offset0:150 offset1:158
	s_nop 1
	ds_read2_b32 v[24:25], v28 offset0:215 offset1:223
	v_cvt_pk_bf16_f32 v7, v14, v16
	s_waitcnt lgkmcnt(3)
	s_nop 1
	s_waitcnt lgkmcnt(2)
	s_nop 2
	v_cvt_pk_bf16_f32 v8, v18, v20
	s_waitcnt lgkmcnt(1)
	s_nop 0
	v_add_u32_e32 v26, 16, v4
	s_nop 0
	s_waitcnt lgkmcnt(0)
	s_nop 0
	v_ashrrev_i32_e32 v27, 31, v26
	s_nop 1
	v_lshlrev_b64 v[26:27], 12, v[26:27]
	v_cvt_pk_bf16_f32 v9, v22, v24
	v_lshl_add_u64 v[26:27], v[2:3], 0, v[26:27]
	v_bfe_u32 v5, v13, 16, 1
	global_store_dwordx4 v[26:27], v[6:9], off
	v_add3_u32 v5, v13, v5, s11
	v_lshrrev_b32_e32 v5, 16, v5
	v_bfe_u32 v6, v11, 16, 1
	v_add3_u32 v6, v11, v6, s11
	v_and_or_b32 v6, v6, s12, v5
	s_nop 4
	v_cvt_pk_bf16_f32 v7, v15, v17
	s_nop 4
	v_cvt_pk_bf16_f32 v8, v19, v21
	s_nop 0
	v_add_u32_e32 v10, 24, v4
	s_nop 1
	v_ashrrev_i32_e32 v11, 31, v10
	s_nop 1
	v_lshlrev_b64 v[10:11], 12, v[10:11]
	v_cvt_pk_bf16_f32 v9, v23, v25
	ds_read2_b32 v[12:13], v78 offset0:32 offset1:40
	v_lshl_add_u64 v[10:11], v[2:3], 0, v[10:11]
	global_store_dwordx4 v[10:11], v[6:9], off
	ds_read2_b32 v[10:11], v78 offset0:97 offset1:105
	ds_read2_b32 v[14:15], v78 offset0:162 offset1:170
	ds_read2_b32 v[16:17], v78 offset0:227 offset1:235
	s_waitcnt lgkmcnt(3)
	s_nop 1
	s_waitcnt lgkmcnt(2)
	s_nop 0
	ds_read2_b32 v[18:19], v28 offset0:36 offset1:44
	s_nop 1
	ds_read2_b32 v[20:21], v28 offset0:101 offset1:109
	v_cvt_pk_bf16_f32 v6, v12, v10
	s_waitcnt lgkmcnt(3)
	s_nop 1
	s_waitcnt lgkmcnt(2)
	s_nop 0
	ds_read2_b32 v[22:23], v28 offset0:166 offset1:174
	s_nop 1
	ds_read2_b32 v[24:25], v28 offset0:231 offset1:239
	v_cvt_pk_bf16_f32 v7, v14, v16
	s_waitcnt lgkmcnt(3)
	s_nop 1
	s_waitcnt lgkmcnt(2)
	s_nop 2
	v_cvt_pk_bf16_f32 v8, v18, v20
	s_waitcnt lgkmcnt(1)
	s_nop 0
	v_add_u32_e32 v26, 32, v4
	s_nop 0
	s_waitcnt lgkmcnt(0)
	s_nop 0
	v_ashrrev_i32_e32 v27, 31, v26
	s_nop 1
	v_lshlrev_b64 v[26:27], 12, v[26:27]
	v_cvt_pk_bf16_f32 v9, v22, v24
	v_lshl_add_u64 v[26:27], v[2:3], 0, v[26:27]
	v_bfe_u32 v5, v13, 16, 1
	global_store_dwordx4 v[26:27], v[6:9], off
	v_add3_u32 v5, v13, v5, s11
	v_lshrrev_b32_e32 v5, 16, v5
	v_bfe_u32 v6, v11, 16, 1
	v_add3_u32 v6, v11, v6, s11
	v_and_or_b32 v6, v6, s12, v5
	s_nop 4
	v_cvt_pk_bf16_f32 v7, v15, v17
	s_nop 4
	v_cvt_pk_bf16_f32 v8, v19, v21
	s_nop 0
	v_add_u32_e32 v10, 40, v4
	s_nop 1
	v_ashrrev_i32_e32 v11, 31, v10
	s_nop 1
	v_lshlrev_b64 v[10:11], 12, v[10:11]
	v_cvt_pk_bf16_f32 v9, v23, v25
	ds_read2_b32 v[12:13], v78 offset0:48 offset1:56
	v_lshl_add_u64 v[10:11], v[2:3], 0, v[10:11]
	global_store_dwordx4 v[10:11], v[6:9], off
	ds_read2_b32 v[10:11], v78 offset0:113 offset1:121
	ds_read2_b32 v[14:15], v78 offset0:178 offset1:186
	ds_read2_b32 v[16:17], v78 offset0:243 offset1:251
	s_waitcnt lgkmcnt(3)
	s_nop 1
	s_waitcnt lgkmcnt(2)
	s_nop 0
	ds_read2_b32 v[18:19], v28 offset0:52 offset1:60
	s_nop 1
	ds_read2_b32 v[20:21], v28 offset0:117 offset1:125
	v_cvt_pk_bf16_f32 v6, v12, v10
	s_waitcnt lgkmcnt(3)
	s_nop 1
	s_waitcnt lgkmcnt(2)
	s_nop 0
	ds_read2_b32 v[22:23], v28 offset0:182 offset1:190
	s_nop 1
	ds_read2_b32 v[24:25], v28 offset0:247 offset1:255
	v_cvt_pk_bf16_f32 v7, v14, v16
	s_waitcnt lgkmcnt(3)
	s_nop 1
	s_waitcnt lgkmcnt(2)
	s_nop 2
	v_cvt_pk_bf16_f32 v8, v18, v20
	s_waitcnt lgkmcnt(1)
	s_nop 0
	v_add_u32_e32 v26, 48, v4
	s_nop 0
	s_waitcnt lgkmcnt(0)
	s_nop 0
	v_ashrrev_i32_e32 v27, 31, v26
	s_nop 1
	v_lshlrev_b64 v[26:27], 12, v[26:27]
	v_cvt_pk_bf16_f32 v9, v22, v24
	v_lshl_add_u64 v[26:27], v[2:3], 0, v[26:27]
	v_bfe_u32 v5, v13, 16, 1
	global_store_dwordx4 v[26:27], v[6:9], off
	v_add3_u32 v5, v13, v5, s11
	v_lshrrev_b32_e32 v5, 16, v5
	v_bfe_u32 v6, v11, 16, 1
	v_add3_u32 v6, v11, v6, s11
	v_and_or_b32 v6, v6, s12, v5
	s_nop 4
	v_cvt_pk_bf16_f32 v7, v15, v17
	s_nop 4
	v_cvt_pk_bf16_f32 v8, v19, v21
	s_nop 4
	v_add_u32_e32 v4, 56, v4
	v_cvt_pk_bf16_f32 v9, v23, v25
	v_ashrrev_i32_e32 v5, 31, v4
	v_lshlrev_b64 v[4:5], 12, v[4:5]
	v_lshl_add_u64 v[2:3], v[2:3], 0, v[4:5]
	global_store_dwordx4 v[2:3], v[6:9], off
	s_waitcnt lgkmcnt(0)
	s_cbranch_scc0 .LBB0_115

; #define LAS __attribute__((address_space(3)))
; #define LDS_WAIT() asm volatile("s_waitcnt lgkmcnt(0)" ::: "memory")
; __device__ __forceinline__ unsigned pk2(float lo, float hi) { return f2bf(lo) | (f2bf(hi) << 16); }
;     ...
;     for (int it = gw0; it < items; it += ngw) {
;         const int kb = it / nblk, nb = it % nblk, k0 = 64 * kb, n0 = 64 * nb, nq = (lane & 15) * 4, kr = lane >> 4; const bool ok = (n0 + nq) < N;
;         f32x4 v[16];
; #pragma unroll
;         for (int i = 0; i < 16; ++i) v[i] = ok ? __builtin_nontemporal_load((const f32x4*)(W + (size_t)(k0 + 4 * i + kr) * N + n0 + nq)) : (f32x4){0.f, 0.f, 0.f, 0.f};
;         if (gain) {
; #pragma unroll
;             for (int i = 0; i < 16; ++i) v[i] *= gain[k0 + 4 * i + kr]; }
; #pragma unroll
;         for (int i = 0; i < 16; ++i) { LAS float* d = scr + (4 * i + kr) * 65 + nq; d[0] = v[i].x; d[1] = v[i].y; d[2] = v[i].z; d[3] = v[i].w; }
;         LDS_WAIT(); asm volatile("" ::: "memory");
;         const int c8 = lane & 7; int d0 = n0;
;         if (ffnmap) { const int bj = n0 >= FFH ? 1 : 0, chn = n0 - FFH * bj; d0 = 256 * (chn >> 7) + 128 * bj + (chn & 127); }
; #pragma unroll
;         for (int j = 0; j < 8; ++j) { const int n = (lane >> 3) + 8 * j; const LAS float* sp = scr + (8 * c8) * 65 + n;
;             v4u o; o.x = pk2(sp[0 * 65], sp[1 * 65]); o.y = pk2(sp[2 * 65], sp[3 * 65]); o.z = pk2(sp[4 * 65], sp[5 * 65]); o.w = pk2(sp[6 * 65], sp[7 * 65]);
;             *(v4u*)(WT + (size_t)(d0 + n) * K + k0 + 8 * c8) = o; }
.LBB0_117:
	s_or_b64 exec, exec, s[6:7]
	s_waitcnt vmcnt(0)
	ds_write2_b32 v77, v2, v3 offset1:1
	ds_write2_b32 v77, v4, v5 offset0:2 offset1:3
	v_add_u32_e32 v2, 0x410, v77
	ds_write2_b32 v2, v10, v11 offset1:1
	v_add_u32_e32 v2, 0x418, v77
	ds_write2_b32 v2, v12, v13 offset1:1
	v_add_u32_e32 v2, 0x820, v77
	ds_write2_b32 v2, v6, v7 offset1:1
	v_add_u32_e32 v2, 0x828, v77
	ds_write2_b32 v2, v8, v9 offset1:1
	v_add_u32_e32 v2, 0xc30, v77
	ds_write2_b32 v2, v18, v19 offset1:1
	v_add_u32_e32 v2, 0xc38, v77
	ds_write2_b32 v2, v20, v21 offset1:1
	v_add_u32_e32 v2, 0x1040, v77
	ds_write2_b32 v2, v14, v15 offset1:1
	v_add_u32_e32 v2, 0x1048, v77
	ds_write2_b32 v2, v16, v17 offset1:1
	v_add_u32_e32 v2, 0x1450, v77
	ds_write2_b32 v2, v26, v27 offset1:1
	v_add_u32_e32 v2, 0x1458, v77
	ds_write2_b32 v2, v28, v29 offset1:1
	v_add_u32_e32 v2, 0x1860, v77
	ds_write2_b32 v2, v22, v23 offset1:1
	v_add_u32_e32 v2, 0x1868, v77
	ds_write2_b32 v2, v24, v25 offset1:1
	v_add_u32_e32 v2, 0x1c70, v77
	ds_write2_b32 v2, v34, v35 offset1:1
	v_add_u32_e32 v2, 0x1c78, v77
	ds_write2_b32 v2, v36, v37 offset1:1
	v_add_u32_e32 v2, 0x2080, v77
	ds_write2_b32 v2, v30, v31 offset1:1
	v_add_u32_e32 v2, 0x2088, v77
	ds_write2_b32 v2, v32, v33 offset1:1
	v_add_u32_e32 v2, 0x2490, v77
	ds_write2_b32 v2, v42, v43 offset1:1
	v_add_u32_e32 v2, 0x2498, v77
	ds_write2_b32 v2, v44, v45 offset1:1
	v_add_u32_e32 v2, 0x28a0, v77
	ds_write2_b32 v2, v38, v39 offset1:1
	v_add_u32_e32 v2, 0x28a8, v77
	ds_write2_b32 v2, v40, v41 offset1:1
	v_add_u32_e32 v2, 0x2cb0, v77
	ds_write2_b32 v2, v50, v51 offset1:1
	v_add_u32_e32 v2, 0x2cb8, v77
	ds_write2_b32 v2, v52, v53 offset1:1
	v_add_u32_e32 v2, 0x30c0, v77
	ds_write2_b32 v2, v46, v47 offset1:1
	v_add_u32_e32 v2, 0x30c8, v77
	ds_write2_b32 v2, v48, v49 offset1:1
	v_add_u32_e32 v2, 0x34d0, v77
	ds_write2_b32 v2, v58, v59 offset1:1
	v_add_u32_e32 v2, 0x34d8, v77
	ds_write2_b32 v2, v60, v61 offset1:1
	v_add_u32_e32 v2, 0x38e0, v77
	ds_write2_b32 v2, v54, v55 offset1:1
	v_add_u32_e32 v2, 0x38e8, v77
	ds_write2_b32 v2, v56, v57 offset1:1
	v_add_u32_e32 v2, 0x3cf0, v77
	ds_write2_b32 v2, v62, v63 offset1:1
	v_add_u32_e32 v2, 0x3cf8, v77
	ds_write2_b32 v2, v64, v65 offset1:1
	s_waitcnt lgkmcnt(0)
	ds_read2_b32 v[10:11], v76 offset1:8
	ds_read2_b32 v[12:13], v76 offset0:65 offset1:73
	ds_read2_b32 v[14:15], v76 offset0:130 offset1:138
	ds_read2_b32 v[16:17], v76 offset0:195 offset1:203
	v_add_u32_e32 v28, 0x400, v76
	s_waitcnt lgkmcnt(3)
	s_nop 1
	s_waitcnt lgkmcnt(2)
	s_nop 0
	ds_read2_b32 v[18:19], v28 offset0:4 offset1:12
	s_nop 1
	ds_read2_b32 v[20:21], v28 offset0:69 offset1:77
	v_cvt_pk_bf16_f32 v6, v10, v12
	s_waitcnt lgkmcnt(3)
	s_nop 1
	s_waitcnt lgkmcnt(2)
	s_nop 0
	ds_read2_b32 v[22:23], v28 offset0:134 offset1:142
	s_nop 1
	ds_read2_b32 v[24:25], v28 offset0:199 offset1:207
	v_cvt_pk_bf16_f32 v7, v14, v16
	s_waitcnt lgkmcnt(3)
	s_nop 1
	s_waitcnt lgkmcnt(2)
	s_nop 2
	v_cvt_pk_bf16_f32 v8, v18, v20
	s_waitcnt lgkmcnt(1)
	s_nop 1
	s_waitcnt lgkmcnt(0)
	s_nop 2
	s_add_i32 s15, s15, s10
	v_cvt_pk_bf16_f32 v9, v22, v24
	v_add_u32_e32 v4, s15, v75
	s_ashr_i32 s3, s2, 31
	v_ashrrev_i32_e32 v5, 31, v4
	v_lshl_add_u64 v[2:3], s[2:3], 1, v[68:69]
	v_lshlrev_b64 v[26:27], 12, v[4:5]
	v_lshl_add_u64 v[26:27], v[2:3], 0, v[26:27]
	v_bfe_u32 v5, v11, 16, 1
	global_store_dwordx4 v[26:27], v[6:9], off
	v_add3_u32 v5, v11, v5, s13
	v_lshrrev_b32_e32 v5, 16, v5
	v_bfe_u32 v6, v13, 16, 1
	v_add3_u32 v6, v13, v6, s13
	v_and_or_b32 v6, v6, s14, v5
	s_nop 4
	v_cvt_pk_bf16_f32 v7, v15, v17
	s_nop 4
	v_cvt_pk_bf16_f32 v8, v19, v21
	s_nop 0
	v_add_u32_e32 v10, 8, v4
	s_nop 1
	v_ashrrev_i32_e32 v11, 31, v10
	s_nop 1
	v_lshlrev_b64 v[10:11], 12, v[10:11]
	v_cvt_pk_bf16_f32 v9, v23, v25
	ds_read2_b32 v[12:13], v76 offset0:16 offset1:24
	v_lshl_add_u64 v[10:11], v[2:3], 0, v[10:11]
	global_store_dwordx4 v[10:11], v[6:9], off
	ds_read2_b32 v[10:11], v76 offset0:81 offset1:89
	ds_read2_b32 v[14:15], v76 offset0:146 offset1:154
	ds_read2_b32 v[16:17], v76 offset0:211 offset1:219
	s_waitcnt lgkmcnt(3)
	s_nop 1
	s_waitcnt lgkmcnt(2)
	s_nop 0
	ds_read2_b32 v[18:19], v28 offset0:20 offset1:28
	s_nop 1
	ds_read2_b32 v[20:21], v28 offset0:85 offset1:93
	v_cvt_pk_bf16_f32 v6, v12, v10
	s_waitcnt lgkmcnt(3)
; #define LAS __attribute__((address_space(3)))
; #define LDS_WAIT() asm volatile("s_waitcnt lgkmcnt(0)" ::: "memory")
; __device__ __forceinline__ unsigned pk2(float lo, float hi) { return f2bf(lo) | (f2bf(hi) << 16); }
;     ...
;         for (int i = 0; i < 16; ++i) { LAS float* d = scr + (4 * i + kr) * 65 + nq; d[0] = v[i].x; d[1] = v[i].y; d[2] = v[i].z; d[3] = v[i].w; }
;         LDS_WAIT(); asm volatile("" ::: "memory");
;         const int c8 = lane & 7; int d0 = n0;
;         if (ffnmap) { const int bj = n0 >= FFH ? 1 : 0, chn = n0 - FFH * bj; d0 = 256 * (chn >> 7) + 128 * bj + (chn & 127); }
; #pragma unroll
;         for (int j = 0; j < 8; ++j) { const int n = (lane >> 3) + 8 * j; const LAS float* sp = scr + (8 * c8) * 65 + n;
;             v4u o; o.x = pk2(sp[0 * 65], sp[1 * 65]); o.y = pk2(sp[2 * 65], sp[3 * 65]); o.z = pk2(sp[4 * 65], sp[5 * 65]); o.w = pk2(sp[6 * 65], sp[7 * 65]);
;             *(v4u*)(WT + (size_t)(d0 + n) * K + k0 + 8 * c8) = o; }
	s_nop 1
	s_waitcnt lgkmcnt(2)
	s_nop 0
	ds_read2_b32 v[22:23], v28 offset0:150 offset1:158
	s_nop 1
	ds_read2_b32 v[24:25], v28 offset0:215 offset1:223
	v_cvt_pk_bf16_f32 v7, v14, v16
	s_waitcnt lgkmcnt(3)
	s_nop 1
	s_waitcnt lgkmcnt(2)
	s_nop 2
	v_cvt_pk_bf16_f32 v8, v18, v20
	s_waitcnt lgkmcnt(1)
	s_nop 0
	v_add_u32_e32 v26, 16, v4
	s_nop 0
	s_waitcnt lgkmcnt(0)
	s_nop 0
	v_ashrrev_i32_e32 v27, 31, v26
	s_nop 1
	v_lshlrev_b64 v[26:27], 12, v[26:27]
	v_cvt_pk_bf16_f32 v9, v22, v24
	v_lshl_add_u64 v[26:27], v[2:3], 0, v[26:27]
	v_bfe_u32 v5, v13, 16, 1
	global_store_dwordx4 v[26:27], v[6:9], off
	v_add3_u32 v5, v13, v5, s13
	v_lshrrev_b32_e32 v5, 16, v5
	v_bfe_u32 v6, v11, 16, 1
	v_add3_u32 v6, v11, v6, s13
	v_and_or_b32 v6, v6, s14, v5
	s_nop 4
	v_cvt_pk_bf16_f32 v7, v15, v17
	s_nop 4
	v_cvt_pk_bf16_f32 v8, v19, v21
	s_nop 0
	v_add_u32_e32 v10, 24, v4
	s_nop 1
	v_ashrrev_i32_e32 v11, 31, v10
	s_nop 1
	v_lshlrev_b64 v[10:11], 12, v[10:11]
	v_cvt_pk_bf16_f32 v9, v23, v25
	ds_read2_b32 v[12:13], v76 offset0:32 offset1:40
	v_lshl_add_u64 v[10:11], v[2:3], 0, v[10:11]
	global_store_dwordx4 v[10:11], v[6:9], off
	ds_read2_b32 v[10:11], v76 offset0:97 offset1:105
	ds_read2_b32 v[14:15], v76 offset0:162 offset1:170
	ds_read2_b32 v[16:17], v76 offset0:227 offset1:235
	s_waitcnt lgkmcnt(3)
	s_nop 1
	s_waitcnt lgkmcnt(2)
	s_nop 0
	ds_read2_b32 v[18:19], v28 offset0:36 offset1:44
	s_nop 1
	ds_read2_b32 v[20:21], v28 offset0:101 offset1:109
	v_cvt_pk_bf16_f32 v6, v12, v10
	s_waitcnt lgkmcnt(3)
	s_nop 1
	s_waitcnt lgkmcnt(2)
	s_nop 0
	ds_read2_b32 v[22:23], v28 offset0:166 offset1:174
	s_nop 1
	ds_read2_b32 v[24:25], v28 offset0:231 offset1:239
	v_cvt_pk_bf16_f32 v7, v14, v16
	s_waitcnt lgkmcnt(3)
	s_nop 1
	s_waitcnt lgkmcnt(2)
	s_nop 2
	v_cvt_pk_bf16_f32 v8, v18, v20
	s_waitcnt lgkmcnt(1)
	s_nop 0
	v_add_u32_e32 v26, 32, v4
	s_nop 0
	s_waitcnt lgkmcnt(0)
	s_nop 0
	v_ashrrev_i32_e32 v27, 31, v26
	s_nop 1
	v_lshlrev_b64 v[26:27], 12, v[26:27]
	v_cvt_pk_bf16_f32 v9, v22, v24
	v_lshl_add_u64 v[26:27], v[2:3], 0, v[26:27]
	v_bfe_u32 v5, v13, 16, 1
	global_store_dwordx4 v[26:27], v[6:9], off
	v_add3_u32 v5, v13, v5, s13
	v_lshrrev_b32_e32 v5, 16, v5
	v_bfe_u32 v6, v11, 16, 1
	v_add3_u32 v6, v11, v6, s13
	v_and_or_b32 v6, v6, s14, v5
	s_nop 4
	v_cvt_pk_bf16_f32 v7, v15, v17
	s_nop 4
	v_cvt_pk_bf16_f32 v8, v19, v21
	s_nop 0
	v_add_u32_e32 v10, 40, v4
	s_nop 1
	v_ashrrev_i32_e32 v11, 31, v10
	s_nop 1
	v_lshlrev_b64 v[10:11], 12, v[10:11]
	v_cvt_pk_bf16_f32 v9, v23, v25
	ds_read2_b32 v[12:13], v76 offset0:48 offset1:56
	v_lshl_add_u64 v[10:11], v[2:3], 0, v[10:11]
	global_store_dwordx4 v[10:11], v[6:9], off
	ds_read2_b32 v[10:11], v76 offset0:113 offset1:121
	ds_read2_b32 v[14:15], v76 offset0:178 offset1:186
	ds_read2_b32 v[16:17], v76 offset0:243 offset1:251
	s_waitcnt lgkmcnt(3)
	s_nop 1
	s_waitcnt lgkmcnt(2)
	s_nop 0
	ds_read2_b32 v[18:19], v28 offset0:52 offset1:60
	s_nop 1
	ds_read2_b32 v[20:21], v28 offset0:117 offset1:125
	v_cvt_pk_bf16_f32 v6, v12, v10
	s_waitcnt lgkmcnt(3)
	s_nop 1
	s_waitcnt lgkmcnt(2)
	s_nop 0
	ds_read2_b32 v[22:23], v28 offset0:182 offset1:190
	s_nop 1
	ds_read2_b32 v[24:25], v28 offset0:247 offset1:255
	v_cvt_pk_bf16_f32 v7, v14, v16
	s_waitcnt lgkmcnt(3)
	s_nop 1
	s_waitcnt lgkmcnt(2)
	s_nop 2
	v_cvt_pk_bf16_f32 v8, v18, v20
	s_waitcnt lgkmcnt(1)
	s_nop 0
	v_add_u32_e32 v26, 48, v4
	s_nop 0
	s_waitcnt lgkmcnt(0)
	s_nop 0
	v_ashrrev_i32_e32 v27, 31, v26
	s_nop 1
	v_lshlrev_b64 v[26:27], 12, v[26:27]
	v_cvt_pk_bf16_f32 v9, v22, v24
	v_lshl_add_u64 v[26:27], v[2:3], 0, v[26:27]
	v_bfe_u32 v5, v13, 16, 1
	global_store_dwordx4 v[26:27], v[6:9], off
	v_add3_u32 v5, v13, v5, s13
	v_lshrrev_b32_e32 v5, 16, v5
	v_bfe_u32 v6, v11, 16, 1
	v_add3_u32 v6, v11, v6, s13
	v_and_or_b32 v6, v6, s14, v5
	s_nop 4
	v_cvt_pk_bf16_f32 v7, v15, v17
	s_nop 4
	v_cvt_pk_bf16_f32 v8, v19, v21
	s_nop 4
	v_add_u32_e32 v4, 56, v4
	v_cvt_pk_bf16_f32 v9, v23, v25
	v_ashrrev_i32_e32 v5, 31, v4
	v_lshlrev_b64 v[4:5], 12, v[4:5]
	v_lshl_add_u64 v[2:3], v[2:3], 0, v[4:5]
	global_store_dwordx4 v[2:3], v[6:9], off
	s_waitcnt lgkmcnt(0)
	s_add_i32 s9, s9, s86
	s_add_i32 s10, s10, s11
	s_cmpk_lt_i32 s9, 0x200
	s_cbranch_scc0 .LBB0_150

; #define LAS __attribute__((address_space(3)))
; #define LDS_WAIT() asm volatile("s_waitcnt lgkmcnt(0)" ::: "memory")
; __device__ __forceinline__ unsigned pk2(float lo, float hi) { return f2bf(lo) | (f2bf(hi) << 16); }
;     ...
;         const int kb = it / nblk, nb = it % nblk, k0 = 64 * kb, n0 = 64 * nb, nq = (lane & 15) * 4, kr = lane >> 4; const bool ok = (n0 + nq) < N;
;         f32x4 v[16];
; #pragma unroll
;         for (int i = 0; i < 16; ++i) v[i] = ok ? __builtin_nontemporal_load((const f32x4*)(W + (size_t)(k0 + 4 * i + kr) * N + n0 + nq)) : (f32x4){0.f, 0.f, 0.f, 0.f};
;         if (gain) {
; #pragma unroll
;             for (int i = 0; i < 16; ++i) v[i] *= gain[k0 + 4 * i + kr]; }
; #pragma unroll
;         for (int i = 0; i < 16; ++i) { LAS float* d = scr + (4 * i + kr) * 65 + nq; d[0] = v[i].x; d[1] = v[i].y; d[2] = v[i].z; d[3] = v[i].w; }
;         LDS_WAIT(); asm volatile("" ::: "memory");
;         const int c8 = lane & 7; int d0 = n0;
;         if (ffnmap) { const int bj = n0 >= FFH ? 1 : 0, chn = n0 - FFH * bj; d0 = 256 * (chn >> 7) + 128 * bj + (chn & 127); }
; #pragma unroll
;         for (int j = 0; j < 8; ++j) { const int n = (lane >> 3) + 8 * j; const LAS float* sp = scr + (8 * c8) * 65 + n;
;             v4u o; o.x = pk2(sp[0 * 65], sp[1 * 65]); o.y = pk2(sp[2 * 65], sp[3 * 65]); o.z = pk2(sp[4 * 65], sp[5 * 65]); o.w = pk2(sp[6 * 65], sp[7 * 65]);
;             *(v4u*)(WT + (size_t)(d0 + n) * K + k0 + 8 * c8) = o; }
.LBB0_152:
	s_or_b64 exec, exec, s[6:7]
	s_waitcnt vmcnt(0)
	ds_write2_b32 v77, v2, v3 offset1:1
	ds_write2_b32 v77, v4, v5 offset0:2 offset1:3
	v_add_u32_e32 v2, 0x410, v77
	ds_write2_b32 v2, v10, v11 offset1:1
	v_add_u32_e32 v2, 0x418, v77
	ds_write2_b32 v2, v12, v13 offset1:1
	v_add_u32_e32 v2, 0x820, v77
	ds_write2_b32 v2, v6, v7 offset1:1
	v_add_u32_e32 v2, 0x828, v77
	ds_write2_b32 v2, v8, v9 offset1:1
	v_add_u32_e32 v2, 0xc30, v77
	ds_write2_b32 v2, v18, v19 offset1:1
	v_add_u32_e32 v2, 0xc38, v77
	ds_write2_b32 v2, v20, v21 offset1:1
	v_add_u32_e32 v2, 0x1040, v77
	ds_write2_b32 v2, v14, v15 offset1:1
	v_add_u32_e32 v2, 0x1048, v77
	ds_write2_b32 v2, v16, v17 offset1:1
	v_add_u32_e32 v2, 0x1450, v77
	ds_write2_b32 v2, v26, v27 offset1:1
	v_add_u32_e32 v2, 0x1458, v77
	ds_write2_b32 v2, v28, v29 offset1:1
	v_add_u32_e32 v2, 0x1860, v77
	ds_write2_b32 v2, v22, v23 offset1:1
	v_add_u32_e32 v2, 0x1868, v77
	ds_write2_b32 v2, v24, v25 offset1:1
	v_add_u32_e32 v2, 0x1c70, v77
	ds_write2_b32 v2, v34, v35 offset1:1
	v_add_u32_e32 v2, 0x1c78, v77
	ds_write2_b32 v2, v36, v37 offset1:1
	v_add_u32_e32 v2, 0x2080, v77
	ds_write2_b32 v2, v30, v31 offset1:1
	v_add_u32_e32 v2, 0x2088, v77
	ds_write2_b32 v2, v32, v33 offset1:1
	v_add_u32_e32 v2, 0x2490, v77
	ds_write2_b32 v2, v42, v43 offset1:1
	v_add_u32_e32 v2, 0x2498, v77
	ds_write2_b32 v2, v44, v45 offset1:1
	v_add_u32_e32 v2, 0x28a0, v77
	ds_write2_b32 v2, v38, v39 offset1:1
	v_add_u32_e32 v2, 0x28a8, v77
	ds_write2_b32 v2, v40, v41 offset1:1
	v_add_u32_e32 v2, 0x2cb0, v77
	ds_write2_b32 v2, v50, v51 offset1:1
	v_add_u32_e32 v2, 0x2cb8, v77
	ds_write2_b32 v2, v52, v53 offset1:1
	v_add_u32_e32 v2, 0x30c0, v77
	ds_write2_b32 v2, v46, v47 offset1:1
	v_add_u32_e32 v2, 0x30c8, v77
	ds_write2_b32 v2, v48, v49 offset1:1
	v_add_u32_e32 v2, 0x34d0, v77
	ds_write2_b32 v2, v58, v59 offset1:1
	v_add_u32_e32 v2, 0x34d8, v77
	ds_write2_b32 v2, v60, v61 offset1:1
	v_add_u32_e32 v2, 0x38e0, v77
	ds_write2_b32 v2, v54, v55 offset1:1
	v_add_u32_e32 v2, 0x38e8, v77
	ds_write2_b32 v2, v56, v57 offset1:1
	v_add_u32_e32 v2, 0x3cf0, v77
	ds_write2_b32 v2, v62, v63 offset1:1
	v_add_u32_e32 v2, 0x3cf8, v77
	ds_write2_b32 v2, v64, v65 offset1:1
	s_waitcnt lgkmcnt(0)
	ds_read2_b32 v[10:11], v76 offset1:8
	ds_read2_b32 v[12:13], v76 offset0:65 offset1:73
	ds_read2_b32 v[14:15], v76 offset0:130 offset1:138
	ds_read2_b32 v[16:17], v76 offset0:195 offset1:203
	v_add_u32_e32 v28, 0x400, v76
	s_waitcnt lgkmcnt(3)
	s_nop 1
	s_waitcnt lgkmcnt(2)
	s_nop 0
	ds_read2_b32 v[18:19], v28 offset0:4 offset1:12
	s_nop 1
	ds_read2_b32 v[20:21], v28 offset0:69 offset1:77
	v_cvt_pk_bf16_f32 v6, v10, v12
	s_waitcnt lgkmcnt(3)
	s_nop 1
	s_waitcnt lgkmcnt(2)
	s_nop 0
	ds_read2_b32 v[22:23], v28 offset0:134 offset1:142
	s_nop 1
	ds_read2_b32 v[24:25], v28 offset0:199 offset1:207
	v_cvt_pk_bf16_f32 v7, v14, v16
	s_waitcnt lgkmcnt(3)
	s_nop 1
	s_waitcnt lgkmcnt(2)
	s_nop 2
	v_cvt_pk_bf16_f32 v8, v18, v20
	s_waitcnt lgkmcnt(1)
	s_nop 1
	s_waitcnt lgkmcnt(0)
	s_nop 2
	s_add_i32 s15, s15, s10
	v_cvt_pk_bf16_f32 v9, v22, v24
	v_add_u32_e32 v4, s15, v75
	s_ashr_i32 s3, s2, 31
	v_ashrrev_i32_e32 v5, 31, v4
	v_lshl_add_u64 v[2:3], s[2:3], 1, v[68:69]
	v_lshlrev_b64 v[26:27], 10, v[4:5]
	v_lshl_add_u64 v[26:27], v[2:3], 0, v[26:27]
	v_bfe_u32 v5, v11, 16, 1
	global_store_dwordx4 v[26:27], v[6:9], off
	v_add3_u32 v5, v11, v5, s13
	v_lshrrev_b32_e32 v5, 16, v5
	v_bfe_u32 v6, v13, 16, 1
	v_add3_u32 v6, v13, v6, s13
	v_and_or_b32 v6, v6, s14, v5
	s_nop 4
	v_cvt_pk_bf16_f32 v7, v15, v17
	s_nop 4
	v_cvt_pk_bf16_f32 v8, v19, v21
	s_nop 0
	v_add_u32_e32 v10, 8, v4
	s_nop 1
	v_ashrrev_i32_e32 v11, 31, v10
	s_nop 1
	v_lshlrev_b64 v[10:11], 10, v[10:11]
	v_cvt_pk_bf16_f32 v9, v23, v25
	ds_read2_b32 v[12:13], v76 offset0:16 offset1:24
	v_lshl_add_u64 v[10:11], v[2:3], 0, v[10:11]
	global_store_dwordx4 v[10:11], v[6:9], off
	ds_read2_b32 v[10:11], v76 offset0:81 offset1:89
	ds_read2_b32 v[14:15], v76 offset0:146 offset1:154
	ds_read2_b32 v[16:17], v76 offset0:211 offset1:219
	s_waitcnt lgkmcnt(3)
	s_nop 1
	s_waitcnt lgkmcnt(2)
	s_nop 0
	ds_read2_b32 v[18:19], v28 offset0:20 offset1:28
	s_nop 1
	ds_read2_b32 v[20:21], v28 offset0:85 offset1:93
	v_cvt_pk_bf16_f32 v6, v12, v10
	s_waitcnt lgkmcnt(3)
; #define LAS __attribute__((address_space(3)))
; #define LDS_WAIT() asm volatile("s_waitcnt lgkmcnt(0)" ::: "memory")
; __device__ __forceinline__ unsigned pk2(float lo, float hi) { return f2bf(lo) | (f2bf(hi) << 16); }
;     ...
;         for (int j = 0; j < 8; ++j) { const int n = (lane >> 3) + 8 * j; const LAS float* sp = scr + (8 * c8) * 65 + n;
;             v4u o; o.x = pk2(sp[0 * 65], sp[1 * 65]); o.y = pk2(sp[2 * 65], sp[3 * 65]); o.z = pk2(sp[4 * 65], sp[5 * 65]); o.w = pk2(sp[6 * 65], sp[7 * 65]);
;             *(v4u*)(WT + (size_t)(d0 + n) * K + k0 + 8 * c8) = o; }
;         LDS_WAIT(); asm volatile("" ::: "memory");
	s_nop 1
	s_waitcnt lgkmcnt(2)
	s_nop 0
	ds_read2_b32 v[22:23], v28 offset0:150 offset1:158
	s_nop 1
	ds_read2_b32 v[24:25], v28 offset0:215 offset1:223
	v_cvt_pk_bf16_f32 v7, v14, v16
	s_waitcnt lgkmcnt(3)
	s_nop 1
	s_waitcnt lgkmcnt(2)
	s_nop 2
	v_cvt_pk_bf16_f32 v8, v18, v20
	s_waitcnt lgkmcnt(1)
	s_nop 0
	v_add_u32_e32 v26, 16, v4
	s_nop 0
	s_waitcnt lgkmcnt(0)
	s_nop 0
	v_ashrrev_i32_e32 v27, 31, v26
	s_nop 1
	v_lshlrev_b64 v[26:27], 10, v[26:27]
	v_cvt_pk_bf16_f32 v9, v22, v24
	v_lshl_add_u64 v[26:27], v[2:3], 0, v[26:27]
	v_bfe_u32 v5, v13, 16, 1
	global_store_dwordx4 v[26:27], v[6:9], off
	v_add3_u32 v5, v13, v5, s13
	v_lshrrev_b32_e32 v5, 16, v5
	v_bfe_u32 v6, v11, 16, 1
	v_add3_u32 v6, v11, v6, s13
	v_and_or_b32 v6, v6, s14, v5
	s_nop 4
	v_cvt_pk_bf16_f32 v7, v15, v17
	s_nop 4
	v_cvt_pk_bf16_f32 v8, v19, v21
	s_nop 0
	v_add_u32_e32 v10, 24, v4
	s_nop 1
	v_ashrrev_i32_e32 v11, 31, v10
	s_nop 1
	v_lshlrev_b64 v[10:11], 10, v[10:11]
	v_cvt_pk_bf16_f32 v9, v23, v25
	ds_read2_b32 v[12:13], v76 offset0:32 offset1:40
	v_lshl_add_u64 v[10:11], v[2:3], 0, v[10:11]
	global_store_dwordx4 v[10:11], v[6:9], off
	ds_read2_b32 v[10:11], v76 offset0:97 offset1:105
	ds_read2_b32 v[14:15], v76 offset0:162 offset1:170
	ds_read2_b32 v[16:17], v76 offset0:227 offset1:235
	s_waitcnt lgkmcnt(3)
	s_nop 1
	s_waitcnt lgkmcnt(2)
	s_nop 0
	ds_read2_b32 v[18:19], v28 offset0:36 offset1:44
	s_nop 1
	ds_read2_b32 v[20:21], v28 offset0:101 offset1:109
	v_cvt_pk_bf16_f32 v6, v12, v10
	s_waitcnt lgkmcnt(3)
	s_nop 1
	s_waitcnt lgkmcnt(2)
	s_nop 0
	ds_read2_b32 v[22:23], v28 offset0:166 offset1:174
	s_nop 1
	ds_read2_b32 v[24:25], v28 offset0:231 offset1:239
	v_cvt_pk_bf16_f32 v7, v14, v16
	s_waitcnt lgkmcnt(3)
	s_nop 1
	s_waitcnt lgkmcnt(2)
	s_nop 2
	v_cvt_pk_bf16_f32 v8, v18, v20
	s_waitcnt lgkmcnt(1)
	s_nop 0
	v_add_u32_e32 v26, 32, v4
	s_nop 0
	s_waitcnt lgkmcnt(0)
	s_nop 0
	v_ashrrev_i32_e32 v27, 31, v26
	s_nop 1
	v_lshlrev_b64 v[26:27], 10, v[26:27]
	v_cvt_pk_bf16_f32 v9, v22, v24
	v_lshl_add_u64 v[26:27], v[2:3], 0, v[26:27]
	v_bfe_u32 v5, v13, 16, 1
	global_store_dwordx4 v[26:27], v[6:9], off
	v_add3_u32 v5, v13, v5, s13
	v_lshrrev_b32_e32 v5, 16, v5
	v_bfe_u32 v6, v11, 16, 1
	v_add3_u32 v6, v11, v6, s13
	v_and_or_b32 v6, v6, s14, v5
	s_nop 4
	v_cvt_pk_bf16_f32 v7, v15, v17
	s_nop 4
	v_cvt_pk_bf16_f32 v8, v19, v21
	s_nop 0
	v_add_u32_e32 v10, 40, v4
	s_nop 1
	v_ashrrev_i32_e32 v11, 31, v10
	s_nop 1
	v_lshlrev_b64 v[10:11], 10, v[10:11]
	v_cvt_pk_bf16_f32 v9, v23, v25
	ds_read2_b32 v[12:13], v76 offset0:48 offset1:56
	v_lshl_add_u64 v[10:11], v[2:3], 0, v[10:11]
	global_store_dwordx4 v[10:11], v[6:9], off
	ds_read2_b32 v[10:11], v76 offset0:113 offset1:121
	ds_read2_b32 v[14:15], v76 offset0:178 offset1:186
	ds_read2_b32 v[16:17], v76 offset0:243 offset1:251
	s_waitcnt lgkmcnt(3)
	s_nop 1
	s_waitcnt lgkmcnt(2)
	s_nop 0
	ds_read2_b32 v[18:19], v28 offset0:52 offset1:60
	s_nop 1
	ds_read2_b32 v[20:21], v28 offset0:117 offset1:125
	v_cvt_pk_bf16_f32 v6, v12, v10
	s_waitcnt lgkmcnt(3)
	s_nop 1
	s_waitcnt lgkmcnt(2)
	s_nop 0
	ds_read2_b32 v[22:23], v28 offset0:182 offset1:190
	s_nop 1
	ds_read2_b32 v[24:25], v28 offset0:247 offset1:255
	v_cvt_pk_bf16_f32 v7, v14, v16
	s_waitcnt lgkmcnt(3)
	s_nop 1
	s_waitcnt lgkmcnt(2)
	s_nop 2
	v_cvt_pk_bf16_f32 v8, v18, v20
	s_waitcnt lgkmcnt(1)
	s_nop 0
	v_add_u32_e32 v26, 48, v4
	s_nop 0
	s_waitcnt lgkmcnt(0)
	s_nop 0
	v_ashrrev_i32_e32 v27, 31, v26
	s_nop 1
	v_lshlrev_b64 v[26:27], 10, v[26:27]
	v_cvt_pk_bf16_f32 v9, v22, v24
	v_lshl_add_u64 v[26:27], v[2:3], 0, v[26:27]
	v_bfe_u32 v5, v13, 16, 1
	global_store_dwordx4 v[26:27], v[6:9], off
	v_add3_u32 v5, v13, v5, s13
	v_lshrrev_b32_e32 v5, 16, v5
	v_bfe_u32 v6, v11, 16, 1
	v_add3_u32 v6, v11, v6, s13
	v_and_or_b32 v6, v6, s14, v5
	s_nop 4
	v_cvt_pk_bf16_f32 v7, v15, v17
	s_nop 4
	v_cvt_pk_bf16_f32 v8, v19, v21
	s_nop 4
	v_add_u32_e32 v4, 56, v4
	v_cvt_pk_bf16_f32 v9, v23, v25
	v_ashrrev_i32_e32 v5, 31, v4
	v_lshlrev_b64 v[4:5], 10, v[4:5]
	v_lshl_add_u64 v[2:3], v[2:3], 0, v[4:5]
	global_store_dwordx4 v[2:3], v[6:9], off
	s_waitcnt lgkmcnt(0)
	s_add_i32 s9, s9, s86
	s_add_i32 s10, s10, s11
	s_cmpk_lt_i32 s9, 0x100
	s_cbranch_scc0 .LBB0_185

; __device__ __forceinline__ unsigned pk2(float lo, float hi) { return f2bf(lo) | (f2bf(hi) << 16); }
; __device__ __forceinline__ void x_to_xb(const Ctx& c, const float* X, bf16* XB, float* RS) {
;     for (int row = c.gw; row < MT; row += c.NGW) {
;         const f32x4* xr = (const f32x4*)(X + (size_t)row * DM) + c.lane; f32x4 v[8]; float s = 0.f;
; #pragma unroll
;         for (int j = 0; j < 8; ++j) { v[j] = xr[64 * j]; s += (v[j].x * v[j].x + v[j].y * v[j].y) + (v[j].z * v[j].z + v[j].w * v[j].w); }
;         const float rs = rsqrtf(wave_sum(s) * (1.f / DM) + EPS); if (c.lane == 0) RS[row] = rs;
;         v2u* o8 = (v2u*)(XB + (size_t)row * DM) + c.lane;
; #pragma unroll
;         for (int j = 0; j < 8; ++j) { v2u o; o.x = pk2(v[j].x, v[j].y); o.y = pk2(v[j].z, v[j].w); o8[64 * j] = o; }
;     }
.LBB0_190:
	s_or_b64 exec, exec, s[12:13]
	s_load_dwordx2 s[12:13], s[52:53], 0x120
	v_bfe_u32 v45, v30, 16, 1
	v_add3_u32 v30, v30, v45, s14
	v_bfe_u32 v45, v31, 16, 1
	v_lshrrev_b32_e32 v30, 16, v30
	v_add3_u32 v31, v31, v45, s14
	v_and_or_b32 v30, v31, s15, v30
	v_bfe_u32 v31, v32, 16, 1
	v_add3_u32 v31, v32, v31, s14
	v_bfe_u32 v32, v33, 16, 1
	s_waitcnt lgkmcnt(0)
	v_lshl_add_u64 v[46:47], s[12:13], 0, v[38:39]
	v_lshrrev_b32_e32 v31, 16, v31
	v_add3_u32 v32, v33, v32, s14
	v_and_or_b32 v31, v32, s15, v31
	v_add_co_u32_e32 v32, vcc, s16, v46
	s_add_i32 s17, s17, s86
	s_nop 0
	v_addc_co_u32_e32 v33, vcc, 0, v47, vcc
	global_store_dwordx2 v[32:33], v[30:31], off
	s_nop 4
	v_cvt_pk_bf16_f32 v26, v26, v27
	v_bfe_u32 v27, v28, 16, 1
	v_add3_u32 v27, v28, v27, s14
	v_bfe_u32 v28, v29, 16, 1
	v_lshrrev_b32_e32 v27, 16, v27
	v_add3_u32 v28, v29, v28, s14
	v_and_or_b32 v27, v28, s15, v27
	global_store_dwordx2 v[32:33], v[26:27], off offset:512
	s_nop 4
	v_cvt_pk_bf16_f32 v22, v22, v23
	v_bfe_u32 v23, v24, 16, 1
	v_add3_u32 v23, v24, v23, s14
	v_bfe_u32 v24, v25, 16, 1
	v_lshrrev_b32_e32 v23, 16, v23
	v_add3_u32 v24, v25, v24, s14
	v_and_or_b32 v23, v24, s15, v23
	global_store_dwordx2 v[32:33], v[22:23], off offset:1024
	s_nop 4
	v_cvt_pk_bf16_f32 v18, v18, v19
	v_bfe_u32 v19, v20, 16, 1
	v_add3_u32 v19, v20, v19, s14
	v_bfe_u32 v20, v21, 16, 1
	v_lshrrev_b32_e32 v19, 16, v19
	v_add3_u32 v20, v21, v20, s14
	v_and_or_b32 v19, v20, s15, v19
	global_store_dwordx2 v[32:33], v[18:19], off offset:1536
	s_nop 4
	v_cvt_pk_bf16_f32 v14, v14, v15
	v_bfe_u32 v15, v16, 16, 1
	v_add3_u32 v15, v16, v15, s14
	v_bfe_u32 v16, v17, 16, 1
	v_lshrrev_b32_e32 v15, 16, v15
	v_add3_u32 v16, v17, v16, s14
	v_and_or_b32 v15, v16, s15, v15
	global_store_dwordx2 v[32:33], v[14:15], off offset:2048
	s_nop 4
	v_cvt_pk_bf16_f32 v10, v10, v11
	v_bfe_u32 v11, v12, 16, 1
	v_add3_u32 v11, v12, v11, s14
	v_bfe_u32 v12, v13, 16, 1
	v_lshrrev_b32_e32 v11, 16, v11
	v_add3_u32 v12, v13, v12, s14
	v_and_or_b32 v11, v12, s15, v11
	global_store_dwordx2 v[32:33], v[10:11], off offset:2560
	v_bfe_u32 v10, v6, 16, 1
	v_add3_u32 v6, v6, v10, s14
	v_bfe_u32 v10, v7, 16, 1
	v_lshrrev_b32_e32 v6, 16, v6
	v_add3_u32 v7, v7, v10, s14
	v_and_or_b32 v6, v7, s15, v6
	v_bfe_u32 v7, v8, 16, 1
	v_add3_u32 v7, v8, v7, s14
	v_bfe_u32 v8, v9, 16, 1
	v_lshrrev_b32_e32 v7, 16, v7
	v_add3_u32 v8, v9, v8, s14
	v_and_or_b32 v7, v8, s15, v7
	global_store_dwordx2 v[32:33], v[6:7], off offset:3072
	v_bfe_u32 v6, v2, 16, 1
	v_add3_u32 v2, v2, v6, s14
	v_bfe_u32 v6, v3, 16, 1
	v_lshrrev_b32_e32 v2, 16, v2
	v_add3_u32 v3, v3, v6, s14
	v_and_or_b32 v2, v3, s15, v2
	v_bfe_u32 v3, v4, 16, 1
	v_add3_u32 v3, v4, v3, s14
	v_bfe_u32 v4, v5, 16, 1
	s_add_u32 s0, s0, s6
	v_lshrrev_b32_e32 v3, 16, v3
	v_add3_u32 v4, v5, v4, s14
	s_addc_u32 s1, s1, s7
	v_and_or_b32 v3, v4, s15, v3
	v_lshl_add_u64 v[36:37], v[36:37], 0, s[8:9]
	s_cmpk_gt_i32 s17, 0x3fff
	v_lshl_add_u64 v[38:39], v[38:39], 0, s[10:11]
	global_store_dwordx2 v[32:33], v[2:3], off offset:3584
	s_cbranch_scc1 .LBB0_193

; #define LAS __attribute__((address_space(3)))
; #define LDS_WAIT() asm volatile("s_waitcnt lgkmcnt(0)" ::: "memory")
;     ...
;         const int kb = it / nblk, nb = it % nblk, k0 = 64 * kb, n0 = 64 * nb, nq = (lane & 15) * 4, kr = lane >> 4; const bool ok = (n0 + nq) < N;
;         f32x4 v[16];
; #pragma unroll
;         for (int i = 0; i < 16; ++i) v[i] = ok ? __builtin_nontemporal_load((const f32x4*)(W + (size_t)(k0 + 4 * i + kr) * N + n0 + nq)) : (f32x4){0.f, 0.f, 0.f, 0.f};
;         if (gain) {
; #pragma unroll
;             for (int i = 0; i < 16; ++i) v[i] *= gain[k0 + 4 * i + kr]; }
; #pragma unroll
;         for (int i = 0; i < 16; ++i) { LAS float* d = scr + (4 * i + kr) * 65 + nq; d[0] = v[i].x; d[1] = v[i].y; d[2] = v[i].z; d[3] = v[i].w; }
;         LDS_WAIT(); asm volatile("" ::: "memory");
;         const int c8 = lane & 7; int d0 = n0;
;         if (ffnmap) { const int bj = n0 >= FFH ? 1 : 0, chn = n0 - FFH * bj; d0 = 256 * (chn >> 7) + 128 * bj + (chn & 127); }
.LBB0_251:
	s_or_b64 exec, exec, s[14:15]
	v_ashrrev_i32_e32 v71, 31, v70
	v_lshl_add_u64 v[72:73], v[74:75], 2, s[8:9]
	v_lshl_add_u64 v[70:71], v[70:71], 2, s[8:9]
	global_load_dword v72, v[72:73], off
	s_nop 0
	global_load_dword v74, v[70:71], off
	global_load_dword v88, v[70:71], off offset:16
	global_load_dword v90, v[70:71], off offset:32
	global_load_dword v92, v[70:71], off offset:48
	global_load_dword v94, v[70:71], off offset:64
	global_load_dword v96, v[70:71], off offset:80
	global_load_dword v98, v[70:71], off offset:96
	global_load_dword v100, v[70:71], off offset:112
	global_load_dword v102, v[70:71], off offset:128
	global_load_dword v104, v[70:71], off offset:144
	global_load_dword v106, v[70:71], off offset:160
	global_load_dword v108, v[70:71], off offset:176
	global_load_dword v110, v[70:71], off offset:192
	global_load_dword v112, v[70:71], off offset:208
	s_nop 0
	global_load_dword v70, v[70:71], off offset:224
	v_add_u32_e32 v75, 0x820, v86
	v_add_u32_e32 v89, 0xc30, v86
	v_add_u32_e32 v91, 0xc38, v86
	v_add_u32_e32 v93, 0x1040, v86
	v_add_u32_e32 v95, 0x1048, v86
	v_add_u32_e32 v97, 0x1450, v86
	v_add_u32_e32 v99, 0x1458, v86
	v_add_u32_e32 v101, 0x1860, v86
	v_add_u32_e32 v103, 0x1868, v86
	v_add_u32_e32 v71, 0x410, v86
	v_add_u32_e32 v73, 0x418, v86
	v_add_u32_e32 v87, 0x828, v86
	v_add_u32_e32 v105, 0x1c70, v86
	v_add_u32_e32 v107, 0x1c78, v86
	v_add_u32_e32 v109, 0x2080, v86
	s_mulk_i32 s23, 0xff50
	s_add_i32 s13, s22, s23
	s_cmpk_gt_i32 s13, 0x57
	s_cselect_b32 s13, 0xffffea00, 0
	s_cselect_b32 s14, 0x80, 0
	s_add_i32 s13, s13, s17
	s_add_i32 s13, s13, s11
	s_lshl_b32 s11, s13, 1
	s_and_b32 s12, s12, 64
	s_and_b32 s11, s11, 0xffffff00
	s_or_b32 s12, s12, s14
	s_or_b32 s12, s12, s11
	s_ashr_i32 s11, s10, 31
	s_add_i32 s22, s22, s1
	s_add_i32 s17, s17, s18
	s_cmpk_lt_i32 s22, 0x1600
	s_waitcnt vmcnt(14)
	v_pk_mul_f32 v[2:3], v[2:3], v[74:75] op_sel_hi:[1,0]
	v_pk_mul_f32 v[4:5], v[4:5], v[74:75] op_sel_hi:[1,0]
	s_waitcnt vmcnt(13)
	v_pk_mul_f32 v[12:13], v[12:13], v[88:89] op_sel_hi:[1,0]
	v_pk_mul_f32 v[10:11], v[10:11], v[88:89] op_sel_hi:[1,0]
	s_waitcnt vmcnt(12)
	v_pk_mul_f32 v[8:9], v[8:9], v[90:91] op_sel_hi:[1,0]
	v_pk_mul_f32 v[6:7], v[6:7], v[90:91] op_sel_hi:[1,0]
	s_waitcnt vmcnt(11)
	v_pk_mul_f32 v[20:21], v[20:21], v[92:93] op_sel_hi:[1,0]
	v_pk_mul_f32 v[18:19], v[18:19], v[92:93] op_sel_hi:[1,0]
	s_waitcnt vmcnt(10)
	v_pk_mul_f32 v[16:17], v[16:17], v[94:95] op_sel_hi:[1,0]
	v_pk_mul_f32 v[14:15], v[14:15], v[94:95] op_sel_hi:[1,0]
	s_waitcnt vmcnt(9)
	v_pk_mul_f32 v[28:29], v[28:29], v[96:97] op_sel_hi:[1,0]
	v_pk_mul_f32 v[26:27], v[26:27], v[96:97] op_sel_hi:[1,0]
	s_waitcnt vmcnt(8)
	v_pk_mul_f32 v[24:25], v[24:25], v[98:99] op_sel_hi:[1,0]
	v_pk_mul_f32 v[22:23], v[22:23], v[98:99] op_sel_hi:[1,0]
	s_waitcnt vmcnt(7)
	v_pk_mul_f32 v[36:37], v[36:37], v[100:101] op_sel_hi:[1,0]
	v_pk_mul_f32 v[34:35], v[34:35], v[100:101] op_sel_hi:[1,0]
	s_waitcnt vmcnt(6)
	v_pk_mul_f32 v[32:33], v[32:33], v[102:103] op_sel_hi:[1,0]
	v_pk_mul_f32 v[30:31], v[30:31], v[102:103] op_sel_hi:[1,0]
	ds_write2_b32 v86, v2, v3 offset1:1
	ds_write2_b32 v86, v4, v5 offset0:2 offset1:3
	ds_write2_b32 v71, v10, v11 offset1:1
	ds_write2_b32 v73, v12, v13 offset1:1
	ds_write2_b32 v75, v6, v7 offset1:1
	ds_write2_b32 v87, v8, v9 offset1:1
	ds_write2_b32 v89, v18, v19 offset1:1
	ds_write2_b32 v91, v20, v21 offset1:1
	ds_write2_b32 v93, v14, v15 offset1:1
	ds_write2_b32 v95, v16, v17 offset1:1
	ds_write2_b32 v97, v26, v27 offset1:1
	ds_write2_b32 v99, v28, v29 offset1:1
	ds_write2_b32 v101, v22, v23 offset1:1
	ds_write2_b32 v103, v24, v25 offset1:1
	ds_write2_b32 v105, v34, v35 offset1:1
	ds_write2_b32 v107, v36, v37 offset1:1
	ds_write2_b32 v109, v30, v31 offset1:1
	v_add_u32_e32 v2, 0x2088, v86
	s_waitcnt vmcnt(5)
	v_pk_mul_f32 v[42:43], v[42:43], v[104:105] op_sel_hi:[1,0]
	ds_write2_b32 v2, v32, v33 offset1:1
	v_add_u32_e32 v2, 0x2490, v86
	v_pk_mul_f32 v[44:45], v[44:45], v[104:105] op_sel_hi:[1,0]
	ds_write2_b32 v2, v42, v43 offset1:1
	v_add_u32_e32 v2, 0x2498, v86
	s_waitcnt vmcnt(4)
	v_pk_mul_f32 v[38:39], v[38:39], v[106:107] op_sel_hi:[1,0]
	ds_write2_b32 v2, v44, v45 offset1:1
	v_add_u32_e32 v2, 0x28a0, v86
	v_pk_mul_f32 v[40:41], v[40:41], v[106:107] op_sel_hi:[1,0]
	ds_write2_b32 v2, v38, v39 offset1:1
	v_add_u32_e32 v2, 0x28a8, v86
	s_waitcnt vmcnt(3)
	v_pk_mul_f32 v[50:51], v[50:51], v[108:109] op_sel_hi:[1,0]
	ds_write2_b32 v2, v40, v41 offset1:1
	v_add_u32_e32 v2, 0x2cb0, v86
	v_pk_mul_f32 v[52:53], v[52:53], v[108:109] op_sel_hi:[1,0]
	ds_write2_b32 v2, v50, v51 offset1:1
	v_add_u32_e32 v2, 0x2cb8, v86
	s_waitcnt vmcnt(2)
	v_pk_mul_f32 v[46:47], v[46:47], v[110:111] op_sel_hi:[1,0]
	ds_write2_b32 v2, v52, v53 offset1:1
	v_add_u32_e32 v2, 0x30c0, v86
	v_pk_mul_f32 v[48:49], v[48:49], v[110:111] op_sel_hi:[1,0]
	ds_write2_b32 v2, v46, v47 offset1:1
	v_add_u32_e32 v2, 0x30c8, v86
	s_waitcnt vmcnt(1)
	v_pk_mul_f32 v[58:59], v[58:59], v[112:113] op_sel_hi:[1,0]
	ds_write2_b32 v2, v48, v49 offset1:1
	v_add_u32_e32 v2, 0x34d0, v86
	v_pk_mul_f32 v[60:61], v[60:61], v[112:113] op_sel_hi:[1,0]
	ds_write2_b32 v2, v58, v59 offset1:1
	v_add_u32_e32 v2, 0x34d8, v86
	s_waitcnt vmcnt(0)
	v_pk_mul_f32 v[54:55], v[54:55], v[70:71] op_sel_hi:[1,0]
	ds_write2_b32 v2, v60, v61 offset1:1
	v_add_u32_e32 v2, 0x38e0, v86
	v_pk_mul_f32 v[56:57], v[56:57], v[70:71] op_sel_hi:[1,0]
	ds_write2_b32 v2, v54, v55 offset1:1
	v_add_u32_e32 v2, 0x38e8, v86
	v_pk_mul_f32 v[62:63], v[62:63], v[72:73] op_sel_hi:[1,0]
	ds_write2_b32 v2, v56, v57 offset1:1
	v_add_u32_e32 v2, 0x3cf0, v86
	v_pk_mul_f32 v[64:65], v[64:65], v[72:73] op_sel_hi:[1,0]
	ds_write2_b32 v2, v62, v63 offset1:1
	v_add_u32_e32 v2, 0x3cf8, v86
	ds_write2_b32 v2, v64, v65 offset1:1
	s_waitcnt lgkmcnt(0)
; #define LAS __attribute__((address_space(3)))
; #define LDS_WAIT() asm volatile("s_waitcnt lgkmcnt(0)" ::: "memory")
; __device__ __forceinline__ unsigned pk2(float lo, float hi) { return f2bf(lo) | (f2bf(hi) << 16); }
;     ...
;         const int c8 = lane & 7; int d0 = n0;
;         if (ffnmap) { const int bj = n0 >= FFH ? 1 : 0, chn = n0 - FFH * bj; d0 = 256 * (chn >> 7) + 128 * bj + (chn & 127); }
; #pragma unroll
;         for (int j = 0; j < 8; ++j) { const int n = (lane >> 3) + 8 * j; const LAS float* sp = scr + (8 * c8) * 65 + n;
;             v4u o; o.x = pk2(sp[0 * 65], sp[1 * 65]); o.y = pk2(sp[2 * 65], sp[3 * 65]); o.z = pk2(sp[4 * 65], sp[5 * 65]); o.w = pk2(sp[6 * 65], sp[7 * 65]);
;             *(v4u*)(WT + (size_t)(d0 + n) * K + k0 + 8 * c8) = o; }
;         LDS_WAIT(); asm volatile("" ::: "memory");
	ds_read2_b32 v[8:9], v78 offset1:8
	ds_read2_b32 v[10:11], v78 offset0:65 offset1:73
	ds_read2_b32 v[12:13], v78 offset0:130 offset1:138
	ds_read2_b32 v[14:15], v78 offset0:195 offset1:203
	v_add_u32_e32 v26, 0x400, v78
	s_waitcnt lgkmcnt(3)
	s_nop 1
	s_waitcnt lgkmcnt(2)
	s_nop 0
	ds_read2_b32 v[16:17], v26 offset0:4 offset1:12
	s_nop 1
	ds_read2_b32 v[18:19], v26 offset0:69 offset1:77
	v_cvt_pk_bf16_f32 v4, v8, v10
	s_waitcnt lgkmcnt(3)
	s_nop 1
	s_waitcnt lgkmcnt(2)
	s_nop 0
	ds_read2_b32 v[20:21], v26 offset0:134 offset1:142
	s_nop 1
	ds_read2_b32 v[22:23], v26 offset0:199 offset1:207
	v_cvt_pk_bf16_f32 v5, v12, v14
	s_waitcnt lgkmcnt(3)
	s_nop 1
	s_waitcnt lgkmcnt(2)
	s_nop 2
	v_cvt_pk_bf16_f32 v6, v16, v18
	s_waitcnt lgkmcnt(1)
	s_nop 0
	v_or_b32_e32 v24, s12, v77
	s_nop 0
	s_waitcnt lgkmcnt(0)
	s_nop 0
	v_ashrrev_i32_e32 v25, 31, v24
	v_lshl_add_u64 v[2:3], s[10:11], 1, v[68:69]
	s_nop 1
	v_lshlrev_b64 v[24:25], 12, v[24:25]
	v_cvt_pk_bf16_f32 v7, v20, v22
	v_lshl_add_u64 v[24:25], v[2:3], 0, v[24:25]
	global_store_dwordx4 v[24:25], v[4:7], off
	s_nop 6
	v_cvt_pk_bf16_f32 v4, v9, v11
	s_nop 4
	v_cvt_pk_bf16_f32 v5, v13, v15
	s_nop 4
	v_cvt_pk_bf16_f32 v6, v17, v19
	s_nop 2
	v_cvt_pk_bf16_f32 v7, v21, v23
	v_or_b32_e32 v8, s12, v79
	v_ashrrev_i32_e32 v9, 31, v8
	v_lshlrev_b64 v[8:9], 12, v[8:9]
	ds_read2_b32 v[10:11], v78 offset0:16 offset1:24
	v_lshl_add_u64 v[8:9], v[2:3], 0, v[8:9]
	global_store_dwordx4 v[8:9], v[4:7], off
	ds_read2_b32 v[8:9], v78 offset0:81 offset1:89
	ds_read2_b32 v[12:13], v78 offset0:146 offset1:154
	ds_read2_b32 v[14:15], v78 offset0:211 offset1:219
	s_waitcnt lgkmcnt(3)
	s_nop 1
	s_waitcnt lgkmcnt(2)
	s_nop 0
	ds_read2_b32 v[16:17], v26 offset0:20 offset1:28
	s_nop 1
	ds_read2_b32 v[18:19], v26 offset0:85 offset1:93
	v_cvt_pk_bf16_f32 v4, v10, v8
	s_waitcnt lgkmcnt(3)
	s_nop 1
	s_waitcnt lgkmcnt(2)
	s_nop 0
	ds_read2_b32 v[20:21], v26 offset0:150 offset1:158
	s_nop 1
	ds_read2_b32 v[22:23], v26 offset0:215 offset1:223
	v_cvt_pk_bf16_f32 v5, v12, v14
	s_waitcnt lgkmcnt(3)
	s_nop 1
	s_waitcnt lgkmcnt(2)
	s_nop 2
	v_cvt_pk_bf16_f32 v6, v16, v18
	s_waitcnt lgkmcnt(1)
	s_nop 0
	v_or_b32_e32 v24, s12, v80
	s_nop 0
	s_waitcnt lgkmcnt(0)
	s_nop 0
	v_ashrrev_i32_e32 v25, 31, v24
	s_nop 1
	v_lshlrev_b64 v[24:25], 12, v[24:25]
	v_cvt_pk_bf16_f32 v7, v20, v22
	v_lshl_add_u64 v[24:25], v[2:3], 0, v[24:25]
	global_store_dwordx4 v[24:25], v[4:7], off
	s_nop 6
	v_cvt_pk_bf16_f32 v4, v11, v9
	s_nop 4
	v_cvt_pk_bf16_f32 v5, v13, v15
	s_nop 4
	v_cvt_pk_bf16_f32 v6, v17, v19
	s_nop 2
	v_cvt_pk_bf16_f32 v7, v21, v23
	v_or_b32_e32 v8, s12, v81
	v_ashrrev_i32_e32 v9, 31, v8
	v_lshlrev_b64 v[8:9], 12, v[8:9]
	ds_read2_b32 v[10:11], v78 offset0:32 offset1:40
	v_lshl_add_u64 v[8:9], v[2:3], 0, v[8:9]
	global_store_dwordx4 v[8:9], v[4:7], off
	ds_read2_b32 v[8:9], v78 offset0:97 offset1:105
	ds_read2_b32 v[12:13], v78 offset0:162 offset1:170
	ds_read2_b32 v[14:15], v78 offset0:227 offset1:235
	s_waitcnt lgkmcnt(3)
	s_nop 1
	s_waitcnt lgkmcnt(2)
	s_nop 0
	ds_read2_b32 v[16:17], v26 offset0:36 offset1:44
	s_nop 1
	ds_read2_b32 v[18:19], v26 offset0:101 offset1:109
	v_cvt_pk_bf16_f32 v4, v10, v8
	s_waitcnt lgkmcnt(3)
	s_nop 1
	s_waitcnt lgkmcnt(2)
	s_nop 0
	ds_read2_b32 v[20:21], v26 offset0:166 offset1:174
	s_nop 1
	ds_read2_b32 v[22:23], v26 offset0:231 offset1:239
	v_cvt_pk_bf16_f32 v5, v12, v14
	s_waitcnt lgkmcnt(3)
	s_nop 1
	s_waitcnt lgkmcnt(2)
	s_nop 2
	v_cvt_pk_bf16_f32 v6, v16, v18
	s_waitcnt lgkmcnt(1)
	s_nop 0
	v_or_b32_e32 v24, s12, v82
	s_nop 0
	s_waitcnt lgkmcnt(0)
	s_nop 0
	v_ashrrev_i32_e32 v25, 31, v24
	s_nop 1
	v_lshlrev_b64 v[24:25], 12, v[24:25]
	v_cvt_pk_bf16_f32 v7, v20, v22
	v_lshl_add_u64 v[24:25], v[2:3], 0, v[24:25]
	global_store_dwordx4 v[24:25], v[4:7], off
	s_nop 6
	v_cvt_pk_bf16_f32 v4, v11, v9
	s_nop 4
	v_cvt_pk_bf16_f32 v5, v13, v15
	s_nop 4
	v_cvt_pk_bf16_f32 v6, v17, v19
	s_nop 2
	v_cvt_pk_bf16_f32 v7, v21, v23
	v_or_b32_e32 v8, s12, v83
	v_ashrrev_i32_e32 v9, 31, v8
	v_lshlrev_b64 v[8:9], 12, v[8:9]
	ds_read2_b32 v[10:11], v78 offset0:48 offset1:56
	v_lshl_add_u64 v[8:9], v[2:3], 0, v[8:9]
	global_store_dwordx4 v[8:9], v[4:7], off
	ds_read2_b32 v[8:9], v78 offset0:113 offset1:121
	ds_read2_b32 v[12:13], v78 offset0:178 offset1:186
	ds_read2_b32 v[14:15], v78 offset0:243 offset1:251
	s_waitcnt lgkmcnt(3)
	s_nop 1
	s_waitcnt lgkmcnt(2)
	s_nop 0
	ds_read2_b32 v[16:17], v26 offset0:52 offset1:60
	s_nop 1
	ds_read2_b32 v[18:19], v26 offset0:117 offset1:125
	v_cvt_pk_bf16_f32 v4, v10, v8
	s_waitcnt lgkmcnt(3)
	s_nop 1
	s_waitcnt lgkmcnt(2)
	s_nop 0
	ds_read2_b32 v[20:21], v26 offset0:182 offset1:190
	s_nop 1
	ds_read2_b32 v[22:23], v26 offset0:247 offset1:255
	v_cvt_pk_bf16_f32 v5, v12, v14
	s_waitcnt lgkmcnt(3)
	s_nop 1
	s_waitcnt lgkmcnt(2)
	s_nop 2
	v_cvt_pk_bf16_f32 v6, v16, v18
	s_waitcnt lgkmcnt(1)
	s_nop 0
	v_or_b32_e32 v24, s12, v84
	s_nop 0
	s_waitcnt lgkmcnt(0)
	s_nop 0
	v_ashrrev_i32_e32 v25, 31, v24
	s_nop 1
	v_lshlrev_b64 v[24:25], 12, v[24:25]
	v_cvt_pk_bf16_f32 v7, v20, v22
	v_lshl_add_u64 v[24:25], v[2:3], 0, v[24:25]
	global_store_dwordx4 v[24:25], v[4:7], off
	s_nop 6
	v_cvt_pk_bf16_f32 v4, v11, v9
	s_nop 4
	v_cvt_pk_bf16_f32 v5, v13, v15
	s_nop 4
	v_cvt_pk_bf16_f32 v6, v17, v19
	s_nop 2
	v_cvt_pk_bf16_f32 v7, v21, v23
	v_or_b32_e32 v8, s12, v85
	v_ashrrev_i32_e32 v9, 31, v8
	v_lshlrev_b64 v[8:9], 12, v[8:9]
	v_lshl_add_u64 v[2:3], v[2:3], 0, v[8:9]
	global_store_dwordx4 v[2:3], v[4:7], off
	s_waitcnt lgkmcnt(0)
	s_cbranch_scc0 .LBB0_284

; #define LAS __attribute__((address_space(3)))
; #define LDS_WAIT() asm volatile("s_waitcnt lgkmcnt(0)" ::: "memory")
; __device__ __forceinline__ unsigned pk2(float lo, float hi) { return f2bf(lo) | (f2bf(hi) << 16); }
;     ...
;         for (int i = 0; i < 16; ++i) { LAS float* d = scr + (4 * i + kr) * 65 + nq; d[0] = v[i].x; d[1] = v[i].y; d[2] = v[i].z; d[3] = v[i].w; }
;         LDS_WAIT(); asm volatile("" ::: "memory");
;         const int c8 = lane & 7; int d0 = n0;
;         if (ffnmap) { const int bj = n0 >= FFH ? 1 : 0, chn = n0 - FFH * bj; d0 = 256 * (chn >> 7) + 128 * bj + (chn & 127); }
; #pragma unroll
;         for (int j = 0; j < 8; ++j) { const int n = (lane >> 3) + 8 * j; const LAS float* sp = scr + (8 * c8) * 65 + n;
;             v4u o; o.x = pk2(sp[0 * 65], sp[1 * 65]); o.y = pk2(sp[2 * 65], sp[3 * 65]); o.z = pk2(sp[4 * 65], sp[5 * 65]); o.w = pk2(sp[6 * 65], sp[7 * 65]);
;             *(v4u*)(WT + (size_t)(d0 + n) * K + k0 + 8 * c8) = o; }
.LBB0_286:
	s_or_b64 exec, exec, s[10:11]
	s_waitcnt vmcnt(0)
	ds_write2_b32 v77, v2, v3 offset1:1
	ds_write2_b32 v77, v4, v5 offset0:2 offset1:3
	v_add_u32_e32 v2, 0x410, v77
	ds_write2_b32 v2, v10, v11 offset1:1
	v_add_u32_e32 v2, 0x418, v77
	ds_write2_b32 v2, v12, v13 offset1:1
	v_add_u32_e32 v2, 0x820, v77
	ds_write2_b32 v2, v6, v7 offset1:1
	v_add_u32_e32 v2, 0x828, v77
	ds_write2_b32 v2, v8, v9 offset1:1
	v_add_u32_e32 v2, 0xc30, v77
	ds_write2_b32 v2, v18, v19 offset1:1
	v_add_u32_e32 v2, 0xc38, v77
	ds_write2_b32 v2, v20, v21 offset1:1
	v_add_u32_e32 v2, 0x1040, v77
	ds_write2_b32 v2, v14, v15 offset1:1
	v_add_u32_e32 v2, 0x1048, v77
	ds_write2_b32 v2, v16, v17 offset1:1
	v_add_u32_e32 v2, 0x1450, v77
	ds_write2_b32 v2, v26, v27 offset1:1
	v_add_u32_e32 v2, 0x1458, v77
	ds_write2_b32 v2, v28, v29 offset1:1
	v_add_u32_e32 v2, 0x1860, v77
	ds_write2_b32 v2, v22, v23 offset1:1
	v_add_u32_e32 v2, 0x1868, v77
	ds_write2_b32 v2, v24, v25 offset1:1
	v_add_u32_e32 v2, 0x1c70, v77
	ds_write2_b32 v2, v34, v35 offset1:1
	v_add_u32_e32 v2, 0x1c78, v77
	ds_write2_b32 v2, v36, v37 offset1:1
	v_add_u32_e32 v2, 0x2080, v77
	ds_write2_b32 v2, v30, v31 offset1:1
	v_add_u32_e32 v2, 0x2088, v77
	ds_write2_b32 v2, v32, v33 offset1:1
	v_add_u32_e32 v2, 0x2490, v77
	ds_write2_b32 v2, v42, v43 offset1:1
	v_add_u32_e32 v2, 0x2498, v77
	ds_write2_b32 v2, v44, v45 offset1:1
	v_add_u32_e32 v2, 0x28a0, v77
	ds_write2_b32 v2, v38, v39 offset1:1
	v_add_u32_e32 v2, 0x28a8, v77
	ds_write2_b32 v2, v40, v41 offset1:1
	v_add_u32_e32 v2, 0x2cb0, v77
	ds_write2_b32 v2, v50, v51 offset1:1
	v_add_u32_e32 v2, 0x2cb8, v77
	ds_write2_b32 v2, v52, v53 offset1:1
	v_add_u32_e32 v2, 0x30c0, v77
	ds_write2_b32 v2, v46, v47 offset1:1
	v_add_u32_e32 v2, 0x30c8, v77
	ds_write2_b32 v2, v48, v49 offset1:1
	v_add_u32_e32 v2, 0x34d0, v77
	ds_write2_b32 v2, v58, v59 offset1:1
	v_add_u32_e32 v2, 0x34d8, v77
	ds_write2_b32 v2, v60, v61 offset1:1
	v_add_u32_e32 v2, 0x38e0, v77
	ds_write2_b32 v2, v54, v55 offset1:1
	v_add_u32_e32 v2, 0x38e8, v77
	ds_write2_b32 v2, v56, v57 offset1:1
	v_add_u32_e32 v2, 0x3cf0, v77
	ds_write2_b32 v2, v62, v63 offset1:1
	v_add_u32_e32 v2, 0x3cf8, v77
	ds_write2_b32 v2, v64, v65 offset1:1
	s_waitcnt lgkmcnt(0)
	ds_read2_b32 v[10:11], v75 offset1:8
	ds_read2_b32 v[12:13], v75 offset0:65 offset1:73
	ds_read2_b32 v[14:15], v75 offset0:130 offset1:138
	ds_read2_b32 v[16:17], v75 offset0:195 offset1:203
	v_add_u32_e32 v28, 0x400, v75
	s_waitcnt lgkmcnt(3)
	s_nop 1
	s_waitcnt lgkmcnt(2)
	s_nop 0
	ds_read2_b32 v[18:19], v28 offset0:4 offset1:12
	s_nop 1
	ds_read2_b32 v[20:21], v28 offset0:69 offset1:77
	v_cvt_pk_bf16_f32 v6, v10, v12
	s_waitcnt lgkmcnt(3)
	s_nop 1
	s_waitcnt lgkmcnt(2)
	s_nop 0
	ds_read2_b32 v[22:23], v28 offset0:134 offset1:142
	s_nop 1
	ds_read2_b32 v[24:25], v28 offset0:199 offset1:207
	v_cvt_pk_bf16_f32 v7, v14, v16
	s_waitcnt lgkmcnt(3)
	s_nop 1
	s_waitcnt lgkmcnt(2)
	s_nop 2
	v_cvt_pk_bf16_f32 v8, v18, v20
	s_waitcnt lgkmcnt(1)
	s_nop 1
	s_waitcnt lgkmcnt(0)
	s_nop 2
	s_mul_i32 s17, s17, 0xfea00000
	s_ashr_i32 s9, s8, 31
	v_cvt_pk_bf16_f32 v9, v22, v24
	v_add_u32_e32 v4, s17, v76
	v_lshl_add_u64 v[2:3], s[8:9], 1, v[68:69]
	v_ashrrev_i32_e32 v5, 31, v4
	v_lshl_add_u64 v[26:27], v[2:3], 0, v[4:5]
	v_bfe_u32 v5, v11, 16, 1
	global_store_dwordx4 v[26:27], v[6:9], off
	v_add3_u32 v5, v11, v5, s14
	v_lshrrev_b32_e32 v5, 16, v5
	v_bfe_u32 v6, v13, 16, 1
	v_add3_u32 v6, v13, v6, s14
	v_and_or_b32 v6, v6, s15, v5
	s_nop 4
	v_cvt_pk_bf16_f32 v7, v15, v17
	s_nop 4
	v_cvt_pk_bf16_f32 v8, v19, v21
	s_nop 2
	v_add_u32_e32 v10, 0x16000, v4
	s_nop 1
	v_ashrrev_i32_e32 v11, 31, v10
	v_cvt_pk_bf16_f32 v9, v23, v25
	ds_read2_b32 v[12:13], v75 offset0:16 offset1:24
	v_lshl_add_u64 v[10:11], v[2:3], 0, v[10:11]
	global_store_dwordx4 v[10:11], v[6:9], off
	ds_read2_b32 v[10:11], v75 offset0:81 offset1:89
	ds_read2_b32 v[14:15], v75 offset0:146 offset1:154
	ds_read2_b32 v[16:17], v75 offset0:211 offset1:219
	s_waitcnt lgkmcnt(3)
	s_nop 1
	s_waitcnt lgkmcnt(2)
; #define LAS __attribute__((address_space(3)))
; #define LDS_WAIT() asm volatile("s_waitcnt lgkmcnt(0)" ::: "memory")
; __device__ __forceinline__ unsigned pk2(float lo, float hi) { return f2bf(lo) | (f2bf(hi) << 16); }
;     ...
;         for (int j = 0; j < 8; ++j) { const int n = (lane >> 3) + 8 * j; const LAS float* sp = scr + (8 * c8) * 65 + n;
;             v4u o; o.x = pk2(sp[0 * 65], sp[1 * 65]); o.y = pk2(sp[2 * 65], sp[3 * 65]); o.z = pk2(sp[4 * 65], sp[5 * 65]); o.w = pk2(sp[6 * 65], sp[7 * 65]);
;             *(v4u*)(WT + (size_t)(d0 + n) * K + k0 + 8 * c8) = o; }
;         LDS_WAIT(); asm volatile("" ::: "memory");
	s_nop 0
	ds_read2_b32 v[18:19], v28 offset0:20 offset1:28
	s_nop 1
	ds_read2_b32 v[20:21], v28 offset0:85 offset1:93
	v_cvt_pk_bf16_f32 v6, v12, v10
	s_waitcnt lgkmcnt(3)
	s_nop 1
	s_waitcnt lgkmcnt(2)
	s_nop 0
	ds_read2_b32 v[22:23], v28 offset0:150 offset1:158
	s_nop 1
	ds_read2_b32 v[24:25], v28 offset0:215 offset1:223
	v_cvt_pk_bf16_f32 v7, v14, v16
	s_waitcnt lgkmcnt(3)
	s_nop 1
	s_waitcnt lgkmcnt(2)
	s_nop 2
	v_cvt_pk_bf16_f32 v8, v18, v20
	s_waitcnt lgkmcnt(1)
	s_nop 1
	s_waitcnt lgkmcnt(0)
	s_nop 0
	v_add_u32_e32 v26, 0x2c000, v4
	s_nop 1
	v_ashrrev_i32_e32 v27, 31, v26
	v_cvt_pk_bf16_f32 v9, v22, v24
	v_lshl_add_u64 v[26:27], v[2:3], 0, v[26:27]
	v_bfe_u32 v5, v13, 16, 1
	global_store_dwordx4 v[26:27], v[6:9], off
	v_add3_u32 v5, v13, v5, s14
	v_lshrrev_b32_e32 v5, 16, v5
	v_bfe_u32 v6, v11, 16, 1
	v_add3_u32 v6, v11, v6, s14
	v_and_or_b32 v6, v6, s15, v5
	s_nop 4
	v_cvt_pk_bf16_f32 v7, v15, v17
	s_nop 4
	v_cvt_pk_bf16_f32 v8, v19, v21
	s_nop 2
	v_add_u32_e32 v10, 0x42000, v4
	s_nop 1
	v_ashrrev_i32_e32 v11, 31, v10
	v_cvt_pk_bf16_f32 v9, v23, v25
	ds_read2_b32 v[12:13], v75 offset0:32 offset1:40
	v_lshl_add_u64 v[10:11], v[2:3], 0, v[10:11]
	global_store_dwordx4 v[10:11], v[6:9], off
	ds_read2_b32 v[10:11], v75 offset0:97 offset1:105
	ds_read2_b32 v[14:15], v75 offset0:162 offset1:170
	ds_read2_b32 v[16:17], v75 offset0:227 offset1:235
	s_waitcnt lgkmcnt(3)
	s_nop 1
	s_waitcnt lgkmcnt(2)
	s_nop 0
	ds_read2_b32 v[18:19], v28 offset0:36 offset1:44
	s_nop 1
	ds_read2_b32 v[20:21], v28 offset0:101 offset1:109
	v_cvt_pk_bf16_f32 v6, v12, v10
	s_waitcnt lgkmcnt(3)
	s_nop 1
	s_waitcnt lgkmcnt(2)
	s_nop 0
	ds_read2_b32 v[22:23], v28 offset0:166 offset1:174
	s_nop 1
	ds_read2_b32 v[24:25], v28 offset0:231 offset1:239
	v_cvt_pk_bf16_f32 v7, v14, v16
	s_waitcnt lgkmcnt(3)
	s_nop 1
	s_waitcnt lgkmcnt(2)
	s_nop 2
	v_cvt_pk_bf16_f32 v8, v18, v20
	s_waitcnt lgkmcnt(1)
	s_nop 1
	s_waitcnt lgkmcnt(0)
	s_nop 0
	v_add_u32_e32 v26, 0x58000, v4
	s_nop 1
	v_ashrrev_i32_e32 v27, 31, v26
	v_cvt_pk_bf16_f32 v9, v22, v24
	v_lshl_add_u64 v[26:27], v[2:3], 0, v[26:27]
	v_bfe_u32 v5, v13, 16, 1
	global_store_dwordx4 v[26:27], v[6:9], off
	v_add3_u32 v5, v13, v5, s14
	v_lshrrev_b32_e32 v5, 16, v5
	v_bfe_u32 v6, v11, 16, 1
	v_add3_u32 v6, v11, v6, s14
	v_and_or_b32 v6, v6, s15, v5
	s_nop 4
	v_cvt_pk_bf16_f32 v7, v15, v17
	s_nop 4
	v_cvt_pk_bf16_f32 v8, v19, v21
	s_nop 2
	v_add_u32_e32 v10, 0x6e000, v4
	s_nop 1
	v_ashrrev_i32_e32 v11, 31, v10
	v_cvt_pk_bf16_f32 v9, v23, v25
	ds_read2_b32 v[12:13], v75 offset0:48 offset1:56
	v_lshl_add_u64 v[10:11], v[2:3], 0, v[10:11]
	global_store_dwordx4 v[10:11], v[6:9], off
	ds_read2_b32 v[10:11], v75 offset0:113 offset1:121
	ds_read2_b32 v[14:15], v75 offset0:178 offset1:186
	ds_read2_b32 v[16:17], v75 offset0:243 offset1:251
	s_waitcnt lgkmcnt(3)
	s_nop 1
	s_waitcnt lgkmcnt(2)
	s_nop 0
	ds_read2_b32 v[18:19], v28 offset0:52 offset1:60
	s_nop 1
	ds_read2_b32 v[20:21], v28 offset0:117 offset1:125
	v_cvt_pk_bf16_f32 v6, v12, v10
	s_waitcnt lgkmcnt(3)
	s_nop 1
	s_waitcnt lgkmcnt(2)
	s_nop 0
	ds_read2_b32 v[22:23], v28 offset0:182 offset1:190
	s_nop 1
	ds_read2_b32 v[24:25], v28 offset0:247 offset1:255
	v_cvt_pk_bf16_f32 v7, v14, v16
	s_waitcnt lgkmcnt(3)
	s_nop 1
	s_waitcnt lgkmcnt(2)
	s_nop 2
	v_cvt_pk_bf16_f32 v8, v18, v20
	s_waitcnt lgkmcnt(1)
	s_nop 1
	s_waitcnt lgkmcnt(0)
	s_nop 0
	v_add_u32_e32 v26, 0x84000, v4
	s_nop 1
	v_ashrrev_i32_e32 v27, 31, v26
	v_cvt_pk_bf16_f32 v9, v22, v24
	v_lshl_add_u64 v[26:27], v[2:3], 0, v[26:27]
	v_bfe_u32 v5, v13, 16, 1
	global_store_dwordx4 v[26:27], v[6:9], off
	v_add3_u32 v5, v13, v5, s14
	v_lshrrev_b32_e32 v5, 16, v5
	v_bfe_u32 v6, v11, 16, 1
	v_add3_u32 v6, v11, v6, s14
	v_and_or_b32 v6, v6, s15, v5
	s_nop 4
	v_cvt_pk_bf16_f32 v7, v15, v17
	s_nop 4
	v_cvt_pk_bf16_f32 v8, v19, v21
	s_nop 4
	v_add_u32_e32 v4, 0x9a000, v4
	v_cvt_pk_bf16_f32 v9, v23, v25
	v_ashrrev_i32_e32 v5, 31, v4
	v_lshl_add_u64 v[2:3], v[2:3], 0, v[4:5]
	global_store_dwordx4 v[2:3], v[6:9], off
	s_waitcnt lgkmcnt(0)
	s_add_i32 s0, s0, s1
	s_add_i32 s12, s12, s13
	s_mul_i32 s8, s1, 0xb0000
	s_cmpk_lt_i32 s0, 0xb00
	v_add_u32_e32 v76, s8, v76
	s_cbranch_scc0 .LBB0_319

; #define LAS __attribute__((address_space(3)))
;     ...
;         const int kb = it / nblk, nb = it % nblk, k0 = 64 * kb, n0 = 64 * nb, nq = (lane & 15) * 4, kr = lane >> 4; const bool ok = (n0 + nq) < N;
;         f32x4 v[16];
; #pragma unroll
;         for (int i = 0; i < 16; ++i) v[i] = ok ? __builtin_nontemporal_load((const f32x4*)(W + (size_t)(k0 + 4 * i + kr) * N + n0 + nq)) : (f32x4){0.f, 0.f, 0.f, 0.f};
;         if (gain) {
; #pragma unroll
;             for (int i = 0; i < 16; ++i) v[i] *= gain[k0 + 4 * i + kr]; }
; #pragma unroll
;         for (int i = 0; i < 16; ++i) { LAS float* d = scr + (4 * i + kr) * 65 + nq; d[0] = v[i].x; d[1] = v[i].y; d[2] = v[i].z; d[3] = v[i].w; }
.LBB0_851:
	s_or_b64 exec, exec, s[10:11]
	v_ashrrev_i32_e32 v73, 31, v72
	v_lshl_add_u64 v[106:107], v[72:73], 2, s[0:1]
	global_load_dword v72, v[106:107], off
	s_ashr_i32 s9, s8, 31
	s_add_i32 s19, s19, s13
	s_add_i32 s14, s14, s15
	s_cmpk_lt_i32 s19, 0xa80
	s_waitcnt vmcnt(0)
	v_pk_mul_f32 v[100:101], v[2:3], v[72:73] op_sel_hi:[1,0]
	global_load_dword v2, v[106:107], off offset:16
	v_pk_mul_f32 v[98:99], v[4:5], v[72:73] op_sel_hi:[1,0]
	global_load_dword v4, v[106:107], off offset:128
	s_waitcnt vmcnt(0)
	v_pk_mul_f32 v[90:91], v[12:13], v[2:3] op_sel_hi:[1,0]
	v_pk_mul_f32 v[94:95], v[10:11], v[2:3] op_sel_hi:[1,0]
	global_load_dword v2, v[106:107], off offset:32
	global_load_dword v10, v[106:107], off offset:160
	s_waitcnt vmcnt(0)
	v_pk_mul_f32 v[86:87], v[8:9], v[2:3] op_sel_hi:[1,0]
	v_pk_mul_f32 v[92:93], v[6:7], v[2:3] op_sel_hi:[1,0]
	global_load_dword v2, v[106:107], off offset:48
	global_load_dword v6, v[106:107], off offset:144
	v_pk_mul_f32 v[8:9], v[44:45], v[10:11] op_sel_hi:[1,0]
	v_pk_mul_f32 v[10:11], v[42:43], v[10:11] op_sel_hi:[1,0]
	s_waitcnt vmcnt(0)
	v_pk_mul_f32 v[82:83], v[20:21], v[2:3] op_sel_hi:[1,0]
	v_pk_mul_f32 v[88:89], v[18:19], v[2:3] op_sel_hi:[1,0]
	global_load_dword v2, v[106:107], off offset:64
	global_load_dword v18, v[106:107], off offset:192
	s_waitcnt vmcnt(0)
	v_pk_mul_f32 v[78:79], v[16:17], v[2:3] op_sel_hi:[1,0]
	v_pk_mul_f32 v[84:85], v[14:15], v[2:3] op_sel_hi:[1,0]
	global_load_dword v2, v[106:107], off offset:80
	global_load_dword v14, v[106:107], off offset:176
	v_pk_mul_f32 v[16:17], v[52:53], v[18:19] op_sel_hi:[1,0]
	v_pk_mul_f32 v[18:19], v[50:51], v[18:19] op_sel_hi:[1,0]
	s_waitcnt vmcnt(0)
	v_pk_mul_f32 v[74:75], v[28:29], v[2:3] op_sel_hi:[1,0]
	v_pk_mul_f32 v[80:81], v[26:27], v[2:3] op_sel_hi:[1,0]
	global_load_dword v2, v[106:107], off offset:96
	global_load_dword v26, v[106:107], off offset:224
	v_lshl_add_u64 v[28:29], v[96:97], 2, s[0:1]
	v_pk_mul_f32 v[12:13], v[56:57], v[14:15] op_sel_hi:[1,0]
	v_pk_mul_f32 v[14:15], v[54:55], v[14:15] op_sel_hi:[1,0]
	s_waitcnt vmcnt(0)
	v_pk_mul_f32 v[72:73], v[24:25], v[2:3] op_sel_hi:[1,0]
	v_pk_mul_f32 v[76:77], v[22:23], v[2:3] op_sel_hi:[1,0]
	global_load_dword v2, v[106:107], off offset:112
	global_load_dword v22, v[106:107], off offset:208
	v_pk_mul_f32 v[24:25], v[60:61], v[26:27] op_sel_hi:[1,0]
	v_pk_mul_f32 v[26:27], v[58:59], v[26:27] op_sel_hi:[1,0]
	s_waitcnt vmcnt(0)
	v_pk_mul_f32 v[36:37], v[36:37], v[2:3] op_sel_hi:[1,0]
	v_pk_mul_f32 v[34:35], v[34:35], v[2:3] op_sel_hi:[1,0]
	v_pk_mul_f32 v[2:3], v[32:33], v[4:5] op_sel_hi:[1,0]
	v_pk_mul_f32 v[32:33], v[30:31], v[4:5] op_sel_hi:[1,0]
	global_load_dword v30, v[28:29], off
	ds_write2_b32 v104, v100, v101 offset1:1
	ds_write2_b32 v104, v98, v99 offset0:2 offset1:3
	v_pk_mul_f32 v[4:5], v[48:49], v[6:7] op_sel_hi:[1,0]
	v_pk_mul_f32 v[6:7], v[46:47], v[6:7] op_sel_hi:[1,0]
	v_pk_mul_f32 v[20:21], v[64:65], v[22:23] op_sel_hi:[1,0]
	v_pk_mul_f32 v[22:23], v[62:63], v[22:23] op_sel_hi:[1,0]
	s_waitcnt vmcnt(0)
	v_pk_mul_f32 v[28:29], v[40:41], v[30:31] op_sel_hi:[1,0]
	v_pk_mul_f32 v[30:31], v[38:39], v[30:31] op_sel_hi:[1,0]
	v_add_u32_e32 v38, 0x410, v104
	ds_write2_b32 v38, v94, v95 offset1:1
	v_add_u32_e32 v38, 0x418, v104
	ds_write2_b32 v38, v90, v91 offset1:1
	v_add_u32_e32 v38, 0x820, v104
	ds_write2_b32 v38, v92, v93 offset1:1
	v_add_u32_e32 v38, 0x828, v104
	ds_write2_b32 v38, v86, v87 offset1:1
	v_add_u32_e32 v38, 0xc30, v104
	ds_write2_b32 v38, v88, v89 offset1:1
	v_add_u32_e32 v38, 0xc38, v104
	ds_write2_b32 v38, v82, v83 offset1:1
	v_add_u32_e32 v38, 0x1040, v104
	ds_write2_b32 v38, v84, v85 offset1:1
	v_add_u32_e32 v38, 0x1048, v104
	ds_write2_b32 v38, v78, v79 offset1:1
	v_add_u32_e32 v38, 0x1450, v104
	ds_write2_b32 v38, v80, v81 offset1:1
	v_add_u32_e32 v38, 0x1458, v104
	ds_write2_b32 v38, v74, v75 offset1:1
	v_add_u32_e32 v38, 0x1860, v104
	ds_write2_b32 v38, v76, v77 offset1:1
	v_add_u32_e32 v38, 0x1868, v104
	ds_write2_b32 v38, v72, v73 offset1:1
	v_add_u32_e32 v38, 0x1c70, v104
	ds_write2_b32 v38, v34, v35 offset1:1
	v_add_u32_e32 v34, 0x1c78, v104
	ds_write2_b32 v34, v36, v37 offset1:1
	v_add_u32_e32 v34, 0x2080, v104
	ds_write2_b32 v34, v32, v33 offset1:1
	v_add_u32_e32 v32, 0x2088, v104
	ds_write2_b32 v32, v2, v3 offset1:1
	v_add_u32_e32 v2, 0x2490, v104
	ds_write2_b32 v2, v6, v7 offset1:1
	v_add_u32_e32 v2, 0x2498, v104
	ds_write2_b32 v2, v4, v5 offset1:1
	v_add_u32_e32 v2, 0x28a0, v104
	ds_write2_b32 v2, v10, v11 offset1:1
	v_add_u32_e32 v2, 0x28a8, v104
	ds_write2_b32 v2, v8, v9 offset1:1
	v_add_u32_e32 v2, 0x2cb0, v104
	ds_write2_b32 v2, v14, v15 offset1:1
	v_add_u32_e32 v2, 0x2cb8, v104
	ds_write2_b32 v2, v12, v13 offset1:1
	v_add_u32_e32 v2, 0x30c0, v104
	ds_write2_b32 v2, v18, v19 offset1:1
	v_add_u32_e32 v2, 0x30c8, v104
	ds_write2_b32 v2, v16, v17 offset1:1
	v_add_u32_e32 v2, 0x34d0, v104
	ds_write2_b32 v2, v22, v23 offset1:1
	v_add_u32_e32 v2, 0x34d8, v104
	ds_write2_b32 v2, v20, v21 offset1:1
	v_add_u32_e32 v2, 0x38e0, v104
	ds_write2_b32 v2, v26, v27 offset1:1
	v_add_u32_e32 v2, 0x38e8, v104
	ds_write2_b32 v2, v24, v25 offset1:1
	v_add_u32_e32 v2, 0x3cf0, v104
	ds_write2_b32 v2, v30, v31 offset1:1
	v_add_u32_e32 v2, 0x3cf8, v104
	ds_write2_b32 v2, v28, v29 offset1:1
	s_waitcnt lgkmcnt(0)
	ds_read2_b32 v[6:7], v103 offset0:65 offset1:73
	ds_read2_b32 v[12:13], v103 offset1:8
	ds_read2_b32 v[14:15], v103 offset0:130 offset1:138
	ds_read2_b32 v[16:17], v103 offset0:195 offset1:203
	v_lshl_add_u64 v[2:3], s[8:9], 1, v[70:71]
	s_waitcnt lgkmcnt(0)
; #define LAS __attribute__((address_space(3)))
; #define LDS_WAIT() asm volatile("s_waitcnt lgkmcnt(0)" ::: "memory")
; __device__ __forceinline__ unsigned pk2(float lo, float hi) { return f2bf(lo) | (f2bf(hi) << 16); }
;     ...
;         for (int j = 0; j < 8; ++j) { const int n = (lane >> 3) + 8 * j; const LAS float* sp = scr + (8 * c8) * 65 + n;
;             v4u o; o.x = pk2(sp[0 * 65], sp[1 * 65]); o.y = pk2(sp[2 * 65], sp[3 * 65]); o.z = pk2(sp[4 * 65], sp[5 * 65]); o.w = pk2(sp[6 * 65], sp[7 * 65]);
;             *(v4u*)(WT + (size_t)(d0 + n) * K + k0 + 8 * c8) = o; }
;         LDS_WAIT(); asm volatile("" ::: "memory");
	v_bfe_u32 v5, v6, 16, 1
	v_bfe_u32 v4, v12, 16, 1
	v_add3_u32 v4, v12, v4, s17
	v_add3_u32 v5, v6, v5, s17
	v_add_u32_e32 v6, 0x400, v103
	v_lshrrev_b32_e32 v4, 16, v4
	ds_read2_b32 v[18:19], v6 offset0:4 offset1:12
	ds_read2_b32 v[20:21], v6 offset0:69 offset1:77
	v_and_or_b32 v8, v5, s18, v4
	s_nop 4
	ds_read2_b32 v[22:23], v6 offset0:134 offset1:142
	ds_read2_b32 v[24:25], v6 offset0:199 offset1:207
	v_cvt_pk_bf16_f32 v9, v14, v16
	s_waitcnt lgkmcnt(3)
	s_nop 1
	s_waitcnt lgkmcnt(2)
	s_nop 2
	v_cvt_pk_bf16_f32 v10, v18, v20
	s_waitcnt lgkmcnt(1)
	s_nop 1
	s_waitcnt lgkmcnt(0)
	s_nop 2
	v_cvt_pk_bf16_f32 v11, v22, v24
	v_add_u32_e32 v4, s6, v102
	v_ashrrev_i32_e32 v5, 31, v4
	v_lshlrev_b64 v[26:27], 12, v[4:5]
	v_lshl_add_u64 v[26:27], v[2:3], 0, v[26:27]
	v_bfe_u32 v5, v13, 16, 1
	global_store_dwordx4 v[26:27], v[8:11], off
	v_add3_u32 v5, v13, v5, s17
	v_lshrrev_b32_e32 v5, 16, v5
	v_bfe_u32 v8, v7, 16, 1
	v_add3_u32 v7, v7, v8, s17
	v_and_or_b32 v8, v7, s18, v5
	s_nop 4
	v_cvt_pk_bf16_f32 v9, v15, v17
	s_nop 4
	v_cvt_pk_bf16_f32 v10, v19, v21
	s_nop 0
	v_add_u32_e32 v12, 8, v4
	s_nop 1
	v_ashrrev_i32_e32 v13, 31, v12
	s_nop 1
	v_lshlrev_b64 v[12:13], 12, v[12:13]
	v_cvt_pk_bf16_f32 v11, v23, v25
	v_lshl_add_u64 v[12:13], v[2:3], 0, v[12:13]
	global_store_dwordx4 v[12:13], v[8:11], off
	ds_read2_b32 v[12:13], v103 offset0:81 offset1:89
	ds_read2_b32 v[14:15], v103 offset0:16 offset1:24
	ds_read2_b32 v[16:17], v103 offset0:146 offset1:154
	ds_read2_b32 v[18:19], v103 offset0:211 offset1:219
	ds_read2_b32 v[20:21], v6 offset0:20 offset1:28
	ds_read2_b32 v[22:23], v6 offset0:85 offset1:93
	ds_read2_b32 v[24:25], v6 offset0:150 offset1:158
	ds_read2_b32 v[26:27], v6 offset0:215 offset1:223
	s_waitcnt lgkmcnt(7)
	s_nop 0
	s_waitcnt lgkmcnt(6)
	s_nop 3
	v_cvt_pk_bf16_f32 v8, v14, v12
	s_waitcnt lgkmcnt(5)
	s_nop 1
	s_waitcnt lgkmcnt(4)
	s_nop 2
	v_cvt_pk_bf16_f32 v9, v16, v18
	s_waitcnt lgkmcnt(3)
	s_nop 1
	s_waitcnt lgkmcnt(2)
	s_nop 2
	v_cvt_pk_bf16_f32 v10, v20, v22
	s_waitcnt lgkmcnt(1)
	s_nop 1
	s_waitcnt lgkmcnt(0)
	s_nop 2
	v_add_u32_e32 v28, 16, v4
	v_cvt_pk_bf16_f32 v11, v24, v26
	v_ashrrev_i32_e32 v29, 31, v28
	v_bfe_u32 v5, v15, 16, 1
	v_lshlrev_b64 v[28:29], 12, v[28:29]
	v_add3_u32 v5, v15, v5, s17
	v_bfe_u32 v7, v13, 16, 1
	v_lshl_add_u64 v[28:29], v[2:3], 0, v[28:29]
	v_lshrrev_b32_e32 v5, 16, v5
	v_add3_u32 v7, v13, v7, s17
	global_store_dwordx4 v[28:29], v[8:11], off
	v_add_u32_e32 v12, 24, v4
	v_ashrrev_i32_e32 v13, 31, v12
	v_and_or_b32 v8, v7, s18, v5
	s_nop 4
	v_cvt_pk_bf16_f32 v9, v17, v19
	s_nop 4
	v_cvt_pk_bf16_f32 v10, v21, v23
	s_nop 4
	v_lshlrev_b64 v[12:13], 12, v[12:13]
	v_cvt_pk_bf16_f32 v11, v25, v27
	v_lshl_add_u64 v[12:13], v[2:3], 0, v[12:13]
	global_store_dwordx4 v[12:13], v[8:11], off
	ds_read2_b32 v[12:13], v103 offset0:97 offset1:105
	ds_read2_b32 v[14:15], v103 offset0:32 offset1:40
	ds_read2_b32 v[16:17], v103 offset0:162 offset1:170
	ds_read2_b32 v[18:19], v103 offset0:227 offset1:235
	ds_read2_b32 v[20:21], v6 offset0:36 offset1:44
	ds_read2_b32 v[22:23], v6 offset0:101 offset1:109
	ds_read2_b32 v[24:25], v6 offset0:166 offset1:174
	ds_read2_b32 v[26:27], v6 offset0:231 offset1:239
	s_waitcnt lgkmcnt(7)
	s_nop 0
	s_waitcnt lgkmcnt(6)
	s_nop 3
	v_cvt_pk_bf16_f32 v8, v14, v12
	s_waitcnt lgkmcnt(5)
	s_nop 1
	s_waitcnt lgkmcnt(4)
	s_nop 2
	v_cvt_pk_bf16_f32 v9, v16, v18
	s_waitcnt lgkmcnt(3)
	s_nop 1
	s_waitcnt lgkmcnt(2)
	s_nop 2
	v_cvt_pk_bf16_f32 v10, v20, v22
	s_waitcnt lgkmcnt(1)
	s_nop 1
	s_waitcnt lgkmcnt(0)
	s_nop 2
	v_add_u32_e32 v28, 32, v4
	v_cvt_pk_bf16_f32 v11, v24, v26
	v_ashrrev_i32_e32 v29, 31, v28
	v_bfe_u32 v5, v15, 16, 1
	v_lshlrev_b64 v[28:29], 12, v[28:29]
	v_add3_u32 v5, v15, v5, s17
	v_bfe_u32 v7, v13, 16, 1
	v_lshl_add_u64 v[28:29], v[2:3], 0, v[28:29]
	v_lshrrev_b32_e32 v5, 16, v5
	v_add3_u32 v7, v13, v7, s17
	global_store_dwordx4 v[28:29], v[8:11], off
	v_add_u32_e32 v12, 40, v4
	v_ashrrev_i32_e32 v13, 31, v12
	v_and_or_b32 v8, v7, s18, v5
	s_nop 4
	v_cvt_pk_bf16_f32 v9, v17, v19
	s_nop 4
	v_cvt_pk_bf16_f32 v10, v21, v23
	s_nop 4
	v_lshlrev_b64 v[12:13], 12, v[12:13]
	v_cvt_pk_bf16_f32 v11, v25, v27
	v_lshl_add_u64 v[12:13], v[2:3], 0, v[12:13]
	global_store_dwordx4 v[12:13], v[8:11], off
	ds_read2_b32 v[12:13], v103 offset0:48 offset1:56
	ds_read2_b32 v[14:15], v103 offset0:113 offset1:121
	ds_read2_b32 v[16:17], v103 offset0:178 offset1:186
	ds_read2_b32 v[18:19], v103 offset0:243 offset1:251
	ds_read2_b32 v[20:21], v6 offset0:52 offset1:60
	ds_read2_b32 v[22:23], v6 offset0:117 offset1:125
	ds_read2_b32 v[24:25], v6 offset0:182 offset1:190
	ds_read2_b32 v[26:27], v6 offset0:247 offset1:255
	s_waitcnt lgkmcnt(7)
	s_nop 1
	s_waitcnt lgkmcnt(6)
	s_nop 2
	v_cvt_pk_bf16_f32 v8, v12, v14
	s_waitcnt lgkmcnt(5)
	s_nop 1
	s_waitcnt lgkmcnt(4)
	s_nop 2
	v_cvt_pk_bf16_f32 v9, v16, v18
	s_waitcnt lgkmcnt(3)
	s_nop 1
	s_waitcnt lgkmcnt(2)
	s_nop 2
	v_cvt_pk_bf16_f32 v10, v20, v22
	s_waitcnt lgkmcnt(1)
	s_nop 1
	s_waitcnt lgkmcnt(0)
	s_nop 2
	v_cvt_pk_bf16_f32 v11, v24, v26
	v_add_u32_e32 v6, 48, v4
	v_ashrrev_i32_e32 v7, 31, v6
	v_lshlrev_b64 v[6:7], 12, v[6:7]
	v_lshl_add_u64 v[6:7], v[2:3], 0, v[6:7]
	v_bfe_u32 v5, v13, 16, 1
	global_store_dwordx4 v[6:7], v[8:11], off
	v_add3_u32 v5, v13, v5, s17
	v_bfe_u32 v6, v15, 16, 1
	v_lshrrev_b32_e32 v5, 16, v5
	v_add3_u32 v6, v15, v6, s17
	v_and_or_b32 v6, v6, s18, v5
	s_nop 4
	v_cvt_pk_bf16_f32 v7, v17, v19
	s_nop 4
	v_cvt_pk_bf16_f32 v8, v21, v23
	s_nop 4
	v_add_u32_e32 v4, 56, v4
	v_cvt_pk_bf16_f32 v9, v25, v27
	v_ashrrev_i32_e32 v5, 31, v4
	v_lshlrev_b64 v[4:5], 12, v[4:5]
	v_lshl_add_u64 v[2:3], v[2:3], 0, v[4:5]
	global_store_dwordx4 v[2:3], v[6:9], off
	s_waitcnt lgkmcnt(0)
	s_cbranch_scc0 .LBB0_884

; #define LAS __attribute__((address_space(3)))
; #define LDS_WAIT() asm volatile("s_waitcnt lgkmcnt(0)" ::: "memory")
; __device__ __forceinline__ unsigned pk2(float lo, float hi) { return f2bf(lo) | (f2bf(hi) << 16); }
;     ...
;         for (int i = 0; i < 16; ++i) { LAS float* d = scr + (4 * i + kr) * 65 + nq; d[0] = v[i].x; d[1] = v[i].y; d[2] = v[i].z; d[3] = v[i].w; }
;         LDS_WAIT(); asm volatile("" ::: "memory");
;         const int c8 = lane & 7; int d0 = n0;
;         if (ffnmap) { const int bj = n0 >= FFH ? 1 : 0, chn = n0 - FFH * bj; d0 = 256 * (chn >> 7) + 128 * bj + (chn & 127); }
; #pragma unroll
;         for (int j = 0; j < 8; ++j) { const int n = (lane >> 3) + 8 * j; const LAS float* sp = scr + (8 * c8) * 65 + n;
;             v4u o; o.x = pk2(sp[0 * 65], sp[1 * 65]); o.y = pk2(sp[2 * 65], sp[3 * 65]); o.z = pk2(sp[4 * 65], sp[5 * 65]); o.w = pk2(sp[6 * 65], sp[7 * 65]);
;             *(v4u*)(WT + (size_t)(d0 + n) * K + k0 + 8 * c8) = o; }
.LBB0_886:
	s_or_b64 exec, exec, s[6:7]
	s_waitcnt vmcnt(0)
	ds_write2_b32 v78, v2, v3 offset1:1
	ds_write2_b32 v78, v4, v5 offset0:2 offset1:3
	v_add_u32_e32 v2, 0x410, v78
	ds_write2_b32 v2, v10, v11 offset1:1
	v_add_u32_e32 v2, 0x418, v78
	ds_write2_b32 v2, v12, v13 offset1:1
	v_add_u32_e32 v2, 0x820, v78
	ds_write2_b32 v2, v6, v7 offset1:1
	v_add_u32_e32 v2, 0x828, v78
	ds_write2_b32 v2, v8, v9 offset1:1
	v_add_u32_e32 v2, 0xc30, v78
	ds_write2_b32 v2, v18, v19 offset1:1
	v_add_u32_e32 v2, 0xc38, v78
	ds_write2_b32 v2, v20, v21 offset1:1
	v_add_u32_e32 v2, 0x1040, v78
	ds_write2_b32 v2, v14, v15 offset1:1
	v_add_u32_e32 v2, 0x1048, v78
	ds_write2_b32 v2, v16, v17 offset1:1
	v_add_u32_e32 v2, 0x1450, v78
	ds_write2_b32 v2, v26, v27 offset1:1
	v_add_u32_e32 v2, 0x1458, v78
	ds_write2_b32 v2, v28, v29 offset1:1
	v_add_u32_e32 v2, 0x1860, v78
	ds_write2_b32 v2, v22, v23 offset1:1
	v_add_u32_e32 v2, 0x1868, v78
	ds_write2_b32 v2, v24, v25 offset1:1
	v_add_u32_e32 v2, 0x1c70, v78
	ds_write2_b32 v2, v34, v35 offset1:1
	v_add_u32_e32 v2, 0x1c78, v78
	ds_write2_b32 v2, v36, v37 offset1:1
	v_add_u32_e32 v2, 0x2080, v78
	ds_write2_b32 v2, v30, v31 offset1:1
	v_add_u32_e32 v2, 0x2088, v78
	ds_write2_b32 v2, v32, v33 offset1:1
	v_add_u32_e32 v2, 0x2490, v78
	ds_write2_b32 v2, v42, v43 offset1:1
	v_add_u32_e32 v2, 0x2498, v78
	ds_write2_b32 v2, v44, v45 offset1:1
	v_add_u32_e32 v2, 0x28a0, v78
	ds_write2_b32 v2, v38, v39 offset1:1
	v_add_u32_e32 v2, 0x28a8, v78
	ds_write2_b32 v2, v40, v41 offset1:1
	v_add_u32_e32 v2, 0x2cb0, v78
	ds_write2_b32 v2, v50, v51 offset1:1
	v_add_u32_e32 v2, 0x2cb8, v78
	ds_write2_b32 v2, v52, v53 offset1:1
	v_add_u32_e32 v2, 0x30c0, v78
	ds_write2_b32 v2, v46, v47 offset1:1
	v_add_u32_e32 v2, 0x30c8, v78
	ds_write2_b32 v2, v48, v49 offset1:1
	v_add_u32_e32 v2, 0x34d0, v78
	ds_write2_b32 v2, v58, v59 offset1:1
	v_add_u32_e32 v2, 0x34d8, v78
	ds_write2_b32 v2, v60, v61 offset1:1
	v_add_u32_e32 v2, 0x38e0, v78
	ds_write2_b32 v2, v54, v55 offset1:1
	v_add_u32_e32 v2, 0x38e8, v78
	ds_write2_b32 v2, v56, v57 offset1:1
	v_add_u32_e32 v2, 0x3cf0, v78
	ds_write2_b32 v2, v62, v63 offset1:1
	v_add_u32_e32 v2, 0x3cf8, v78
	ds_write2_b32 v2, v64, v65 offset1:1
	s_waitcnt lgkmcnt(0)
	ds_read2_b32 v[10:11], v77 offset1:8
	ds_read2_b32 v[12:13], v77 offset0:65 offset1:73
	ds_read2_b32 v[14:15], v77 offset0:130 offset1:138
	ds_read2_b32 v[16:17], v77 offset0:195 offset1:203
	v_add_u32_e32 v28, 0x400, v77
	s_waitcnt lgkmcnt(0)
	s_nop 2
	ds_read2_b32 v[18:19], v28 offset0:4 offset1:12
	s_nop 1
	ds_read2_b32 v[20:21], v28 offset0:69 offset1:77
	v_cvt_pk_bf16_f32 v6, v10, v12
	s_nop 2
	ds_read2_b32 v[22:23], v28 offset0:134 offset1:142
	s_nop 1
	ds_read2_b32 v[24:25], v28 offset0:199 offset1:207
	v_cvt_pk_bf16_f32 v7, v14, v16
	s_waitcnt lgkmcnt(3)
	s_nop 1
	s_waitcnt lgkmcnt(2)
	s_nop 2
	v_cvt_pk_bf16_f32 v8, v18, v20
	s_waitcnt lgkmcnt(1)
	s_nop 1
	s_waitcnt lgkmcnt(0)
	s_nop 2
	s_add_i32 s15, s15, s8
	v_cvt_pk_bf16_f32 v9, v22, v24
	v_add_u32_e32 v4, s15, v76
	s_ashr_i32 s1, s0, 31
	v_ashrrev_i32_e32 v5, 31, v4
	v_lshl_add_u64 v[2:3], s[0:1], 1, v[70:71]
	v_lshlrev_b64 v[26:27], 12, v[4:5]
	v_lshl_add_u64 v[26:27], v[2:3], 0, v[26:27]
	v_bfe_u32 v5, v11, 16, 1
	global_store_dwordx4 v[26:27], v[6:9], off
	v_add3_u32 v5, v11, v5, s10
	v_lshrrev_b32_e32 v5, 16, v5
	v_bfe_u32 v6, v13, 16, 1
	v_add3_u32 v6, v13, v6, s10
	v_and_or_b32 v6, v6, s11, v5
	s_nop 4
	v_cvt_pk_bf16_f32 v7, v15, v17
	s_nop 4
	v_cvt_pk_bf16_f32 v8, v19, v21
	s_nop 0
	v_add_u32_e32 v10, 8, v4
	s_nop 1
	v_ashrrev_i32_e32 v11, 31, v10
	s_nop 1
	v_lshlrev_b64 v[10:11], 12, v[10:11]
	v_cvt_pk_bf16_f32 v9, v23, v25
	ds_read2_b32 v[12:13], v77 offset0:16 offset1:24
	v_lshl_add_u64 v[10:11], v[2:3], 0, v[10:11]
	global_store_dwordx4 v[10:11], v[6:9], off
	ds_read2_b32 v[10:11], v77 offset0:81 offset1:89
	ds_read2_b32 v[14:15], v77 offset0:146 offset1:154
	ds_read2_b32 v[16:17], v77 offset0:211 offset1:219
	s_waitcnt lgkmcnt(3)
	s_nop 1
	s_waitcnt lgkmcnt(2)
	s_nop 0
	ds_read2_b32 v[18:19], v28 offset0:20 offset1:28
	s_nop 1
	ds_read2_b32 v[20:21], v28 offset0:85 offset1:93
	v_cvt_pk_bf16_f32 v6, v12, v10
	s_waitcnt lgkmcnt(3)
; #define LAS __attribute__((address_space(3)))
; #define LDS_WAIT() asm volatile("s_waitcnt lgkmcnt(0)" ::: "memory")
; __device__ __forceinline__ unsigned pk2(float lo, float hi) { return f2bf(lo) | (f2bf(hi) << 16); }
;     ...
;         for (int j = 0; j < 8; ++j) { const int n = (lane >> 3) + 8 * j; const LAS float* sp = scr + (8 * c8) * 65 + n;
;             v4u o; o.x = pk2(sp[0 * 65], sp[1 * 65]); o.y = pk2(sp[2 * 65], sp[3 * 65]); o.z = pk2(sp[4 * 65], sp[5 * 65]); o.w = pk2(sp[6 * 65], sp[7 * 65]);
;             *(v4u*)(WT + (size_t)(d0 + n) * K + k0 + 8 * c8) = o; }
;         LDS_WAIT(); asm volatile("" ::: "memory");
	s_nop 1
	s_waitcnt lgkmcnt(2)
	s_nop 0
	ds_read2_b32 v[22:23], v28 offset0:150 offset1:158
	s_nop 1
	ds_read2_b32 v[24:25], v28 offset0:215 offset1:223
	v_cvt_pk_bf16_f32 v7, v14, v16
	s_waitcnt lgkmcnt(3)
	s_nop 1
	s_waitcnt lgkmcnt(2)
	s_nop 2
	v_cvt_pk_bf16_f32 v8, v18, v20
	s_waitcnt lgkmcnt(1)
	s_nop 0
	v_add_u32_e32 v26, 16, v4
	s_nop 0
	s_waitcnt lgkmcnt(0)
	s_nop 0
	v_ashrrev_i32_e32 v27, 31, v26
	s_nop 1
	v_lshlrev_b64 v[26:27], 12, v[26:27]
	v_cvt_pk_bf16_f32 v9, v22, v24
	v_lshl_add_u64 v[26:27], v[2:3], 0, v[26:27]
	v_bfe_u32 v5, v13, 16, 1
	global_store_dwordx4 v[26:27], v[6:9], off
	v_add3_u32 v5, v13, v5, s10
	v_lshrrev_b32_e32 v5, 16, v5
	v_bfe_u32 v6, v11, 16, 1
	v_add3_u32 v6, v11, v6, s10
	v_and_or_b32 v6, v6, s11, v5
	s_nop 4
	v_cvt_pk_bf16_f32 v7, v15, v17
	s_nop 4
	v_cvt_pk_bf16_f32 v8, v19, v21
	s_nop 0
	v_add_u32_e32 v10, 24, v4
	s_nop 1
	v_ashrrev_i32_e32 v11, 31, v10
	s_nop 1
	v_lshlrev_b64 v[10:11], 12, v[10:11]
	v_cvt_pk_bf16_f32 v9, v23, v25
	ds_read2_b32 v[12:13], v77 offset0:32 offset1:40
	v_lshl_add_u64 v[10:11], v[2:3], 0, v[10:11]
	global_store_dwordx4 v[10:11], v[6:9], off
	ds_read2_b32 v[10:11], v77 offset0:97 offset1:105
	ds_read2_b32 v[14:15], v77 offset0:162 offset1:170
	ds_read2_b32 v[16:17], v77 offset0:227 offset1:235
	s_waitcnt lgkmcnt(3)
	s_nop 1
	s_waitcnt lgkmcnt(2)
	s_nop 0
	ds_read2_b32 v[18:19], v28 offset0:36 offset1:44
	s_nop 1
	ds_read2_b32 v[20:21], v28 offset0:101 offset1:109
	v_cvt_pk_bf16_f32 v6, v12, v10
	s_waitcnt lgkmcnt(3)
	s_nop 1
	s_waitcnt lgkmcnt(2)
	s_nop 0
	ds_read2_b32 v[22:23], v28 offset0:166 offset1:174
	s_nop 1
	ds_read2_b32 v[24:25], v28 offset0:231 offset1:239
	v_cvt_pk_bf16_f32 v7, v14, v16
	s_waitcnt lgkmcnt(3)
	s_nop 1
	s_waitcnt lgkmcnt(2)
	s_nop 2
	v_cvt_pk_bf16_f32 v8, v18, v20
	s_waitcnt lgkmcnt(1)
	s_nop 0
	v_add_u32_e32 v26, 32, v4
	s_nop 0
	s_waitcnt lgkmcnt(0)
	s_nop 0
	v_ashrrev_i32_e32 v27, 31, v26
	s_nop 1
	v_lshlrev_b64 v[26:27], 12, v[26:27]
	v_cvt_pk_bf16_f32 v9, v22, v24
	v_lshl_add_u64 v[26:27], v[2:3], 0, v[26:27]
	v_bfe_u32 v5, v13, 16, 1
	global_store_dwordx4 v[26:27], v[6:9], off
	v_add3_u32 v5, v13, v5, s10
	v_lshrrev_b32_e32 v5, 16, v5
	v_bfe_u32 v6, v11, 16, 1
	v_add3_u32 v6, v11, v6, s10
	v_and_or_b32 v6, v6, s11, v5
	s_nop 4
	v_cvt_pk_bf16_f32 v7, v15, v17
	s_nop 4
	v_cvt_pk_bf16_f32 v8, v19, v21
	s_nop 0
	v_add_u32_e32 v10, 40, v4
	s_nop 1
	v_ashrrev_i32_e32 v11, 31, v10
	s_nop 1
	v_lshlrev_b64 v[10:11], 12, v[10:11]
	v_cvt_pk_bf16_f32 v9, v23, v25
	ds_read2_b32 v[12:13], v77 offset0:48 offset1:56
	v_lshl_add_u64 v[10:11], v[2:3], 0, v[10:11]
	global_store_dwordx4 v[10:11], v[6:9], off
	ds_read2_b32 v[10:11], v77 offset0:113 offset1:121
	ds_read2_b32 v[14:15], v77 offset0:178 offset1:186
	ds_read2_b32 v[16:17], v77 offset0:243 offset1:251
	s_waitcnt lgkmcnt(3)
	s_nop 1
	s_waitcnt lgkmcnt(2)
	s_nop 0
	ds_read2_b32 v[18:19], v28 offset0:52 offset1:60
	s_nop 1
	ds_read2_b32 v[20:21], v28 offset0:117 offset1:125
	v_cvt_pk_bf16_f32 v6, v12, v10
	s_waitcnt lgkmcnt(3)
	s_nop 1
	s_waitcnt lgkmcnt(2)
	s_nop 0
	ds_read2_b32 v[22:23], v28 offset0:182 offset1:190
	s_nop 1
	ds_read2_b32 v[24:25], v28 offset0:247 offset1:255
	v_cvt_pk_bf16_f32 v7, v14, v16
	s_waitcnt lgkmcnt(3)
	s_nop 1
	s_waitcnt lgkmcnt(2)
	s_nop 2
	v_cvt_pk_bf16_f32 v8, v18, v20
	s_waitcnt lgkmcnt(1)
	s_nop 0
	v_add_u32_e32 v26, 48, v4
	s_nop 0
	s_waitcnt lgkmcnt(0)
	s_nop 0
	v_ashrrev_i32_e32 v27, 31, v26
	s_nop 1
	v_lshlrev_b64 v[26:27], 12, v[26:27]
	v_cvt_pk_bf16_f32 v9, v22, v24
	v_lshl_add_u64 v[26:27], v[2:3], 0, v[26:27]
	v_bfe_u32 v5, v13, 16, 1
	global_store_dwordx4 v[26:27], v[6:9], off
	v_add3_u32 v5, v13, v5, s10
	v_lshrrev_b32_e32 v5, 16, v5
	v_bfe_u32 v6, v11, 16, 1
	v_add3_u32 v6, v11, v6, s10
	v_and_or_b32 v6, v6, s11, v5
	s_nop 4
	v_cvt_pk_bf16_f32 v7, v15, v17
	s_nop 4
	v_cvt_pk_bf16_f32 v8, v19, v21
	s_nop 4
	v_add_u32_e32 v4, 56, v4
	v_cvt_pk_bf16_f32 v9, v23, v25
	v_ashrrev_i32_e32 v5, 31, v4
	v_lshlrev_b64 v[4:5], 12, v[4:5]
	v_lshl_add_u64 v[2:3], v[2:3], 0, v[4:5]
	global_store_dwordx4 v[2:3], v[6:9], off
	s_waitcnt lgkmcnt(0)
	s_add_i32 s14, s14, s13
	s_add_i32 s8, s8, s9
	s_cmpk_lt_i32 s14, 0x400
	s_cbranch_scc0 .LBB0_919

; #define LAS __attribute__((address_space(3)))
; #define LDS_WAIT() asm volatile("s_waitcnt lgkmcnt(0)" ::: "memory")
; __device__ __forceinline__ unsigned pk2(float lo, float hi) { return f2bf(lo) | (f2bf(hi) << 16); }
;     ...
;         for (int i = 0; i < 16; ++i) { LAS float* d = scr + (4 * i + kr) * 65 + nq; d[0] = v[i].x; d[1] = v[i].y; d[2] = v[i].z; d[3] = v[i].w; }
;         LDS_WAIT(); asm volatile("" ::: "memory");
;         const int c8 = lane & 7; int d0 = n0;
;         if (ffnmap) { const int bj = n0 >= FFH ? 1 : 0, chn = n0 - FFH * bj; d0 = 256 * (chn >> 7) + 128 * bj + (chn & 127); }
; #pragma unroll
;         for (int j = 0; j < 8; ++j) { const int n = (lane >> 3) + 8 * j; const LAS float* sp = scr + (8 * c8) * 65 + n;
;             v4u o; o.x = pk2(sp[0 * 65], sp[1 * 65]); o.y = pk2(sp[2 * 65], sp[3 * 65]); o.z = pk2(sp[4 * 65], sp[5 * 65]); o.w = pk2(sp[6 * 65], sp[7 * 65]);
;             *(v4u*)(WT + (size_t)(d0 + n) * K + k0 + 8 * c8) = o; }
.LBB0_921:
	s_or_b64 exec, exec, s[6:7]
	s_waitcnt vmcnt(0)
	ds_write2_b32 v80, v2, v3 offset1:1
	ds_write2_b32 v80, v4, v5 offset0:2 offset1:3
	v_add_u32_e32 v2, 0x410, v80
	ds_write2_b32 v2, v10, v11 offset1:1
	v_add_u32_e32 v2, 0x418, v80
	ds_write2_b32 v2, v12, v13 offset1:1
	v_add_u32_e32 v2, 0x820, v80
	ds_write2_b32 v2, v6, v7 offset1:1
	v_add_u32_e32 v2, 0x828, v80
	ds_write2_b32 v2, v8, v9 offset1:1
	v_add_u32_e32 v2, 0xc30, v80
	ds_write2_b32 v2, v18, v19 offset1:1
	v_add_u32_e32 v2, 0xc38, v80
	ds_write2_b32 v2, v20, v21 offset1:1
	v_add_u32_e32 v2, 0x1040, v80
	ds_write2_b32 v2, v14, v15 offset1:1
	v_add_u32_e32 v2, 0x1048, v80
	ds_write2_b32 v2, v16, v17 offset1:1
	v_add_u32_e32 v2, 0x1450, v80
	ds_write2_b32 v2, v26, v27 offset1:1
	v_add_u32_e32 v2, 0x1458, v80
	ds_write2_b32 v2, v28, v29 offset1:1
	v_add_u32_e32 v2, 0x1860, v80
	ds_write2_b32 v2, v22, v23 offset1:1
	v_add_u32_e32 v2, 0x1868, v80
	ds_write2_b32 v2, v24, v25 offset1:1
	v_add_u32_e32 v2, 0x1c70, v80
	ds_write2_b32 v2, v34, v35 offset1:1
	v_add_u32_e32 v2, 0x1c78, v80
	ds_write2_b32 v2, v36, v37 offset1:1
	v_add_u32_e32 v2, 0x2080, v80
	ds_write2_b32 v2, v30, v31 offset1:1
	v_add_u32_e32 v2, 0x2088, v80
	ds_write2_b32 v2, v32, v33 offset1:1
	v_add_u32_e32 v2, 0x2490, v80
	ds_write2_b32 v2, v42, v43 offset1:1
	v_add_u32_e32 v2, 0x2498, v80
	ds_write2_b32 v2, v44, v45 offset1:1
	v_add_u32_e32 v2, 0x28a0, v80
	ds_write2_b32 v2, v38, v39 offset1:1
	v_add_u32_e32 v2, 0x28a8, v80
	ds_write2_b32 v2, v40, v41 offset1:1
	v_add_u32_e32 v2, 0x2cb0, v80
	ds_write2_b32 v2, v50, v51 offset1:1
	v_add_u32_e32 v2, 0x2cb8, v80
	ds_write2_b32 v2, v52, v53 offset1:1
	v_add_u32_e32 v2, 0x30c0, v80
	ds_write2_b32 v2, v46, v47 offset1:1
	v_add_u32_e32 v2, 0x30c8, v80
	ds_write2_b32 v2, v48, v49 offset1:1
	v_add_u32_e32 v2, 0x34d0, v80
	ds_write2_b32 v2, v58, v59 offset1:1
	v_add_u32_e32 v2, 0x34d8, v80
	ds_write2_b32 v2, v60, v61 offset1:1
	v_add_u32_e32 v2, 0x38e0, v80
	ds_write2_b32 v2, v54, v55 offset1:1
	v_add_u32_e32 v2, 0x38e8, v80
	ds_write2_b32 v2, v56, v57 offset1:1
	v_add_u32_e32 v2, 0x3cf0, v80
	ds_write2_b32 v2, v62, v63 offset1:1
	v_add_u32_e32 v2, 0x3cf8, v80
	ds_write2_b32 v2, v64, v65 offset1:1
	s_waitcnt lgkmcnt(0)
	ds_read2_b32 v[10:11], v79 offset1:8
	ds_read2_b32 v[12:13], v79 offset0:65 offset1:73
	ds_read2_b32 v[14:15], v79 offset0:130 offset1:138
	ds_read2_b32 v[16:17], v79 offset0:195 offset1:203
	v_add_u32_e32 v28, 0x400, v79
	s_waitcnt lgkmcnt(0)
	s_nop 2
	ds_read2_b32 v[18:19], v28 offset0:4 offset1:12
	s_nop 1
	ds_read2_b32 v[20:21], v28 offset0:69 offset1:77
	v_cvt_pk_bf16_f32 v6, v10, v12
	s_nop 2
	ds_read2_b32 v[22:23], v28 offset0:134 offset1:142
	s_nop 1
	ds_read2_b32 v[24:25], v28 offset0:199 offset1:207
	v_cvt_pk_bf16_f32 v7, v14, v16
	s_waitcnt lgkmcnt(3)
	s_nop 1
	s_waitcnt lgkmcnt(2)
	s_nop 2
	v_cvt_pk_bf16_f32 v8, v18, v20
	s_waitcnt lgkmcnt(1)
	s_nop 1
	s_waitcnt lgkmcnt(0)
	s_nop 2
	s_add_i32 s16, s16, s14
	v_cvt_pk_bf16_f32 v9, v22, v24
	v_add_u32_e32 v4, s16, v78
	s_ashr_i32 s1, s0, 31
	v_ashrrev_i32_e32 v5, 31, v4
	v_lshl_add_u64 v[2:3], s[0:1], 1, v[72:73]
	v_lshlrev_b64 v[26:27], 13, v[4:5]
	v_lshl_add_u64 v[26:27], v[2:3], 0, v[26:27]
	v_bfe_u32 v5, v11, 16, 1
	global_store_dwordx4 v[26:27], v[6:9], off
	v_add3_u32 v5, v11, v5, s10
	v_lshrrev_b32_e32 v5, 16, v5
	v_bfe_u32 v6, v13, 16, 1
	v_add3_u32 v6, v13, v6, s10
	v_and_or_b32 v6, v6, s11, v5
	s_nop 4
	v_cvt_pk_bf16_f32 v7, v15, v17
	s_nop 4
	v_cvt_pk_bf16_f32 v8, v19, v21
	s_nop 0
	v_add_u32_e32 v10, 8, v4
	s_nop 1
	v_ashrrev_i32_e32 v11, 31, v10
	s_nop 1
	v_lshlrev_b64 v[10:11], 13, v[10:11]
	v_cvt_pk_bf16_f32 v9, v23, v25
	ds_read2_b32 v[12:13], v79 offset0:16 offset1:24
	v_lshl_add_u64 v[10:11], v[2:3], 0, v[10:11]
	global_store_dwordx4 v[10:11], v[6:9], off
	ds_read2_b32 v[10:11], v79 offset0:81 offset1:89
	ds_read2_b32 v[14:15], v79 offset0:146 offset1:154
	ds_read2_b32 v[16:17], v79 offset0:211 offset1:219
	s_waitcnt lgkmcnt(3)
	s_nop 1
	s_waitcnt lgkmcnt(2)
	s_nop 0
	ds_read2_b32 v[18:19], v28 offset0:20 offset1:28
	s_nop 1
	ds_read2_b32 v[20:21], v28 offset0:85 offset1:93
	v_cvt_pk_bf16_f32 v6, v12, v10
	s_waitcnt lgkmcnt(3)
; #define LAS __attribute__((address_space(3)))
; #define LDS_WAIT() asm volatile("s_waitcnt lgkmcnt(0)" ::: "memory")
; __device__ __forceinline__ unsigned pk2(float lo, float hi) { return f2bf(lo) | (f2bf(hi) << 16); }
;     ...
;         for (int j = 0; j < 8; ++j) { const int n = (lane >> 3) + 8 * j; const LAS float* sp = scr + (8 * c8) * 65 + n;
;             v4u o; o.x = pk2(sp[0 * 65], sp[1 * 65]); o.y = pk2(sp[2 * 65], sp[3 * 65]); o.z = pk2(sp[4 * 65], sp[5 * 65]); o.w = pk2(sp[6 * 65], sp[7 * 65]);
;             *(v4u*)(WT + (size_t)(d0 + n) * K + k0 + 8 * c8) = o; }
;         LDS_WAIT(); asm volatile("" ::: "memory");
	s_nop 1
	s_waitcnt lgkmcnt(2)
	s_nop 0
	ds_read2_b32 v[22:23], v28 offset0:150 offset1:158
	s_nop 1
	ds_read2_b32 v[24:25], v28 offset0:215 offset1:223
	v_cvt_pk_bf16_f32 v7, v14, v16
	s_waitcnt lgkmcnt(3)
	s_nop 1
	s_waitcnt lgkmcnt(2)
	s_nop 2
	v_cvt_pk_bf16_f32 v8, v18, v20
	s_waitcnt lgkmcnt(1)
	s_nop 0
	v_add_u32_e32 v26, 16, v4
	s_nop 0
	s_waitcnt lgkmcnt(0)
	s_nop 0
	v_ashrrev_i32_e32 v27, 31, v26
	s_nop 1
	v_lshlrev_b64 v[26:27], 13, v[26:27]
	v_cvt_pk_bf16_f32 v9, v22, v24
	v_lshl_add_u64 v[26:27], v[2:3], 0, v[26:27]
	v_bfe_u32 v5, v13, 16, 1
	global_store_dwordx4 v[26:27], v[6:9], off
	v_add3_u32 v5, v13, v5, s10
	v_lshrrev_b32_e32 v5, 16, v5
	v_bfe_u32 v6, v11, 16, 1
	v_add3_u32 v6, v11, v6, s10
	v_and_or_b32 v6, v6, s11, v5
	s_nop 4
	v_cvt_pk_bf16_f32 v7, v15, v17
	s_nop 4
	v_cvt_pk_bf16_f32 v8, v19, v21
	s_nop 0
	v_add_u32_e32 v10, 24, v4
	s_nop 1
	v_ashrrev_i32_e32 v11, 31, v10
	s_nop 1
	v_lshlrev_b64 v[10:11], 13, v[10:11]
	v_cvt_pk_bf16_f32 v9, v23, v25
	ds_read2_b32 v[12:13], v79 offset0:32 offset1:40
	v_lshl_add_u64 v[10:11], v[2:3], 0, v[10:11]
	global_store_dwordx4 v[10:11], v[6:9], off
	ds_read2_b32 v[10:11], v79 offset0:97 offset1:105
	ds_read2_b32 v[14:15], v79 offset0:162 offset1:170
	ds_read2_b32 v[16:17], v79 offset0:227 offset1:235
	s_waitcnt lgkmcnt(3)
	s_nop 1
	s_waitcnt lgkmcnt(2)
	s_nop 0
	ds_read2_b32 v[18:19], v28 offset0:36 offset1:44
	s_nop 1
	ds_read2_b32 v[20:21], v28 offset0:101 offset1:109
	v_cvt_pk_bf16_f32 v6, v12, v10
	s_waitcnt lgkmcnt(3)
	s_nop 1
	s_waitcnt lgkmcnt(2)
	s_nop 0
	ds_read2_b32 v[22:23], v28 offset0:166 offset1:174
	s_nop 1
	ds_read2_b32 v[24:25], v28 offset0:231 offset1:239
	v_cvt_pk_bf16_f32 v7, v14, v16
	s_waitcnt lgkmcnt(3)
	s_nop 1
	s_waitcnt lgkmcnt(2)
	s_nop 2
	v_cvt_pk_bf16_f32 v8, v18, v20
	s_waitcnt lgkmcnt(1)
	s_nop 0
	v_add_u32_e32 v26, 32, v4
	s_nop 0
	s_waitcnt lgkmcnt(0)
	s_nop 0
	v_ashrrev_i32_e32 v27, 31, v26
	s_nop 1
	v_lshlrev_b64 v[26:27], 13, v[26:27]
	v_cvt_pk_bf16_f32 v9, v22, v24
	v_lshl_add_u64 v[26:27], v[2:3], 0, v[26:27]
	v_bfe_u32 v5, v13, 16, 1
	global_store_dwordx4 v[26:27], v[6:9], off
	v_add3_u32 v5, v13, v5, s10
	v_lshrrev_b32_e32 v5, 16, v5
	v_bfe_u32 v6, v11, 16, 1
	v_add3_u32 v6, v11, v6, s10
	v_and_or_b32 v6, v6, s11, v5
	s_nop 4
	v_cvt_pk_bf16_f32 v7, v15, v17
	s_nop 4
	v_cvt_pk_bf16_f32 v8, v19, v21
	s_nop 0
	v_add_u32_e32 v10, 40, v4
	s_nop 1
	v_ashrrev_i32_e32 v11, 31, v10
	s_nop 1
	v_lshlrev_b64 v[10:11], 13, v[10:11]
	v_cvt_pk_bf16_f32 v9, v23, v25
	ds_read2_b32 v[12:13], v79 offset0:48 offset1:56
	v_lshl_add_u64 v[10:11], v[2:3], 0, v[10:11]
	global_store_dwordx4 v[10:11], v[6:9], off
	ds_read2_b32 v[10:11], v79 offset0:113 offset1:121
	ds_read2_b32 v[14:15], v79 offset0:178 offset1:186
	ds_read2_b32 v[16:17], v79 offset0:243 offset1:251
	s_waitcnt lgkmcnt(3)
	s_nop 1
	s_waitcnt lgkmcnt(2)
	s_nop 0
	ds_read2_b32 v[18:19], v28 offset0:52 offset1:60
	s_nop 1
	ds_read2_b32 v[20:21], v28 offset0:117 offset1:125
	v_cvt_pk_bf16_f32 v6, v12, v10
	s_waitcnt lgkmcnt(3)
	s_nop 1
	s_waitcnt lgkmcnt(2)
	s_nop 0
	ds_read2_b32 v[22:23], v28 offset0:182 offset1:190
	s_nop 1
	ds_read2_b32 v[24:25], v28 offset0:247 offset1:255
	v_cvt_pk_bf16_f32 v7, v14, v16
	s_waitcnt lgkmcnt(3)
	s_nop 1
	s_waitcnt lgkmcnt(2)
	s_nop 2
	v_cvt_pk_bf16_f32 v8, v18, v20
	s_waitcnt lgkmcnt(1)
	s_nop 0
	v_add_u32_e32 v26, 48, v4
	s_nop 0
	s_waitcnt lgkmcnt(0)
	s_nop 0
	v_ashrrev_i32_e32 v27, 31, v26
	s_nop 1
	v_lshlrev_b64 v[26:27], 13, v[26:27]
	v_cvt_pk_bf16_f32 v9, v22, v24
	v_lshl_add_u64 v[26:27], v[2:3], 0, v[26:27]
	v_bfe_u32 v5, v13, 16, 1
	global_store_dwordx4 v[26:27], v[6:9], off
	v_add3_u32 v5, v13, v5, s10
	v_lshrrev_b32_e32 v5, 16, v5
	v_bfe_u32 v6, v11, 16, 1
	v_add3_u32 v6, v11, v6, s10
	v_and_or_b32 v6, v6, s11, v5
	s_nop 4
	v_cvt_pk_bf16_f32 v7, v15, v17
	s_nop 4
	v_cvt_pk_bf16_f32 v8, v19, v21
	s_nop 4
	v_add_u32_e32 v4, 56, v4
	v_cvt_pk_bf16_f32 v9, v23, v25
	v_ashrrev_i32_e32 v5, 31, v4
	v_lshlrev_b64 v[4:5], 13, v[4:5]
	v_lshl_add_u64 v[2:3], v[2:3], 0, v[4:5]
	global_store_dwordx4 v[2:3], v[6:9], off
	s_waitcnt lgkmcnt(0)
	s_add_i32 s15, s15, s13
	s_add_i32 s14, s14, s9
	s_cmpk_lt_i32 s15, 0x100
	s_cbranch_scc0 .LBB0_954

; #define LAS __attribute__((address_space(3)))
; #define LDS_WAIT() asm volatile("s_waitcnt lgkmcnt(0)" ::: "memory")
; __device__ __forceinline__ unsigned pk2(float lo, float hi) { return f2bf(lo) | (f2bf(hi) << 16); }
;     ...
;         for (int i = 0; i < 16; ++i) { LAS float* d = scr + (4 * i + kr) * 65 + nq; d[0] = v[i].x; d[1] = v[i].y; d[2] = v[i].z; d[3] = v[i].w; }
;         LDS_WAIT(); asm volatile("" ::: "memory");
;         const int c8 = lane & 7; int d0 = n0;
;         if (ffnmap) { const int bj = n0 >= FFH ? 1 : 0, chn = n0 - FFH * bj; d0 = 256 * (chn >> 7) + 128 * bj + (chn & 127); }
; #pragma unroll
;         for (int j = 0; j < 8; ++j) { const int n = (lane >> 3) + 8 * j; const LAS float* sp = scr + (8 * c8) * 65 + n;
;             v4u o; o.x = pk2(sp[0 * 65], sp[1 * 65]); o.y = pk2(sp[2 * 65], sp[3 * 65]); o.z = pk2(sp[4 * 65], sp[5 * 65]); o.w = pk2(sp[6 * 65], sp[7 * 65]);
;             *(v4u*)(WT + (size_t)(d0 + n) * K + k0 + 8 * c8) = o; }
.LBB0_955:
	s_or_b64 exec, exec, s[6:7]
	s_waitcnt vmcnt(0)
	ds_write2_b32 v80, v2, v3 offset1:1
	ds_write2_b32 v80, v4, v5 offset0:2 offset1:3
	v_add_u32_e32 v2, 0x410, v80
	ds_write2_b32 v2, v10, v11 offset1:1
	v_add_u32_e32 v2, 0x418, v80
	ds_write2_b32 v2, v12, v13 offset1:1
	v_add_u32_e32 v2, 0x820, v80
	ds_write2_b32 v2, v6, v7 offset1:1
	v_add_u32_e32 v2, 0x828, v80
	ds_write2_b32 v2, v8, v9 offset1:1
	v_add_u32_e32 v2, 0xc30, v80
	ds_write2_b32 v2, v18, v19 offset1:1
	v_add_u32_e32 v2, 0xc38, v80
	ds_write2_b32 v2, v20, v21 offset1:1
	v_add_u32_e32 v2, 0x1040, v80
	ds_write2_b32 v2, v14, v15 offset1:1
	v_add_u32_e32 v2, 0x1048, v80
	ds_write2_b32 v2, v16, v17 offset1:1
	v_add_u32_e32 v2, 0x1450, v80
	ds_write2_b32 v2, v26, v27 offset1:1
	v_add_u32_e32 v2, 0x1458, v80
	ds_write2_b32 v2, v28, v29 offset1:1
	v_add_u32_e32 v2, 0x1860, v80
	ds_write2_b32 v2, v22, v23 offset1:1
	v_add_u32_e32 v2, 0x1868, v80
	ds_write2_b32 v2, v24, v25 offset1:1
	v_add_u32_e32 v2, 0x1c70, v80
	ds_write2_b32 v2, v34, v35 offset1:1
	v_add_u32_e32 v2, 0x1c78, v80
	ds_write2_b32 v2, v36, v37 offset1:1
	v_add_u32_e32 v2, 0x2080, v80
	ds_write2_b32 v2, v30, v31 offset1:1
	v_add_u32_e32 v2, 0x2088, v80
	ds_write2_b32 v2, v32, v33 offset1:1
	v_add_u32_e32 v2, 0x2490, v80
	ds_write2_b32 v2, v42, v43 offset1:1
	v_add_u32_e32 v2, 0x2498, v80
	ds_write2_b32 v2, v44, v45 offset1:1
	v_add_u32_e32 v2, 0x28a0, v80
	ds_write2_b32 v2, v38, v39 offset1:1
	v_add_u32_e32 v2, 0x28a8, v80
	ds_write2_b32 v2, v40, v41 offset1:1
	v_add_u32_e32 v2, 0x2cb0, v80
	ds_write2_b32 v2, v50, v51 offset1:1
	v_add_u32_e32 v2, 0x2cb8, v80
	ds_write2_b32 v2, v52, v53 offset1:1
	v_add_u32_e32 v2, 0x30c0, v80
	ds_write2_b32 v2, v46, v47 offset1:1
	v_add_u32_e32 v2, 0x30c8, v80
	ds_write2_b32 v2, v48, v49 offset1:1
	v_add_u32_e32 v2, 0x34d0, v80
	ds_write2_b32 v2, v58, v59 offset1:1
	v_add_u32_e32 v2, 0x34d8, v80
	ds_write2_b32 v2, v60, v61 offset1:1
	v_add_u32_e32 v2, 0x38e0, v80
	ds_write2_b32 v2, v54, v55 offset1:1
	v_add_u32_e32 v2, 0x38e8, v80
	ds_write2_b32 v2, v56, v57 offset1:1
	v_add_u32_e32 v2, 0x3cf0, v80
	ds_write2_b32 v2, v62, v63 offset1:1
	v_add_u32_e32 v2, 0x3cf8, v80
	ds_write2_b32 v2, v64, v65 offset1:1
	s_waitcnt lgkmcnt(0)
	ds_read2_b32 v[10:11], v79 offset1:8
	ds_read2_b32 v[12:13], v79 offset0:65 offset1:73
	ds_read2_b32 v[14:15], v79 offset0:130 offset1:138
	ds_read2_b32 v[16:17], v79 offset0:195 offset1:203
	v_add_u32_e32 v28, 0x400, v79
	s_waitcnt lgkmcnt(3)
	s_nop 1
	s_waitcnt lgkmcnt(2)
	s_nop 0
	ds_read2_b32 v[18:19], v28 offset0:4 offset1:12
	s_nop 1
	ds_read2_b32 v[20:21], v28 offset0:69 offset1:77
	v_cvt_pk_bf16_f32 v6, v10, v12
	s_waitcnt lgkmcnt(3)
	s_nop 1
	s_waitcnt lgkmcnt(2)
	s_nop 0
	ds_read2_b32 v[22:23], v28 offset0:134 offset1:142
	s_nop 1
	ds_read2_b32 v[24:25], v28 offset0:199 offset1:207
	v_cvt_pk_bf16_f32 v7, v14, v16
	s_waitcnt lgkmcnt(3)
	s_nop 1
	s_waitcnt lgkmcnt(2)
	s_nop 2
	v_cvt_pk_bf16_f32 v8, v18, v20
	s_waitcnt lgkmcnt(1)
	s_nop 1
	s_waitcnt lgkmcnt(0)
	s_nop 2
	s_add_i32 s14, s14, s8
	v_cvt_pk_bf16_f32 v9, v22, v24
	v_add_u32_e32 v4, s14, v78
	s_ashr_i32 s1, s0, 31
	v_ashrrev_i32_e32 v5, 31, v4
	v_lshl_add_u64 v[2:3], s[0:1], 1, v[68:69]
	v_lshlrev_b64 v[26:27], 13, v[4:5]
	v_lshl_add_u64 v[26:27], v[2:3], 0, v[26:27]
	v_bfe_u32 v5, v11, 16, 1
	global_store_dwordx4 v[26:27], v[6:9], off
	v_add3_u32 v5, v11, v5, s10
	v_lshrrev_b32_e32 v5, 16, v5
	v_bfe_u32 v6, v13, 16, 1
	v_add3_u32 v6, v13, v6, s10
	v_and_or_b32 v6, v6, s11, v5
	s_nop 4
	v_cvt_pk_bf16_f32 v7, v15, v17
	s_nop 4
	v_cvt_pk_bf16_f32 v8, v19, v21
	s_nop 0
	v_add_u32_e32 v10, 8, v4
	s_nop 1
	v_ashrrev_i32_e32 v11, 31, v10
	s_nop 1
	v_lshlrev_b64 v[10:11], 13, v[10:11]
	v_cvt_pk_bf16_f32 v9, v23, v25
	ds_read2_b32 v[12:13], v79 offset0:16 offset1:24
	v_lshl_add_u64 v[10:11], v[2:3], 0, v[10:11]
	global_store_dwordx4 v[10:11], v[6:9], off
	ds_read2_b32 v[10:11], v79 offset0:81 offset1:89
	ds_read2_b32 v[14:15], v79 offset0:146 offset1:154
	ds_read2_b32 v[16:17], v79 offset0:211 offset1:219
	s_waitcnt lgkmcnt(3)
	s_nop 1
	s_waitcnt lgkmcnt(2)
	s_nop 0
	ds_read2_b32 v[18:19], v28 offset0:20 offset1:28
	s_nop 1
	ds_read2_b32 v[20:21], v28 offset0:85 offset1:93
	v_cvt_pk_bf16_f32 v6, v12, v10
	s_waitcnt lgkmcnt(3)
; #define LAS __attribute__((address_space(3)))
; #define LDS_WAIT() asm volatile("s_waitcnt lgkmcnt(0)" ::: "memory")
; __device__ __forceinline__ unsigned pk2(float lo, float hi) { return f2bf(lo) | (f2bf(hi) << 16); }
;     ...
;         for (int j = 0; j < 8; ++j) { const int n = (lane >> 3) + 8 * j; const LAS float* sp = scr + (8 * c8) * 65 + n;
;             v4u o; o.x = pk2(sp[0 * 65], sp[1 * 65]); o.y = pk2(sp[2 * 65], sp[3 * 65]); o.z = pk2(sp[4 * 65], sp[5 * 65]); o.w = pk2(sp[6 * 65], sp[7 * 65]);
;             *(v4u*)(WT + (size_t)(d0 + n) * K + k0 + 8 * c8) = o; }
;         LDS_WAIT(); asm volatile("" ::: "memory");
	s_nop 1
	s_waitcnt lgkmcnt(2)
	s_nop 0
	ds_read2_b32 v[22:23], v28 offset0:150 offset1:158
	s_nop 1
	ds_read2_b32 v[24:25], v28 offset0:215 offset1:223
	v_cvt_pk_bf16_f32 v7, v14, v16
	s_waitcnt lgkmcnt(3)
	s_nop 1
	s_waitcnt lgkmcnt(2)
	s_nop 2
	v_cvt_pk_bf16_f32 v8, v18, v20
	s_waitcnt lgkmcnt(1)
	s_nop 0
	v_add_u32_e32 v26, 16, v4
	s_nop 0
	s_waitcnt lgkmcnt(0)
	s_nop 0
	v_ashrrev_i32_e32 v27, 31, v26
	s_nop 1
	v_lshlrev_b64 v[26:27], 13, v[26:27]
	v_cvt_pk_bf16_f32 v9, v22, v24
	v_lshl_add_u64 v[26:27], v[2:3], 0, v[26:27]
	v_bfe_u32 v5, v13, 16, 1
	global_store_dwordx4 v[26:27], v[6:9], off
	v_add3_u32 v5, v13, v5, s10
	v_lshrrev_b32_e32 v5, 16, v5
	v_bfe_u32 v6, v11, 16, 1
	v_add3_u32 v6, v11, v6, s10
	v_and_or_b32 v6, v6, s11, v5
	s_nop 4
	v_cvt_pk_bf16_f32 v7, v15, v17
	s_nop 4
	v_cvt_pk_bf16_f32 v8, v19, v21
	s_nop 0
	v_add_u32_e32 v10, 24, v4
	s_nop 1
	v_ashrrev_i32_e32 v11, 31, v10
	s_nop 1
	v_lshlrev_b64 v[10:11], 13, v[10:11]
	v_cvt_pk_bf16_f32 v9, v23, v25
	ds_read2_b32 v[12:13], v79 offset0:32 offset1:40
	v_lshl_add_u64 v[10:11], v[2:3], 0, v[10:11]
	global_store_dwordx4 v[10:11], v[6:9], off
	ds_read2_b32 v[10:11], v79 offset0:97 offset1:105
	ds_read2_b32 v[14:15], v79 offset0:162 offset1:170
	ds_read2_b32 v[16:17], v79 offset0:227 offset1:235
	s_waitcnt lgkmcnt(3)
	s_nop 1
	s_waitcnt lgkmcnt(2)
	s_nop 0
	ds_read2_b32 v[18:19], v28 offset0:36 offset1:44
	s_nop 1
	ds_read2_b32 v[20:21], v28 offset0:101 offset1:109
	v_cvt_pk_bf16_f32 v6, v12, v10
	s_waitcnt lgkmcnt(3)
	s_nop 1
	s_waitcnt lgkmcnt(2)
	s_nop 0
	ds_read2_b32 v[22:23], v28 offset0:166 offset1:174
	s_nop 1
	ds_read2_b32 v[24:25], v28 offset0:231 offset1:239
	v_cvt_pk_bf16_f32 v7, v14, v16
	s_waitcnt lgkmcnt(3)
	s_nop 1
	s_waitcnt lgkmcnt(2)
	s_nop 2
	v_cvt_pk_bf16_f32 v8, v18, v20
	s_waitcnt lgkmcnt(1)
	s_nop 0
	v_add_u32_e32 v26, 32, v4
	s_nop 0
	s_waitcnt lgkmcnt(0)
	s_nop 0
	v_ashrrev_i32_e32 v27, 31, v26
	s_nop 1
	v_lshlrev_b64 v[26:27], 13, v[26:27]
	v_cvt_pk_bf16_f32 v9, v22, v24
	v_lshl_add_u64 v[26:27], v[2:3], 0, v[26:27]
	v_bfe_u32 v5, v13, 16, 1
	global_store_dwordx4 v[26:27], v[6:9], off
	v_add3_u32 v5, v13, v5, s10
	v_lshrrev_b32_e32 v5, 16, v5
	v_bfe_u32 v6, v11, 16, 1
	v_add3_u32 v6, v11, v6, s10
	v_and_or_b32 v6, v6, s11, v5
	s_nop 4
	v_cvt_pk_bf16_f32 v7, v15, v17
	s_nop 4
	v_cvt_pk_bf16_f32 v8, v19, v21
	s_nop 0
	v_add_u32_e32 v10, 40, v4
	s_nop 1
	v_ashrrev_i32_e32 v11, 31, v10
	s_nop 1
	v_lshlrev_b64 v[10:11], 13, v[10:11]
	v_cvt_pk_bf16_f32 v9, v23, v25
	ds_read2_b32 v[12:13], v79 offset0:48 offset1:56
	v_lshl_add_u64 v[10:11], v[2:3], 0, v[10:11]
	global_store_dwordx4 v[10:11], v[6:9], off
	ds_read2_b32 v[10:11], v79 offset0:113 offset1:121
	ds_read2_b32 v[14:15], v79 offset0:178 offset1:186
	ds_read2_b32 v[16:17], v79 offset0:243 offset1:251
	s_waitcnt lgkmcnt(3)
	s_nop 1
	s_waitcnt lgkmcnt(2)
	s_nop 0
	ds_read2_b32 v[18:19], v28 offset0:52 offset1:60
	s_nop 1
	ds_read2_b32 v[20:21], v28 offset0:117 offset1:125
	v_cvt_pk_bf16_f32 v6, v12, v10
	s_waitcnt lgkmcnt(3)
	s_nop 1
	s_waitcnt lgkmcnt(2)
	s_nop 0
	ds_read2_b32 v[22:23], v28 offset0:182 offset1:190
	s_nop 1
	ds_read2_b32 v[24:25], v28 offset0:247 offset1:255
	v_cvt_pk_bf16_f32 v7, v14, v16
	s_waitcnt lgkmcnt(3)
	s_nop 1
	s_waitcnt lgkmcnt(2)
	s_nop 2
	v_cvt_pk_bf16_f32 v8, v18, v20
	s_waitcnt lgkmcnt(1)
	s_nop 0
	v_add_u32_e32 v26, 48, v4
	s_nop 0
	s_waitcnt lgkmcnt(0)
	s_nop 0
	v_ashrrev_i32_e32 v27, 31, v26
	s_nop 1
	v_lshlrev_b64 v[26:27], 13, v[26:27]
	v_cvt_pk_bf16_f32 v9, v22, v24
	v_lshl_add_u64 v[26:27], v[2:3], 0, v[26:27]
	v_bfe_u32 v5, v13, 16, 1
	global_store_dwordx4 v[26:27], v[6:9], off
	v_add3_u32 v5, v13, v5, s10
	v_lshrrev_b32_e32 v5, 16, v5
	v_bfe_u32 v6, v11, 16, 1
	v_add3_u32 v6, v11, v6, s10
	v_and_or_b32 v6, v6, s11, v5
	s_nop 4
	v_cvt_pk_bf16_f32 v7, v15, v17
	s_nop 4
	v_cvt_pk_bf16_f32 v8, v19, v21
	s_nop 4
	v_add_u32_e32 v4, 56, v4
	v_cvt_pk_bf16_f32 v9, v23, v25
	v_ashrrev_i32_e32 v5, 31, v4
	v_lshlrev_b64 v[4:5], 13, v[4:5]
	v_lshl_add_u64 v[2:3], v[2:3], 0, v[4:5]
	global_store_dwordx4 v[2:3], v[6:9], off
	s_waitcnt lgkmcnt(0)
	s_add_i32 s12, s12, s13
	s_add_i32 s8, s8, s9
	s_cmpk_lt_i32 s12, 0x100
	s_cbranch_scc0 .LBB0_988

; __device__ __forceinline__ unsigned pk2(float lo, float hi) { return f2bf(lo) | (f2bf(hi) << 16); }
; __device__ __forceinline__ void xa_attn_fa(const Ctx& c, const bf16* Q, const bf16* KV, const bf16* XVT, bf16* Oo) {
;     ...
;         for (int mi = 0; mi < 2; ++mi) { float lt = l[mi]; lt += __shfl_xor(lt, 16); lt += __shfl_xor(lt, 32); const float il = 1.f / lt;
; #pragma unroll
;             for (int dt = 0; dt < 8; ++dt) { const f32x4 o = O[dt][mi] * il; v2u w; w.x = pk2(o[0], o[1]); w.y = pk2(o[2], o[3]);
;                 *(v2u*)(Oo + grow[mi] * 512 + hd * 128 + 16 * dt + 4 * lg) = w; } }
.LBB0_1044:
	v_mul_f32_e32 v4, 0x3e800000, v128
	ds_bpermute_b32 v4, v167, v4
	s_lshl_b32 s8, s21, 1
	v_lshl_add_u64 v[6:7], v[172:173], 0, s[8:9]
	v_lshl_add_u64 v[42:43], v[6:7], 0, v[188:189]
	v_mul_f32_e32 v48, 0x3e800000, v40
	s_waitcnt lgkmcnt(0)
	v_fmac_f32_e32 v4, 0x3e800000, v128
	ds_bpermute_b32 v41, v196, v4
	v_lshl_add_u64 v[6:7], v[6:7], 0, v[186:187]
	s_add_i32 s20, s20, s33
	s_cmpk_lt_i32 s20, 0x100
	s_waitcnt lgkmcnt(0)
	v_add_f32_e32 v4, v4, v41
	v_div_scale_f32 v41, s[10:11], v4, v4, 1.0
	v_rcp_f32_e32 v44, v41
	v_div_scale_f32 v45, vcc, 1.0, v4, 1.0
	v_fma_f32 v46, -v41, v44, 1.0
	v_fmac_f32_e32 v44, v46, v44
	v_mul_f32_e32 v46, v45, v44
	v_fma_f32 v47, -v41, v46, v45
	v_fmac_f32_e32 v46, v47, v44
	v_fma_f32 v41, -v41, v46, v45
	v_div_fmas_f32 v41, v41, v44, v46
	v_div_fixup_f32 v4, v41, v4, 1.0
	v_pk_mul_f32 v[46:47], v[104:105], v[4:5] op_sel_hi:[1,0]
	v_pk_mul_f32 v[44:45], v[106:107], v[4:5] op_sel_hi:[1,0]
	s_nop 4
	v_cvt_pk_bf16_f32 v46, v46, v47
	v_bfe_u32 v41, v44, 16, 1
	v_add3_u32 v41, v44, v41, s18
	v_bfe_u32 v44, v45, 16, 1
	v_lshrrev_b32_e32 v41, 16, v41
	v_add3_u32 v44, v45, v44, s18
	v_and_or_b32 v47, v44, s19, v41
	global_store_dwordx2 v[42:43], v[46:47], off
	v_pk_mul_f32 v[46:47], v[100:101], v[4:5] op_sel_hi:[1,0]
	v_pk_mul_f32 v[44:45], v[102:103], v[4:5] op_sel_hi:[1,0]
	v_bfe_u32 v41, v46, 16, 1
	v_add3_u32 v41, v46, v41, s18
	v_bfe_u32 v46, v47, 16, 1
	v_lshrrev_b32_e32 v41, 16, v41
	v_add3_u32 v46, v47, v46, s18
	v_and_or_b32 v46, v46, s19, v41
	v_bfe_u32 v41, v44, 16, 1
	v_add3_u32 v41, v44, v41, s18
	v_bfe_u32 v44, v45, 16, 1
	v_lshrrev_b32_e32 v41, 16, v41
	v_add3_u32 v44, v45, v44, s18
	v_and_or_b32 v47, v44, s19, v41
	global_store_dwordx2 v[42:43], v[46:47], off offset:32
	v_pk_mul_f32 v[46:47], v[96:97], v[4:5] op_sel_hi:[1,0]
	v_pk_mul_f32 v[44:45], v[98:99], v[4:5] op_sel_hi:[1,0]
	v_bfe_u32 v41, v46, 16, 1
	v_add3_u32 v41, v46, v41, s18
	v_bfe_u32 v46, v47, 16, 1
	v_lshrrev_b32_e32 v41, 16, v41
	v_add3_u32 v46, v47, v46, s18
	v_and_or_b32 v46, v46, s19, v41
	v_bfe_u32 v41, v44, 16, 1
	v_add3_u32 v41, v44, v41, s18
	v_bfe_u32 v44, v45, 16, 1
	v_lshrrev_b32_e32 v41, 16, v41
	v_add3_u32 v44, v45, v44, s18
	v_and_or_b32 v47, v44, s19, v41
	global_store_dwordx2 v[42:43], v[46:47], off offset:64
	v_pk_mul_f32 v[46:47], v[92:93], v[4:5] op_sel_hi:[1,0]
	v_pk_mul_f32 v[44:45], v[94:95], v[4:5] op_sel_hi:[1,0]
	v_bfe_u32 v41, v46, 16, 1
	v_add3_u32 v41, v46, v41, s18
	v_bfe_u32 v46, v47, 16, 1
	v_lshrrev_b32_e32 v41, 16, v41
	v_add3_u32 v46, v47, v46, s18
	v_and_or_b32 v46, v46, s19, v41
	v_bfe_u32 v41, v44, 16, 1
	v_add3_u32 v41, v44, v41, s18
	v_bfe_u32 v44, v45, 16, 1
	v_lshrrev_b32_e32 v41, 16, v41
	v_add3_u32 v44, v45, v44, s18
	v_and_or_b32 v47, v44, s19, v41
	global_store_dwordx2 v[42:43], v[46:47], off offset:96
	v_pk_mul_f32 v[46:47], v[88:89], v[4:5] op_sel_hi:[1,0]
	v_pk_mul_f32 v[44:45], v[90:91], v[4:5] op_sel_hi:[1,0]
	v_bfe_u32 v41, v46, 16, 1
	v_add3_u32 v41, v46, v41, s18
	v_bfe_u32 v46, v47, 16, 1
	v_lshrrev_b32_e32 v41, 16, v41
	v_add3_u32 v46, v47, v46, s18
	v_and_or_b32 v46, v46, s19, v41
	v_bfe_u32 v41, v44, 16, 1
	v_add3_u32 v41, v44, v41, s18
	v_bfe_u32 v44, v45, 16, 1
	v_lshrrev_b32_e32 v41, 16, v41
	v_add3_u32 v44, v45, v44, s18
	v_and_or_b32 v47, v44, s19, v41
	global_store_dwordx2 v[42:43], v[46:47], off offset:128
	v_pk_mul_f32 v[46:47], v[84:85], v[4:5] op_sel_hi:[1,0]
	v_pk_mul_f32 v[44:45], v[86:87], v[4:5] op_sel_hi:[1,0]
	v_bfe_u32 v41, v46, 16, 1
	v_add3_u32 v41, v46, v41, s18
	v_bfe_u32 v46, v47, 16, 1
	v_lshrrev_b32_e32 v41, 16, v41
	v_add3_u32 v46, v47, v46, s18
	v_and_or_b32 v46, v46, s19, v41
	v_bfe_u32 v41, v44, 16, 1
	v_add3_u32 v41, v44, v41, s18
	v_bfe_u32 v44, v45, 16, 1
	v_lshrrev_b32_e32 v41, 16, v41
	v_add3_u32 v44, v45, v44, s18
	v_and_or_b32 v47, v44, s19, v41
	global_store_dwordx2 v[42:43], v[46:47], off offset:160
	v_pk_mul_f32 v[46:47], v[80:81], v[4:5] op_sel_hi:[1,0]
	v_pk_mul_f32 v[44:45], v[82:83], v[4:5] op_sel_hi:[1,0]
	v_bfe_u32 v41, v46, 16, 1
	v_add3_u32 v41, v46, v41, s18
	v_bfe_u32 v46, v47, 16, 1
	v_lshrrev_b32_e32 v41, 16, v41
	v_add3_u32 v46, v47, v46, s18
	v_and_or_b32 v46, v46, s19, v41
	v_bfe_u32 v41, v44, 16, 1
	v_add3_u32 v41, v44, v41, s18
	v_bfe_u32 v44, v45, 16, 1
	v_lshrrev_b32_e32 v41, 16, v41
	v_add3_u32 v44, v45, v44, s18
	v_and_or_b32 v47, v44, s19, v41
	ds_bpermute_b32 v41, v167, v48
	global_store_dwordx2 v[42:43], v[46:47], off offset:192
	v_pk_mul_f32 v[46:47], v[76:77], v[4:5] op_sel_hi:[1,0]
	v_pk_mul_f32 v[44:45], v[78:79], v[4:5] op_sel_hi:[1,0]
	v_bfe_u32 v4, v46, 16, 1
	v_add3_u32 v4, v46, v4, s18
	v_bfe_u32 v46, v47, 16, 1
	v_lshrrev_b32_e32 v4, 16, v4
	v_add3_u32 v46, v47, v46, s18
	s_waitcnt lgkmcnt(0)
; __device__ __forceinline__ unsigned pk2(float lo, float hi) { return f2bf(lo) | (f2bf(hi) << 16); }
; __device__ __forceinline__ void xa_attn_fa(const Ctx& c, const bf16* Q, const bf16* KV, const bf16* XVT, bf16* Oo) {
;     ...
;         for (int mi = 0; mi < 2; ++mi) { float lt = l[mi]; lt += __shfl_xor(lt, 16); lt += __shfl_xor(lt, 32); const float il = 1.f / lt;
; #pragma unroll
;             for (int dt = 0; dt < 8; ++dt) { const f32x4 o = O[dt][mi] * il; v2u w; w.x = pk2(o[0], o[1]); w.y = pk2(o[2], o[3]);
;                 *(v2u*)(Oo + grow[mi] * 512 + hd * 128 + 16 * dt + 4 * lg) = w; } }
	v_fmac_f32_e32 v41, 0x3e800000, v40
	v_and_or_b32 v46, v46, s19, v4
	ds_bpermute_b32 v4, v196, v41
	v_bfe_u32 v40, v44, 16, 1
	v_add3_u32 v40, v44, v40, s18
	v_bfe_u32 v44, v45, 16, 1
	v_lshrrev_b32_e32 v40, 16, v40
	s_waitcnt lgkmcnt(0)
	v_add_f32_e32 v4, v41, v4
	v_div_scale_f32 v41, s[10:11], v4, v4, 1.0
	v_rcp_f32_e32 v48, v41
	v_add3_u32 v44, v45, v44, s18
	v_and_or_b32 v47, v44, s19, v40
	global_store_dwordx2 v[42:43], v[46:47], off offset:224
	v_fma_f32 v40, -v41, v48, 1.0
	v_fmac_f32_e32 v48, v40, v48
	v_div_scale_f32 v40, vcc, 1.0, v4, 1.0
	v_mul_f32_e32 v42, v40, v48
	v_fma_f32 v43, -v41, v42, v40
	v_fmac_f32_e32 v42, v43, v48
	v_fma_f32 v40, -v41, v42, v40
	v_div_fmas_f32 v40, v40, v48, v42
	v_div_fixup_f32 v4, v40, v4, 1.0
	v_pk_mul_f32 v[36:37], v[36:37], v[4:5] op_sel_hi:[1,0]
	v_pk_mul_f32 v[38:39], v[38:39], v[4:5] op_sel_hi:[1,0]
	s_nop 4
	v_cvt_pk_bf16_f32 v36, v36, v37
	v_bfe_u32 v37, v38, 16, 1
	v_add3_u32 v37, v38, v37, s18
	v_bfe_u32 v38, v39, 16, 1
	v_lshrrev_b32_e32 v37, 16, v37
	v_add3_u32 v38, v39, v38, s18
	v_and_or_b32 v37, v38, s19, v37
	v_pk_mul_f32 v[32:33], v[32:33], v[4:5] op_sel_hi:[1,0]
	global_store_dwordx2 v[6:7], v[36:37], off
	s_nop 2
	v_pk_mul_f32 v[34:35], v[34:35], v[4:5] op_sel_hi:[1,0]
	s_nop 1
	v_cvt_pk_bf16_f32 v32, v32, v33
	v_bfe_u32 v33, v34, 16, 1
	v_add3_u32 v33, v34, v33, s18
	v_bfe_u32 v34, v35, 16, 1
	v_lshrrev_b32_e32 v33, 16, v33
	v_add3_u32 v34, v35, v34, s18
	v_and_or_b32 v33, v34, s19, v33
	v_pk_mul_f32 v[28:29], v[28:29], v[4:5] op_sel_hi:[1,0]
	global_store_dwordx2 v[6:7], v[32:33], off offset:32
	s_nop 2
	v_pk_mul_f32 v[30:31], v[30:31], v[4:5] op_sel_hi:[1,0]
	s_nop 1
	v_cvt_pk_bf16_f32 v28, v28, v29
	v_bfe_u32 v29, v30, 16, 1
	v_add3_u32 v29, v30, v29, s18
	v_bfe_u32 v30, v31, 16, 1
	v_lshrrev_b32_e32 v29, 16, v29
	v_add3_u32 v30, v31, v30, s18
	v_and_or_b32 v29, v30, s19, v29
	v_pk_mul_f32 v[24:25], v[24:25], v[4:5] op_sel_hi:[1,0]
	global_store_dwordx2 v[6:7], v[28:29], off offset:64
	s_nop 2
	v_pk_mul_f32 v[26:27], v[26:27], v[4:5] op_sel_hi:[1,0]
	s_nop 1
	v_cvt_pk_bf16_f32 v24, v24, v25
	v_bfe_u32 v25, v26, 16, 1
	v_add3_u32 v25, v26, v25, s18
	v_bfe_u32 v26, v27, 16, 1
	v_lshrrev_b32_e32 v25, 16, v25
	v_add3_u32 v26, v27, v26, s18
	v_and_or_b32 v25, v26, s19, v25
	v_pk_mul_f32 v[20:21], v[20:21], v[4:5] op_sel_hi:[1,0]
	global_store_dwordx2 v[6:7], v[24:25], off offset:96
	s_nop 2
	v_pk_mul_f32 v[22:23], v[22:23], v[4:5] op_sel_hi:[1,0]
	s_nop 1
	v_cvt_pk_bf16_f32 v20, v20, v21
	v_bfe_u32 v21, v22, 16, 1
	v_add3_u32 v21, v22, v21, s18
	v_bfe_u32 v22, v23, 16, 1
	v_lshrrev_b32_e32 v21, 16, v21
	v_add3_u32 v22, v23, v22, s18
	v_and_or_b32 v21, v22, s19, v21
	v_pk_mul_f32 v[16:17], v[16:17], v[4:5] op_sel_hi:[1,0]
	global_store_dwordx2 v[6:7], v[20:21], off offset:128
	s_nop 2
	v_pk_mul_f32 v[18:19], v[18:19], v[4:5] op_sel_hi:[1,0]
	s_nop 1
	v_cvt_pk_bf16_f32 v16, v16, v17
	v_bfe_u32 v17, v18, 16, 1
	v_add3_u32 v17, v18, v17, s18
	v_bfe_u32 v18, v19, 16, 1
	v_lshrrev_b32_e32 v17, 16, v17
	v_add3_u32 v18, v19, v18, s18
	v_and_or_b32 v17, v18, s19, v17
	v_pk_mul_f32 v[12:13], v[12:13], v[4:5] op_sel_hi:[1,0]
	v_pk_mul_f32 v[8:9], v[8:9], v[4:5] op_sel_hi:[1,0]
	global_store_dwordx2 v[6:7], v[16:17], off offset:160
	v_pk_mul_f32 v[14:15], v[14:15], v[4:5] op_sel_hi:[1,0]
	s_nop 0
	v_pk_mul_f32 v[10:11], v[10:11], v[4:5] op_sel_hi:[1,0]
	v_bfe_u32 v4, v8, 16, 1
	s_nop 1
	v_add3_u32 v4, v8, v4, s18
	v_bfe_u32 v8, v9, 16, 1
	s_nop 1
	v_lshrrev_b32_e32 v4, 16, v4
	v_add3_u32 v8, v9, v8, s18
	v_cvt_pk_bf16_f32 v12, v12, v13
	v_bfe_u32 v13, v14, 16, 1
	v_and_or_b32 v8, v8, s19, v4
	v_bfe_u32 v4, v10, 16, 1
	v_add3_u32 v13, v14, v13, s18
	v_bfe_u32 v14, v15, 16, 1
	v_add3_u32 v4, v10, v4, s18
	v_bfe_u32 v9, v11, 16, 1
	v_lshrrev_b32_e32 v13, 16, v13
	v_add3_u32 v14, v15, v14, s18
	v_lshrrev_b32_e32 v4, 16, v4
	v_add3_u32 v9, v11, v9, s18
	v_and_or_b32 v13, v14, s19, v13
	v_and_or_b32 v9, v9, s19, v4
	global_store_dwordx2 v[6:7], v[12:13], off offset:192
	global_store_dwordx2 v[6:7], v[8:9], off offset:224
	s_cbranch_scc0 .LBB0_1056

; __device__ __forceinline__ void postnorm(const Ctx& c, const bf16* MF, bf16* XB, float* RS, const float* gpost, float* OUT) {
;     ...
;         const v4u* mr = (const v4u*)(MF + (size_t)row * DM) + c.lane; v4u* xr = (v4u*)(XB + (size_t)row * DM) + c.lane;
;         v4u mv[4], xv[4]; float v[4][8]; float s = 0.f;
; #pragma unroll
;         for (int j = 0; j < 4; ++j) { mv[j] = mr[64 * j]; xv[j] = xr[64 * j]; }
; #pragma unroll
;         for (int j = 0; j < 4; ++j)
; #pragma unroll
;             for (int k = 0; k < 4; ++k) { v[j][2 * k] = bflo(mv[j][k]); v[j][2 * k + 1] = bfhi(mv[j][k]); s += v[j][2 * k] * v[j][2 * k] + v[j][2 * k + 1] * v[j][2 * k + 1]; }
;         const float rs = rsqrtf(wave_sum(s) * (1.f / DM) + EPS);
;         float s2 = 0.f;
; #pragma unroll
;         for (int j = 0; j < 4; ++j) { const float* gp = gpost + (c.lane + 64 * j) * 8; const f32x4 g0 = *(CF4)gp, g1 = *(CF4)(gp + 4);
; #pragma unroll
;             for (int k = 0; k < 4; ++k) { const float ga = (k < 2) ? g0[2 * k] : g1[2 * k - 4], gb = (k < 2) ? g0[2 * k + 1] : g1[2 * k - 3];
;                 v[j][2 * k] = bflo(xv[j][k]) + v[j][2 * k] * rs * ga; v[j][2 * k + 1] = bfhi(xv[j][k]) + v[j][2 * k + 1] * rs * gb;
;                 s2 += v[j][2 * k] * v[j][2 * k] + v[j][2 * k + 1] * v[j][2 * k + 1]; } }
.LBB0_1188:
	v_readlane_b32 s10, v253, 0
	v_readlane_b32 s11, v253, 1
	s_nop 1
	v_lshl_add_u64 v[38:39], s[10:11], 0, v[30:31]
	v_add_co_u32_e32 v58, vcc, 0xd400000, v38
	s_nop 1
	v_addc_co_u32_e32 v59, vcc, 0, v39, vcc
	s_waitcnt lgkmcnt(0)
	global_load_dwordx4 v[46:49], v[58:59], off
	global_load_dwordx4 v[50:53], v[58:59], off offset:1024
	global_load_dwordx4 v[54:57], v[58:59], off offset:2048
	s_nop 0
	global_load_dwordx4 v[58:61], v[58:59], off offset:3072
	v_add_co_u32_e32 v38, vcc, 0x9400000, v38
	s_waitcnt vmcnt(0)
	v_lshlrev_b32_e32 v79, 16, v47
	v_addc_co_u32_e32 v39, vcc, 0, v39, vcc
	global_load_dwordx4 v[62:65], v[38:39], off
	global_load_dwordx4 v[66:69], v[38:39], off offset:1024
	global_load_dwordx4 v[70:73], v[38:39], off offset:2048
	global_load_dwordx4 v[74:77], v[38:39], off offset:3072
	v_lshlrev_b32_e32 v78, 16, v46
	v_and_b32_e32 v47, 0xffff0000, v47
	v_and_b32_e32 v46, 0xffff0000, v46
	v_lshlrev_b32_e32 v81, 16, v49
	v_lshlrev_b32_e32 v80, 16, v48
	v_and_b32_e32 v49, 0xffff0000, v49
	v_and_b32_e32 v48, 0xffff0000, v48
	v_pk_mul_f32 v[94:95], v[46:47], v[46:47]
	v_pk_mul_f32 v[98:99], v[48:49], v[48:49]
	v_pk_fma_f32 v[94:95], v[78:79], v[78:79], v[94:95]
	v_lshlrev_b32_e32 v83, 16, v51
	v_lshlrev_b32_e32 v82, 16, v50
	v_and_b32_e32 v51, 0xffff0000, v51
	v_and_b32_e32 v50, 0xffff0000, v50
	v_pk_fma_f32 v[98:99], v[80:81], v[80:81], v[98:99]
	v_add_f32_e32 v94, v94, v95
	v_pk_mul_f32 v[102:103], v[50:51], v[50:51]
	v_add_f32_e32 v94, v98, v94
	v_lshlrev_b32_e32 v85, 16, v53
	v_lshlrev_b32_e32 v84, 16, v52
	v_and_b32_e32 v53, 0xffff0000, v53
	v_and_b32_e32 v52, 0xffff0000, v52
	v_pk_fma_f32 v[102:103], v[82:83], v[82:83], v[102:103]
	v_add_f32_e32 v94, v99, v94
	v_pk_mul_f32 v[104:105], v[52:53], v[52:53]
	v_add_f32_e32 v94, v102, v94
	v_lshlrev_b32_e32 v87, 16, v55
	v_lshlrev_b32_e32 v86, 16, v54
	v_and_b32_e32 v55, 0xffff0000, v55
	v_and_b32_e32 v54, 0xffff0000, v54
	v_pk_fma_f32 v[104:105], v[84:85], v[84:85], v[104:105]
	v_add_f32_e32 v94, v103, v94
	v_pk_mul_f32 v[106:107], v[54:55], v[54:55]
	v_add_f32_e32 v94, v104, v94
	v_lshlrev_b32_e32 v89, 16, v57
	v_lshlrev_b32_e32 v88, 16, v56
	v_and_b32_e32 v57, 0xffff0000, v57
	v_and_b32_e32 v56, 0xffff0000, v56
	v_pk_fma_f32 v[106:107], v[86:87], v[86:87], v[106:107]
	v_add_f32_e32 v94, v105, v94
	v_pk_mul_f32 v[108:109], v[56:57], v[56:57]
	v_add_f32_e32 v94, v106, v94
	v_lshlrev_b32_e32 v91, 16, v59
	v_lshlrev_b32_e32 v90, 16, v58
	v_and_b32_e32 v59, 0xffff0000, v59
	v_and_b32_e32 v58, 0xffff0000, v58
	v_pk_fma_f32 v[108:109], v[88:89], v[88:89], v[108:109]
	v_add_f32_e32 v94, v107, v94
	v_pk_mul_f32 v[110:111], v[58:59], v[58:59]
	v_add_f32_e32 v94, v108, v94
	v_lshlrev_b32_e32 v93, 16, v61
	v_lshlrev_b32_e32 v92, 16, v60
	v_and_b32_e32 v61, 0xffff0000, v61
	v_and_b32_e32 v60, 0xffff0000, v60
	v_pk_fma_f32 v[110:111], v[90:91], v[90:91], v[110:111]
	v_add_f32_e32 v94, v109, v94
	v_pk_mul_f32 v[112:113], v[60:61], v[60:61]
	v_add_f32_e32 v94, v110, v94
	v_pk_fma_f32 v[112:113], v[92:93], v[92:93], v[112:113]
	v_add_f32_e32 v94, v111, v94
	v_add_f32_e32 v94, v112, v94
	v_add_f32_e32 v94, v113, v94
	ds_bpermute_b32 v98, v3, v94
	s_waitcnt lgkmcnt(0)
	v_add_f32_e32 v98, v94, v98
	ds_bpermute_b32 v102, v40, v98
	s_waitcnt lgkmcnt(0)
	v_add_f32_e32 v102, v98, v102
	ds_bpermute_b32 v104, v41, v102
	s_waitcnt vmcnt(3)
	v_lshlrev_b32_e32 v97, 16, v63
	v_lshlrev_b32_e32 v96, 16, v62
	v_and_b32_e32 v63, 0xffff0000, v63
	s_waitcnt lgkmcnt(0)
	v_add_f32_e32 v104, v102, v104
	ds_bpermute_b32 v106, v42, v104
	v_and_b32_e32 v62, 0xffff0000, v62
	v_lshlrev_b32_e32 v101, 16, v65
	v_lshlrev_b32_e32 v100, 16, v64
	v_and_b32_e32 v65, 0xffff0000, v65
	s_waitcnt lgkmcnt(0)
	v_add_f32_e32 v106, v104, v106
	ds_bpermute_b32 v108, v43, v106
	v_and_b32_e32 v64, 0xffff0000, v64
	s_waitcnt vmcnt(0)
	v_lshlrev_b32_e32 v109, 16, v77
	v_and_b32_e32 v77, 0xffff0000, v77
	v_lshlrev_b32_e32 v95, 16, v67
	s_waitcnt lgkmcnt(0)
	v_add_f32_e32 v108, v106, v108
	ds_bpermute_b32 v110, v44, v108
	v_lshlrev_b32_e32 v94, 16, v66
	v_and_b32_e32 v67, 0xffff0000, v67
	v_and_b32_e32 v66, 0xffff0000, v66
	v_lshlrev_b32_e32 v99, 16, v69
	s_waitcnt lgkmcnt(0)
	v_add_f32_e32 v108, v108, v110
	v_fmamk_f32 v108, v108, 0x3a000000, v45
	v_mul_f32_e32 v110, 0x4b800000, v108
	v_cmp_gt_f32_e32 vcc, s15, v108
	v_lshlrev_b32_e32 v98, 16, v68
	v_and_b32_e32 v69, 0xffff0000, v69
	v_cndmask_b32_e32 v108, v108, v110, vcc
	v_rsq_f32_e32 v110, v108
	v_lshlrev_b32_e32 v108, 16, v76
	v_and_b32_e32 v76, 0xffff0000, v76
	v_and_b32_e32 v68, 0xffff0000, v68
	v_mul_f32_e32 v111, 0x45800000, v110
	v_cndmask_b32_e32 v110, v110, v111, vcc
	v_pk_mul_f32 v[46:47], v[110:111], v[46:47] op_sel_hi:[0,1]
	v_pk_mul_f32 v[78:79], v[110:111], v[78:79] op_sel_hi:[0,1]
	v_pk_mul_f32 v[48:49], v[110:111], v[48:49] op_sel_hi:[0,1]
	v_pk_fma_f32 v[46:47], v[36:37], v[46:47], v[62:63]
	v_pk_mul_f32 v[60:61], v[110:111], v[60:61] op_sel_hi:[0,1]
	v_pk_mul_f32 v[80:81], v[110:111], v[80:81] op_sel_hi:[0,1]
	v_pk_fma_f32 v[78:79], v[8:9], v[78:79], v[96:97]
	v_pk_fma_f32 v[48:49], v[10:11], v[48:49], v[64:65]
	v_pk_fma_f32 v[60:61], v[34:35], v[60:61], v[76:77]
	v_pk_mul_f32 v[76:77], v[46:47], v[46:47]
	v_pk_mul_f32 v[50:51], v[110:111], v[50:51] op_sel_hi:[0,1]
	v_pk_fma_f32 v[62:63], v[4:5], v[80:81], v[100:101]
	v_pk_fma_f32 v[76:77], v[78:79], v[78:79], v[76:77]
	v_pk_mul_f32 v[80:81], v[48:49], v[48:49]
	v_pk_mul_f32 v[82:83], v[110:111], v[82:83] op_sel_hi:[0,1]
	v_pk_fma_f32 v[50:51], v[6:7], v[50:51], v[66:67]
	v_pk_fma_f32 v[80:81], v[62:63], v[62:63], v[80:81]
	v_add_f32_e32 v76, v76, v77
	v_pk_fma_f32 v[64:65], v[16:17], v[82:83], v[94:95]
; __device__ __forceinline__ unsigned pk2(float lo, float hi) { return f2bf(lo) | (f2bf(hi) << 16); }
; __device__ __forceinline__ void postnorm(const Ctx& c, const bf16* MF, bf16* XB, float* RS, const float* gpost, float* OUT) {
;     ...
;         const float rs = rsqrtf(wave_sum(s) * (1.f / DM) + EPS);
;         float s2 = 0.f;
; #pragma unroll
;         for (int j = 0; j < 4; ++j) { const float* gp = gpost + (c.lane + 64 * j) * 8; const f32x4 g0 = *(CF4)gp, g1 = *(CF4)(gp + 4);
; #pragma unroll
;             for (int k = 0; k < 4; ++k) { const float ga = (k < 2) ? g0[2 * k] : g1[2 * k - 4], gb = (k < 2) ? g0[2 * k + 1] : g1[2 * k - 3];
;                 v[j][2 * k] = bflo(xv[j][k]) + v[j][2 * k] * rs * ga; v[j][2 * k + 1] = bfhi(xv[j][k]) + v[j][2 * k + 1] * rs * gb;
;                 s2 += v[j][2 * k] * v[j][2 * k] + v[j][2 * k + 1] * v[j][2 * k + 1]; } }
;         if (OUT) {
; #pragma unroll
;             for (int j = 0; j < 4; ++j) { float* op = OUT + (size_t)row * DM + (c.lane + 64 * j) * 8; *(f32x4*)op = (f32x4){v[j][0], v[j][1], v[j][2], v[j][3]}; *(f32x4*)(op + 4) = (f32x4){v[j][4], v[j][5], v[j][6], v[j][7]}; }
;         } else {
; #pragma unroll
;             for (int j = 0; j < 4; ++j) { v4u o; o.x = pk2(v[j][0], v[j][1]); o.y = pk2(v[j][2], v[j][3]); o.z = pk2(v[j][4], v[j][5]); o.w = pk2(v[j][6], v[j][7]); xr[64 * j] = o; }
;             const float rs2 = rsqrtf(wave_sum(s2) * (1.f / DM) + EPS); if (c.lane == 0) RS[row] = rs2;
	v_pk_mul_f32 v[82:83], v[50:51], v[50:51]
	v_add_f32_e32 v76, v80, v76
	v_pk_fma_f32 v[82:83], v[64:65], v[64:65], v[82:83]
	v_add_f32_e32 v76, v81, v76
	v_add_f32_e32 v76, v82, v76
	v_bfe_u32 v77, v49, 16, 1
	v_bfe_u32 v80, v48, 16, 1
	v_bfe_u32 v81, v47, 16, 1
	v_bfe_u32 v82, v46, 16, 1
	v_pk_mul_f32 v[52:53], v[110:111], v[52:53] op_sel_hi:[0,1]
	v_add3_u32 v46, v46, v82, s16
	v_add3_u32 v47, v47, v81, s16
	v_add3_u32 v48, v48, v80, s16
	v_add3_u32 v49, v49, v77, s16
	v_bfe_u32 v77, v78, 16, 1
	v_bfe_u32 v80, v79, 16, 1
	v_bfe_u32 v81, v62, 16, 1
	v_bfe_u32 v82, v63, 16, 1
	v_pk_mul_f32 v[84:85], v[110:111], v[84:85] op_sel_hi:[0,1]
	v_pk_fma_f32 v[52:53], v[18:19], v[52:53], v[68:69]
	v_add3_u32 v63, v63, v82, s16
	v_add3_u32 v62, v62, v81, s16
	v_add3_u32 v79, v79, v80, s16
	v_add3_u32 v77, v78, v77, s16
	v_lshlrev_b32_e32 v103, 16, v71
	v_lshlrev_b32_e32 v102, 16, v70
	v_and_b32_e32 v71, 0xffff0000, v71
	v_and_b32_e32 v70, 0xffff0000, v70
	v_pk_fma_f32 v[66:67], v[12:13], v[84:85], v[98:99]
	v_pk_mul_f32 v[54:55], v[110:111], v[54:55] op_sel_hi:[0,1]
	v_pk_mul_f32 v[84:85], v[52:53], v[52:53]
	v_lshrrev_b32_e32 v77, 16, v77
	v_lshrrev_b32_e32 v78, 16, v79
	v_lshrrev_b32_e32 v62, 16, v62
	v_lshrrev_b32_e32 v63, 16, v63
	v_pk_mul_f32 v[68:69], v[110:111], v[86:87] op_sel_hi:[0,1]
	v_pk_fma_f32 v[54:55], v[14:15], v[54:55], v[70:71]
	v_pk_fma_f32 v[84:85], v[66:67], v[66:67], v[84:85]
	v_add_f32_e32 v76, v83, v76
	v_and_or_b32 v49, v49, s14, v63
	v_and_or_b32 v48, v48, s14, v62
	v_and_or_b32 v47, v47, s14, v78
	v_and_or_b32 v46, v46, s14, v77
	v_lshlrev_b32_e32 v105, 16, v73
	v_lshlrev_b32_e32 v104, 16, v72
	v_and_b32_e32 v73, 0xffff0000, v73
	v_and_b32_e32 v72, 0xffff0000, v72
	v_pk_fma_f32 v[68:69], v[24:25], v[68:69], v[102:103]
	v_pk_mul_f32 v[56:57], v[110:111], v[56:57] op_sel_hi:[0,1]
	v_pk_mul_f32 v[86:87], v[54:55], v[54:55]
	v_add_f32_e32 v76, v84, v76
	global_store_dwordx4 v[38:39], v[46:49], off
	v_pk_mul_f32 v[70:71], v[110:111], v[88:89] op_sel_hi:[0,1]
	v_pk_fma_f32 v[56:57], v[26:27], v[56:57], v[72:73]
	v_bfe_u32 v46, v53, 16, 1
	v_bfe_u32 v47, v52, 16, 1
	v_bfe_u32 v48, v51, 16, 1
	v_bfe_u32 v49, v50, 16, 1
	v_pk_fma_f32 v[86:87], v[68:69], v[68:69], v[86:87]
	v_add_f32_e32 v76, v85, v76
	v_add3_u32 v50, v50, v49, s16
	v_add3_u32 v51, v51, v48, s16
	v_add3_u32 v47, v52, v47, s16
	v_add3_u32 v46, v53, v46, s16
	v_bfe_u32 v48, v64, 16, 1
	v_bfe_u32 v49, v65, 16, 1
	v_bfe_u32 v52, v66, 16, 1
	v_bfe_u32 v53, v67, 16, 1
	v_lshlrev_b32_e32 v107, 16, v75
	v_lshlrev_b32_e32 v106, 16, v74
	v_and_b32_e32 v75, 0xffff0000, v75
	v_and_b32_e32 v74, 0xffff0000, v74
	v_pk_fma_f32 v[70:71], v[20:21], v[70:71], v[104:105]
	v_pk_mul_f32 v[58:59], v[110:111], v[58:59] op_sel_hi:[0,1]
	v_pk_mul_f32 v[88:89], v[56:57], v[56:57]
	v_add_f32_e32 v76, v86, v76
	v_add3_u32 v53, v67, v53, s16
	v_add3_u32 v52, v66, v52, s16
	v_add3_u32 v49, v65, v49, s16
	v_add3_u32 v48, v64, v48, s16
	v_pk_mul_f32 v[72:73], v[110:111], v[90:91] op_sel_hi:[0,1]
	v_pk_fma_f32 v[58:59], v[22:23], v[58:59], v[74:75]
	v_pk_fma_f32 v[88:89], v[70:71], v[70:71], v[88:89]
	v_add_f32_e32 v76, v87, v76
	v_lshrrev_b32_e32 v62, 16, v48
	v_lshrrev_b32_e32 v63, 16, v49
	v_lshrrev_b32_e32 v48, 16, v52
	v_lshrrev_b32_e32 v49, 16, v53
	v_pk_fma_f32 v[72:73], v[32:33], v[72:73], v[106:107]
	v_pk_mul_f32 v[90:91], v[58:59], v[58:59]
	v_add_f32_e32 v76, v88, v76
	v_and_or_b32 v49, v46, s14, v49
	v_and_or_b32 v48, v47, s14, v48
	v_and_or_b32 v47, v51, s14, v63
	v_and_or_b32 v46, v50, s14, v62
	v_pk_mul_f32 v[74:75], v[110:111], v[92:93] op_sel_hi:[0,1]
	v_pk_fma_f32 v[90:91], v[72:73], v[72:73], v[90:91]
	v_add_f32_e32 v76, v89, v76
	global_store_dwordx4 v[38:39], v[46:49], off offset:1024
	v_pk_fma_f32 v[74:75], v[28:29], v[74:75], v[108:109]
	v_pk_mul_f32 v[92:93], v[60:61], v[60:61]
	v_bfe_u32 v48, v55, 16, 1
	v_bfe_u32 v49, v54, 16, 1
	v_add_f32_e32 v76, v90, v76
	v_add3_u32 v50, v54, v49, s16
	v_add3_u32 v51, v55, v48, s16
	v_bfe_u32 v48, v68, 16, 1
	v_bfe_u32 v49, v69, 16, 1
	v_bfe_u32 v52, v70, 16, 1
	v_bfe_u32 v53, v71, 16, 1
	v_pk_fma_f32 v[92:93], v[74:75], v[74:75], v[92:93]
	v_add_f32_e32 v76, v91, v76
	v_bfe_u32 v46, v57, 16, 1
	v_bfe_u32 v47, v56, 16, 1
	v_add3_u32 v53, v71, v53, s16
	v_add3_u32 v52, v70, v52, s16
	v_add3_u32 v49, v69, v49, s16
	v_add3_u32 v48, v68, v48, s16
	v_add_f32_e32 v76, v92, v76
	v_add3_u32 v47, v56, v47, s16
	v_add3_u32 v46, v57, v46, s16
	v_lshrrev_b32_e32 v54, 16, v48
	v_lshrrev_b32_e32 v55, 16, v49
	v_lshrrev_b32_e32 v48, 16, v52
	v_lshrrev_b32_e32 v49, 16, v53
	v_add_f32_e32 v76, v93, v76
	v_and_or_b32 v49, v46, s14, v49
	v_and_or_b32 v48, v47, s14, v48
	v_and_or_b32 v47, v51, s14, v55
	v_and_or_b32 v46, v50, s14, v54
	global_store_dwordx4 v[38:39], v[46:49], off offset:2048
	ds_bpermute_b32 v47, v3, v76
	v_bfe_u32 v50, v58, 16, 1
	v_add3_u32 v52, v58, v50, s16
	v_bfe_u32 v51, v72, 16, 1
	v_bfe_u32 v55, v75, 16, 1
	s_waitcnt lgkmcnt(0)
	v_add_f32_e32 v47, v76, v47
	ds_bpermute_b32 v50, v40, v47
	v_bfe_u32 v46, v61, 16, 1
	v_add3_u32 v55, v75, v55, s16
	v_add3_u32 v51, v72, v51, s16
	v_add3_u32 v46, v61, v46, s16
	s_waitcnt lgkmcnt(0)
	v_add_f32_e32 v47, v47, v50
	ds_bpermute_b32 v50, v41, v47
	v_lshrrev_b32_e32 v56, 16, v51
	v_lshrrev_b32_e32 v51, 16, v55
	v_and_or_b32 v51, v46, s14, v51
	s_nop 0
	s_waitcnt lgkmcnt(0)
	v_add_f32_e32 v47, v47, v50
	ds_bpermute_b32 v50, v42, v47
	v_bfe_u32 v54, v74, 16, 1
	v_bfe_u32 v48, v60, 16, 1
	s_nop 0
	v_add3_u32 v54, v74, v54, s16
	s_waitcnt lgkmcnt(0)
	v_add_f32_e32 v47, v47, v50
	ds_bpermute_b32 v50, v43, v47
	s_nop 1
	v_add3_u32 v48, v60, v48, s16
	s_nop 0
	s_waitcnt lgkmcnt(0)
	v_add_f32_e32 v46, v47, v50
	ds_bpermute_b32 v47, v44, v46
	v_lshrrev_b32_e32 v54, 16, v54
	v_and_or_b32 v50, v48, s14, v54
	v_cvt_pk_bf16_f32 v49, v73, v59
	v_and_or_b32 v48, v52, s14, v56
	global_store_dwordx4 v[38:39], v[48:51], off offset:3072
	s_and_saveexec_b64 s[10:11], s[0:1]
	s_cbranch_execz .LBB0_1187
	s_waitcnt lgkmcnt(0)
	v_add_f32_e32 v38, v46, v47
	v_fmamk_f32 v38, v38, 0x3a000000, v45
	v_mul_f32_e32 v39, 0x4b800000, v38
	v_cmp_gt_f32_e32 vcc, s15, v38
	v_readlane_b32 s18, v253, 0
	v_readlane_b32 s19, v253, 1
	v_cndmask_b32_e32 v38, v38, v39, vcc
	v_rsq_f32_e32 v38, v38
	s_add_u32 s18, s18, s12
	s_addc_u32 s19, s19, s13
	v_mul_f32_e32 v39, 0x45800000, v38
	v_cndmask_b32_e32 v38, v38, v39, vcc
	global_store_dword v251, v38, s[18:19]
	s_branch .LBB0_1187

; __device__ __forceinline__ void postnorm(const Ctx& c, const bf16* MF, bf16* XB, float* RS, const float* gpost, float* OUT) {
;     for (int row = c.gw; row < MT; row += c.NGW) {
;         const v4u* mr = (const v4u*)(MF + (size_t)row * DM) + c.lane; v4u* xr = (v4u*)(XB + (size_t)row * DM) + c.lane;
;         v4u mv[4], xv[4]; float v[4][8]; float s = 0.f;
; #pragma unroll
;         for (int j = 0; j < 4; ++j) { mv[j] = mr[64 * j]; xv[j] = xr[64 * j]; }
; #pragma unroll
;         for (int j = 0; j < 4; ++j)
; #pragma unroll
;             for (int k = 0; k < 4; ++k) { v[j][2 * k] = bflo(mv[j][k]); v[j][2 * k + 1] = bfhi(mv[j][k]); s += v[j][2 * k] * v[j][2 * k] + v[j][2 * k + 1] * v[j][2 * k + 1]; }
;         const float rs = rsqrtf(wave_sum(s) * (1.f / DM) + EPS);
;         float s2 = 0.f;
; #pragma unroll
;         for (int j = 0; j < 4; ++j) { const float* gp = gpost + (c.lane + 64 * j) * 8; const f32x4 g0 = *(CF4)gp, g1 = *(CF4)(gp + 4);
; #pragma unroll
;             for (int k = 0; k < 4; ++k) { const float ga = (k < 2) ? g0[2 * k] : g1[2 * k - 4], gb = (k < 2) ? g0[2 * k + 1] : g1[2 * k - 3];
;                 v[j][2 * k] = bflo(xv[j][k]) + v[j][2 * k] * rs * ga; v[j][2 * k + 1] = bfhi(xv[j][k]) + v[j][2 * k + 1] * rs * gb;
;                 s2 += v[j][2 * k] * v[j][2 * k] + v[j][2 * k + 1] * v[j][2 * k + 1]; } }
.LBB0_1474:
	v_readlane_b32 s8, v253, 0
	v_readlane_b32 s9, v253, 1
	s_nop 1
	v_lshl_add_u64 v[38:39], s[8:9], 0, v[30:31]
	v_add_co_u32_e32 v58, vcc, 0xd400000, v38
	s_nop 1
	v_addc_co_u32_e32 v59, vcc, 0, v39, vcc
	s_waitcnt lgkmcnt(0)
	global_load_dwordx4 v[46:49], v[58:59], off
	global_load_dwordx4 v[50:53], v[58:59], off offset:1024
	global_load_dwordx4 v[54:57], v[58:59], off offset:2048
	s_nop 0
	global_load_dwordx4 v[58:61], v[58:59], off offset:3072
	v_add_co_u32_e32 v38, vcc, 0x9400000, v38
	s_waitcnt vmcnt(3)
	v_lshlrev_b32_e32 v79, 16, v47
	v_addc_co_u32_e32 v39, vcc, 0, v39, vcc
	global_load_dwordx4 v[62:65], v[38:39], off
	global_load_dwordx4 v[66:69], v[38:39], off offset:1024
	global_load_dwordx4 v[70:73], v[38:39], off offset:2048
	global_load_dwordx4 v[74:77], v[38:39], off offset:3072
	v_lshlrev_b32_e32 v78, 16, v46
	v_and_b32_e32 v47, 0xffff0000, v47
	v_and_b32_e32 v46, 0xffff0000, v46
	v_lshlrev_b32_e32 v81, 16, v49
	v_lshlrev_b32_e32 v80, 16, v48
	v_and_b32_e32 v49, 0xffff0000, v49
	v_and_b32_e32 v48, 0xffff0000, v48
	v_pk_mul_f32 v[94:95], v[46:47], v[46:47]
	v_pk_mul_f32 v[98:99], v[48:49], v[48:49]
	v_pk_fma_f32 v[94:95], v[78:79], v[78:79], v[94:95]
	s_waitcnt vmcnt(6)
	v_lshlrev_b32_e32 v83, 16, v51
	v_lshlrev_b32_e32 v82, 16, v50
	v_and_b32_e32 v51, 0xffff0000, v51
	v_and_b32_e32 v50, 0xffff0000, v50
	v_pk_fma_f32 v[98:99], v[80:81], v[80:81], v[98:99]
	v_add_f32_e32 v94, v94, v95
	v_pk_mul_f32 v[102:103], v[50:51], v[50:51]
	v_add_f32_e32 v94, v98, v94
	v_lshlrev_b32_e32 v85, 16, v53
	v_lshlrev_b32_e32 v84, 16, v52
	v_and_b32_e32 v53, 0xffff0000, v53
	v_and_b32_e32 v52, 0xffff0000, v52
	v_pk_fma_f32 v[102:103], v[82:83], v[82:83], v[102:103]
	v_add_f32_e32 v94, v99, v94
	v_pk_mul_f32 v[104:105], v[52:53], v[52:53]
	v_add_f32_e32 v94, v102, v94
	s_waitcnt vmcnt(5)
	v_lshlrev_b32_e32 v87, 16, v55
	v_lshlrev_b32_e32 v86, 16, v54
	v_and_b32_e32 v55, 0xffff0000, v55
	v_and_b32_e32 v54, 0xffff0000, v54
	v_pk_fma_f32 v[104:105], v[84:85], v[84:85], v[104:105]
	v_add_f32_e32 v94, v103, v94
	v_pk_mul_f32 v[106:107], v[54:55], v[54:55]
	v_add_f32_e32 v94, v104, v94
	v_lshlrev_b32_e32 v89, 16, v57
	v_lshlrev_b32_e32 v88, 16, v56
	v_and_b32_e32 v57, 0xffff0000, v57
	v_and_b32_e32 v56, 0xffff0000, v56
	v_pk_fma_f32 v[106:107], v[86:87], v[86:87], v[106:107]
	v_add_f32_e32 v94, v105, v94
	v_pk_mul_f32 v[108:109], v[56:57], v[56:57]
	v_add_f32_e32 v94, v106, v94
	s_waitcnt vmcnt(4)
	v_lshlrev_b32_e32 v91, 16, v59
	v_lshlrev_b32_e32 v90, 16, v58
	v_and_b32_e32 v59, 0xffff0000, v59
	v_and_b32_e32 v58, 0xffff0000, v58
	v_pk_fma_f32 v[108:109], v[88:89], v[88:89], v[108:109]
	v_add_f32_e32 v94, v107, v94
	v_pk_mul_f32 v[110:111], v[58:59], v[58:59]
	v_add_f32_e32 v94, v108, v94
	v_lshlrev_b32_e32 v93, 16, v61
	v_lshlrev_b32_e32 v92, 16, v60
	v_and_b32_e32 v61, 0xffff0000, v61
	v_and_b32_e32 v60, 0xffff0000, v60
	v_pk_fma_f32 v[110:111], v[90:91], v[90:91], v[110:111]
	v_add_f32_e32 v94, v109, v94
	v_pk_mul_f32 v[112:113], v[60:61], v[60:61]
	v_add_f32_e32 v94, v110, v94
	v_pk_fma_f32 v[112:113], v[92:93], v[92:93], v[112:113]
	v_add_f32_e32 v94, v111, v94
	v_add_f32_e32 v94, v112, v94
	v_add_f32_e32 v94, v113, v94
	ds_bpermute_b32 v98, v3, v94
	s_waitcnt lgkmcnt(0)
	v_add_f32_e32 v98, v94, v98
	ds_bpermute_b32 v102, v40, v98
	s_waitcnt lgkmcnt(0)
	v_add_f32_e32 v102, v98, v102
	ds_bpermute_b32 v104, v41, v102
	s_waitcnt vmcnt(3)
	v_lshlrev_b32_e32 v97, 16, v63
	v_lshlrev_b32_e32 v96, 16, v62
	v_and_b32_e32 v63, 0xffff0000, v63
	s_waitcnt lgkmcnt(0)
	v_add_f32_e32 v104, v102, v104
	ds_bpermute_b32 v106, v42, v104
	v_and_b32_e32 v62, 0xffff0000, v62
	v_lshlrev_b32_e32 v101, 16, v65
	v_lshlrev_b32_e32 v100, 16, v64
	v_and_b32_e32 v65, 0xffff0000, v65
	s_waitcnt lgkmcnt(0)
	v_add_f32_e32 v106, v104, v106
	ds_bpermute_b32 v108, v43, v106
	v_and_b32_e32 v64, 0xffff0000, v64
	s_waitcnt vmcnt(0)
	v_lshlrev_b32_e32 v109, 16, v77
	v_and_b32_e32 v77, 0xffff0000, v77
	v_lshlrev_b32_e32 v95, 16, v67
	s_waitcnt lgkmcnt(0)
	v_add_f32_e32 v108, v106, v108
	ds_bpermute_b32 v110, v44, v108
	v_lshlrev_b32_e32 v94, 16, v66
	v_and_b32_e32 v67, 0xffff0000, v67
	v_and_b32_e32 v66, 0xffff0000, v66
	v_lshlrev_b32_e32 v99, 16, v69
	s_waitcnt lgkmcnt(0)
	v_add_f32_e32 v108, v108, v110
	v_fmamk_f32 v108, v108, 0x3a000000, v45
	v_mul_f32_e32 v110, 0x4b800000, v108
	v_cmp_gt_f32_e32 vcc, s13, v108
	v_lshlrev_b32_e32 v98, 16, v68
	v_and_b32_e32 v69, 0xffff0000, v69
	v_cndmask_b32_e32 v108, v108, v110, vcc
	v_rsq_f32_e32 v110, v108
	v_lshlrev_b32_e32 v108, 16, v76
	v_and_b32_e32 v76, 0xffff0000, v76
	v_and_b32_e32 v68, 0xffff0000, v68
	v_mul_f32_e32 v111, 0x45800000, v110
	v_cndmask_b32_e32 v110, v110, v111, vcc
	v_pk_mul_f32 v[46:47], v[110:111], v[46:47] op_sel_hi:[0,1]
	v_pk_mul_f32 v[78:79], v[110:111], v[78:79] op_sel_hi:[0,1]
	v_pk_mul_f32 v[48:49], v[110:111], v[48:49] op_sel_hi:[0,1]
	v_pk_fma_f32 v[46:47], v[36:37], v[46:47], v[62:63]
	v_pk_mul_f32 v[60:61], v[110:111], v[60:61] op_sel_hi:[0,1]
	v_pk_mul_f32 v[80:81], v[110:111], v[80:81] op_sel_hi:[0,1]
	v_pk_fma_f32 v[78:79], v[8:9], v[78:79], v[96:97]
	v_pk_fma_f32 v[48:49], v[10:11], v[48:49], v[64:65]
	v_pk_fma_f32 v[60:61], v[34:35], v[60:61], v[76:77]
	v_pk_mul_f32 v[76:77], v[46:47], v[46:47]
	v_pk_mul_f32 v[50:51], v[110:111], v[50:51] op_sel_hi:[0,1]
	v_pk_fma_f32 v[62:63], v[4:5], v[80:81], v[100:101]
	v_pk_fma_f32 v[76:77], v[78:79], v[78:79], v[76:77]
	v_pk_mul_f32 v[80:81], v[48:49], v[48:49]
	v_pk_mul_f32 v[82:83], v[110:111], v[82:83] op_sel_hi:[0,1]
	v_pk_fma_f32 v[50:51], v[6:7], v[50:51], v[66:67]
	v_pk_fma_f32 v[80:81], v[62:63], v[62:63], v[80:81]
	v_add_f32_e32 v76, v76, v77
; __device__ __forceinline__ unsigned pk2(float lo, float hi) { return f2bf(lo) | (f2bf(hi) << 16); }
; __device__ __forceinline__ void postnorm(const Ctx& c, const bf16* MF, bf16* XB, float* RS, const float* gpost, float* OUT) {
;     ...
;         const float rs = rsqrtf(wave_sum(s) * (1.f / DM) + EPS);
;         float s2 = 0.f;
; #pragma unroll
;         for (int j = 0; j < 4; ++j) { const float* gp = gpost + (c.lane + 64 * j) * 8; const f32x4 g0 = *(CF4)gp, g1 = *(CF4)(gp + 4);
; #pragma unroll
;             for (int k = 0; k < 4; ++k) { const float ga = (k < 2) ? g0[2 * k] : g1[2 * k - 4], gb = (k < 2) ? g0[2 * k + 1] : g1[2 * k - 3];
;                 v[j][2 * k] = bflo(xv[j][k]) + v[j][2 * k] * rs * ga; v[j][2 * k + 1] = bfhi(xv[j][k]) + v[j][2 * k + 1] * rs * gb;
;                 s2 += v[j][2 * k] * v[j][2 * k] + v[j][2 * k + 1] * v[j][2 * k + 1]; } }
;         if (OUT) {
; #pragma unroll
;             for (int j = 0; j < 4; ++j) { float* op = OUT + (size_t)row * DM + (c.lane + 64 * j) * 8; *(f32x4*)op = (f32x4){v[j][0], v[j][1], v[j][2], v[j][3]}; *(f32x4*)(op + 4) = (f32x4){v[j][4], v[j][5], v[j][6], v[j][7]}; }
;         } else {
; #pragma unroll
;             for (int j = 0; j < 4; ++j) { v4u o; o.x = pk2(v[j][0], v[j][1]); o.y = pk2(v[j][2], v[j][3]); o.z = pk2(v[j][4], v[j][5]); o.w = pk2(v[j][6], v[j][7]); xr[64 * j] = o; }
;             const float rs2 = rsqrtf(wave_sum(s2) * (1.f / DM) + EPS); if (c.lane == 0) RS[row] = rs2;
	v_pk_fma_f32 v[64:65], v[16:17], v[82:83], v[94:95]
	v_pk_mul_f32 v[82:83], v[50:51], v[50:51]
	v_add_f32_e32 v76, v80, v76
	v_pk_fma_f32 v[82:83], v[64:65], v[64:65], v[82:83]
	v_add_f32_e32 v76, v81, v76
	v_add_f32_e32 v76, v82, v76
	v_bfe_u32 v77, v49, 16, 1
	v_bfe_u32 v80, v48, 16, 1
	v_bfe_u32 v81, v47, 16, 1
	v_bfe_u32 v82, v46, 16, 1
	v_pk_mul_f32 v[52:53], v[110:111], v[52:53] op_sel_hi:[0,1]
	v_add3_u32 v46, v46, v82, s14
	v_add3_u32 v47, v47, v81, s14
	v_add3_u32 v48, v48, v80, s14
	v_add3_u32 v49, v49, v77, s14
	v_bfe_u32 v77, v78, 16, 1
	v_bfe_u32 v80, v79, 16, 1
	v_bfe_u32 v81, v62, 16, 1
	v_bfe_u32 v82, v63, 16, 1
	v_pk_mul_f32 v[84:85], v[110:111], v[84:85] op_sel_hi:[0,1]
	v_pk_fma_f32 v[52:53], v[18:19], v[52:53], v[68:69]
	v_add3_u32 v63, v63, v82, s14
	v_add3_u32 v62, v62, v81, s14
	v_add3_u32 v79, v79, v80, s14
	v_add3_u32 v77, v78, v77, s14
	v_lshlrev_b32_e32 v103, 16, v71
	v_lshlrev_b32_e32 v102, 16, v70
	v_and_b32_e32 v71, 0xffff0000, v71
	v_and_b32_e32 v70, 0xffff0000, v70
	v_pk_fma_f32 v[66:67], v[12:13], v[84:85], v[98:99]
	v_pk_mul_f32 v[54:55], v[110:111], v[54:55] op_sel_hi:[0,1]
	v_pk_mul_f32 v[84:85], v[52:53], v[52:53]
	v_lshrrev_b32_e32 v77, 16, v77
	v_lshrrev_b32_e32 v78, 16, v79
	v_lshrrev_b32_e32 v62, 16, v62
	v_lshrrev_b32_e32 v63, 16, v63
	v_pk_mul_f32 v[68:69], v[110:111], v[86:87] op_sel_hi:[0,1]
	v_pk_fma_f32 v[54:55], v[14:15], v[54:55], v[70:71]
	v_pk_fma_f32 v[84:85], v[66:67], v[66:67], v[84:85]
	v_add_f32_e32 v76, v83, v76
	v_and_or_b32 v49, v49, s12, v63
	v_and_or_b32 v48, v48, s12, v62
	v_and_or_b32 v47, v47, s12, v78
	v_and_or_b32 v46, v46, s12, v77
	v_lshlrev_b32_e32 v105, 16, v73
	v_lshlrev_b32_e32 v104, 16, v72
	v_and_b32_e32 v73, 0xffff0000, v73
	v_and_b32_e32 v72, 0xffff0000, v72
	v_pk_fma_f32 v[68:69], v[24:25], v[68:69], v[102:103]
	v_pk_mul_f32 v[56:57], v[110:111], v[56:57] op_sel_hi:[0,1]
	v_pk_mul_f32 v[86:87], v[54:55], v[54:55]
	v_add_f32_e32 v76, v84, v76
	global_store_dwordx4 v[38:39], v[46:49], off
	v_pk_mul_f32 v[70:71], v[110:111], v[88:89] op_sel_hi:[0,1]
	v_pk_fma_f32 v[56:57], v[26:27], v[56:57], v[72:73]
	v_bfe_u32 v46, v53, 16, 1
	v_bfe_u32 v47, v52, 16, 1
	v_bfe_u32 v48, v51, 16, 1
	v_bfe_u32 v49, v50, 16, 1
	v_pk_fma_f32 v[86:87], v[68:69], v[68:69], v[86:87]
	v_add_f32_e32 v76, v85, v76
	v_add3_u32 v50, v50, v49, s14
	v_add3_u32 v51, v51, v48, s14
	v_add3_u32 v47, v52, v47, s14
	v_add3_u32 v46, v53, v46, s14
	v_bfe_u32 v48, v64, 16, 1
	v_bfe_u32 v49, v65, 16, 1
	v_bfe_u32 v52, v66, 16, 1
	v_bfe_u32 v53, v67, 16, 1
	v_lshlrev_b32_e32 v107, 16, v75
	v_lshlrev_b32_e32 v106, 16, v74
	v_and_b32_e32 v75, 0xffff0000, v75
	v_and_b32_e32 v74, 0xffff0000, v74
	v_pk_fma_f32 v[70:71], v[20:21], v[70:71], v[104:105]
	v_pk_mul_f32 v[58:59], v[110:111], v[58:59] op_sel_hi:[0,1]
	v_pk_mul_f32 v[88:89], v[56:57], v[56:57]
	v_add_f32_e32 v76, v86, v76
	v_add3_u32 v53, v67, v53, s14
	v_add3_u32 v52, v66, v52, s14
	v_add3_u32 v49, v65, v49, s14
	v_add3_u32 v48, v64, v48, s14
	v_pk_mul_f32 v[72:73], v[110:111], v[90:91] op_sel_hi:[0,1]
	v_pk_fma_f32 v[58:59], v[22:23], v[58:59], v[74:75]
	v_pk_fma_f32 v[88:89], v[70:71], v[70:71], v[88:89]
	v_add_f32_e32 v76, v87, v76
	v_lshrrev_b32_e32 v62, 16, v48
	v_lshrrev_b32_e32 v63, 16, v49
	v_lshrrev_b32_e32 v48, 16, v52
	v_lshrrev_b32_e32 v49, 16, v53
	v_pk_fma_f32 v[72:73], v[32:33], v[72:73], v[106:107]
	v_pk_mul_f32 v[90:91], v[58:59], v[58:59]
	v_add_f32_e32 v76, v88, v76
	v_and_or_b32 v49, v46, s12, v49
	v_and_or_b32 v48, v47, s12, v48
	v_and_or_b32 v47, v51, s12, v63
	v_and_or_b32 v46, v50, s12, v62
	v_pk_mul_f32 v[74:75], v[110:111], v[92:93] op_sel_hi:[0,1]
	v_pk_fma_f32 v[90:91], v[72:73], v[72:73], v[90:91]
	v_add_f32_e32 v76, v89, v76
	global_store_dwordx4 v[38:39], v[46:49], off offset:1024
	v_pk_fma_f32 v[74:75], v[28:29], v[74:75], v[108:109]
	v_pk_mul_f32 v[92:93], v[60:61], v[60:61]
	v_bfe_u32 v48, v55, 16, 1
	v_bfe_u32 v49, v54, 16, 1
	v_add_f32_e32 v76, v90, v76
	v_add3_u32 v50, v54, v49, s14
	v_add3_u32 v51, v55, v48, s14
	v_bfe_u32 v48, v68, 16, 1
	v_bfe_u32 v49, v69, 16, 1
	v_bfe_u32 v52, v70, 16, 1
	v_bfe_u32 v53, v71, 16, 1
	v_pk_fma_f32 v[92:93], v[74:75], v[74:75], v[92:93]
	v_add_f32_e32 v76, v91, v76
	v_bfe_u32 v46, v57, 16, 1
	v_bfe_u32 v47, v56, 16, 1
	v_add3_u32 v53, v71, v53, s14
	v_add3_u32 v52, v70, v52, s14
	v_add3_u32 v49, v69, v49, s14
	v_add3_u32 v48, v68, v48, s14
	v_add_f32_e32 v76, v92, v76
	v_add3_u32 v47, v56, v47, s14
	v_add3_u32 v46, v57, v46, s14
	v_lshrrev_b32_e32 v54, 16, v48
	v_lshrrev_b32_e32 v55, 16, v49
	v_lshrrev_b32_e32 v48, 16, v52
	v_lshrrev_b32_e32 v49, 16, v53
	v_add_f32_e32 v76, v93, v76
	v_and_or_b32 v49, v46, s12, v49
	v_and_or_b32 v48, v47, s12, v48
	v_and_or_b32 v47, v51, s12, v55
	v_and_or_b32 v46, v50, s12, v54
	global_store_dwordx4 v[38:39], v[46:49], off offset:2048
	ds_bpermute_b32 v47, v3, v76
	v_bfe_u32 v50, v58, 16, 1
	v_add3_u32 v52, v58, v50, s14
	v_bfe_u32 v51, v72, 16, 1
	v_bfe_u32 v55, v75, 16, 1
	s_waitcnt lgkmcnt(0)
	v_add_f32_e32 v47, v76, v47
	ds_bpermute_b32 v50, v40, v47
	v_bfe_u32 v46, v61, 16, 1
	v_add3_u32 v55, v75, v55, s14
	v_add3_u32 v51, v72, v51, s14
	v_add3_u32 v46, v61, v46, s14
	s_waitcnt lgkmcnt(0)
	v_add_f32_e32 v47, v47, v50
	ds_bpermute_b32 v50, v41, v47
	v_lshrrev_b32_e32 v56, 16, v51
	v_lshrrev_b32_e32 v51, 16, v55
	v_and_or_b32 v51, v46, s12, v51
	s_nop 0
	s_waitcnt lgkmcnt(0)
	v_add_f32_e32 v47, v47, v50
	ds_bpermute_b32 v50, v42, v47
	v_bfe_u32 v54, v74, 16, 1
	v_bfe_u32 v48, v60, 16, 1
	s_nop 0
	v_add3_u32 v54, v74, v54, s14
	s_waitcnt lgkmcnt(0)
	v_add_f32_e32 v47, v47, v50
	ds_bpermute_b32 v50, v43, v47
	s_nop 1
	v_add3_u32 v48, v60, v48, s14
	s_nop 0
	s_waitcnt lgkmcnt(0)
	v_add_f32_e32 v46, v47, v50
	ds_bpermute_b32 v47, v44, v46
	v_lshrrev_b32_e32 v54, 16, v54
	v_and_or_b32 v50, v48, s12, v54
	v_cvt_pk_bf16_f32 v49, v73, v59
	v_and_or_b32 v48, v52, s12, v56
	global_store_dwordx4 v[38:39], v[48:51], off offset:3072
	s_and_saveexec_b64 s[8:9], s[0:1]
	s_cbranch_execz .LBB0_1473
	s_waitcnt lgkmcnt(0)
	v_add_f32_e32 v38, v46, v47
	v_fmamk_f32 v38, v38, 0x3a000000, v45
	v_mul_f32_e32 v39, 0x4b800000, v38
	v_cmp_gt_f32_e32 vcc, s13, v38
	v_readlane_b32 s16, v253, 0
	v_readlane_b32 s17, v253, 1
	v_cndmask_b32_e32 v38, v38, v39, vcc
	v_rsq_f32_e32 v38, v38
	s_add_u32 s16, s16, s10
	s_addc_u32 s17, s17, s11
	v_mul_f32_e32 v39, 0x45800000, v38
	v_cndmask_b32_e32 v38, v38, v39, vcc
	global_store_dword v251, v38, s[16:17]
	s_branch .LBB0_1473

; #define LAS __attribute__((address_space(3)))
; #define LDS_WAIT() asm volatile("s_waitcnt lgkmcnt(0)" ::: "memory")
;     ...
;     for (int it = gw0; it < items; it += ngw) {
;         const int kb = it / nblk, nb = it % nblk, k0 = 64 * kb, n0 = 64 * nb, nq = (lane & 15) * 4, kr = lane >> 4; const bool ok = (n0 + nq) < N;
;         f32x4 v[16];
; #pragma unroll
;         for (int i = 0; i < 16; ++i) v[i] = ok ? __builtin_nontemporal_load((const f32x4*)(W + (size_t)(k0 + 4 * i + kr) * N + n0 + nq)) : (f32x4){0.f, 0.f, 0.f, 0.f};
;         if (gain) {
; #pragma unroll
;             for (int i = 0; i < 16; ++i) v[i] *= gain[k0 + 4 * i + kr]; }
; #pragma unroll
;         for (int i = 0; i < 16; ++i) { LAS float* d = scr + (4 * i + kr) * 65 + nq; d[0] = v[i].x; d[1] = v[i].y; d[2] = v[i].z; d[3] = v[i].w; }
;         LDS_WAIT(); asm volatile("" ::: "memory");
;         const int c8 = lane & 7; int d0 = n0;
;         if (ffnmap) { const int bj = n0 >= FFH ? 1 : 0, chn = n0 - FFH * bj; d0 = 256 * (chn >> 7) + 128 * bj + (chn & 127); }
; #pragma unroll
;         for (int j = 0; j < 8; ++j) { const int n = (lane >> 3) + 8 * j; const LAS float* sp = scr + (8 * c8) * 65 + n;
.LBB0_1484:
	s_or_b64 exec, exec, s[8:9]
	v_lshl_add_u64 v[82:83], v[72:73], 2, s[2:3]
	global_load_dword v72, v[82:83], off
	s_add_i32 s15, s15, s10
	s_ashr_i32 s7, s6, 31
	s_add_i32 s14, s14, s86
	s_add_i32 s10, s10, s11
	s_cmpk_lt_i32 s14, 0x100
	s_waitcnt vmcnt(0)
	v_pk_mul_f32 v[86:87], v[8:9], v[72:73] op_sel_hi:[1,0]
	global_load_dword v8, v[82:83], off offset:16
	v_pk_mul_f32 v[84:85], v[10:11], v[72:73] op_sel_hi:[1,0]
	s_waitcnt vmcnt(0)
	v_pk_mul_f32 v[72:73], v[14:15], v[8:9] op_sel_hi:[1,0]
	v_pk_mul_f32 v[88:89], v[12:13], v[8:9] op_sel_hi:[1,0]
	global_load_dword v8, v[82:83], off offset:32
	global_load_dword v12, v[82:83], off offset:160
	s_waitcnt vmcnt(1)
	v_pk_mul_f32 v[90:91], v[4:5], v[8:9] op_sel_hi:[1,0]
	global_load_dword v4, v[82:83], off offset:48
	v_pk_mul_f32 v[74:75], v[6:7], v[8:9] op_sel_hi:[1,0]
	global_load_dword v6, v[82:83], off offset:128
	global_load_dword v8, v[82:83], off offset:144
	s_waitcnt vmcnt(3)
	v_pk_mul_f32 v[10:11], v[42:43], v[12:13] op_sel_hi:[1,0]
	v_pk_mul_f32 v[12:13], v[40:41], v[12:13] op_sel_hi:[1,0]
	v_add_u32_e32 v40, 0x410, v81
	s_waitcnt vmcnt(2)
	v_pk_mul_f32 v[92:93], v[22:23], v[4:5] op_sel_hi:[1,0]
	v_pk_mul_f32 v[94:95], v[20:21], v[4:5] op_sel_hi:[1,0]
	global_load_dword v4, v[82:83], off offset:64
	global_load_dword v20, v[82:83], off offset:192
	s_waitcnt vmcnt(1)
	v_pk_mul_f32 v[96:97], v[18:19], v[4:5] op_sel_hi:[1,0]
	v_pk_mul_f32 v[98:99], v[16:17], v[4:5] op_sel_hi:[1,0]
	global_load_dword v4, v[82:83], off offset:80
	global_load_dword v16, v[82:83], off offset:176
	s_waitcnt vmcnt(2)
	v_pk_mul_f32 v[18:19], v[50:51], v[20:21] op_sel_hi:[1,0]
	v_pk_mul_f32 v[20:21], v[48:49], v[20:21] op_sel_hi:[1,0]
	s_waitcnt vmcnt(1)
	v_pk_mul_f32 v[100:101], v[30:31], v[4:5] op_sel_hi:[1,0]
	v_pk_mul_f32 v[102:103], v[28:29], v[4:5] op_sel_hi:[1,0]
	global_load_dword v4, v[82:83], off offset:96
	global_load_dword v28, v[82:83], off offset:224
	v_lshl_add_u64 v[30:31], v[76:77], 2, s[2:3]
	s_waitcnt vmcnt(2)
	v_pk_mul_f32 v[14:15], v[54:55], v[16:17] op_sel_hi:[1,0]
	v_pk_mul_f32 v[16:17], v[52:53], v[16:17] op_sel_hi:[1,0]
	s_waitcnt vmcnt(1)
	v_pk_mul_f32 v[104:105], v[26:27], v[4:5] op_sel_hi:[1,0]
	v_pk_mul_f32 v[106:107], v[24:25], v[4:5] op_sel_hi:[1,0]
	global_load_dword v4, v[82:83], off offset:112
	global_load_dword v24, v[82:83], off offset:208
	s_waitcnt vmcnt(2)
	v_pk_mul_f32 v[26:27], v[58:59], v[28:29] op_sel_hi:[1,0]
	v_pk_mul_f32 v[28:29], v[56:57], v[28:29] op_sel_hi:[1,0]
	s_waitcnt vmcnt(1)
	v_pk_mul_f32 v[38:39], v[38:39], v[4:5] op_sel_hi:[1,0]
	v_pk_mul_f32 v[36:37], v[36:37], v[4:5] op_sel_hi:[1,0]
	v_pk_mul_f32 v[4:5], v[34:35], v[6:7] op_sel_hi:[1,0]
	v_pk_mul_f32 v[34:35], v[32:33], v[6:7] op_sel_hi:[1,0]
	global_load_dword v32, v[30:31], off
	ds_write2_b32 v81, v86, v87 offset1:1
	ds_write2_b32 v81, v84, v85 offset0:2 offset1:3
	ds_write2_b32 v40, v88, v89 offset1:1
	v_add_u32_e32 v40, 0x418, v81
	ds_write2_b32 v40, v72, v73 offset1:1
	v_add_u32_e32 v40, 0x820, v81
	ds_write2_b32 v40, v90, v91 offset1:1
	v_add_u32_e32 v40, 0x828, v81
	ds_write2_b32 v40, v74, v75 offset1:1
	v_add_u32_e32 v40, 0xc30, v81
	ds_write2_b32 v40, v94, v95 offset1:1
	v_add_u32_e32 v40, 0xc38, v81
	ds_write2_b32 v40, v92, v93 offset1:1
	v_add_u32_e32 v40, 0x1040, v81
	ds_write2_b32 v40, v98, v99 offset1:1
	v_add_u32_e32 v40, 0x1048, v81
	ds_write2_b32 v40, v96, v97 offset1:1
	v_add_u32_e32 v40, 0x1450, v81
	ds_write2_b32 v40, v102, v103 offset1:1
	v_add_u32_e32 v40, 0x1458, v81
	ds_write2_b32 v40, v100, v101 offset1:1
	v_add_u32_e32 v40, 0x1860, v81
	ds_write2_b32 v40, v106, v107 offset1:1
	v_add_u32_e32 v40, 0x1868, v81
	ds_write2_b32 v40, v104, v105 offset1:1
	v_add_u32_e32 v40, 0x1c70, v81
	ds_write2_b32 v40, v36, v37 offset1:1
	v_add_u32_e32 v36, 0x1c78, v81
	ds_write2_b32 v36, v38, v39 offset1:1
	v_add_u32_e32 v36, 0x2080, v81
	ds_write2_b32 v36, v34, v35 offset1:1
	v_add_u32_e32 v34, 0x2088, v81
	v_pk_mul_f32 v[6:7], v[46:47], v[8:9] op_sel_hi:[1,0]
	v_pk_mul_f32 v[8:9], v[44:45], v[8:9] op_sel_hi:[1,0]
	ds_write2_b32 v34, v4, v5 offset1:1
	v_add_u32_e32 v4, 0x2490, v81
	ds_write2_b32 v4, v8, v9 offset1:1
	v_add_u32_e32 v4, 0x2498, v81
	ds_write2_b32 v4, v6, v7 offset1:1
	v_add_u32_e32 v4, 0x28a0, v81
	ds_write2_b32 v4, v12, v13 offset1:1
	v_add_u32_e32 v4, 0x28a8, v81
	ds_write2_b32 v4, v10, v11 offset1:1
	v_add_u32_e32 v4, 0x2cb0, v81
	ds_write2_b32 v4, v16, v17 offset1:1
	v_add_u32_e32 v4, 0x2cb8, v81
	ds_write2_b32 v4, v14, v15 offset1:1
	v_add_u32_e32 v4, 0x30c0, v81
	ds_write2_b32 v4, v20, v21 offset1:1
	v_add_u32_e32 v4, 0x30c8, v81
	s_waitcnt vmcnt(1)
	v_pk_mul_f32 v[22:23], v[62:63], v[24:25] op_sel_hi:[1,0]
	v_pk_mul_f32 v[24:25], v[60:61], v[24:25] op_sel_hi:[1,0]
	ds_write2_b32 v4, v18, v19 offset1:1
	v_add_u32_e32 v4, 0x34d0, v81
	ds_write2_b32 v4, v24, v25 offset1:1
	v_add_u32_e32 v4, 0x34d8, v81
	ds_write2_b32 v4, v22, v23 offset1:1
	v_add_u32_e32 v4, 0x38e0, v81
	ds_write2_b32 v4, v28, v29 offset1:1
	v_add_u32_e32 v4, 0x38e8, v81
	ds_write2_b32 v4, v26, v27 offset1:1
	v_add_u32_e32 v4, 0x3cf0, v81
	s_waitcnt vmcnt(0)
	v_pk_mul_f32 v[30:31], v[66:67], v[32:33] op_sel_hi:[1,0]
	v_pk_mul_f32 v[32:33], v[64:65], v[32:33] op_sel_hi:[1,0]
	ds_write2_b32 v4, v32, v33 offset1:1
	v_add_u32_e32 v4, 0x3cf8, v81
	ds_write2_b32 v4, v30, v31 offset1:1
	s_waitcnt lgkmcnt(0)
	ds_read2_b32 v[8:9], v80 offset0:65 offset1:73
	ds_read2_b32 v[14:15], v80 offset1:8
	ds_read2_b32 v[16:17], v80 offset0:130 offset1:138
	ds_read2_b32 v[18:19], v80 offset0:195 offset1:203
	v_lshl_add_u64 v[4:5], s[6:7], 1, v[70:71]
	s_waitcnt lgkmcnt(3)
	v_bfe_u32 v7, v8, 16, 1
	s_waitcnt lgkmcnt(2)
; #define LAS __attribute__((address_space(3)))
; #define LDS_WAIT() asm volatile("s_waitcnt lgkmcnt(0)" ::: "memory")
; __device__ __forceinline__ unsigned pk2(float lo, float hi) { return f2bf(lo) | (f2bf(hi) << 16); }
;     ...
;         const int c8 = lane & 7; int d0 = n0;
;         if (ffnmap) { const int bj = n0 >= FFH ? 1 : 0, chn = n0 - FFH * bj; d0 = 256 * (chn >> 7) + 128 * bj + (chn & 127); }
; #pragma unroll
;         for (int j = 0; j < 8; ++j) { const int n = (lane >> 3) + 8 * j; const LAS float* sp = scr + (8 * c8) * 65 + n;
;             v4u o; o.x = pk2(sp[0 * 65], sp[1 * 65]); o.y = pk2(sp[2 * 65], sp[3 * 65]); o.z = pk2(sp[4 * 65], sp[5 * 65]); o.w = pk2(sp[6 * 65], sp[7 * 65]);
;             *(v4u*)(WT + (size_t)(d0 + n) * K + k0 + 8 * c8) = o; }
;         LDS_WAIT(); asm volatile("" ::: "memory");
	v_bfe_u32 v6, v14, 16, 1
	v_add3_u32 v6, v14, v6, s12
	v_add3_u32 v7, v8, v7, s12
	v_add_u32_e32 v8, 0x400, v80
	v_lshrrev_b32_e32 v6, 16, v6
	ds_read2_b32 v[20:21], v8 offset0:4 offset1:12
	ds_read2_b32 v[22:23], v8 offset0:69 offset1:77
	v_and_or_b32 v10, v7, s13, v6
	s_waitcnt lgkmcnt(3)
	s_nop 1
	s_waitcnt lgkmcnt(2)
	s_nop 2
	ds_read2_b32 v[24:25], v8 offset0:134 offset1:142
	ds_read2_b32 v[26:27], v8 offset0:199 offset1:207
	v_cvt_pk_bf16_f32 v11, v16, v18
	s_waitcnt lgkmcnt(3)
	s_nop 1
	s_waitcnt lgkmcnt(2)
	s_nop 2
	v_cvt_pk_bf16_f32 v12, v20, v22
	s_waitcnt lgkmcnt(1)
	s_nop 1
	s_waitcnt lgkmcnt(0)
	s_nop 2
	v_cvt_pk_bf16_f32 v13, v24, v26
	v_add_u32_e32 v6, s15, v79
	v_ashrrev_i32_e32 v7, 31, v6
	v_lshlrev_b64 v[28:29], 12, v[6:7]
	v_lshl_add_u64 v[28:29], v[4:5], 0, v[28:29]
	v_bfe_u32 v7, v15, 16, 1
	global_store_dwordx4 v[28:29], v[10:13], off
	v_add3_u32 v7, v15, v7, s12
	v_lshrrev_b32_e32 v7, 16, v7
	v_bfe_u32 v10, v9, 16, 1
	v_add3_u32 v9, v9, v10, s12
	v_and_or_b32 v10, v9, s13, v7
	s_nop 4
	v_cvt_pk_bf16_f32 v11, v17, v19
	s_nop 4
	v_cvt_pk_bf16_f32 v12, v21, v23
	s_nop 0
	v_add_u32_e32 v14, 8, v6
	s_nop 1
	v_ashrrev_i32_e32 v15, 31, v14
	s_nop 1
	v_lshlrev_b64 v[14:15], 12, v[14:15]
	v_cvt_pk_bf16_f32 v13, v25, v27
	v_lshl_add_u64 v[14:15], v[4:5], 0, v[14:15]
	global_store_dwordx4 v[14:15], v[10:13], off
	ds_read2_b32 v[14:15], v80 offset0:81 offset1:89
	ds_read2_b32 v[16:17], v80 offset0:16 offset1:24
	ds_read2_b32 v[18:19], v80 offset0:146 offset1:154
	ds_read2_b32 v[20:21], v80 offset0:211 offset1:219
	ds_read2_b32 v[22:23], v8 offset0:20 offset1:28
	ds_read2_b32 v[24:25], v8 offset0:85 offset1:93
	ds_read2_b32 v[26:27], v8 offset0:150 offset1:158
	ds_read2_b32 v[28:29], v8 offset0:215 offset1:223
	s_waitcnt lgkmcnt(7)
	s_nop 0
	s_waitcnt lgkmcnt(6)
	s_nop 3
	v_cvt_pk_bf16_f32 v10, v16, v14
	s_waitcnt lgkmcnt(5)
	s_nop 1
	s_waitcnt lgkmcnt(4)
	s_nop 2
	v_cvt_pk_bf16_f32 v11, v18, v20
	s_waitcnt lgkmcnt(3)
	s_nop 1
	s_waitcnt lgkmcnt(2)
	s_nop 2
	v_cvt_pk_bf16_f32 v12, v22, v24
	s_waitcnt lgkmcnt(1)
	s_nop 1
	s_waitcnt lgkmcnt(0)
	s_nop 2
	v_add_u32_e32 v30, 16, v6
	v_cvt_pk_bf16_f32 v13, v26, v28
	v_ashrrev_i32_e32 v31, 31, v30
	v_bfe_u32 v7, v17, 16, 1
	v_lshlrev_b64 v[30:31], 12, v[30:31]
	v_add3_u32 v7, v17, v7, s12
	v_bfe_u32 v9, v15, 16, 1
	v_lshl_add_u64 v[30:31], v[4:5], 0, v[30:31]
	v_lshrrev_b32_e32 v7, 16, v7
	v_add3_u32 v9, v15, v9, s12
	global_store_dwordx4 v[30:31], v[10:13], off
	v_add_u32_e32 v14, 24, v6
	v_ashrrev_i32_e32 v15, 31, v14
	v_and_or_b32 v10, v9, s13, v7
	s_nop 4
	v_cvt_pk_bf16_f32 v11, v19, v21
	s_nop 4
	v_cvt_pk_bf16_f32 v12, v23, v25
	s_nop 4
	v_lshlrev_b64 v[14:15], 12, v[14:15]
	v_cvt_pk_bf16_f32 v13, v27, v29
	v_lshl_add_u64 v[14:15], v[4:5], 0, v[14:15]
	global_store_dwordx4 v[14:15], v[10:13], off
	ds_read2_b32 v[14:15], v80 offset0:97 offset1:105
	ds_read2_b32 v[16:17], v80 offset0:32 offset1:40
	ds_read2_b32 v[18:19], v80 offset0:162 offset1:170
	ds_read2_b32 v[20:21], v80 offset0:227 offset1:235
	ds_read2_b32 v[22:23], v8 offset0:36 offset1:44
	ds_read2_b32 v[24:25], v8 offset0:101 offset1:109
	ds_read2_b32 v[26:27], v8 offset0:166 offset1:174
	ds_read2_b32 v[28:29], v8 offset0:231 offset1:239
	s_waitcnt lgkmcnt(7)
	s_nop 0
	s_waitcnt lgkmcnt(6)
	s_nop 3
	v_cvt_pk_bf16_f32 v10, v16, v14
	s_waitcnt lgkmcnt(5)
	s_nop 1
	s_waitcnt lgkmcnt(4)
	s_nop 2
	v_cvt_pk_bf16_f32 v11, v18, v20
	s_waitcnt lgkmcnt(3)
	s_nop 1
	s_waitcnt lgkmcnt(2)
	s_nop 2
	v_cvt_pk_bf16_f32 v12, v22, v24
	s_waitcnt lgkmcnt(1)
	s_nop 1
	s_waitcnt lgkmcnt(0)
	s_nop 2
	v_add_u32_e32 v30, 32, v6
	v_cvt_pk_bf16_f32 v13, v26, v28
	v_ashrrev_i32_e32 v31, 31, v30
	v_bfe_u32 v7, v17, 16, 1
	v_lshlrev_b64 v[30:31], 12, v[30:31]
	v_add3_u32 v7, v17, v7, s12
	v_bfe_u32 v9, v15, 16, 1
	v_lshl_add_u64 v[30:31], v[4:5], 0, v[30:31]
	v_lshrrev_b32_e32 v7, 16, v7
	v_add3_u32 v9, v15, v9, s12
	global_store_dwordx4 v[30:31], v[10:13], off
	v_add_u32_e32 v14, 40, v6
	v_ashrrev_i32_e32 v15, 31, v14
	v_and_or_b32 v10, v9, s13, v7
	s_nop 4
	v_cvt_pk_bf16_f32 v11, v19, v21
	s_nop 4
	v_cvt_pk_bf16_f32 v12, v23, v25
	s_nop 4
	v_lshlrev_b64 v[14:15], 12, v[14:15]
	v_cvt_pk_bf16_f32 v13, v27, v29
	v_lshl_add_u64 v[14:15], v[4:5], 0, v[14:15]
	global_store_dwordx4 v[14:15], v[10:13], off
	ds_read2_b32 v[14:15], v80 offset0:48 offset1:56
	ds_read2_b32 v[16:17], v80 offset0:113 offset1:121
	ds_read2_b32 v[18:19], v80 offset0:178 offset1:186
	ds_read2_b32 v[20:21], v80 offset0:243 offset1:251
	ds_read2_b32 v[22:23], v8 offset0:52 offset1:60
	ds_read2_b32 v[24:25], v8 offset0:117 offset1:125
	ds_read2_b32 v[26:27], v8 offset0:182 offset1:190
	ds_read2_b32 v[28:29], v8 offset0:247 offset1:255
	s_waitcnt lgkmcnt(7)
	s_nop 1
	s_waitcnt lgkmcnt(6)
	s_nop 2
	v_cvt_pk_bf16_f32 v10, v14, v16
	s_waitcnt lgkmcnt(5)
	s_nop 1
	s_waitcnt lgkmcnt(4)
	s_nop 2
	v_cvt_pk_bf16_f32 v11, v18, v20
	s_waitcnt lgkmcnt(3)
	s_nop 1
	s_waitcnt lgkmcnt(2)
	s_nop 2
	v_cvt_pk_bf16_f32 v12, v22, v24
	s_waitcnt lgkmcnt(1)
	s_nop 1
	s_waitcnt lgkmcnt(0)
	s_nop 2
	v_cvt_pk_bf16_f32 v13, v26, v28
	v_add_u32_e32 v8, 48, v6
	v_ashrrev_i32_e32 v9, 31, v8
	v_lshlrev_b64 v[8:9], 12, v[8:9]
	v_lshl_add_u64 v[8:9], v[4:5], 0, v[8:9]
	v_bfe_u32 v7, v15, 16, 1
	global_store_dwordx4 v[8:9], v[10:13], off
	v_add3_u32 v7, v15, v7, s12
	v_bfe_u32 v8, v17, 16, 1
	v_lshrrev_b32_e32 v7, 16, v7
	v_add3_u32 v8, v17, v8, s12
	v_and_or_b32 v8, v8, s13, v7
	s_nop 4
	v_cvt_pk_bf16_f32 v9, v19, v21
	s_nop 4
	v_cvt_pk_bf16_f32 v10, v23, v25
	s_nop 4
	v_add_u32_e32 v6, 56, v6
	v_cvt_pk_bf16_f32 v11, v27, v29
	v_ashrrev_i32_e32 v7, 31, v6
	v_lshlrev_b64 v[6:7], 12, v[6:7]
	v_lshl_add_u64 v[4:5], v[4:5], 0, v[6:7]
	global_store_dwordx4 v[4:5], v[8:11], off
	s_waitcnt lgkmcnt(0)
	s_cbranch_scc0 .LBB0_1517

; #define LAS __attribute__((address_space(3)))
; #define LDS_WAIT() asm volatile("s_waitcnt lgkmcnt(0)" ::: "memory")
; __device__ __forceinline__ unsigned pk2(float lo, float hi) { return f2bf(lo) | (f2bf(hi) << 16); }
;     ...
;         for (int i = 0; i < 16; ++i) { LAS float* d = scr + (4 * i + kr) * 65 + nq; d[0] = v[i].x; d[1] = v[i].y; d[2] = v[i].z; d[3] = v[i].w; }
;         LDS_WAIT(); asm volatile("" ::: "memory");
;         const int c8 = lane & 7; int d0 = n0;
;         if (ffnmap) { const int bj = n0 >= FFH ? 1 : 0, chn = n0 - FFH * bj; d0 = 256 * (chn >> 7) + 128 * bj + (chn & 127); }
; #pragma unroll
;         for (int j = 0; j < 8; ++j) { const int n = (lane >> 3) + 8 * j; const LAS float* sp = scr + (8 * c8) * 65 + n;
;             v4u o; o.x = pk2(sp[0 * 65], sp[1 * 65]); o.y = pk2(sp[2 * 65], sp[3 * 65]); o.z = pk2(sp[4 * 65], sp[5 * 65]); o.w = pk2(sp[6 * 65], sp[7 * 65]);
;             *(v4u*)(WT + (size_t)(d0 + n) * K + k0 + 8 * c8) = o; }
;         LDS_WAIT(); asm volatile("" ::: "memory");
.LBB0_1520:
	s_or_b64 exec, exec, s[6:7]
	s_waitcnt vmcnt(0)
	ds_write2_b32 v79, v4, v5 offset1:1
	ds_write2_b32 v79, v6, v7 offset0:2 offset1:3
	v_add_u32_e32 v4, 0x410, v79
	ds_write2_b32 v4, v12, v13 offset1:1
	v_add_u32_e32 v4, 0x418, v79
	ds_write2_b32 v4, v14, v15 offset1:1
	v_add_u32_e32 v4, 0x820, v79
	ds_write2_b32 v4, v8, v9 offset1:1
	v_add_u32_e32 v4, 0x828, v79
	ds_write2_b32 v4, v10, v11 offset1:1
	v_add_u32_e32 v4, 0xc30, v79
	ds_write2_b32 v4, v20, v21 offset1:1
	v_add_u32_e32 v4, 0xc38, v79
	ds_write2_b32 v4, v22, v23 offset1:1
	v_add_u32_e32 v4, 0x1040, v79
	ds_write2_b32 v4, v16, v17 offset1:1
	v_add_u32_e32 v4, 0x1048, v79
	ds_write2_b32 v4, v18, v19 offset1:1
	v_add_u32_e32 v4, 0x1450, v79
	ds_write2_b32 v4, v28, v29 offset1:1
	v_add_u32_e32 v4, 0x1458, v79
	ds_write2_b32 v4, v30, v31 offset1:1
	v_add_u32_e32 v4, 0x1860, v79
	ds_write2_b32 v4, v24, v25 offset1:1
	v_add_u32_e32 v4, 0x1868, v79
	ds_write2_b32 v4, v26, v27 offset1:1
	v_add_u32_e32 v4, 0x1c70, v79
	ds_write2_b32 v4, v36, v37 offset1:1
	v_add_u32_e32 v4, 0x1c78, v79
	ds_write2_b32 v4, v38, v39 offset1:1
	v_add_u32_e32 v4, 0x2080, v79
	ds_write2_b32 v4, v32, v33 offset1:1
	v_add_u32_e32 v4, 0x2088, v79
	ds_write2_b32 v4, v34, v35 offset1:1
	v_add_u32_e32 v4, 0x2490, v79
	ds_write2_b32 v4, v44, v45 offset1:1
	v_add_u32_e32 v4, 0x2498, v79
	ds_write2_b32 v4, v46, v47 offset1:1
	v_add_u32_e32 v4, 0x28a0, v79
	ds_write2_b32 v4, v40, v41 offset1:1
	v_add_u32_e32 v4, 0x28a8, v79
	ds_write2_b32 v4, v42, v43 offset1:1
	v_add_u32_e32 v4, 0x2cb0, v79
	ds_write2_b32 v4, v52, v53 offset1:1
	v_add_u32_e32 v4, 0x2cb8, v79
	ds_write2_b32 v4, v54, v55 offset1:1
	v_add_u32_e32 v4, 0x30c0, v79
	ds_write2_b32 v4, v48, v49 offset1:1
	v_add_u32_e32 v4, 0x30c8, v79
	ds_write2_b32 v4, v50, v51 offset1:1
	v_add_u32_e32 v4, 0x34d0, v79
	ds_write2_b32 v4, v60, v61 offset1:1
	v_add_u32_e32 v4, 0x34d8, v79
	ds_write2_b32 v4, v62, v63 offset1:1
	v_add_u32_e32 v4, 0x38e0, v79
	ds_write2_b32 v4, v56, v57 offset1:1
	v_add_u32_e32 v4, 0x38e8, v79
	ds_write2_b32 v4, v58, v59 offset1:1
	v_add_u32_e32 v4, 0x3cf0, v79
	ds_write2_b32 v4, v64, v65 offset1:1
	v_add_u32_e32 v4, 0x3cf8, v79
	ds_write2_b32 v4, v66, v67 offset1:1
	s_waitcnt lgkmcnt(0)
	ds_read2_b32 v[12:13], v78 offset1:8
	ds_read2_b32 v[14:15], v78 offset0:65 offset1:73
	ds_read2_b32 v[16:17], v78 offset0:130 offset1:138
	ds_read2_b32 v[18:19], v78 offset0:195 offset1:203
	v_add_u32_e32 v30, 0x400, v78
	s_waitcnt lgkmcnt(3)
	s_nop 1
	s_waitcnt lgkmcnt(2)
	s_nop 0
	ds_read2_b32 v[20:21], v30 offset0:4 offset1:12
	s_nop 1
	ds_read2_b32 v[22:23], v30 offset0:69 offset1:77
	v_cvt_pk_bf16_f32 v8, v12, v14
	s_waitcnt lgkmcnt(3)
	s_nop 1
	s_waitcnt lgkmcnt(2)
	s_nop 0
	ds_read2_b32 v[24:25], v30 offset0:134 offset1:142
	s_nop 1
	ds_read2_b32 v[26:27], v30 offset0:199 offset1:207
	v_cvt_pk_bf16_f32 v9, v16, v18
	s_waitcnt lgkmcnt(3)
	s_nop 1
	s_waitcnt lgkmcnt(2)
	s_nop 2
	v_cvt_pk_bf16_f32 v10, v20, v22
	s_waitcnt lgkmcnt(1)
	s_nop 1
	s_waitcnt lgkmcnt(0)
	s_nop 2
	s_add_i32 s16, s16, s12
	v_cvt_pk_bf16_f32 v11, v24, v26
	v_add_u32_e32 v6, s16, v77
	s_ashr_i32 s3, s2, 31
	v_ashrrev_i32_e32 v7, 31, v6
	v_lshl_add_u64 v[4:5], s[2:3], 1, v[70:71]
	v_lshlrev_b64 v[28:29], 12, v[6:7]
	v_lshl_add_u64 v[28:29], v[4:5], 0, v[28:29]
	v_bfe_u32 v7, v13, 16, 1
	global_store_dwordx4 v[28:29], v[8:11], off
	v_add3_u32 v7, v13, v7, s14
	v_lshrrev_b32_e32 v7, 16, v7
	v_bfe_u32 v8, v15, 16, 1
	v_add3_u32 v8, v15, v8, s14
	v_and_or_b32 v8, v8, s15, v7
	s_nop 4
	v_cvt_pk_bf16_f32 v9, v17, v19
	s_nop 4
	v_cvt_pk_bf16_f32 v10, v21, v23
	s_nop 0
	v_add_u32_e32 v12, 8, v6
	s_nop 1
	v_ashrrev_i32_e32 v13, 31, v12
	s_nop 1
	v_lshlrev_b64 v[12:13], 12, v[12:13]
	v_cvt_pk_bf16_f32 v11, v25, v27
	ds_read2_b32 v[14:15], v78 offset0:16 offset1:24
	v_lshl_add_u64 v[12:13], v[4:5], 0, v[12:13]
	global_store_dwordx4 v[12:13], v[8:11], off
	ds_read2_b32 v[12:13], v78 offset0:81 offset1:89
	ds_read2_b32 v[16:17], v78 offset0:146 offset1:154
	ds_read2_b32 v[18:19], v78 offset0:211 offset1:219
	s_waitcnt lgkmcnt(3)
	s_nop 1
	s_waitcnt lgkmcnt(2)
	s_nop 0
	ds_read2_b32 v[20:21], v30 offset0:20 offset1:28
	s_nop 1
	ds_read2_b32 v[22:23], v30 offset0:85 offset1:93
	v_cvt_pk_bf16_f32 v8, v14, v12
	s_waitcnt lgkmcnt(3)
; #define LAS __attribute__((address_space(3)))
; #define LDS_WAIT() asm volatile("s_waitcnt lgkmcnt(0)" ::: "memory")
; __device__ __forceinline__ unsigned pk2(float lo, float hi) { return f2bf(lo) | (f2bf(hi) << 16); }
;     ...
; #pragma unroll
;         for (int j = 0; j < 8; ++j) { const int n = (lane >> 3) + 8 * j; const LAS float* sp = scr + (8 * c8) * 65 + n;
;             v4u o; o.x = pk2(sp[0 * 65], sp[1 * 65]); o.y = pk2(sp[2 * 65], sp[3 * 65]); o.z = pk2(sp[4 * 65], sp[5 * 65]); o.w = pk2(sp[6 * 65], sp[7 * 65]);
;             *(v4u*)(WT + (size_t)(d0 + n) * K + k0 + 8 * c8) = o; }
;         LDS_WAIT(); asm volatile("" ::: "memory");
	s_nop 1
	s_waitcnt lgkmcnt(2)
	s_nop 0
	ds_read2_b32 v[24:25], v30 offset0:150 offset1:158
	s_nop 1
	ds_read2_b32 v[26:27], v30 offset0:215 offset1:223
	v_cvt_pk_bf16_f32 v9, v16, v18
	s_waitcnt lgkmcnt(3)
	s_nop 1
	s_waitcnt lgkmcnt(2)
	s_nop 2
	v_cvt_pk_bf16_f32 v10, v20, v22
	s_waitcnt lgkmcnt(1)
	s_nop 0
	v_add_u32_e32 v28, 16, v6
	s_nop 0
	s_waitcnt lgkmcnt(0)
	s_nop 0
	v_ashrrev_i32_e32 v29, 31, v28
	s_nop 1
	v_lshlrev_b64 v[28:29], 12, v[28:29]
	v_cvt_pk_bf16_f32 v11, v24, v26
	v_lshl_add_u64 v[28:29], v[4:5], 0, v[28:29]
	v_bfe_u32 v7, v15, 16, 1
	global_store_dwordx4 v[28:29], v[8:11], off
	v_add3_u32 v7, v15, v7, s14
	v_lshrrev_b32_e32 v7, 16, v7
	v_bfe_u32 v8, v13, 16, 1
	v_add3_u32 v8, v13, v8, s14
	v_and_or_b32 v8, v8, s15, v7
	s_nop 4
	v_cvt_pk_bf16_f32 v9, v17, v19
	s_nop 4
	v_cvt_pk_bf16_f32 v10, v21, v23
	s_nop 0
	v_add_u32_e32 v12, 24, v6
	s_nop 1
	v_ashrrev_i32_e32 v13, 31, v12
	s_nop 1
	v_lshlrev_b64 v[12:13], 12, v[12:13]
	v_cvt_pk_bf16_f32 v11, v25, v27
	ds_read2_b32 v[14:15], v78 offset0:32 offset1:40
	v_lshl_add_u64 v[12:13], v[4:5], 0, v[12:13]
	global_store_dwordx4 v[12:13], v[8:11], off
	ds_read2_b32 v[12:13], v78 offset0:97 offset1:105
	ds_read2_b32 v[16:17], v78 offset0:162 offset1:170
	ds_read2_b32 v[18:19], v78 offset0:227 offset1:235
	s_waitcnt lgkmcnt(3)
	s_nop 1
	s_waitcnt lgkmcnt(2)
	s_nop 0
	ds_read2_b32 v[20:21], v30 offset0:36 offset1:44
	s_nop 1
	ds_read2_b32 v[22:23], v30 offset0:101 offset1:109
	v_cvt_pk_bf16_f32 v8, v14, v12
	s_waitcnt lgkmcnt(3)
	s_nop 1
	s_waitcnt lgkmcnt(2)
	s_nop 0
	ds_read2_b32 v[24:25], v30 offset0:166 offset1:174
	s_nop 1
	ds_read2_b32 v[26:27], v30 offset0:231 offset1:239
	v_cvt_pk_bf16_f32 v9, v16, v18
	s_waitcnt lgkmcnt(3)
	s_nop 1
	s_waitcnt lgkmcnt(2)
	s_nop 2
	v_cvt_pk_bf16_f32 v10, v20, v22
	s_waitcnt lgkmcnt(1)
	s_nop 0
	v_add_u32_e32 v28, 32, v6
	s_nop 0
	s_waitcnt lgkmcnt(0)
	s_nop 0
	v_ashrrev_i32_e32 v29, 31, v28
	s_nop 1
	v_lshlrev_b64 v[28:29], 12, v[28:29]
	v_cvt_pk_bf16_f32 v11, v24, v26
	v_lshl_add_u64 v[28:29], v[4:5], 0, v[28:29]
	v_bfe_u32 v7, v15, 16, 1
	global_store_dwordx4 v[28:29], v[8:11], off
	v_add3_u32 v7, v15, v7, s14
	v_lshrrev_b32_e32 v7, 16, v7
	v_bfe_u32 v8, v13, 16, 1
	v_add3_u32 v8, v13, v8, s14
	v_and_or_b32 v8, v8, s15, v7
	s_nop 4
	v_cvt_pk_bf16_f32 v9, v17, v19
	s_nop 4
	v_cvt_pk_bf16_f32 v10, v21, v23
	s_nop 0
	v_add_u32_e32 v12, 40, v6
	s_nop 1
	v_ashrrev_i32_e32 v13, 31, v12
	s_nop 1
	v_lshlrev_b64 v[12:13], 12, v[12:13]
	v_cvt_pk_bf16_f32 v11, v25, v27
	ds_read2_b32 v[14:15], v78 offset0:48 offset1:56
	v_lshl_add_u64 v[12:13], v[4:5], 0, v[12:13]
	global_store_dwordx4 v[12:13], v[8:11], off
	ds_read2_b32 v[12:13], v78 offset0:113 offset1:121
	ds_read2_b32 v[16:17], v78 offset0:178 offset1:186
	ds_read2_b32 v[18:19], v78 offset0:243 offset1:251
	s_waitcnt lgkmcnt(3)
	s_nop 1
	s_waitcnt lgkmcnt(2)
	s_nop 0
	ds_read2_b32 v[20:21], v30 offset0:52 offset1:60
	s_nop 1
	ds_read2_b32 v[22:23], v30 offset0:117 offset1:125
	v_cvt_pk_bf16_f32 v8, v14, v12
	s_waitcnt lgkmcnt(3)
	s_nop 1
	s_waitcnt lgkmcnt(2)
	s_nop 0
	ds_read2_b32 v[24:25], v30 offset0:182 offset1:190
	s_nop 1
	ds_read2_b32 v[26:27], v30 offset0:247 offset1:255
	v_cvt_pk_bf16_f32 v9, v16, v18
	s_waitcnt lgkmcnt(3)
	s_nop 1
	s_waitcnt lgkmcnt(2)
	s_nop 2
	v_cvt_pk_bf16_f32 v10, v20, v22
	s_waitcnt lgkmcnt(1)
	s_nop 0
	v_add_u32_e32 v28, 48, v6
	s_nop 0
	s_waitcnt lgkmcnt(0)
	s_nop 0
	v_ashrrev_i32_e32 v29, 31, v28
	s_nop 1
	v_lshlrev_b64 v[28:29], 12, v[28:29]
	v_cvt_pk_bf16_f32 v11, v24, v26
	v_lshl_add_u64 v[28:29], v[4:5], 0, v[28:29]
	v_bfe_u32 v7, v15, 16, 1
	global_store_dwordx4 v[28:29], v[8:11], off
	v_add3_u32 v7, v15, v7, s14
	v_lshrrev_b32_e32 v7, 16, v7
	v_bfe_u32 v8, v13, 16, 1
	v_add3_u32 v8, v13, v8, s14
	v_and_or_b32 v8, v8, s15, v7
	s_nop 4
	v_cvt_pk_bf16_f32 v9, v17, v19
	s_nop 4
	v_cvt_pk_bf16_f32 v10, v21, v23
	s_nop 4
	v_add_u32_e32 v6, 56, v6
	v_cvt_pk_bf16_f32 v11, v25, v27
	v_ashrrev_i32_e32 v7, 31, v6
	v_lshlrev_b64 v[6:7], 12, v[6:7]
	v_lshl_add_u64 v[4:5], v[4:5], 0, v[6:7]
	global_store_dwordx4 v[4:5], v[8:11], off
	s_waitcnt lgkmcnt(0)
	s_add_i32 s11, s11, s86
	s_add_i32 s12, s12, s13
	s_cmpk_lt_i32 s11, 0x200
	s_cbranch_scc0 .LBB0_1553

; #define LAS __attribute__((address_space(3)))
; #define LDS_WAIT() asm volatile("s_waitcnt lgkmcnt(0)" ::: "memory")
; __device__ __forceinline__ unsigned pk2(float lo, float hi) { return f2bf(lo) | (f2bf(hi) << 16); }
;     ...
;         for (int i = 0; i < 16; ++i) { LAS float* d = scr + (4 * i + kr) * 65 + nq; d[0] = v[i].x; d[1] = v[i].y; d[2] = v[i].z; d[3] = v[i].w; }
;         LDS_WAIT(); asm volatile("" ::: "memory");
;         const int c8 = lane & 7; int d0 = n0;
;         if (ffnmap) { const int bj = n0 >= FFH ? 1 : 0, chn = n0 - FFH * bj; d0 = 256 * (chn >> 7) + 128 * bj + (chn & 127); }
; #pragma unroll
;         for (int j = 0; j < 8; ++j) { const int n = (lane >> 3) + 8 * j; const LAS float* sp = scr + (8 * c8) * 65 + n;
;             v4u o; o.x = pk2(sp[0 * 65], sp[1 * 65]); o.y = pk2(sp[2 * 65], sp[3 * 65]); o.z = pk2(sp[4 * 65], sp[5 * 65]); o.w = pk2(sp[6 * 65], sp[7 * 65]);
;             *(v4u*)(WT + (size_t)(d0 + n) * K + k0 + 8 * c8) = o; }
;         LDS_WAIT(); asm volatile("" ::: "memory");
.LBB0_1555:
	s_or_b64 exec, exec, s[6:7]
	s_waitcnt vmcnt(0)
	ds_write2_b32 v79, v4, v5 offset1:1
	ds_write2_b32 v79, v6, v7 offset0:2 offset1:3
	v_add_u32_e32 v4, 0x410, v79
	ds_write2_b32 v4, v12, v13 offset1:1
	v_add_u32_e32 v4, 0x418, v79
	ds_write2_b32 v4, v14, v15 offset1:1
	v_add_u32_e32 v4, 0x820, v79
	ds_write2_b32 v4, v8, v9 offset1:1
	v_add_u32_e32 v4, 0x828, v79
	ds_write2_b32 v4, v10, v11 offset1:1
	v_add_u32_e32 v4, 0xc30, v79
	ds_write2_b32 v4, v20, v21 offset1:1
	v_add_u32_e32 v4, 0xc38, v79
	ds_write2_b32 v4, v22, v23 offset1:1
	v_add_u32_e32 v4, 0x1040, v79
	ds_write2_b32 v4, v16, v17 offset1:1
	v_add_u32_e32 v4, 0x1048, v79
	ds_write2_b32 v4, v18, v19 offset1:1
	v_add_u32_e32 v4, 0x1450, v79
	ds_write2_b32 v4, v28, v29 offset1:1
	v_add_u32_e32 v4, 0x1458, v79
	ds_write2_b32 v4, v30, v31 offset1:1
	v_add_u32_e32 v4, 0x1860, v79
	ds_write2_b32 v4, v24, v25 offset1:1
	v_add_u32_e32 v4, 0x1868, v79
	ds_write2_b32 v4, v26, v27 offset1:1
	v_add_u32_e32 v4, 0x1c70, v79
	ds_write2_b32 v4, v36, v37 offset1:1
	v_add_u32_e32 v4, 0x1c78, v79
	ds_write2_b32 v4, v38, v39 offset1:1
	v_add_u32_e32 v4, 0x2080, v79
	ds_write2_b32 v4, v32, v33 offset1:1
	v_add_u32_e32 v4, 0x2088, v79
	ds_write2_b32 v4, v34, v35 offset1:1
	v_add_u32_e32 v4, 0x2490, v79
	ds_write2_b32 v4, v44, v45 offset1:1
	v_add_u32_e32 v4, 0x2498, v79
	ds_write2_b32 v4, v46, v47 offset1:1
	v_add_u32_e32 v4, 0x28a0, v79
	ds_write2_b32 v4, v40, v41 offset1:1
	v_add_u32_e32 v4, 0x28a8, v79
	ds_write2_b32 v4, v42, v43 offset1:1
	v_add_u32_e32 v4, 0x2cb0, v79
	ds_write2_b32 v4, v52, v53 offset1:1
	v_add_u32_e32 v4, 0x2cb8, v79
	ds_write2_b32 v4, v54, v55 offset1:1
	v_add_u32_e32 v4, 0x30c0, v79
	ds_write2_b32 v4, v48, v49 offset1:1
	v_add_u32_e32 v4, 0x30c8, v79
	ds_write2_b32 v4, v50, v51 offset1:1
	v_add_u32_e32 v4, 0x34d0, v79
	ds_write2_b32 v4, v60, v61 offset1:1
	v_add_u32_e32 v4, 0x34d8, v79
	ds_write2_b32 v4, v62, v63 offset1:1
	v_add_u32_e32 v4, 0x38e0, v79
	ds_write2_b32 v4, v56, v57 offset1:1
	v_add_u32_e32 v4, 0x38e8, v79
	ds_write2_b32 v4, v58, v59 offset1:1
	v_add_u32_e32 v4, 0x3cf0, v79
	ds_write2_b32 v4, v64, v65 offset1:1
	v_add_u32_e32 v4, 0x3cf8, v79
	ds_write2_b32 v4, v66, v67 offset1:1
	s_waitcnt lgkmcnt(0)
	ds_read2_b32 v[12:13], v78 offset1:8
	ds_read2_b32 v[14:15], v78 offset0:65 offset1:73
	ds_read2_b32 v[16:17], v78 offset0:130 offset1:138
	ds_read2_b32 v[18:19], v78 offset0:195 offset1:203
	v_add_u32_e32 v30, 0x400, v78
	s_waitcnt lgkmcnt(3)
	s_nop 1
	s_waitcnt lgkmcnt(2)
	s_nop 0
	ds_read2_b32 v[20:21], v30 offset0:4 offset1:12
	s_nop 1
	ds_read2_b32 v[22:23], v30 offset0:69 offset1:77
	v_cvt_pk_bf16_f32 v8, v12, v14
	s_waitcnt lgkmcnt(3)
	s_nop 1
	s_waitcnt lgkmcnt(2)
	s_nop 0
	ds_read2_b32 v[24:25], v30 offset0:134 offset1:142
	s_nop 1
	ds_read2_b32 v[26:27], v30 offset0:199 offset1:207
	v_cvt_pk_bf16_f32 v9, v16, v18
	s_waitcnt lgkmcnt(3)
	s_nop 1
	s_waitcnt lgkmcnt(2)
	s_nop 2
	v_cvt_pk_bf16_f32 v10, v20, v22
	s_waitcnt lgkmcnt(1)
	s_nop 1
	s_waitcnt lgkmcnt(0)
	s_nop 2
	s_add_i32 s16, s16, s12
	v_cvt_pk_bf16_f32 v11, v24, v26
	v_add_u32_e32 v6, s16, v77
	s_ashr_i32 s3, s2, 31
	v_ashrrev_i32_e32 v7, 31, v6
	v_lshl_add_u64 v[4:5], s[2:3], 1, v[70:71]
	v_lshlrev_b64 v[28:29], 10, v[6:7]
	v_lshl_add_u64 v[28:29], v[4:5], 0, v[28:29]
	v_bfe_u32 v7, v13, 16, 1
	global_store_dwordx4 v[28:29], v[8:11], off
	v_add3_u32 v7, v13, v7, s14
	v_lshrrev_b32_e32 v7, 16, v7
	v_bfe_u32 v8, v15, 16, 1
	v_add3_u32 v8, v15, v8, s14
	v_and_or_b32 v8, v8, s15, v7
	s_nop 4
	v_cvt_pk_bf16_f32 v9, v17, v19
	s_nop 4
	v_cvt_pk_bf16_f32 v10, v21, v23
	s_nop 0
	v_add_u32_e32 v12, 8, v6
	s_nop 1
	v_ashrrev_i32_e32 v13, 31, v12
	s_nop 1
	v_lshlrev_b64 v[12:13], 10, v[12:13]
	v_cvt_pk_bf16_f32 v11, v25, v27
	ds_read2_b32 v[14:15], v78 offset0:16 offset1:24
	v_lshl_add_u64 v[12:13], v[4:5], 0, v[12:13]
	global_store_dwordx4 v[12:13], v[8:11], off
	ds_read2_b32 v[12:13], v78 offset0:81 offset1:89
	ds_read2_b32 v[16:17], v78 offset0:146 offset1:154
	ds_read2_b32 v[18:19], v78 offset0:211 offset1:219
	s_waitcnt lgkmcnt(3)
	s_nop 1
	s_waitcnt lgkmcnt(2)
	s_nop 0
	ds_read2_b32 v[20:21], v30 offset0:20 offset1:28
	s_nop 1
	ds_read2_b32 v[22:23], v30 offset0:85 offset1:93
	v_cvt_pk_bf16_f32 v8, v14, v12
	s_waitcnt lgkmcnt(3)
; #define LAS __attribute__((address_space(3)))
; #define LDS_WAIT() asm volatile("s_waitcnt lgkmcnt(0)" ::: "memory")
; __device__ __forceinline__ unsigned pk2(float lo, float hi) { return f2bf(lo) | (f2bf(hi) << 16); }
;     ...
; #pragma unroll
;         for (int j = 0; j < 8; ++j) { const int n = (lane >> 3) + 8 * j; const LAS float* sp = scr + (8 * c8) * 65 + n;
;             v4u o; o.x = pk2(sp[0 * 65], sp[1 * 65]); o.y = pk2(sp[2 * 65], sp[3 * 65]); o.z = pk2(sp[4 * 65], sp[5 * 65]); o.w = pk2(sp[6 * 65], sp[7 * 65]);
;             *(v4u*)(WT + (size_t)(d0 + n) * K + k0 + 8 * c8) = o; }
;         LDS_WAIT(); asm volatile("" ::: "memory");
	s_nop 1
	s_waitcnt lgkmcnt(2)
	s_nop 0
	ds_read2_b32 v[24:25], v30 offset0:150 offset1:158
	s_nop 1
	ds_read2_b32 v[26:27], v30 offset0:215 offset1:223
	v_cvt_pk_bf16_f32 v9, v16, v18
	s_waitcnt lgkmcnt(3)
	s_nop 1
	s_waitcnt lgkmcnt(2)
	s_nop 2
	v_cvt_pk_bf16_f32 v10, v20, v22
	s_waitcnt lgkmcnt(1)
	s_nop 0
	v_add_u32_e32 v28, 16, v6
	s_nop 0
	s_waitcnt lgkmcnt(0)
	s_nop 0
	v_ashrrev_i32_e32 v29, 31, v28
	s_nop 1
	v_lshlrev_b64 v[28:29], 10, v[28:29]
	v_cvt_pk_bf16_f32 v11, v24, v26
	v_lshl_add_u64 v[28:29], v[4:5], 0, v[28:29]
	v_bfe_u32 v7, v15, 16, 1
	global_store_dwordx4 v[28:29], v[8:11], off
	v_add3_u32 v7, v15, v7, s14
	v_lshrrev_b32_e32 v7, 16, v7
	v_bfe_u32 v8, v13, 16, 1
	v_add3_u32 v8, v13, v8, s14
	v_and_or_b32 v8, v8, s15, v7
	s_nop 4
	v_cvt_pk_bf16_f32 v9, v17, v19
	s_nop 4
	v_cvt_pk_bf16_f32 v10, v21, v23
	s_nop 0
	v_add_u32_e32 v12, 24, v6
	s_nop 1
	v_ashrrev_i32_e32 v13, 31, v12
	s_nop 1
	v_lshlrev_b64 v[12:13], 10, v[12:13]
	v_cvt_pk_bf16_f32 v11, v25, v27
	ds_read2_b32 v[14:15], v78 offset0:32 offset1:40
	v_lshl_add_u64 v[12:13], v[4:5], 0, v[12:13]
	global_store_dwordx4 v[12:13], v[8:11], off
	ds_read2_b32 v[12:13], v78 offset0:97 offset1:105
	ds_read2_b32 v[16:17], v78 offset0:162 offset1:170
	ds_read2_b32 v[18:19], v78 offset0:227 offset1:235
	s_waitcnt lgkmcnt(3)
	s_nop 1
	s_waitcnt lgkmcnt(2)
	s_nop 0
	ds_read2_b32 v[20:21], v30 offset0:36 offset1:44
	s_nop 1
	ds_read2_b32 v[22:23], v30 offset0:101 offset1:109
	v_cvt_pk_bf16_f32 v8, v14, v12
	s_waitcnt lgkmcnt(3)
	s_nop 1
	s_waitcnt lgkmcnt(2)
	s_nop 0
	ds_read2_b32 v[24:25], v30 offset0:166 offset1:174
	s_nop 1
	ds_read2_b32 v[26:27], v30 offset0:231 offset1:239
	v_cvt_pk_bf16_f32 v9, v16, v18
	s_waitcnt lgkmcnt(3)
	s_nop 1
	s_waitcnt lgkmcnt(2)
	s_nop 2
	v_cvt_pk_bf16_f32 v10, v20, v22
	s_waitcnt lgkmcnt(1)
	s_nop 0
	v_add_u32_e32 v28, 32, v6
	s_nop 0
	s_waitcnt lgkmcnt(0)
	s_nop 0
	v_ashrrev_i32_e32 v29, 31, v28
	s_nop 1
	v_lshlrev_b64 v[28:29], 10, v[28:29]
	v_cvt_pk_bf16_f32 v11, v24, v26
	v_lshl_add_u64 v[28:29], v[4:5], 0, v[28:29]
	v_bfe_u32 v7, v15, 16, 1
	global_store_dwordx4 v[28:29], v[8:11], off
	v_add3_u32 v7, v15, v7, s14
	v_lshrrev_b32_e32 v7, 16, v7
	v_bfe_u32 v8, v13, 16, 1
	v_add3_u32 v8, v13, v8, s14
	v_and_or_b32 v8, v8, s15, v7
	s_nop 4
	v_cvt_pk_bf16_f32 v9, v17, v19
	s_nop 4
	v_cvt_pk_bf16_f32 v10, v21, v23
	s_nop 0
	v_add_u32_e32 v12, 40, v6
	s_nop 1
	v_ashrrev_i32_e32 v13, 31, v12
	s_nop 1
	v_lshlrev_b64 v[12:13], 10, v[12:13]
	v_cvt_pk_bf16_f32 v11, v25, v27
	ds_read2_b32 v[14:15], v78 offset0:48 offset1:56
	v_lshl_add_u64 v[12:13], v[4:5], 0, v[12:13]
	global_store_dwordx4 v[12:13], v[8:11], off
	ds_read2_b32 v[12:13], v78 offset0:113 offset1:121
	ds_read2_b32 v[16:17], v78 offset0:178 offset1:186
	ds_read2_b32 v[18:19], v78 offset0:243 offset1:251
	s_waitcnt lgkmcnt(3)
	s_nop 1
	s_waitcnt lgkmcnt(2)
	s_nop 0
	ds_read2_b32 v[20:21], v30 offset0:52 offset1:60
	s_nop 1
	ds_read2_b32 v[22:23], v30 offset0:117 offset1:125
	v_cvt_pk_bf16_f32 v8, v14, v12
	s_waitcnt lgkmcnt(3)
	s_nop 1
	s_waitcnt lgkmcnt(2)
	s_nop 0
	ds_read2_b32 v[24:25], v30 offset0:182 offset1:190
	s_nop 1
	ds_read2_b32 v[26:27], v30 offset0:247 offset1:255
	v_cvt_pk_bf16_f32 v9, v16, v18
	s_waitcnt lgkmcnt(3)
	s_nop 1
	s_waitcnt lgkmcnt(2)
	s_nop 2
	v_cvt_pk_bf16_f32 v10, v20, v22
	s_waitcnt lgkmcnt(1)
	s_nop 0
	v_add_u32_e32 v28, 48, v6
	s_nop 0
	s_waitcnt lgkmcnt(0)
	s_nop 0
	v_ashrrev_i32_e32 v29, 31, v28
	s_nop 1
	v_lshlrev_b64 v[28:29], 10, v[28:29]
	v_cvt_pk_bf16_f32 v11, v24, v26
	v_lshl_add_u64 v[28:29], v[4:5], 0, v[28:29]
	v_bfe_u32 v7, v15, 16, 1
	global_store_dwordx4 v[28:29], v[8:11], off
	v_add3_u32 v7, v15, v7, s14
	v_lshrrev_b32_e32 v7, 16, v7
	v_bfe_u32 v8, v13, 16, 1
	v_add3_u32 v8, v13, v8, s14
	v_and_or_b32 v8, v8, s15, v7
	s_nop 4
	v_cvt_pk_bf16_f32 v9, v17, v19
	s_nop 4
	v_cvt_pk_bf16_f32 v10, v21, v23
	s_nop 4
	v_add_u32_e32 v6, 56, v6
	v_cvt_pk_bf16_f32 v11, v25, v27
	v_ashrrev_i32_e32 v7, 31, v6
	v_lshlrev_b64 v[6:7], 10, v[6:7]
	v_lshl_add_u64 v[4:5], v[4:5], 0, v[6:7]
	global_store_dwordx4 v[4:5], v[8:11], off
	s_waitcnt lgkmcnt(0)
	s_add_i32 s11, s11, s86
	s_add_i32 s12, s12, s13
	s_cmpk_lt_i32 s11, 0x100
	s_cbranch_scc0 .LBB0_1588

; #define LAS __attribute__((address_space(3)))
; #define LDS_WAIT() asm volatile("s_waitcnt lgkmcnt(0)" ::: "memory")
;     ...
;         const int kb = it / nblk, nb = it % nblk, k0 = 64 * kb, n0 = 64 * nb, nq = (lane & 15) * 4, kr = lane >> 4; const bool ok = (n0 + nq) < N;
;         f32x4 v[16];
; #pragma unroll
;         for (int i = 0; i < 16; ++i) v[i] = ok ? __builtin_nontemporal_load((const f32x4*)(W + (size_t)(k0 + 4 * i + kr) * N + n0 + nq)) : (f32x4){0.f, 0.f, 0.f, 0.f};
;         if (gain) {
; #pragma unroll
;             for (int i = 0; i < 16; ++i) v[i] *= gain[k0 + 4 * i + kr]; }
; #pragma unroll
;         for (int i = 0; i < 16; ++i) { LAS float* d = scr + (4 * i + kr) * 65 + nq; d[0] = v[i].x; d[1] = v[i].y; d[2] = v[i].z; d[3] = v[i].w; }
;         LDS_WAIT(); asm volatile("" ::: "memory");
;         const int c8 = lane & 7; int d0 = n0;
;         if (ffnmap) { const int bj = n0 >= FFH ? 1 : 0, chn = n0 - FFH * bj; d0 = 256 * (chn >> 7) + 128 * bj + (chn & 127); }
; #pragma unroll
;         for (int j = 0; j < 8; ++j) { const int n = (lane >> 3) + 8 * j; const LAS float* sp = scr + (8 * c8) * 65 + n;
.LBB0_1649:
	s_or_b64 exec, exec, s[14:15]
	v_ashrrev_i32_e32 v73, 31, v72
	v_lshl_add_u64 v[114:115], v[72:73], 2, s[2:3]
	global_load_dword v72, v[114:115], off
	s_mulk_i32 s28, 0xff50
	s_add_i32 s13, s27, s28
	s_cmpk_gt_i32 s13, 0x57
	s_cselect_b32 s13, 0xffffea00, 0
	s_cselect_b32 s14, 0x80, 0
	s_add_i32 s13, s13, s22
	s_add_i32 s13, s13, s11
	s_lshl_b32 s11, s13, 1
	s_and_b32 s12, s12, 64
	s_and_b32 s11, s11, 0xffffff00
	s_or_b32 s12, s12, s14
	s_or_b32 s12, s12, s11
	s_ashr_i32 s11, s10, 31
	s_add_i32 s27, s27, s21
	s_add_i32 s22, s22, s23
	s_cmpk_lt_i32 s27, 0x1600
	s_waitcnt vmcnt(0)
	v_pk_mul_f32 v[100:101], v[4:5], v[72:73] op_sel_hi:[1,0]
	global_load_dword v4, v[114:115], off offset:16
	v_pk_mul_f32 v[98:99], v[6:7], v[72:73] op_sel_hi:[1,0]
	global_load_dword v6, v[114:115], off offset:128
	s_waitcnt vmcnt(1)
	v_pk_mul_f32 v[90:91], v[14:15], v[4:5] op_sel_hi:[1,0]
	v_pk_mul_f32 v[96:97], v[12:13], v[4:5] op_sel_hi:[1,0]
	global_load_dword v4, v[114:115], off offset:32
	global_load_dword v14, v[114:115], off offset:160
	s_waitcnt vmcnt(1)
	v_pk_mul_f32 v[86:87], v[10:11], v[4:5] op_sel_hi:[1,0]
	v_pk_mul_f32 v[92:93], v[8:9], v[4:5] op_sel_hi:[1,0]
	global_load_dword v4, v[114:115], off offset:48
	global_load_dword v10, v[114:115], off offset:144
	s_waitcnt vmcnt(2)
	v_pk_mul_f32 v[12:13], v[46:47], v[14:15] op_sel_hi:[1,0]
	v_pk_mul_f32 v[14:15], v[44:45], v[14:15] op_sel_hi:[1,0]
	s_waitcnt vmcnt(1)
	v_pk_mul_f32 v[82:83], v[22:23], v[4:5] op_sel_hi:[1,0]
	v_pk_mul_f32 v[88:89], v[20:21], v[4:5] op_sel_hi:[1,0]
	global_load_dword v4, v[114:115], off offset:64
	global_load_dword v22, v[114:115], off offset:192
	s_waitcnt vmcnt(1)
	v_pk_mul_f32 v[78:79], v[18:19], v[4:5] op_sel_hi:[1,0]
	v_pk_mul_f32 v[84:85], v[16:17], v[4:5] op_sel_hi:[1,0]
	global_load_dword v4, v[114:115], off offset:80
	global_load_dword v18, v[114:115], off offset:176
	s_waitcnt vmcnt(2)
	v_pk_mul_f32 v[20:21], v[54:55], v[22:23] op_sel_hi:[1,0]
	v_pk_mul_f32 v[22:23], v[52:53], v[22:23] op_sel_hi:[1,0]
	s_waitcnt vmcnt(1)
	v_pk_mul_f32 v[74:75], v[30:31], v[4:5] op_sel_hi:[1,0]
	v_pk_mul_f32 v[80:81], v[28:29], v[4:5] op_sel_hi:[1,0]
	global_load_dword v4, v[114:115], off offset:96
	global_load_dword v30, v[114:115], off offset:224
	s_waitcnt vmcnt(2)
	v_pk_mul_f32 v[16:17], v[58:59], v[18:19] op_sel_hi:[1,0]
	v_pk_mul_f32 v[18:19], v[56:57], v[18:19] op_sel_hi:[1,0]
	s_waitcnt vmcnt(1)
	v_pk_mul_f32 v[72:73], v[26:27], v[4:5] op_sel_hi:[1,0]
	v_pk_mul_f32 v[76:77], v[24:25], v[4:5] op_sel_hi:[1,0]
	global_load_dword v4, v[114:115], off offset:112
	global_load_dword v26, v[114:115], off offset:208
	s_waitcnt vmcnt(2)
	v_pk_mul_f32 v[28:29], v[62:63], v[30:31] op_sel_hi:[1,0]
	v_pk_mul_f32 v[30:31], v[60:61], v[30:31] op_sel_hi:[1,0]
	s_waitcnt vmcnt(1)
	v_pk_mul_f32 v[38:39], v[38:39], v[4:5] op_sel_hi:[1,0]
	v_pk_mul_f32 v[36:37], v[36:37], v[4:5] op_sel_hi:[1,0]
	v_pk_mul_f32 v[4:5], v[34:35], v[6:7] op_sel_hi:[1,0]
	v_pk_mul_f32 v[6:7], v[32:33], v[6:7] op_sel_hi:[1,0]
	v_lshl_add_u64 v[32:33], v[94:95], 2, s[2:3]
	global_load_dword v34, v[32:33], off
	ds_write2_b32 v112, v100, v101 offset1:1
	ds_write2_b32 v112, v98, v99 offset0:2 offset1:3
	v_pk_mul_f32 v[8:9], v[50:51], v[10:11] op_sel_hi:[1,0]
	v_pk_mul_f32 v[10:11], v[48:49], v[10:11] op_sel_hi:[1,0]
	s_waitcnt vmcnt(1)
	v_pk_mul_f32 v[24:25], v[66:67], v[26:27] op_sel_hi:[1,0]
	v_pk_mul_f32 v[26:27], v[64:65], v[26:27] op_sel_hi:[1,0]
	s_waitcnt vmcnt(0)
	v_pk_mul_f32 v[32:33], v[42:43], v[34:35] op_sel_hi:[1,0]
	v_pk_mul_f32 v[34:35], v[40:41], v[34:35] op_sel_hi:[1,0]
	v_add_u32_e32 v40, 0x410, v112
	ds_write2_b32 v40, v96, v97 offset1:1
	v_add_u32_e32 v40, 0x418, v112
	ds_write2_b32 v40, v90, v91 offset1:1
	v_add_u32_e32 v40, 0x820, v112
	ds_write2_b32 v40, v92, v93 offset1:1
	v_add_u32_e32 v40, 0x828, v112
	ds_write2_b32 v40, v86, v87 offset1:1
	v_add_u32_e32 v40, 0xc30, v112
	ds_write2_b32 v40, v88, v89 offset1:1
	v_add_u32_e32 v40, 0xc38, v112
	ds_write2_b32 v40, v82, v83 offset1:1
	v_add_u32_e32 v40, 0x1040, v112
	ds_write2_b32 v40, v84, v85 offset1:1
	v_add_u32_e32 v40, 0x1048, v112
	ds_write2_b32 v40, v78, v79 offset1:1
	v_add_u32_e32 v40, 0x1450, v112
	ds_write2_b32 v40, v80, v81 offset1:1
	v_add_u32_e32 v40, 0x1458, v112
	ds_write2_b32 v40, v74, v75 offset1:1
	v_add_u32_e32 v40, 0x1860, v112
	ds_write2_b32 v40, v76, v77 offset1:1
	v_add_u32_e32 v40, 0x1868, v112
	ds_write2_b32 v40, v72, v73 offset1:1
	v_add_u32_e32 v40, 0x1c70, v112
	ds_write2_b32 v40, v36, v37 offset1:1
	v_add_u32_e32 v36, 0x1c78, v112
	ds_write2_b32 v36, v38, v39 offset1:1
	v_add_u32_e32 v36, 0x2080, v112
	ds_write2_b32 v36, v6, v7 offset1:1
	v_add_u32_e32 v6, 0x2088, v112
	ds_write2_b32 v6, v4, v5 offset1:1
	v_add_u32_e32 v4, 0x2490, v112
	ds_write2_b32 v4, v10, v11 offset1:1
	v_add_u32_e32 v4, 0x2498, v112
	ds_write2_b32 v4, v8, v9 offset1:1
	v_add_u32_e32 v4, 0x28a0, v112
	ds_write2_b32 v4, v14, v15 offset1:1
	v_add_u32_e32 v4, 0x28a8, v112
	ds_write2_b32 v4, v12, v13 offset1:1
	v_add_u32_e32 v4, 0x2cb0, v112
	ds_write2_b32 v4, v18, v19 offset1:1
	v_add_u32_e32 v4, 0x2cb8, v112
	ds_write2_b32 v4, v16, v17 offset1:1
	v_add_u32_e32 v4, 0x30c0, v112
	ds_write2_b32 v4, v22, v23 offset1:1
	v_add_u32_e32 v4, 0x30c8, v112
	ds_write2_b32 v4, v20, v21 offset1:1
	v_add_u32_e32 v4, 0x34d0, v112
	ds_write2_b32 v4, v26, v27 offset1:1
	v_add_u32_e32 v4, 0x34d8, v112
	ds_write2_b32 v4, v24, v25 offset1:1
	v_add_u32_e32 v4, 0x38e0, v112
	ds_write2_b32 v4, v30, v31 offset1:1
	v_add_u32_e32 v4, 0x38e8, v112
	ds_write2_b32 v4, v28, v29 offset1:1
	v_add_u32_e32 v4, 0x3cf0, v112
	ds_write2_b32 v4, v34, v35 offset1:1
	v_add_u32_e32 v4, 0x3cf8, v112
	ds_write2_b32 v4, v32, v33 offset1:1
	s_waitcnt lgkmcnt(0)
; #define LAS __attribute__((address_space(3)))
; #define LDS_WAIT() asm volatile("s_waitcnt lgkmcnt(0)" ::: "memory")
; __device__ __forceinline__ unsigned pk2(float lo, float hi) { return f2bf(lo) | (f2bf(hi) << 16); }
;     ...
;         const int c8 = lane & 7; int d0 = n0;
;         if (ffnmap) { const int bj = n0 >= FFH ? 1 : 0, chn = n0 - FFH * bj; d0 = 256 * (chn >> 7) + 128 * bj + (chn & 127); }
; #pragma unroll
;         for (int j = 0; j < 8; ++j) { const int n = (lane >> 3) + 8 * j; const LAS float* sp = scr + (8 * c8) * 65 + n;
;             v4u o; o.x = pk2(sp[0 * 65], sp[1 * 65]); o.y = pk2(sp[2 * 65], sp[3 * 65]); o.z = pk2(sp[4 * 65], sp[5 * 65]); o.w = pk2(sp[6 * 65], sp[7 * 65]);
;             *(v4u*)(WT + (size_t)(d0 + n) * K + k0 + 8 * c8) = o; }
;         LDS_WAIT(); asm volatile("" ::: "memory");
	ds_read2_b32 v[6:7], v104 offset0:65 offset1:73
	ds_read2_b32 v[12:13], v104 offset1:8
	ds_read2_b32 v[14:15], v104 offset0:130 offset1:138
	ds_read2_b32 v[16:17], v104 offset0:195 offset1:203
	v_or_b32_e32 v26, s12, v103
	v_ashrrev_i32_e32 v27, 31, v26
	s_waitcnt lgkmcnt(3)
	s_nop 0
	s_waitcnt lgkmcnt(2)
	s_nop 3
	v_cvt_pk_bf16_f32 v8, v12, v6
	s_waitcnt lgkmcnt(1)
	s_nop 1
	s_waitcnt lgkmcnt(0)
	s_nop 2
	v_cvt_pk_bf16_f32 v9, v14, v16
	v_add_u32_e32 v6, 0x400, v104
	ds_read2_b32 v[18:19], v6 offset0:4 offset1:12
	ds_read2_b32 v[20:21], v6 offset0:69 offset1:77
	ds_read2_b32 v[22:23], v6 offset0:134 offset1:142
	ds_read2_b32 v[24:25], v6 offset0:199 offset1:207
	v_lshl_add_u64 v[4:5], s[10:11], 1, v[70:71]
	v_lshlrev_b64 v[26:27], 12, v[26:27]
	s_waitcnt lgkmcnt(3)
	s_nop 1
	s_waitcnt lgkmcnt(2)
	s_nop 2
	v_cvt_pk_bf16_f32 v10, v18, v20
	s_waitcnt lgkmcnt(1)
	s_nop 1
	s_waitcnt lgkmcnt(0)
	s_nop 2
	v_cvt_pk_bf16_f32 v11, v22, v24
	v_lshl_add_u64 v[26:27], v[4:5], 0, v[26:27]
	global_store_dwordx4 v[26:27], v[8:11], off
	v_or_b32_e32 v12, s12, v105
	v_or_b32_e32 v28, s12, v106
	s_nop 4
	v_cvt_pk_bf16_f32 v8, v13, v7
	s_nop 4
	v_cvt_pk_bf16_f32 v9, v15, v17
	s_nop 4
	v_cvt_pk_bf16_f32 v10, v19, v21
	s_nop 2
	v_ashrrev_i32_e32 v13, 31, v12
	s_nop 1
	v_lshlrev_b64 v[12:13], 12, v[12:13]
	v_cvt_pk_bf16_f32 v11, v23, v25
	v_lshl_add_u64 v[12:13], v[4:5], 0, v[12:13]
	global_store_dwordx4 v[12:13], v[8:11], off
	ds_read2_b32 v[12:13], v104 offset0:81 offset1:89
	ds_read2_b32 v[14:15], v104 offset0:16 offset1:24
	ds_read2_b32 v[16:17], v104 offset0:146 offset1:154
	ds_read2_b32 v[18:19], v104 offset0:211 offset1:219
	ds_read2_b32 v[20:21], v6 offset0:20 offset1:28
	ds_read2_b32 v[22:23], v6 offset0:85 offset1:93
	ds_read2_b32 v[24:25], v6 offset0:150 offset1:158
	ds_read2_b32 v[26:27], v6 offset0:215 offset1:223
	s_waitcnt lgkmcnt(7)
	s_nop 0
	s_waitcnt lgkmcnt(6)
	s_nop 3
	v_cvt_pk_bf16_f32 v8, v14, v12
	s_waitcnt lgkmcnt(5)
	s_nop 1
	s_waitcnt lgkmcnt(4)
	s_nop 2
	v_cvt_pk_bf16_f32 v9, v16, v18
	s_waitcnt lgkmcnt(3)
	s_nop 1
	s_waitcnt lgkmcnt(2)
	s_nop 2
	v_cvt_pk_bf16_f32 v10, v20, v22
	s_waitcnt lgkmcnt(1)
	s_nop 1
	s_waitcnt lgkmcnt(0)
	s_nop 0
	v_ashrrev_i32_e32 v29, 31, v28
	s_nop 1
	v_lshlrev_b64 v[28:29], 12, v[28:29]
	v_cvt_pk_bf16_f32 v11, v24, v26
	v_lshl_add_u64 v[28:29], v[4:5], 0, v[28:29]
	v_bfe_u32 v7, v15, 16, 1
	global_store_dwordx4 v[28:29], v[8:11], off
	v_add3_u32 v7, v15, v7, s25
	v_lshrrev_b32_e32 v7, 16, v7
	v_bfe_u32 v8, v13, 16, 1
	v_add3_u32 v8, v13, v8, s25
	v_and_or_b32 v8, v8, s26, v7
	s_nop 4
	v_cvt_pk_bf16_f32 v9, v17, v19
	s_nop 4
	v_cvt_pk_bf16_f32 v10, v21, v23
	s_nop 0
	v_or_b32_e32 v12, s12, v107
	s_nop 1
	v_ashrrev_i32_e32 v13, 31, v12
	s_nop 1
	v_lshlrev_b64 v[12:13], 12, v[12:13]
	v_cvt_pk_bf16_f32 v11, v25, v27
	v_lshl_add_u64 v[12:13], v[4:5], 0, v[12:13]
	global_store_dwordx4 v[12:13], v[8:11], off
	ds_read2_b32 v[12:13], v104 offset0:97 offset1:105
	ds_read2_b32 v[14:15], v104 offset0:32 offset1:40
	ds_read2_b32 v[16:17], v104 offset0:162 offset1:170
	ds_read2_b32 v[18:19], v104 offset0:227 offset1:235
	ds_read2_b32 v[20:21], v6 offset0:36 offset1:44
	ds_read2_b32 v[22:23], v6 offset0:101 offset1:109
	ds_read2_b32 v[24:25], v6 offset0:166 offset1:174
	ds_read2_b32 v[26:27], v6 offset0:231 offset1:239
	s_waitcnt lgkmcnt(7)
	s_nop 0
	s_waitcnt lgkmcnt(6)
	s_nop 3
	v_cvt_pk_bf16_f32 v8, v14, v12
	s_waitcnt lgkmcnt(5)
	s_nop 1
	s_waitcnt lgkmcnt(4)
	s_nop 2
	v_cvt_pk_bf16_f32 v9, v16, v18
	s_waitcnt lgkmcnt(3)
	s_nop 1
	s_waitcnt lgkmcnt(2)
	s_nop 2
	v_cvt_pk_bf16_f32 v10, v20, v22
	s_waitcnt lgkmcnt(1)
	s_nop 0
	v_or_b32_e32 v28, s12, v108
	s_nop 0
	s_waitcnt lgkmcnt(0)
	s_nop 0
	v_ashrrev_i32_e32 v29, 31, v28
	s_nop 1
	v_lshlrev_b64 v[28:29], 12, v[28:29]
	v_cvt_pk_bf16_f32 v11, v24, v26
	v_lshl_add_u64 v[28:29], v[4:5], 0, v[28:29]
	v_bfe_u32 v7, v15, 16, 1
	global_store_dwordx4 v[28:29], v[8:11], off
	v_add3_u32 v7, v15, v7, s25
	v_lshrrev_b32_e32 v7, 16, v7
	v_bfe_u32 v8, v13, 16, 1
	v_add3_u32 v8, v13, v8, s25
	v_and_or_b32 v8, v8, s26, v7
	s_nop 4
	v_cvt_pk_bf16_f32 v9, v17, v19
	s_nop 4
	v_cvt_pk_bf16_f32 v10, v21, v23
	s_nop 0
	v_or_b32_e32 v12, s12, v109
	s_nop 1
	v_ashrrev_i32_e32 v13, 31, v12
	s_nop 1
	v_lshlrev_b64 v[12:13], 12, v[12:13]
	v_cvt_pk_bf16_f32 v11, v25, v27
	v_lshl_add_u64 v[12:13], v[4:5], 0, v[12:13]
	global_store_dwordx4 v[12:13], v[8:11], off
	ds_read2_b32 v[12:13], v104 offset0:48 offset1:56
	ds_read2_b32 v[14:15], v104 offset0:113 offset1:121
	ds_read2_b32 v[16:17], v104 offset0:178 offset1:186
	ds_read2_b32 v[18:19], v104 offset0:243 offset1:251
	ds_read2_b32 v[20:21], v6 offset0:52 offset1:60
	ds_read2_b32 v[22:23], v6 offset0:117 offset1:125
	ds_read2_b32 v[24:25], v6 offset0:182 offset1:190
	ds_read2_b32 v[26:27], v6 offset0:247 offset1:255
	s_waitcnt lgkmcnt(7)
	s_nop 1
	s_waitcnt lgkmcnt(6)
	s_nop 2
	v_cvt_pk_bf16_f32 v8, v12, v14
	s_waitcnt lgkmcnt(5)
	s_nop 1
	s_waitcnt lgkmcnt(4)
	s_nop 2
	v_cvt_pk_bf16_f32 v9, v16, v18
	s_waitcnt lgkmcnt(3)
	s_nop 1
	s_waitcnt lgkmcnt(2)
	s_nop 2
	s_waitcnt lgkmcnt(1)
	s_nop 0
	v_cvt_pk_bf16_f32 v10, v20, v22
	s_nop 0
	s_waitcnt lgkmcnt(0)
	s_nop 2
	v_cvt_pk_bf16_f32 v11, v24, v26
	v_or_b32_e32 v6, s12, v110
	v_ashrrev_i32_e32 v7, 31, v6
	v_lshlrev_b64 v[6:7], 12, v[6:7]
	v_lshl_add_u64 v[6:7], v[4:5], 0, v[6:7]
	global_store_dwordx4 v[6:7], v[8:11], off
	s_nop 4
	v_cvt_pk_bf16_f32 v6, v13, v15
	s_nop 4
	v_cvt_pk_bf16_f32 v7, v17, v19
	s_nop 4
	v_cvt_pk_bf16_f32 v8, v21, v23
	s_nop 4
	v_cvt_pk_bf16_f32 v9, v25, v27
	v_or_b32_e32 v10, s12, v111
	v_ashrrev_i32_e32 v11, 31, v10
	v_lshlrev_b64 v[10:11], 12, v[10:11]
	v_lshl_add_u64 v[4:5], v[4:5], 0, v[10:11]
	global_store_dwordx4 v[4:5], v[6:9], off
	s_waitcnt lgkmcnt(0)
	s_cbranch_scc0 .LBB0_1682

; #define LAS __attribute__((address_space(3)))
; #define LDS_WAIT() asm volatile("s_waitcnt lgkmcnt(0)" ::: "memory")
; __device__ __forceinline__ unsigned pk2(float lo, float hi) { return f2bf(lo) | (f2bf(hi) << 16); }
;     ...
;         for (int i = 0; i < 16; ++i) { LAS float* d = scr + (4 * i + kr) * 65 + nq; d[0] = v[i].x; d[1] = v[i].y; d[2] = v[i].z; d[3] = v[i].w; }
;         LDS_WAIT(); asm volatile("" ::: "memory");
;         const int c8 = lane & 7; int d0 = n0;
;         if (ffnmap) { const int bj = n0 >= FFH ? 1 : 0, chn = n0 - FFH * bj; d0 = 256 * (chn >> 7) + 128 * bj + (chn & 127); }
; #pragma unroll
;         for (int j = 0; j < 8; ++j) { const int n = (lane >> 3) + 8 * j; const LAS float* sp = scr + (8 * c8) * 65 + n;
;             v4u o; o.x = pk2(sp[0 * 65], sp[1 * 65]); o.y = pk2(sp[2 * 65], sp[3 * 65]); o.z = pk2(sp[4 * 65], sp[5 * 65]); o.w = pk2(sp[6 * 65], sp[7 * 65]);
;             *(v4u*)(WT + (size_t)(d0 + n) * K + k0 + 8 * c8) = o; }
;         LDS_WAIT(); asm volatile("" ::: "memory");
.LBB0_1684:
	s_or_b64 exec, exec, s[10:11]
	s_waitcnt vmcnt(0)
	ds_write2_b32 v79, v4, v5 offset1:1
	ds_write2_b32 v79, v6, v7 offset0:2 offset1:3
	v_add_u32_e32 v4, 0x410, v79
	ds_write2_b32 v4, v12, v13 offset1:1
	v_add_u32_e32 v4, 0x418, v79
	ds_write2_b32 v4, v14, v15 offset1:1
	v_add_u32_e32 v4, 0x820, v79
	ds_write2_b32 v4, v8, v9 offset1:1
	v_add_u32_e32 v4, 0x828, v79
	ds_write2_b32 v4, v10, v11 offset1:1
	v_add_u32_e32 v4, 0xc30, v79
	ds_write2_b32 v4, v20, v21 offset1:1
	v_add_u32_e32 v4, 0xc38, v79
	ds_write2_b32 v4, v22, v23 offset1:1
	v_add_u32_e32 v4, 0x1040, v79
	ds_write2_b32 v4, v16, v17 offset1:1
	v_add_u32_e32 v4, 0x1048, v79
	ds_write2_b32 v4, v18, v19 offset1:1
	v_add_u32_e32 v4, 0x1450, v79
	ds_write2_b32 v4, v28, v29 offset1:1
	v_add_u32_e32 v4, 0x1458, v79
	ds_write2_b32 v4, v30, v31 offset1:1
	v_add_u32_e32 v4, 0x1860, v79
	ds_write2_b32 v4, v24, v25 offset1:1
	v_add_u32_e32 v4, 0x1868, v79
	ds_write2_b32 v4, v26, v27 offset1:1
	v_add_u32_e32 v4, 0x1c70, v79
	ds_write2_b32 v4, v36, v37 offset1:1
	v_add_u32_e32 v4, 0x1c78, v79
	ds_write2_b32 v4, v38, v39 offset1:1
	v_add_u32_e32 v4, 0x2080, v79
	ds_write2_b32 v4, v32, v33 offset1:1
	v_add_u32_e32 v4, 0x2088, v79
	ds_write2_b32 v4, v34, v35 offset1:1
	v_add_u32_e32 v4, 0x2490, v79
	ds_write2_b32 v4, v44, v45 offset1:1
	v_add_u32_e32 v4, 0x2498, v79
	ds_write2_b32 v4, v46, v47 offset1:1
	v_add_u32_e32 v4, 0x28a0, v79
	ds_write2_b32 v4, v40, v41 offset1:1
	v_add_u32_e32 v4, 0x28a8, v79
	ds_write2_b32 v4, v42, v43 offset1:1
	v_add_u32_e32 v4, 0x2cb0, v79
	ds_write2_b32 v4, v52, v53 offset1:1
	v_add_u32_e32 v4, 0x2cb8, v79
	ds_write2_b32 v4, v54, v55 offset1:1
	v_add_u32_e32 v4, 0x30c0, v79
	ds_write2_b32 v4, v48, v49 offset1:1
	v_add_u32_e32 v4, 0x30c8, v79
	ds_write2_b32 v4, v50, v51 offset1:1
	v_add_u32_e32 v4, 0x34d0, v79
	ds_write2_b32 v4, v60, v61 offset1:1
	v_add_u32_e32 v4, 0x34d8, v79
	ds_write2_b32 v4, v62, v63 offset1:1
	v_add_u32_e32 v4, 0x38e0, v79
	ds_write2_b32 v4, v56, v57 offset1:1
	v_add_u32_e32 v4, 0x38e8, v79
	ds_write2_b32 v4, v58, v59 offset1:1
	v_add_u32_e32 v4, 0x3cf0, v79
	ds_write2_b32 v4, v64, v65 offset1:1
	v_add_u32_e32 v4, 0x3cf8, v79
	ds_write2_b32 v4, v66, v67 offset1:1
	s_waitcnt lgkmcnt(0)
	ds_read2_b32 v[12:13], v77 offset1:8
	ds_read2_b32 v[14:15], v77 offset0:65 offset1:73
	ds_read2_b32 v[16:17], v77 offset0:130 offset1:138
	ds_read2_b32 v[18:19], v77 offset0:195 offset1:203
	v_add_u32_e32 v30, 0x400, v77
	s_waitcnt lgkmcnt(3)
	s_nop 1
	s_waitcnt lgkmcnt(2)
	s_nop 0
	ds_read2_b32 v[20:21], v30 offset0:4 offset1:12
	s_nop 1
	ds_read2_b32 v[22:23], v30 offset0:69 offset1:77
	v_cvt_pk_bf16_f32 v8, v12, v14
	s_waitcnt lgkmcnt(3)
	s_nop 1
	s_waitcnt lgkmcnt(2)
	s_nop 0
	ds_read2_b32 v[24:25], v30 offset0:134 offset1:142
	s_nop 1
	ds_read2_b32 v[26:27], v30 offset0:199 offset1:207
	v_cvt_pk_bf16_f32 v9, v16, v18
	s_waitcnt lgkmcnt(3)
	s_nop 1
	s_waitcnt lgkmcnt(2)
	s_nop 2
	v_cvt_pk_bf16_f32 v10, v20, v22
	s_waitcnt lgkmcnt(1)
	s_nop 1
	s_waitcnt lgkmcnt(0)
	s_nop 2
	s_mul_i32 s22, s22, 0xfea00000
	s_ashr_i32 s3, s2, 31
	v_cvt_pk_bf16_f32 v11, v24, v26
	v_add_u32_e32 v6, s22, v78
	v_lshl_add_u64 v[4:5], s[2:3], 1, v[70:71]
	v_ashrrev_i32_e32 v7, 31, v6
	v_lshl_add_u64 v[28:29], v[4:5], 0, v[6:7]
	v_bfe_u32 v7, v13, 16, 1
	global_store_dwordx4 v[28:29], v[8:11], off
	v_add3_u32 v7, v13, v7, s14
	v_lshrrev_b32_e32 v7, 16, v7
	v_bfe_u32 v8, v15, 16, 1
	v_add3_u32 v8, v15, v8, s14
	v_and_or_b32 v8, v8, s15, v7
	s_nop 4
	v_cvt_pk_bf16_f32 v9, v17, v19
	s_nop 4
	v_cvt_pk_bf16_f32 v10, v21, v23
	s_nop 2
	v_add_u32_e32 v12, 0x16000, v6
	s_nop 1
	v_ashrrev_i32_e32 v13, 31, v12
	v_cvt_pk_bf16_f32 v11, v25, v27
	ds_read2_b32 v[14:15], v77 offset0:16 offset1:24
	v_lshl_add_u64 v[12:13], v[4:5], 0, v[12:13]
	global_store_dwordx4 v[12:13], v[8:11], off
	ds_read2_b32 v[12:13], v77 offset0:81 offset1:89
	ds_read2_b32 v[16:17], v77 offset0:146 offset1:154
	ds_read2_b32 v[18:19], v77 offset0:211 offset1:219
	s_waitcnt lgkmcnt(3)
	s_nop 1
	s_waitcnt lgkmcnt(2)
	s_nop 0
	ds_read2_b32 v[20:21], v30 offset0:20 offset1:28
	s_nop 1
	ds_read2_b32 v[22:23], v30 offset0:85 offset1:93
	v_cvt_pk_bf16_f32 v8, v14, v12
	s_waitcnt lgkmcnt(3)
; #define LAS __attribute__((address_space(3)))
; #define LDS_WAIT() asm volatile("s_waitcnt lgkmcnt(0)" ::: "memory")
; __device__ __forceinline__ unsigned pk2(float lo, float hi) { return f2bf(lo) | (f2bf(hi) << 16); }
;     ...
; #pragma unroll
;         for (int j = 0; j < 8; ++j) { const int n = (lane >> 3) + 8 * j; const LAS float* sp = scr + (8 * c8) * 65 + n;
;             v4u o; o.x = pk2(sp[0 * 65], sp[1 * 65]); o.y = pk2(sp[2 * 65], sp[3 * 65]); o.z = pk2(sp[4 * 65], sp[5 * 65]); o.w = pk2(sp[6 * 65], sp[7 * 65]);
;             *(v4u*)(WT + (size_t)(d0 + n) * K + k0 + 8 * c8) = o; }
;         LDS_WAIT(); asm volatile("" ::: "memory");
	s_nop 1
	s_waitcnt lgkmcnt(2)
	s_nop 0
	ds_read2_b32 v[24:25], v30 offset0:150 offset1:158
	s_nop 1
	ds_read2_b32 v[26:27], v30 offset0:215 offset1:223
	v_cvt_pk_bf16_f32 v9, v16, v18
	s_waitcnt lgkmcnt(3)
	s_nop 1
	s_waitcnt lgkmcnt(2)
	s_nop 2
	v_cvt_pk_bf16_f32 v10, v20, v22
	s_waitcnt lgkmcnt(1)
	s_nop 1
	s_waitcnt lgkmcnt(0)
	s_nop 0
	v_add_u32_e32 v28, 0x2c000, v6
	s_nop 1
	v_ashrrev_i32_e32 v29, 31, v28
	v_cvt_pk_bf16_f32 v11, v24, v26
	v_lshl_add_u64 v[28:29], v[4:5], 0, v[28:29]
	v_bfe_u32 v7, v15, 16, 1
	global_store_dwordx4 v[28:29], v[8:11], off
	v_add3_u32 v7, v15, v7, s14
	v_lshrrev_b32_e32 v7, 16, v7
	v_bfe_u32 v8, v13, 16, 1
	v_add3_u32 v8, v13, v8, s14
	v_and_or_b32 v8, v8, s15, v7
	s_nop 4
	v_cvt_pk_bf16_f32 v9, v17, v19
	s_nop 4
	v_cvt_pk_bf16_f32 v10, v21, v23
	s_nop 2
	v_add_u32_e32 v12, 0x42000, v6
	s_nop 1
	v_ashrrev_i32_e32 v13, 31, v12
	v_cvt_pk_bf16_f32 v11, v25, v27
	ds_read2_b32 v[14:15], v77 offset0:32 offset1:40
	v_lshl_add_u64 v[12:13], v[4:5], 0, v[12:13]
	global_store_dwordx4 v[12:13], v[8:11], off
	ds_read2_b32 v[12:13], v77 offset0:97 offset1:105
	ds_read2_b32 v[16:17], v77 offset0:162 offset1:170
	ds_read2_b32 v[18:19], v77 offset0:227 offset1:235
	s_waitcnt lgkmcnt(3)
	s_nop 1
	s_waitcnt lgkmcnt(2)
	s_nop 0
	ds_read2_b32 v[20:21], v30 offset0:36 offset1:44
	s_nop 1
	ds_read2_b32 v[22:23], v30 offset0:101 offset1:109
	v_cvt_pk_bf16_f32 v8, v14, v12
	s_waitcnt lgkmcnt(3)
	s_nop 1
	s_waitcnt lgkmcnt(2)
	s_nop 0
	ds_read2_b32 v[24:25], v30 offset0:166 offset1:174
	s_nop 1
	ds_read2_b32 v[26:27], v30 offset0:231 offset1:239
	v_cvt_pk_bf16_f32 v9, v16, v18
	s_waitcnt lgkmcnt(3)
	s_nop 1
	s_waitcnt lgkmcnt(2)
	s_nop 2
	v_cvt_pk_bf16_f32 v10, v20, v22
	s_waitcnt lgkmcnt(1)
	s_nop 1
	s_waitcnt lgkmcnt(0)
	s_nop 0
	v_add_u32_e32 v28, 0x58000, v6
	s_nop 1
	v_ashrrev_i32_e32 v29, 31, v28
	v_cvt_pk_bf16_f32 v11, v24, v26
	v_lshl_add_u64 v[28:29], v[4:5], 0, v[28:29]
	v_bfe_u32 v7, v15, 16, 1
	global_store_dwordx4 v[28:29], v[8:11], off
	v_add3_u32 v7, v15, v7, s14
	v_lshrrev_b32_e32 v7, 16, v7
	v_bfe_u32 v8, v13, 16, 1
	v_add3_u32 v8, v13, v8, s14
	v_and_or_b32 v8, v8, s15, v7
	s_nop 4
	v_cvt_pk_bf16_f32 v9, v17, v19
	s_nop 4
	v_cvt_pk_bf16_f32 v10, v21, v23
	s_nop 2
	v_add_u32_e32 v12, 0x6e000, v6
	s_nop 1
	v_ashrrev_i32_e32 v13, 31, v12
	v_cvt_pk_bf16_f32 v11, v25, v27
	ds_read2_b32 v[14:15], v77 offset0:48 offset1:56
	v_lshl_add_u64 v[12:13], v[4:5], 0, v[12:13]
	global_store_dwordx4 v[12:13], v[8:11], off
	ds_read2_b32 v[12:13], v77 offset0:113 offset1:121
	ds_read2_b32 v[16:17], v77 offset0:178 offset1:186
	ds_read2_b32 v[18:19], v77 offset0:243 offset1:251
	s_waitcnt lgkmcnt(3)
	s_nop 1
	s_waitcnt lgkmcnt(2)
	s_nop 0
	ds_read2_b32 v[20:21], v30 offset0:52 offset1:60
	s_nop 1
	ds_read2_b32 v[22:23], v30 offset0:117 offset1:125
	v_cvt_pk_bf16_f32 v8, v14, v12
	s_waitcnt lgkmcnt(3)
	s_nop 1
	s_waitcnt lgkmcnt(2)
	s_nop 0
	ds_read2_b32 v[24:25], v30 offset0:182 offset1:190
	s_nop 1
	ds_read2_b32 v[26:27], v30 offset0:247 offset1:255
	v_cvt_pk_bf16_f32 v9, v16, v18
	s_waitcnt lgkmcnt(3)
	s_nop 1
	s_waitcnt lgkmcnt(2)
	s_nop 2
	v_cvt_pk_bf16_f32 v10, v20, v22
	s_waitcnt lgkmcnt(1)
	s_nop 1
	s_waitcnt lgkmcnt(0)
	s_nop 0
	v_add_u32_e32 v28, 0x84000, v6
	s_nop 1
	v_ashrrev_i32_e32 v29, 31, v28
	v_cvt_pk_bf16_f32 v11, v24, v26
	v_lshl_add_u64 v[28:29], v[4:5], 0, v[28:29]
	v_bfe_u32 v7, v15, 16, 1
	global_store_dwordx4 v[28:29], v[8:11], off
	v_add3_u32 v7, v15, v7, s14
	v_lshrrev_b32_e32 v7, 16, v7
	v_bfe_u32 v8, v13, 16, 1
	v_add3_u32 v8, v13, v8, s14
	v_and_or_b32 v8, v8, s15, v7
	s_nop 4
	v_cvt_pk_bf16_f32 v9, v17, v19
	s_nop 4
	v_cvt_pk_bf16_f32 v10, v21, v23
	s_nop 4
	v_add_u32_e32 v6, 0x9a000, v6
	v_cvt_pk_bf16_f32 v11, v25, v27
	v_ashrrev_i32_e32 v7, 31, v6
	v_lshl_add_u64 v[4:5], v[4:5], 0, v[6:7]
	global_store_dwordx4 v[4:5], v[8:11], off
	s_waitcnt lgkmcnt(0)
	s_add_i32 s20, s20, s21
	s_add_i32 s12, s12, s13
	s_mul_i32 s2, s21, 0xb0000
	s_cmpk_lt_i32 s20, 0xb00
	v_add_u32_e32 v78, s2, v78
	s_cbranch_scc0 .LBB0_1717

; __device__ __forceinline__ unsigned pk2(float lo, float hi) { return f2bf(lo) | (f2bf(hi) << 16); }
; __device__ __forceinline__ float sigmoidf_(float x) { return 1.f / (1.f + __expf(-x)); }
; __device__ __forceinline__ void nsa_attn_sw(const Ctx& c, const bf16* Q, const bf16* T, const bf16* VT, const float* Gt, const float* NACC, float* NACC2, const unsigned long long* SMg, bf16* OUT) {
;     ...
;           for (int mi = 0; mi < 2; ++mi) { float lt = l[mi]; lt += __shfl_xor(lt, 16); lt += __shfl_xor(lt, 32); const float sc = sigmoidf_(Gt[(size_t)grow[mi] * 48 + (hcol[mi] >> 7) * 3 + 2]) / lt;
; #pragma unroll
;               for (int dt = 0; dt < 8; ++dt) { const f32x4 a = *(const f32x4*)(NACC2 + (size_t)grow[mi] * 2048 + hcol[mi] + 16 * dt + 4 * lg) + O[dt][mi] * sc; v2u w_; w_.x = pk2(a[0], a[1]); w_.y = pk2(a[2], a[3]);
;                   *(v2u*)(OUT + (size_t)grow[mi] * 2048 + hcol[mi] + 16 * dt + 4 * lg) = w_; } }
.LBB0_2308:
	ds_bpermute_b32 v4, v208, v11
	v_mov_b32_e32 v13, v5
	v_lshlrev_b32_e32 v14, 1, v200
	v_mov_b32_e32 v15, v5
	v_lshlrev_b32_e32 v16, 1, v170
	s_waitcnt lgkmcnt(0)
	v_add_f32_e32 v4, v11, v4
	ds_bpermute_b32 v6, v209, v4
	v_mov_b32_e32 v17, v5
	s_add_i32 s36, s36, s33
	s_cmpk_lt_i32 s36, 0x400
	s_waitcnt lgkmcnt(0)
	v_add_f32_e32 v4, v4, v6
	global_load_dword v6, v[194:195], off offset:8
	s_waitcnt vmcnt(0)
	v_mul_f32_e32 v6, 0xbfb8aa3b, v6
	v_exp_f32_e32 v6, v6
	s_nop 0
	v_add_f32_e32 v6, 1.0, v6
	v_div_scale_f32 v7, s[0:1], v6, v6, 1.0
	v_rcp_f32_e32 v8, v7
	s_nop 0
	v_fma_f32 v9, -v7, v8, 1.0
	v_fmac_f32_e32 v8, v9, v8
	v_div_scale_f32 v9, vcc, 1.0, v6, 1.0
	v_mul_f32_e32 v11, v9, v8
	v_fma_f32 v12, -v7, v11, v9
	v_fmac_f32_e32 v11, v12, v8
	v_fma_f32 v7, -v7, v11, v9
	v_div_fmas_f32 v7, v7, v8, v11
	v_div_fixup_f32 v6, v7, v6, 1.0
	v_div_scale_f32 v7, s[0:1], v4, v4, v6
	v_rcp_f32_e32 v8, v7
	s_nop 0
	v_fma_f32 v9, -v7, v8, 1.0
	v_fmac_f32_e32 v8, v9, v8
	v_div_scale_f32 v9, vcc, v6, v4, v6
	v_mul_f32_e32 v11, v9, v8
	v_fma_f32 v12, -v7, v11, v9
	v_fmac_f32_e32 v11, v12, v8
	v_fma_f32 v7, -v7, v11, v9
	v_div_fmas_f32 v7, v7, v8, v11
	v_div_fixup_f32 v18, v7, v4, v6
	v_lshl_add_u64 v[6:7], s[14:15], 0, v[196:197]
	v_lshlrev_b32_e32 v4, 2, v200
	v_lshl_add_u64 v[6:7], v[6:7], 0, v[4:5]
	v_lshlrev_b32_e32 v12, 2, v170
	v_lshl_add_u64 v[6:7], v[6:7], 0, v[12:13]
	global_load_dwordx4 v[124:127], v[6:7], off
	global_load_dwordx4 v[128:131], v[6:7], off offset:64
	global_load_dwordx4 v[132:135], v[6:7], off offset:128
	global_load_dwordx4 v[136:139], v[6:7], off offset:192
	global_load_dwordx4 v[140:143], v[6:7], off offset:256
	global_load_dwordx4 v[144:147], v[6:7], off offset:320
	global_load_dwordx4 v[148:151], v[6:7], off offset:384
	global_load_dwordx4 v[152:155], v[6:7], off offset:448
	v_lshl_add_u64 v[8:9], s[78:79], 0, v[184:185]
	v_lshl_add_u64 v[8:9], v[8:9], 0, v[14:15]
	v_lshl_add_u64 v[20:21], v[8:9], 0, v[16:17]
	s_waitcnt vmcnt(7)
	v_pk_fma_f32 v[22:23], v[100:101], v[18:19], v[124:125] op_sel_hi:[1,0,1]
	s_nop 0
	v_bfe_u32 v11, v22, 16, 1
	v_pk_fma_f32 v[8:9], v[102:103], v[18:19], v[126:127] op_sel_hi:[1,0,1]
	v_add3_u32 v11, v22, v11, s34
	v_bfe_u32 v19, v23, 16, 1
	v_lshrrev_b32_e32 v11, 16, v11
	v_add3_u32 v19, v23, v19, s34
	v_and_or_b32 v22, v19, s35, v11
	s_nop 4
	v_cvt_pk_bf16_f32 v23, v8, v9
	global_store_dwordx2 v[20:21], v[22:23], off
	s_waitcnt vmcnt(7)
	v_pk_fma_f32 v[22:23], v[96:97], v[18:19], v[128:129] op_sel_hi:[1,0,1]
	s_nop 0
	v_bfe_u32 v11, v22, 16, 1
	v_pk_fma_f32 v[8:9], v[98:99], v[18:19], v[130:131] op_sel_hi:[1,0,1]
	v_add3_u32 v11, v22, v11, s34
	v_bfe_u32 v19, v23, 16, 1
	v_lshrrev_b32_e32 v11, 16, v11
	v_add3_u32 v19, v23, v19, s34
	v_and_or_b32 v22, v19, s35, v11
	s_nop 4
	v_cvt_pk_bf16_f32 v23, v8, v9
	global_store_dwordx2 v[20:21], v[22:23], off offset:32
	s_waitcnt vmcnt(7)
	v_pk_fma_f32 v[22:23], v[92:93], v[18:19], v[132:133] op_sel_hi:[1,0,1]
	s_nop 0
	v_bfe_u32 v11, v22, 16, 1
	v_pk_fma_f32 v[8:9], v[94:95], v[18:19], v[134:135] op_sel_hi:[1,0,1]
	v_add3_u32 v11, v22, v11, s34
	v_bfe_u32 v19, v23, 16, 1
	v_lshrrev_b32_e32 v11, 16, v11
	v_add3_u32 v19, v23, v19, s34
	v_and_or_b32 v22, v19, s35, v11
	s_nop 4
	v_cvt_pk_bf16_f32 v23, v8, v9
	global_store_dwordx2 v[20:21], v[22:23], off offset:64
	s_waitcnt vmcnt(7)
	v_pk_fma_f32 v[22:23], v[88:89], v[18:19], v[136:137] op_sel_hi:[1,0,1]
	s_nop 0
	v_bfe_u32 v11, v22, 16, 1
	v_pk_fma_f32 v[8:9], v[90:91], v[18:19], v[138:139] op_sel_hi:[1,0,1]
	v_add3_u32 v11, v22, v11, s34
	v_bfe_u32 v19, v23, 16, 1
	v_lshrrev_b32_e32 v11, 16, v11
	v_add3_u32 v19, v23, v19, s34
	v_and_or_b32 v22, v19, s35, v11
	s_nop 4
	v_cvt_pk_bf16_f32 v23, v8, v9
	global_store_dwordx2 v[20:21], v[22:23], off offset:96
	s_waitcnt vmcnt(7)
	v_pk_fma_f32 v[22:23], v[84:85], v[18:19], v[140:141] op_sel_hi:[1,0,1]
	s_nop 0
	v_bfe_u32 v11, v22, 16, 1
	v_pk_fma_f32 v[8:9], v[86:87], v[18:19], v[142:143] op_sel_hi:[1,0,1]
	v_add3_u32 v11, v22, v11, s34
	v_bfe_u32 v19, v23, 16, 1
	v_lshrrev_b32_e32 v11, 16, v11
	v_add3_u32 v19, v23, v19, s34
	v_and_or_b32 v22, v19, s35, v11
	s_nop 4
	v_cvt_pk_bf16_f32 v23, v8, v9
	global_store_dwordx2 v[20:21], v[22:23], off offset:128
	s_waitcnt vmcnt(7)
	v_pk_fma_f32 v[22:23], v[80:81], v[18:19], v[144:145] op_sel_hi:[1,0,1]
	s_nop 0
	v_bfe_u32 v11, v22, 16, 1
	v_pk_fma_f32 v[8:9], v[82:83], v[18:19], v[146:147] op_sel_hi:[1,0,1]
	v_add3_u32 v11, v22, v11, s34
	v_bfe_u32 v19, v23, 16, 1
	v_lshrrev_b32_e32 v11, 16, v11
	v_add3_u32 v19, v23, v19, s34
	v_and_or_b32 v22, v19, s35, v11
	s_nop 4
	v_cvt_pk_bf16_f32 v23, v8, v9
	global_store_dwordx2 v[20:21], v[22:23], off offset:160
	s_waitcnt vmcnt(7)
	v_pk_fma_f32 v[22:23], v[76:77], v[18:19], v[148:149] op_sel_hi:[1,0,1]
	s_nop 0
	v_bfe_u32 v11, v22, 16, 1
	v_pk_fma_f32 v[8:9], v[78:79], v[18:19], v[150:151] op_sel_hi:[1,0,1]
	v_add3_u32 v11, v22, v11, s34
	v_bfe_u32 v19, v23, 16, 1
	v_lshrrev_b32_e32 v11, 16, v11
	v_add3_u32 v19, v23, v19, s34
	v_and_or_b32 v22, v19, s35, v11
	s_nop 4
	v_cvt_pk_bf16_f32 v23, v8, v9
	s_waitcnt vmcnt(6)
	v_pk_fma_f32 v[6:7], v[72:73], v[18:19], v[152:153] op_sel_hi:[1,0,1]
	s_nop 0
	s_nop 2
	v_pk_fma_f32 v[8:9], v[74:75], v[18:19], v[154:155] op_sel_hi:[1,0,1]
	s_nop 1
	v_cvt_pk_bf16_f32 v6, v6, v7
	v_bfe_u32 v7, v8, 16, 1
	v_add3_u32 v7, v8, v7, s34
	v_bfe_u32 v8, v9, 16, 1
	v_lshrrev_b32_e32 v7, 16, v7
	v_add3_u32 v8, v9, v8, s34
	v_and_or_b32 v7, v8, s35, v7
	global_store_dwordx2 v[20:21], v[6:7], off offset:224
	ds_bpermute_b32 v6, v208, v10
	global_store_dwordx2 v[20:21], v[22:23], off offset:192
	s_waitcnt lgkmcnt(0)
; __device__ __forceinline__ unsigned pk2(float lo, float hi) { return f2bf(lo) | (f2bf(hi) << 16); }
; __device__ __forceinline__ float sigmoidf_(float x) { return 1.f / (1.f + __expf(-x)); }
; __device__ __forceinline__ void nsa_attn_sw(const Ctx& c, const bf16* Q, const bf16* T, const bf16* VT, const float* Gt, const float* NACC, float* NACC2, const unsigned long long* SMg, bf16* OUT) {
;     ...
;           for (int mi = 0; mi < 2; ++mi) { float lt = l[mi]; lt += __shfl_xor(lt, 16); lt += __shfl_xor(lt, 32); const float sc = sigmoidf_(Gt[(size_t)grow[mi] * 48 + (hcol[mi] >> 7) * 3 + 2]) / lt;
; #pragma unroll
;               for (int dt = 0; dt < 8; ++dt) { const f32x4 a = *(const f32x4*)(NACC2 + (size_t)grow[mi] * 2048 + hcol[mi] + 16 * dt + 4 * lg) + O[dt][mi] * sc; v2u w_; w_.x = pk2(a[0], a[1]); w_.y = pk2(a[2], a[3]);
;                   *(v2u*)(OUT + (size_t)grow[mi] * 2048 + hcol[mi] + 16 * dt + 4 * lg) = w_; } }
	v_add_f32_e32 v6, v10, v6
	ds_bpermute_b32 v7, v209, v6
	s_waitcnt lgkmcnt(0)
	v_add_f32_e32 v6, v6, v7
	global_load_dword v7, v[186:187], off offset:8
	s_waitcnt vmcnt(0)
	v_mul_f32_e32 v7, 0xbfb8aa3b, v7
	v_exp_f32_e32 v7, v7
	s_nop 0
	v_add_f32_e32 v7, 1.0, v7
	v_div_scale_f32 v8, s[0:1], v7, v7, 1.0
	v_rcp_f32_e32 v9, v8
	s_nop 0
	v_fma_f32 v10, -v8, v9, 1.0
	v_fmac_f32_e32 v9, v10, v9
	v_div_scale_f32 v10, vcc, 1.0, v7, 1.0
	v_mul_f32_e32 v11, v10, v9
	v_fma_f32 v18, -v8, v11, v10
	v_fmac_f32_e32 v11, v18, v9
	v_fma_f32 v8, -v8, v11, v10
	v_div_fmas_f32 v8, v8, v9, v11
	v_div_fixup_f32 v7, v8, v7, 1.0
	v_div_scale_f32 v8, s[0:1], v6, v6, v7
	v_rcp_f32_e32 v9, v8
	s_nop 0
	v_fma_f32 v10, -v8, v9, 1.0
	v_fmac_f32_e32 v9, v10, v9
	v_div_scale_f32 v10, vcc, v7, v6, v7
	v_mul_f32_e32 v11, v10, v9
	v_fma_f32 v18, -v8, v11, v10
	v_fmac_f32_e32 v11, v18, v9
	v_fma_f32 v8, -v8, v11, v10
	v_div_fmas_f32 v8, v8, v9, v11
	v_div_fixup_f32 v6, v8, v6, v7
	v_lshl_add_u64 v[8:9], s[14:15], 0, v[188:189]
	v_lshl_add_u64 v[8:9], v[8:9], 0, v[4:5]
	v_lshl_add_u64 v[10:11], v[8:9], 0, v[12:13]
	v_lshl_add_u64 v[8:9], s[78:79], 0, v[182:183]
	v_lshl_add_u64 v[8:9], v[8:9], 0, v[14:15]
	global_load_dwordx4 v[124:127], v[10:11], off
	global_load_dwordx4 v[128:131], v[10:11], off offset:64
	global_load_dwordx4 v[132:135], v[10:11], off offset:128
	global_load_dwordx4 v[136:139], v[10:11], off offset:192
	global_load_dwordx4 v[140:143], v[10:11], off offset:256
	global_load_dwordx4 v[144:147], v[10:11], off offset:320
	global_load_dwordx4 v[148:151], v[10:11], off offset:384
	global_load_dwordx4 v[152:155], v[10:11], off offset:448
	v_lshl_add_u64 v[8:9], v[8:9], 0, v[16:17]
	s_waitcnt vmcnt(7)
	v_pk_fma_f32 v[12:13], v[68:69], v[6:7], v[124:125] op_sel_hi:[1,0,1]
	s_nop 0
	v_bfe_u32 v4, v12, 16, 1
	v_pk_fma_f32 v[14:15], v[70:71], v[6:7], v[126:127] op_sel_hi:[1,0,1]
	v_add3_u32 v4, v12, v4, s34
	v_bfe_u32 v7, v13, 16, 1
	v_lshrrev_b32_e32 v4, 16, v4
	v_add3_u32 v7, v13, v7, s34
	v_and_or_b32 v12, v7, s35, v4
	v_bfe_u32 v4, v14, 16, 1
	v_add3_u32 v4, v14, v4, s34
	v_bfe_u32 v7, v15, 16, 1
	v_lshrrev_b32_e32 v4, 16, v4
	v_add3_u32 v7, v15, v7, s34
	v_and_or_b32 v13, v7, s35, v4
	global_store_dwordx2 v[8:9], v[12:13], off
	s_waitcnt vmcnt(7)
	v_pk_fma_f32 v[12:13], v[64:65], v[6:7], v[128:129] op_sel_hi:[1,0,1]
	s_nop 0
	v_bfe_u32 v4, v12, 16, 1
	v_pk_fma_f32 v[14:15], v[66:67], v[6:7], v[130:131] op_sel_hi:[1,0,1]
	v_add3_u32 v4, v12, v4, s34
	v_bfe_u32 v7, v13, 16, 1
	v_lshrrev_b32_e32 v4, 16, v4
	v_add3_u32 v7, v13, v7, s34
	v_and_or_b32 v12, v7, s35, v4
	v_bfe_u32 v4, v14, 16, 1
	v_add3_u32 v4, v14, v4, s34
	v_bfe_u32 v7, v15, 16, 1
	v_lshrrev_b32_e32 v4, 16, v4
	v_add3_u32 v7, v15, v7, s34
	v_and_or_b32 v13, v7, s35, v4
	global_store_dwordx2 v[8:9], v[12:13], off offset:32
	s_waitcnt vmcnt(7)
	v_pk_fma_f32 v[12:13], v[60:61], v[6:7], v[132:133] op_sel_hi:[1,0,1]
	s_nop 0
	v_bfe_u32 v4, v12, 16, 1
	v_pk_fma_f32 v[14:15], v[62:63], v[6:7], v[134:135] op_sel_hi:[1,0,1]
	v_add3_u32 v4, v12, v4, s34
	v_bfe_u32 v7, v13, 16, 1
	v_lshrrev_b32_e32 v4, 16, v4
	v_add3_u32 v7, v13, v7, s34
	v_and_or_b32 v12, v7, s35, v4
	v_bfe_u32 v4, v14, 16, 1
	v_add3_u32 v4, v14, v4, s34
	v_bfe_u32 v7, v15, 16, 1
	v_lshrrev_b32_e32 v4, 16, v4
	v_add3_u32 v7, v15, v7, s34
	v_and_or_b32 v13, v7, s35, v4
	global_store_dwordx2 v[8:9], v[12:13], off offset:64
	s_waitcnt vmcnt(7)
	v_pk_fma_f32 v[12:13], v[56:57], v[6:7], v[136:137] op_sel_hi:[1,0,1]
	s_nop 0
	v_bfe_u32 v4, v12, 16, 1
	v_pk_fma_f32 v[14:15], v[58:59], v[6:7], v[138:139] op_sel_hi:[1,0,1]
	v_add3_u32 v4, v12, v4, s34
	v_bfe_u32 v7, v13, 16, 1
	v_lshrrev_b32_e32 v4, 16, v4
	v_add3_u32 v7, v13, v7, s34
	v_and_or_b32 v12, v7, s35, v4
	v_bfe_u32 v4, v14, 16, 1
	v_add3_u32 v4, v14, v4, s34
	v_bfe_u32 v7, v15, 16, 1
	v_lshrrev_b32_e32 v4, 16, v4
	v_add3_u32 v7, v15, v7, s34
	v_and_or_b32 v13, v7, s35, v4
	global_store_dwordx2 v[8:9], v[12:13], off offset:96
	s_waitcnt vmcnt(7)
	v_pk_fma_f32 v[12:13], v[52:53], v[6:7], v[140:141] op_sel_hi:[1,0,1]
	s_nop 0
	v_bfe_u32 v4, v12, 16, 1
	v_pk_fma_f32 v[14:15], v[54:55], v[6:7], v[142:143] op_sel_hi:[1,0,1]
	v_add3_u32 v4, v12, v4, s34
	v_bfe_u32 v7, v13, 16, 1
	v_lshrrev_b32_e32 v4, 16, v4
	v_add3_u32 v7, v13, v7, s34
	v_and_or_b32 v12, v7, s35, v4
	v_bfe_u32 v4, v14, 16, 1
	v_add3_u32 v4, v14, v4, s34
	v_bfe_u32 v7, v15, 16, 1
	v_lshrrev_b32_e32 v4, 16, v4
	v_add3_u32 v7, v15, v7, s34
	v_and_or_b32 v13, v7, s35, v4
	global_store_dwordx2 v[8:9], v[12:13], off offset:128
	s_waitcnt vmcnt(7)
	v_pk_fma_f32 v[12:13], v[48:49], v[6:7], v[144:145] op_sel_hi:[1,0,1]
	s_nop 0
	v_bfe_u32 v4, v12, 16, 1
	v_pk_fma_f32 v[14:15], v[50:51], v[6:7], v[146:147] op_sel_hi:[1,0,1]
	v_add3_u32 v4, v12, v4, s34
	v_bfe_u32 v7, v13, 16, 1
	v_lshrrev_b32_e32 v4, 16, v4
	v_add3_u32 v7, v13, v7, s34
	v_and_or_b32 v12, v7, s35, v4
	v_bfe_u32 v4, v14, 16, 1
	v_add3_u32 v4, v14, v4, s34
	v_bfe_u32 v7, v15, 16, 1
	v_lshrrev_b32_e32 v4, 16, v4
	v_add3_u32 v7, v15, v7, s34
	v_and_or_b32 v13, v7, s35, v4
	global_store_dwordx2 v[8:9], v[12:13], off offset:160
	s_waitcnt vmcnt(7)
	v_pk_fma_f32 v[12:13], v[44:45], v[6:7], v[148:149] op_sel_hi:[1,0,1]
	s_nop 0
	v_bfe_u32 v4, v12, 16, 1
	v_pk_fma_f32 v[14:15], v[46:47], v[6:7], v[150:151] op_sel_hi:[1,0,1]
	v_add3_u32 v4, v12, v4, s34
	v_bfe_u32 v7, v13, 16, 1
	v_lshrrev_b32_e32 v4, 16, v4
	v_add3_u32 v7, v13, v7, s34
	v_and_or_b32 v12, v7, s35, v4
	v_bfe_u32 v4, v14, 16, 1
	v_add3_u32 v4, v14, v4, s34
	v_bfe_u32 v7, v15, 16, 1
	v_lshrrev_b32_e32 v4, 16, v4
	v_add3_u32 v7, v15, v7, s34
	v_and_or_b32 v13, v7, s35, v4
	global_store_dwordx2 v[8:9], v[12:13], off offset:192
	s_waitcnt vmcnt(7)
	v_pk_fma_f32 v[12:13], v[42:43], v[6:7], v[154:155] op_sel_hi:[1,0,1]
	v_pk_fma_f32 v[6:7], v[40:41], v[6:7], v[152:153] op_sel_hi:[1,0,1]
	s_nop 0
	v_bfe_u32 v4, v6, 16, 1
	v_add3_u32 v4, v6, v4, s34
	v_bfe_u32 v6, v7, 16, 1
	v_lshrrev_b32_e32 v4, 16, v4
	v_add3_u32 v6, v7, v6, s34
	v_and_or_b32 v6, v6, s35, v4
	v_bfe_u32 v4, v12, 16, 1
	v_add3_u32 v4, v12, v4, s34
	v_bfe_u32 v7, v13, 16, 1
	v_lshrrev_b32_e32 v4, 16, v4
	v_add3_u32 v7, v13, v7, s34
	v_and_or_b32 v7, v7, s35, v4
	global_store_dwordx2 v[8:9], v[6:7], off offset:224
	s_cbranch_scc0 .LBB0_2352

; __device__ __forceinline__ void postnorm(const Ctx& c, const bf16* MF, bf16* XB, float* RS, const float* gpost, float* OUT) {
;     for (int row = c.gw; row < MT; row += c.NGW) {
;         const v4u* mr = (const v4u*)(MF + (size_t)row * DM) + c.lane; v4u* xr = (v4u*)(XB + (size_t)row * DM) + c.lane;
;         v4u mv[4], xv[4]; float v[4][8]; float s = 0.f;
; #pragma unroll
;         for (int j = 0; j < 4; ++j) { mv[j] = mr[64 * j]; xv[j] = xr[64 * j]; }
; #pragma unroll
;         for (int j = 0; j < 4; ++j)
; #pragma unroll
;             for (int k = 0; k < 4; ++k) { v[j][2 * k] = bflo(mv[j][k]); v[j][2 * k + 1] = bfhi(mv[j][k]); s += v[j][2 * k] * v[j][2 * k] + v[j][2 * k + 1] * v[j][2 * k + 1]; }
;         const float rs = rsqrtf(wave_sum(s) * (1.f / DM) + EPS);
;         float s2 = 0.f;
; #pragma unroll
;         for (int j = 0; j < 4; ++j) { const float* gp = gpost + (c.lane + 64 * j) * 8; const f32x4 g0 = *(CF4)gp, g1 = *(CF4)(gp + 4);
; #pragma unroll
;             for (int k = 0; k < 4; ++k) { const float ga = (k < 2) ? g0[2 * k] : g1[2 * k - 4], gb = (k < 2) ? g0[2 * k + 1] : g1[2 * k - 3];
;                 v[j][2 * k] = bflo(xv[j][k]) + v[j][2 * k] * rs * ga; v[j][2 * k + 1] = bfhi(xv[j][k]) + v[j][2 * k + 1] * rs * gb;
;                 s2 += v[j][2 * k] * v[j][2 * k] + v[j][2 * k + 1] * v[j][2 * k + 1]; } }
.LBB0_2484:
	v_readlane_b32 s12, v253, 0
	v_readlane_b32 s13, v253, 1
	s_nop 1
	v_lshl_add_u64 v[38:39], s[12:13], 0, v[30:31]
	v_add_co_u32_e32 v58, vcc, 0xd400000, v38
	s_nop 1
	v_addc_co_u32_e32 v59, vcc, 0, v39, vcc
	s_waitcnt lgkmcnt(0)
	global_load_dwordx4 v[46:49], v[58:59], off
	global_load_dwordx4 v[50:53], v[58:59], off offset:1024
	global_load_dwordx4 v[54:57], v[58:59], off offset:2048
	s_nop 0
	global_load_dwordx4 v[58:61], v[58:59], off offset:3072
	v_add_co_u32_e32 v38, vcc, 0x9400000, v38
	s_waitcnt vmcnt(3)
	v_lshlrev_b32_e32 v79, 16, v47
	v_addc_co_u32_e32 v39, vcc, 0, v39, vcc
	global_load_dwordx4 v[62:65], v[38:39], off
	global_load_dwordx4 v[66:69], v[38:39], off offset:1024
	global_load_dwordx4 v[70:73], v[38:39], off offset:2048
	global_load_dwordx4 v[74:77], v[38:39], off offset:3072
	v_lshlrev_b32_e32 v78, 16, v46
	v_and_b32_e32 v47, 0xffff0000, v47
	v_and_b32_e32 v46, 0xffff0000, v46
	v_lshlrev_b32_e32 v81, 16, v49
	v_lshlrev_b32_e32 v80, 16, v48
	v_and_b32_e32 v49, 0xffff0000, v49
	v_and_b32_e32 v48, 0xffff0000, v48
	v_pk_mul_f32 v[94:95], v[46:47], v[46:47]
	v_pk_mul_f32 v[98:99], v[48:49], v[48:49]
	v_pk_fma_f32 v[94:95], v[78:79], v[78:79], v[94:95]
	s_waitcnt vmcnt(6)
	v_lshlrev_b32_e32 v83, 16, v51
	v_lshlrev_b32_e32 v82, 16, v50
	v_and_b32_e32 v51, 0xffff0000, v51
	v_and_b32_e32 v50, 0xffff0000, v50
	v_pk_fma_f32 v[98:99], v[80:81], v[80:81], v[98:99]
	v_add_f32_e32 v94, v94, v95
	v_pk_mul_f32 v[102:103], v[50:51], v[50:51]
	v_add_f32_e32 v94, v98, v94
	v_lshlrev_b32_e32 v85, 16, v53
	v_lshlrev_b32_e32 v84, 16, v52
	v_and_b32_e32 v53, 0xffff0000, v53
	v_and_b32_e32 v52, 0xffff0000, v52
	v_pk_fma_f32 v[102:103], v[82:83], v[82:83], v[102:103]
	v_add_f32_e32 v94, v99, v94
	v_pk_mul_f32 v[104:105], v[52:53], v[52:53]
	v_add_f32_e32 v94, v102, v94
	s_waitcnt vmcnt(5)
	v_lshlrev_b32_e32 v87, 16, v55
	v_lshlrev_b32_e32 v86, 16, v54
	v_and_b32_e32 v55, 0xffff0000, v55
	v_and_b32_e32 v54, 0xffff0000, v54
	v_pk_fma_f32 v[104:105], v[84:85], v[84:85], v[104:105]
	v_add_f32_e32 v94, v103, v94
	v_pk_mul_f32 v[106:107], v[54:55], v[54:55]
	v_add_f32_e32 v94, v104, v94
	v_lshlrev_b32_e32 v89, 16, v57
	v_lshlrev_b32_e32 v88, 16, v56
	v_and_b32_e32 v57, 0xffff0000, v57
	v_and_b32_e32 v56, 0xffff0000, v56
	v_pk_fma_f32 v[106:107], v[86:87], v[86:87], v[106:107]
	v_add_f32_e32 v94, v105, v94
	v_pk_mul_f32 v[108:109], v[56:57], v[56:57]
	v_add_f32_e32 v94, v106, v94
	s_waitcnt vmcnt(4)
	v_lshlrev_b32_e32 v91, 16, v59
	v_lshlrev_b32_e32 v90, 16, v58
	v_and_b32_e32 v59, 0xffff0000, v59
	v_and_b32_e32 v58, 0xffff0000, v58
	v_pk_fma_f32 v[108:109], v[88:89], v[88:89], v[108:109]
	v_add_f32_e32 v94, v107, v94
	v_pk_mul_f32 v[110:111], v[58:59], v[58:59]
	v_add_f32_e32 v94, v108, v94
	v_lshlrev_b32_e32 v93, 16, v61
	v_lshlrev_b32_e32 v92, 16, v60
	v_and_b32_e32 v61, 0xffff0000, v61
	v_and_b32_e32 v60, 0xffff0000, v60
	v_pk_fma_f32 v[110:111], v[90:91], v[90:91], v[110:111]
	v_add_f32_e32 v94, v109, v94
	v_pk_mul_f32 v[112:113], v[60:61], v[60:61]
	v_add_f32_e32 v94, v110, v94
	v_pk_fma_f32 v[112:113], v[92:93], v[92:93], v[112:113]
	v_add_f32_e32 v94, v111, v94
	v_add_f32_e32 v94, v112, v94
	v_add_f32_e32 v94, v113, v94
	ds_bpermute_b32 v98, v3, v94
	s_waitcnt lgkmcnt(0)
	v_add_f32_e32 v98, v94, v98
	ds_bpermute_b32 v102, v40, v98
	s_waitcnt lgkmcnt(0)
	v_add_f32_e32 v102, v98, v102
	ds_bpermute_b32 v104, v41, v102
	s_waitcnt vmcnt(3)
	v_lshlrev_b32_e32 v97, 16, v63
	v_lshlrev_b32_e32 v96, 16, v62
	v_and_b32_e32 v63, 0xffff0000, v63
	s_waitcnt lgkmcnt(0)
	v_add_f32_e32 v104, v102, v104
	ds_bpermute_b32 v106, v42, v104
	v_and_b32_e32 v62, 0xffff0000, v62
	v_lshlrev_b32_e32 v101, 16, v65
	v_lshlrev_b32_e32 v100, 16, v64
	v_and_b32_e32 v65, 0xffff0000, v65
	s_waitcnt lgkmcnt(0)
	v_add_f32_e32 v106, v104, v106
	ds_bpermute_b32 v108, v43, v106
	v_and_b32_e32 v64, 0xffff0000, v64
	s_waitcnt vmcnt(0)
	v_lshlrev_b32_e32 v109, 16, v77
	v_and_b32_e32 v77, 0xffff0000, v77
	v_lshlrev_b32_e32 v95, 16, v67
	s_waitcnt lgkmcnt(0)
	v_add_f32_e32 v108, v106, v108
	ds_bpermute_b32 v110, v44, v108
	v_lshlrev_b32_e32 v94, 16, v66
	v_and_b32_e32 v67, 0xffff0000, v67
	v_and_b32_e32 v66, 0xffff0000, v66
	v_lshlrev_b32_e32 v99, 16, v69
	s_waitcnt lgkmcnt(0)
	v_add_f32_e32 v108, v108, v110
	v_fmamk_f32 v108, v108, 0x3a000000, v45
	v_mul_f32_e32 v110, 0x4b800000, v108
	v_cmp_gt_f32_e32 vcc, s17, v108
	v_lshlrev_b32_e32 v98, 16, v68
	v_and_b32_e32 v69, 0xffff0000, v69
	v_cndmask_b32_e32 v108, v108, v110, vcc
	v_rsq_f32_e32 v110, v108
	v_lshlrev_b32_e32 v108, 16, v76
	v_and_b32_e32 v76, 0xffff0000, v76
	v_and_b32_e32 v68, 0xffff0000, v68
	v_mul_f32_e32 v111, 0x45800000, v110
	v_cndmask_b32_e32 v110, v110, v111, vcc
	v_pk_mul_f32 v[46:47], v[110:111], v[46:47] op_sel_hi:[0,1]
	v_pk_mul_f32 v[78:79], v[110:111], v[78:79] op_sel_hi:[0,1]
	v_pk_mul_f32 v[48:49], v[110:111], v[48:49] op_sel_hi:[0,1]
	v_pk_fma_f32 v[46:47], v[36:37], v[46:47], v[62:63]
	v_pk_mul_f32 v[60:61], v[110:111], v[60:61] op_sel_hi:[0,1]
	v_pk_mul_f32 v[80:81], v[110:111], v[80:81] op_sel_hi:[0,1]
	v_pk_fma_f32 v[78:79], v[8:9], v[78:79], v[96:97]
	v_pk_fma_f32 v[48:49], v[10:11], v[48:49], v[64:65]
	v_pk_fma_f32 v[60:61], v[34:35], v[60:61], v[76:77]
	v_pk_mul_f32 v[76:77], v[46:47], v[46:47]
	v_pk_mul_f32 v[50:51], v[110:111], v[50:51] op_sel_hi:[0,1]
	v_pk_fma_f32 v[62:63], v[4:5], v[80:81], v[100:101]
	v_pk_fma_f32 v[76:77], v[78:79], v[78:79], v[76:77]
	v_pk_mul_f32 v[80:81], v[48:49], v[48:49]
	v_pk_mul_f32 v[82:83], v[110:111], v[82:83] op_sel_hi:[0,1]
	v_pk_fma_f32 v[50:51], v[6:7], v[50:51], v[66:67]
	v_pk_fma_f32 v[80:81], v[62:63], v[62:63], v[80:81]
	v_add_f32_e32 v76, v76, v77
; __device__ __forceinline__ unsigned pk2(float lo, float hi) { return f2bf(lo) | (f2bf(hi) << 16); }
; __device__ __forceinline__ void postnorm(const Ctx& c, const bf16* MF, bf16* XB, float* RS, const float* gpost, float* OUT) {
;     ...
;         const float rs = rsqrtf(wave_sum(s) * (1.f / DM) + EPS);
;         float s2 = 0.f;
; #pragma unroll
;         for (int j = 0; j < 4; ++j) { const float* gp = gpost + (c.lane + 64 * j) * 8; const f32x4 g0 = *(CF4)gp, g1 = *(CF4)(gp + 4);
; #pragma unroll
;             for (int k = 0; k < 4; ++k) { const float ga = (k < 2) ? g0[2 * k] : g1[2 * k - 4], gb = (k < 2) ? g0[2 * k + 1] : g1[2 * k - 3];
;                 v[j][2 * k] = bflo(xv[j][k]) + v[j][2 * k] * rs * ga; v[j][2 * k + 1] = bfhi(xv[j][k]) + v[j][2 * k + 1] * rs * gb;
;                 s2 += v[j][2 * k] * v[j][2 * k] + v[j][2 * k + 1] * v[j][2 * k + 1]; } }
;         if (OUT) {
; #pragma unroll
;             for (int j = 0; j < 4; ++j) { float* op = OUT + (size_t)row * DM + (c.lane + 64 * j) * 8; *(f32x4*)op = (f32x4){v[j][0], v[j][1], v[j][2], v[j][3]}; *(f32x4*)(op + 4) = (f32x4){v[j][4], v[j][5], v[j][6], v[j][7]}; }
;         } else {
; #pragma unroll
;             for (int j = 0; j < 4; ++j) { v4u o; o.x = pk2(v[j][0], v[j][1]); o.y = pk2(v[j][2], v[j][3]); o.z = pk2(v[j][4], v[j][5]); o.w = pk2(v[j][6], v[j][7]); xr[64 * j] = o; }
;             const float rs2 = rsqrtf(wave_sum(s2) * (1.f / DM) + EPS); if (c.lane == 0) RS[row] = rs2;
	v_pk_fma_f32 v[64:65], v[16:17], v[82:83], v[94:95]
	v_pk_mul_f32 v[82:83], v[50:51], v[50:51]
	v_add_f32_e32 v76, v80, v76
	v_pk_fma_f32 v[82:83], v[64:65], v[64:65], v[82:83]
	v_add_f32_e32 v76, v81, v76
	v_add_f32_e32 v76, v82, v76
	v_bfe_u32 v77, v49, 16, 1
	v_bfe_u32 v80, v48, 16, 1
	v_bfe_u32 v81, v47, 16, 1
	v_bfe_u32 v82, v46, 16, 1
	v_pk_mul_f32 v[52:53], v[110:111], v[52:53] op_sel_hi:[0,1]
	v_add3_u32 v46, v46, v82, s18
	v_add3_u32 v47, v47, v81, s18
	v_add3_u32 v48, v48, v80, s18
	v_add3_u32 v49, v49, v77, s18
	v_bfe_u32 v77, v78, 16, 1
	v_bfe_u32 v80, v79, 16, 1
	v_bfe_u32 v81, v62, 16, 1
	v_bfe_u32 v82, v63, 16, 1
	v_pk_mul_f32 v[84:85], v[110:111], v[84:85] op_sel_hi:[0,1]
	v_pk_fma_f32 v[52:53], v[18:19], v[52:53], v[68:69]
	v_add3_u32 v63, v63, v82, s18
	v_add3_u32 v62, v62, v81, s18
	v_add3_u32 v79, v79, v80, s18
	v_add3_u32 v77, v78, v77, s18
	v_lshlrev_b32_e32 v103, 16, v71
	v_lshlrev_b32_e32 v102, 16, v70
	v_and_b32_e32 v71, 0xffff0000, v71
	v_and_b32_e32 v70, 0xffff0000, v70
	v_pk_fma_f32 v[66:67], v[12:13], v[84:85], v[98:99]
	v_pk_mul_f32 v[54:55], v[110:111], v[54:55] op_sel_hi:[0,1]
	v_pk_mul_f32 v[84:85], v[52:53], v[52:53]
	v_lshrrev_b32_e32 v77, 16, v77
	v_lshrrev_b32_e32 v78, 16, v79
	v_lshrrev_b32_e32 v62, 16, v62
	v_lshrrev_b32_e32 v63, 16, v63
	v_pk_mul_f32 v[68:69], v[110:111], v[86:87] op_sel_hi:[0,1]
	v_pk_fma_f32 v[54:55], v[14:15], v[54:55], v[70:71]
	v_pk_fma_f32 v[84:85], v[66:67], v[66:67], v[84:85]
	v_add_f32_e32 v76, v83, v76
	v_and_or_b32 v49, v49, s16, v63
	v_and_or_b32 v48, v48, s16, v62
	v_and_or_b32 v47, v47, s16, v78
	v_and_or_b32 v46, v46, s16, v77
	v_lshlrev_b32_e32 v105, 16, v73
	v_lshlrev_b32_e32 v104, 16, v72
	v_and_b32_e32 v73, 0xffff0000, v73
	v_and_b32_e32 v72, 0xffff0000, v72
	v_pk_fma_f32 v[68:69], v[24:25], v[68:69], v[102:103]
	v_pk_mul_f32 v[56:57], v[110:111], v[56:57] op_sel_hi:[0,1]
	v_pk_mul_f32 v[86:87], v[54:55], v[54:55]
	v_add_f32_e32 v76, v84, v76
	global_store_dwordx4 v[38:39], v[46:49], off
	v_pk_mul_f32 v[70:71], v[110:111], v[88:89] op_sel_hi:[0,1]
	v_pk_fma_f32 v[56:57], v[26:27], v[56:57], v[72:73]
	v_bfe_u32 v46, v53, 16, 1
	v_bfe_u32 v47, v52, 16, 1
	v_bfe_u32 v48, v51, 16, 1
	v_bfe_u32 v49, v50, 16, 1
	v_pk_fma_f32 v[86:87], v[68:69], v[68:69], v[86:87]
	v_add_f32_e32 v76, v85, v76
	v_add3_u32 v50, v50, v49, s18
	v_add3_u32 v51, v51, v48, s18
	v_add3_u32 v47, v52, v47, s18
	v_add3_u32 v46, v53, v46, s18
	v_bfe_u32 v48, v64, 16, 1
	v_bfe_u32 v49, v65, 16, 1
	v_bfe_u32 v52, v66, 16, 1
	v_bfe_u32 v53, v67, 16, 1
	v_lshlrev_b32_e32 v107, 16, v75
	v_lshlrev_b32_e32 v106, 16, v74
	v_and_b32_e32 v75, 0xffff0000, v75
	v_and_b32_e32 v74, 0xffff0000, v74
	v_pk_fma_f32 v[70:71], v[20:21], v[70:71], v[104:105]
	v_pk_mul_f32 v[58:59], v[110:111], v[58:59] op_sel_hi:[0,1]
	v_pk_mul_f32 v[88:89], v[56:57], v[56:57]
	v_add_f32_e32 v76, v86, v76
	v_add3_u32 v53, v67, v53, s18
	v_add3_u32 v52, v66, v52, s18
	v_add3_u32 v49, v65, v49, s18
	v_add3_u32 v48, v64, v48, s18
	v_pk_mul_f32 v[72:73], v[110:111], v[90:91] op_sel_hi:[0,1]
	v_pk_fma_f32 v[58:59], v[22:23], v[58:59], v[74:75]
	v_pk_fma_f32 v[88:89], v[70:71], v[70:71], v[88:89]
	v_add_f32_e32 v76, v87, v76
	v_lshrrev_b32_e32 v62, 16, v48
	v_lshrrev_b32_e32 v63, 16, v49
	v_lshrrev_b32_e32 v48, 16, v52
	v_lshrrev_b32_e32 v49, 16, v53
	v_pk_fma_f32 v[72:73], v[32:33], v[72:73], v[106:107]
	v_pk_mul_f32 v[90:91], v[58:59], v[58:59]
	v_add_f32_e32 v76, v88, v76
	v_and_or_b32 v49, v46, s16, v49
	v_and_or_b32 v48, v47, s16, v48
	v_and_or_b32 v47, v51, s16, v63
	v_and_or_b32 v46, v50, s16, v62
	v_pk_mul_f32 v[74:75], v[110:111], v[92:93] op_sel_hi:[0,1]
	v_pk_fma_f32 v[90:91], v[72:73], v[72:73], v[90:91]
	v_add_f32_e32 v76, v89, v76
	global_store_dwordx4 v[38:39], v[46:49], off offset:1024
	v_pk_fma_f32 v[74:75], v[28:29], v[74:75], v[108:109]
	v_pk_mul_f32 v[92:93], v[60:61], v[60:61]
	v_bfe_u32 v48, v55, 16, 1
	v_bfe_u32 v49, v54, 16, 1
	v_add_f32_e32 v76, v90, v76
	v_add3_u32 v50, v54, v49, s18
	v_add3_u32 v51, v55, v48, s18
	v_bfe_u32 v48, v68, 16, 1
	v_bfe_u32 v49, v69, 16, 1
	v_bfe_u32 v52, v70, 16, 1
	v_bfe_u32 v53, v71, 16, 1
	v_pk_fma_f32 v[92:93], v[74:75], v[74:75], v[92:93]
	v_add_f32_e32 v76, v91, v76
	v_bfe_u32 v46, v57, 16, 1
	v_bfe_u32 v47, v56, 16, 1
	v_add3_u32 v53, v71, v53, s18
	v_add3_u32 v52, v70, v52, s18
	v_add3_u32 v49, v69, v49, s18
	v_add3_u32 v48, v68, v48, s18
	v_add_f32_e32 v76, v92, v76
	v_add3_u32 v47, v56, v47, s18
	v_add3_u32 v46, v57, v46, s18
	v_lshrrev_b32_e32 v54, 16, v48
	v_lshrrev_b32_e32 v55, 16, v49
	v_lshrrev_b32_e32 v48, 16, v52
	v_lshrrev_b32_e32 v49, 16, v53
	v_add_f32_e32 v76, v93, v76
	v_and_or_b32 v49, v46, s16, v49
	v_and_or_b32 v48, v47, s16, v48
	v_and_or_b32 v47, v51, s16, v55
	v_and_or_b32 v46, v50, s16, v54
	global_store_dwordx4 v[38:39], v[46:49], off offset:2048
	ds_bpermute_b32 v47, v3, v76
	v_bfe_u32 v50, v58, 16, 1
	v_add3_u32 v52, v58, v50, s18
	v_bfe_u32 v51, v72, 16, 1
	v_bfe_u32 v55, v75, 16, 1
	s_waitcnt lgkmcnt(0)
	v_add_f32_e32 v47, v76, v47
	ds_bpermute_b32 v50, v40, v47
	v_bfe_u32 v46, v61, 16, 1
	v_add3_u32 v55, v75, v55, s18
	v_add3_u32 v51, v72, v51, s18
	v_add3_u32 v46, v61, v46, s18
	s_waitcnt lgkmcnt(0)
	v_add_f32_e32 v47, v47, v50
	ds_bpermute_b32 v50, v41, v47
	v_lshrrev_b32_e32 v56, 16, v51
	v_lshrrev_b32_e32 v51, 16, v55
	v_and_or_b32 v51, v46, s16, v51
	s_nop 0
	s_waitcnt lgkmcnt(0)
	v_add_f32_e32 v47, v47, v50
	ds_bpermute_b32 v50, v42, v47
	v_bfe_u32 v54, v74, 16, 1
	v_bfe_u32 v48, v60, 16, 1
	s_nop 0
	v_add3_u32 v54, v74, v54, s18
	s_waitcnt lgkmcnt(0)
	v_add_f32_e32 v47, v47, v50
	ds_bpermute_b32 v50, v43, v47
	s_nop 1
	v_add3_u32 v48, v60, v48, s18
	s_nop 0
	s_waitcnt lgkmcnt(0)
	v_add_f32_e32 v46, v47, v50
	ds_bpermute_b32 v47, v44, v46
	v_lshrrev_b32_e32 v54, 16, v54
	v_and_or_b32 v50, v48, s16, v54
	v_cvt_pk_bf16_f32 v49, v73, v59
	v_and_or_b32 v48, v52, s16, v56
	global_store_dwordx4 v[38:39], v[48:51], off offset:3072
	s_and_saveexec_b64 s[12:13], s[0:1]
	s_cbranch_execz .LBB0_2483
	s_waitcnt lgkmcnt(0)
	v_add_f32_e32 v38, v46, v47
	v_fmamk_f32 v38, v38, 0x3a000000, v45
	v_mul_f32_e32 v39, 0x4b800000, v38
	v_cmp_gt_f32_e32 vcc, s17, v38
	v_readlane_b32 s20, v253, 0
	v_readlane_b32 s21, v253, 1
	v_cndmask_b32_e32 v38, v38, v39, vcc
	v_rsq_f32_e32 v38, v38
	s_add_u32 s20, s20, s14
	s_addc_u32 s21, s21, s15
	v_mul_f32_e32 v39, 0x45800000, v38
	v_cndmask_b32_e32 v38, v38, v39, vcc
	global_store_dword v251, v38, s[20:21]
	s_branch .LBB0_2483

; #define LAS __attribute__((address_space(3)))
; #define LDS_WAIT() asm volatile("s_waitcnt lgkmcnt(0)" ::: "memory")
;     ...
;         const int kb = it / nblk, nb = it % nblk, k0 = 64 * kb, n0 = 64 * nb, nq = (lane & 15) * 4, kr = lane >> 4; const bool ok = (n0 + nq) < N;
;         f32x4 v[16];
; #pragma unroll
;         for (int i = 0; i < 16; ++i) v[i] = ok ? __builtin_nontemporal_load((const f32x4*)(W + (size_t)(k0 + 4 * i + kr) * N + n0 + nq)) : (f32x4){0.f, 0.f, 0.f, 0.f};
;         if (gain) {
; #pragma unroll
;             for (int i = 0; i < 16; ++i) v[i] *= gain[k0 + 4 * i + kr]; }
; #pragma unroll
;         for (int i = 0; i < 16; ++i) { LAS float* d = scr + (4 * i + kr) * 65 + nq; d[0] = v[i].x; d[1] = v[i].y; d[2] = v[i].z; d[3] = v[i].w; }
;         LDS_WAIT(); asm volatile("" ::: "memory");
;         const int c8 = lane & 7; int d0 = n0;
;         if (ffnmap) { const int bj = n0 >= FFH ? 1 : 0, chn = n0 - FFH * bj; d0 = 256 * (chn >> 7) + 128 * bj + (chn & 127); }
; #pragma unroll
;         for (int j = 0; j < 8; ++j) { const int n = (lane >> 3) + 8 * j; const LAS float* sp = scr + (8 * c8) * 65 + n;
.LBB0_2650:
	s_or_b64 exec, exec, s[10:11]
	v_lshl_add_u64 v[82:83], v[72:73], 2, s[0:1]
	global_load_dword v72, v[82:83], off
	s_add_i32 s19, s19, s14
	s_ashr_i32 s9, s8, 31
	s_add_i32 s18, s18, s13
	s_add_i32 s14, s14, s15
	s_cmpk_lt_i32 s18, 0x1000
	s_waitcnt vmcnt(0)
	v_pk_mul_f32 v[86:87], v[8:9], v[72:73] op_sel_hi:[1,0]
	global_load_dword v8, v[82:83], off offset:16
	v_pk_mul_f32 v[84:85], v[10:11], v[72:73] op_sel_hi:[1,0]
	s_waitcnt vmcnt(0)
	v_pk_mul_f32 v[72:73], v[14:15], v[8:9] op_sel_hi:[1,0]
	v_pk_mul_f32 v[88:89], v[12:13], v[8:9] op_sel_hi:[1,0]
	global_load_dword v8, v[82:83], off offset:32
	global_load_dword v12, v[82:83], off offset:160
	s_waitcnt vmcnt(1)
	v_pk_mul_f32 v[90:91], v[4:5], v[8:9] op_sel_hi:[1,0]
	global_load_dword v4, v[82:83], off offset:48
	v_pk_mul_f32 v[74:75], v[6:7], v[8:9] op_sel_hi:[1,0]
	global_load_dword v6, v[82:83], off offset:128
	global_load_dword v8, v[82:83], off offset:144
	s_waitcnt vmcnt(3)
	v_pk_mul_f32 v[10:11], v[42:43], v[12:13] op_sel_hi:[1,0]
	v_pk_mul_f32 v[12:13], v[40:41], v[12:13] op_sel_hi:[1,0]
	v_add_u32_e32 v40, 0x410, v81
	s_waitcnt vmcnt(2)
	v_pk_mul_f32 v[92:93], v[22:23], v[4:5] op_sel_hi:[1,0]
	v_pk_mul_f32 v[94:95], v[20:21], v[4:5] op_sel_hi:[1,0]
	global_load_dword v4, v[82:83], off offset:64
	global_load_dword v20, v[82:83], off offset:192
	s_waitcnt vmcnt(1)
	v_pk_mul_f32 v[96:97], v[18:19], v[4:5] op_sel_hi:[1,0]
	v_pk_mul_f32 v[98:99], v[16:17], v[4:5] op_sel_hi:[1,0]
	global_load_dword v4, v[82:83], off offset:80
	global_load_dword v16, v[82:83], off offset:176
	s_waitcnt vmcnt(2)
	v_pk_mul_f32 v[18:19], v[50:51], v[20:21] op_sel_hi:[1,0]
	v_pk_mul_f32 v[20:21], v[48:49], v[20:21] op_sel_hi:[1,0]
	s_waitcnt vmcnt(1)
	v_pk_mul_f32 v[100:101], v[30:31], v[4:5] op_sel_hi:[1,0]
	v_pk_mul_f32 v[102:103], v[28:29], v[4:5] op_sel_hi:[1,0]
	global_load_dword v4, v[82:83], off offset:96
	global_load_dword v28, v[82:83], off offset:224
	v_lshl_add_u64 v[30:31], v[76:77], 2, s[0:1]
	s_waitcnt vmcnt(2)
	v_pk_mul_f32 v[14:15], v[54:55], v[16:17] op_sel_hi:[1,0]
	v_pk_mul_f32 v[16:17], v[52:53], v[16:17] op_sel_hi:[1,0]
	s_waitcnt vmcnt(1)
	v_pk_mul_f32 v[104:105], v[26:27], v[4:5] op_sel_hi:[1,0]
	v_pk_mul_f32 v[106:107], v[24:25], v[4:5] op_sel_hi:[1,0]
	global_load_dword v4, v[82:83], off offset:112
	global_load_dword v24, v[82:83], off offset:208
	s_waitcnt vmcnt(2)
	v_pk_mul_f32 v[26:27], v[58:59], v[28:29] op_sel_hi:[1,0]
	v_pk_mul_f32 v[28:29], v[56:57], v[28:29] op_sel_hi:[1,0]
	s_waitcnt vmcnt(1)
	v_pk_mul_f32 v[38:39], v[38:39], v[4:5] op_sel_hi:[1,0]
	v_pk_mul_f32 v[36:37], v[36:37], v[4:5] op_sel_hi:[1,0]
	v_pk_mul_f32 v[4:5], v[34:35], v[6:7] op_sel_hi:[1,0]
	v_pk_mul_f32 v[34:35], v[32:33], v[6:7] op_sel_hi:[1,0]
	global_load_dword v32, v[30:31], off
	ds_write2_b32 v81, v86, v87 offset1:1
	ds_write2_b32 v81, v84, v85 offset0:2 offset1:3
	ds_write2_b32 v40, v88, v89 offset1:1
	v_add_u32_e32 v40, 0x418, v81
	ds_write2_b32 v40, v72, v73 offset1:1
	v_add_u32_e32 v40, 0x820, v81
	ds_write2_b32 v40, v90, v91 offset1:1
	v_add_u32_e32 v40, 0x828, v81
	ds_write2_b32 v40, v74, v75 offset1:1
	v_add_u32_e32 v40, 0xc30, v81
	ds_write2_b32 v40, v94, v95 offset1:1
	v_add_u32_e32 v40, 0xc38, v81
	ds_write2_b32 v40, v92, v93 offset1:1
	v_add_u32_e32 v40, 0x1040, v81
	ds_write2_b32 v40, v98, v99 offset1:1
	v_add_u32_e32 v40, 0x1048, v81
	ds_write2_b32 v40, v96, v97 offset1:1
	v_add_u32_e32 v40, 0x1450, v81
	ds_write2_b32 v40, v102, v103 offset1:1
	v_add_u32_e32 v40, 0x1458, v81
	ds_write2_b32 v40, v100, v101 offset1:1
	v_add_u32_e32 v40, 0x1860, v81
	ds_write2_b32 v40, v106, v107 offset1:1
	v_add_u32_e32 v40, 0x1868, v81
	ds_write2_b32 v40, v104, v105 offset1:1
	v_add_u32_e32 v40, 0x1c70, v81
	ds_write2_b32 v40, v36, v37 offset1:1
	v_add_u32_e32 v36, 0x1c78, v81
	ds_write2_b32 v36, v38, v39 offset1:1
	v_add_u32_e32 v36, 0x2080, v81
	ds_write2_b32 v36, v34, v35 offset1:1
	v_add_u32_e32 v34, 0x2088, v81
	v_pk_mul_f32 v[6:7], v[46:47], v[8:9] op_sel_hi:[1,0]
	v_pk_mul_f32 v[8:9], v[44:45], v[8:9] op_sel_hi:[1,0]
	ds_write2_b32 v34, v4, v5 offset1:1
	v_add_u32_e32 v4, 0x2490, v81
	ds_write2_b32 v4, v8, v9 offset1:1
	v_add_u32_e32 v4, 0x2498, v81
	ds_write2_b32 v4, v6, v7 offset1:1
	v_add_u32_e32 v4, 0x28a0, v81
	ds_write2_b32 v4, v12, v13 offset1:1
	v_add_u32_e32 v4, 0x28a8, v81
	ds_write2_b32 v4, v10, v11 offset1:1
	v_add_u32_e32 v4, 0x2cb0, v81
	ds_write2_b32 v4, v16, v17 offset1:1
	v_add_u32_e32 v4, 0x2cb8, v81
	ds_write2_b32 v4, v14, v15 offset1:1
	v_add_u32_e32 v4, 0x30c0, v81
	ds_write2_b32 v4, v20, v21 offset1:1
	v_add_u32_e32 v4, 0x30c8, v81
	s_waitcnt vmcnt(1)
	v_pk_mul_f32 v[22:23], v[62:63], v[24:25] op_sel_hi:[1,0]
	v_pk_mul_f32 v[24:25], v[60:61], v[24:25] op_sel_hi:[1,0]
	ds_write2_b32 v4, v18, v19 offset1:1
	v_add_u32_e32 v4, 0x34d0, v81
	ds_write2_b32 v4, v24, v25 offset1:1
	v_add_u32_e32 v4, 0x34d8, v81
	ds_write2_b32 v4, v22, v23 offset1:1
	v_add_u32_e32 v4, 0x38e0, v81
	ds_write2_b32 v4, v28, v29 offset1:1
	v_add_u32_e32 v4, 0x38e8, v81
	ds_write2_b32 v4, v26, v27 offset1:1
	v_add_u32_e32 v4, 0x3cf0, v81
	s_waitcnt vmcnt(0)
	v_pk_mul_f32 v[30:31], v[66:67], v[32:33] op_sel_hi:[1,0]
	v_pk_mul_f32 v[32:33], v[64:65], v[32:33] op_sel_hi:[1,0]
	ds_write2_b32 v4, v32, v33 offset1:1
	v_add_u32_e32 v4, 0x3cf8, v81
	ds_write2_b32 v4, v30, v31 offset1:1
	s_waitcnt lgkmcnt(0)
	ds_read2_b32 v[8:9], v80 offset0:65 offset1:73
	ds_read2_b32 v[14:15], v80 offset1:8
	ds_read2_b32 v[16:17], v80 offset0:130 offset1:138
	ds_read2_b32 v[18:19], v80 offset0:195 offset1:203
	v_lshl_add_u64 v[4:5], s[8:9], 1, v[70:71]
	s_waitcnt lgkmcnt(3)
	v_bfe_u32 v7, v8, 16, 1
	s_waitcnt lgkmcnt(2)
; #define LAS __attribute__((address_space(3)))
; #define LDS_WAIT() asm volatile("s_waitcnt lgkmcnt(0)" ::: "memory")
; __device__ __forceinline__ unsigned pk2(float lo, float hi) { return f2bf(lo) | (f2bf(hi) << 16); }
;     ...
;         for (int i = 0; i < 16; ++i) { LAS float* d = scr + (4 * i + kr) * 65 + nq; d[0] = v[i].x; d[1] = v[i].y; d[2] = v[i].z; d[3] = v[i].w; }
;         LDS_WAIT(); asm volatile("" ::: "memory");
;         const int c8 = lane & 7; int d0 = n0;
;         if (ffnmap) { const int bj = n0 >= FFH ? 1 : 0, chn = n0 - FFH * bj; d0 = 256 * (chn >> 7) + 128 * bj + (chn & 127); }
; #pragma unroll
;         for (int j = 0; j < 8; ++j) { const int n = (lane >> 3) + 8 * j; const LAS float* sp = scr + (8 * c8) * 65 + n;
;             v4u o; o.x = pk2(sp[0 * 65], sp[1 * 65]); o.y = pk2(sp[2 * 65], sp[3 * 65]); o.z = pk2(sp[4 * 65], sp[5 * 65]); o.w = pk2(sp[6 * 65], sp[7 * 65]);
;             *(v4u*)(WT + (size_t)(d0 + n) * K + k0 + 8 * c8) = o; }
;         LDS_WAIT(); asm volatile("" ::: "memory");
	v_bfe_u32 v6, v14, 16, 1
	v_add3_u32 v6, v14, v6, s16
	v_add3_u32 v7, v8, v7, s16
	v_add_u32_e32 v8, 0x400, v80
	v_lshrrev_b32_e32 v6, 16, v6
	ds_read2_b32 v[20:21], v8 offset0:4 offset1:12
	ds_read2_b32 v[22:23], v8 offset0:69 offset1:77
	v_and_or_b32 v10, v7, s17, v6
	s_waitcnt lgkmcnt(3)
	s_nop 1
	s_waitcnt lgkmcnt(2)
	s_nop 2
	ds_read2_b32 v[24:25], v8 offset0:134 offset1:142
	ds_read2_b32 v[26:27], v8 offset0:199 offset1:207
	v_cvt_pk_bf16_f32 v11, v16, v18
	s_waitcnt lgkmcnt(3)
	s_nop 1
	s_waitcnt lgkmcnt(2)
	s_nop 2
	v_cvt_pk_bf16_f32 v12, v20, v22
	s_waitcnt lgkmcnt(1)
	s_nop 1
	s_waitcnt lgkmcnt(0)
	s_nop 2
	v_cvt_pk_bf16_f32 v13, v24, v26
	v_add_u32_e32 v6, s19, v79
	v_ashrrev_i32_e32 v7, 31, v6
	v_lshlrev_b64 v[28:29], 12, v[6:7]
	v_lshl_add_u64 v[28:29], v[4:5], 0, v[28:29]
	v_bfe_u32 v7, v15, 16, 1
	global_store_dwordx4 v[28:29], v[10:13], off
	v_add3_u32 v7, v15, v7, s16
	v_lshrrev_b32_e32 v7, 16, v7
	v_bfe_u32 v10, v9, 16, 1
	v_add3_u32 v9, v9, v10, s16
	v_and_or_b32 v10, v9, s17, v7
	s_nop 4
	v_cvt_pk_bf16_f32 v11, v17, v19
	s_nop 4
	v_cvt_pk_bf16_f32 v12, v21, v23
	s_nop 0
	v_add_u32_e32 v14, 8, v6
	s_nop 1
	v_ashrrev_i32_e32 v15, 31, v14
	s_nop 1
	v_lshlrev_b64 v[14:15], 12, v[14:15]
	v_cvt_pk_bf16_f32 v13, v25, v27
	v_lshl_add_u64 v[14:15], v[4:5], 0, v[14:15]
	global_store_dwordx4 v[14:15], v[10:13], off
	ds_read2_b32 v[14:15], v80 offset0:81 offset1:89
	ds_read2_b32 v[16:17], v80 offset0:16 offset1:24
	ds_read2_b32 v[18:19], v80 offset0:146 offset1:154
	ds_read2_b32 v[20:21], v80 offset0:211 offset1:219
	ds_read2_b32 v[22:23], v8 offset0:20 offset1:28
	ds_read2_b32 v[24:25], v8 offset0:85 offset1:93
	ds_read2_b32 v[26:27], v8 offset0:150 offset1:158
	ds_read2_b32 v[28:29], v8 offset0:215 offset1:223
	s_waitcnt lgkmcnt(7)
	s_nop 0
	s_waitcnt lgkmcnt(6)
	s_nop 3
	v_cvt_pk_bf16_f32 v10, v16, v14
	s_waitcnt lgkmcnt(5)
	s_nop 1
	s_waitcnt lgkmcnt(4)
	s_nop 2
	v_cvt_pk_bf16_f32 v11, v18, v20
	s_waitcnt lgkmcnt(3)
	s_nop 1
	s_waitcnt lgkmcnt(2)
	s_nop 2
	v_cvt_pk_bf16_f32 v12, v22, v24
	s_waitcnt lgkmcnt(1)
	s_nop 1
	s_waitcnt lgkmcnt(0)
	s_nop 2
	v_add_u32_e32 v30, 16, v6
	v_cvt_pk_bf16_f32 v13, v26, v28
	v_ashrrev_i32_e32 v31, 31, v30
	v_bfe_u32 v7, v17, 16, 1
	v_lshlrev_b64 v[30:31], 12, v[30:31]
	v_add3_u32 v7, v17, v7, s16
	v_bfe_u32 v9, v15, 16, 1
	v_lshl_add_u64 v[30:31], v[4:5], 0, v[30:31]
	v_lshrrev_b32_e32 v7, 16, v7
	v_add3_u32 v9, v15, v9, s16
	global_store_dwordx4 v[30:31], v[10:13], off
	v_add_u32_e32 v14, 24, v6
	v_ashrrev_i32_e32 v15, 31, v14
	v_and_or_b32 v10, v9, s17, v7
	s_nop 4
	v_cvt_pk_bf16_f32 v11, v19, v21
	s_nop 4
	v_cvt_pk_bf16_f32 v12, v23, v25
	s_nop 4
	v_lshlrev_b64 v[14:15], 12, v[14:15]
	v_cvt_pk_bf16_f32 v13, v27, v29
	v_lshl_add_u64 v[14:15], v[4:5], 0, v[14:15]
	global_store_dwordx4 v[14:15], v[10:13], off
	ds_read2_b32 v[14:15], v80 offset0:97 offset1:105
	ds_read2_b32 v[16:17], v80 offset0:32 offset1:40
	ds_read2_b32 v[18:19], v80 offset0:162 offset1:170
	ds_read2_b32 v[20:21], v80 offset0:227 offset1:235
	ds_read2_b32 v[22:23], v8 offset0:36 offset1:44
	ds_read2_b32 v[24:25], v8 offset0:101 offset1:109
	ds_read2_b32 v[26:27], v8 offset0:166 offset1:174
	ds_read2_b32 v[28:29], v8 offset0:231 offset1:239
	s_waitcnt lgkmcnt(7)
	s_nop 0
	s_waitcnt lgkmcnt(6)
	s_nop 3
	v_cvt_pk_bf16_f32 v10, v16, v14
	s_waitcnt lgkmcnt(5)
	s_nop 1
	s_waitcnt lgkmcnt(4)
	s_nop 2
	v_cvt_pk_bf16_f32 v11, v18, v20
	s_waitcnt lgkmcnt(3)
	s_nop 1
	s_waitcnt lgkmcnt(2)
	s_nop 2
	v_cvt_pk_bf16_f32 v12, v22, v24
	s_waitcnt lgkmcnt(1)
	s_nop 1
	s_waitcnt lgkmcnt(0)
	s_nop 2
	v_add_u32_e32 v30, 32, v6
	v_cvt_pk_bf16_f32 v13, v26, v28
	v_ashrrev_i32_e32 v31, 31, v30
	v_bfe_u32 v7, v17, 16, 1
	v_lshlrev_b64 v[30:31], 12, v[30:31]
	v_add3_u32 v7, v17, v7, s16
	v_bfe_u32 v9, v15, 16, 1
	v_lshl_add_u64 v[30:31], v[4:5], 0, v[30:31]
	v_lshrrev_b32_e32 v7, 16, v7
	v_add3_u32 v9, v15, v9, s16
	global_store_dwordx4 v[30:31], v[10:13], off
	v_add_u32_e32 v14, 40, v6
	v_ashrrev_i32_e32 v15, 31, v14
	v_and_or_b32 v10, v9, s17, v7
	s_nop 4
	v_cvt_pk_bf16_f32 v11, v19, v21
	s_nop 4
	v_cvt_pk_bf16_f32 v12, v23, v25
	s_nop 4
	v_lshlrev_b64 v[14:15], 12, v[14:15]
	v_cvt_pk_bf16_f32 v13, v27, v29
	v_lshl_add_u64 v[14:15], v[4:5], 0, v[14:15]
	global_store_dwordx4 v[14:15], v[10:13], off
	ds_read2_b32 v[14:15], v80 offset0:48 offset1:56
	ds_read2_b32 v[16:17], v80 offset0:113 offset1:121
	ds_read2_b32 v[18:19], v80 offset0:178 offset1:186
	ds_read2_b32 v[20:21], v80 offset0:243 offset1:251
	ds_read2_b32 v[22:23], v8 offset0:52 offset1:60
	ds_read2_b32 v[24:25], v8 offset0:117 offset1:125
	ds_read2_b32 v[26:27], v8 offset0:182 offset1:190
	ds_read2_b32 v[28:29], v8 offset0:247 offset1:255
	s_waitcnt lgkmcnt(7)
	s_nop 1
	s_waitcnt lgkmcnt(6)
	s_nop 2
	v_cvt_pk_bf16_f32 v10, v14, v16
	s_waitcnt lgkmcnt(5)
	s_nop 1
	s_waitcnt lgkmcnt(4)
	s_nop 2
	v_cvt_pk_bf16_f32 v11, v18, v20
	s_waitcnt lgkmcnt(3)
	s_nop 1
	s_waitcnt lgkmcnt(2)
	s_nop 2
	v_cvt_pk_bf16_f32 v12, v22, v24
	s_waitcnt lgkmcnt(1)
	s_nop 1
	s_waitcnt lgkmcnt(0)
	s_nop 2
	v_cvt_pk_bf16_f32 v13, v26, v28
	v_add_u32_e32 v8, 48, v6
	v_ashrrev_i32_e32 v9, 31, v8
	v_lshlrev_b64 v[8:9], 12, v[8:9]
	v_lshl_add_u64 v[8:9], v[4:5], 0, v[8:9]
	v_bfe_u32 v7, v15, 16, 1
	global_store_dwordx4 v[8:9], v[10:13], off
	v_add3_u32 v7, v15, v7, s16
	v_bfe_u32 v8, v17, 16, 1
	v_lshrrev_b32_e32 v7, 16, v7
	v_add3_u32 v8, v17, v8, s16
	v_and_or_b32 v8, v8, s17, v7
	s_nop 4
	v_cvt_pk_bf16_f32 v9, v19, v21
	s_nop 4
	v_cvt_pk_bf16_f32 v10, v23, v25
	s_nop 4
	v_add_u32_e32 v6, 56, v6
	v_cvt_pk_bf16_f32 v11, v27, v29
	v_ashrrev_i32_e32 v7, 31, v6
	v_lshlrev_b64 v[6:7], 12, v[6:7]
	v_lshl_add_u64 v[4:5], v[4:5], 0, v[6:7]
	global_store_dwordx4 v[4:5], v[8:11], off
	s_waitcnt lgkmcnt(0)
	s_cbranch_scc0 .LBB0_2683

; #define LAS __attribute__((address_space(3)))
; #define LDS_WAIT() asm volatile("s_waitcnt lgkmcnt(0)" ::: "memory")
; __device__ __forceinline__ unsigned pk2(float lo, float hi) { return f2bf(lo) | (f2bf(hi) << 16); }
;     ...
;         for (int i = 0; i < 16; ++i) { LAS float* d = scr + (4 * i + kr) * 65 + nq; d[0] = v[i].x; d[1] = v[i].y; d[2] = v[i].z; d[3] = v[i].w; }
;         LDS_WAIT(); asm volatile("" ::: "memory");
;         const int c8 = lane & 7; int d0 = n0;
;         if (ffnmap) { const int bj = n0 >= FFH ? 1 : 0, chn = n0 - FFH * bj; d0 = 256 * (chn >> 7) + 128 * bj + (chn & 127); }
; #pragma unroll
;         for (int j = 0; j < 8; ++j) { const int n = (lane >> 3) + 8 * j; const LAS float* sp = scr + (8 * c8) * 65 + n;
;             v4u o; o.x = pk2(sp[0 * 65], sp[1 * 65]); o.y = pk2(sp[2 * 65], sp[3 * 65]); o.z = pk2(sp[4 * 65], sp[5 * 65]); o.w = pk2(sp[6 * 65], sp[7 * 65]);
;             *(v4u*)(WT + (size_t)(d0 + n) * K + k0 + 8 * c8) = o; }
;         LDS_WAIT(); asm volatile("" ::: "memory");
.LBB0_2685:
	s_or_b64 exec, exec, s[8:9]
	s_waitcnt vmcnt(0)
	ds_write2_b32 v79, v4, v5 offset1:1
	ds_write2_b32 v79, v6, v7 offset0:2 offset1:3
	v_add_u32_e32 v4, 0x410, v79
	ds_write2_b32 v4, v12, v13 offset1:1
	v_add_u32_e32 v4, 0x418, v79
	ds_write2_b32 v4, v14, v15 offset1:1
	v_add_u32_e32 v4, 0x820, v79
	ds_write2_b32 v4, v8, v9 offset1:1
	v_add_u32_e32 v4, 0x828, v79
	ds_write2_b32 v4, v10, v11 offset1:1
	v_add_u32_e32 v4, 0xc30, v79
	ds_write2_b32 v4, v20, v21 offset1:1
	v_add_u32_e32 v4, 0xc38, v79
	ds_write2_b32 v4, v22, v23 offset1:1
	v_add_u32_e32 v4, 0x1040, v79
	ds_write2_b32 v4, v16, v17 offset1:1
	v_add_u32_e32 v4, 0x1048, v79
	ds_write2_b32 v4, v18, v19 offset1:1
	v_add_u32_e32 v4, 0x1450, v79
	ds_write2_b32 v4, v28, v29 offset1:1
	v_add_u32_e32 v4, 0x1458, v79
	ds_write2_b32 v4, v30, v31 offset1:1
	v_add_u32_e32 v4, 0x1860, v79
	ds_write2_b32 v4, v24, v25 offset1:1
	v_add_u32_e32 v4, 0x1868, v79
	ds_write2_b32 v4, v26, v27 offset1:1
	v_add_u32_e32 v4, 0x1c70, v79
	ds_write2_b32 v4, v36, v37 offset1:1
	v_add_u32_e32 v4, 0x1c78, v79
	ds_write2_b32 v4, v38, v39 offset1:1
	v_add_u32_e32 v4, 0x2080, v79
	ds_write2_b32 v4, v32, v33 offset1:1
	v_add_u32_e32 v4, 0x2088, v79
	ds_write2_b32 v4, v34, v35 offset1:1
	v_add_u32_e32 v4, 0x2490, v79
	ds_write2_b32 v4, v44, v45 offset1:1
	v_add_u32_e32 v4, 0x2498, v79
	ds_write2_b32 v4, v46, v47 offset1:1
	v_add_u32_e32 v4, 0x28a0, v79
	ds_write2_b32 v4, v40, v41 offset1:1
	v_add_u32_e32 v4, 0x28a8, v79
	ds_write2_b32 v4, v42, v43 offset1:1
	v_add_u32_e32 v4, 0x2cb0, v79
	ds_write2_b32 v4, v52, v53 offset1:1
	v_add_u32_e32 v4, 0x2cb8, v79
	ds_write2_b32 v4, v54, v55 offset1:1
	v_add_u32_e32 v4, 0x30c0, v79
	ds_write2_b32 v4, v48, v49 offset1:1
	v_add_u32_e32 v4, 0x30c8, v79
	ds_write2_b32 v4, v50, v51 offset1:1
	v_add_u32_e32 v4, 0x34d0, v79
	ds_write2_b32 v4, v60, v61 offset1:1
	v_add_u32_e32 v4, 0x34d8, v79
	ds_write2_b32 v4, v62, v63 offset1:1
	v_add_u32_e32 v4, 0x38e0, v79
	ds_write2_b32 v4, v56, v57 offset1:1
	v_add_u32_e32 v4, 0x38e8, v79
	ds_write2_b32 v4, v58, v59 offset1:1
	v_add_u32_e32 v4, 0x3cf0, v79
	ds_write2_b32 v4, v64, v65 offset1:1
	v_add_u32_e32 v4, 0x3cf8, v79
	ds_write2_b32 v4, v66, v67 offset1:1
	s_waitcnt lgkmcnt(0)
	ds_read2_b32 v[12:13], v78 offset1:8
	ds_read2_b32 v[14:15], v78 offset0:65 offset1:73
	ds_read2_b32 v[16:17], v78 offset0:130 offset1:138
	ds_read2_b32 v[18:19], v78 offset0:195 offset1:203
	v_add_u32_e32 v30, 0x400, v78
	s_waitcnt lgkmcnt(3)
	s_nop 1
	s_waitcnt lgkmcnt(2)
	s_nop 0
	ds_read2_b32 v[20:21], v30 offset0:4 offset1:12
	s_nop 1
	ds_read2_b32 v[22:23], v30 offset0:69 offset1:77
	v_cvt_pk_bf16_f32 v8, v12, v14
	s_waitcnt lgkmcnt(3)
	s_nop 1
	s_waitcnt lgkmcnt(2)
	s_nop 0
	ds_read2_b32 v[24:25], v30 offset0:134 offset1:142
	s_nop 1
	ds_read2_b32 v[26:27], v30 offset0:199 offset1:207
	v_cvt_pk_bf16_f32 v9, v16, v18
	s_waitcnt lgkmcnt(3)
	s_nop 1
	s_waitcnt lgkmcnt(2)
	s_nop 2
	v_cvt_pk_bf16_f32 v10, v20, v22
	s_waitcnt lgkmcnt(1)
	s_nop 1
	s_waitcnt lgkmcnt(0)
	s_nop 2
	s_add_i32 s16, s16, s10
	v_cvt_pk_bf16_f32 v11, v24, v26
	v_add_u32_e32 v6, s16, v77
	s_ashr_i32 s1, s0, 31
	v_ashrrev_i32_e32 v7, 31, v6
	v_lshl_add_u64 v[4:5], s[0:1], 1, v[70:71]
	v_lshlrev_b64 v[28:29], 13, v[6:7]
	v_lshl_add_u64 v[28:29], v[4:5], 0, v[28:29]
	v_bfe_u32 v7, v13, 16, 1
	global_store_dwordx4 v[28:29], v[8:11], off
	v_add3_u32 v7, v13, v7, s14
	v_lshrrev_b32_e32 v7, 16, v7
	v_bfe_u32 v8, v15, 16, 1
	v_add3_u32 v8, v15, v8, s14
	v_and_or_b32 v8, v8, s15, v7
	s_nop 4
	v_cvt_pk_bf16_f32 v9, v17, v19
	s_nop 4
	v_cvt_pk_bf16_f32 v10, v21, v23
	s_nop 0
	v_add_u32_e32 v12, 8, v6
	s_nop 1
	v_ashrrev_i32_e32 v13, 31, v12
	s_nop 1
	v_lshlrev_b64 v[12:13], 13, v[12:13]
	v_cvt_pk_bf16_f32 v11, v25, v27
	ds_read2_b32 v[14:15], v78 offset0:16 offset1:24
	v_lshl_add_u64 v[12:13], v[4:5], 0, v[12:13]
	global_store_dwordx4 v[12:13], v[8:11], off
	ds_read2_b32 v[12:13], v78 offset0:81 offset1:89
	ds_read2_b32 v[16:17], v78 offset0:146 offset1:154
	ds_read2_b32 v[18:19], v78 offset0:211 offset1:219
	s_waitcnt lgkmcnt(3)
	s_nop 1
	s_waitcnt lgkmcnt(2)
	s_nop 0
	ds_read2_b32 v[20:21], v30 offset0:20 offset1:28
	s_nop 1
	ds_read2_b32 v[22:23], v30 offset0:85 offset1:93
	v_cvt_pk_bf16_f32 v8, v14, v12
	s_waitcnt lgkmcnt(3)
; #define LAS __attribute__((address_space(3)))
; #define LDS_WAIT() asm volatile("s_waitcnt lgkmcnt(0)" ::: "memory")
; __device__ __forceinline__ unsigned pk2(float lo, float hi) { return f2bf(lo) | (f2bf(hi) << 16); }
;     ...
;         for (int j = 0; j < 8; ++j) { const int n = (lane >> 3) + 8 * j; const LAS float* sp = scr + (8 * c8) * 65 + n;
;             v4u o; o.x = pk2(sp[0 * 65], sp[1 * 65]); o.y = pk2(sp[2 * 65], sp[3 * 65]); o.z = pk2(sp[4 * 65], sp[5 * 65]); o.w = pk2(sp[6 * 65], sp[7 * 65]);
;             *(v4u*)(WT + (size_t)(d0 + n) * K + k0 + 8 * c8) = o; }
;         LDS_WAIT(); asm volatile("" ::: "memory");
	s_nop 1
	s_waitcnt lgkmcnt(2)
	s_nop 0
	ds_read2_b32 v[24:25], v30 offset0:150 offset1:158
	s_nop 1
	ds_read2_b32 v[26:27], v30 offset0:215 offset1:223
	v_cvt_pk_bf16_f32 v9, v16, v18
	s_waitcnt lgkmcnt(3)
	s_nop 1
	s_waitcnt lgkmcnt(2)
	s_nop 2
	v_cvt_pk_bf16_f32 v10, v20, v22
	s_waitcnt lgkmcnt(1)
	s_nop 0
	v_add_u32_e32 v28, 16, v6
	s_nop 0
	s_waitcnt lgkmcnt(0)
	s_nop 0
	v_ashrrev_i32_e32 v29, 31, v28
	s_nop 1
	v_lshlrev_b64 v[28:29], 13, v[28:29]
	v_cvt_pk_bf16_f32 v11, v24, v26
	v_lshl_add_u64 v[28:29], v[4:5], 0, v[28:29]
	v_bfe_u32 v7, v15, 16, 1
	global_store_dwordx4 v[28:29], v[8:11], off
	v_add3_u32 v7, v15, v7, s14
	v_lshrrev_b32_e32 v7, 16, v7
	v_bfe_u32 v8, v13, 16, 1
	v_add3_u32 v8, v13, v8, s14
	v_and_or_b32 v8, v8, s15, v7
	s_nop 4
	v_cvt_pk_bf16_f32 v9, v17, v19
	s_nop 4
	v_cvt_pk_bf16_f32 v10, v21, v23
	s_nop 0
	v_add_u32_e32 v12, 24, v6
	s_nop 1
	v_ashrrev_i32_e32 v13, 31, v12
	s_nop 1
	v_lshlrev_b64 v[12:13], 13, v[12:13]
	v_cvt_pk_bf16_f32 v11, v25, v27
	ds_read2_b32 v[14:15], v78 offset0:32 offset1:40
	v_lshl_add_u64 v[12:13], v[4:5], 0, v[12:13]
	global_store_dwordx4 v[12:13], v[8:11], off
	ds_read2_b32 v[12:13], v78 offset0:97 offset1:105
	ds_read2_b32 v[16:17], v78 offset0:162 offset1:170
	ds_read2_b32 v[18:19], v78 offset0:227 offset1:235
	s_waitcnt lgkmcnt(3)
	s_nop 1
	s_waitcnt lgkmcnt(2)
	s_nop 0
	ds_read2_b32 v[20:21], v30 offset0:36 offset1:44
	s_nop 1
	ds_read2_b32 v[22:23], v30 offset0:101 offset1:109
	v_cvt_pk_bf16_f32 v8, v14, v12
	s_waitcnt lgkmcnt(3)
	s_nop 1
	s_waitcnt lgkmcnt(2)
	s_nop 0
	ds_read2_b32 v[24:25], v30 offset0:166 offset1:174
	s_nop 1
	ds_read2_b32 v[26:27], v30 offset0:231 offset1:239
	v_cvt_pk_bf16_f32 v9, v16, v18
	s_waitcnt lgkmcnt(3)
	s_nop 1
	s_waitcnt lgkmcnt(2)
	s_nop 2
	v_cvt_pk_bf16_f32 v10, v20, v22
	s_waitcnt lgkmcnt(1)
	s_nop 0
	v_add_u32_e32 v28, 32, v6
	s_nop 0
	s_waitcnt lgkmcnt(0)
	s_nop 0
	v_ashrrev_i32_e32 v29, 31, v28
	s_nop 1
	v_lshlrev_b64 v[28:29], 13, v[28:29]
	v_cvt_pk_bf16_f32 v11, v24, v26
	v_lshl_add_u64 v[28:29], v[4:5], 0, v[28:29]
	v_bfe_u32 v7, v15, 16, 1
	global_store_dwordx4 v[28:29], v[8:11], off
	v_add3_u32 v7, v15, v7, s14
	v_lshrrev_b32_e32 v7, 16, v7
	v_bfe_u32 v8, v13, 16, 1
	v_add3_u32 v8, v13, v8, s14
	v_and_or_b32 v8, v8, s15, v7
	s_nop 4
	v_cvt_pk_bf16_f32 v9, v17, v19
	s_nop 4
	v_cvt_pk_bf16_f32 v10, v21, v23
	s_nop 0
	v_add_u32_e32 v12, 40, v6
	s_nop 1
	v_ashrrev_i32_e32 v13, 31, v12
	s_nop 1
	v_lshlrev_b64 v[12:13], 13, v[12:13]
	v_cvt_pk_bf16_f32 v11, v25, v27
	ds_read2_b32 v[14:15], v78 offset0:48 offset1:56
	v_lshl_add_u64 v[12:13], v[4:5], 0, v[12:13]
	global_store_dwordx4 v[12:13], v[8:11], off
	ds_read2_b32 v[12:13], v78 offset0:113 offset1:121
	ds_read2_b32 v[16:17], v78 offset0:178 offset1:186
	ds_read2_b32 v[18:19], v78 offset0:243 offset1:251
	s_waitcnt lgkmcnt(3)
	s_nop 1
	s_waitcnt lgkmcnt(2)
	s_nop 0
	ds_read2_b32 v[20:21], v30 offset0:52 offset1:60
	s_nop 1
	ds_read2_b32 v[22:23], v30 offset0:117 offset1:125
	v_cvt_pk_bf16_f32 v8, v14, v12
	s_waitcnt lgkmcnt(3)
	s_nop 1
	s_waitcnt lgkmcnt(2)
	s_nop 0
	ds_read2_b32 v[24:25], v30 offset0:182 offset1:190
	s_nop 1
	ds_read2_b32 v[26:27], v30 offset0:247 offset1:255
	v_cvt_pk_bf16_f32 v9, v16, v18
	s_waitcnt lgkmcnt(3)
	s_nop 1
	s_waitcnt lgkmcnt(2)
	s_nop 2
	v_cvt_pk_bf16_f32 v10, v20, v22
	s_waitcnt lgkmcnt(1)
	s_nop 0
	v_add_u32_e32 v28, 48, v6
	s_nop 0
	s_waitcnt lgkmcnt(0)
	s_nop 0
	v_ashrrev_i32_e32 v29, 31, v28
	s_nop 1
	v_lshlrev_b64 v[28:29], 13, v[28:29]
	v_cvt_pk_bf16_f32 v11, v24, v26
	v_lshl_add_u64 v[28:29], v[4:5], 0, v[28:29]
	v_bfe_u32 v7, v15, 16, 1
	global_store_dwordx4 v[28:29], v[8:11], off
	v_add3_u32 v7, v15, v7, s14
	v_lshrrev_b32_e32 v7, 16, v7
	v_bfe_u32 v8, v13, 16, 1
	v_add3_u32 v8, v13, v8, s14
	v_and_or_b32 v8, v8, s15, v7
	s_nop 4
	v_cvt_pk_bf16_f32 v9, v17, v19
	s_nop 4
	v_cvt_pk_bf16_f32 v10, v21, v23
	s_nop 4
	v_add_u32_e32 v6, 56, v6
	v_cvt_pk_bf16_f32 v11, v25, v27
	v_ashrrev_i32_e32 v7, 31, v6
	v_lshlrev_b64 v[6:7], 13, v[6:7]
	v_lshl_add_u64 v[4:5], v[4:5], 0, v[6:7]
	global_store_dwordx4 v[4:5], v[8:11], off
	s_waitcnt lgkmcnt(0)
	s_add_i32 s12, s12, s13
	s_add_i32 s10, s10, s11
	s_cmpk_lt_i32 s12, 0x800
	s_cbranch_scc0 .LBB0_2718

; __device__ __forceinline__ unsigned pk2(float lo, float hi) { return f2bf(lo) | (f2bf(hi) << 16); }
; template <int MODE, class MaskF> ...
;     ...
;     if constexpr (MODE == 0) { l[0] = OL[0][0] * 0.25f; l[1] = OL[1][0] * 0.25f; }
; __device__ __forceinline__ void xa_attn_fa(const Ctx& c, const bf16* Q, const bf16* KV, const bf16* XVT, bf16* Oo) {
;     ...
;         for (int mi = 0; mi < 2; ++mi) { float lt = l[mi]; lt += __shfl_xor(lt, 16); lt += __shfl_xor(lt, 32); const float il = 1.f / lt;
; #pragma unroll
;             for (int dt = 0; dt < 8; ++dt) { const f32x4 o = O[dt][mi] * il; v2u w; w.x = pk2(o[0], o[1]); w.y = pk2(o[2], o[3]);
;                 *(v2u*)(Oo + grow[mi] * 512 + hd * 128 + 16 * dt + 4 * lg) = w; } }
.LBB0_2774:
	v_mul_f32_e32 v4, 0x3e800000, v128
	ds_bpermute_b32 v4, v167, v4
	s_lshl_b32 s6, s23, 1
	v_lshl_add_u64 v[6:7], v[172:173], 0, s[6:7]
	v_lshl_add_u64 v[42:43], v[6:7], 0, v[188:189]
	v_mul_f32_e32 v48, 0x3e800000, v40
	s_waitcnt lgkmcnt(0)
	v_fmac_f32_e32 v4, 0x3e800000, v128
	ds_bpermute_b32 v41, v196, v4
	v_lshl_add_u64 v[6:7], v[6:7], 0, v[186:187]
	s_add_i32 s22, s22, s33
	s_cmpk_lt_i32 s22, 0x100
	s_waitcnt lgkmcnt(0)
	v_add_f32_e32 v4, v4, v41
	v_div_scale_f32 v41, s[12:13], v4, v4, 1.0
	v_rcp_f32_e32 v44, v41
	v_div_scale_f32 v45, vcc, 1.0, v4, 1.0
	v_fma_f32 v46, -v41, v44, 1.0
	v_fmac_f32_e32 v44, v46, v44
	v_mul_f32_e32 v46, v45, v44
	v_fma_f32 v47, -v41, v46, v45
	v_fmac_f32_e32 v46, v47, v44
	v_fma_f32 v41, -v41, v46, v45
	v_div_fmas_f32 v41, v41, v44, v46
	v_div_fixup_f32 v4, v41, v4, 1.0
	v_pk_mul_f32 v[46:47], v[104:105], v[4:5] op_sel_hi:[1,0]
	v_pk_mul_f32 v[44:45], v[106:107], v[4:5] op_sel_hi:[1,0]
	s_nop 4
	v_cvt_pk_bf16_f32 v46, v46, v47
	v_bfe_u32 v41, v44, 16, 1
	v_add3_u32 v41, v44, v41, s20
	v_bfe_u32 v44, v45, 16, 1
	v_lshrrev_b32_e32 v41, 16, v41
	v_add3_u32 v44, v45, v44, s20
	v_and_or_b32 v47, v44, s21, v41
	global_store_dwordx2 v[42:43], v[46:47], off
	v_pk_mul_f32 v[46:47], v[100:101], v[4:5] op_sel_hi:[1,0]
	v_pk_mul_f32 v[44:45], v[102:103], v[4:5] op_sel_hi:[1,0]
	v_bfe_u32 v41, v46, 16, 1
	v_add3_u32 v41, v46, v41, s20
	v_bfe_u32 v46, v47, 16, 1
	v_lshrrev_b32_e32 v41, 16, v41
	v_add3_u32 v46, v47, v46, s20
	v_and_or_b32 v46, v46, s21, v41
	v_bfe_u32 v41, v44, 16, 1
	v_add3_u32 v41, v44, v41, s20
	v_bfe_u32 v44, v45, 16, 1
	v_lshrrev_b32_e32 v41, 16, v41
	v_add3_u32 v44, v45, v44, s20
	v_and_or_b32 v47, v44, s21, v41
	global_store_dwordx2 v[42:43], v[46:47], off offset:32
	v_pk_mul_f32 v[46:47], v[96:97], v[4:5] op_sel_hi:[1,0]
	v_pk_mul_f32 v[44:45], v[98:99], v[4:5] op_sel_hi:[1,0]
	v_bfe_u32 v41, v46, 16, 1
	v_add3_u32 v41, v46, v41, s20
	v_bfe_u32 v46, v47, 16, 1
	v_lshrrev_b32_e32 v41, 16, v41
	v_add3_u32 v46, v47, v46, s20
	v_and_or_b32 v46, v46, s21, v41
	v_bfe_u32 v41, v44, 16, 1
	v_add3_u32 v41, v44, v41, s20
	v_bfe_u32 v44, v45, 16, 1
	v_lshrrev_b32_e32 v41, 16, v41
	v_add3_u32 v44, v45, v44, s20
	v_and_or_b32 v47, v44, s21, v41
	global_store_dwordx2 v[42:43], v[46:47], off offset:64
	v_pk_mul_f32 v[46:47], v[92:93], v[4:5] op_sel_hi:[1,0]
	v_pk_mul_f32 v[44:45], v[94:95], v[4:5] op_sel_hi:[1,0]
	v_bfe_u32 v41, v46, 16, 1
	v_add3_u32 v41, v46, v41, s20
	v_bfe_u32 v46, v47, 16, 1
	v_lshrrev_b32_e32 v41, 16, v41
	v_add3_u32 v46, v47, v46, s20
	v_and_or_b32 v46, v46, s21, v41
	v_bfe_u32 v41, v44, 16, 1
	v_add3_u32 v41, v44, v41, s20
	v_bfe_u32 v44, v45, 16, 1
	v_lshrrev_b32_e32 v41, 16, v41
	v_add3_u32 v44, v45, v44, s20
	v_and_or_b32 v47, v44, s21, v41
	global_store_dwordx2 v[42:43], v[46:47], off offset:96
	v_pk_mul_f32 v[46:47], v[88:89], v[4:5] op_sel_hi:[1,0]
	v_pk_mul_f32 v[44:45], v[90:91], v[4:5] op_sel_hi:[1,0]
	v_bfe_u32 v41, v46, 16, 1
	v_add3_u32 v41, v46, v41, s20
	v_bfe_u32 v46, v47, 16, 1
	v_lshrrev_b32_e32 v41, 16, v41
	v_add3_u32 v46, v47, v46, s20
	v_and_or_b32 v46, v46, s21, v41
	v_bfe_u32 v41, v44, 16, 1
	v_add3_u32 v41, v44, v41, s20
	v_bfe_u32 v44, v45, 16, 1
	v_lshrrev_b32_e32 v41, 16, v41
	v_add3_u32 v44, v45, v44, s20
	v_and_or_b32 v47, v44, s21, v41
	global_store_dwordx2 v[42:43], v[46:47], off offset:128
	v_pk_mul_f32 v[46:47], v[84:85], v[4:5] op_sel_hi:[1,0]
	v_pk_mul_f32 v[44:45], v[86:87], v[4:5] op_sel_hi:[1,0]
	v_bfe_u32 v41, v46, 16, 1
	v_add3_u32 v41, v46, v41, s20
	v_bfe_u32 v46, v47, 16, 1
	v_lshrrev_b32_e32 v41, 16, v41
	v_add3_u32 v46, v47, v46, s20
	v_and_or_b32 v46, v46, s21, v41
	v_bfe_u32 v41, v44, 16, 1
	v_add3_u32 v41, v44, v41, s20
	v_bfe_u32 v44, v45, 16, 1
	v_lshrrev_b32_e32 v41, 16, v41
	v_add3_u32 v44, v45, v44, s20
	v_and_or_b32 v47, v44, s21, v41
	global_store_dwordx2 v[42:43], v[46:47], off offset:160
	v_pk_mul_f32 v[46:47], v[80:81], v[4:5] op_sel_hi:[1,0]
	v_pk_mul_f32 v[44:45], v[82:83], v[4:5] op_sel_hi:[1,0]
	v_bfe_u32 v41, v46, 16, 1
	v_add3_u32 v41, v46, v41, s20
	v_bfe_u32 v46, v47, 16, 1
	v_lshrrev_b32_e32 v41, 16, v41
	v_add3_u32 v46, v47, v46, s20
	v_and_or_b32 v46, v46, s21, v41
	v_bfe_u32 v41, v44, 16, 1
	v_add3_u32 v41, v44, v41, s20
	v_bfe_u32 v44, v45, 16, 1
	v_lshrrev_b32_e32 v41, 16, v41
	v_add3_u32 v44, v45, v44, s20
	v_and_or_b32 v47, v44, s21, v41
	ds_bpermute_b32 v41, v167, v48
	global_store_dwordx2 v[42:43], v[46:47], off offset:192
	v_pk_mul_f32 v[46:47], v[76:77], v[4:5] op_sel_hi:[1,0]
	v_pk_mul_f32 v[44:45], v[78:79], v[4:5] op_sel_hi:[1,0]
	v_bfe_u32 v4, v46, 16, 1
	v_add3_u32 v4, v46, v4, s20
	v_bfe_u32 v46, v47, 16, 1
	v_lshrrev_b32_e32 v4, 16, v4
	v_add3_u32 v46, v47, v46, s20
	s_waitcnt lgkmcnt(0)
; __device__ __forceinline__ unsigned pk2(float lo, float hi) { return f2bf(lo) | (f2bf(hi) << 16); }
; __device__ __forceinline__ void xa_attn_fa(const Ctx& c, const bf16* Q, const bf16* KV, const bf16* XVT, bf16* Oo) {
;     ...
;         for (int mi = 0; mi < 2; ++mi) { float lt = l[mi]; lt += __shfl_xor(lt, 16); lt += __shfl_xor(lt, 32); const float il = 1.f / lt;
; #pragma unroll
;             for (int dt = 0; dt < 8; ++dt) { const f32x4 o = O[dt][mi] * il; v2u w; w.x = pk2(o[0], o[1]); w.y = pk2(o[2], o[3]);
;                 *(v2u*)(Oo + grow[mi] * 512 + hd * 128 + 16 * dt + 4 * lg) = w; } }
	v_fmac_f32_e32 v41, 0x3e800000, v40
	v_and_or_b32 v46, v46, s21, v4
	ds_bpermute_b32 v4, v196, v41
	v_bfe_u32 v40, v44, 16, 1
	v_add3_u32 v40, v44, v40, s20
	v_bfe_u32 v44, v45, 16, 1
	v_lshrrev_b32_e32 v40, 16, v40
	s_waitcnt lgkmcnt(0)
	v_add_f32_e32 v4, v41, v4
	v_div_scale_f32 v41, s[12:13], v4, v4, 1.0
	v_rcp_f32_e32 v48, v41
	v_add3_u32 v44, v45, v44, s20
	v_and_or_b32 v47, v44, s21, v40
	global_store_dwordx2 v[42:43], v[46:47], off offset:224
	v_fma_f32 v40, -v41, v48, 1.0
	v_fmac_f32_e32 v48, v40, v48
	v_div_scale_f32 v40, vcc, 1.0, v4, 1.0
	v_mul_f32_e32 v42, v40, v48
	v_fma_f32 v43, -v41, v42, v40
	v_fmac_f32_e32 v42, v43, v48
	v_fma_f32 v40, -v41, v42, v40
	v_div_fmas_f32 v40, v40, v48, v42
	v_div_fixup_f32 v4, v40, v4, 1.0
	v_pk_mul_f32 v[36:37], v[36:37], v[4:5] op_sel_hi:[1,0]
	v_pk_mul_f32 v[38:39], v[38:39], v[4:5] op_sel_hi:[1,0]
	s_nop 4
	v_cvt_pk_bf16_f32 v36, v36, v37
	v_bfe_u32 v37, v38, 16, 1
	v_add3_u32 v37, v38, v37, s20
	v_bfe_u32 v38, v39, 16, 1
	v_lshrrev_b32_e32 v37, 16, v37
	v_add3_u32 v38, v39, v38, s20
	v_and_or_b32 v37, v38, s21, v37
	v_pk_mul_f32 v[32:33], v[32:33], v[4:5] op_sel_hi:[1,0]
	global_store_dwordx2 v[6:7], v[36:37], off
	s_nop 2
	v_pk_mul_f32 v[34:35], v[34:35], v[4:5] op_sel_hi:[1,0]
	s_nop 1
	v_cvt_pk_bf16_f32 v32, v32, v33
	v_bfe_u32 v33, v34, 16, 1
	v_add3_u32 v33, v34, v33, s20
	v_bfe_u32 v34, v35, 16, 1
	v_lshrrev_b32_e32 v33, 16, v33
	v_add3_u32 v34, v35, v34, s20
	v_and_or_b32 v33, v34, s21, v33
	v_pk_mul_f32 v[28:29], v[28:29], v[4:5] op_sel_hi:[1,0]
	global_store_dwordx2 v[6:7], v[32:33], off offset:32
	s_nop 2
	v_pk_mul_f32 v[30:31], v[30:31], v[4:5] op_sel_hi:[1,0]
	s_nop 1
	v_cvt_pk_bf16_f32 v28, v28, v29
	v_bfe_u32 v29, v30, 16, 1
	v_add3_u32 v29, v30, v29, s20
	v_bfe_u32 v30, v31, 16, 1
	v_lshrrev_b32_e32 v29, 16, v29
	v_add3_u32 v30, v31, v30, s20
	v_and_or_b32 v29, v30, s21, v29
	v_pk_mul_f32 v[24:25], v[24:25], v[4:5] op_sel_hi:[1,0]
	global_store_dwordx2 v[6:7], v[28:29], off offset:64
	s_nop 2
	v_pk_mul_f32 v[26:27], v[26:27], v[4:5] op_sel_hi:[1,0]
	s_nop 1
	v_cvt_pk_bf16_f32 v24, v24, v25
	v_bfe_u32 v25, v26, 16, 1
	v_add3_u32 v25, v26, v25, s20
	v_bfe_u32 v26, v27, 16, 1
	v_lshrrev_b32_e32 v25, 16, v25
	v_add3_u32 v26, v27, v26, s20
	v_and_or_b32 v25, v26, s21, v25
	v_pk_mul_f32 v[20:21], v[20:21], v[4:5] op_sel_hi:[1,0]
	global_store_dwordx2 v[6:7], v[24:25], off offset:96
	s_nop 2
	v_pk_mul_f32 v[22:23], v[22:23], v[4:5] op_sel_hi:[1,0]
	s_nop 1
	v_cvt_pk_bf16_f32 v20, v20, v21
	v_bfe_u32 v21, v22, 16, 1
	v_add3_u32 v21, v22, v21, s20
	v_bfe_u32 v22, v23, 16, 1
	v_lshrrev_b32_e32 v21, 16, v21
	v_add3_u32 v22, v23, v22, s20
	v_and_or_b32 v21, v22, s21, v21
	v_pk_mul_f32 v[16:17], v[16:17], v[4:5] op_sel_hi:[1,0]
	global_store_dwordx2 v[6:7], v[20:21], off offset:128
	s_nop 2
	v_pk_mul_f32 v[18:19], v[18:19], v[4:5] op_sel_hi:[1,0]
	s_nop 1
	v_cvt_pk_bf16_f32 v16, v16, v17
	v_bfe_u32 v17, v18, 16, 1
	v_add3_u32 v17, v18, v17, s20
	v_bfe_u32 v18, v19, 16, 1
	v_lshrrev_b32_e32 v17, 16, v17
	v_add3_u32 v18, v19, v18, s20
	v_and_or_b32 v17, v18, s21, v17
	v_pk_mul_f32 v[12:13], v[12:13], v[4:5] op_sel_hi:[1,0]
	v_pk_mul_f32 v[8:9], v[8:9], v[4:5] op_sel_hi:[1,0]
	global_store_dwordx2 v[6:7], v[16:17], off offset:160
	v_pk_mul_f32 v[14:15], v[14:15], v[4:5] op_sel_hi:[1,0]
	s_nop 0
	v_pk_mul_f32 v[10:11], v[10:11], v[4:5] op_sel_hi:[1,0]
	v_bfe_u32 v4, v8, 16, 1
	s_nop 1
	v_add3_u32 v4, v8, v4, s20
	v_bfe_u32 v8, v9, 16, 1
	s_nop 1
	v_lshrrev_b32_e32 v4, 16, v4
	v_add3_u32 v8, v9, v8, s20
	v_cvt_pk_bf16_f32 v12, v12, v13
	v_bfe_u32 v13, v14, 16, 1
	v_and_or_b32 v8, v8, s21, v4
	v_bfe_u32 v4, v10, 16, 1
	v_add3_u32 v13, v14, v13, s20
	v_bfe_u32 v14, v15, 16, 1
	v_add3_u32 v4, v10, v4, s20
	v_bfe_u32 v9, v11, 16, 1
	v_lshrrev_b32_e32 v13, 16, v13
	v_add3_u32 v14, v15, v14, s20
	v_lshrrev_b32_e32 v4, 16, v4
	v_add3_u32 v9, v11, v9, s20
	v_and_or_b32 v13, v14, s21, v13
	v_and_or_b32 v9, v9, s21, v4
	global_store_dwordx2 v[6:7], v[12:13], off offset:192
	global_store_dwordx2 v[6:7], v[8:9], off offset:224
	s_cbranch_scc0 .LBB0_2786

; __device__ __forceinline__ void postnorm(const Ctx& c, const bf16* MF, bf16* XB, float* RS, const float* gpost, float* OUT) {
;     for (int row = c.gw; row < MT; row += c.NGW) {
;         const v4u* mr = (const v4u*)(MF + (size_t)row * DM) + c.lane; v4u* xr = (v4u*)(XB + (size_t)row * DM) + c.lane;
;         v4u mv[4], xv[4]; float v[4][8]; float s = 0.f;
; #pragma unroll
;         for (int j = 0; j < 4; ++j) { mv[j] = mr[64 * j]; xv[j] = xr[64 * j]; }
; #pragma unroll
;         for (int j = 0; j < 4; ++j)
; #pragma unroll
;             for (int k = 0; k < 4; ++k) { v[j][2 * k] = bflo(mv[j][k]); v[j][2 * k + 1] = bfhi(mv[j][k]); s += v[j][2 * k] * v[j][2 * k] + v[j][2 * k + 1] * v[j][2 * k + 1]; }
;         const float rs = rsqrtf(wave_sum(s) * (1.f / DM) + EPS);
;         float s2 = 0.f;
; #pragma unroll
;         for (int j = 0; j < 4; ++j) { const float* gp = gpost + (c.lane + 64 * j) * 8; const f32x4 g0 = *(CF4)gp, g1 = *(CF4)(gp + 4);
.LBB0_3204:
	v_readlane_b32 s10, v253, 0
	v_readlane_b32 s11, v253, 1
	s_nop 1
	v_lshl_add_u64 v[38:39], s[10:11], 0, v[30:31]
	v_add_co_u32_e32 v58, vcc, 0xd400000, v38
	s_nop 1
	v_addc_co_u32_e32 v59, vcc, 0, v39, vcc
	s_waitcnt lgkmcnt(0)
	global_load_dwordx4 v[46:49], v[58:59], off
	global_load_dwordx4 v[50:53], v[58:59], off offset:1024
	global_load_dwordx4 v[54:57], v[58:59], off offset:2048
	s_nop 0
	global_load_dwordx4 v[58:61], v[58:59], off offset:3072
	v_add_co_u32_e32 v38, vcc, 0x9400000, v38
	s_waitcnt vmcnt(3)
	v_lshlrev_b32_e32 v79, 16, v47
	v_addc_co_u32_e32 v39, vcc, 0, v39, vcc
	global_load_dwordx4 v[62:65], v[38:39], off
	global_load_dwordx4 v[66:69], v[38:39], off offset:1024
	global_load_dwordx4 v[70:73], v[38:39], off offset:2048
	global_load_dwordx4 v[74:77], v[38:39], off offset:3072
	v_lshlrev_b32_e32 v78, 16, v46
	v_and_b32_e32 v47, 0xffff0000, v47
	v_and_b32_e32 v46, 0xffff0000, v46
	v_lshlrev_b32_e32 v81, 16, v49
	v_lshlrev_b32_e32 v80, 16, v48
	v_and_b32_e32 v49, 0xffff0000, v49
	v_and_b32_e32 v48, 0xffff0000, v48
	v_pk_mul_f32 v[94:95], v[46:47], v[46:47]
	v_pk_mul_f32 v[98:99], v[48:49], v[48:49]
	v_pk_fma_f32 v[94:95], v[78:79], v[78:79], v[94:95]
	s_waitcnt vmcnt(6)
	v_lshlrev_b32_e32 v83, 16, v51
	v_lshlrev_b32_e32 v82, 16, v50
	v_and_b32_e32 v51, 0xffff0000, v51
	v_and_b32_e32 v50, 0xffff0000, v50
	v_pk_fma_f32 v[98:99], v[80:81], v[80:81], v[98:99]
	v_add_f32_e32 v94, v94, v95
	v_pk_mul_f32 v[102:103], v[50:51], v[50:51]
	v_add_f32_e32 v94, v98, v94
	v_lshlrev_b32_e32 v85, 16, v53
	v_lshlrev_b32_e32 v84, 16, v52
	v_and_b32_e32 v53, 0xffff0000, v53
	v_and_b32_e32 v52, 0xffff0000, v52
	v_pk_fma_f32 v[102:103], v[82:83], v[82:83], v[102:103]
	v_add_f32_e32 v94, v99, v94
	v_pk_mul_f32 v[104:105], v[52:53], v[52:53]
	v_add_f32_e32 v94, v102, v94
	s_waitcnt vmcnt(5)
	v_lshlrev_b32_e32 v87, 16, v55
	v_lshlrev_b32_e32 v86, 16, v54
	v_and_b32_e32 v55, 0xffff0000, v55
	v_and_b32_e32 v54, 0xffff0000, v54
	v_pk_fma_f32 v[104:105], v[84:85], v[84:85], v[104:105]
	v_add_f32_e32 v94, v103, v94
	v_pk_mul_f32 v[106:107], v[54:55], v[54:55]
	v_add_f32_e32 v94, v104, v94
	v_lshlrev_b32_e32 v89, 16, v57
	v_lshlrev_b32_e32 v88, 16, v56
	v_and_b32_e32 v57, 0xffff0000, v57
	v_and_b32_e32 v56, 0xffff0000, v56
	v_pk_fma_f32 v[106:107], v[86:87], v[86:87], v[106:107]
	v_add_f32_e32 v94, v105, v94
	v_pk_mul_f32 v[108:109], v[56:57], v[56:57]
	v_add_f32_e32 v94, v106, v94
	s_waitcnt vmcnt(4)
	v_lshlrev_b32_e32 v91, 16, v59
	v_lshlrev_b32_e32 v90, 16, v58
	v_and_b32_e32 v59, 0xffff0000, v59
	v_and_b32_e32 v58, 0xffff0000, v58
	v_pk_fma_f32 v[108:109], v[88:89], v[88:89], v[108:109]
	v_add_f32_e32 v94, v107, v94
	v_pk_mul_f32 v[110:111], v[58:59], v[58:59]
	v_add_f32_e32 v94, v108, v94
	v_lshlrev_b32_e32 v93, 16, v61
	v_lshlrev_b32_e32 v92, 16, v60
	v_and_b32_e32 v61, 0xffff0000, v61
	v_and_b32_e32 v60, 0xffff0000, v60
	v_pk_fma_f32 v[110:111], v[90:91], v[90:91], v[110:111]
	v_add_f32_e32 v94, v109, v94
	v_pk_mul_f32 v[112:113], v[60:61], v[60:61]
	v_add_f32_e32 v94, v110, v94
	v_pk_fma_f32 v[112:113], v[92:93], v[92:93], v[112:113]
	v_add_f32_e32 v94, v111, v94
	v_add_f32_e32 v94, v112, v94
	v_add_f32_e32 v94, v113, v94
	ds_bpermute_b32 v98, v3, v94
	s_waitcnt lgkmcnt(0)
	v_add_f32_e32 v98, v94, v98
	ds_bpermute_b32 v102, v40, v98
	s_waitcnt lgkmcnt(0)
	v_add_f32_e32 v102, v98, v102
	ds_bpermute_b32 v104, v41, v102
	s_waitcnt vmcnt(3)
	v_lshlrev_b32_e32 v97, 16, v63
	v_lshlrev_b32_e32 v96, 16, v62
	v_and_b32_e32 v63, 0xffff0000, v63
	s_waitcnt lgkmcnt(0)
	v_add_f32_e32 v104, v102, v104
	ds_bpermute_b32 v106, v42, v104
	v_and_b32_e32 v62, 0xffff0000, v62
	v_lshlrev_b32_e32 v101, 16, v65
	v_lshlrev_b32_e32 v100, 16, v64
	v_and_b32_e32 v65, 0xffff0000, v65
	s_waitcnt lgkmcnt(0)
	v_add_f32_e32 v106, v104, v106
	ds_bpermute_b32 v108, v43, v106
	v_and_b32_e32 v64, 0xffff0000, v64
	s_waitcnt vmcnt(0)
	v_lshlrev_b32_e32 v109, 16, v77
	v_and_b32_e32 v77, 0xffff0000, v77
	v_lshlrev_b32_e32 v95, 16, v67
	s_waitcnt lgkmcnt(0)
	v_add_f32_e32 v108, v106, v108
	ds_bpermute_b32 v110, v44, v108
	v_lshlrev_b32_e32 v94, 16, v66
	v_and_b32_e32 v67, 0xffff0000, v67
	v_and_b32_e32 v66, 0xffff0000, v66
	v_lshlrev_b32_e32 v99, 16, v69
	s_waitcnt lgkmcnt(0)
	v_add_f32_e32 v108, v108, v110
	v_fmamk_f32 v108, v108, 0x3a000000, v45
	v_mul_f32_e32 v110, 0x4b800000, v108
	v_cmp_gt_f32_e32 vcc, s15, v108
	v_lshlrev_b32_e32 v98, 16, v68
	v_and_b32_e32 v69, 0xffff0000, v69
	v_cndmask_b32_e32 v108, v108, v110, vcc
	v_rsq_f32_e32 v110, v108
	v_lshlrev_b32_e32 v108, 16, v76
	v_and_b32_e32 v76, 0xffff0000, v76
	v_and_b32_e32 v68, 0xffff0000, v68
	v_mul_f32_e32 v111, 0x45800000, v110
	v_cndmask_b32_e32 v110, v110, v111, vcc
	v_pk_mul_f32 v[46:47], v[110:111], v[46:47] op_sel_hi:[0,1]
	v_pk_mul_f32 v[78:79], v[110:111], v[78:79] op_sel_hi:[0,1]
	v_pk_mul_f32 v[48:49], v[110:111], v[48:49] op_sel_hi:[0,1]
	v_pk_fma_f32 v[46:47], v[36:37], v[46:47], v[62:63]
	v_pk_mul_f32 v[60:61], v[110:111], v[60:61] op_sel_hi:[0,1]
	v_pk_mul_f32 v[80:81], v[110:111], v[80:81] op_sel_hi:[0,1]
	v_pk_fma_f32 v[78:79], v[8:9], v[78:79], v[96:97]
	v_pk_fma_f32 v[48:49], v[10:11], v[48:49], v[64:65]
	v_pk_fma_f32 v[60:61], v[34:35], v[60:61], v[76:77]
	v_pk_mul_f32 v[76:77], v[46:47], v[46:47]
	v_pk_mul_f32 v[50:51], v[110:111], v[50:51] op_sel_hi:[0,1]
	v_pk_fma_f32 v[62:63], v[4:5], v[80:81], v[100:101]
	v_pk_fma_f32 v[76:77], v[78:79], v[78:79], v[76:77]
	v_pk_mul_f32 v[80:81], v[48:49], v[48:49]
	v_pk_mul_f32 v[82:83], v[110:111], v[82:83] op_sel_hi:[0,1]
	v_pk_fma_f32 v[50:51], v[6:7], v[50:51], v[66:67]
	v_pk_fma_f32 v[80:81], v[62:63], v[62:63], v[80:81]
	v_add_f32_e32 v76, v76, v77
; __device__ __forceinline__ unsigned pk2(float lo, float hi) { return f2bf(lo) | (f2bf(hi) << 16); }
; __device__ __forceinline__ void postnorm(const Ctx& c, const bf16* MF, bf16* XB, float* RS, const float* gpost, float* OUT) {
;     ...
; #pragma unroll
;             for (int k = 0; k < 4; ++k) { const float ga = (k < 2) ? g0[2 * k] : g1[2 * k - 4], gb = (k < 2) ? g0[2 * k + 1] : g1[2 * k - 3];
;                 v[j][2 * k] = bflo(xv[j][k]) + v[j][2 * k] * rs * ga; v[j][2 * k + 1] = bfhi(xv[j][k]) + v[j][2 * k + 1] * rs * gb;
;                 s2 += v[j][2 * k] * v[j][2 * k] + v[j][2 * k + 1] * v[j][2 * k + 1]; } }
;         if (OUT) {
; #pragma unroll
;             for (int j = 0; j < 4; ++j) { float* op = OUT + (size_t)row * DM + (c.lane + 64 * j) * 8; *(f32x4*)op = (f32x4){v[j][0], v[j][1], v[j][2], v[j][3]}; *(f32x4*)(op + 4) = (f32x4){v[j][4], v[j][5], v[j][6], v[j][7]}; }
;         } else {
; #pragma unroll
;             for (int j = 0; j < 4; ++j) { v4u o; o.x = pk2(v[j][0], v[j][1]); o.y = pk2(v[j][2], v[j][3]); o.z = pk2(v[j][4], v[j][5]); o.w = pk2(v[j][6], v[j][7]); xr[64 * j] = o; }
;             const float rs2 = rsqrtf(wave_sum(s2) * (1.f / DM) + EPS); if (c.lane == 0) RS[row] = rs2;
	v_pk_fma_f32 v[64:65], v[16:17], v[82:83], v[94:95]
	v_pk_mul_f32 v[82:83], v[50:51], v[50:51]
	v_add_f32_e32 v76, v80, v76
	v_pk_fma_f32 v[82:83], v[64:65], v[64:65], v[82:83]
	v_add_f32_e32 v76, v81, v76
	v_add_f32_e32 v76, v82, v76
	v_bfe_u32 v77, v49, 16, 1
	v_bfe_u32 v80, v48, 16, 1
	v_bfe_u32 v81, v47, 16, 1
	v_bfe_u32 v82, v46, 16, 1
	v_pk_mul_f32 v[52:53], v[110:111], v[52:53] op_sel_hi:[0,1]
	v_add3_u32 v46, v46, v82, s16
	v_add3_u32 v47, v47, v81, s16
	v_add3_u32 v48, v48, v80, s16
	v_add3_u32 v49, v49, v77, s16
	v_bfe_u32 v77, v78, 16, 1
	v_bfe_u32 v80, v79, 16, 1
	v_bfe_u32 v81, v62, 16, 1
	v_bfe_u32 v82, v63, 16, 1
	v_pk_mul_f32 v[84:85], v[110:111], v[84:85] op_sel_hi:[0,1]
	v_pk_fma_f32 v[52:53], v[18:19], v[52:53], v[68:69]
	v_add3_u32 v63, v63, v82, s16
	v_add3_u32 v62, v62, v81, s16
	v_add3_u32 v79, v79, v80, s16
	v_add3_u32 v77, v78, v77, s16
	v_lshlrev_b32_e32 v103, 16, v71
	v_lshlrev_b32_e32 v102, 16, v70
	v_and_b32_e32 v71, 0xffff0000, v71
	v_and_b32_e32 v70, 0xffff0000, v70
	v_pk_fma_f32 v[66:67], v[12:13], v[84:85], v[98:99]
	v_pk_mul_f32 v[54:55], v[110:111], v[54:55] op_sel_hi:[0,1]
	v_pk_mul_f32 v[84:85], v[52:53], v[52:53]
	v_lshrrev_b32_e32 v77, 16, v77
	v_lshrrev_b32_e32 v78, 16, v79
	v_lshrrev_b32_e32 v62, 16, v62
	v_lshrrev_b32_e32 v63, 16, v63
	v_pk_mul_f32 v[68:69], v[110:111], v[86:87] op_sel_hi:[0,1]
	v_pk_fma_f32 v[54:55], v[14:15], v[54:55], v[70:71]
	v_pk_fma_f32 v[84:85], v[66:67], v[66:67], v[84:85]
	v_add_f32_e32 v76, v83, v76
	v_and_or_b32 v49, v49, s14, v63
	v_and_or_b32 v48, v48, s14, v62
	v_and_or_b32 v47, v47, s14, v78
	v_and_or_b32 v46, v46, s14, v77
	v_lshlrev_b32_e32 v105, 16, v73
	v_lshlrev_b32_e32 v104, 16, v72
	v_and_b32_e32 v73, 0xffff0000, v73
	v_and_b32_e32 v72, 0xffff0000, v72
	v_pk_fma_f32 v[68:69], v[24:25], v[68:69], v[102:103]
	v_pk_mul_f32 v[56:57], v[110:111], v[56:57] op_sel_hi:[0,1]
	v_pk_mul_f32 v[86:87], v[54:55], v[54:55]
	v_add_f32_e32 v76, v84, v76
	global_store_dwordx4 v[38:39], v[46:49], off
	v_pk_mul_f32 v[70:71], v[110:111], v[88:89] op_sel_hi:[0,1]
	v_pk_fma_f32 v[56:57], v[26:27], v[56:57], v[72:73]
	v_bfe_u32 v46, v53, 16, 1
	v_bfe_u32 v47, v52, 16, 1
	v_bfe_u32 v48, v51, 16, 1
	v_bfe_u32 v49, v50, 16, 1
	v_pk_fma_f32 v[86:87], v[68:69], v[68:69], v[86:87]
	v_add_f32_e32 v76, v85, v76
	v_add3_u32 v50, v50, v49, s16
	v_add3_u32 v51, v51, v48, s16
	v_add3_u32 v47, v52, v47, s16
	v_add3_u32 v46, v53, v46, s16
	v_bfe_u32 v48, v64, 16, 1
	v_bfe_u32 v49, v65, 16, 1
	v_bfe_u32 v52, v66, 16, 1
	v_bfe_u32 v53, v67, 16, 1
	v_lshlrev_b32_e32 v107, 16, v75
	v_lshlrev_b32_e32 v106, 16, v74
	v_and_b32_e32 v75, 0xffff0000, v75
	v_and_b32_e32 v74, 0xffff0000, v74
	v_pk_fma_f32 v[70:71], v[20:21], v[70:71], v[104:105]
	v_pk_mul_f32 v[58:59], v[110:111], v[58:59] op_sel_hi:[0,1]
	v_pk_mul_f32 v[88:89], v[56:57], v[56:57]
	v_add_f32_e32 v76, v86, v76
	v_add3_u32 v53, v67, v53, s16
	v_add3_u32 v52, v66, v52, s16
	v_add3_u32 v49, v65, v49, s16
	v_add3_u32 v48, v64, v48, s16
	v_pk_mul_f32 v[72:73], v[110:111], v[90:91] op_sel_hi:[0,1]
	v_pk_fma_f32 v[58:59], v[22:23], v[58:59], v[74:75]
	v_pk_fma_f32 v[88:89], v[70:71], v[70:71], v[88:89]
	v_add_f32_e32 v76, v87, v76
	v_lshrrev_b32_e32 v62, 16, v48
	v_lshrrev_b32_e32 v63, 16, v49
	v_lshrrev_b32_e32 v48, 16, v52
	v_lshrrev_b32_e32 v49, 16, v53
	v_pk_fma_f32 v[72:73], v[32:33], v[72:73], v[106:107]
	v_pk_mul_f32 v[90:91], v[58:59], v[58:59]
	v_add_f32_e32 v76, v88, v76
	v_and_or_b32 v49, v46, s14, v49
	v_and_or_b32 v48, v47, s14, v48
	v_and_or_b32 v47, v51, s14, v63
	v_and_or_b32 v46, v50, s14, v62
	v_pk_mul_f32 v[74:75], v[110:111], v[92:93] op_sel_hi:[0,1]
	v_pk_fma_f32 v[90:91], v[72:73], v[72:73], v[90:91]
	v_add_f32_e32 v76, v89, v76
	global_store_dwordx4 v[38:39], v[46:49], off offset:1024
	v_pk_fma_f32 v[74:75], v[28:29], v[74:75], v[108:109]
	v_pk_mul_f32 v[92:93], v[60:61], v[60:61]
	v_bfe_u32 v48, v55, 16, 1
	v_bfe_u32 v49, v54, 16, 1
	v_add_f32_e32 v76, v90, v76
	v_add3_u32 v50, v54, v49, s16
	v_add3_u32 v51, v55, v48, s16
	v_bfe_u32 v48, v68, 16, 1
	v_bfe_u32 v49, v69, 16, 1
	v_bfe_u32 v52, v70, 16, 1
	v_bfe_u32 v53, v71, 16, 1
	v_pk_fma_f32 v[92:93], v[74:75], v[74:75], v[92:93]
	v_add_f32_e32 v76, v91, v76
	v_bfe_u32 v46, v57, 16, 1
	v_bfe_u32 v47, v56, 16, 1
	v_add3_u32 v53, v71, v53, s16
	v_add3_u32 v52, v70, v52, s16
	v_add3_u32 v49, v69, v49, s16
	v_add3_u32 v48, v68, v48, s16
	v_add_f32_e32 v76, v92, v76
	v_add3_u32 v47, v56, v47, s16
	v_add3_u32 v46, v57, v46, s16
	v_lshrrev_b32_e32 v54, 16, v48
	v_lshrrev_b32_e32 v55, 16, v49
	v_lshrrev_b32_e32 v48, 16, v52
	v_lshrrev_b32_e32 v49, 16, v53
	v_add_f32_e32 v76, v93, v76
	v_and_or_b32 v49, v46, s14, v49
	v_and_or_b32 v48, v47, s14, v48
	v_and_or_b32 v47, v51, s14, v55
	v_and_or_b32 v46, v50, s14, v54
	global_store_dwordx4 v[38:39], v[46:49], off offset:2048
	ds_bpermute_b32 v47, v3, v76
	v_bfe_u32 v50, v58, 16, 1
	v_add3_u32 v52, v58, v50, s16
	v_bfe_u32 v51, v72, 16, 1
	v_bfe_u32 v55, v75, 16, 1
	s_waitcnt lgkmcnt(0)
	v_add_f32_e32 v47, v76, v47
	ds_bpermute_b32 v50, v40, v47
	v_bfe_u32 v46, v61, 16, 1
	v_add3_u32 v55, v75, v55, s16
	v_add3_u32 v51, v72, v51, s16
	v_add3_u32 v46, v61, v46, s16
	s_waitcnt lgkmcnt(0)
	v_add_f32_e32 v47, v47, v50
	ds_bpermute_b32 v50, v41, v47
	v_lshrrev_b32_e32 v56, 16, v51
	v_lshrrev_b32_e32 v51, 16, v55
	v_and_or_b32 v51, v46, s14, v51
	s_nop 0
	s_waitcnt lgkmcnt(0)
	v_add_f32_e32 v47, v47, v50
	ds_bpermute_b32 v50, v42, v47
	v_bfe_u32 v54, v74, 16, 1
	v_bfe_u32 v48, v60, 16, 1
	s_nop 0
	v_add3_u32 v54, v74, v54, s16
	s_waitcnt lgkmcnt(0)
	v_add_f32_e32 v47, v47, v50
	ds_bpermute_b32 v50, v43, v47
	s_nop 1
	v_add3_u32 v48, v60, v48, s16
	s_nop 0
	s_waitcnt lgkmcnt(0)
	v_add_f32_e32 v46, v47, v50
	ds_bpermute_b32 v47, v44, v46
	v_lshrrev_b32_e32 v54, 16, v54
	v_and_or_b32 v50, v48, s14, v54
	v_cvt_pk_bf16_f32 v49, v73, v59
	v_and_or_b32 v48, v52, s14, v56
	global_store_dwordx4 v[38:39], v[48:51], off offset:3072
	s_and_saveexec_b64 s[10:11], s[0:1]
	s_cbranch_execz .LBB0_3203
	s_waitcnt lgkmcnt(0)
	v_add_f32_e32 v38, v46, v47
	v_fmamk_f32 v38, v38, 0x3a000000, v45
	v_mul_f32_e32 v39, 0x4b800000, v38
	v_cmp_gt_f32_e32 vcc, s15, v38
	v_readlane_b32 s18, v253, 0
	v_readlane_b32 s19, v253, 1
	v_cndmask_b32_e32 v38, v38, v39, vcc
	v_rsq_f32_e32 v38, v38
	s_add_u32 s18, s18, s12
	s_addc_u32 s19, s19, s13
	v_mul_f32_e32 v39, 0x45800000, v38
	v_cndmask_b32_e32 v38, v38, v39, vcc
	global_store_dword v251, v38, s[18:19]
	s_branch .LBB0_3203

; #define LAS __attribute__((address_space(3)))
; #define LDS_WAIT() asm volatile("s_waitcnt lgkmcnt(0)" ::: "memory")
;     ...
;         const int kb = it / nblk, nb = it % nblk, k0 = 64 * kb, n0 = 64 * nb, nq = (lane & 15) * 4, kr = lane >> 4; const bool ok = (n0 + nq) < N;
;         f32x4 v[16];
; #pragma unroll
;         for (int i = 0; i < 16; ++i) v[i] = ok ? __builtin_nontemporal_load((const f32x4*)(W + (size_t)(k0 + 4 * i + kr) * N + n0 + nq)) : (f32x4){0.f, 0.f, 0.f, 0.f};
;         if (gain) {
; #pragma unroll
;             for (int i = 0; i < 16; ++i) v[i] *= gain[k0 + 4 * i + kr]; }
; #pragma unroll
;         for (int i = 0; i < 16; ++i) { LAS float* d = scr + (4 * i + kr) * 65 + nq; d[0] = v[i].x; d[1] = v[i].y; d[2] = v[i].z; d[3] = v[i].w; }
;         LDS_WAIT(); asm volatile("" ::: "memory");
.LBB0_3209:
	s_or_b64 exec, exec, s[10:11]
	v_lshl_add_u64 v[82:83], v[72:73], 2, s[6:7]
	global_load_dword v72, v[82:83], off
	s_add_i32 s17, s17, s12
	s_ashr_i32 s9, s8, 31
	s_add_i32 s16, s16, s86
	s_add_i32 s12, s12, s13
	s_cmpk_lt_i32 s16, 0x100
	s_waitcnt vmcnt(0)
	v_pk_mul_f32 v[86:87], v[8:9], v[72:73] op_sel_hi:[1,0]
	global_load_dword v8, v[82:83], off offset:16
	v_pk_mul_f32 v[84:85], v[10:11], v[72:73] op_sel_hi:[1,0]
	s_waitcnt vmcnt(0)
	v_pk_mul_f32 v[72:73], v[14:15], v[8:9] op_sel_hi:[1,0]
	v_pk_mul_f32 v[88:89], v[12:13], v[8:9] op_sel_hi:[1,0]
	global_load_dword v8, v[82:83], off offset:32
	global_load_dword v12, v[82:83], off offset:160
	s_waitcnt vmcnt(1)
	v_pk_mul_f32 v[90:91], v[4:5], v[8:9] op_sel_hi:[1,0]
	global_load_dword v4, v[82:83], off offset:48
	v_pk_mul_f32 v[74:75], v[6:7], v[8:9] op_sel_hi:[1,0]
	global_load_dword v6, v[82:83], off offset:128
	global_load_dword v8, v[82:83], off offset:144
	s_waitcnt vmcnt(3)
	v_pk_mul_f32 v[10:11], v[42:43], v[12:13] op_sel_hi:[1,0]
	v_pk_mul_f32 v[12:13], v[40:41], v[12:13] op_sel_hi:[1,0]
	v_add_u32_e32 v40, 0x410, v81
	s_waitcnt vmcnt(2)
	v_pk_mul_f32 v[92:93], v[22:23], v[4:5] op_sel_hi:[1,0]
	v_pk_mul_f32 v[94:95], v[20:21], v[4:5] op_sel_hi:[1,0]
	global_load_dword v4, v[82:83], off offset:64
	global_load_dword v20, v[82:83], off offset:192
	s_waitcnt vmcnt(1)
	v_pk_mul_f32 v[96:97], v[18:19], v[4:5] op_sel_hi:[1,0]
	v_pk_mul_f32 v[98:99], v[16:17], v[4:5] op_sel_hi:[1,0]
	global_load_dword v4, v[82:83], off offset:80
	global_load_dword v16, v[82:83], off offset:176
	s_waitcnt vmcnt(2)
	v_pk_mul_f32 v[18:19], v[50:51], v[20:21] op_sel_hi:[1,0]
	v_pk_mul_f32 v[20:21], v[48:49], v[20:21] op_sel_hi:[1,0]
	s_waitcnt vmcnt(1)
	v_pk_mul_f32 v[100:101], v[30:31], v[4:5] op_sel_hi:[1,0]
	v_pk_mul_f32 v[102:103], v[28:29], v[4:5] op_sel_hi:[1,0]
	global_load_dword v4, v[82:83], off offset:96
	global_load_dword v28, v[82:83], off offset:224
	v_lshl_add_u64 v[30:31], v[76:77], 2, s[6:7]
	s_waitcnt vmcnt(2)
	v_pk_mul_f32 v[14:15], v[54:55], v[16:17] op_sel_hi:[1,0]
	v_pk_mul_f32 v[16:17], v[52:53], v[16:17] op_sel_hi:[1,0]
	s_waitcnt vmcnt(1)
	v_pk_mul_f32 v[104:105], v[26:27], v[4:5] op_sel_hi:[1,0]
	v_pk_mul_f32 v[106:107], v[24:25], v[4:5] op_sel_hi:[1,0]
	global_load_dword v4, v[82:83], off offset:112
	global_load_dword v24, v[82:83], off offset:208
	s_waitcnt vmcnt(2)
	v_pk_mul_f32 v[26:27], v[58:59], v[28:29] op_sel_hi:[1,0]
	v_pk_mul_f32 v[28:29], v[56:57], v[28:29] op_sel_hi:[1,0]
	s_waitcnt vmcnt(1)
	v_pk_mul_f32 v[38:39], v[38:39], v[4:5] op_sel_hi:[1,0]
	v_pk_mul_f32 v[36:37], v[36:37], v[4:5] op_sel_hi:[1,0]
	v_pk_mul_f32 v[4:5], v[34:35], v[6:7] op_sel_hi:[1,0]
	v_pk_mul_f32 v[34:35], v[32:33], v[6:7] op_sel_hi:[1,0]
	global_load_dword v32, v[30:31], off
	ds_write2_b32 v81, v86, v87 offset1:1
	ds_write2_b32 v81, v84, v85 offset0:2 offset1:3
	ds_write2_b32 v40, v88, v89 offset1:1
	v_add_u32_e32 v40, 0x418, v81
	ds_write2_b32 v40, v72, v73 offset1:1
	v_add_u32_e32 v40, 0x820, v81
	ds_write2_b32 v40, v90, v91 offset1:1
	v_add_u32_e32 v40, 0x828, v81
	ds_write2_b32 v40, v74, v75 offset1:1
	v_add_u32_e32 v40, 0xc30, v81
	ds_write2_b32 v40, v94, v95 offset1:1
	v_add_u32_e32 v40, 0xc38, v81
	ds_write2_b32 v40, v92, v93 offset1:1
	v_add_u32_e32 v40, 0x1040, v81
	ds_write2_b32 v40, v98, v99 offset1:1
	v_add_u32_e32 v40, 0x1048, v81
	ds_write2_b32 v40, v96, v97 offset1:1
	v_add_u32_e32 v40, 0x1450, v81
	ds_write2_b32 v40, v102, v103 offset1:1
	v_add_u32_e32 v40, 0x1458, v81
	ds_write2_b32 v40, v100, v101 offset1:1
	v_add_u32_e32 v40, 0x1860, v81
	ds_write2_b32 v40, v106, v107 offset1:1
	v_add_u32_e32 v40, 0x1868, v81
	ds_write2_b32 v40, v104, v105 offset1:1
	v_add_u32_e32 v40, 0x1c70, v81
	ds_write2_b32 v40, v36, v37 offset1:1
	v_add_u32_e32 v36, 0x1c78, v81
	ds_write2_b32 v36, v38, v39 offset1:1
	v_add_u32_e32 v36, 0x2080, v81
	ds_write2_b32 v36, v34, v35 offset1:1
	v_add_u32_e32 v34, 0x2088, v81
	v_pk_mul_f32 v[6:7], v[46:47], v[8:9] op_sel_hi:[1,0]
	v_pk_mul_f32 v[8:9], v[44:45], v[8:9] op_sel_hi:[1,0]
	ds_write2_b32 v34, v4, v5 offset1:1
	v_add_u32_e32 v4, 0x2490, v81
	ds_write2_b32 v4, v8, v9 offset1:1
	v_add_u32_e32 v4, 0x2498, v81
	ds_write2_b32 v4, v6, v7 offset1:1
	v_add_u32_e32 v4, 0x28a0, v81
	ds_write2_b32 v4, v12, v13 offset1:1
	v_add_u32_e32 v4, 0x28a8, v81
	ds_write2_b32 v4, v10, v11 offset1:1
	v_add_u32_e32 v4, 0x2cb0, v81
	ds_write2_b32 v4, v16, v17 offset1:1
	v_add_u32_e32 v4, 0x2cb8, v81
	ds_write2_b32 v4, v14, v15 offset1:1
	v_add_u32_e32 v4, 0x30c0, v81
	ds_write2_b32 v4, v20, v21 offset1:1
	v_add_u32_e32 v4, 0x30c8, v81
	s_waitcnt vmcnt(1)
	v_pk_mul_f32 v[22:23], v[62:63], v[24:25] op_sel_hi:[1,0]
	v_pk_mul_f32 v[24:25], v[60:61], v[24:25] op_sel_hi:[1,0]
	ds_write2_b32 v4, v18, v19 offset1:1
	v_add_u32_e32 v4, 0x34d0, v81
	ds_write2_b32 v4, v24, v25 offset1:1
	v_add_u32_e32 v4, 0x34d8, v81
	ds_write2_b32 v4, v22, v23 offset1:1
	v_add_u32_e32 v4, 0x38e0, v81
	ds_write2_b32 v4, v28, v29 offset1:1
	v_add_u32_e32 v4, 0x38e8, v81
	ds_write2_b32 v4, v26, v27 offset1:1
	v_add_u32_e32 v4, 0x3cf0, v81
	s_waitcnt vmcnt(0)
	v_pk_mul_f32 v[30:31], v[66:67], v[32:33] op_sel_hi:[1,0]
	v_pk_mul_f32 v[32:33], v[64:65], v[32:33] op_sel_hi:[1,0]
	ds_write2_b32 v4, v32, v33 offset1:1
	v_add_u32_e32 v4, 0x3cf8, v81
	ds_write2_b32 v4, v30, v31 offset1:1
	s_waitcnt lgkmcnt(0)
	ds_read2_b32 v[8:9], v80 offset0:65 offset1:73
	ds_read2_b32 v[14:15], v80 offset1:8
	ds_read2_b32 v[16:17], v80 offset0:130 offset1:138
	ds_read2_b32 v[18:19], v80 offset0:195 offset1:203
	v_lshl_add_u64 v[4:5], s[8:9], 1, v[70:71]
	s_waitcnt lgkmcnt(3)
	v_bfe_u32 v7, v8, 16, 1
	s_waitcnt lgkmcnt(2)
; #define LAS __attribute__((address_space(3)))
; #define LDS_WAIT() asm volatile("s_waitcnt lgkmcnt(0)" ::: "memory")
; __device__ __forceinline__ unsigned pk2(float lo, float hi) { return f2bf(lo) | (f2bf(hi) << 16); }
;     ...
;         for (int i = 0; i < 16; ++i) { LAS float* d = scr + (4 * i + kr) * 65 + nq; d[0] = v[i].x; d[1] = v[i].y; d[2] = v[i].z; d[3] = v[i].w; }
;         LDS_WAIT(); asm volatile("" ::: "memory");
;         const int c8 = lane & 7; int d0 = n0;
;         if (ffnmap) { const int bj = n0 >= FFH ? 1 : 0, chn = n0 - FFH * bj; d0 = 256 * (chn >> 7) + 128 * bj + (chn & 127); }
; #pragma unroll
;         for (int j = 0; j < 8; ++j) { const int n = (lane >> 3) + 8 * j; const LAS float* sp = scr + (8 * c8) * 65 + n;
;             v4u o; o.x = pk2(sp[0 * 65], sp[1 * 65]); o.y = pk2(sp[2 * 65], sp[3 * 65]); o.z = pk2(sp[4 * 65], sp[5 * 65]); o.w = pk2(sp[6 * 65], sp[7 * 65]);
;             *(v4u*)(WT + (size_t)(d0 + n) * K + k0 + 8 * c8) = o; }
;         LDS_WAIT(); asm volatile("" ::: "memory");
	v_bfe_u32 v6, v14, 16, 1
	v_add3_u32 v6, v14, v6, s14
	v_add3_u32 v7, v8, v7, s14
	v_add_u32_e32 v8, 0x400, v80
	v_lshrrev_b32_e32 v6, 16, v6
	ds_read2_b32 v[20:21], v8 offset0:4 offset1:12
	ds_read2_b32 v[22:23], v8 offset0:69 offset1:77
	v_and_or_b32 v10, v7, s15, v6
	s_waitcnt lgkmcnt(3)
	s_nop 1
	s_waitcnt lgkmcnt(2)
	s_nop 2
	ds_read2_b32 v[24:25], v8 offset0:134 offset1:142
	ds_read2_b32 v[26:27], v8 offset0:199 offset1:207
	v_cvt_pk_bf16_f32 v11, v16, v18
	s_waitcnt lgkmcnt(3)
	s_nop 1
	s_waitcnt lgkmcnt(2)
	s_nop 2
	v_cvt_pk_bf16_f32 v12, v20, v22
	s_waitcnt lgkmcnt(1)
	s_nop 1
	s_waitcnt lgkmcnt(0)
	s_nop 2
	v_cvt_pk_bf16_f32 v13, v24, v26
	v_add_u32_e32 v6, s17, v79
	v_ashrrev_i32_e32 v7, 31, v6
	v_lshlrev_b64 v[28:29], 12, v[6:7]
	v_lshl_add_u64 v[28:29], v[4:5], 0, v[28:29]
	v_bfe_u32 v7, v15, 16, 1
	global_store_dwordx4 v[28:29], v[10:13], off
	v_add3_u32 v7, v15, v7, s14
	v_lshrrev_b32_e32 v7, 16, v7
	v_bfe_u32 v10, v9, 16, 1
	v_add3_u32 v9, v9, v10, s14
	v_and_or_b32 v10, v9, s15, v7
	s_nop 4
	v_cvt_pk_bf16_f32 v11, v17, v19
	s_nop 4
	v_cvt_pk_bf16_f32 v12, v21, v23
	s_nop 0
	v_add_u32_e32 v14, 8, v6
	s_nop 1
	v_ashrrev_i32_e32 v15, 31, v14
	s_nop 1
	v_lshlrev_b64 v[14:15], 12, v[14:15]
	v_cvt_pk_bf16_f32 v13, v25, v27
	v_lshl_add_u64 v[14:15], v[4:5], 0, v[14:15]
	global_store_dwordx4 v[14:15], v[10:13], off
	ds_read2_b32 v[14:15], v80 offset0:81 offset1:89
	ds_read2_b32 v[16:17], v80 offset0:16 offset1:24
	ds_read2_b32 v[18:19], v80 offset0:146 offset1:154
	ds_read2_b32 v[20:21], v80 offset0:211 offset1:219
	ds_read2_b32 v[22:23], v8 offset0:20 offset1:28
	ds_read2_b32 v[24:25], v8 offset0:85 offset1:93
	ds_read2_b32 v[26:27], v8 offset0:150 offset1:158
	ds_read2_b32 v[28:29], v8 offset0:215 offset1:223
	s_waitcnt lgkmcnt(7)
	s_nop 0
	s_waitcnt lgkmcnt(6)
	s_nop 3
	v_cvt_pk_bf16_f32 v10, v16, v14
	s_waitcnt lgkmcnt(5)
	s_nop 1
	s_waitcnt lgkmcnt(4)
	s_nop 2
	v_cvt_pk_bf16_f32 v11, v18, v20
	s_waitcnt lgkmcnt(3)
	s_nop 1
	s_waitcnt lgkmcnt(2)
	s_nop 2
	v_cvt_pk_bf16_f32 v12, v22, v24
	s_waitcnt lgkmcnt(1)
	s_nop 1
	s_waitcnt lgkmcnt(0)
	s_nop 2
	v_add_u32_e32 v30, 16, v6
	v_cvt_pk_bf16_f32 v13, v26, v28
	v_ashrrev_i32_e32 v31, 31, v30
	v_bfe_u32 v7, v17, 16, 1
	v_lshlrev_b64 v[30:31], 12, v[30:31]
	v_add3_u32 v7, v17, v7, s14
	v_bfe_u32 v9, v15, 16, 1
	v_lshl_add_u64 v[30:31], v[4:5], 0, v[30:31]
	v_lshrrev_b32_e32 v7, 16, v7
	v_add3_u32 v9, v15, v9, s14
	global_store_dwordx4 v[30:31], v[10:13], off
	v_add_u32_e32 v14, 24, v6
	v_ashrrev_i32_e32 v15, 31, v14
	v_and_or_b32 v10, v9, s15, v7
	s_nop 4
	v_cvt_pk_bf16_f32 v11, v19, v21
	s_nop 4
	v_cvt_pk_bf16_f32 v12, v23, v25
	s_nop 4
	v_lshlrev_b64 v[14:15], 12, v[14:15]
	v_cvt_pk_bf16_f32 v13, v27, v29
	v_lshl_add_u64 v[14:15], v[4:5], 0, v[14:15]
	global_store_dwordx4 v[14:15], v[10:13], off
	ds_read2_b32 v[14:15], v80 offset0:97 offset1:105
	ds_read2_b32 v[16:17], v80 offset0:32 offset1:40
	ds_read2_b32 v[18:19], v80 offset0:162 offset1:170
	ds_read2_b32 v[20:21], v80 offset0:227 offset1:235
	ds_read2_b32 v[22:23], v8 offset0:36 offset1:44
	ds_read2_b32 v[24:25], v8 offset0:101 offset1:109
	ds_read2_b32 v[26:27], v8 offset0:166 offset1:174
	ds_read2_b32 v[28:29], v8 offset0:231 offset1:239
	s_waitcnt lgkmcnt(7)
	s_nop 0
	s_waitcnt lgkmcnt(6)
	s_nop 3
	v_cvt_pk_bf16_f32 v10, v16, v14
	s_waitcnt lgkmcnt(5)
	s_nop 1
	s_waitcnt lgkmcnt(4)
	s_nop 2
	v_cvt_pk_bf16_f32 v11, v18, v20
	s_waitcnt lgkmcnt(3)
	s_nop 1
	s_waitcnt lgkmcnt(2)
	s_nop 2
	v_cvt_pk_bf16_f32 v12, v22, v24
	s_waitcnt lgkmcnt(1)
	s_nop 1
	s_waitcnt lgkmcnt(0)
	s_nop 2
	v_add_u32_e32 v30, 32, v6
	v_cvt_pk_bf16_f32 v13, v26, v28
	v_ashrrev_i32_e32 v31, 31, v30
	v_bfe_u32 v7, v17, 16, 1
	v_lshlrev_b64 v[30:31], 12, v[30:31]
	v_add3_u32 v7, v17, v7, s14
	v_bfe_u32 v9, v15, 16, 1
	v_lshl_add_u64 v[30:31], v[4:5], 0, v[30:31]
	v_lshrrev_b32_e32 v7, 16, v7
	v_add3_u32 v9, v15, v9, s14
	global_store_dwordx4 v[30:31], v[10:13], off
	v_add_u32_e32 v14, 40, v6
	v_ashrrev_i32_e32 v15, 31, v14
	v_and_or_b32 v10, v9, s15, v7
	s_nop 4
	v_cvt_pk_bf16_f32 v11, v19, v21
	s_nop 4
	v_cvt_pk_bf16_f32 v12, v23, v25
	s_nop 4
	v_lshlrev_b64 v[14:15], 12, v[14:15]
	v_cvt_pk_bf16_f32 v13, v27, v29
	v_lshl_add_u64 v[14:15], v[4:5], 0, v[14:15]
	global_store_dwordx4 v[14:15], v[10:13], off
	ds_read2_b32 v[14:15], v80 offset0:48 offset1:56
	ds_read2_b32 v[16:17], v80 offset0:113 offset1:121
	ds_read2_b32 v[18:19], v80 offset0:178 offset1:186
	ds_read2_b32 v[20:21], v80 offset0:243 offset1:251
	ds_read2_b32 v[22:23], v8 offset0:52 offset1:60
	ds_read2_b32 v[24:25], v8 offset0:117 offset1:125
	ds_read2_b32 v[26:27], v8 offset0:182 offset1:190
	ds_read2_b32 v[28:29], v8 offset0:247 offset1:255
	s_waitcnt lgkmcnt(7)
	s_nop 1
	s_waitcnt lgkmcnt(6)
	s_nop 2
	v_cvt_pk_bf16_f32 v10, v14, v16
	s_waitcnt lgkmcnt(5)
	s_nop 1
	s_waitcnt lgkmcnt(4)
	s_nop 2
	v_cvt_pk_bf16_f32 v11, v18, v20
	s_waitcnt lgkmcnt(3)
	s_nop 1
	s_waitcnt lgkmcnt(2)
	s_nop 2
	v_cvt_pk_bf16_f32 v12, v22, v24
	s_waitcnt lgkmcnt(1)
	s_nop 1
	s_waitcnt lgkmcnt(0)
	s_nop 2
	v_cvt_pk_bf16_f32 v13, v26, v28
	v_add_u32_e32 v8, 48, v6
	v_ashrrev_i32_e32 v9, 31, v8
	v_lshlrev_b64 v[8:9], 12, v[8:9]
	v_lshl_add_u64 v[8:9], v[4:5], 0, v[8:9]
	v_bfe_u32 v7, v15, 16, 1
	global_store_dwordx4 v[8:9], v[10:13], off
	v_add3_u32 v7, v15, v7, s14
	v_bfe_u32 v8, v17, 16, 1
	v_lshrrev_b32_e32 v7, 16, v7
	v_add3_u32 v8, v17, v8, s14
	v_and_or_b32 v8, v8, s15, v7
	s_nop 4
	v_cvt_pk_bf16_f32 v9, v19, v21
	s_nop 4
	v_cvt_pk_bf16_f32 v10, v23, v25
	s_nop 4
	v_add_u32_e32 v6, 56, v6
	v_cvt_pk_bf16_f32 v11, v27, v29
	v_ashrrev_i32_e32 v7, 31, v6
	v_lshlrev_b64 v[6:7], 12, v[6:7]
	v_lshl_add_u64 v[4:5], v[4:5], 0, v[6:7]
	global_store_dwordx4 v[4:5], v[8:11], off
	s_waitcnt lgkmcnt(0)
	s_cbranch_scc0 .LBB0_3242

; #define LAS __attribute__((address_space(3)))
; #define LDS_WAIT() asm volatile("s_waitcnt lgkmcnt(0)" ::: "memory")
; __device__ __forceinline__ unsigned pk2(float lo, float hi) { return f2bf(lo) | (f2bf(hi) << 16); }
;     ...
;         for (int i = 0; i < 16; ++i) { LAS float* d = scr + (4 * i + kr) * 65 + nq; d[0] = v[i].x; d[1] = v[i].y; d[2] = v[i].z; d[3] = v[i].w; }
;         LDS_WAIT(); asm volatile("" ::: "memory");
;         const int c8 = lane & 7; int d0 = n0;
;         if (ffnmap) { const int bj = n0 >= FFH ? 1 : 0, chn = n0 - FFH * bj; d0 = 256 * (chn >> 7) + 128 * bj + (chn & 127); }
; #pragma unroll
;         for (int j = 0; j < 8; ++j) { const int n = (lane >> 3) + 8 * j; const LAS float* sp = scr + (8 * c8) * 65 + n;
;             v4u o; o.x = pk2(sp[0 * 65], sp[1 * 65]); o.y = pk2(sp[2 * 65], sp[3 * 65]); o.z = pk2(sp[4 * 65], sp[5 * 65]); o.w = pk2(sp[6 * 65], sp[7 * 65]);
;             *(v4u*)(WT + (size_t)(d0 + n) * K + k0 + 8 * c8) = o; }
;         LDS_WAIT(); asm volatile("" ::: "memory");
.LBB0_3244:
	s_or_b64 exec, exec, s[8:9]
	s_waitcnt vmcnt(0)
	ds_write2_b32 v79, v4, v5 offset1:1
	ds_write2_b32 v79, v6, v7 offset0:2 offset1:3
	v_add_u32_e32 v4, 0x410, v79
	ds_write2_b32 v4, v12, v13 offset1:1
	v_add_u32_e32 v4, 0x418, v79
	ds_write2_b32 v4, v14, v15 offset1:1
	v_add_u32_e32 v4, 0x820, v79
	ds_write2_b32 v4, v8, v9 offset1:1
	v_add_u32_e32 v4, 0x828, v79
	ds_write2_b32 v4, v10, v11 offset1:1
	v_add_u32_e32 v4, 0xc30, v79
	ds_write2_b32 v4, v20, v21 offset1:1
	v_add_u32_e32 v4, 0xc38, v79
	ds_write2_b32 v4, v22, v23 offset1:1
	v_add_u32_e32 v4, 0x1040, v79
	ds_write2_b32 v4, v16, v17 offset1:1
	v_add_u32_e32 v4, 0x1048, v79
	ds_write2_b32 v4, v18, v19 offset1:1
	v_add_u32_e32 v4, 0x1450, v79
	ds_write2_b32 v4, v28, v29 offset1:1
	v_add_u32_e32 v4, 0x1458, v79
	ds_write2_b32 v4, v30, v31 offset1:1
	v_add_u32_e32 v4, 0x1860, v79
	ds_write2_b32 v4, v24, v25 offset1:1
	v_add_u32_e32 v4, 0x1868, v79
	ds_write2_b32 v4, v26, v27 offset1:1
	v_add_u32_e32 v4, 0x1c70, v79
	ds_write2_b32 v4, v36, v37 offset1:1
	v_add_u32_e32 v4, 0x1c78, v79
	ds_write2_b32 v4, v38, v39 offset1:1
	v_add_u32_e32 v4, 0x2080, v79
	ds_write2_b32 v4, v32, v33 offset1:1
	v_add_u32_e32 v4, 0x2088, v79
	ds_write2_b32 v4, v34, v35 offset1:1
	v_add_u32_e32 v4, 0x2490, v79
	ds_write2_b32 v4, v44, v45 offset1:1
	v_add_u32_e32 v4, 0x2498, v79
	ds_write2_b32 v4, v46, v47 offset1:1
	v_add_u32_e32 v4, 0x28a0, v79
	ds_write2_b32 v4, v40, v41 offset1:1
	v_add_u32_e32 v4, 0x28a8, v79
	ds_write2_b32 v4, v42, v43 offset1:1
	v_add_u32_e32 v4, 0x2cb0, v79
	ds_write2_b32 v4, v52, v53 offset1:1
	v_add_u32_e32 v4, 0x2cb8, v79
	ds_write2_b32 v4, v54, v55 offset1:1
	v_add_u32_e32 v4, 0x30c0, v79
	ds_write2_b32 v4, v48, v49 offset1:1
	v_add_u32_e32 v4, 0x30c8, v79
	ds_write2_b32 v4, v50, v51 offset1:1
	v_add_u32_e32 v4, 0x34d0, v79
	ds_write2_b32 v4, v60, v61 offset1:1
	v_add_u32_e32 v4, 0x34d8, v79
	ds_write2_b32 v4, v62, v63 offset1:1
	v_add_u32_e32 v4, 0x38e0, v79
	ds_write2_b32 v4, v56, v57 offset1:1
	v_add_u32_e32 v4, 0x38e8, v79
	ds_write2_b32 v4, v58, v59 offset1:1
	v_add_u32_e32 v4, 0x3cf0, v79
	ds_write2_b32 v4, v64, v65 offset1:1
	v_add_u32_e32 v4, 0x3cf8, v79
	ds_write2_b32 v4, v66, v67 offset1:1
	s_waitcnt lgkmcnt(0)
	ds_read2_b32 v[12:13], v78 offset1:8
	ds_read2_b32 v[14:15], v78 offset0:65 offset1:73
	ds_read2_b32 v[16:17], v78 offset0:130 offset1:138
	ds_read2_b32 v[18:19], v78 offset0:195 offset1:203
	v_add_u32_e32 v30, 0x400, v78
	s_waitcnt lgkmcnt(3)
	s_nop 1
	s_waitcnt lgkmcnt(2)
	s_nop 0
	ds_read2_b32 v[20:21], v30 offset0:4 offset1:12
	s_nop 1
	ds_read2_b32 v[22:23], v30 offset0:69 offset1:77
	v_cvt_pk_bf16_f32 v8, v12, v14
	s_waitcnt lgkmcnt(3)
	s_nop 1
	s_waitcnt lgkmcnt(2)
	s_nop 0
	ds_read2_b32 v[24:25], v30 offset0:134 offset1:142
	s_nop 1
	ds_read2_b32 v[26:27], v30 offset0:199 offset1:207
	v_cvt_pk_bf16_f32 v9, v16, v18
	s_waitcnt lgkmcnt(3)
	s_nop 1
	s_waitcnt lgkmcnt(2)
	s_nop 2
	v_cvt_pk_bf16_f32 v10, v20, v22
	s_waitcnt lgkmcnt(1)
	s_nop 1
	s_waitcnt lgkmcnt(0)
	s_nop 2
	s_add_i32 s18, s18, s14
	v_cvt_pk_bf16_f32 v11, v24, v26
	v_add_u32_e32 v6, s18, v77
	s_ashr_i32 s7, s6, 31
	v_ashrrev_i32_e32 v7, 31, v6
	v_lshl_add_u64 v[4:5], s[6:7], 1, v[70:71]
	v_lshlrev_b64 v[28:29], 12, v[6:7]
	v_lshl_add_u64 v[28:29], v[4:5], 0, v[28:29]
	v_bfe_u32 v7, v13, 16, 1
	global_store_dwordx4 v[28:29], v[8:11], off
	v_add3_u32 v7, v13, v7, s16
	v_lshrrev_b32_e32 v7, 16, v7
	v_bfe_u32 v8, v15, 16, 1
	v_add3_u32 v8, v15, v8, s16
	v_and_or_b32 v8, v8, s17, v7
	s_nop 4
	v_cvt_pk_bf16_f32 v9, v17, v19
	s_nop 4
	v_cvt_pk_bf16_f32 v10, v21, v23
	s_nop 0
	v_add_u32_e32 v12, 8, v6
	s_nop 1
	v_ashrrev_i32_e32 v13, 31, v12
	s_nop 1
	v_lshlrev_b64 v[12:13], 12, v[12:13]
	v_cvt_pk_bf16_f32 v11, v25, v27
	ds_read2_b32 v[14:15], v78 offset0:16 offset1:24
	v_lshl_add_u64 v[12:13], v[4:5], 0, v[12:13]
	global_store_dwordx4 v[12:13], v[8:11], off
	ds_read2_b32 v[12:13], v78 offset0:81 offset1:89
	ds_read2_b32 v[16:17], v78 offset0:146 offset1:154
	ds_read2_b32 v[18:19], v78 offset0:211 offset1:219
	s_waitcnt lgkmcnt(3)
	s_nop 1
	s_waitcnt lgkmcnt(2)
	s_nop 0
	ds_read2_b32 v[20:21], v30 offset0:20 offset1:28
	s_nop 1
	ds_read2_b32 v[22:23], v30 offset0:85 offset1:93
	v_cvt_pk_bf16_f32 v8, v14, v12
	s_waitcnt lgkmcnt(3)
; #define LAS __attribute__((address_space(3)))
; #define LDS_WAIT() asm volatile("s_waitcnt lgkmcnt(0)" ::: "memory")
; __device__ __forceinline__ unsigned pk2(float lo, float hi) { return f2bf(lo) | (f2bf(hi) << 16); }
;     ...
;         for (int j = 0; j < 8; ++j) { const int n = (lane >> 3) + 8 * j; const LAS float* sp = scr + (8 * c8) * 65 + n;
;             v4u o; o.x = pk2(sp[0 * 65], sp[1 * 65]); o.y = pk2(sp[2 * 65], sp[3 * 65]); o.z = pk2(sp[4 * 65], sp[5 * 65]); o.w = pk2(sp[6 * 65], sp[7 * 65]);
;             *(v4u*)(WT + (size_t)(d0 + n) * K + k0 + 8 * c8) = o; }
;         LDS_WAIT(); asm volatile("" ::: "memory");
	s_nop 1
	s_waitcnt lgkmcnt(2)
	s_nop 0
	ds_read2_b32 v[24:25], v30 offset0:150 offset1:158
	s_nop 1
	ds_read2_b32 v[26:27], v30 offset0:215 offset1:223
	v_cvt_pk_bf16_f32 v9, v16, v18
	s_waitcnt lgkmcnt(3)
	s_nop 1
	s_waitcnt lgkmcnt(2)
	s_nop 2
	v_cvt_pk_bf16_f32 v10, v20, v22
	s_waitcnt lgkmcnt(1)
	s_nop 0
	v_add_u32_e32 v28, 16, v6
	s_nop 0
	s_waitcnt lgkmcnt(0)
	s_nop 0
	v_ashrrev_i32_e32 v29, 31, v28
	s_nop 1
	v_lshlrev_b64 v[28:29], 12, v[28:29]
	v_cvt_pk_bf16_f32 v11, v24, v26
	v_lshl_add_u64 v[28:29], v[4:5], 0, v[28:29]
	v_bfe_u32 v7, v15, 16, 1
	global_store_dwordx4 v[28:29], v[8:11], off
	v_add3_u32 v7, v15, v7, s16
	v_lshrrev_b32_e32 v7, 16, v7
	v_bfe_u32 v8, v13, 16, 1
	v_add3_u32 v8, v13, v8, s16
	v_and_or_b32 v8, v8, s17, v7
	s_nop 4
	v_cvt_pk_bf16_f32 v9, v17, v19
	s_nop 4
	v_cvt_pk_bf16_f32 v10, v21, v23
	s_nop 0
	v_add_u32_e32 v12, 24, v6
	s_nop 1
	v_ashrrev_i32_e32 v13, 31, v12
	s_nop 1
	v_lshlrev_b64 v[12:13], 12, v[12:13]
	v_cvt_pk_bf16_f32 v11, v25, v27
	ds_read2_b32 v[14:15], v78 offset0:32 offset1:40
	v_lshl_add_u64 v[12:13], v[4:5], 0, v[12:13]
	global_store_dwordx4 v[12:13], v[8:11], off
	ds_read2_b32 v[12:13], v78 offset0:97 offset1:105
	ds_read2_b32 v[16:17], v78 offset0:162 offset1:170
	ds_read2_b32 v[18:19], v78 offset0:227 offset1:235
	s_waitcnt lgkmcnt(3)
	s_nop 1
	s_waitcnt lgkmcnt(2)
	s_nop 0
	ds_read2_b32 v[20:21], v30 offset0:36 offset1:44
	s_nop 1
	ds_read2_b32 v[22:23], v30 offset0:101 offset1:109
	v_cvt_pk_bf16_f32 v8, v14, v12
	s_waitcnt lgkmcnt(3)
	s_nop 1
	s_waitcnt lgkmcnt(2)
	s_nop 0
	ds_read2_b32 v[24:25], v30 offset0:166 offset1:174
	s_nop 1
	ds_read2_b32 v[26:27], v30 offset0:231 offset1:239
	v_cvt_pk_bf16_f32 v9, v16, v18
	s_waitcnt lgkmcnt(3)
	s_nop 1
	s_waitcnt lgkmcnt(2)
	s_nop 2
	v_cvt_pk_bf16_f32 v10, v20, v22
	s_waitcnt lgkmcnt(1)
	s_nop 0
	v_add_u32_e32 v28, 32, v6
	s_nop 0
	s_waitcnt lgkmcnt(0)
	s_nop 0
	v_ashrrev_i32_e32 v29, 31, v28
	s_nop 1
	v_lshlrev_b64 v[28:29], 12, v[28:29]
	v_cvt_pk_bf16_f32 v11, v24, v26
	v_lshl_add_u64 v[28:29], v[4:5], 0, v[28:29]
	v_bfe_u32 v7, v15, 16, 1
	global_store_dwordx4 v[28:29], v[8:11], off
	v_add3_u32 v7, v15, v7, s16
	v_lshrrev_b32_e32 v7, 16, v7
	v_bfe_u32 v8, v13, 16, 1
	v_add3_u32 v8, v13, v8, s16
	v_and_or_b32 v8, v8, s17, v7
	s_nop 4
	v_cvt_pk_bf16_f32 v9, v17, v19
	s_nop 4
	v_cvt_pk_bf16_f32 v10, v21, v23
	s_nop 0
	v_add_u32_e32 v12, 40, v6
	s_nop 1
	v_ashrrev_i32_e32 v13, 31, v12
	s_nop 1
	v_lshlrev_b64 v[12:13], 12, v[12:13]
	v_cvt_pk_bf16_f32 v11, v25, v27
	ds_read2_b32 v[14:15], v78 offset0:48 offset1:56
	v_lshl_add_u64 v[12:13], v[4:5], 0, v[12:13]
	global_store_dwordx4 v[12:13], v[8:11], off
	ds_read2_b32 v[12:13], v78 offset0:113 offset1:121
	ds_read2_b32 v[16:17], v78 offset0:178 offset1:186
	ds_read2_b32 v[18:19], v78 offset0:243 offset1:251
	s_waitcnt lgkmcnt(3)
	s_nop 1
	s_waitcnt lgkmcnt(2)
	s_nop 0
	ds_read2_b32 v[20:21], v30 offset0:52 offset1:60
	s_nop 1
	ds_read2_b32 v[22:23], v30 offset0:117 offset1:125
	v_cvt_pk_bf16_f32 v8, v14, v12
	s_waitcnt lgkmcnt(3)
	s_nop 1
	s_waitcnt lgkmcnt(2)
	s_nop 0
	ds_read2_b32 v[24:25], v30 offset0:182 offset1:190
	s_nop 1
	ds_read2_b32 v[26:27], v30 offset0:247 offset1:255
	v_cvt_pk_bf16_f32 v9, v16, v18
	s_waitcnt lgkmcnt(3)
	s_nop 1
	s_waitcnt lgkmcnt(2)
	s_nop 2
	v_cvt_pk_bf16_f32 v10, v20, v22
	s_waitcnt lgkmcnt(1)
	s_nop 0
	v_add_u32_e32 v28, 48, v6
	s_nop 0
	s_waitcnt lgkmcnt(0)
	s_nop 0
	v_ashrrev_i32_e32 v29, 31, v28
	s_nop 1
	v_lshlrev_b64 v[28:29], 12, v[28:29]
	v_cvt_pk_bf16_f32 v11, v24, v26
	v_lshl_add_u64 v[28:29], v[4:5], 0, v[28:29]
	v_bfe_u32 v7, v15, 16, 1
	global_store_dwordx4 v[28:29], v[8:11], off
	v_add3_u32 v7, v15, v7, s16
	v_lshrrev_b32_e32 v7, 16, v7
	v_bfe_u32 v8, v13, 16, 1
	v_add3_u32 v8, v13, v8, s16
	v_and_or_b32 v8, v8, s17, v7
	s_nop 4
	v_cvt_pk_bf16_f32 v9, v17, v19
	s_nop 4
	v_cvt_pk_bf16_f32 v10, v21, v23
	s_nop 4
	v_add_u32_e32 v6, 56, v6
	v_cvt_pk_bf16_f32 v11, v25, v27
	v_ashrrev_i32_e32 v7, 31, v6
	v_lshlrev_b64 v[6:7], 12, v[6:7]
	v_lshl_add_u64 v[4:5], v[4:5], 0, v[6:7]
	global_store_dwordx4 v[4:5], v[8:11], off
	s_waitcnt lgkmcnt(0)
	s_add_i32 s13, s13, s86
	s_add_i32 s14, s14, s15
	s_cmpk_lt_i32 s13, 0x200
	s_cbranch_scc0 .LBB0_3277

; #define LAS __attribute__((address_space(3)))
; #define LDS_WAIT() asm volatile("s_waitcnt lgkmcnt(0)" ::: "memory")
; __device__ __forceinline__ unsigned pk2(float lo, float hi) { return f2bf(lo) | (f2bf(hi) << 16); }
;     ...
;         for (int i = 0; i < 16; ++i) { LAS float* d = scr + (4 * i + kr) * 65 + nq; d[0] = v[i].x; d[1] = v[i].y; d[2] = v[i].z; d[3] = v[i].w; }
;         LDS_WAIT(); asm volatile("" ::: "memory");
;         const int c8 = lane & 7; int d0 = n0;
;         if (ffnmap) { const int bj = n0 >= FFH ? 1 : 0, chn = n0 - FFH * bj; d0 = 256 * (chn >> 7) + 128 * bj + (chn & 127); }
; #pragma unroll
;         for (int j = 0; j < 8; ++j) { const int n = (lane >> 3) + 8 * j; const LAS float* sp = scr + (8 * c8) * 65 + n;
;             v4u o; o.x = pk2(sp[0 * 65], sp[1 * 65]); o.y = pk2(sp[2 * 65], sp[3 * 65]); o.z = pk2(sp[4 * 65], sp[5 * 65]); o.w = pk2(sp[6 * 65], sp[7 * 65]);
;             *(v4u*)(WT + (size_t)(d0 + n) * K + k0 + 8 * c8) = o; }
;         LDS_WAIT(); asm volatile("" ::: "memory");
.LBB0_3279:
	s_or_b64 exec, exec, s[8:9]
	s_waitcnt vmcnt(0)
	ds_write2_b32 v79, v4, v5 offset1:1
	ds_write2_b32 v79, v6, v7 offset0:2 offset1:3
	v_add_u32_e32 v4, 0x410, v79
	ds_write2_b32 v4, v12, v13 offset1:1
	v_add_u32_e32 v4, 0x418, v79
	ds_write2_b32 v4, v14, v15 offset1:1
	v_add_u32_e32 v4, 0x820, v79
	ds_write2_b32 v4, v8, v9 offset1:1
	v_add_u32_e32 v4, 0x828, v79
	ds_write2_b32 v4, v10, v11 offset1:1
	v_add_u32_e32 v4, 0xc30, v79
	ds_write2_b32 v4, v20, v21 offset1:1
	v_add_u32_e32 v4, 0xc38, v79
	ds_write2_b32 v4, v22, v23 offset1:1
	v_add_u32_e32 v4, 0x1040, v79
	ds_write2_b32 v4, v16, v17 offset1:1
	v_add_u32_e32 v4, 0x1048, v79
	ds_write2_b32 v4, v18, v19 offset1:1
	v_add_u32_e32 v4, 0x1450, v79
	ds_write2_b32 v4, v28, v29 offset1:1
	v_add_u32_e32 v4, 0x1458, v79
	ds_write2_b32 v4, v30, v31 offset1:1
	v_add_u32_e32 v4, 0x1860, v79
	ds_write2_b32 v4, v24, v25 offset1:1
	v_add_u32_e32 v4, 0x1868, v79
	ds_write2_b32 v4, v26, v27 offset1:1
	v_add_u32_e32 v4, 0x1c70, v79
	ds_write2_b32 v4, v36, v37 offset1:1
	v_add_u32_e32 v4, 0x1c78, v79
	ds_write2_b32 v4, v38, v39 offset1:1
	v_add_u32_e32 v4, 0x2080, v79
	ds_write2_b32 v4, v32, v33 offset1:1
	v_add_u32_e32 v4, 0x2088, v79
	ds_write2_b32 v4, v34, v35 offset1:1
	v_add_u32_e32 v4, 0x2490, v79
	ds_write2_b32 v4, v44, v45 offset1:1
	v_add_u32_e32 v4, 0x2498, v79
	ds_write2_b32 v4, v46, v47 offset1:1
	v_add_u32_e32 v4, 0x28a0, v79
	ds_write2_b32 v4, v40, v41 offset1:1
	v_add_u32_e32 v4, 0x28a8, v79
	ds_write2_b32 v4, v42, v43 offset1:1
	v_add_u32_e32 v4, 0x2cb0, v79
	ds_write2_b32 v4, v52, v53 offset1:1
	v_add_u32_e32 v4, 0x2cb8, v79
	ds_write2_b32 v4, v54, v55 offset1:1
	v_add_u32_e32 v4, 0x30c0, v79
	ds_write2_b32 v4, v48, v49 offset1:1
	v_add_u32_e32 v4, 0x30c8, v79
	ds_write2_b32 v4, v50, v51 offset1:1
	v_add_u32_e32 v4, 0x34d0, v79
	ds_write2_b32 v4, v60, v61 offset1:1
	v_add_u32_e32 v4, 0x34d8, v79
	ds_write2_b32 v4, v62, v63 offset1:1
	v_add_u32_e32 v4, 0x38e0, v79
	ds_write2_b32 v4, v56, v57 offset1:1
	v_add_u32_e32 v4, 0x38e8, v79
	ds_write2_b32 v4, v58, v59 offset1:1
	v_add_u32_e32 v4, 0x3cf0, v79
	ds_write2_b32 v4, v64, v65 offset1:1
	v_add_u32_e32 v4, 0x3cf8, v79
	ds_write2_b32 v4, v66, v67 offset1:1
	s_waitcnt lgkmcnt(0)
	ds_read2_b32 v[12:13], v78 offset1:8
	ds_read2_b32 v[14:15], v78 offset0:65 offset1:73
	ds_read2_b32 v[16:17], v78 offset0:130 offset1:138
	ds_read2_b32 v[18:19], v78 offset0:195 offset1:203
	v_add_u32_e32 v30, 0x400, v78
	s_waitcnt lgkmcnt(3)
	s_nop 1
	s_waitcnt lgkmcnt(2)
	s_nop 0
	ds_read2_b32 v[20:21], v30 offset0:4 offset1:12
	s_nop 1
	ds_read2_b32 v[22:23], v30 offset0:69 offset1:77
	v_cvt_pk_bf16_f32 v8, v12, v14
	s_waitcnt lgkmcnt(3)
	s_nop 1
	s_waitcnt lgkmcnt(2)
	s_nop 0
	ds_read2_b32 v[24:25], v30 offset0:134 offset1:142
	s_nop 1
	ds_read2_b32 v[26:27], v30 offset0:199 offset1:207
	v_cvt_pk_bf16_f32 v9, v16, v18
	s_waitcnt lgkmcnt(3)
	s_nop 1
	s_waitcnt lgkmcnt(2)
	s_nop 2
	v_cvt_pk_bf16_f32 v10, v20, v22
	s_waitcnt lgkmcnt(1)
	s_nop 1
	s_waitcnt lgkmcnt(0)
	s_nop 2
	s_add_i32 s18, s18, s14
	v_cvt_pk_bf16_f32 v11, v24, v26
	v_add_u32_e32 v6, s18, v77
	s_ashr_i32 s7, s6, 31
	v_ashrrev_i32_e32 v7, 31, v6
	v_lshl_add_u64 v[4:5], s[6:7], 1, v[70:71]
	v_lshlrev_b64 v[28:29], 10, v[6:7]
	v_lshl_add_u64 v[28:29], v[4:5], 0, v[28:29]
	v_bfe_u32 v7, v13, 16, 1
	global_store_dwordx4 v[28:29], v[8:11], off
	v_add3_u32 v7, v13, v7, s16
	v_lshrrev_b32_e32 v7, 16, v7
	v_bfe_u32 v8, v15, 16, 1
	v_add3_u32 v8, v15, v8, s16
	v_and_or_b32 v8, v8, s17, v7
	s_nop 4
	v_cvt_pk_bf16_f32 v9, v17, v19
	s_nop 4
	v_cvt_pk_bf16_f32 v10, v21, v23
	s_nop 0
	v_add_u32_e32 v12, 8, v6
	s_nop 1
	v_ashrrev_i32_e32 v13, 31, v12
	s_nop 1
	v_lshlrev_b64 v[12:13], 10, v[12:13]
	v_cvt_pk_bf16_f32 v11, v25, v27
	ds_read2_b32 v[14:15], v78 offset0:16 offset1:24
	v_lshl_add_u64 v[12:13], v[4:5], 0, v[12:13]
	global_store_dwordx4 v[12:13], v[8:11], off
	ds_read2_b32 v[12:13], v78 offset0:81 offset1:89
	ds_read2_b32 v[16:17], v78 offset0:146 offset1:154
	ds_read2_b32 v[18:19], v78 offset0:211 offset1:219
	s_waitcnt lgkmcnt(3)
	s_nop 1
	s_waitcnt lgkmcnt(2)
	s_nop 0
	ds_read2_b32 v[20:21], v30 offset0:20 offset1:28
	s_nop 1
	ds_read2_b32 v[22:23], v30 offset0:85 offset1:93
	v_cvt_pk_bf16_f32 v8, v14, v12
	s_waitcnt lgkmcnt(3)
; #define LAS __attribute__((address_space(3)))
; #define LDS_WAIT() asm volatile("s_waitcnt lgkmcnt(0)" ::: "memory")
; __device__ __forceinline__ unsigned pk2(float lo, float hi) { return f2bf(lo) | (f2bf(hi) << 16); }
;     ...
;         for (int j = 0; j < 8; ++j) { const int n = (lane >> 3) + 8 * j; const LAS float* sp = scr + (8 * c8) * 65 + n;
;             v4u o; o.x = pk2(sp[0 * 65], sp[1 * 65]); o.y = pk2(sp[2 * 65], sp[3 * 65]); o.z = pk2(sp[4 * 65], sp[5 * 65]); o.w = pk2(sp[6 * 65], sp[7 * 65]);
;             *(v4u*)(WT + (size_t)(d0 + n) * K + k0 + 8 * c8) = o; }
;         LDS_WAIT(); asm volatile("" ::: "memory");
	s_nop 1
	s_waitcnt lgkmcnt(2)
	s_nop 0
	ds_read2_b32 v[24:25], v30 offset0:150 offset1:158
	s_nop 1
	ds_read2_b32 v[26:27], v30 offset0:215 offset1:223
	v_cvt_pk_bf16_f32 v9, v16, v18
	s_waitcnt lgkmcnt(3)
	s_nop 1
	s_waitcnt lgkmcnt(2)
	s_nop 2
	v_cvt_pk_bf16_f32 v10, v20, v22
	s_waitcnt lgkmcnt(1)
	s_nop 0
	v_add_u32_e32 v28, 16, v6
	s_nop 0
	s_waitcnt lgkmcnt(0)
	s_nop 0
	v_ashrrev_i32_e32 v29, 31, v28
	s_nop 1
	v_lshlrev_b64 v[28:29], 10, v[28:29]
	v_cvt_pk_bf16_f32 v11, v24, v26
	v_lshl_add_u64 v[28:29], v[4:5], 0, v[28:29]
	v_bfe_u32 v7, v15, 16, 1
	global_store_dwordx4 v[28:29], v[8:11], off
	v_add3_u32 v7, v15, v7, s16
	v_lshrrev_b32_e32 v7, 16, v7
	v_bfe_u32 v8, v13, 16, 1
	v_add3_u32 v8, v13, v8, s16
	v_and_or_b32 v8, v8, s17, v7
	s_nop 4
	v_cvt_pk_bf16_f32 v9, v17, v19
	s_nop 4
	v_cvt_pk_bf16_f32 v10, v21, v23
	s_nop 0
	v_add_u32_e32 v12, 24, v6
	s_nop 1
	v_ashrrev_i32_e32 v13, 31, v12
	s_nop 1
	v_lshlrev_b64 v[12:13], 10, v[12:13]
	v_cvt_pk_bf16_f32 v11, v25, v27
	ds_read2_b32 v[14:15], v78 offset0:32 offset1:40
	v_lshl_add_u64 v[12:13], v[4:5], 0, v[12:13]
	global_store_dwordx4 v[12:13], v[8:11], off
	ds_read2_b32 v[12:13], v78 offset0:97 offset1:105
	ds_read2_b32 v[16:17], v78 offset0:162 offset1:170
	ds_read2_b32 v[18:19], v78 offset0:227 offset1:235
	s_waitcnt lgkmcnt(3)
	s_nop 1
	s_waitcnt lgkmcnt(2)
	s_nop 0
	ds_read2_b32 v[20:21], v30 offset0:36 offset1:44
	s_nop 1
	ds_read2_b32 v[22:23], v30 offset0:101 offset1:109
	v_cvt_pk_bf16_f32 v8, v14, v12
	s_waitcnt lgkmcnt(3)
	s_nop 1
	s_waitcnt lgkmcnt(2)
	s_nop 0
	ds_read2_b32 v[24:25], v30 offset0:166 offset1:174
	s_nop 1
	ds_read2_b32 v[26:27], v30 offset0:231 offset1:239
	v_cvt_pk_bf16_f32 v9, v16, v18
	s_waitcnt lgkmcnt(3)
	s_nop 1
	s_waitcnt lgkmcnt(2)
	s_nop 2
	v_cvt_pk_bf16_f32 v10, v20, v22
	s_waitcnt lgkmcnt(1)
	s_nop 0
	v_add_u32_e32 v28, 32, v6
	s_nop 0
	s_waitcnt lgkmcnt(0)
	s_nop 0
	v_ashrrev_i32_e32 v29, 31, v28
	s_nop 1
	v_lshlrev_b64 v[28:29], 10, v[28:29]
	v_cvt_pk_bf16_f32 v11, v24, v26
	v_lshl_add_u64 v[28:29], v[4:5], 0, v[28:29]
	v_bfe_u32 v7, v15, 16, 1
	global_store_dwordx4 v[28:29], v[8:11], off
	v_add3_u32 v7, v15, v7, s16
	v_lshrrev_b32_e32 v7, 16, v7
	v_bfe_u32 v8, v13, 16, 1
	v_add3_u32 v8, v13, v8, s16
	v_and_or_b32 v8, v8, s17, v7
	s_nop 4
	v_cvt_pk_bf16_f32 v9, v17, v19
	s_nop 4
	v_cvt_pk_bf16_f32 v10, v21, v23
	s_nop 0
	v_add_u32_e32 v12, 40, v6
	s_nop 1
	v_ashrrev_i32_e32 v13, 31, v12
	s_nop 1
	v_lshlrev_b64 v[12:13], 10, v[12:13]
	v_cvt_pk_bf16_f32 v11, v25, v27
	ds_read2_b32 v[14:15], v78 offset0:48 offset1:56
	v_lshl_add_u64 v[12:13], v[4:5], 0, v[12:13]
	global_store_dwordx4 v[12:13], v[8:11], off
	ds_read2_b32 v[12:13], v78 offset0:113 offset1:121
	ds_read2_b32 v[16:17], v78 offset0:178 offset1:186
	ds_read2_b32 v[18:19], v78 offset0:243 offset1:251
	s_waitcnt lgkmcnt(3)
	s_nop 1
	s_waitcnt lgkmcnt(2)
	s_nop 0
	ds_read2_b32 v[20:21], v30 offset0:52 offset1:60
	s_nop 1
	ds_read2_b32 v[22:23], v30 offset0:117 offset1:125
	v_cvt_pk_bf16_f32 v8, v14, v12
	s_waitcnt lgkmcnt(3)
	s_nop 1
	s_waitcnt lgkmcnt(2)
	s_nop 0
	ds_read2_b32 v[24:25], v30 offset0:182 offset1:190
	s_nop 1
	ds_read2_b32 v[26:27], v30 offset0:247 offset1:255
	v_cvt_pk_bf16_f32 v9, v16, v18
	s_waitcnt lgkmcnt(3)
	s_nop 1
	s_waitcnt lgkmcnt(2)
	s_nop 2
	v_cvt_pk_bf16_f32 v10, v20, v22
	s_waitcnt lgkmcnt(1)
	s_nop 0
	v_add_u32_e32 v28, 48, v6
	s_nop 0
	s_waitcnt lgkmcnt(0)
	s_nop 0
	v_ashrrev_i32_e32 v29, 31, v28
	s_nop 1
	v_lshlrev_b64 v[28:29], 10, v[28:29]
	v_cvt_pk_bf16_f32 v11, v24, v26
	v_lshl_add_u64 v[28:29], v[4:5], 0, v[28:29]
	v_bfe_u32 v7, v15, 16, 1
	global_store_dwordx4 v[28:29], v[8:11], off
	v_add3_u32 v7, v15, v7, s16
	v_lshrrev_b32_e32 v7, 16, v7
	v_bfe_u32 v8, v13, 16, 1
	v_add3_u32 v8, v13, v8, s16
	v_and_or_b32 v8, v8, s17, v7
	s_nop 4
	v_cvt_pk_bf16_f32 v9, v17, v19
	s_nop 4
	v_cvt_pk_bf16_f32 v10, v21, v23
	s_nop 4
	v_add_u32_e32 v6, 56, v6
	v_cvt_pk_bf16_f32 v11, v25, v27
	v_ashrrev_i32_e32 v7, 31, v6
	v_lshlrev_b64 v[6:7], 10, v[6:7]
	v_lshl_add_u64 v[4:5], v[4:5], 0, v[6:7]
	global_store_dwordx4 v[4:5], v[8:11], off
	s_waitcnt lgkmcnt(0)
	s_add_i32 s13, s13, s86
	s_add_i32 s14, s14, s15
	s_cmpk_lt_i32 s13, 0x100
	s_cbranch_scc0 .LBB0_3312

; #define LAS __attribute__((address_space(3)))
; #define LDS_WAIT() asm volatile("s_waitcnt lgkmcnt(0)" ::: "memory")
;     ...
;         const int kb = it / nblk, nb = it % nblk, k0 = 64 * kb, n0 = 64 * nb, nq = (lane & 15) * 4, kr = lane >> 4; const bool ok = (n0 + nq) < N;
;         f32x4 v[16];
; #pragma unroll
;         for (int i = 0; i < 16; ++i) v[i] = ok ? __builtin_nontemporal_load((const f32x4*)(W + (size_t)(k0 + 4 * i + kr) * N + n0 + nq)) : (f32x4){0.f, 0.f, 0.f, 0.f};
;         if (gain) {
; #pragma unroll
;             for (int i = 0; i < 16; ++i) v[i] *= gain[k0 + 4 * i + kr]; }
; #pragma unroll
;         for (int i = 0; i < 16; ++i) { LAS float* d = scr + (4 * i + kr) * 65 + nq; d[0] = v[i].x; d[1] = v[i].y; d[2] = v[i].z; d[3] = v[i].w; }
;         LDS_WAIT(); asm volatile("" ::: "memory");
;         const int c8 = lane & 7; int d0 = n0;
;         if (ffnmap) { const int bj = n0 >= FFH ? 1 : 0, chn = n0 - FFH * bj; d0 = 256 * (chn >> 7) + 128 * bj + (chn & 127); }
.LBB0_3373:
	s_or_b64 exec, exec, s[12:13]
	v_ashrrev_i32_e32 v73, 31, v72
	v_lshl_add_u64 v[114:115], v[72:73], 2, s[6:7]
	global_load_dword v72, v[114:115], off
	s_mulk_i32 s22, 0xff50
	s_add_i32 s11, s21, s22
	s_cmpk_gt_i32 s11, 0x57
	s_cselect_b32 s11, 0xffffea00, 0
	s_cselect_b32 s12, 0x80, 0
	s_add_i32 s11, s11, s16
	s_add_i32 s11, s11, s9
	s_lshl_b32 s9, s11, 1
	s_and_b32 s10, s10, 64
	s_and_b32 s9, s9, 0xffffff00
	s_or_b32 s10, s10, s12
	s_or_b32 s10, s10, s9
	s_ashr_i32 s9, s8, 31
	s_add_i32 s21, s21, s15
	s_add_i32 s16, s16, s17
	s_cmpk_lt_i32 s21, 0x1600
	s_waitcnt vmcnt(0)
	v_pk_mul_f32 v[100:101], v[4:5], v[72:73] op_sel_hi:[1,0]
	global_load_dword v4, v[114:115], off offset:16
	v_pk_mul_f32 v[98:99], v[6:7], v[72:73] op_sel_hi:[1,0]
	global_load_dword v6, v[114:115], off offset:128
	s_waitcnt vmcnt(1)
	v_pk_mul_f32 v[90:91], v[14:15], v[4:5] op_sel_hi:[1,0]
	v_pk_mul_f32 v[96:97], v[12:13], v[4:5] op_sel_hi:[1,0]
	global_load_dword v4, v[114:115], off offset:32
	global_load_dword v14, v[114:115], off offset:160
	s_waitcnt vmcnt(1)
	v_pk_mul_f32 v[86:87], v[10:11], v[4:5] op_sel_hi:[1,0]
	v_pk_mul_f32 v[92:93], v[8:9], v[4:5] op_sel_hi:[1,0]
	global_load_dword v4, v[114:115], off offset:48
	global_load_dword v10, v[114:115], off offset:144
	s_waitcnt vmcnt(2)
	v_pk_mul_f32 v[12:13], v[46:47], v[14:15] op_sel_hi:[1,0]
	v_pk_mul_f32 v[14:15], v[44:45], v[14:15] op_sel_hi:[1,0]
	s_waitcnt vmcnt(1)
	v_pk_mul_f32 v[82:83], v[22:23], v[4:5] op_sel_hi:[1,0]
	v_pk_mul_f32 v[88:89], v[20:21], v[4:5] op_sel_hi:[1,0]
	global_load_dword v4, v[114:115], off offset:64
	global_load_dword v22, v[114:115], off offset:192
	s_waitcnt vmcnt(1)
	v_pk_mul_f32 v[78:79], v[18:19], v[4:5] op_sel_hi:[1,0]
	v_pk_mul_f32 v[84:85], v[16:17], v[4:5] op_sel_hi:[1,0]
	global_load_dword v4, v[114:115], off offset:80
	global_load_dword v18, v[114:115], off offset:176
	s_waitcnt vmcnt(2)
	v_pk_mul_f32 v[20:21], v[54:55], v[22:23] op_sel_hi:[1,0]
	v_pk_mul_f32 v[22:23], v[52:53], v[22:23] op_sel_hi:[1,0]
	s_waitcnt vmcnt(1)
	v_pk_mul_f32 v[74:75], v[30:31], v[4:5] op_sel_hi:[1,0]
	v_pk_mul_f32 v[80:81], v[28:29], v[4:5] op_sel_hi:[1,0]
	global_load_dword v4, v[114:115], off offset:96
	global_load_dword v30, v[114:115], off offset:224
	s_waitcnt vmcnt(2)
	v_pk_mul_f32 v[16:17], v[58:59], v[18:19] op_sel_hi:[1,0]
	v_pk_mul_f32 v[18:19], v[56:57], v[18:19] op_sel_hi:[1,0]
	s_waitcnt vmcnt(1)
	v_pk_mul_f32 v[72:73], v[26:27], v[4:5] op_sel_hi:[1,0]
	v_pk_mul_f32 v[76:77], v[24:25], v[4:5] op_sel_hi:[1,0]
	global_load_dword v4, v[114:115], off offset:112
	global_load_dword v26, v[114:115], off offset:208
	s_waitcnt vmcnt(2)
	v_pk_mul_f32 v[28:29], v[62:63], v[30:31] op_sel_hi:[1,0]
	v_pk_mul_f32 v[30:31], v[60:61], v[30:31] op_sel_hi:[1,0]
	s_waitcnt vmcnt(1)
	v_pk_mul_f32 v[38:39], v[38:39], v[4:5] op_sel_hi:[1,0]
	v_pk_mul_f32 v[36:37], v[36:37], v[4:5] op_sel_hi:[1,0]
	v_pk_mul_f32 v[4:5], v[34:35], v[6:7] op_sel_hi:[1,0]
	v_pk_mul_f32 v[6:7], v[32:33], v[6:7] op_sel_hi:[1,0]
	v_lshl_add_u64 v[32:33], v[94:95], 2, s[6:7]
	global_load_dword v34, v[32:33], off
	ds_write2_b32 v112, v100, v101 offset1:1
	ds_write2_b32 v112, v98, v99 offset0:2 offset1:3
	v_pk_mul_f32 v[8:9], v[50:51], v[10:11] op_sel_hi:[1,0]
	v_pk_mul_f32 v[10:11], v[48:49], v[10:11] op_sel_hi:[1,0]
	s_waitcnt vmcnt(1)
	v_pk_mul_f32 v[24:25], v[66:67], v[26:27] op_sel_hi:[1,0]
	v_pk_mul_f32 v[26:27], v[64:65], v[26:27] op_sel_hi:[1,0]
	s_waitcnt vmcnt(0)
	v_pk_mul_f32 v[32:33], v[42:43], v[34:35] op_sel_hi:[1,0]
	v_pk_mul_f32 v[34:35], v[40:41], v[34:35] op_sel_hi:[1,0]
	v_add_u32_e32 v40, 0x410, v112
	ds_write2_b32 v40, v96, v97 offset1:1
	v_add_u32_e32 v40, 0x418, v112
	ds_write2_b32 v40, v90, v91 offset1:1
	v_add_u32_e32 v40, 0x820, v112
	ds_write2_b32 v40, v92, v93 offset1:1
	v_add_u32_e32 v40, 0x828, v112
	ds_write2_b32 v40, v86, v87 offset1:1
	v_add_u32_e32 v40, 0xc30, v112
	ds_write2_b32 v40, v88, v89 offset1:1
	v_add_u32_e32 v40, 0xc38, v112
	ds_write2_b32 v40, v82, v83 offset1:1
	v_add_u32_e32 v40, 0x1040, v112
	ds_write2_b32 v40, v84, v85 offset1:1
	v_add_u32_e32 v40, 0x1048, v112
	ds_write2_b32 v40, v78, v79 offset1:1
	v_add_u32_e32 v40, 0x1450, v112
	ds_write2_b32 v40, v80, v81 offset1:1
	v_add_u32_e32 v40, 0x1458, v112
	ds_write2_b32 v40, v74, v75 offset1:1
	v_add_u32_e32 v40, 0x1860, v112
	ds_write2_b32 v40, v76, v77 offset1:1
	v_add_u32_e32 v40, 0x1868, v112
	ds_write2_b32 v40, v72, v73 offset1:1
	v_add_u32_e32 v40, 0x1c70, v112
	ds_write2_b32 v40, v36, v37 offset1:1
	v_add_u32_e32 v36, 0x1c78, v112
	ds_write2_b32 v36, v38, v39 offset1:1
	v_add_u32_e32 v36, 0x2080, v112
	ds_write2_b32 v36, v6, v7 offset1:1
	v_add_u32_e32 v6, 0x2088, v112
	ds_write2_b32 v6, v4, v5 offset1:1
	v_add_u32_e32 v4, 0x2490, v112
	ds_write2_b32 v4, v10, v11 offset1:1
	v_add_u32_e32 v4, 0x2498, v112
	ds_write2_b32 v4, v8, v9 offset1:1
	v_add_u32_e32 v4, 0x28a0, v112
	ds_write2_b32 v4, v14, v15 offset1:1
	v_add_u32_e32 v4, 0x28a8, v112
	ds_write2_b32 v4, v12, v13 offset1:1
	v_add_u32_e32 v4, 0x2cb0, v112
	ds_write2_b32 v4, v18, v19 offset1:1
	v_add_u32_e32 v4, 0x2cb8, v112
	ds_write2_b32 v4, v16, v17 offset1:1
	v_add_u32_e32 v4, 0x30c0, v112
	ds_write2_b32 v4, v22, v23 offset1:1
	v_add_u32_e32 v4, 0x30c8, v112
	ds_write2_b32 v4, v20, v21 offset1:1
	v_add_u32_e32 v4, 0x34d0, v112
	ds_write2_b32 v4, v26, v27 offset1:1
	v_add_u32_e32 v4, 0x34d8, v112
	ds_write2_b32 v4, v24, v25 offset1:1
	v_add_u32_e32 v4, 0x38e0, v112
	ds_write2_b32 v4, v30, v31 offset1:1
	v_add_u32_e32 v4, 0x38e8, v112
	ds_write2_b32 v4, v28, v29 offset1:1
	v_add_u32_e32 v4, 0x3cf0, v112
	ds_write2_b32 v4, v34, v35 offset1:1
	v_add_u32_e32 v4, 0x3cf8, v112
	ds_write2_b32 v4, v32, v33 offset1:1
	s_waitcnt lgkmcnt(0)
; #define LAS __attribute__((address_space(3)))
; #define LDS_WAIT() asm volatile("s_waitcnt lgkmcnt(0)" ::: "memory")
; __device__ __forceinline__ unsigned pk2(float lo, float hi) { return f2bf(lo) | (f2bf(hi) << 16); }
;     ...
;         if (ffnmap) { const int bj = n0 >= FFH ? 1 : 0, chn = n0 - FFH * bj; d0 = 256 * (chn >> 7) + 128 * bj + (chn & 127); }
; #pragma unroll
;         for (int j = 0; j < 8; ++j) { const int n = (lane >> 3) + 8 * j; const LAS float* sp = scr + (8 * c8) * 65 + n;
;             v4u o; o.x = pk2(sp[0 * 65], sp[1 * 65]); o.y = pk2(sp[2 * 65], sp[3 * 65]); o.z = pk2(sp[4 * 65], sp[5 * 65]); o.w = pk2(sp[6 * 65], sp[7 * 65]);
;             *(v4u*)(WT + (size_t)(d0 + n) * K + k0 + 8 * c8) = o; }
;         LDS_WAIT(); asm volatile("" ::: "memory");
	ds_read2_b32 v[6:7], v104 offset0:65 offset1:73
	ds_read2_b32 v[12:13], v104 offset1:8
	ds_read2_b32 v[14:15], v104 offset0:130 offset1:138
	ds_read2_b32 v[16:17], v104 offset0:195 offset1:203
	v_or_b32_e32 v26, s10, v103
	v_ashrrev_i32_e32 v27, 31, v26
	s_waitcnt lgkmcnt(3)
	s_nop 0
	s_waitcnt lgkmcnt(2)
	s_nop 3
	v_cvt_pk_bf16_f32 v8, v12, v6
	s_waitcnt lgkmcnt(1)
	s_nop 1
	s_waitcnt lgkmcnt(0)
	s_nop 2
	v_cvt_pk_bf16_f32 v9, v14, v16
	v_add_u32_e32 v6, 0x400, v104
	ds_read2_b32 v[18:19], v6 offset0:4 offset1:12
	ds_read2_b32 v[20:21], v6 offset0:69 offset1:77
	ds_read2_b32 v[22:23], v6 offset0:134 offset1:142
	ds_read2_b32 v[24:25], v6 offset0:199 offset1:207
	v_lshl_add_u64 v[4:5], s[8:9], 1, v[70:71]
	v_lshlrev_b64 v[26:27], 12, v[26:27]
	s_waitcnt lgkmcnt(3)
	s_nop 1
	s_waitcnt lgkmcnt(2)
	s_nop 2
	v_cvt_pk_bf16_f32 v10, v18, v20
	s_waitcnt lgkmcnt(1)
	s_nop 1
	s_waitcnt lgkmcnt(0)
	s_nop 2
	v_cvt_pk_bf16_f32 v11, v22, v24
	v_lshl_add_u64 v[26:27], v[4:5], 0, v[26:27]
	global_store_dwordx4 v[26:27], v[8:11], off
	v_or_b32_e32 v12, s10, v105
	v_or_b32_e32 v28, s10, v106
	s_nop 4
	v_cvt_pk_bf16_f32 v8, v13, v7
	s_nop 4
	v_cvt_pk_bf16_f32 v9, v15, v17
	s_nop 4
	v_cvt_pk_bf16_f32 v10, v19, v21
	s_nop 2
	v_ashrrev_i32_e32 v13, 31, v12
	s_nop 1
	v_lshlrev_b64 v[12:13], 12, v[12:13]
	v_cvt_pk_bf16_f32 v11, v23, v25
	v_lshl_add_u64 v[12:13], v[4:5], 0, v[12:13]
	global_store_dwordx4 v[12:13], v[8:11], off
	ds_read2_b32 v[12:13], v104 offset0:81 offset1:89
	ds_read2_b32 v[14:15], v104 offset0:16 offset1:24
	ds_read2_b32 v[16:17], v104 offset0:146 offset1:154
	ds_read2_b32 v[18:19], v104 offset0:211 offset1:219
	ds_read2_b32 v[20:21], v6 offset0:20 offset1:28
	ds_read2_b32 v[22:23], v6 offset0:85 offset1:93
	ds_read2_b32 v[24:25], v6 offset0:150 offset1:158
	ds_read2_b32 v[26:27], v6 offset0:215 offset1:223
	s_waitcnt lgkmcnt(7)
	s_nop 0
	s_waitcnt lgkmcnt(6)
	s_nop 3
	v_cvt_pk_bf16_f32 v8, v14, v12
	s_waitcnt lgkmcnt(5)
	s_nop 1
	s_waitcnt lgkmcnt(4)
	s_nop 2
	v_cvt_pk_bf16_f32 v9, v16, v18
	s_waitcnt lgkmcnt(3)
	s_nop 1
	s_waitcnt lgkmcnt(2)
	s_nop 2
	v_cvt_pk_bf16_f32 v10, v20, v22
	s_waitcnt lgkmcnt(1)
	s_nop 1
	s_waitcnt lgkmcnt(0)
	s_nop 0
	v_ashrrev_i32_e32 v29, 31, v28
	s_nop 1
	v_lshlrev_b64 v[28:29], 12, v[28:29]
	v_cvt_pk_bf16_f32 v11, v24, v26
	v_lshl_add_u64 v[28:29], v[4:5], 0, v[28:29]
	v_bfe_u32 v7, v15, 16, 1
	global_store_dwordx4 v[28:29], v[8:11], off
	v_add3_u32 v7, v15, v7, s19
	v_lshrrev_b32_e32 v7, 16, v7
	v_bfe_u32 v8, v13, 16, 1
	v_add3_u32 v8, v13, v8, s19
	v_and_or_b32 v8, v8, s20, v7
	s_nop 4
	v_cvt_pk_bf16_f32 v9, v17, v19
	s_nop 4
	v_cvt_pk_bf16_f32 v10, v21, v23
	s_nop 0
	v_or_b32_e32 v12, s10, v107
	s_nop 1
	v_ashrrev_i32_e32 v13, 31, v12
	s_nop 1
	v_lshlrev_b64 v[12:13], 12, v[12:13]
	v_cvt_pk_bf16_f32 v11, v25, v27
	v_lshl_add_u64 v[12:13], v[4:5], 0, v[12:13]
	global_store_dwordx4 v[12:13], v[8:11], off
	ds_read2_b32 v[12:13], v104 offset0:97 offset1:105
	ds_read2_b32 v[14:15], v104 offset0:32 offset1:40
	ds_read2_b32 v[16:17], v104 offset0:162 offset1:170
	ds_read2_b32 v[18:19], v104 offset0:227 offset1:235
	ds_read2_b32 v[20:21], v6 offset0:36 offset1:44
	ds_read2_b32 v[22:23], v6 offset0:101 offset1:109
	ds_read2_b32 v[24:25], v6 offset0:166 offset1:174
	ds_read2_b32 v[26:27], v6 offset0:231 offset1:239
	s_waitcnt lgkmcnt(7)
	s_nop 0
	s_waitcnt lgkmcnt(6)
	s_nop 3
	v_cvt_pk_bf16_f32 v8, v14, v12
	s_waitcnt lgkmcnt(5)
	s_nop 1
	s_waitcnt lgkmcnt(4)
	s_nop 2
	v_cvt_pk_bf16_f32 v9, v16, v18
	s_waitcnt lgkmcnt(3)
	s_nop 1
	s_waitcnt lgkmcnt(2)
	s_nop 2
	v_cvt_pk_bf16_f32 v10, v20, v22
	s_waitcnt lgkmcnt(1)
	s_nop 0
	v_or_b32_e32 v28, s10, v108
	s_nop 0
	s_waitcnt lgkmcnt(0)
	s_nop 0
	v_ashrrev_i32_e32 v29, 31, v28
	s_nop 1
	v_lshlrev_b64 v[28:29], 12, v[28:29]
	v_cvt_pk_bf16_f32 v11, v24, v26
	v_lshl_add_u64 v[28:29], v[4:5], 0, v[28:29]
	v_bfe_u32 v7, v15, 16, 1
	global_store_dwordx4 v[28:29], v[8:11], off
	v_add3_u32 v7, v15, v7, s19
	v_lshrrev_b32_e32 v7, 16, v7
	v_bfe_u32 v8, v13, 16, 1
	v_add3_u32 v8, v13, v8, s19
	v_and_or_b32 v8, v8, s20, v7
	s_nop 4
	v_cvt_pk_bf16_f32 v9, v17, v19
	s_nop 4
	v_cvt_pk_bf16_f32 v10, v21, v23
	s_nop 0
	v_or_b32_e32 v12, s10, v109
	s_nop 1
	v_ashrrev_i32_e32 v13, 31, v12
	s_nop 1
	v_lshlrev_b64 v[12:13], 12, v[12:13]
	v_cvt_pk_bf16_f32 v11, v25, v27
	v_lshl_add_u64 v[12:13], v[4:5], 0, v[12:13]
	global_store_dwordx4 v[12:13], v[8:11], off
	ds_read2_b32 v[12:13], v104 offset0:48 offset1:56
	ds_read2_b32 v[14:15], v104 offset0:113 offset1:121
	ds_read2_b32 v[16:17], v104 offset0:178 offset1:186
	ds_read2_b32 v[18:19], v104 offset0:243 offset1:251
	ds_read2_b32 v[20:21], v6 offset0:52 offset1:60
	ds_read2_b32 v[22:23], v6 offset0:117 offset1:125
	ds_read2_b32 v[24:25], v6 offset0:182 offset1:190
	ds_read2_b32 v[26:27], v6 offset0:247 offset1:255
	s_waitcnt lgkmcnt(7)
	s_nop 1
	s_waitcnt lgkmcnt(6)
	s_nop 2
	v_cvt_pk_bf16_f32 v8, v12, v14
	s_waitcnt lgkmcnt(5)
	s_nop 1
	s_waitcnt lgkmcnt(4)
	s_nop 2
	v_cvt_pk_bf16_f32 v9, v16, v18
	s_waitcnt lgkmcnt(3)
	s_nop 1
	s_waitcnt lgkmcnt(2)
	s_nop 2
	s_waitcnt lgkmcnt(1)
	s_nop 0
	v_cvt_pk_bf16_f32 v10, v20, v22
	s_nop 0
	s_waitcnt lgkmcnt(0)
	s_nop 2
	v_cvt_pk_bf16_f32 v11, v24, v26
	v_or_b32_e32 v6, s10, v110
	v_ashrrev_i32_e32 v7, 31, v6
	v_lshlrev_b64 v[6:7], 12, v[6:7]
	v_lshl_add_u64 v[6:7], v[4:5], 0, v[6:7]
	global_store_dwordx4 v[6:7], v[8:11], off
	s_nop 4
	v_cvt_pk_bf16_f32 v6, v13, v15
	s_nop 4
	v_cvt_pk_bf16_f32 v7, v17, v19
	s_nop 4
	v_cvt_pk_bf16_f32 v8, v21, v23
	s_nop 4
	v_cvt_pk_bf16_f32 v9, v25, v27
	v_or_b32_e32 v10, s10, v111
	v_ashrrev_i32_e32 v11, 31, v10
	v_lshlrev_b64 v[10:11], 12, v[10:11]
	v_lshl_add_u64 v[4:5], v[4:5], 0, v[10:11]
	global_store_dwordx4 v[4:5], v[6:9], off
	s_waitcnt lgkmcnt(0)
	s_cbranch_scc0 .LBB0_3406

; #define LAS __attribute__((address_space(3)))
; #define LDS_WAIT() asm volatile("s_waitcnt lgkmcnt(0)" ::: "memory")
; __device__ __forceinline__ unsigned pk2(float lo, float hi) { return f2bf(lo) | (f2bf(hi) << 16); }
;     ...
;         for (int i = 0; i < 16; ++i) { LAS float* d = scr + (4 * i + kr) * 65 + nq; d[0] = v[i].x; d[1] = v[i].y; d[2] = v[i].z; d[3] = v[i].w; }
;         LDS_WAIT(); asm volatile("" ::: "memory");
;         const int c8 = lane & 7; int d0 = n0;
;         if (ffnmap) { const int bj = n0 >= FFH ? 1 : 0, chn = n0 - FFH * bj; d0 = 256 * (chn >> 7) + 128 * bj + (chn & 127); }
; #pragma unroll
;         for (int j = 0; j < 8; ++j) { const int n = (lane >> 3) + 8 * j; const LAS float* sp = scr + (8 * c8) * 65 + n;
;             v4u o; o.x = pk2(sp[0 * 65], sp[1 * 65]); o.y = pk2(sp[2 * 65], sp[3 * 65]); o.z = pk2(sp[4 * 65], sp[5 * 65]); o.w = pk2(sp[6 * 65], sp[7 * 65]);
;             *(v4u*)(WT + (size_t)(d0 + n) * K + k0 + 8 * c8) = o; }
;         LDS_WAIT(); asm volatile("" ::: "memory");
.LBB0_3408:
	s_or_b64 exec, exec, s[8:9]
	s_waitcnt vmcnt(0)
	ds_write2_b32 v79, v4, v5 offset1:1
	ds_write2_b32 v79, v6, v7 offset0:2 offset1:3
	v_add_u32_e32 v4, 0x410, v79
	ds_write2_b32 v4, v12, v13 offset1:1
	v_add_u32_e32 v4, 0x418, v79
	ds_write2_b32 v4, v14, v15 offset1:1
	v_add_u32_e32 v4, 0x820, v79
	ds_write2_b32 v4, v8, v9 offset1:1
	v_add_u32_e32 v4, 0x828, v79
	ds_write2_b32 v4, v10, v11 offset1:1
	v_add_u32_e32 v4, 0xc30, v79
	ds_write2_b32 v4, v20, v21 offset1:1
	v_add_u32_e32 v4, 0xc38, v79
	ds_write2_b32 v4, v22, v23 offset1:1
	v_add_u32_e32 v4, 0x1040, v79
	ds_write2_b32 v4, v16, v17 offset1:1
	v_add_u32_e32 v4, 0x1048, v79
	ds_write2_b32 v4, v18, v19 offset1:1
	v_add_u32_e32 v4, 0x1450, v79
	ds_write2_b32 v4, v28, v29 offset1:1
	v_add_u32_e32 v4, 0x1458, v79
	ds_write2_b32 v4, v30, v31 offset1:1
	v_add_u32_e32 v4, 0x1860, v79
	ds_write2_b32 v4, v24, v25 offset1:1
	v_add_u32_e32 v4, 0x1868, v79
	ds_write2_b32 v4, v26, v27 offset1:1
	v_add_u32_e32 v4, 0x1c70, v79
	ds_write2_b32 v4, v36, v37 offset1:1
	v_add_u32_e32 v4, 0x1c78, v79
	ds_write2_b32 v4, v38, v39 offset1:1
	v_add_u32_e32 v4, 0x2080, v79
	ds_write2_b32 v4, v32, v33 offset1:1
	v_add_u32_e32 v4, 0x2088, v79
	ds_write2_b32 v4, v34, v35 offset1:1
	v_add_u32_e32 v4, 0x2490, v79
	ds_write2_b32 v4, v44, v45 offset1:1
	v_add_u32_e32 v4, 0x2498, v79
	ds_write2_b32 v4, v46, v47 offset1:1
	v_add_u32_e32 v4, 0x28a0, v79
	ds_write2_b32 v4, v40, v41 offset1:1
	v_add_u32_e32 v4, 0x28a8, v79
	ds_write2_b32 v4, v42, v43 offset1:1
	v_add_u32_e32 v4, 0x2cb0, v79
	ds_write2_b32 v4, v52, v53 offset1:1
	v_add_u32_e32 v4, 0x2cb8, v79
	ds_write2_b32 v4, v54, v55 offset1:1
	v_add_u32_e32 v4, 0x30c0, v79
	ds_write2_b32 v4, v48, v49 offset1:1
	v_add_u32_e32 v4, 0x30c8, v79
	ds_write2_b32 v4, v50, v51 offset1:1
	v_add_u32_e32 v4, 0x34d0, v79
	ds_write2_b32 v4, v60, v61 offset1:1
	v_add_u32_e32 v4, 0x34d8, v79
	ds_write2_b32 v4, v62, v63 offset1:1
	v_add_u32_e32 v4, 0x38e0, v79
	ds_write2_b32 v4, v56, v57 offset1:1
	v_add_u32_e32 v4, 0x38e8, v79
	ds_write2_b32 v4, v58, v59 offset1:1
	v_add_u32_e32 v4, 0x3cf0, v79
	ds_write2_b32 v4, v64, v65 offset1:1
	v_add_u32_e32 v4, 0x3cf8, v79
	ds_write2_b32 v4, v66, v67 offset1:1
	s_waitcnt lgkmcnt(0)
	ds_read2_b32 v[12:13], v77 offset1:8
	ds_read2_b32 v[14:15], v77 offset0:65 offset1:73
	ds_read2_b32 v[16:17], v77 offset0:130 offset1:138
	ds_read2_b32 v[18:19], v77 offset0:195 offset1:203
	v_add_u32_e32 v30, 0x400, v77
	s_waitcnt lgkmcnt(3)
	s_nop 1
	s_waitcnt lgkmcnt(2)
	s_nop 0
	ds_read2_b32 v[20:21], v30 offset0:4 offset1:12
	s_nop 1
	ds_read2_b32 v[22:23], v30 offset0:69 offset1:77
	v_cvt_pk_bf16_f32 v8, v12, v14
	s_waitcnt lgkmcnt(3)
	s_nop 1
	s_waitcnt lgkmcnt(2)
	s_nop 0
	ds_read2_b32 v[24:25], v30 offset0:134 offset1:142
	s_nop 1
	ds_read2_b32 v[26:27], v30 offset0:199 offset1:207
	v_cvt_pk_bf16_f32 v9, v16, v18
	s_waitcnt lgkmcnt(3)
	s_nop 1
	s_waitcnt lgkmcnt(2)
	s_nop 2
	v_cvt_pk_bf16_f32 v10, v20, v22
	s_waitcnt lgkmcnt(1)
	s_nop 1
	s_waitcnt lgkmcnt(0)
	s_nop 2
	s_mul_i32 s16, s16, 0xfea00000
	s_ashr_i32 s7, s6, 31
	v_cvt_pk_bf16_f32 v11, v24, v26
	v_add_u32_e32 v6, s16, v78
	v_lshl_add_u64 v[4:5], s[6:7], 1, v[70:71]
	v_ashrrev_i32_e32 v7, 31, v6
	v_lshl_add_u64 v[28:29], v[4:5], 0, v[6:7]
	v_bfe_u32 v7, v13, 16, 1
	global_store_dwordx4 v[28:29], v[8:11], off
	v_add3_u32 v7, v13, v7, s12
	v_lshrrev_b32_e32 v7, 16, v7
	v_bfe_u32 v8, v15, 16, 1
	v_add3_u32 v8, v15, v8, s12
	v_and_or_b32 v8, v8, s13, v7
	s_nop 4
	v_cvt_pk_bf16_f32 v9, v17, v19
	s_nop 4
	v_cvt_pk_bf16_f32 v10, v21, v23
	s_nop 2
	v_add_u32_e32 v12, 0x16000, v6
	s_nop 1
	v_ashrrev_i32_e32 v13, 31, v12
	v_cvt_pk_bf16_f32 v11, v25, v27
	ds_read2_b32 v[14:15], v77 offset0:16 offset1:24
	v_lshl_add_u64 v[12:13], v[4:5], 0, v[12:13]
	global_store_dwordx4 v[12:13], v[8:11], off
	ds_read2_b32 v[12:13], v77 offset0:81 offset1:89
	ds_read2_b32 v[16:17], v77 offset0:146 offset1:154
	ds_read2_b32 v[18:19], v77 offset0:211 offset1:219
	s_waitcnt lgkmcnt(3)
	s_nop 1
	s_waitcnt lgkmcnt(2)
	s_nop 0
	ds_read2_b32 v[20:21], v30 offset0:20 offset1:28
	s_nop 1
	ds_read2_b32 v[22:23], v30 offset0:85 offset1:93
	v_cvt_pk_bf16_f32 v8, v14, v12
	s_waitcnt lgkmcnt(3)
; #define LAS __attribute__((address_space(3)))
; #define LDS_WAIT() asm volatile("s_waitcnt lgkmcnt(0)" ::: "memory")
; __device__ __forceinline__ unsigned pk2(float lo, float hi) { return f2bf(lo) | (f2bf(hi) << 16); }
;     ...
;         for (int j = 0; j < 8; ++j) { const int n = (lane >> 3) + 8 * j; const LAS float* sp = scr + (8 * c8) * 65 + n;
;             v4u o; o.x = pk2(sp[0 * 65], sp[1 * 65]); o.y = pk2(sp[2 * 65], sp[3 * 65]); o.z = pk2(sp[4 * 65], sp[5 * 65]); o.w = pk2(sp[6 * 65], sp[7 * 65]);
;             *(v4u*)(WT + (size_t)(d0 + n) * K + k0 + 8 * c8) = o; }
;         LDS_WAIT(); asm volatile("" ::: "memory");
	s_nop 1
	s_waitcnt lgkmcnt(2)
	s_nop 0
	ds_read2_b32 v[24:25], v30 offset0:150 offset1:158
	s_nop 1
	ds_read2_b32 v[26:27], v30 offset0:215 offset1:223
	v_cvt_pk_bf16_f32 v9, v16, v18
	s_waitcnt lgkmcnt(3)
	s_nop 1
	s_waitcnt lgkmcnt(2)
	s_nop 2
	v_cvt_pk_bf16_f32 v10, v20, v22
	s_waitcnt lgkmcnt(1)
	s_nop 1
	s_waitcnt lgkmcnt(0)
	s_nop 0
	v_add_u32_e32 v28, 0x2c000, v6
	s_nop 1
	v_ashrrev_i32_e32 v29, 31, v28
	v_cvt_pk_bf16_f32 v11, v24, v26
	v_lshl_add_u64 v[28:29], v[4:5], 0, v[28:29]
	v_bfe_u32 v7, v15, 16, 1
	global_store_dwordx4 v[28:29], v[8:11], off
	v_add3_u32 v7, v15, v7, s12
	v_lshrrev_b32_e32 v7, 16, v7
	v_bfe_u32 v8, v13, 16, 1
	v_add3_u32 v8, v13, v8, s12
	v_and_or_b32 v8, v8, s13, v7
	s_nop 4
	v_cvt_pk_bf16_f32 v9, v17, v19
	s_nop 4
	v_cvt_pk_bf16_f32 v10, v21, v23
	s_nop 2
	v_add_u32_e32 v12, 0x42000, v6
	s_nop 1
	v_ashrrev_i32_e32 v13, 31, v12
	v_cvt_pk_bf16_f32 v11, v25, v27
	ds_read2_b32 v[14:15], v77 offset0:32 offset1:40
	v_lshl_add_u64 v[12:13], v[4:5], 0, v[12:13]
	global_store_dwordx4 v[12:13], v[8:11], off
	ds_read2_b32 v[12:13], v77 offset0:97 offset1:105
	ds_read2_b32 v[16:17], v77 offset0:162 offset1:170
	ds_read2_b32 v[18:19], v77 offset0:227 offset1:235
	s_waitcnt lgkmcnt(3)
	s_nop 1
	s_waitcnt lgkmcnt(2)
	s_nop 0
	ds_read2_b32 v[20:21], v30 offset0:36 offset1:44
	s_nop 1
	ds_read2_b32 v[22:23], v30 offset0:101 offset1:109
	v_cvt_pk_bf16_f32 v8, v14, v12
	s_waitcnt lgkmcnt(3)
	s_nop 1
	s_waitcnt lgkmcnt(2)
	s_nop 0
	ds_read2_b32 v[24:25], v30 offset0:166 offset1:174
	s_nop 1
	ds_read2_b32 v[26:27], v30 offset0:231 offset1:239
	v_cvt_pk_bf16_f32 v9, v16, v18
	s_waitcnt lgkmcnt(3)
	s_nop 1
	s_waitcnt lgkmcnt(2)
	s_nop 2
	v_cvt_pk_bf16_f32 v10, v20, v22
	s_waitcnt lgkmcnt(1)
	s_nop 1
	s_waitcnt lgkmcnt(0)
	s_nop 0
	v_add_u32_e32 v28, 0x58000, v6
	s_nop 1
	v_ashrrev_i32_e32 v29, 31, v28
	v_cvt_pk_bf16_f32 v11, v24, v26
	v_lshl_add_u64 v[28:29], v[4:5], 0, v[28:29]
	v_bfe_u32 v7, v15, 16, 1
	global_store_dwordx4 v[28:29], v[8:11], off
	v_add3_u32 v7, v15, v7, s12
	v_lshrrev_b32_e32 v7, 16, v7
	v_bfe_u32 v8, v13, 16, 1
	v_add3_u32 v8, v13, v8, s12
	v_and_or_b32 v8, v8, s13, v7
	s_nop 4
	v_cvt_pk_bf16_f32 v9, v17, v19
	s_nop 4
	v_cvt_pk_bf16_f32 v10, v21, v23
	s_nop 2
	v_add_u32_e32 v12, 0x6e000, v6
	s_nop 1
	v_ashrrev_i32_e32 v13, 31, v12
	v_cvt_pk_bf16_f32 v11, v25, v27
	ds_read2_b32 v[14:15], v77 offset0:48 offset1:56
	v_lshl_add_u64 v[12:13], v[4:5], 0, v[12:13]
	global_store_dwordx4 v[12:13], v[8:11], off
	ds_read2_b32 v[12:13], v77 offset0:113 offset1:121
	ds_read2_b32 v[16:17], v77 offset0:178 offset1:186
	ds_read2_b32 v[18:19], v77 offset0:243 offset1:251
	s_waitcnt lgkmcnt(3)
	s_nop 1
	s_waitcnt lgkmcnt(2)
	s_nop 0
	ds_read2_b32 v[20:21], v30 offset0:52 offset1:60
	s_nop 1
	ds_read2_b32 v[22:23], v30 offset0:117 offset1:125
	v_cvt_pk_bf16_f32 v8, v14, v12
	s_waitcnt lgkmcnt(3)
	s_nop 1
	s_waitcnt lgkmcnt(2)
	s_nop 0
	ds_read2_b32 v[24:25], v30 offset0:182 offset1:190
	s_nop 1
	ds_read2_b32 v[26:27], v30 offset0:247 offset1:255
	v_cvt_pk_bf16_f32 v9, v16, v18
	s_waitcnt lgkmcnt(3)
	s_nop 1
	s_waitcnt lgkmcnt(2)
	s_nop 2
	v_cvt_pk_bf16_f32 v10, v20, v22
	s_waitcnt lgkmcnt(1)
	s_nop 1
	s_waitcnt lgkmcnt(0)
	s_nop 0
	v_add_u32_e32 v28, 0x84000, v6
	s_nop 1
	v_ashrrev_i32_e32 v29, 31, v28
	v_cvt_pk_bf16_f32 v11, v24, v26
	v_lshl_add_u64 v[28:29], v[4:5], 0, v[28:29]
	v_bfe_u32 v7, v15, 16, 1
	global_store_dwordx4 v[28:29], v[8:11], off
	v_add3_u32 v7, v15, v7, s12
	v_lshrrev_b32_e32 v7, 16, v7
	v_bfe_u32 v8, v13, 16, 1
	v_add3_u32 v8, v13, v8, s12
	v_and_or_b32 v8, v8, s13, v7
	s_nop 4
	v_cvt_pk_bf16_f32 v9, v17, v19
	s_nop 4
	v_cvt_pk_bf16_f32 v10, v21, v23
	s_nop 4
	v_add_u32_e32 v6, 0x9a000, v6
	v_cvt_pk_bf16_f32 v11, v25, v27
	v_ashrrev_i32_e32 v7, 31, v6
	v_lshl_add_u64 v[4:5], v[4:5], 0, v[6:7]
	global_store_dwordx4 v[4:5], v[8:11], off
	s_waitcnt lgkmcnt(0)
	s_add_i32 s14, s14, s15
	s_add_i32 s10, s10, s11
	s_mul_i32 s6, s15, 0xb0000
	s_cmpk_lt_i32 s14, 0xb00
	v_add_u32_e32 v78, s6, v78
	s_cbranch_scc0 .LBB0_3441

; #define LAS __attribute__((address_space(3)))
; __device__ __forceinline__ unsigned pk2(float lo, float hi) { return f2bf(lo) | (f2bf(hi) << 16); }
; __device__ __forceinline__ void sgu_spatial_mfma(const Ctx& c, const bf16* P, const float* Wsp, const float* bsp, bf16* ACT) {
;     ...
;     for (int u_ = c.vcu; u_ < (PROBE == 22 ? 2 : 1) * NB * 32 * 8; u_ += c.G) {
;         const int u = u_ & (NB * 32 * 8 - 1); const int g = u & 7, bc = u >> 3; const size_t row0 = (size_t)bc * 128;
;         __syncthreads();
; #pragma unroll
;         for (int e = 0; e < 4; ++e) { const int cc = tid + 512 * e, t = cc >> 4, s8 = cc & 15; const float* wp = Wsp + ((size_t)g * 128 + t) * 128 + s8 * 8; f32x4 a = *(const f32x4*)wp, b = *(const f32x4*)(wp + 4);
; #pragma unroll
;             for (int j = 0; j < 4; ++j) { if (s8 * 8 + j > t) a[j] = 0.f; if (s8 * 8 + 4 + j > t) b[j] = 0.f; }
;             v4u q; q.x = pk2(a[0], a[1]); q.y = pk2(a[2], a[3]); q.z = pk2(b[0], b[1]); q.w = pk2(b[2], b[3]); *(LAS v4u*)(L + WB + t * WRS + s8 * 16) = q; }
.LBB0_3579:
	s_and_b32 s69, s81, 7
	s_lshl_b32 s70, s69, 7
	v_or_b32_e32 v4, s70, v231
	v_lshlrev_b32_e32 v24, 9, v4
	v_lshl_add_u64 v[8:9], v[26:27], 0, v[24:25]
	s_waitcnt lgkmcnt(0)
	s_barrier
	global_load_dwordx4 v[4:7], v[8:9], off offset:16
	s_nop 0
	global_load_dwordx4 v[8:11], v[8:9], off
	v_mov_b32_e32 v12, s83
	v_readlane_b32 s0, v253, 52
	v_readlane_b32 s1, v253, 53
	s_lshl_b32 s68, s81, 4
	s_and_b32 s68, s68, 0x3f80
	s_lshl_b32 s82, s69, 10
	s_lshl_b32 s96, s69, 9
	s_mov_b64 s[76:77], -1
	s_waitcnt vmcnt(1)
	v_cndmask_b32_e64 v15, v4, 0, s[94:95]
	s_waitcnt vmcnt(0)
	v_cndmask_b32_e64 v14, v11, v11, s[90:91]
	v_cndmask_b32_e64 v12, v8, v12, s[90:91]
	v_cndmask_b32_e64 v13, v10, v10, s[90:91]
	v_cndmask_b32_e64 v4, v12, v8, s[16:17]
	v_cndmask_b32_e64 v8, v14, v11, s[16:17]
	v_cndmask_b32_e64 v11, v5, 0, s[0:1]
	v_readlane_b32 s0, v254, 62
	v_cndmask_b32_e64 v10, v13, v10, s[16:17]
	v_readlane_b32 s1, v254, 63
	v_cndmask_b32_e64 v9, 0, v9, s[16:17]
	v_mov_b32_e32 v12, s83
	v_cndmask_b32_e64 v5, v10, 0, s[0:1]
	v_readlane_b32 s0, v255, 0
	v_readlane_b32 s1, v255, 1
	s_nop 1
	v_cndmask_b32_e64 v10, v6, 0, s[0:1]
	v_readlane_b32 s0, v255, 2
	v_readlane_b32 s1, v255, 3
	s_nop 1
	v_cndmask_b32_e64 v6, v8, 0, s[0:1]
	s_nop 4
	v_cvt_pk_bf16_f32 v4, v4, v9
	s_nop 4
	v_cvt_pk_bf16_f32 v5, v5, v6
	s_nop 0
	v_readlane_b32 s0, v255, 4
	s_nop 1
	v_readlane_b32 s1, v255, 5
	s_nop 1
	v_cndmask_b32_e64 v7, v7, 0, s[0:1]
	v_cvt_pk_bf16_f32 v6, v15, v11
	s_nop 4
	v_cvt_pk_bf16_f32 v7, v10, v7
	ds_write_b128 v102, v[4:7]
	v_or_b32_e32 v4, s70, v91
	v_lshlrev_b32_e32 v24, 9, v4
	v_lshl_add_u64 v[8:9], v[26:27], 0, v[24:25]
	global_load_dwordx4 v[4:7], v[8:9], off offset:16
	s_nop 0
	global_load_dwordx4 v[8:11], v[8:9], off
	v_readlane_b32 s0, v254, 28
	v_readlane_b32 s1, v254, 29
	v_readlane_b32 s12, v254, 40
	v_readlane_b32 s13, v254, 41
	v_readlane_b32 s0, v254, 10
	v_readlane_b32 s1, v254, 11
	v_readlane_b32 s2, v254, 30
	v_readlane_b32 s3, v254, 31
	v_readlane_b32 s4, v254, 32
	v_readlane_b32 s5, v254, 33
	v_readlane_b32 s6, v254, 34
	v_readlane_b32 s7, v254, 35
	v_readlane_b32 s8, v254, 36
	v_readlane_b32 s9, v254, 37
	v_readlane_b32 s10, v254, 38
	v_readlane_b32 s11, v254, 39
	v_readlane_b32 s14, v254, 42
	v_readlane_b32 s15, v254, 43
	s_waitcnt vmcnt(1)
	v_cndmask_b32_e64 v15, v4, 0, s[20:21]
	s_waitcnt vmcnt(0)
	v_cndmask_b32_e64 v13, v10, v10, s[18:19]
	v_cndmask_b32_e64 v14, v11, v11, s[18:19]
	v_cndmask_b32_e64 v12, v8, v12, s[18:19]
	v_cndmask_b32_e64 v4, v12, v8, s[22:23]
	v_cndmask_b32_e64 v8, v14, v11, s[22:23]
	v_cndmask_b32_e64 v10, v13, v10, s[22:23]
	v_cndmask_b32_e64 v9, 0, v9, s[22:23]
	v_cndmask_b32_e64 v11, v5, 0, s[24:25]
	v_cndmask_b32_e64 v5, v10, 0, s[26:27]
	v_cndmask_b32_e64 v10, v6, 0, s[28:29]
	v_cndmask_b32_e64 v6, v8, 0, s[30:31]
	s_nop 4
	v_cvt_pk_bf16_f32 v4, v4, v9
	s_nop 4
	v_cvt_pk_bf16_f32 v5, v5, v6
	s_nop 4
	v_cndmask_b32_e64 v7, v7, 0, s[34:35]
	v_cvt_pk_bf16_f32 v6, v15, v11
	s_nop 4
	v_cvt_pk_bf16_f32 v7, v10, v7
	ds_write_b128 v103, v[4:7]
	v_or_b32_e32 v4, s70, v92
	v_lshlrev_b32_e32 v24, 9, v4
	v_lshl_add_u64 v[8:9], v[26:27], 0, v[24:25]
	global_load_dwordx4 v[4:7], v[8:9], off offset:16
	s_nop 0
	global_load_dwordx4 v[8:11], v[8:9], off
	v_mov_b32_e32 v12, s83
	s_waitcnt vmcnt(1)
	v_cndmask_b32_e64 v15, v4, 0, s[38:39]
	s_waitcnt vmcnt(0)
; #define LAS __attribute__((address_space(3)))
; __device__ __forceinline__ unsigned pk2(float lo, float hi) { return f2bf(lo) | (f2bf(hi) << 16); }
; __device__ __forceinline__ void sgu_spatial_mfma(const Ctx& c, const bf16* P, const float* Wsp, const float* bsp, bf16* ACT) {
;     ...
;         for (int e = 0; e < 4; ++e) { const int cc = tid + 512 * e, t = cc >> 4, s8 = cc & 15; const float* wp = Wsp + ((size_t)g * 128 + t) * 128 + s8 * 8; f32x4 a = *(const f32x4*)wp, b = *(const f32x4*)(wp + 4);
; #pragma unroll
;             for (int j = 0; j < 4; ++j) { if (s8 * 8 + j > t) a[j] = 0.f; if (s8 * 8 + 4 + j > t) b[j] = 0.f; }
;             v4u q; q.x = pk2(a[0], a[1]); q.y = pk2(a[2], a[3]); q.z = pk2(b[0], b[1]); q.w = pk2(b[2], b[3]); *(LAS v4u*)(L + WB + t * WRS + s8 * 16) = q; }
;         for (int half = 0; half < 2; ++half) {
;             if (half) __syncthreads();
; #pragma unroll
;             for (int e = 0; e < 8; ++e) { const int cc = tid + 512 * e, sr = cc >> 5, d8 = cc & 31; *(LAS v4u*)(L + sr * RS + d8 * 16) = *(const v4u*)(P + (row0 + sr) * 8192 + 4096 + g * 512 + 256 * half + d8 * 8); }
;             __syncthreads();
;             bf16x8 Wf[4];
; #pragma unroll
;             for (int ks = 0; ks < 4; ++ks) Wf[ks] = *(const LAS bf16x8*)(L + WB + (16 * w + l15) * WRS + (32 * ks + 8 * lg) * 2);
;             const int nks = (w >> 1) + 1; const int t = 16 * w + l15; const float bb = bsp[g * 128 + t];
;             const LAS unsigned char* vb = L + (8 * lg + (l15 >> 2)) * RS + (l15 & 3) * 8;
;             v2u uv[16];
; #pragma unroll
;             for (int dt = 0; dt < 16; ++dt) uv[dt] = *(const v2u*)(P + (row0 + t) * 8192 + (size_t)g * 512 + 256 * half + 16 * dt + 4 * lg);
	v_cndmask_b32_e64 v13, v10, v10, s[36:37]
	v_cndmask_b32_e64 v14, v11, v11, s[36:37]
	v_cndmask_b32_e64 v12, v8, v12, s[36:37]
	v_cndmask_b32_e64 v4, v12, v8, s[40:41]
	v_cndmask_b32_e64 v8, v14, v11, s[40:41]
	v_cndmask_b32_e64 v10, v13, v10, s[40:41]
	v_cndmask_b32_e64 v9, 0, v9, s[40:41]
	v_cndmask_b32_e64 v11, v5, 0, s[42:43]
	v_cndmask_b32_e64 v5, v10, 0, s[44:45]
	v_cndmask_b32_e64 v10, v6, 0, s[46:47]
	v_cndmask_b32_e64 v6, v8, 0, s[48:49]
	s_nop 4
	v_cvt_pk_bf16_f32 v4, v4, v9
	s_nop 4
	v_cvt_pk_bf16_f32 v5, v5, v6
	s_nop 4
	v_cndmask_b32_e64 v7, v7, 0, s[50:51]
	v_cvt_pk_bf16_f32 v6, v15, v11
	s_nop 4
	v_cvt_pk_bf16_f32 v7, v10, v7
	ds_write_b128 v104, v[4:7]
	v_or_b32_e32 v4, s70, v93
	v_lshlrev_b32_e32 v24, 9, v4
	v_lshl_add_u64 v[8:9], v[26:27], 0, v[24:25]
	global_load_dwordx4 v[4:7], v[8:9], off offset:16
	s_nop 0
	global_load_dwordx4 v[8:11], v[8:9], off
	v_mov_b32_e32 v12, s83
	v_add_u32_e32 v24, s70, v3
	v_lshl_add_u64 v[34:35], v[24:25], 2, s[12:13]
	v_add_u32_e32 v24, s68, v3
	s_waitcnt vmcnt(1)
	v_cndmask_b32_e64 v15, v4, 0, s[54:55]
	s_waitcnt vmcnt(0)
	v_cndmask_b32_e64 v13, v10, v10, s[52:53]
	v_cndmask_b32_e64 v14, v11, v11, s[52:53]
	v_cndmask_b32_e64 v12, v8, v12, s[52:53]
	v_cndmask_b32_e64 v4, v12, v8, s[56:57]
	v_cndmask_b32_e64 v8, v14, v11, s[56:57]
	v_cndmask_b32_e64 v10, v13, v10, s[56:57]
	v_cndmask_b32_e64 v9, 0, v9, s[56:57]
	v_cndmask_b32_e64 v11, v5, 0, s[58:59]
	v_cndmask_b32_e64 v5, v10, 0, s[60:61]
	v_cndmask_b32_e64 v10, v6, 0, s[62:63]
	v_cndmask_b32_e64 v6, v8, 0, s[64:65]
	s_nop 4
	v_cvt_pk_bf16_f32 v4, v4, v9
	s_nop 4
	v_cvt_pk_bf16_f32 v5, v5, v6
	s_nop 4
	v_cndmask_b32_e64 v7, v7, 0, s[66:67]
	v_cvt_pk_bf16_f32 v6, v15, v11
	s_nop 4
	v_cvt_pk_bf16_f32 v7, v10, v7
	ds_write_b128 v105, v[4:7]
	v_lshlrev_b64 v[4:5], 14, v[24:25]
	v_lshl_add_u64 v[4:5], s[0:1], 0, v[4:5]
	v_lshl_add_u64 v[4:5], v[4:5], 0, s[82:83]
	v_lshl_add_u64 v[36:37], v[4:5], 0, v[30:31]
	v_lshlrev_b64 v[4:5], 13, v[24:25]
	v_lshl_add_u64 v[38:39], v[28:29], 0, v[4:5]
	v_or_b32_e32 v4, s68, v94
	v_lshlrev_b32_e32 v24, 14, v4
	v_lshl_add_u64 v[4:5], s[0:1], 0, v[24:25]
	v_lshl_add_u64 v[4:5], v[4:5], 0, s[82:83]
	v_lshl_add_u64 v[4:5], v[4:5], 0, v[32:33]
	v_lshl_add_u64 v[40:41], v[4:5], 0, s[92:93]
	v_or_b32_e32 v4, s68, v95
	v_lshlrev_b32_e32 v24, 14, v4
	v_lshl_add_u64 v[4:5], s[0:1], 0, v[24:25]
	v_lshl_add_u64 v[4:5], v[4:5], 0, s[82:83]
	v_lshl_add_u64 v[4:5], v[4:5], 0, v[32:33]
	v_lshl_add_u64 v[42:43], v[4:5], 0, s[92:93]
	v_or_b32_e32 v4, s68, v96
	v_lshlrev_b32_e32 v24, 14, v4
	v_lshl_add_u64 v[4:5], s[0:1], 0, v[24:25]
	v_lshl_add_u64 v[4:5], v[4:5], 0, s[82:83]
	v_lshl_add_u64 v[4:5], v[4:5], 0, v[32:33]
	v_lshl_add_u64 v[44:45], v[4:5], 0, s[92:93]
	v_or_b32_e32 v4, s68, v97
	v_lshlrev_b32_e32 v24, 14, v4
	v_lshl_add_u64 v[4:5], s[0:1], 0, v[24:25]
	v_lshl_add_u64 v[4:5], v[4:5], 0, s[82:83]
	v_lshl_add_u64 v[4:5], v[4:5], 0, v[32:33]
	v_lshl_add_u64 v[46:47], v[4:5], 0, s[92:93]
	v_or_b32_e32 v4, s68, v98
	v_lshlrev_b32_e32 v24, 14, v4
	v_lshl_add_u64 v[4:5], s[0:1], 0, v[24:25]
	v_lshl_add_u64 v[4:5], v[4:5], 0, s[82:83]
	v_lshl_add_u64 v[4:5], v[4:5], 0, v[32:33]
	v_lshl_add_u64 v[48:49], v[4:5], 0, s[92:93]
	v_or_b32_e32 v4, s68, v99
	v_lshlrev_b32_e32 v24, 14, v4
	v_lshl_add_u64 v[4:5], s[0:1], 0, v[24:25]
	v_lshl_add_u64 v[4:5], v[4:5], 0, s[82:83]
	v_lshl_add_u64 v[4:5], v[4:5], 0, v[32:33]
	v_lshl_add_u64 v[50:51], v[4:5], 0, s[92:93]
	v_or_b32_e32 v4, s68, v100
	v_lshlrev_b32_e32 v24, 14, v4
	v_lshl_add_u64 v[4:5], s[0:1], 0, v[24:25]
	v_lshl_add_u64 v[4:5], v[4:5], 0, s[82:83]
	v_lshl_add_u64 v[4:5], v[4:5], 0, v[32:33]
	v_lshl_add_u64 v[52:53], v[4:5], 0, s[92:93]
	v_or_b32_e32 v4, s68, v101
	v_lshlrev_b32_e32 v24, 14, v4
	v_lshl_add_u64 v[4:5], s[0:1], 0, v[24:25]
	v_lshl_add_u64 v[4:5], v[4:5], 0, s[82:83]
	v_lshl_add_u64 v[4:5], v[4:5], 0, v[32:33]
	v_lshl_add_u64 v[54:55], v[4:5], 0, s[92:93]
	s_mov_b32 s82, s83
	s_branch .LBB0_3581

; __device__ __forceinline__ void postnorm(const Ctx& c, const bf16* MF, bf16* XB, float* RS, const float* gpost, float* OUT) {
;     for (int row = c.gw; row < MT; row += c.NGW) {
;         const v4u* mr = (const v4u*)(MF + (size_t)row * DM) + c.lane; v4u* xr = (v4u*)(XB + (size_t)row * DM) + c.lane;
;         v4u mv[4], xv[4]; float v[4][8]; float s = 0.f;
; #pragma unroll
;         for (int j = 0; j < 4; ++j) { mv[j] = mr[64 * j]; xv[j] = xr[64 * j]; }
; #pragma unroll
;         for (int j = 0; j < 4; ++j)
; #pragma unroll
;             for (int k = 0; k < 4; ++k) { v[j][2 * k] = bflo(mv[j][k]); v[j][2 * k + 1] = bfhi(mv[j][k]); s += v[j][2 * k] * v[j][2 * k] + v[j][2 * k + 1] * v[j][2 * k + 1]; }
;         const float rs = rsqrtf(wave_sum(s) * (1.f / DM) + EPS);
;         float s2 = 0.f;
; #pragma unroll
.LBB0_3812:
	v_readlane_b32 s10, v253, 0
	v_readlane_b32 s11, v253, 1
	s_nop 1
	v_lshl_add_u64 v[34:35], s[10:11], 0, v[36:37]
	v_add_co_u32_e32 v58, vcc, 0xd400000, v34
	s_nop 1
	v_addc_co_u32_e32 v59, vcc, 0, v35, vcc
	s_waitcnt lgkmcnt(0)
	global_load_dwordx4 v[46:49], v[58:59], off
	global_load_dwordx4 v[50:53], v[58:59], off offset:1024
	global_load_dwordx4 v[54:57], v[58:59], off offset:2048
	s_nop 0
	global_load_dwordx4 v[58:61], v[58:59], off offset:3072
	v_add_co_u32_e32 v34, vcc, 0x9400000, v34
	s_waitcnt vmcnt(3)
	v_lshlrev_b32_e32 v79, 16, v47
	v_addc_co_u32_e32 v35, vcc, 0, v35, vcc
	global_load_dwordx4 v[62:65], v[34:35], off
	global_load_dwordx4 v[66:69], v[34:35], off offset:1024
	global_load_dwordx4 v[70:73], v[34:35], off offset:2048
	global_load_dwordx4 v[74:77], v[34:35], off offset:3072
	v_lshlrev_b32_e32 v78, 16, v46
	v_and_b32_e32 v47, 0xffff0000, v47
	v_and_b32_e32 v46, 0xffff0000, v46
	v_lshlrev_b32_e32 v81, 16, v49
	v_lshlrev_b32_e32 v80, 16, v48
	v_and_b32_e32 v49, 0xffff0000, v49
	v_and_b32_e32 v48, 0xffff0000, v48
	v_pk_mul_f32 v[94:95], v[46:47], v[46:47]
	v_pk_mul_f32 v[98:99], v[48:49], v[48:49]
	v_pk_fma_f32 v[94:95], v[78:79], v[78:79], v[94:95]
	s_waitcnt vmcnt(6)
	v_lshlrev_b32_e32 v83, 16, v51
	v_lshlrev_b32_e32 v82, 16, v50
	v_and_b32_e32 v51, 0xffff0000, v51
	v_and_b32_e32 v50, 0xffff0000, v50
	v_pk_fma_f32 v[98:99], v[80:81], v[80:81], v[98:99]
	v_add_f32_e32 v94, v94, v95
	v_pk_mul_f32 v[102:103], v[50:51], v[50:51]
	v_add_f32_e32 v94, v98, v94
	v_lshlrev_b32_e32 v85, 16, v53
	v_lshlrev_b32_e32 v84, 16, v52
	v_and_b32_e32 v53, 0xffff0000, v53
	v_and_b32_e32 v52, 0xffff0000, v52
	v_pk_fma_f32 v[102:103], v[82:83], v[82:83], v[102:103]
	v_add_f32_e32 v94, v99, v94
	v_pk_mul_f32 v[104:105], v[52:53], v[52:53]
	v_add_f32_e32 v94, v102, v94
	s_waitcnt vmcnt(5)
	v_lshlrev_b32_e32 v87, 16, v55
	v_lshlrev_b32_e32 v86, 16, v54
	v_and_b32_e32 v55, 0xffff0000, v55
	v_and_b32_e32 v54, 0xffff0000, v54
	v_pk_fma_f32 v[104:105], v[84:85], v[84:85], v[104:105]
	v_add_f32_e32 v94, v103, v94
	v_pk_mul_f32 v[106:107], v[54:55], v[54:55]
	v_add_f32_e32 v94, v104, v94
	v_lshlrev_b32_e32 v89, 16, v57
	v_lshlrev_b32_e32 v88, 16, v56
	v_and_b32_e32 v57, 0xffff0000, v57
	v_and_b32_e32 v56, 0xffff0000, v56
	v_pk_fma_f32 v[106:107], v[86:87], v[86:87], v[106:107]
	v_add_f32_e32 v94, v105, v94
	v_pk_mul_f32 v[108:109], v[56:57], v[56:57]
	v_add_f32_e32 v94, v106, v94
	s_waitcnt vmcnt(4)
	v_lshlrev_b32_e32 v91, 16, v59
	v_lshlrev_b32_e32 v90, 16, v58
	v_and_b32_e32 v59, 0xffff0000, v59
	v_and_b32_e32 v58, 0xffff0000, v58
	v_pk_fma_f32 v[108:109], v[88:89], v[88:89], v[108:109]
	v_add_f32_e32 v94, v107, v94
	v_pk_mul_f32 v[110:111], v[58:59], v[58:59]
	v_add_f32_e32 v94, v108, v94
	v_lshlrev_b32_e32 v93, 16, v61
	v_lshlrev_b32_e32 v92, 16, v60
	v_and_b32_e32 v61, 0xffff0000, v61
	v_and_b32_e32 v60, 0xffff0000, v60
	v_pk_fma_f32 v[110:111], v[90:91], v[90:91], v[110:111]
	v_add_f32_e32 v94, v109, v94
	v_pk_mul_f32 v[112:113], v[60:61], v[60:61]
	v_add_f32_e32 v94, v110, v94
	v_pk_fma_f32 v[112:113], v[92:93], v[92:93], v[112:113]
	v_add_f32_e32 v94, v111, v94
	v_add_f32_e32 v94, v112, v94
	v_add_f32_e32 v94, v113, v94
	ds_bpermute_b32 v98, v40, v94
	s_waitcnt lgkmcnt(0)
	v_add_f32_e32 v98, v94, v98
	ds_bpermute_b32 v102, v41, v98
	s_waitcnt lgkmcnt(0)
	v_add_f32_e32 v102, v98, v102
	ds_bpermute_b32 v104, v42, v102
	s_waitcnt vmcnt(3)
	v_lshlrev_b32_e32 v97, 16, v63
	v_lshlrev_b32_e32 v96, 16, v62
	v_and_b32_e32 v63, 0xffff0000, v63
	s_waitcnt lgkmcnt(0)
	v_add_f32_e32 v104, v102, v104
	ds_bpermute_b32 v106, v43, v104
	v_and_b32_e32 v62, 0xffff0000, v62
	v_lshlrev_b32_e32 v101, 16, v65
	v_lshlrev_b32_e32 v100, 16, v64
	v_and_b32_e32 v65, 0xffff0000, v65
	s_waitcnt lgkmcnt(0)
	v_add_f32_e32 v106, v104, v106
	ds_bpermute_b32 v108, v44, v106
	v_and_b32_e32 v64, 0xffff0000, v64
	s_waitcnt vmcnt(0)
	v_lshlrev_b32_e32 v109, 16, v77
	v_and_b32_e32 v77, 0xffff0000, v77
	v_lshlrev_b32_e32 v95, 16, v67
	s_waitcnt lgkmcnt(0)
	v_add_f32_e32 v108, v106, v108
	ds_bpermute_b32 v110, v45, v108
	v_lshlrev_b32_e32 v94, 16, v66
	v_and_b32_e32 v67, 0xffff0000, v67
	v_and_b32_e32 v66, 0xffff0000, v66
	v_lshlrev_b32_e32 v99, 16, v69
	s_waitcnt lgkmcnt(0)
	v_add_f32_e32 v108, v108, v110
	v_fmamk_f32 v108, v108, 0x3a000000, v3
	v_mul_f32_e32 v110, 0x4b800000, v108
	v_cmp_gt_f32_e32 vcc, s15, v108
	v_lshlrev_b32_e32 v98, 16, v68
	v_and_b32_e32 v69, 0xffff0000, v69
	v_cndmask_b32_e32 v108, v108, v110, vcc
	v_rsq_f32_e32 v110, v108
	v_lshlrev_b32_e32 v108, 16, v76
	v_and_b32_e32 v76, 0xffff0000, v76
	v_and_b32_e32 v68, 0xffff0000, v68
	v_mul_f32_e32 v111, 0x45800000, v110
	v_cndmask_b32_e32 v110, v110, v111, vcc
	v_pk_mul_f32 v[46:47], v[110:111], v[46:47] op_sel_hi:[0,1]
	v_pk_mul_f32 v[78:79], v[110:111], v[78:79] op_sel_hi:[0,1]
	v_pk_mul_f32 v[48:49], v[110:111], v[48:49] op_sel_hi:[0,1]
	v_pk_fma_f32 v[46:47], v[38:39], v[46:47], v[62:63]
	v_pk_mul_f32 v[60:61], v[110:111], v[60:61] op_sel_hi:[0,1]
	v_pk_mul_f32 v[80:81], v[110:111], v[80:81] op_sel_hi:[0,1]
	v_pk_fma_f32 v[78:79], v[4:5], v[78:79], v[96:97]
	v_pk_fma_f32 v[48:49], v[6:7], v[48:49], v[64:65]
	v_pk_fma_f32 v[60:61], v[30:31], v[60:61], v[76:77]
	v_pk_mul_f32 v[76:77], v[46:47], v[46:47]
	v_pk_mul_f32 v[50:51], v[110:111], v[50:51] op_sel_hi:[0,1]
	v_pk_fma_f32 v[62:63], v[8:9], v[80:81], v[100:101]
	v_pk_fma_f32 v[76:77], v[78:79], v[78:79], v[76:77]
	v_pk_mul_f32 v[80:81], v[48:49], v[48:49]
	v_pk_mul_f32 v[82:83], v[110:111], v[82:83] op_sel_hi:[0,1]
	v_pk_fma_f32 v[50:51], v[10:11], v[50:51], v[66:67]
	v_pk_fma_f32 v[80:81], v[62:63], v[62:63], v[80:81]
	v_add_f32_e32 v76, v76, v77
; __device__ __forceinline__ unsigned pk2(float lo, float hi) { return f2bf(lo) | (f2bf(hi) << 16); }
; __device__ __forceinline__ void postnorm(const Ctx& c, const bf16* MF, bf16* XB, float* RS, const float* gpost, float* OUT) {
;     ...
;         for (int j = 0; j < 4; ++j) { const float* gp = gpost + (c.lane + 64 * j) * 8; const f32x4 g0 = *(CF4)gp, g1 = *(CF4)(gp + 4);
; #pragma unroll
;             for (int k = 0; k < 4; ++k) { const float ga = (k < 2) ? g0[2 * k] : g1[2 * k - 4], gb = (k < 2) ? g0[2 * k + 1] : g1[2 * k - 3];
;                 v[j][2 * k] = bflo(xv[j][k]) + v[j][2 * k] * rs * ga; v[j][2 * k + 1] = bfhi(xv[j][k]) + v[j][2 * k + 1] * rs * gb;
;                 s2 += v[j][2 * k] * v[j][2 * k] + v[j][2 * k + 1] * v[j][2 * k + 1]; } }
;         if (OUT) {
; #pragma unroll
;             for (int j = 0; j < 4; ++j) { float* op = OUT + (size_t)row * DM + (c.lane + 64 * j) * 8; *(f32x4*)op = (f32x4){v[j][0], v[j][1], v[j][2], v[j][3]}; *(f32x4*)(op + 4) = (f32x4){v[j][4], v[j][5], v[j][6], v[j][7]}; }
;         } else {
; #pragma unroll
;             for (int j = 0; j < 4; ++j) { v4u o; o.x = pk2(v[j][0], v[j][1]); o.y = pk2(v[j][2], v[j][3]); o.z = pk2(v[j][4], v[j][5]); o.w = pk2(v[j][6], v[j][7]); xr[64 * j] = o; }
;             const float rs2 = rsqrtf(wave_sum(s2) * (1.f / DM) + EPS); if (c.lane == 0) RS[row] = rs2;
	v_pk_fma_f32 v[64:65], v[12:13], v[82:83], v[94:95]
	v_pk_mul_f32 v[82:83], v[50:51], v[50:51]
	v_add_f32_e32 v76, v80, v76
	v_pk_fma_f32 v[82:83], v[64:65], v[64:65], v[82:83]
	v_add_f32_e32 v76, v81, v76
	v_add_f32_e32 v76, v82, v76
	v_bfe_u32 v77, v49, 16, 1
	v_bfe_u32 v80, v48, 16, 1
	v_bfe_u32 v81, v47, 16, 1
	v_bfe_u32 v82, v46, 16, 1
	v_pk_mul_f32 v[52:53], v[110:111], v[52:53] op_sel_hi:[0,1]
	v_add3_u32 v46, v46, v82, s16
	v_add3_u32 v47, v47, v81, s16
	v_add3_u32 v48, v48, v80, s16
	v_add3_u32 v49, v49, v77, s16
	v_bfe_u32 v77, v78, 16, 1
	v_bfe_u32 v80, v79, 16, 1
	v_bfe_u32 v81, v62, 16, 1
	v_bfe_u32 v82, v63, 16, 1
	v_pk_mul_f32 v[84:85], v[110:111], v[84:85] op_sel_hi:[0,1]
	v_pk_fma_f32 v[52:53], v[14:15], v[52:53], v[68:69]
	v_add3_u32 v63, v63, v82, s16
	v_add3_u32 v62, v62, v81, s16
	v_add3_u32 v79, v79, v80, s16
	v_add3_u32 v77, v78, v77, s16
	v_lshlrev_b32_e32 v103, 16, v71
	v_lshlrev_b32_e32 v102, 16, v70
	v_and_b32_e32 v71, 0xffff0000, v71
	v_and_b32_e32 v70, 0xffff0000, v70
	v_pk_fma_f32 v[66:67], v[16:17], v[84:85], v[98:99]
	v_pk_mul_f32 v[54:55], v[110:111], v[54:55] op_sel_hi:[0,1]
	v_pk_mul_f32 v[84:85], v[52:53], v[52:53]
	v_lshrrev_b32_e32 v77, 16, v77
	v_lshrrev_b32_e32 v78, 16, v79
	v_lshrrev_b32_e32 v62, 16, v62
	v_lshrrev_b32_e32 v63, 16, v63
	v_pk_mul_f32 v[68:69], v[110:111], v[86:87] op_sel_hi:[0,1]
	v_pk_fma_f32 v[54:55], v[18:19], v[54:55], v[70:71]
	v_pk_fma_f32 v[84:85], v[66:67], v[66:67], v[84:85]
	v_add_f32_e32 v76, v83, v76
	v_and_or_b32 v49, v49, s12, v63
	v_and_or_b32 v48, v48, s12, v62
	v_and_or_b32 v47, v47, s12, v78
	v_and_or_b32 v46, v46, s12, v77
	v_lshlrev_b32_e32 v105, 16, v73
	v_lshlrev_b32_e32 v104, 16, v72
	v_and_b32_e32 v73, 0xffff0000, v73
	v_and_b32_e32 v72, 0xffff0000, v72
	v_pk_fma_f32 v[68:69], v[20:21], v[68:69], v[102:103]
	v_pk_mul_f32 v[56:57], v[110:111], v[56:57] op_sel_hi:[0,1]
	v_pk_mul_f32 v[86:87], v[54:55], v[54:55]
	v_add_f32_e32 v76, v84, v76
	global_store_dwordx4 v[34:35], v[46:49], off
	v_pk_mul_f32 v[70:71], v[110:111], v[88:89] op_sel_hi:[0,1]
	v_pk_fma_f32 v[56:57], v[22:23], v[56:57], v[72:73]
	v_bfe_u32 v46, v53, 16, 1
	v_bfe_u32 v47, v52, 16, 1
	v_bfe_u32 v48, v51, 16, 1
	v_bfe_u32 v49, v50, 16, 1
	v_pk_fma_f32 v[86:87], v[68:69], v[68:69], v[86:87]
	v_add_f32_e32 v76, v85, v76
	v_add3_u32 v50, v50, v49, s16
	v_add3_u32 v51, v51, v48, s16
	v_add3_u32 v47, v52, v47, s16
	v_add3_u32 v46, v53, v46, s16
	v_bfe_u32 v48, v64, 16, 1
	v_bfe_u32 v49, v65, 16, 1
	v_bfe_u32 v52, v66, 16, 1
	v_bfe_u32 v53, v67, 16, 1
	v_lshlrev_b32_e32 v107, 16, v75
	v_lshlrev_b32_e32 v106, 16, v74
	v_and_b32_e32 v75, 0xffff0000, v75
	v_and_b32_e32 v74, 0xffff0000, v74
	v_pk_fma_f32 v[70:71], v[24:25], v[70:71], v[104:105]
	v_pk_mul_f32 v[58:59], v[110:111], v[58:59] op_sel_hi:[0,1]
	v_pk_mul_f32 v[88:89], v[56:57], v[56:57]
	v_add_f32_e32 v76, v86, v76
	v_add3_u32 v53, v67, v53, s16
	v_add3_u32 v52, v66, v52, s16
	v_add3_u32 v49, v65, v49, s16
	v_add3_u32 v48, v64, v48, s16
	v_pk_mul_f32 v[72:73], v[110:111], v[90:91] op_sel_hi:[0,1]
	v_pk_fma_f32 v[58:59], v[26:27], v[58:59], v[74:75]
	v_pk_fma_f32 v[88:89], v[70:71], v[70:71], v[88:89]
	v_add_f32_e32 v76, v87, v76
	v_lshrrev_b32_e32 v62, 16, v48
	v_lshrrev_b32_e32 v63, 16, v49
	v_lshrrev_b32_e32 v48, 16, v52
	v_lshrrev_b32_e32 v49, 16, v53
	v_pk_fma_f32 v[72:73], v[28:29], v[72:73], v[106:107]
	v_pk_mul_f32 v[90:91], v[58:59], v[58:59]
	v_add_f32_e32 v76, v88, v76
	v_and_or_b32 v49, v46, s12, v49
	v_and_or_b32 v48, v47, s12, v48
	v_and_or_b32 v47, v51, s12, v63
	v_and_or_b32 v46, v50, s12, v62
	v_pk_mul_f32 v[74:75], v[110:111], v[92:93] op_sel_hi:[0,1]
	v_pk_fma_f32 v[90:91], v[72:73], v[72:73], v[90:91]
	v_add_f32_e32 v76, v89, v76
	global_store_dwordx4 v[34:35], v[46:49], off offset:1024
	v_pk_fma_f32 v[74:75], v[32:33], v[74:75], v[108:109]
	v_pk_mul_f32 v[92:93], v[60:61], v[60:61]
	v_bfe_u32 v48, v55, 16, 1
	v_bfe_u32 v49, v54, 16, 1
	v_add_f32_e32 v76, v90, v76
	v_add3_u32 v50, v54, v49, s16
	v_add3_u32 v51, v55, v48, s16
	v_bfe_u32 v48, v68, 16, 1
	v_bfe_u32 v49, v69, 16, 1
	v_bfe_u32 v52, v70, 16, 1
	v_bfe_u32 v53, v71, 16, 1
	v_pk_fma_f32 v[92:93], v[74:75], v[74:75], v[92:93]
	v_add_f32_e32 v76, v91, v76
	v_bfe_u32 v46, v57, 16, 1
	v_bfe_u32 v47, v56, 16, 1
	v_add3_u32 v53, v71, v53, s16
	v_add3_u32 v52, v70, v52, s16
	v_add3_u32 v49, v69, v49, s16
	v_add3_u32 v48, v68, v48, s16
	v_add_f32_e32 v76, v92, v76
	v_add3_u32 v47, v56, v47, s16
	v_add3_u32 v46, v57, v46, s16
	v_lshrrev_b32_e32 v54, 16, v48
	v_lshrrev_b32_e32 v55, 16, v49
	v_lshrrev_b32_e32 v48, 16, v52
	v_lshrrev_b32_e32 v49, 16, v53
	v_add_f32_e32 v76, v93, v76
	v_and_or_b32 v49, v46, s12, v49
	v_and_or_b32 v48, v47, s12, v48
	v_and_or_b32 v47, v51, s12, v55
	v_and_or_b32 v46, v50, s12, v54
	global_store_dwordx4 v[34:35], v[46:49], off offset:2048
	ds_bpermute_b32 v47, v40, v76
	v_bfe_u32 v50, v58, 16, 1
	v_add3_u32 v52, v58, v50, s16
	v_bfe_u32 v51, v72, 16, 1
	v_bfe_u32 v55, v75, 16, 1
	s_waitcnt lgkmcnt(0)
	v_add_f32_e32 v47, v76, v47
	ds_bpermute_b32 v50, v41, v47
	v_bfe_u32 v46, v61, 16, 1
	v_add3_u32 v55, v75, v55, s16
	v_add3_u32 v51, v72, v51, s16
	v_add3_u32 v46, v61, v46, s16
	s_waitcnt lgkmcnt(0)
	v_add_f32_e32 v47, v47, v50
	ds_bpermute_b32 v50, v42, v47
	v_lshrrev_b32_e32 v56, 16, v51
	v_lshrrev_b32_e32 v51, 16, v55
	v_and_or_b32 v51, v46, s12, v51
	s_nop 0
	s_waitcnt lgkmcnt(0)
	v_add_f32_e32 v47, v47, v50
	ds_bpermute_b32 v50, v43, v47
	v_bfe_u32 v54, v74, 16, 1
	v_bfe_u32 v48, v60, 16, 1
	s_nop 0
	v_add3_u32 v54, v74, v54, s16
	s_waitcnt lgkmcnt(0)
	v_add_f32_e32 v47, v47, v50
	ds_bpermute_b32 v50, v44, v47
	s_nop 1
	v_add3_u32 v48, v60, v48, s16
	s_nop 0
	s_waitcnt lgkmcnt(0)
	v_add_f32_e32 v46, v47, v50
	ds_bpermute_b32 v47, v45, v46
	v_lshrrev_b32_e32 v54, 16, v54
	v_and_or_b32 v50, v48, s12, v54
	v_cvt_pk_bf16_f32 v49, v73, v59
	v_and_or_b32 v48, v52, s12, v56
	global_store_dwordx4 v[34:35], v[48:51], off offset:3072
	s_and_saveexec_b64 s[10:11], s[0:1]
	s_cbranch_execz .LBB0_3811
	s_waitcnt lgkmcnt(0)
	v_add_f32_e32 v34, v46, v47
	v_fmamk_f32 v34, v34, 0x3a000000, v3
	v_mul_f32_e32 v35, 0x4b800000, v34
	v_cmp_gt_f32_e32 vcc, s15, v34
	v_readlane_b32 s18, v253, 0
	v_readlane_b32 s19, v253, 1
	v_cndmask_b32_e32 v34, v34, v35, vcc
	v_rsq_f32_e32 v34, v34
	s_add_u32 s18, s18, s13
	s_addc_u32 s19, s19, s14
	v_mul_f32_e32 v35, 0x45800000, v34
	v_cndmask_b32_e32 v34, v34, v35, vcc
	global_store_dword v251, v34, s[18:19]
	s_branch .LBB0_3811

; #define LAS __attribute__((address_space(3)))
; #define LDS_WAIT() asm volatile("s_waitcnt lgkmcnt(0)" ::: "memory")
; __device__ __forceinline__ unsigned pk2(float lo, float hi) { return f2bf(lo) | (f2bf(hi) << 16); }
;     ...
;     for (int it = gw0; it < items; it += ngw) {
;         const int kb = it / nblk, nb = it % nblk, k0 = 64 * kb, n0 = 64 * nb, nq = (lane & 15) * 4, kr = lane >> 4; const bool ok = (n0 + nq) < N;
;         f32x4 v[16];
; #pragma unroll
;         for (int i = 0; i < 16; ++i) v[i] = ok ? __builtin_nontemporal_load((const f32x4*)(W + (size_t)(k0 + 4 * i + kr) * N + n0 + nq)) : (f32x4){0.f, 0.f, 0.f, 0.f};
;         if (gain) {
; #pragma unroll
;             for (int i = 0; i < 16; ++i) v[i] *= gain[k0 + 4 * i + kr]; }
; #pragma unroll
;         for (int i = 0; i < 16; ++i) { LAS float* d = scr + (4 * i + kr) * 65 + nq; d[0] = v[i].x; d[1] = v[i].y; d[2] = v[i].z; d[3] = v[i].w; }
;         LDS_WAIT(); asm volatile("" ::: "memory");
;         const int c8 = lane & 7; int d0 = n0;
;         if (ffnmap) { const int bj = n0 >= FFH ? 1 : 0, chn = n0 - FFH * bj; d0 = 256 * (chn >> 7) + 128 * bj + (chn & 127); }
; #pragma unroll
;         for (int j = 0; j < 8; ++j) { const int n = (lane >> 3) + 8 * j; const LAS float* sp = scr + (8 * c8) * 65 + n;
;             v4u o; o.x = pk2(sp[0 * 65], sp[1 * 65]); o.y = pk2(sp[2 * 65], sp[3 * 65]); o.z = pk2(sp[4 * 65], sp[5 * 65]); o.w = pk2(sp[6 * 65], sp[7 * 65]);
;             *(v4u*)(WT + (size_t)(d0 + n) * K + k0 + 8 * c8) = o; }
.LBB0_3980:
	s_or_b64 exec, exec, s[8:9]
	v_lshl_add_u64 v[76:77], v[76:77], 2, s[0:1]
	global_load_dword v78, v[76:77], off
	global_load_dword v86, v[76:77], off offset:16
	global_load_dword v88, v[76:77], off offset:32
	global_load_dword v90, v[76:77], off offset:48
	global_load_dword v94, v[76:77], off offset:64
	global_load_dword v96, v[76:77], off offset:80
	global_load_dword v98, v[76:77], off offset:96
	global_load_dword v100, v[76:77], off offset:112
	global_load_dword v102, v[76:77], off offset:128
	global_load_dword v104, v[76:77], off offset:144
	global_load_dword v106, v[76:77], off offset:160
	global_load_dword v108, v[76:77], off offset:176
	global_load_dword v110, v[76:77], off offset:192
	global_load_dword v112, v[76:77], off offset:208
	s_nop 0
	global_load_dword v76, v[76:77], off offset:224
	v_lshl_add_u64 v[80:81], v[80:81], 2, s[0:1]
	global_load_dword v80, v[80:81], off
	v_add_u32_e32 v79, 0x418, v93
	v_add_u32_e32 v87, 0xc30, v93
	v_add_u32_e32 v89, 0xc38, v93
	v_add_u32_e32 v91, 0x1040, v93
	v_add_u32_e32 v95, 0x1048, v93
	v_add_u32_e32 v97, 0x1450, v93
	v_add_u32_e32 v99, 0x1458, v93
	v_add_u32_e32 v101, 0x1860, v93
	v_add_u32_e32 v103, 0x1868, v93
	v_add_u32_e32 v105, 0x1c70, v93
	v_add_u32_e32 v77, 0x410, v93
	v_add_u32_e32 v81, 0x820, v93
	v_add_u32_e32 v85, 0x828, v93
	v_add_u32_e32 v107, 0x1c78, v93
	s_waitcnt vmcnt(0)
	v_add_u32_e32 v109, 0x2080, v93
	v_add_u32_e32 v111, 0x2088, v93
	s_add_i32 s19, s19, s17
	s_ashr_i32 s7, s6, 31
	s_add_i32 s18, s18, s13
	s_add_i32 s17, s17, s14
	s_cmpk_lt_i32 s18, 0x400
	v_pk_mul_f32 v[4:5], v[4:5], v[78:79] op_sel_hi:[1,0]
	v_pk_mul_f32 v[6:7], v[6:7], v[78:79] op_sel_hi:[1,0]
	v_pk_mul_f32 v[14:15], v[14:15], v[86:87] op_sel_hi:[1,0]
	v_pk_mul_f32 v[12:13], v[12:13], v[86:87] op_sel_hi:[1,0]
	v_pk_mul_f32 v[10:11], v[10:11], v[88:89] op_sel_hi:[1,0]
	v_pk_mul_f32 v[8:9], v[8:9], v[88:89] op_sel_hi:[1,0]
	v_pk_mul_f32 v[22:23], v[22:23], v[90:91] op_sel_hi:[1,0]
	v_pk_mul_f32 v[20:21], v[20:21], v[90:91] op_sel_hi:[1,0]
	v_pk_mul_f32 v[18:19], v[18:19], v[94:95] op_sel_hi:[1,0]
	v_pk_mul_f32 v[16:17], v[16:17], v[94:95] op_sel_hi:[1,0]
	v_pk_mul_f32 v[30:31], v[30:31], v[96:97] op_sel_hi:[1,0]
	v_pk_mul_f32 v[28:29], v[28:29], v[96:97] op_sel_hi:[1,0]
	v_pk_mul_f32 v[26:27], v[26:27], v[98:99] op_sel_hi:[1,0]
	v_pk_mul_f32 v[24:25], v[24:25], v[98:99] op_sel_hi:[1,0]
	v_pk_mul_f32 v[38:39], v[38:39], v[100:101] op_sel_hi:[1,0]
	v_pk_mul_f32 v[36:37], v[36:37], v[100:101] op_sel_hi:[1,0]
	v_pk_mul_f32 v[34:35], v[34:35], v[102:103] op_sel_hi:[1,0]
	v_pk_mul_f32 v[32:33], v[32:33], v[102:103] op_sel_hi:[1,0]
	v_pk_mul_f32 v[44:45], v[44:45], v[104:105] op_sel_hi:[1,0]
	ds_write2_b32 v93, v4, v5 offset1:1
	ds_write2_b32 v93, v6, v7 offset0:2 offset1:3
	ds_write2_b32 v77, v12, v13 offset1:1
	ds_write2_b32 v79, v14, v15 offset1:1
	ds_write2_b32 v81, v8, v9 offset1:1
	ds_write2_b32 v85, v10, v11 offset1:1
	ds_write2_b32 v87, v20, v21 offset1:1
	ds_write2_b32 v89, v22, v23 offset1:1
	ds_write2_b32 v91, v16, v17 offset1:1
	ds_write2_b32 v95, v18, v19 offset1:1
	ds_write2_b32 v97, v28, v29 offset1:1
	ds_write2_b32 v99, v30, v31 offset1:1
	ds_write2_b32 v101, v24, v25 offset1:1
	ds_write2_b32 v103, v26, v27 offset1:1
	ds_write2_b32 v105, v36, v37 offset1:1
	ds_write2_b32 v107, v38, v39 offset1:1
	ds_write2_b32 v109, v32, v33 offset1:1
	ds_write2_b32 v111, v34, v35 offset1:1
	v_add_u32_e32 v4, 0x2490, v93
	v_pk_mul_f32 v[46:47], v[46:47], v[104:105] op_sel_hi:[1,0]
	ds_write2_b32 v4, v44, v45 offset1:1
	v_add_u32_e32 v4, 0x2498, v93
	v_pk_mul_f32 v[40:41], v[40:41], v[106:107] op_sel_hi:[1,0]
	ds_write2_b32 v4, v46, v47 offset1:1
	v_add_u32_e32 v4, 0x28a0, v93
	v_pk_mul_f32 v[42:43], v[42:43], v[106:107] op_sel_hi:[1,0]
	ds_write2_b32 v4, v40, v41 offset1:1
	v_add_u32_e32 v4, 0x28a8, v93
	v_pk_mul_f32 v[52:53], v[52:53], v[108:109] op_sel_hi:[1,0]
	ds_write2_b32 v4, v42, v43 offset1:1
	v_add_u32_e32 v4, 0x2cb0, v93
	v_pk_mul_f32 v[54:55], v[54:55], v[108:109] op_sel_hi:[1,0]
	ds_write2_b32 v4, v52, v53 offset1:1
	v_add_u32_e32 v4, 0x2cb8, v93
	v_pk_mul_f32 v[48:49], v[48:49], v[110:111] op_sel_hi:[1,0]
	ds_write2_b32 v4, v54, v55 offset1:1
	v_add_u32_e32 v4, 0x30c0, v93
	v_pk_mul_f32 v[50:51], v[50:51], v[110:111] op_sel_hi:[1,0]
	ds_write2_b32 v4, v48, v49 offset1:1
	v_add_u32_e32 v4, 0x30c8, v93
	v_pk_mul_f32 v[60:61], v[60:61], v[112:113] op_sel_hi:[1,0]
	ds_write2_b32 v4, v50, v51 offset1:1
	v_add_u32_e32 v4, 0x34d0, v93
	v_pk_mul_f32 v[62:63], v[62:63], v[112:113] op_sel_hi:[1,0]
	ds_write2_b32 v4, v60, v61 offset1:1
	v_add_u32_e32 v4, 0x34d8, v93
	v_pk_mul_f32 v[56:57], v[56:57], v[76:77] op_sel_hi:[1,0]
	ds_write2_b32 v4, v62, v63 offset1:1
	v_add_u32_e32 v4, 0x38e0, v93
	v_pk_mul_f32 v[58:59], v[58:59], v[76:77] op_sel_hi:[1,0]
	ds_write2_b32 v4, v56, v57 offset1:1
	v_add_u32_e32 v4, 0x38e8, v93
	v_pk_mul_f32 v[64:65], v[64:65], v[80:81] op_sel_hi:[1,0]
	ds_write2_b32 v4, v58, v59 offset1:1
	v_add_u32_e32 v4, 0x3cf0, v93
	v_pk_mul_f32 v[66:67], v[66:67], v[80:81] op_sel_hi:[1,0]
	ds_write2_b32 v4, v64, v65 offset1:1
	v_add_u32_e32 v4, 0x3cf8, v93
	ds_write2_b32 v4, v66, v67 offset1:1
	s_waitcnt lgkmcnt(0)
	ds_read2_b32 v[12:13], v92 offset1:8
	ds_read2_b32 v[14:15], v92 offset0:65 offset1:73
	ds_read2_b32 v[16:17], v92 offset0:130 offset1:138
	ds_read2_b32 v[18:19], v92 offset0:195 offset1:203
	v_add_u32_e32 v30, 0x400, v92
	s_waitcnt lgkmcnt(3)
	s_nop 1
	s_waitcnt lgkmcnt(2)
	s_nop 0
	ds_read2_b32 v[20:21], v30 offset0:4 offset1:12
	s_nop 1
	ds_read2_b32 v[22:23], v30 offset0:69 offset1:77
	v_cvt_pk_bf16_f32 v8, v12, v14
	s_waitcnt lgkmcnt(3)
	s_nop 1
	s_waitcnt lgkmcnt(2)
; #define LAS __attribute__((address_space(3)))
; #define LDS_WAIT() asm volatile("s_waitcnt lgkmcnt(0)" ::: "memory")
; __device__ __forceinline__ unsigned pk2(float lo, float hi) { return f2bf(lo) | (f2bf(hi) << 16); }
;     ...
; #pragma unroll
;         for (int j = 0; j < 8; ++j) { const int n = (lane >> 3) + 8 * j; const LAS float* sp = scr + (8 * c8) * 65 + n;
;             v4u o; o.x = pk2(sp[0 * 65], sp[1 * 65]); o.y = pk2(sp[2 * 65], sp[3 * 65]); o.z = pk2(sp[4 * 65], sp[5 * 65]); o.w = pk2(sp[6 * 65], sp[7 * 65]);
;             *(v4u*)(WT + (size_t)(d0 + n) * K + k0 + 8 * c8) = o; }
;         LDS_WAIT(); asm volatile("" ::: "memory");
	s_nop 0
	ds_read2_b32 v[24:25], v30 offset0:134 offset1:142
	s_nop 1
	ds_read2_b32 v[26:27], v30 offset0:199 offset1:207
	v_cvt_pk_bf16_f32 v9, v16, v18
	s_waitcnt lgkmcnt(3)
	s_nop 1
	s_waitcnt lgkmcnt(2)
	s_nop 2
	v_cvt_pk_bf16_f32 v10, v20, v22
	s_waitcnt lgkmcnt(1)
	s_nop 1
	s_waitcnt lgkmcnt(0)
	s_nop 2
	v_cvt_pk_bf16_f32 v11, v24, v26
	v_add_u32_e32 v6, s19, v82
	v_ashrrev_i32_e32 v7, 31, v6
	v_lshl_add_u64 v[4:5], s[6:7], 1, v[74:75]
	v_lshlrev_b64 v[28:29], 12, v[6:7]
	v_lshl_add_u64 v[28:29], v[4:5], 0, v[28:29]
	v_bfe_u32 v7, v13, 16, 1
	global_store_dwordx4 v[28:29], v[8:11], off
	v_add3_u32 v7, v13, v7, s15
	v_lshrrev_b32_e32 v7, 16, v7
	v_bfe_u32 v8, v15, 16, 1
	v_add3_u32 v8, v15, v8, s15
	v_and_or_b32 v8, v8, s16, v7
	s_nop 4
	v_cvt_pk_bf16_f32 v9, v17, v19
	s_nop 4
	v_cvt_pk_bf16_f32 v10, v21, v23
	s_nop 0
	v_add_u32_e32 v12, 8, v6
	s_nop 1
	v_ashrrev_i32_e32 v13, 31, v12
	s_nop 1
	v_lshlrev_b64 v[12:13], 12, v[12:13]
	v_cvt_pk_bf16_f32 v11, v25, v27
	ds_read2_b32 v[14:15], v92 offset0:16 offset1:24
	v_lshl_add_u64 v[12:13], v[4:5], 0, v[12:13]
	global_store_dwordx4 v[12:13], v[8:11], off
	ds_read2_b32 v[12:13], v92 offset0:81 offset1:89
	ds_read2_b32 v[16:17], v92 offset0:146 offset1:154
	ds_read2_b32 v[18:19], v92 offset0:211 offset1:219
	s_waitcnt lgkmcnt(3)
	s_nop 1
	s_waitcnt lgkmcnt(2)
	s_nop 0
	ds_read2_b32 v[20:21], v30 offset0:20 offset1:28
	s_nop 1
	ds_read2_b32 v[22:23], v30 offset0:85 offset1:93
	v_cvt_pk_bf16_f32 v8, v14, v12
	s_waitcnt lgkmcnt(3)
	s_nop 1
	s_waitcnt lgkmcnt(2)
	s_nop 0
	ds_read2_b32 v[24:25], v30 offset0:150 offset1:158
	s_nop 1
	ds_read2_b32 v[26:27], v30 offset0:215 offset1:223
	v_cvt_pk_bf16_f32 v9, v16, v18
	s_waitcnt lgkmcnt(3)
	s_nop 1
	s_waitcnt lgkmcnt(2)
	s_nop 2
	v_cvt_pk_bf16_f32 v10, v20, v22
	s_waitcnt lgkmcnt(1)
	s_nop 0
	v_add_u32_e32 v28, 16, v6
	s_nop 0
	s_waitcnt lgkmcnt(0)
	s_nop 0
	v_ashrrev_i32_e32 v29, 31, v28
	s_nop 1
	v_lshlrev_b64 v[28:29], 12, v[28:29]
	v_cvt_pk_bf16_f32 v11, v24, v26
	v_lshl_add_u64 v[28:29], v[4:5], 0, v[28:29]
	v_bfe_u32 v7, v15, 16, 1
	global_store_dwordx4 v[28:29], v[8:11], off
	v_add3_u32 v7, v15, v7, s15
	v_lshrrev_b32_e32 v7, 16, v7
	v_bfe_u32 v8, v13, 16, 1
	v_add3_u32 v8, v13, v8, s15
	v_and_or_b32 v8, v8, s16, v7
	s_nop 4
	v_cvt_pk_bf16_f32 v9, v17, v19
	s_nop 4
	v_cvt_pk_bf16_f32 v10, v21, v23
	s_nop 0
	v_add_u32_e32 v12, 24, v6
	s_nop 1
	v_ashrrev_i32_e32 v13, 31, v12
	s_nop 1
	v_lshlrev_b64 v[12:13], 12, v[12:13]
	v_cvt_pk_bf16_f32 v11, v25, v27
	ds_read2_b32 v[14:15], v92 offset0:32 offset1:40
	v_lshl_add_u64 v[12:13], v[4:5], 0, v[12:13]
	global_store_dwordx4 v[12:13], v[8:11], off
	ds_read2_b32 v[12:13], v92 offset0:97 offset1:105
	ds_read2_b32 v[16:17], v92 offset0:162 offset1:170
	ds_read2_b32 v[18:19], v92 offset0:227 offset1:235
	s_waitcnt lgkmcnt(3)
	s_nop 1
	s_waitcnt lgkmcnt(2)
	s_nop 0
	ds_read2_b32 v[20:21], v30 offset0:36 offset1:44
	s_nop 1
	ds_read2_b32 v[22:23], v30 offset0:101 offset1:109
	v_cvt_pk_bf16_f32 v8, v14, v12
	s_waitcnt lgkmcnt(3)
	s_nop 1
	s_waitcnt lgkmcnt(2)
	s_nop 0
	ds_read2_b32 v[24:25], v30 offset0:166 offset1:174
	s_nop 1
	ds_read2_b32 v[26:27], v30 offset0:231 offset1:239
	v_cvt_pk_bf16_f32 v9, v16, v18
	s_waitcnt lgkmcnt(3)
	s_nop 1
	s_waitcnt lgkmcnt(2)
	s_nop 2
	v_cvt_pk_bf16_f32 v10, v20, v22
	s_waitcnt lgkmcnt(1)
	s_nop 0
	v_add_u32_e32 v28, 32, v6
	s_nop 0
	s_waitcnt lgkmcnt(0)
	s_nop 0
	v_ashrrev_i32_e32 v29, 31, v28
	s_nop 1
	v_lshlrev_b64 v[28:29], 12, v[28:29]
	v_cvt_pk_bf16_f32 v11, v24, v26
	v_lshl_add_u64 v[28:29], v[4:5], 0, v[28:29]
	v_bfe_u32 v7, v15, 16, 1
	global_store_dwordx4 v[28:29], v[8:11], off
	v_add3_u32 v7, v15, v7, s15
	v_lshrrev_b32_e32 v7, 16, v7
	v_bfe_u32 v8, v13, 16, 1
	v_add3_u32 v8, v13, v8, s15
	v_and_or_b32 v8, v8, s16, v7
	s_nop 4
	v_cvt_pk_bf16_f32 v9, v17, v19
	s_nop 4
	v_cvt_pk_bf16_f32 v10, v21, v23
	s_nop 0
	v_add_u32_e32 v12, 40, v6
	s_nop 1
	v_ashrrev_i32_e32 v13, 31, v12
	s_nop 1
	v_lshlrev_b64 v[12:13], 12, v[12:13]
	v_cvt_pk_bf16_f32 v11, v25, v27
	ds_read2_b32 v[14:15], v92 offset0:48 offset1:56
	v_lshl_add_u64 v[12:13], v[4:5], 0, v[12:13]
	global_store_dwordx4 v[12:13], v[8:11], off
	ds_read2_b32 v[12:13], v92 offset0:113 offset1:121
	ds_read2_b32 v[16:17], v92 offset0:178 offset1:186
	ds_read2_b32 v[18:19], v92 offset0:243 offset1:251
	s_waitcnt lgkmcnt(3)
	s_nop 1
	s_waitcnt lgkmcnt(2)
	s_nop 0
	ds_read2_b32 v[20:21], v30 offset0:52 offset1:60
	s_nop 1
	ds_read2_b32 v[22:23], v30 offset0:117 offset1:125
	v_cvt_pk_bf16_f32 v8, v14, v12
	s_waitcnt lgkmcnt(3)
	s_nop 1
	s_waitcnt lgkmcnt(2)
	s_nop 0
	ds_read2_b32 v[24:25], v30 offset0:182 offset1:190
	s_nop 1
	ds_read2_b32 v[26:27], v30 offset0:247 offset1:255
	v_cvt_pk_bf16_f32 v9, v16, v18
	s_waitcnt lgkmcnt(3)
	s_nop 1
	s_waitcnt lgkmcnt(2)
	s_nop 2
	v_cvt_pk_bf16_f32 v10, v20, v22
	s_waitcnt lgkmcnt(1)
	s_nop 0
	v_add_u32_e32 v28, 48, v6
	s_nop 0
	s_waitcnt lgkmcnt(0)
	s_nop 0
	v_ashrrev_i32_e32 v29, 31, v28
	s_nop 1
	v_lshlrev_b64 v[28:29], 12, v[28:29]
	v_cvt_pk_bf16_f32 v11, v24, v26
	v_lshl_add_u64 v[28:29], v[4:5], 0, v[28:29]
	v_bfe_u32 v7, v15, 16, 1
	global_store_dwordx4 v[28:29], v[8:11], off
	v_add3_u32 v7, v15, v7, s15
	v_lshrrev_b32_e32 v7, 16, v7
	v_bfe_u32 v8, v13, 16, 1
	v_add3_u32 v8, v13, v8, s15
	v_and_or_b32 v8, v8, s16, v7
	s_nop 4
	v_cvt_pk_bf16_f32 v9, v17, v19
	s_nop 4
	v_cvt_pk_bf16_f32 v10, v21, v23
	s_nop 4
	v_add_u32_e32 v6, 56, v6
	v_cvt_pk_bf16_f32 v11, v25, v27
	v_ashrrev_i32_e32 v7, 31, v6
	v_lshlrev_b64 v[6:7], 12, v[6:7]
	v_lshl_add_u64 v[4:5], v[4:5], 0, v[6:7]
	global_store_dwordx4 v[4:5], v[8:11], off
	s_waitcnt lgkmcnt(0)
	s_cbranch_scc0 .LBB0_4013

; #define LAS __attribute__((address_space(3)))
; #define LDS_WAIT() asm volatile("s_waitcnt lgkmcnt(0)" ::: "memory")
; __device__ __forceinline__ unsigned pk2(float lo, float hi) { return f2bf(lo) | (f2bf(hi) << 16); }
;     ...
; #pragma unroll
;         for (int i = 0; i < 16; ++i) { LAS float* d = scr + (4 * i + kr) * 65 + nq; d[0] = v[i].x; d[1] = v[i].y; d[2] = v[i].z; d[3] = v[i].w; }
;         LDS_WAIT(); asm volatile("" ::: "memory");
;         const int c8 = lane & 7; int d0 = n0;
;         if (ffnmap) { const int bj = n0 >= FFH ? 1 : 0, chn = n0 - FFH * bj; d0 = 256 * (chn >> 7) + 128 * bj + (chn & 127); }
; #pragma unroll
;         for (int j = 0; j < 8; ++j) { const int n = (lane >> 3) + 8 * j; const LAS float* sp = scr + (8 * c8) * 65 + n;
;             v4u o; o.x = pk2(sp[0 * 65], sp[1 * 65]); o.y = pk2(sp[2 * 65], sp[3 * 65]); o.z = pk2(sp[4 * 65], sp[5 * 65]); o.w = pk2(sp[6 * 65], sp[7 * 65]);
;             *(v4u*)(WT + (size_t)(d0 + n) * K + k0 + 8 * c8) = o; }
.LBB0_4014:
	s_or_b64 exec, exec, s[6:7]
	s_waitcnt vmcnt(0)
	ds_write2_b32 v93, v4, v5 offset1:1
	ds_write2_b32 v93, v6, v7 offset0:2 offset1:3
	v_add_u32_e32 v4, 0x410, v93
	ds_write2_b32 v4, v12, v13 offset1:1
	v_add_u32_e32 v4, 0x418, v93
	ds_write2_b32 v4, v14, v15 offset1:1
	v_add_u32_e32 v4, 0x820, v93
	ds_write2_b32 v4, v8, v9 offset1:1
	v_add_u32_e32 v4, 0x828, v93
	ds_write2_b32 v4, v10, v11 offset1:1
	v_add_u32_e32 v4, 0xc30, v93
	ds_write2_b32 v4, v20, v21 offset1:1
	v_add_u32_e32 v4, 0xc38, v93
	ds_write2_b32 v4, v22, v23 offset1:1
	v_add_u32_e32 v4, 0x1040, v93
	ds_write2_b32 v4, v16, v17 offset1:1
	v_add_u32_e32 v4, 0x1048, v93
	ds_write2_b32 v4, v18, v19 offset1:1
	v_add_u32_e32 v4, 0x1450, v93
	ds_write2_b32 v4, v28, v29 offset1:1
	v_add_u32_e32 v4, 0x1458, v93
	ds_write2_b32 v4, v30, v31 offset1:1
	v_add_u32_e32 v4, 0x1860, v93
	ds_write2_b32 v4, v24, v25 offset1:1
	v_add_u32_e32 v4, 0x1868, v93
	ds_write2_b32 v4, v26, v27 offset1:1
	v_add_u32_e32 v4, 0x1c70, v93
	ds_write2_b32 v4, v36, v37 offset1:1
	v_add_u32_e32 v4, 0x1c78, v93
	ds_write2_b32 v4, v38, v39 offset1:1
	v_add_u32_e32 v4, 0x2080, v93
	ds_write2_b32 v4, v32, v33 offset1:1
	v_add_u32_e32 v4, 0x2088, v93
	ds_write2_b32 v4, v34, v35 offset1:1
	v_add_u32_e32 v4, 0x2490, v93
	ds_write2_b32 v4, v44, v45 offset1:1
	v_add_u32_e32 v4, 0x2498, v93
	ds_write2_b32 v4, v46, v47 offset1:1
	v_add_u32_e32 v4, 0x28a0, v93
	ds_write2_b32 v4, v40, v41 offset1:1
	v_add_u32_e32 v4, 0x28a8, v93
	ds_write2_b32 v4, v42, v43 offset1:1
	v_add_u32_e32 v4, 0x2cb0, v93
	ds_write2_b32 v4, v52, v53 offset1:1
	v_add_u32_e32 v4, 0x2cb8, v93
	ds_write2_b32 v4, v54, v55 offset1:1
	v_add_u32_e32 v4, 0x30c0, v93
	ds_write2_b32 v4, v48, v49 offset1:1
	v_add_u32_e32 v4, 0x30c8, v93
	ds_write2_b32 v4, v50, v51 offset1:1
	v_add_u32_e32 v4, 0x34d0, v93
	ds_write2_b32 v4, v60, v61 offset1:1
	v_add_u32_e32 v4, 0x34d8, v93
	ds_write2_b32 v4, v62, v63 offset1:1
	v_add_u32_e32 v4, 0x38e0, v93
	ds_write2_b32 v4, v56, v57 offset1:1
	v_add_u32_e32 v4, 0x38e8, v93
	ds_write2_b32 v4, v58, v59 offset1:1
	v_add_u32_e32 v4, 0x3cf0, v93
	ds_write2_b32 v4, v64, v65 offset1:1
	v_add_u32_e32 v4, 0x3cf8, v93
	ds_write2_b32 v4, v66, v67 offset1:1
	s_waitcnt lgkmcnt(0)
	ds_read2_b32 v[12:13], v92 offset1:8
	ds_read2_b32 v[14:15], v92 offset0:65 offset1:73
	ds_read2_b32 v[16:17], v92 offset0:130 offset1:138
	ds_read2_b32 v[18:19], v92 offset0:195 offset1:203
	v_add_u32_e32 v30, 0x400, v92
	s_waitcnt lgkmcnt(3)
	s_nop 1
	s_waitcnt lgkmcnt(2)
	s_nop 0
	ds_read2_b32 v[20:21], v30 offset0:4 offset1:12
	s_nop 1
	ds_read2_b32 v[22:23], v30 offset0:69 offset1:77
	v_cvt_pk_bf16_f32 v8, v12, v14
	s_waitcnt lgkmcnt(3)
	s_nop 1
	s_waitcnt lgkmcnt(2)
	s_nop 0
	ds_read2_b32 v[24:25], v30 offset0:134 offset1:142
	s_nop 1
	ds_read2_b32 v[26:27], v30 offset0:199 offset1:207
	v_cvt_pk_bf16_f32 v9, v16, v18
	s_waitcnt lgkmcnt(3)
	s_nop 1
	s_waitcnt lgkmcnt(2)
	s_nop 2
	v_cvt_pk_bf16_f32 v10, v20, v22
	s_waitcnt lgkmcnt(1)
	s_nop 1
	s_waitcnt lgkmcnt(0)
	s_nop 2
	s_add_i32 s17, s17, s11
	v_cvt_pk_bf16_f32 v11, v24, v26
	v_add_u32_e32 v6, s17, v82
	s_ashr_i32 s1, s0, 31
	v_ashrrev_i32_e32 v7, 31, v6
	v_lshl_add_u64 v[4:5], s[0:1], 1, v[74:75]
	v_lshlrev_b64 v[28:29], 12, v[6:7]
	v_lshl_add_u64 v[28:29], v[4:5], 0, v[28:29]
	v_bfe_u32 v7, v13, 16, 1
	global_store_dwordx4 v[28:29], v[8:11], off
	v_add3_u32 v7, v13, v7, s9
	v_lshrrev_b32_e32 v7, 16, v7
	v_bfe_u32 v8, v15, 16, 1
	v_add3_u32 v8, v15, v8, s9
	v_and_or_b32 v8, v8, s15, v7
	s_nop 4
	v_cvt_pk_bf16_f32 v9, v17, v19
	s_nop 4
	v_cvt_pk_bf16_f32 v10, v21, v23
	s_nop 0
	v_add_u32_e32 v12, 8, v6
	s_nop 1
	v_ashrrev_i32_e32 v13, 31, v12
	s_nop 1
	v_lshlrev_b64 v[12:13], 12, v[12:13]
	v_cvt_pk_bf16_f32 v11, v25, v27
	ds_read2_b32 v[14:15], v92 offset0:16 offset1:24
	v_lshl_add_u64 v[12:13], v[4:5], 0, v[12:13]
	global_store_dwordx4 v[12:13], v[8:11], off
	ds_read2_b32 v[12:13], v92 offset0:81 offset1:89
	ds_read2_b32 v[16:17], v92 offset0:146 offset1:154
	ds_read2_b32 v[18:19], v92 offset0:211 offset1:219
	s_waitcnt lgkmcnt(3)
	s_nop 1
	s_waitcnt lgkmcnt(2)
	s_nop 0
	ds_read2_b32 v[20:21], v30 offset0:20 offset1:28
	s_nop 1
	ds_read2_b32 v[22:23], v30 offset0:85 offset1:93
	v_cvt_pk_bf16_f32 v8, v14, v12
	s_waitcnt lgkmcnt(3)
; #define LAS __attribute__((address_space(3)))
; #define LDS_WAIT() asm volatile("s_waitcnt lgkmcnt(0)" ::: "memory")
; __device__ __forceinline__ unsigned pk2(float lo, float hi) { return f2bf(lo) | (f2bf(hi) << 16); }
;     ...
; #pragma unroll
;         for (int j = 0; j < 8; ++j) { const int n = (lane >> 3) + 8 * j; const LAS float* sp = scr + (8 * c8) * 65 + n;
;             v4u o; o.x = pk2(sp[0 * 65], sp[1 * 65]); o.y = pk2(sp[2 * 65], sp[3 * 65]); o.z = pk2(sp[4 * 65], sp[5 * 65]); o.w = pk2(sp[6 * 65], sp[7 * 65]);
;             *(v4u*)(WT + (size_t)(d0 + n) * K + k0 + 8 * c8) = o; }
;         LDS_WAIT(); asm volatile("" ::: "memory");
	s_nop 1
	s_waitcnt lgkmcnt(2)
	s_nop 0
	ds_read2_b32 v[24:25], v30 offset0:150 offset1:158
	s_nop 1
	ds_read2_b32 v[26:27], v30 offset0:215 offset1:223
	v_cvt_pk_bf16_f32 v9, v16, v18
	s_waitcnt lgkmcnt(3)
	s_nop 1
	s_waitcnt lgkmcnt(2)
	s_nop 2
	v_cvt_pk_bf16_f32 v10, v20, v22
	s_waitcnt lgkmcnt(1)
	s_nop 0
	v_add_u32_e32 v28, 16, v6
	s_nop 0
	s_waitcnt lgkmcnt(0)
	s_nop 0
	v_ashrrev_i32_e32 v29, 31, v28
	s_nop 1
	v_lshlrev_b64 v[28:29], 12, v[28:29]
	v_cvt_pk_bf16_f32 v11, v24, v26
	v_lshl_add_u64 v[28:29], v[4:5], 0, v[28:29]
	v_bfe_u32 v7, v15, 16, 1
	global_store_dwordx4 v[28:29], v[8:11], off
	v_add3_u32 v7, v15, v7, s9
	v_lshrrev_b32_e32 v7, 16, v7
	v_bfe_u32 v8, v13, 16, 1
	v_add3_u32 v8, v13, v8, s9
	v_and_or_b32 v8, v8, s15, v7
	s_nop 4
	v_cvt_pk_bf16_f32 v9, v17, v19
	s_nop 4
	v_cvt_pk_bf16_f32 v10, v21, v23
	s_nop 0
	v_add_u32_e32 v12, 24, v6
	s_nop 1
	v_ashrrev_i32_e32 v13, 31, v12
	s_nop 1
	v_lshlrev_b64 v[12:13], 12, v[12:13]
	v_cvt_pk_bf16_f32 v11, v25, v27
	ds_read2_b32 v[14:15], v92 offset0:32 offset1:40
	v_lshl_add_u64 v[12:13], v[4:5], 0, v[12:13]
	global_store_dwordx4 v[12:13], v[8:11], off
	ds_read2_b32 v[12:13], v92 offset0:97 offset1:105
	ds_read2_b32 v[16:17], v92 offset0:162 offset1:170
	ds_read2_b32 v[18:19], v92 offset0:227 offset1:235
	s_waitcnt lgkmcnt(3)
	s_nop 1
	s_waitcnt lgkmcnt(2)
	s_nop 0
	ds_read2_b32 v[20:21], v30 offset0:36 offset1:44
	s_nop 1
	ds_read2_b32 v[22:23], v30 offset0:101 offset1:109
	v_cvt_pk_bf16_f32 v8, v14, v12
	s_waitcnt lgkmcnt(3)
	s_nop 1
	s_waitcnt lgkmcnt(2)
	s_nop 0
	ds_read2_b32 v[24:25], v30 offset0:166 offset1:174
	s_nop 1
	ds_read2_b32 v[26:27], v30 offset0:231 offset1:239
	v_cvt_pk_bf16_f32 v9, v16, v18
	s_waitcnt lgkmcnt(3)
	s_nop 1
	s_waitcnt lgkmcnt(2)
	s_nop 2
	v_cvt_pk_bf16_f32 v10, v20, v22
	s_waitcnt lgkmcnt(1)
	s_nop 0
	v_add_u32_e32 v28, 32, v6
	s_nop 0
	s_waitcnt lgkmcnt(0)
	s_nop 0
	v_ashrrev_i32_e32 v29, 31, v28
	s_nop 1
	v_lshlrev_b64 v[28:29], 12, v[28:29]
	v_cvt_pk_bf16_f32 v11, v24, v26
	v_lshl_add_u64 v[28:29], v[4:5], 0, v[28:29]
	v_bfe_u32 v7, v15, 16, 1
	global_store_dwordx4 v[28:29], v[8:11], off
	v_add3_u32 v7, v15, v7, s9
	v_lshrrev_b32_e32 v7, 16, v7
	v_bfe_u32 v8, v13, 16, 1
	v_add3_u32 v8, v13, v8, s9
	v_and_or_b32 v8, v8, s15, v7
	s_nop 4
	v_cvt_pk_bf16_f32 v9, v17, v19
	s_nop 4
	v_cvt_pk_bf16_f32 v10, v21, v23
	s_nop 0
	v_add_u32_e32 v12, 40, v6
	s_nop 1
	v_ashrrev_i32_e32 v13, 31, v12
	s_nop 1
	v_lshlrev_b64 v[12:13], 12, v[12:13]
	v_cvt_pk_bf16_f32 v11, v25, v27
	ds_read2_b32 v[14:15], v92 offset0:48 offset1:56
	v_lshl_add_u64 v[12:13], v[4:5], 0, v[12:13]
	global_store_dwordx4 v[12:13], v[8:11], off
	ds_read2_b32 v[12:13], v92 offset0:113 offset1:121
	ds_read2_b32 v[16:17], v92 offset0:178 offset1:186
	ds_read2_b32 v[18:19], v92 offset0:243 offset1:251
	s_waitcnt lgkmcnt(3)
	s_nop 1
	s_waitcnt lgkmcnt(2)
	s_nop 0
	ds_read2_b32 v[20:21], v30 offset0:52 offset1:60
	s_nop 1
	ds_read2_b32 v[22:23], v30 offset0:117 offset1:125
	v_cvt_pk_bf16_f32 v8, v14, v12
	s_waitcnt lgkmcnt(3)
	s_nop 1
	s_waitcnt lgkmcnt(2)
	s_nop 0
	ds_read2_b32 v[24:25], v30 offset0:182 offset1:190
	s_nop 1
	ds_read2_b32 v[26:27], v30 offset0:247 offset1:255
	v_cvt_pk_bf16_f32 v9, v16, v18
	s_waitcnt lgkmcnt(3)
	s_nop 1
	s_waitcnt lgkmcnt(2)
	s_nop 2
	v_cvt_pk_bf16_f32 v10, v20, v22
	s_waitcnt lgkmcnt(1)
	s_nop 0
	v_add_u32_e32 v28, 48, v6
	s_nop 0
	s_waitcnt lgkmcnt(0)
	s_nop 0
	v_ashrrev_i32_e32 v29, 31, v28
	s_nop 1
	v_lshlrev_b64 v[28:29], 12, v[28:29]
	v_cvt_pk_bf16_f32 v11, v24, v26
	v_lshl_add_u64 v[28:29], v[4:5], 0, v[28:29]
	v_bfe_u32 v7, v15, 16, 1
	global_store_dwordx4 v[28:29], v[8:11], off
	v_add3_u32 v7, v15, v7, s9
	v_lshrrev_b32_e32 v7, 16, v7
	v_bfe_u32 v8, v13, 16, 1
	v_add3_u32 v8, v13, v8, s9
	v_and_or_b32 v8, v8, s15, v7
	s_nop 4
	v_cvt_pk_bf16_f32 v9, v17, v19
	s_nop 4
	v_cvt_pk_bf16_f32 v10, v21, v23
	s_nop 4
	v_add_u32_e32 v6, 56, v6
	v_cvt_pk_bf16_f32 v11, v25, v27
	v_ashrrev_i32_e32 v7, 31, v6
	v_lshlrev_b64 v[6:7], 12, v[6:7]
	v_lshl_add_u64 v[4:5], v[4:5], 0, v[6:7]
	global_store_dwordx4 v[4:5], v[8:11], off
	s_waitcnt lgkmcnt(0)
	s_add_i32 s16, s16, s13
	s_add_i32 s11, s11, s14
	s_cmpk_lt_i32 s16, 0x400
	s_cbranch_scc0 .LBB0_4047

; #define LAS __attribute__((address_space(3)))
; #define LDS_WAIT() asm volatile("s_waitcnt lgkmcnt(0)" ::: "memory")
; __device__ __forceinline__ unsigned pk2(float lo, float hi) { return f2bf(lo) | (f2bf(hi) << 16); }
;     ...
; #pragma unroll
;         for (int i = 0; i < 16; ++i) { LAS float* d = scr + (4 * i + kr) * 65 + nq; d[0] = v[i].x; d[1] = v[i].y; d[2] = v[i].z; d[3] = v[i].w; }
;         LDS_WAIT(); asm volatile("" ::: "memory");
;         const int c8 = lane & 7; int d0 = n0;
;         if (ffnmap) { const int bj = n0 >= FFH ? 1 : 0, chn = n0 - FFH * bj; d0 = 256 * (chn >> 7) + 128 * bj + (chn & 127); }
; #pragma unroll
;         for (int j = 0; j < 8; ++j) { const int n = (lane >> 3) + 8 * j; const LAS float* sp = scr + (8 * c8) * 65 + n;
;             v4u o; o.x = pk2(sp[0 * 65], sp[1 * 65]); o.y = pk2(sp[2 * 65], sp[3 * 65]); o.z = pk2(sp[4 * 65], sp[5 * 65]); o.w = pk2(sp[6 * 65], sp[7 * 65]);
;             *(v4u*)(WT + (size_t)(d0 + n) * K + k0 + 8 * c8) = o; }
.LBB0_4052:
	s_or_b64 exec, exec, s[10:11]
	s_waitcnt vmcnt(0)
	ds_write2_b32 v84, v8, v9 offset1:1
	ds_write2_b32 v84, v10, v11 offset0:2 offset1:3
	v_add_u32_e32 v8, 0x410, v84
	ds_write2_b32 v8, v4, v5 offset1:1
	v_add_u32_e32 v4, 0x418, v84
	ds_write2_b32 v4, v6, v7 offset1:1
	v_add_u32_e32 v4, 0x820, v84
	ds_write2_b32 v4, v16, v17 offset1:1
	v_add_u32_e32 v4, 0x828, v84
	ds_write2_b32 v4, v18, v19 offset1:1
	v_add_u32_e32 v4, 0xc30, v84
	ds_write2_b32 v4, v12, v13 offset1:1
	v_add_u32_e32 v4, 0xc38, v84
	ds_write2_b32 v4, v14, v15 offset1:1
	v_add_u32_e32 v4, 0x1040, v84
	ds_write2_b32 v4, v24, v25 offset1:1
	v_add_u32_e32 v4, 0x1048, v84
	ds_write2_b32 v4, v26, v27 offset1:1
	v_add_u32_e32 v4, 0x1450, v84
	ds_write2_b32 v4, v20, v21 offset1:1
	v_add_u32_e32 v4, 0x1458, v84
	ds_write2_b32 v4, v22, v23 offset1:1
	v_add_u32_e32 v4, 0x1860, v84
	ds_write2_b32 v4, v32, v33 offset1:1
	v_add_u32_e32 v4, 0x1868, v84
	ds_write2_b32 v4, v34, v35 offset1:1
	v_add_u32_e32 v4, 0x1c70, v84
	ds_write2_b32 v4, v28, v29 offset1:1
	v_add_u32_e32 v4, 0x1c78, v84
	ds_write2_b32 v4, v30, v31 offset1:1
	v_add_u32_e32 v4, 0x2080, v84
	ds_write2_b32 v4, v40, v41 offset1:1
	v_add_u32_e32 v4, 0x2088, v84
	ds_write2_b32 v4, v42, v43 offset1:1
	v_add_u32_e32 v4, 0x2490, v84
	ds_write2_b32 v4, v36, v37 offset1:1
	v_add_u32_e32 v4, 0x2498, v84
	ds_write2_b32 v4, v38, v39 offset1:1
	v_add_u32_e32 v4, 0x28a0, v84
	ds_write2_b32 v4, v48, v49 offset1:1
	v_add_u32_e32 v4, 0x28a8, v84
	ds_write2_b32 v4, v50, v51 offset1:1
	v_add_u32_e32 v4, 0x2cb0, v84
	ds_write2_b32 v4, v44, v45 offset1:1
	v_add_u32_e32 v4, 0x2cb8, v84
	ds_write2_b32 v4, v46, v47 offset1:1
	v_add_u32_e32 v4, 0x30c0, v84
	ds_write2_b32 v4, v56, v57 offset1:1
	v_add_u32_e32 v4, 0x30c8, v84
	ds_write2_b32 v4, v58, v59 offset1:1
	v_add_u32_e32 v4, 0x34d0, v84
	ds_write2_b32 v4, v52, v53 offset1:1
	v_add_u32_e32 v4, 0x34d8, v84
	ds_write2_b32 v4, v54, v55 offset1:1
	v_add_u32_e32 v4, 0x38e0, v84
	ds_write2_b32 v4, v64, v65 offset1:1
	v_add_u32_e32 v4, 0x38e8, v84
	ds_write2_b32 v4, v66, v67 offset1:1
	v_add_u32_e32 v4, 0x3cf0, v84
	ds_write2_b32 v4, v60, v61 offset1:1
	v_add_u32_e32 v4, 0x3cf8, v84
	ds_write2_b32 v4, v62, v63 offset1:1
	s_waitcnt lgkmcnt(0)
	ds_read2_b32 v[6:7], v73 offset1:65
	s_ashr_i32 s9, s8, 31
	v_lshl_add_u64 v[4:5], s[8:9], 1, v[76:77]
	s_add_i32 s8, s20, s6
	s_add_i32 s19, s19, s13
	s_waitcnt lgkmcnt(0)
	v_bfe_u32 v8, v6, 16, 1
	v_add3_u32 v6, v6, v8, s16
	ds_read2_b32 v[8:9], v73 offset0:130 offset1:195
	v_bfe_u32 v10, v7, 16, 1
	v_lshrrev_b32_e32 v6, 16, v6
	v_add3_u32 v7, v7, v10, s16
	v_and_or_b32 v6, v7, s17, v6
	s_waitcnt lgkmcnt(0)
	v_bfe_u32 v7, v8, 16, 1
	v_add3_u32 v7, v8, v7, s16
	v_add_u32_e32 v8, 0x400, v73
	ds_read2_b32 v[10:11], v8 offset0:4 offset1:69
	v_bfe_u32 v12, v9, 16, 1
	v_lshrrev_b32_e32 v7, 16, v7
	v_add3_u32 v9, v9, v12, s16
	ds_read2_b32 v[12:13], v8 offset0:134 offset1:199
	v_and_or_b32 v7, v9, s17, v7
	s_waitcnt lgkmcnt(1)
	s_nop 4
	v_cvt_pk_bf16_f32 v8, v10, v11
	s_waitcnt lgkmcnt(0)
	s_nop 4
	v_cvt_pk_bf16_f32 v9, v12, v13
	v_add_u32_e32 v10, s8, v82
	ds_read2_b32 v[12:13], v83 offset1:65
	v_ashrrev_i32_e32 v11, 31, v10
	v_lshlrev_b64 v[10:11], 10, v[10:11]
	v_lshl_add_u64 v[10:11], v[4:5], 0, v[10:11]
	global_store_dwordx4 v[10:11], v[6:9], off
	ds_read2_b32 v[8:9], v83 offset0:130 offset1:195
	s_add_i32 s6, s6, s15
	s_waitcnt lgkmcnt(1)
	s_nop 4
	v_cvt_pk_bf16_f32 v6, v12, v13
	s_waitcnt lgkmcnt(0)
	v_bfe_u32 v7, v8, 16, 1
	v_add3_u32 v7, v8, v7, s16
	v_add_u32_e32 v8, 0x400, v83
	ds_read2_b32 v[10:11], v8 offset0:4 offset1:69
	v_bfe_u32 v12, v9, 16, 1
	v_lshrrev_b32_e32 v7, 16, v7
	v_add3_u32 v9, v9, v12, s16
	ds_read2_b32 v[12:13], v8 offset0:134 offset1:199
	v_and_or_b32 v7, v9, s17, v7
	s_waitcnt lgkmcnt(1)
	s_nop 4
	v_cvt_pk_bf16_f32 v8, v10, v11
	s_waitcnt lgkmcnt(0)
	s_nop 4
	v_cvt_pk_bf16_f32 v9, v12, v13
	v_add_u32_e32 v10, s8, v85
	ds_read2_b32 v[12:13], v92 offset1:65
	v_ashrrev_i32_e32 v11, 31, v10
	v_lshlrev_b64 v[10:11], 10, v[10:11]
	v_lshl_add_u64 v[10:11], v[4:5], 0, v[10:11]
	global_store_dwordx4 v[10:11], v[6:9], off
	ds_read2_b32 v[8:9], v92 offset0:130 offset1:195
	s_cmp_lt_i32 s19, 64
	s_waitcnt lgkmcnt(1)
	s_nop 4
	v_cvt_pk_bf16_f32 v6, v12, v13
	s_waitcnt lgkmcnt(0)
	v_bfe_u32 v7, v8, 16, 1
	v_add3_u32 v7, v8, v7, s16
	v_add_u32_e32 v8, 0x400, v92
	ds_read2_b32 v[10:11], v8 offset0:4 offset1:69
	v_bfe_u32 v12, v9, 16, 1
	v_lshrrev_b32_e32 v7, 16, v7
	v_add3_u32 v9, v9, v12, s16
	ds_read2_b32 v[12:13], v8 offset0:134 offset1:199
	v_and_or_b32 v7, v9, s17, v7
	s_waitcnt lgkmcnt(1)
; #define LAS __attribute__((address_space(3)))
; #define LDS_WAIT() asm volatile("s_waitcnt lgkmcnt(0)" ::: "memory")
; __device__ __forceinline__ unsigned pk2(float lo, float hi) { return f2bf(lo) | (f2bf(hi) << 16); }
;     ...
; #pragma unroll
;         for (int j = 0; j < 8; ++j) { const int n = (lane >> 3) + 8 * j; const LAS float* sp = scr + (8 * c8) * 65 + n;
;             v4u o; o.x = pk2(sp[0 * 65], sp[1 * 65]); o.y = pk2(sp[2 * 65], sp[3 * 65]); o.z = pk2(sp[4 * 65], sp[5 * 65]); o.w = pk2(sp[6 * 65], sp[7 * 65]);
;             *(v4u*)(WT + (size_t)(d0 + n) * K + k0 + 8 * c8) = o; }
;         LDS_WAIT(); asm volatile("" ::: "memory");
	s_nop 4
	v_cvt_pk_bf16_f32 v8, v10, v11
	s_waitcnt lgkmcnt(0)
	s_nop 4
	v_cvt_pk_bf16_f32 v9, v12, v13
	v_add_u32_e32 v10, s8, v86
	ds_read2_b32 v[12:13], v93 offset1:65
	v_ashrrev_i32_e32 v11, 31, v10
	v_lshlrev_b64 v[10:11], 10, v[10:11]
	v_lshl_add_u64 v[10:11], v[4:5], 0, v[10:11]
	global_store_dwordx4 v[10:11], v[6:9], off
	ds_read2_b32 v[8:9], v93 offset0:130 offset1:195
	s_waitcnt lgkmcnt(1)
	s_nop 4
	v_cvt_pk_bf16_f32 v6, v12, v13
	s_waitcnt lgkmcnt(0)
	v_bfe_u32 v7, v8, 16, 1
	v_add3_u32 v7, v8, v7, s16
	v_add_u32_e32 v8, 0x400, v93
	ds_read2_b32 v[10:11], v8 offset0:4 offset1:69
	v_bfe_u32 v12, v9, 16, 1
	v_lshrrev_b32_e32 v7, 16, v7
	v_add3_u32 v9, v9, v12, s16
	ds_read2_b32 v[12:13], v8 offset0:134 offset1:199
	v_and_or_b32 v7, v9, s17, v7
	s_waitcnt lgkmcnt(1)
	s_nop 4
	v_cvt_pk_bf16_f32 v8, v10, v11
	s_waitcnt lgkmcnt(0)
	s_nop 4
	v_cvt_pk_bf16_f32 v9, v12, v13
	v_add_u32_e32 v10, s8, v87
	ds_read2_b32 v[12:13], v94 offset1:65
	v_ashrrev_i32_e32 v11, 31, v10
	v_lshlrev_b64 v[10:11], 10, v[10:11]
	v_lshl_add_u64 v[10:11], v[4:5], 0, v[10:11]
	global_store_dwordx4 v[10:11], v[6:9], off
	ds_read2_b32 v[8:9], v94 offset0:130 offset1:195
	s_waitcnt lgkmcnt(1)
	s_nop 4
	v_cvt_pk_bf16_f32 v6, v12, v13
	s_waitcnt lgkmcnt(0)
	v_bfe_u32 v7, v8, 16, 1
	v_add3_u32 v7, v8, v7, s16
	v_add_u32_e32 v8, 0x400, v94
	ds_read2_b32 v[10:11], v8 offset0:4 offset1:69
	v_bfe_u32 v12, v9, 16, 1
	v_lshrrev_b32_e32 v7, 16, v7
	v_add3_u32 v9, v9, v12, s16
	ds_read2_b32 v[12:13], v8 offset0:134 offset1:199
	v_and_or_b32 v7, v9, s17, v7
	s_waitcnt lgkmcnt(1)
	s_nop 4
	v_cvt_pk_bf16_f32 v8, v10, v11
	s_waitcnt lgkmcnt(0)
	s_nop 4
	v_cvt_pk_bf16_f32 v9, v12, v13
	v_add_u32_e32 v10, s8, v88
	ds_read2_b32 v[12:13], v95 offset1:65
	v_ashrrev_i32_e32 v11, 31, v10
	v_lshlrev_b64 v[10:11], 10, v[10:11]
	v_lshl_add_u64 v[10:11], v[4:5], 0, v[10:11]
	global_store_dwordx4 v[10:11], v[6:9], off
	ds_read2_b32 v[8:9], v95 offset0:130 offset1:195
	s_waitcnt lgkmcnt(1)
	s_nop 4
	v_cvt_pk_bf16_f32 v6, v12, v13
	s_waitcnt lgkmcnt(0)
	v_bfe_u32 v7, v8, 16, 1
	v_add3_u32 v7, v8, v7, s16
	v_add_u32_e32 v8, 0x400, v95
	ds_read2_b32 v[10:11], v8 offset0:4 offset1:69
	v_bfe_u32 v12, v9, 16, 1
	v_lshrrev_b32_e32 v7, 16, v7
	v_add3_u32 v9, v9, v12, s16
	ds_read2_b32 v[12:13], v8 offset0:134 offset1:199
	v_and_or_b32 v7, v9, s17, v7
	s_waitcnt lgkmcnt(1)
	s_nop 4
	v_cvt_pk_bf16_f32 v8, v10, v11
	s_waitcnt lgkmcnt(0)
	s_nop 4
	v_cvt_pk_bf16_f32 v9, v12, v13
	v_add_u32_e32 v10, s8, v89
	ds_read2_b32 v[12:13], v96 offset1:65
	v_ashrrev_i32_e32 v11, 31, v10
	v_lshlrev_b64 v[10:11], 10, v[10:11]
	v_lshl_add_u64 v[10:11], v[4:5], 0, v[10:11]
	global_store_dwordx4 v[10:11], v[6:9], off
	ds_read2_b32 v[8:9], v96 offset0:130 offset1:195
	s_waitcnt lgkmcnt(1)
	s_nop 4
	v_cvt_pk_bf16_f32 v6, v12, v13
	s_waitcnt lgkmcnt(0)
	v_bfe_u32 v7, v8, 16, 1
	v_add3_u32 v7, v8, v7, s16
	v_add_u32_e32 v8, 0x400, v96
	ds_read2_b32 v[10:11], v8 offset0:4 offset1:69
	v_bfe_u32 v12, v9, 16, 1
	v_lshrrev_b32_e32 v7, 16, v7
	v_add3_u32 v9, v9, v12, s16
	ds_read2_b32 v[12:13], v8 offset0:134 offset1:199
	v_and_or_b32 v7, v9, s17, v7
	s_waitcnt lgkmcnt(1)
	s_nop 4
	v_cvt_pk_bf16_f32 v8, v10, v11
	s_waitcnt lgkmcnt(0)
	s_nop 4
	v_cvt_pk_bf16_f32 v9, v12, v13
	v_add_u32_e32 v10, s8, v90
	ds_read2_b32 v[12:13], v97 offset1:65
	v_ashrrev_i32_e32 v11, 31, v10
	v_lshlrev_b64 v[10:11], 10, v[10:11]
	v_lshl_add_u64 v[10:11], v[4:5], 0, v[10:11]
	global_store_dwordx4 v[10:11], v[6:9], off
	ds_read2_b32 v[8:9], v97 offset0:130 offset1:195
	s_waitcnt lgkmcnt(1)
	s_nop 4
	v_cvt_pk_bf16_f32 v6, v12, v13
	s_waitcnt lgkmcnt(0)
	v_bfe_u32 v7, v8, 16, 1
	v_add3_u32 v7, v8, v7, s16
	v_add_u32_e32 v8, 0x400, v97
	ds_read2_b32 v[10:11], v8 offset0:4 offset1:69
	v_bfe_u32 v12, v9, 16, 1
	v_lshrrev_b32_e32 v7, 16, v7
	v_add3_u32 v9, v9, v12, s16
	ds_read2_b32 v[12:13], v8 offset0:134 offset1:199
	v_and_or_b32 v7, v9, s17, v7
	s_waitcnt lgkmcnt(1)
	s_nop 4
	v_cvt_pk_bf16_f32 v8, v10, v11
	s_waitcnt lgkmcnt(0)
	s_nop 4
	v_cvt_pk_bf16_f32 v9, v12, v13
	v_add_u32_e32 v10, s8, v91
	v_ashrrev_i32_e32 v11, 31, v10
	v_lshlrev_b64 v[10:11], 10, v[10:11]
	v_lshl_add_u64 v[4:5], v[4:5], 0, v[10:11]
	global_store_dwordx4 v[4:5], v[6:9], off
	s_waitcnt lgkmcnt(0)
	s_cbranch_scc0 .LBB0_4049

; __device__ __forceinline__ unsigned pk2(float lo, float hi) { return f2bf(lo) | (f2bf(hi) << 16); }
; __device__ __forceinline__ void xa_attn_fa(const Ctx& c, const bf16* Q, const bf16* KV, const bf16* XVT, bf16* Oo) {
;     ...
;         for (int mi = 0; mi < 2; ++mi) { float lt = l[mi]; lt += __shfl_xor(lt, 16); lt += __shfl_xor(lt, 32); const float il = 1.f / lt;
; #pragma unroll
;             for (int dt = 0; dt < 8; ++dt) { const f32x4 o = O[dt][mi] * il; v2u w; w.x = pk2(o[0], o[1]); w.y = pk2(o[2], o[3]);
;                 *(v2u*)(Oo + grow[mi] * 512 + hd * 128 + 16 * dt + 4 * lg) = w; } }
.LBB0_4141:
	v_mul_f32_e32 v4, 0x3e800000, v128
	ds_bpermute_b32 v4, v167, v4
	s_lshl_b32 s8, s21, 1
	v_lshl_add_u64 v[6:7], v[172:173], 0, s[8:9]
	v_lshl_add_u64 v[30:31], v[6:7], 0, v[188:189]
	v_mul_f32_e32 v52, 0x3e800000, v28
	s_waitcnt lgkmcnt(0)
	v_fmac_f32_e32 v4, 0x3e800000, v128
	ds_bpermute_b32 v29, v194, v4
	v_lshl_add_u64 v[6:7], v[6:7], 0, v[186:187]
	s_add_i32 s20, s20, s33
	s_cmpk_lt_i32 s20, 0x100
	s_waitcnt lgkmcnt(0)
	v_add_f32_e32 v4, v4, v29
	v_div_scale_f32 v29, s[10:11], v4, v4, 1.0
	v_rcp_f32_e32 v48, v29
	v_div_scale_f32 v49, vcc, 1.0, v4, 1.0
	v_fma_f32 v50, -v29, v48, 1.0
	v_fmac_f32_e32 v48, v50, v48
	v_mul_f32_e32 v50, v49, v48
	v_fma_f32 v51, -v29, v50, v49
	v_fmac_f32_e32 v50, v51, v48
	v_fma_f32 v29, -v29, v50, v49
	v_div_fmas_f32 v29, v29, v48, v50
	v_div_fixup_f32 v4, v29, v4, 1.0
	v_pk_mul_f32 v[50:51], v[120:121], v[4:5] op_sel_hi:[1,0]
	v_pk_mul_f32 v[48:49], v[122:123], v[4:5] op_sel_hi:[1,0]
	s_nop 4
	v_cvt_pk_bf16_f32 v50, v50, v51
	v_bfe_u32 v29, v48, 16, 1
	v_add3_u32 v29, v48, v29, s18
	v_bfe_u32 v48, v49, 16, 1
	v_lshrrev_b32_e32 v29, 16, v29
	v_add3_u32 v48, v49, v48, s18
	v_and_or_b32 v51, v48, s19, v29
	global_store_dwordx2 v[30:31], v[50:51], off
	v_pk_mul_f32 v[50:51], v[116:117], v[4:5] op_sel_hi:[1,0]
	v_pk_mul_f32 v[48:49], v[118:119], v[4:5] op_sel_hi:[1,0]
	v_bfe_u32 v29, v50, 16, 1
	v_add3_u32 v29, v50, v29, s18
	v_bfe_u32 v50, v51, 16, 1
	v_lshrrev_b32_e32 v29, 16, v29
	v_add3_u32 v50, v51, v50, s18
	v_and_or_b32 v50, v50, s19, v29
	v_bfe_u32 v29, v48, 16, 1
	v_add3_u32 v29, v48, v29, s18
	v_bfe_u32 v48, v49, 16, 1
	v_lshrrev_b32_e32 v29, 16, v29
	v_add3_u32 v48, v49, v48, s18
	v_and_or_b32 v51, v48, s19, v29
	global_store_dwordx2 v[30:31], v[50:51], off offset:32
	v_pk_mul_f32 v[50:51], v[112:113], v[4:5] op_sel_hi:[1,0]
	v_pk_mul_f32 v[48:49], v[114:115], v[4:5] op_sel_hi:[1,0]
	v_bfe_u32 v29, v50, 16, 1
	v_add3_u32 v29, v50, v29, s18
	v_bfe_u32 v50, v51, 16, 1
	v_lshrrev_b32_e32 v29, 16, v29
	v_add3_u32 v50, v51, v50, s18
	v_and_or_b32 v50, v50, s19, v29
	v_bfe_u32 v29, v48, 16, 1
	v_add3_u32 v29, v48, v29, s18
	v_bfe_u32 v48, v49, 16, 1
	v_lshrrev_b32_e32 v29, 16, v29
	v_add3_u32 v48, v49, v48, s18
	v_and_or_b32 v51, v48, s19, v29
	global_store_dwordx2 v[30:31], v[50:51], off offset:64
	v_pk_mul_f32 v[50:51], v[92:93], v[4:5] op_sel_hi:[1,0]
	v_pk_mul_f32 v[48:49], v[94:95], v[4:5] op_sel_hi:[1,0]
	v_bfe_u32 v29, v50, 16, 1
	v_add3_u32 v29, v50, v29, s18
	v_bfe_u32 v50, v51, 16, 1
	v_lshrrev_b32_e32 v29, 16, v29
	v_add3_u32 v50, v51, v50, s18
	v_and_or_b32 v50, v50, s19, v29
	v_bfe_u32 v29, v48, 16, 1
	v_add3_u32 v29, v48, v29, s18
	v_bfe_u32 v48, v49, 16, 1
	v_lshrrev_b32_e32 v29, 16, v29
	v_add3_u32 v48, v49, v48, s18
	v_and_or_b32 v51, v48, s19, v29
	global_store_dwordx2 v[30:31], v[50:51], off offset:96
	v_pk_mul_f32 v[50:51], v[88:89], v[4:5] op_sel_hi:[1,0]
	v_pk_mul_f32 v[48:49], v[90:91], v[4:5] op_sel_hi:[1,0]
	v_bfe_u32 v29, v50, 16, 1
	v_add3_u32 v29, v50, v29, s18
	v_bfe_u32 v50, v51, 16, 1
	v_lshrrev_b32_e32 v29, 16, v29
	v_add3_u32 v50, v51, v50, s18
	v_and_or_b32 v50, v50, s19, v29
	v_bfe_u32 v29, v48, 16, 1
	v_add3_u32 v29, v48, v29, s18
	v_bfe_u32 v48, v49, 16, 1
	v_lshrrev_b32_e32 v29, 16, v29
	v_add3_u32 v48, v49, v48, s18
	v_and_or_b32 v51, v48, s19, v29
	global_store_dwordx2 v[30:31], v[50:51], off offset:128
	v_pk_mul_f32 v[50:51], v[84:85], v[4:5] op_sel_hi:[1,0]
	v_pk_mul_f32 v[48:49], v[86:87], v[4:5] op_sel_hi:[1,0]
	v_bfe_u32 v29, v50, 16, 1
	v_add3_u32 v29, v50, v29, s18
	v_bfe_u32 v50, v51, 16, 1
	v_lshrrev_b32_e32 v29, 16, v29
	v_add3_u32 v50, v51, v50, s18
	v_and_or_b32 v50, v50, s19, v29
	v_bfe_u32 v29, v48, 16, 1
	v_add3_u32 v29, v48, v29, s18
	v_bfe_u32 v48, v49, 16, 1
	v_lshrrev_b32_e32 v29, 16, v29
	v_add3_u32 v48, v49, v48, s18
	v_and_or_b32 v51, v48, s19, v29
	global_store_dwordx2 v[30:31], v[50:51], off offset:160
	v_pk_mul_f32 v[50:51], v[64:65], v[4:5] op_sel_hi:[1,0]
	v_pk_mul_f32 v[48:49], v[66:67], v[4:5] op_sel_hi:[1,0]
	v_bfe_u32 v29, v50, 16, 1
	v_add3_u32 v29, v50, v29, s18
	v_bfe_u32 v50, v51, 16, 1
	v_lshrrev_b32_e32 v29, 16, v29
	v_add3_u32 v50, v51, v50, s18
	v_and_or_b32 v50, v50, s19, v29
	v_bfe_u32 v29, v48, 16, 1
	v_add3_u32 v29, v48, v29, s18
	v_bfe_u32 v48, v49, 16, 1
	v_lshrrev_b32_e32 v29, 16, v29
	v_add3_u32 v48, v49, v48, s18
	v_and_or_b32 v51, v48, s19, v29
	ds_bpermute_b32 v29, v167, v52
	v_pk_mul_f32 v[44:45], v[44:45], v[4:5] op_sel_hi:[1,0]
	v_pk_mul_f32 v[46:47], v[46:47], v[4:5] op_sel_hi:[1,0]
	v_bfe_u32 v4, v44, 16, 1
	v_add3_u32 v4, v44, v4, s18
	v_bfe_u32 v44, v45, 16, 1
	v_lshrrev_b32_e32 v4, 16, v4
	v_add3_u32 v44, v45, v44, s18
	s_waitcnt lgkmcnt(0)
; __device__ __forceinline__ unsigned pk2(float lo, float hi) { return f2bf(lo) | (f2bf(hi) << 16); }
; __device__ __forceinline__ void xa_attn_fa(const Ctx& c, const bf16* Q, const bf16* KV, const bf16* XVT, bf16* Oo) {
;     ...
;         for (int mi = 0; mi < 2; ++mi) { float lt = l[mi]; lt += __shfl_xor(lt, 16); lt += __shfl_xor(lt, 32); const float il = 1.f / lt;
; #pragma unroll
;             for (int dt = 0; dt < 8; ++dt) { const f32x4 o = O[dt][mi] * il; v2u w; w.x = pk2(o[0], o[1]); w.y = pk2(o[2], o[3]);
;                 *(v2u*)(Oo + grow[mi] * 512 + hd * 128 + 16 * dt + 4 * lg) = w; } }
	v_fmac_f32_e32 v29, 0x3e800000, v28
	v_and_or_b32 v44, v44, s19, v4
	ds_bpermute_b32 v4, v194, v29
	v_bfe_u32 v28, v46, 16, 1
	v_add3_u32 v28, v46, v28, s18
	v_bfe_u32 v45, v47, 16, 1
	v_lshrrev_b32_e32 v28, 16, v28
	s_waitcnt lgkmcnt(0)
	v_add_f32_e32 v4, v29, v4
	v_div_scale_f32 v29, s[10:11], v4, v4, 1.0
	v_rcp_f32_e32 v46, v29
	v_add3_u32 v45, v47, v45, s18
	v_and_or_b32 v45, v45, s19, v28
	global_store_dwordx2 v[30:31], v[50:51], off offset:192
	v_fma_f32 v28, -v29, v46, 1.0
	v_fmac_f32_e32 v46, v28, v46
	v_div_scale_f32 v28, vcc, 1.0, v4, 1.0
	global_store_dwordx2 v[30:31], v[44:45], off offset:224
	v_mul_f32_e32 v30, v28, v46
	v_fma_f32 v31, -v29, v30, v28
	v_fmac_f32_e32 v30, v31, v46
	v_fma_f32 v28, -v29, v30, v28
	v_div_fmas_f32 v28, v28, v46, v30
	v_div_fixup_f32 v4, v28, v4, 1.0
	v_pk_mul_f32 v[30:31], v[40:41], v[4:5] op_sel_hi:[1,0]
	v_pk_mul_f32 v[28:29], v[42:43], v[4:5] op_sel_hi:[1,0]
	s_nop 4
	v_cvt_pk_bf16_f32 v30, v30, v31
	s_nop 4
	v_cvt_pk_bf16_f32 v31, v28, v29
	global_store_dwordx2 v[6:7], v[30:31], off
	v_pk_mul_f32 v[30:31], v[36:37], v[4:5] op_sel_hi:[1,0]
	v_pk_mul_f32 v[28:29], v[38:39], v[4:5] op_sel_hi:[1,0]
	s_nop 4
	v_cvt_pk_bf16_f32 v30, v30, v31
	s_nop 4
	v_cvt_pk_bf16_f32 v31, v28, v29
	global_store_dwordx2 v[6:7], v[30:31], off offset:32
	v_pk_mul_f32 v[30:31], v[32:33], v[4:5] op_sel_hi:[1,0]
	v_pk_mul_f32 v[28:29], v[34:35], v[4:5] op_sel_hi:[1,0]
	s_nop 4
	v_cvt_pk_bf16_f32 v30, v30, v31
	s_nop 4
	v_pk_mul_f32 v[24:25], v[24:25], v[4:5] op_sel_hi:[1,0]
	v_cvt_pk_bf16_f32 v31, v28, v29
	s_nop 2
	v_pk_mul_f32 v[26:27], v[26:27], v[4:5] op_sel_hi:[1,0]
	s_nop 1
	v_cvt_pk_bf16_f32 v24, v24, v25
	v_bfe_u32 v25, v26, 16, 1
	v_add3_u32 v25, v26, v25, s18
	v_bfe_u32 v26, v27, 16, 1
	v_lshrrev_b32_e32 v25, 16, v25
	v_add3_u32 v26, v27, v26, s18
	v_and_or_b32 v25, v26, s19, v25
	v_pk_mul_f32 v[20:21], v[20:21], v[4:5] op_sel_hi:[1,0]
	global_store_dwordx2 v[6:7], v[24:25], off offset:96
	s_nop 2
	v_pk_mul_f32 v[22:23], v[22:23], v[4:5] op_sel_hi:[1,0]
	s_nop 1
	v_cvt_pk_bf16_f32 v20, v20, v21
	v_bfe_u32 v21, v22, 16, 1
	v_add3_u32 v21, v22, v21, s18
	v_bfe_u32 v22, v23, 16, 1
	v_lshrrev_b32_e32 v21, 16, v21
	v_add3_u32 v22, v23, v22, s18
	v_and_or_b32 v21, v22, s19, v21
	v_pk_mul_f32 v[16:17], v[16:17], v[4:5] op_sel_hi:[1,0]
	global_store_dwordx2 v[6:7], v[20:21], off offset:128
	s_nop 2
	v_pk_mul_f32 v[18:19], v[18:19], v[4:5] op_sel_hi:[1,0]
	s_nop 1
	v_cvt_pk_bf16_f32 v16, v16, v17
	v_bfe_u32 v17, v18, 16, 1
	v_add3_u32 v17, v18, v17, s18
	v_bfe_u32 v18, v19, 16, 1
	v_lshrrev_b32_e32 v17, 16, v17
	v_add3_u32 v18, v19, v18, s18
	v_and_or_b32 v17, v18, s19, v17
	v_pk_mul_f32 v[12:13], v[12:13], v[4:5] op_sel_hi:[1,0]
	v_pk_mul_f32 v[8:9], v[8:9], v[4:5] op_sel_hi:[1,0]
	global_store_dwordx2 v[6:7], v[16:17], off offset:160
	v_pk_mul_f32 v[14:15], v[14:15], v[4:5] op_sel_hi:[1,0]
	s_nop 0
	v_pk_mul_f32 v[10:11], v[10:11], v[4:5] op_sel_hi:[1,0]
	v_bfe_u32 v4, v8, 16, 1
	s_nop 1
	v_add3_u32 v4, v8, v4, s18
	v_bfe_u32 v8, v9, 16, 1
	s_nop 1
	v_lshrrev_b32_e32 v4, 16, v4
	v_add3_u32 v8, v9, v8, s18
	v_cvt_pk_bf16_f32 v12, v12, v13
	v_bfe_u32 v13, v14, 16, 1
	v_and_or_b32 v8, v8, s19, v4
	v_bfe_u32 v4, v10, 16, 1
	v_add3_u32 v13, v14, v13, s18
	v_bfe_u32 v14, v15, 16, 1
	v_add3_u32 v4, v10, v4, s18
	v_bfe_u32 v9, v11, 16, 1
	v_lshrrev_b32_e32 v13, 16, v13
	v_add3_u32 v14, v15, v14, s18
	v_lshrrev_b32_e32 v4, 16, v4
	v_add3_u32 v9, v11, v9, s18
	v_and_or_b32 v13, v14, s19, v13
	v_and_or_b32 v9, v9, s19, v4
	global_store_dwordx2 v[6:7], v[30:31], off offset:64
	global_store_dwordx2 v[6:7], v[12:13], off offset:192
	global_store_dwordx2 v[6:7], v[8:9], off offset:224
	s_cbranch_scc0 .LBB0_4153

; __device__ __forceinline__ void postnorm(const Ctx& c, const bf16* MF, bf16* XB, float* RS, const float* gpost, float* OUT) {
;     for (int row = c.gw; row < MT; row += c.NGW) {
;         const v4u* mr = (const v4u*)(MF + (size_t)row * DM) + c.lane; v4u* xr = (v4u*)(XB + (size_t)row * DM) + c.lane;
;         v4u mv[4], xv[4]; float v[4][8]; float s = 0.f;
; #pragma unroll
;         for (int j = 0; j < 4; ++j) { mv[j] = mr[64 * j]; xv[j] = xr[64 * j]; }
; #pragma unroll
;         for (int j = 0; j < 4; ++j)
; #pragma unroll
;             for (int k = 0; k < 4; ++k) { v[j][2 * k] = bflo(mv[j][k]); v[j][2 * k + 1] = bfhi(mv[j][k]); s += v[j][2 * k] * v[j][2 * k] + v[j][2 * k + 1] * v[j][2 * k + 1]; }
;         const float rs = rsqrtf(wave_sum(s) * (1.f / DM) + EPS);
;         float s2 = 0.f;
; #pragma unroll
.LBB0_4571:
	v_readlane_b32 s8, v253, 0
	v_readlane_b32 s9, v253, 1
	s_nop 1
	v_lshl_add_u64 v[34:35], s[8:9], 0, v[36:37]
	v_add_co_u32_e32 v58, vcc, 0xd400000, v34
	s_nop 1
	v_addc_co_u32_e32 v59, vcc, 0, v35, vcc
	s_waitcnt lgkmcnt(0)
	global_load_dwordx4 v[46:49], v[58:59], off
	global_load_dwordx4 v[50:53], v[58:59], off offset:1024
	global_load_dwordx4 v[54:57], v[58:59], off offset:2048
	s_nop 0
	global_load_dwordx4 v[58:61], v[58:59], off offset:3072
	v_add_co_u32_e32 v34, vcc, 0x9400000, v34
	s_waitcnt vmcnt(3)
	v_lshlrev_b32_e32 v79, 16, v47
	v_addc_co_u32_e32 v35, vcc, 0, v35, vcc
	global_load_dwordx4 v[62:65], v[34:35], off
	global_load_dwordx4 v[66:69], v[34:35], off offset:1024
	global_load_dwordx4 v[70:73], v[34:35], off offset:2048
	global_load_dwordx4 v[74:77], v[34:35], off offset:3072
	v_lshlrev_b32_e32 v78, 16, v46
	v_and_b32_e32 v47, 0xffff0000, v47
	v_and_b32_e32 v46, 0xffff0000, v46
	v_lshlrev_b32_e32 v81, 16, v49
	v_lshlrev_b32_e32 v80, 16, v48
	v_and_b32_e32 v49, 0xffff0000, v49
	v_and_b32_e32 v48, 0xffff0000, v48
	v_pk_mul_f32 v[94:95], v[46:47], v[46:47]
	v_pk_mul_f32 v[98:99], v[48:49], v[48:49]
	v_pk_fma_f32 v[94:95], v[78:79], v[78:79], v[94:95]
	s_waitcnt vmcnt(6)
	v_lshlrev_b32_e32 v83, 16, v51
	v_lshlrev_b32_e32 v82, 16, v50
	v_and_b32_e32 v51, 0xffff0000, v51
	v_and_b32_e32 v50, 0xffff0000, v50
	v_pk_fma_f32 v[98:99], v[80:81], v[80:81], v[98:99]
	v_add_f32_e32 v94, v94, v95
	v_pk_mul_f32 v[102:103], v[50:51], v[50:51]
	v_add_f32_e32 v94, v98, v94
	v_lshlrev_b32_e32 v85, 16, v53
	v_lshlrev_b32_e32 v84, 16, v52
	v_and_b32_e32 v53, 0xffff0000, v53
	v_and_b32_e32 v52, 0xffff0000, v52
	v_pk_fma_f32 v[102:103], v[82:83], v[82:83], v[102:103]
	v_add_f32_e32 v94, v99, v94
	v_pk_mul_f32 v[104:105], v[52:53], v[52:53]
	v_add_f32_e32 v94, v102, v94
	s_waitcnt vmcnt(5)
	v_lshlrev_b32_e32 v87, 16, v55
	v_lshlrev_b32_e32 v86, 16, v54
	v_and_b32_e32 v55, 0xffff0000, v55
	v_and_b32_e32 v54, 0xffff0000, v54
	v_pk_fma_f32 v[104:105], v[84:85], v[84:85], v[104:105]
	v_add_f32_e32 v94, v103, v94
	v_pk_mul_f32 v[106:107], v[54:55], v[54:55]
	v_add_f32_e32 v94, v104, v94
	v_lshlrev_b32_e32 v89, 16, v57
	v_lshlrev_b32_e32 v88, 16, v56
	v_and_b32_e32 v57, 0xffff0000, v57
	v_and_b32_e32 v56, 0xffff0000, v56
	v_pk_fma_f32 v[106:107], v[86:87], v[86:87], v[106:107]
	v_add_f32_e32 v94, v105, v94
	v_pk_mul_f32 v[108:109], v[56:57], v[56:57]
	v_add_f32_e32 v94, v106, v94
	s_waitcnt vmcnt(4)
	v_lshlrev_b32_e32 v91, 16, v59
	v_lshlrev_b32_e32 v90, 16, v58
	v_and_b32_e32 v59, 0xffff0000, v59
	v_and_b32_e32 v58, 0xffff0000, v58
	v_pk_fma_f32 v[108:109], v[88:89], v[88:89], v[108:109]
	v_add_f32_e32 v94, v107, v94
	v_pk_mul_f32 v[110:111], v[58:59], v[58:59]
	v_add_f32_e32 v94, v108, v94
	v_lshlrev_b32_e32 v93, 16, v61
	v_lshlrev_b32_e32 v92, 16, v60
	v_and_b32_e32 v61, 0xffff0000, v61
	v_and_b32_e32 v60, 0xffff0000, v60
	v_pk_fma_f32 v[110:111], v[90:91], v[90:91], v[110:111]
	v_add_f32_e32 v94, v109, v94
	v_pk_mul_f32 v[112:113], v[60:61], v[60:61]
	v_add_f32_e32 v94, v110, v94
	v_pk_fma_f32 v[112:113], v[92:93], v[92:93], v[112:113]
	v_add_f32_e32 v94, v111, v94
	v_add_f32_e32 v94, v112, v94
	v_add_f32_e32 v94, v113, v94
	ds_bpermute_b32 v98, v40, v94
	s_waitcnt lgkmcnt(0)
	v_add_f32_e32 v98, v94, v98
	ds_bpermute_b32 v102, v41, v98
	s_waitcnt lgkmcnt(0)
	v_add_f32_e32 v102, v98, v102
	ds_bpermute_b32 v104, v42, v102
	s_waitcnt vmcnt(3)
	v_lshlrev_b32_e32 v97, 16, v63
	v_lshlrev_b32_e32 v96, 16, v62
	v_and_b32_e32 v63, 0xffff0000, v63
	s_waitcnt lgkmcnt(0)
	v_add_f32_e32 v104, v102, v104
	ds_bpermute_b32 v106, v43, v104
	v_and_b32_e32 v62, 0xffff0000, v62
	v_lshlrev_b32_e32 v101, 16, v65
	v_lshlrev_b32_e32 v100, 16, v64
	v_and_b32_e32 v65, 0xffff0000, v65
	s_waitcnt lgkmcnt(0)
	v_add_f32_e32 v106, v104, v106
	ds_bpermute_b32 v108, v44, v106
	v_and_b32_e32 v64, 0xffff0000, v64
	s_waitcnt vmcnt(0)
	v_lshlrev_b32_e32 v109, 16, v77
	v_and_b32_e32 v77, 0xffff0000, v77
	v_lshlrev_b32_e32 v95, 16, v67
	s_waitcnt lgkmcnt(0)
	v_add_f32_e32 v108, v106, v108
	ds_bpermute_b32 v110, v45, v108
	v_lshlrev_b32_e32 v94, 16, v66
	v_and_b32_e32 v67, 0xffff0000, v67
	v_and_b32_e32 v66, 0xffff0000, v66
	v_lshlrev_b32_e32 v99, 16, v69
	s_waitcnt lgkmcnt(0)
	v_add_f32_e32 v108, v108, v110
	v_fmamk_f32 v108, v108, 0x3a000000, v3
	v_mul_f32_e32 v110, 0x4b800000, v108
	v_cmp_gt_f32_e32 vcc, s13, v108
	v_lshlrev_b32_e32 v98, 16, v68
	v_and_b32_e32 v69, 0xffff0000, v69
	v_cndmask_b32_e32 v108, v108, v110, vcc
	v_rsq_f32_e32 v110, v108
	v_lshlrev_b32_e32 v108, 16, v76
	v_and_b32_e32 v76, 0xffff0000, v76
	v_and_b32_e32 v68, 0xffff0000, v68
	v_mul_f32_e32 v111, 0x45800000, v110
	v_cndmask_b32_e32 v110, v110, v111, vcc
	v_pk_mul_f32 v[46:47], v[110:111], v[46:47] op_sel_hi:[0,1]
	v_pk_mul_f32 v[78:79], v[110:111], v[78:79] op_sel_hi:[0,1]
	v_pk_mul_f32 v[48:49], v[110:111], v[48:49] op_sel_hi:[0,1]
	v_pk_fma_f32 v[46:47], v[38:39], v[46:47], v[62:63]
	v_pk_mul_f32 v[60:61], v[110:111], v[60:61] op_sel_hi:[0,1]
	v_pk_mul_f32 v[80:81], v[110:111], v[80:81] op_sel_hi:[0,1]
	v_pk_fma_f32 v[78:79], v[4:5], v[78:79], v[96:97]
	v_pk_fma_f32 v[48:49], v[6:7], v[48:49], v[64:65]
	v_pk_fma_f32 v[60:61], v[30:31], v[60:61], v[76:77]
	v_pk_mul_f32 v[76:77], v[46:47], v[46:47]
	v_pk_mul_f32 v[50:51], v[110:111], v[50:51] op_sel_hi:[0,1]
	v_pk_fma_f32 v[62:63], v[8:9], v[80:81], v[100:101]
	v_pk_fma_f32 v[76:77], v[78:79], v[78:79], v[76:77]
	v_pk_mul_f32 v[80:81], v[48:49], v[48:49]
	v_pk_mul_f32 v[82:83], v[110:111], v[82:83] op_sel_hi:[0,1]
	v_pk_fma_f32 v[50:51], v[10:11], v[50:51], v[66:67]
	v_pk_fma_f32 v[80:81], v[62:63], v[62:63], v[80:81]
	v_add_f32_e32 v76, v76, v77
; __device__ __forceinline__ unsigned pk2(float lo, float hi) { return f2bf(lo) | (f2bf(hi) << 16); }
; __device__ __forceinline__ void postnorm(const Ctx& c, const bf16* MF, bf16* XB, float* RS, const float* gpost, float* OUT) {
;     ...
;         for (int j = 0; j < 4; ++j) { const float* gp = gpost + (c.lane + 64 * j) * 8; const f32x4 g0 = *(CF4)gp, g1 = *(CF4)(gp + 4);
; #pragma unroll
;             for (int k = 0; k < 4; ++k) { const float ga = (k < 2) ? g0[2 * k] : g1[2 * k - 4], gb = (k < 2) ? g0[2 * k + 1] : g1[2 * k - 3];
;                 v[j][2 * k] = bflo(xv[j][k]) + v[j][2 * k] * rs * ga; v[j][2 * k + 1] = bfhi(xv[j][k]) + v[j][2 * k + 1] * rs * gb;
;                 s2 += v[j][2 * k] * v[j][2 * k] + v[j][2 * k + 1] * v[j][2 * k + 1]; } }
;         if (OUT) {
; #pragma unroll
;             for (int j = 0; j < 4; ++j) { float* op = OUT + (size_t)row * DM + (c.lane + 64 * j) * 8; *(f32x4*)op = (f32x4){v[j][0], v[j][1], v[j][2], v[j][3]}; *(f32x4*)(op + 4) = (f32x4){v[j][4], v[j][5], v[j][6], v[j][7]}; }
;         } else {
; #pragma unroll
;             for (int j = 0; j < 4; ++j) { v4u o; o.x = pk2(v[j][0], v[j][1]); o.y = pk2(v[j][2], v[j][3]); o.z = pk2(v[j][4], v[j][5]); o.w = pk2(v[j][6], v[j][7]); xr[64 * j] = o; }
;             const float rs2 = rsqrtf(wave_sum(s2) * (1.f / DM) + EPS); if (c.lane == 0) RS[row] = rs2;
	v_pk_fma_f32 v[64:65], v[12:13], v[82:83], v[94:95]
	v_pk_mul_f32 v[82:83], v[50:51], v[50:51]
	v_add_f32_e32 v76, v80, v76
	v_pk_fma_f32 v[82:83], v[64:65], v[64:65], v[82:83]
	v_add_f32_e32 v76, v81, v76
	v_add_f32_e32 v76, v82, v76
	v_bfe_u32 v77, v49, 16, 1
	v_bfe_u32 v80, v48, 16, 1
	v_bfe_u32 v81, v47, 16, 1
	v_bfe_u32 v82, v46, 16, 1
	v_pk_mul_f32 v[52:53], v[110:111], v[52:53] op_sel_hi:[0,1]
	v_add3_u32 v46, v46, v82, s14
	v_add3_u32 v47, v47, v81, s14
	v_add3_u32 v48, v48, v80, s14
	v_add3_u32 v49, v49, v77, s14
	v_bfe_u32 v77, v78, 16, 1
	v_bfe_u32 v80, v79, 16, 1
	v_bfe_u32 v81, v62, 16, 1
	v_bfe_u32 v82, v63, 16, 1
	v_pk_mul_f32 v[84:85], v[110:111], v[84:85] op_sel_hi:[0,1]
	v_pk_fma_f32 v[52:53], v[14:15], v[52:53], v[68:69]
	v_add3_u32 v63, v63, v82, s14
	v_add3_u32 v62, v62, v81, s14
	v_add3_u32 v79, v79, v80, s14
	v_add3_u32 v77, v78, v77, s14
	v_lshlrev_b32_e32 v103, 16, v71
	v_lshlrev_b32_e32 v102, 16, v70
	v_and_b32_e32 v71, 0xffff0000, v71
	v_and_b32_e32 v70, 0xffff0000, v70
	v_pk_fma_f32 v[66:67], v[16:17], v[84:85], v[98:99]
	v_pk_mul_f32 v[54:55], v[110:111], v[54:55] op_sel_hi:[0,1]
	v_pk_mul_f32 v[84:85], v[52:53], v[52:53]
	v_lshrrev_b32_e32 v77, 16, v77
	v_lshrrev_b32_e32 v78, 16, v79
	v_lshrrev_b32_e32 v62, 16, v62
	v_lshrrev_b32_e32 v63, 16, v63
	v_pk_mul_f32 v[68:69], v[110:111], v[86:87] op_sel_hi:[0,1]
	v_pk_fma_f32 v[54:55], v[18:19], v[54:55], v[70:71]
	v_pk_fma_f32 v[84:85], v[66:67], v[66:67], v[84:85]
	v_add_f32_e32 v76, v83, v76
	v_and_or_b32 v49, v49, s10, v63
	v_and_or_b32 v48, v48, s10, v62
	v_and_or_b32 v47, v47, s10, v78
	v_and_or_b32 v46, v46, s10, v77
	v_lshlrev_b32_e32 v105, 16, v73
	v_lshlrev_b32_e32 v104, 16, v72
	v_and_b32_e32 v73, 0xffff0000, v73
	v_and_b32_e32 v72, 0xffff0000, v72
	v_pk_fma_f32 v[68:69], v[20:21], v[68:69], v[102:103]
	v_pk_mul_f32 v[56:57], v[110:111], v[56:57] op_sel_hi:[0,1]
	v_pk_mul_f32 v[86:87], v[54:55], v[54:55]
	v_add_f32_e32 v76, v84, v76
	global_store_dwordx4 v[34:35], v[46:49], off
	v_pk_mul_f32 v[70:71], v[110:111], v[88:89] op_sel_hi:[0,1]
	v_pk_fma_f32 v[56:57], v[22:23], v[56:57], v[72:73]
	v_bfe_u32 v46, v53, 16, 1
	v_bfe_u32 v47, v52, 16, 1
	v_bfe_u32 v48, v51, 16, 1
	v_bfe_u32 v49, v50, 16, 1
	v_pk_fma_f32 v[86:87], v[68:69], v[68:69], v[86:87]
	v_add_f32_e32 v76, v85, v76
	v_add3_u32 v50, v50, v49, s14
	v_add3_u32 v51, v51, v48, s14
	v_add3_u32 v47, v52, v47, s14
	v_add3_u32 v46, v53, v46, s14
	v_bfe_u32 v48, v64, 16, 1
	v_bfe_u32 v49, v65, 16, 1
	v_bfe_u32 v52, v66, 16, 1
	v_bfe_u32 v53, v67, 16, 1
	v_lshlrev_b32_e32 v107, 16, v75
	v_lshlrev_b32_e32 v106, 16, v74
	v_and_b32_e32 v75, 0xffff0000, v75
	v_and_b32_e32 v74, 0xffff0000, v74
	v_pk_fma_f32 v[70:71], v[24:25], v[70:71], v[104:105]
	v_pk_mul_f32 v[58:59], v[110:111], v[58:59] op_sel_hi:[0,1]
	v_pk_mul_f32 v[88:89], v[56:57], v[56:57]
	v_add_f32_e32 v76, v86, v76
	v_add3_u32 v53, v67, v53, s14
	v_add3_u32 v52, v66, v52, s14
	v_add3_u32 v49, v65, v49, s14
	v_add3_u32 v48, v64, v48, s14
	v_pk_mul_f32 v[72:73], v[110:111], v[90:91] op_sel_hi:[0,1]
	v_pk_fma_f32 v[58:59], v[26:27], v[58:59], v[74:75]
	v_pk_fma_f32 v[88:89], v[70:71], v[70:71], v[88:89]
	v_add_f32_e32 v76, v87, v76
	v_lshrrev_b32_e32 v62, 16, v48
	v_lshrrev_b32_e32 v63, 16, v49
	v_lshrrev_b32_e32 v48, 16, v52
	v_lshrrev_b32_e32 v49, 16, v53
	v_pk_fma_f32 v[72:73], v[28:29], v[72:73], v[106:107]
	v_pk_mul_f32 v[90:91], v[58:59], v[58:59]
	v_add_f32_e32 v76, v88, v76
	v_and_or_b32 v49, v46, s10, v49
	v_and_or_b32 v48, v47, s10, v48
	v_and_or_b32 v47, v51, s10, v63
	v_and_or_b32 v46, v50, s10, v62
	v_pk_mul_f32 v[74:75], v[110:111], v[92:93] op_sel_hi:[0,1]
	v_pk_fma_f32 v[90:91], v[72:73], v[72:73], v[90:91]
	v_add_f32_e32 v76, v89, v76
	global_store_dwordx4 v[34:35], v[46:49], off offset:1024
	v_pk_fma_f32 v[74:75], v[32:33], v[74:75], v[108:109]
	v_pk_mul_f32 v[92:93], v[60:61], v[60:61]
	v_bfe_u32 v48, v55, 16, 1
	v_bfe_u32 v49, v54, 16, 1
	v_add_f32_e32 v76, v90, v76
	v_add3_u32 v50, v54, v49, s14
	v_add3_u32 v51, v55, v48, s14
	v_bfe_u32 v48, v68, 16, 1
	v_bfe_u32 v49, v69, 16, 1
	v_bfe_u32 v52, v70, 16, 1
	v_bfe_u32 v53, v71, 16, 1
	v_pk_fma_f32 v[92:93], v[74:75], v[74:75], v[92:93]
	v_add_f32_e32 v76, v91, v76
	v_bfe_u32 v46, v57, 16, 1
	v_bfe_u32 v47, v56, 16, 1
	v_add3_u32 v53, v71, v53, s14
	v_add3_u32 v52, v70, v52, s14
	v_add3_u32 v49, v69, v49, s14
	v_add3_u32 v48, v68, v48, s14
	v_add_f32_e32 v76, v92, v76
	v_add3_u32 v47, v56, v47, s14
	v_add3_u32 v46, v57, v46, s14
	v_lshrrev_b32_e32 v54, 16, v48
	v_lshrrev_b32_e32 v55, 16, v49
	v_lshrrev_b32_e32 v48, 16, v52
	v_lshrrev_b32_e32 v49, 16, v53
	v_add_f32_e32 v76, v93, v76
	v_and_or_b32 v49, v46, s10, v49
	v_and_or_b32 v48, v47, s10, v48
	v_and_or_b32 v47, v51, s10, v55
	v_and_or_b32 v46, v50, s10, v54
	global_store_dwordx4 v[34:35], v[46:49], off offset:2048
	ds_bpermute_b32 v47, v40, v76
	v_bfe_u32 v50, v58, 16, 1
	v_add3_u32 v52, v58, v50, s14
	v_bfe_u32 v51, v72, 16, 1
	v_bfe_u32 v55, v75, 16, 1
	s_waitcnt lgkmcnt(0)
	v_add_f32_e32 v47, v76, v47
	ds_bpermute_b32 v50, v41, v47
	v_bfe_u32 v46, v61, 16, 1
	v_add3_u32 v55, v75, v55, s14
	v_add3_u32 v51, v72, v51, s14
	v_add3_u32 v46, v61, v46, s14
	s_waitcnt lgkmcnt(0)
	v_add_f32_e32 v47, v47, v50
	ds_bpermute_b32 v50, v42, v47
	v_lshrrev_b32_e32 v56, 16, v51
	v_lshrrev_b32_e32 v51, 16, v55
	v_and_or_b32 v51, v46, s10, v51
	s_nop 0
	s_waitcnt lgkmcnt(0)
	v_add_f32_e32 v47, v47, v50
	ds_bpermute_b32 v50, v43, v47
	v_bfe_u32 v54, v74, 16, 1
	v_bfe_u32 v48, v60, 16, 1
	s_nop 0
	v_add3_u32 v54, v74, v54, s14
	s_waitcnt lgkmcnt(0)
	v_add_f32_e32 v47, v47, v50
	ds_bpermute_b32 v50, v44, v47
	s_nop 1
	v_add3_u32 v48, v60, v48, s14
	s_nop 0
	s_waitcnt lgkmcnt(0)
	v_add_f32_e32 v46, v47, v50
	ds_bpermute_b32 v47, v45, v46
	v_lshrrev_b32_e32 v54, 16, v54
	v_and_or_b32 v50, v48, s10, v54
	v_cvt_pk_bf16_f32 v49, v73, v59
	v_and_or_b32 v48, v52, s10, v56
	global_store_dwordx4 v[34:35], v[48:51], off offset:3072
	s_and_saveexec_b64 s[8:9], s[0:1]
	s_cbranch_execz .LBB0_4570
	s_waitcnt lgkmcnt(0)
	v_add_f32_e32 v34, v46, v47
	v_fmamk_f32 v34, v34, 0x3a000000, v3
	v_mul_f32_e32 v35, 0x4b800000, v34
	v_cmp_gt_f32_e32 vcc, s13, v34
	v_readlane_b32 s16, v253, 0
	v_readlane_b32 s17, v253, 1
	v_cndmask_b32_e32 v34, v34, v35, vcc
	v_rsq_f32_e32 v34, v34
	s_add_u32 s16, s16, s11
	s_addc_u32 s17, s17, s12
	v_mul_f32_e32 v35, 0x45800000, v34
	v_cndmask_b32_e32 v34, v34, v35, vcc
	global_store_dword v251, v34, s[16:17]
	s_branch .LBB0_4570

; #define LAS __attribute__((address_space(3)))
; #define LDS_WAIT() asm volatile("s_waitcnt lgkmcnt(0)" ::: "memory")
; __device__ __forceinline__ unsigned pk2(float lo, float hi) { return f2bf(lo) | (f2bf(hi) << 16); }
;     ...
;     for (int it = gw0; it < items; it += ngw) {
;         const int kb = it / nblk, nb = it % nblk, k0 = 64 * kb, n0 = 64 * nb, nq = (lane & 15) * 4, kr = lane >> 4; const bool ok = (n0 + nq) < N;
;         f32x4 v[16];
; #pragma unroll
;         for (int i = 0; i < 16; ++i) v[i] = ok ? __builtin_nontemporal_load((const f32x4*)(W + (size_t)(k0 + 4 * i + kr) * N + n0 + nq)) : (f32x4){0.f, 0.f, 0.f, 0.f};
;         if (gain) {
; #pragma unroll
;             for (int i = 0; i < 16; ++i) v[i] *= gain[k0 + 4 * i + kr]; }
; #pragma unroll
;         for (int i = 0; i < 16; ++i) { LAS float* d = scr + (4 * i + kr) * 65 + nq; d[0] = v[i].x; d[1] = v[i].y; d[2] = v[i].z; d[3] = v[i].w; }
;         LDS_WAIT(); asm volatile("" ::: "memory");
;         const int c8 = lane & 7; int d0 = n0;
;         if (ffnmap) { const int bj = n0 >= FFH ? 1 : 0, chn = n0 - FFH * bj; d0 = 256 * (chn >> 7) + 128 * bj + (chn & 127); }
; #pragma unroll
;         for (int j = 0; j < 8; ++j) { const int n = (lane >> 3) + 8 * j; const LAS float* sp = scr + (8 * c8) * 65 + n;
;             v4u o; o.x = pk2(sp[0 * 65], sp[1 * 65]); o.y = pk2(sp[2 * 65], sp[3 * 65]); o.z = pk2(sp[4 * 65], sp[5 * 65]); o.w = pk2(sp[6 * 65], sp[7 * 65]);
;             *(v4u*)(WT + (size_t)(d0 + n) * K + k0 + 8 * c8) = o; }
.LBB0_4576:
	s_or_b64 exec, exec, s[8:9]
	v_lshl_add_u64 v[72:73], v[72:73], 2, s[2:3]
	global_load_dword v74, v[72:73], off
	global_load_dword v82, v[72:73], off offset:16
	global_load_dword v84, v[72:73], off offset:32
	global_load_dword v86, v[72:73], off offset:48
	global_load_dword v88, v[72:73], off offset:64
	global_load_dword v90, v[72:73], off offset:80
	global_load_dword v92, v[72:73], off offset:96
	global_load_dword v94, v[72:73], off offset:112
	global_load_dword v96, v[72:73], off offset:128
	global_load_dword v98, v[72:73], off offset:144
	global_load_dword v100, v[72:73], off offset:160
	global_load_dword v102, v[72:73], off offset:176
	global_load_dword v104, v[72:73], off offset:192
	global_load_dword v106, v[72:73], off offset:208
	s_nop 0
	global_load_dword v72, v[72:73], off offset:224
	v_lshl_add_u64 v[76:77], v[76:77], 2, s[2:3]
	global_load_dword v76, v[76:77], off
	v_add_u32_e32 v75, 0x418, v81
	v_add_u32_e32 v83, 0x828, v81
	v_add_u32_e32 v85, 0xc30, v81
	v_add_u32_e32 v87, 0xc38, v81
	v_add_u32_e32 v89, 0x1040, v81
	v_add_u32_e32 v91, 0x1048, v81
	v_add_u32_e32 v93, 0x1450, v81
	v_add_u32_e32 v95, 0x1458, v81
	s_waitcnt vmcnt(0)
	v_add_u32_e32 v97, 0x1860, v81
	v_add_u32_e32 v99, 0x1868, v81
	v_add_u32_e32 v73, 0x410, v81
	v_add_u32_e32 v77, 0x820, v81
	v_add_u32_e32 v101, 0x1c70, v81
	v_add_u32_e32 v103, 0x1c78, v81
	v_add_u32_e32 v105, 0x2080, v81
	v_add_u32_e32 v107, 0x2088, v81
	s_add_i32 s16, s16, s10
	s_ashr_i32 s7, s6, 31
	s_add_i32 s15, s15, s86
	s_add_i32 s10, s10, s11
	s_cmpk_lt_i32 s15, 0x100
	v_pk_mul_f32 v[4:5], v[4:5], v[74:75] op_sel_hi:[1,0]
	v_pk_mul_f32 v[6:7], v[6:7], v[74:75] op_sel_hi:[1,0]
	v_pk_mul_f32 v[14:15], v[14:15], v[82:83] op_sel_hi:[1,0]
	v_pk_mul_f32 v[12:13], v[12:13], v[82:83] op_sel_hi:[1,0]
	v_pk_mul_f32 v[10:11], v[10:11], v[84:85] op_sel_hi:[1,0]
	v_pk_mul_f32 v[8:9], v[8:9], v[84:85] op_sel_hi:[1,0]
	v_pk_mul_f32 v[22:23], v[22:23], v[86:87] op_sel_hi:[1,0]
	v_pk_mul_f32 v[20:21], v[20:21], v[86:87] op_sel_hi:[1,0]
	v_pk_mul_f32 v[18:19], v[18:19], v[88:89] op_sel_hi:[1,0]
	v_pk_mul_f32 v[16:17], v[16:17], v[88:89] op_sel_hi:[1,0]
	v_pk_mul_f32 v[30:31], v[30:31], v[90:91] op_sel_hi:[1,0]
	v_pk_mul_f32 v[28:29], v[28:29], v[90:91] op_sel_hi:[1,0]
	v_pk_mul_f32 v[26:27], v[26:27], v[92:93] op_sel_hi:[1,0]
	v_pk_mul_f32 v[24:25], v[24:25], v[92:93] op_sel_hi:[1,0]
	v_pk_mul_f32 v[38:39], v[38:39], v[94:95] op_sel_hi:[1,0]
	v_pk_mul_f32 v[36:37], v[36:37], v[94:95] op_sel_hi:[1,0]
	v_pk_mul_f32 v[34:35], v[34:35], v[96:97] op_sel_hi:[1,0]
	v_pk_mul_f32 v[32:33], v[32:33], v[96:97] op_sel_hi:[1,0]
	v_pk_mul_f32 v[44:45], v[44:45], v[98:99] op_sel_hi:[1,0]
	ds_write2_b32 v81, v4, v5 offset1:1
	ds_write2_b32 v81, v6, v7 offset0:2 offset1:3
	ds_write2_b32 v73, v12, v13 offset1:1
	ds_write2_b32 v75, v14, v15 offset1:1
	ds_write2_b32 v77, v8, v9 offset1:1
	ds_write2_b32 v83, v10, v11 offset1:1
	ds_write2_b32 v85, v20, v21 offset1:1
	ds_write2_b32 v87, v22, v23 offset1:1
	ds_write2_b32 v89, v16, v17 offset1:1
	ds_write2_b32 v91, v18, v19 offset1:1
	ds_write2_b32 v93, v28, v29 offset1:1
	ds_write2_b32 v95, v30, v31 offset1:1
	ds_write2_b32 v97, v24, v25 offset1:1
	ds_write2_b32 v99, v26, v27 offset1:1
	ds_write2_b32 v101, v36, v37 offset1:1
	ds_write2_b32 v103, v38, v39 offset1:1
	ds_write2_b32 v105, v32, v33 offset1:1
	ds_write2_b32 v107, v34, v35 offset1:1
	v_add_u32_e32 v4, 0x2490, v81
	v_pk_mul_f32 v[46:47], v[46:47], v[98:99] op_sel_hi:[1,0]
	ds_write2_b32 v4, v44, v45 offset1:1
	v_add_u32_e32 v4, 0x2498, v81
	v_pk_mul_f32 v[40:41], v[40:41], v[100:101] op_sel_hi:[1,0]
	ds_write2_b32 v4, v46, v47 offset1:1
	v_add_u32_e32 v4, 0x28a0, v81
	v_pk_mul_f32 v[42:43], v[42:43], v[100:101] op_sel_hi:[1,0]
	ds_write2_b32 v4, v40, v41 offset1:1
	v_add_u32_e32 v4, 0x28a8, v81
	v_pk_mul_f32 v[52:53], v[52:53], v[102:103] op_sel_hi:[1,0]
	ds_write2_b32 v4, v42, v43 offset1:1
	v_add_u32_e32 v4, 0x2cb0, v81
	v_pk_mul_f32 v[54:55], v[54:55], v[102:103] op_sel_hi:[1,0]
	ds_write2_b32 v4, v52, v53 offset1:1
	v_add_u32_e32 v4, 0x2cb8, v81
	v_pk_mul_f32 v[48:49], v[48:49], v[104:105] op_sel_hi:[1,0]
	ds_write2_b32 v4, v54, v55 offset1:1
	v_add_u32_e32 v4, 0x30c0, v81
	v_pk_mul_f32 v[50:51], v[50:51], v[104:105] op_sel_hi:[1,0]
	ds_write2_b32 v4, v48, v49 offset1:1
	v_add_u32_e32 v4, 0x30c8, v81
	v_pk_mul_f32 v[60:61], v[60:61], v[106:107] op_sel_hi:[1,0]
	ds_write2_b32 v4, v50, v51 offset1:1
	v_add_u32_e32 v4, 0x34d0, v81
	v_pk_mul_f32 v[62:63], v[62:63], v[106:107] op_sel_hi:[1,0]
	ds_write2_b32 v4, v60, v61 offset1:1
	v_add_u32_e32 v4, 0x34d8, v81
	v_pk_mul_f32 v[56:57], v[56:57], v[72:73] op_sel_hi:[1,0]
	ds_write2_b32 v4, v62, v63 offset1:1
	v_add_u32_e32 v4, 0x38e0, v81
	v_pk_mul_f32 v[58:59], v[58:59], v[72:73] op_sel_hi:[1,0]
	ds_write2_b32 v4, v56, v57 offset1:1
	v_add_u32_e32 v4, 0x38e8, v81
	v_pk_mul_f32 v[64:65], v[64:65], v[76:77] op_sel_hi:[1,0]
	ds_write2_b32 v4, v58, v59 offset1:1
	v_add_u32_e32 v4, 0x3cf0, v81
	v_pk_mul_f32 v[66:67], v[66:67], v[76:77] op_sel_hi:[1,0]
	ds_write2_b32 v4, v64, v65 offset1:1
	v_add_u32_e32 v4, 0x3cf8, v81
	ds_write2_b32 v4, v66, v67 offset1:1
	s_waitcnt lgkmcnt(0)
	ds_read2_b32 v[12:13], v80 offset1:8
	ds_read2_b32 v[14:15], v80 offset0:65 offset1:73
	ds_read2_b32 v[16:17], v80 offset0:130 offset1:138
	ds_read2_b32 v[18:19], v80 offset0:195 offset1:203
	v_add_u32_e32 v30, 0x400, v80
	s_waitcnt lgkmcnt(3)
	s_nop 1
	s_waitcnt lgkmcnt(2)
	s_nop 0
	ds_read2_b32 v[20:21], v30 offset0:4 offset1:12
	s_nop 1
	ds_read2_b32 v[22:23], v30 offset0:69 offset1:77
	v_cvt_pk_bf16_f32 v8, v12, v14
	s_waitcnt lgkmcnt(3)
	s_nop 1
	s_waitcnt lgkmcnt(2)
; #define LAS __attribute__((address_space(3)))
; #define LDS_WAIT() asm volatile("s_waitcnt lgkmcnt(0)" ::: "memory")
; __device__ __forceinline__ unsigned pk2(float lo, float hi) { return f2bf(lo) | (f2bf(hi) << 16); }
;     ...
; #pragma unroll
;         for (int j = 0; j < 8; ++j) { const int n = (lane >> 3) + 8 * j; const LAS float* sp = scr + (8 * c8) * 65 + n;
;             v4u o; o.x = pk2(sp[0 * 65], sp[1 * 65]); o.y = pk2(sp[2 * 65], sp[3 * 65]); o.z = pk2(sp[4 * 65], sp[5 * 65]); o.w = pk2(sp[6 * 65], sp[7 * 65]);
;             *(v4u*)(WT + (size_t)(d0 + n) * K + k0 + 8 * c8) = o; }
;         LDS_WAIT(); asm volatile("" ::: "memory");
	s_nop 0
	ds_read2_b32 v[24:25], v30 offset0:134 offset1:142
	s_nop 1
	ds_read2_b32 v[26:27], v30 offset0:199 offset1:207
	v_cvt_pk_bf16_f32 v9, v16, v18
	s_waitcnt lgkmcnt(3)
	s_nop 1
	s_waitcnt lgkmcnt(2)
	s_nop 2
	v_cvt_pk_bf16_f32 v10, v20, v22
	s_waitcnt lgkmcnt(1)
	s_nop 1
	s_waitcnt lgkmcnt(0)
	s_nop 2
	v_cvt_pk_bf16_f32 v11, v24, v26
	v_add_u32_e32 v6, s16, v79
	v_ashrrev_i32_e32 v7, 31, v6
	v_lshl_add_u64 v[4:5], s[6:7], 1, v[70:71]
	v_lshlrev_b64 v[28:29], 12, v[6:7]
	v_lshl_add_u64 v[28:29], v[4:5], 0, v[28:29]
	v_bfe_u32 v7, v13, 16, 1
	global_store_dwordx4 v[28:29], v[8:11], off
	v_add3_u32 v7, v13, v7, s13
	v_lshrrev_b32_e32 v7, 16, v7
	v_bfe_u32 v8, v15, 16, 1
	v_add3_u32 v8, v15, v8, s13
	v_and_or_b32 v8, v8, s14, v7
	s_nop 4
	v_cvt_pk_bf16_f32 v9, v17, v19
	s_nop 4
	v_cvt_pk_bf16_f32 v10, v21, v23
	s_nop 0
	v_add_u32_e32 v12, 8, v6
	s_nop 1
	v_ashrrev_i32_e32 v13, 31, v12
	s_nop 1
	v_lshlrev_b64 v[12:13], 12, v[12:13]
	v_cvt_pk_bf16_f32 v11, v25, v27
	ds_read2_b32 v[14:15], v80 offset0:16 offset1:24
	v_lshl_add_u64 v[12:13], v[4:5], 0, v[12:13]
	global_store_dwordx4 v[12:13], v[8:11], off
	ds_read2_b32 v[12:13], v80 offset0:81 offset1:89
	ds_read2_b32 v[16:17], v80 offset0:146 offset1:154
	ds_read2_b32 v[18:19], v80 offset0:211 offset1:219
	s_waitcnt lgkmcnt(3)
	s_nop 1
	s_waitcnt lgkmcnt(2)
	s_nop 0
	ds_read2_b32 v[20:21], v30 offset0:20 offset1:28
	s_nop 1
	ds_read2_b32 v[22:23], v30 offset0:85 offset1:93
	v_cvt_pk_bf16_f32 v8, v14, v12
	s_waitcnt lgkmcnt(3)
	s_nop 1
	s_waitcnt lgkmcnt(2)
	s_nop 0
	ds_read2_b32 v[24:25], v30 offset0:150 offset1:158
	s_nop 1
	ds_read2_b32 v[26:27], v30 offset0:215 offset1:223
	v_cvt_pk_bf16_f32 v9, v16, v18
	s_waitcnt lgkmcnt(3)
	s_nop 1
	s_waitcnt lgkmcnt(2)
	s_nop 2
	v_cvt_pk_bf16_f32 v10, v20, v22
	s_waitcnt lgkmcnt(1)
	s_nop 0
	v_add_u32_e32 v28, 16, v6
	s_nop 0
	s_waitcnt lgkmcnt(0)
	s_nop 0
	v_ashrrev_i32_e32 v29, 31, v28
	s_nop 1
	v_lshlrev_b64 v[28:29], 12, v[28:29]
	v_cvt_pk_bf16_f32 v11, v24, v26
	v_lshl_add_u64 v[28:29], v[4:5], 0, v[28:29]
	v_bfe_u32 v7, v15, 16, 1
	global_store_dwordx4 v[28:29], v[8:11], off
	v_add3_u32 v7, v15, v7, s13
	v_lshrrev_b32_e32 v7, 16, v7
	v_bfe_u32 v8, v13, 16, 1
	v_add3_u32 v8, v13, v8, s13
	v_and_or_b32 v8, v8, s14, v7
	s_nop 4
	v_cvt_pk_bf16_f32 v9, v17, v19
	s_nop 4
	v_cvt_pk_bf16_f32 v10, v21, v23
	s_nop 0
	v_add_u32_e32 v12, 24, v6
	s_nop 1
	v_ashrrev_i32_e32 v13, 31, v12
	s_nop 1
	v_lshlrev_b64 v[12:13], 12, v[12:13]
	v_cvt_pk_bf16_f32 v11, v25, v27
	ds_read2_b32 v[14:15], v80 offset0:32 offset1:40
	v_lshl_add_u64 v[12:13], v[4:5], 0, v[12:13]
	global_store_dwordx4 v[12:13], v[8:11], off
	ds_read2_b32 v[12:13], v80 offset0:97 offset1:105
	ds_read2_b32 v[16:17], v80 offset0:162 offset1:170
	ds_read2_b32 v[18:19], v80 offset0:227 offset1:235
	s_waitcnt lgkmcnt(3)
	s_nop 1
	s_waitcnt lgkmcnt(2)
	s_nop 0
	ds_read2_b32 v[20:21], v30 offset0:36 offset1:44
	s_nop 1
	ds_read2_b32 v[22:23], v30 offset0:101 offset1:109
	v_cvt_pk_bf16_f32 v8, v14, v12
	s_waitcnt lgkmcnt(3)
	s_nop 1
	s_waitcnt lgkmcnt(2)
	s_nop 0
	ds_read2_b32 v[24:25], v30 offset0:166 offset1:174
	s_nop 1
	ds_read2_b32 v[26:27], v30 offset0:231 offset1:239
	v_cvt_pk_bf16_f32 v9, v16, v18
	s_waitcnt lgkmcnt(3)
	s_nop 1
	s_waitcnt lgkmcnt(2)
	s_nop 2
	v_cvt_pk_bf16_f32 v10, v20, v22
	s_waitcnt lgkmcnt(1)
	s_nop 0
	v_add_u32_e32 v28, 32, v6
	s_nop 0
	s_waitcnt lgkmcnt(0)
	s_nop 0
	v_ashrrev_i32_e32 v29, 31, v28
	s_nop 1
	v_lshlrev_b64 v[28:29], 12, v[28:29]
	v_cvt_pk_bf16_f32 v11, v24, v26
	v_lshl_add_u64 v[28:29], v[4:5], 0, v[28:29]
	v_bfe_u32 v7, v15, 16, 1
	global_store_dwordx4 v[28:29], v[8:11], off
	v_add3_u32 v7, v15, v7, s13
	v_lshrrev_b32_e32 v7, 16, v7
	v_bfe_u32 v8, v13, 16, 1
	v_add3_u32 v8, v13, v8, s13
	v_and_or_b32 v8, v8, s14, v7
	s_nop 4
	v_cvt_pk_bf16_f32 v9, v17, v19
	s_nop 4
	v_cvt_pk_bf16_f32 v10, v21, v23
	s_nop 0
	v_add_u32_e32 v12, 40, v6
	s_nop 1
	v_ashrrev_i32_e32 v13, 31, v12
	s_nop 1
	v_lshlrev_b64 v[12:13], 12, v[12:13]
	v_cvt_pk_bf16_f32 v11, v25, v27
	ds_read2_b32 v[14:15], v80 offset0:48 offset1:56
	v_lshl_add_u64 v[12:13], v[4:5], 0, v[12:13]
	global_store_dwordx4 v[12:13], v[8:11], off
	ds_read2_b32 v[12:13], v80 offset0:113 offset1:121
	ds_read2_b32 v[16:17], v80 offset0:178 offset1:186
	ds_read2_b32 v[18:19], v80 offset0:243 offset1:251
	s_waitcnt lgkmcnt(3)
	s_nop 1
	s_waitcnt lgkmcnt(2)
	s_nop 0
	ds_read2_b32 v[20:21], v30 offset0:52 offset1:60
	s_nop 1
	ds_read2_b32 v[22:23], v30 offset0:117 offset1:125
	v_cvt_pk_bf16_f32 v8, v14, v12
	s_waitcnt lgkmcnt(3)
	s_nop 1
	s_waitcnt lgkmcnt(2)
	s_nop 0
	ds_read2_b32 v[24:25], v30 offset0:182 offset1:190
	s_nop 1
	ds_read2_b32 v[26:27], v30 offset0:247 offset1:255
	v_cvt_pk_bf16_f32 v9, v16, v18
	s_waitcnt lgkmcnt(3)
	s_nop 1
	s_waitcnt lgkmcnt(2)
	s_nop 2
	v_cvt_pk_bf16_f32 v10, v20, v22
	s_waitcnt lgkmcnt(1)
	s_nop 0
	v_add_u32_e32 v28, 48, v6
	s_nop 0
	s_waitcnt lgkmcnt(0)
	s_nop 0
	v_ashrrev_i32_e32 v29, 31, v28
	s_nop 1
	v_lshlrev_b64 v[28:29], 12, v[28:29]
	v_cvt_pk_bf16_f32 v11, v24, v26
	v_lshl_add_u64 v[28:29], v[4:5], 0, v[28:29]
	v_bfe_u32 v7, v15, 16, 1
	global_store_dwordx4 v[28:29], v[8:11], off
	v_add3_u32 v7, v15, v7, s13
	v_lshrrev_b32_e32 v7, 16, v7
	v_bfe_u32 v8, v13, 16, 1
	v_add3_u32 v8, v13, v8, s13
	v_and_or_b32 v8, v8, s14, v7
	s_nop 4
	v_cvt_pk_bf16_f32 v9, v17, v19
	s_nop 4
	v_cvt_pk_bf16_f32 v10, v21, v23
	s_nop 4
	v_add_u32_e32 v6, 56, v6
	v_cvt_pk_bf16_f32 v11, v25, v27
	v_ashrrev_i32_e32 v7, 31, v6
	v_lshlrev_b64 v[6:7], 12, v[6:7]
	v_lshl_add_u64 v[4:5], v[4:5], 0, v[6:7]
	global_store_dwordx4 v[4:5], v[8:11], off
	s_waitcnt lgkmcnt(0)
	s_cbranch_scc0 .LBB0_4609

; #define LAS __attribute__((address_space(3)))
; #define LDS_WAIT() asm volatile("s_waitcnt lgkmcnt(0)" ::: "memory")
; __device__ __forceinline__ unsigned pk2(float lo, float hi) { return f2bf(lo) | (f2bf(hi) << 16); }
;     ...
; #pragma unroll
;         for (int i = 0; i < 16; ++i) { LAS float* d = scr + (4 * i + kr) * 65 + nq; d[0] = v[i].x; d[1] = v[i].y; d[2] = v[i].z; d[3] = v[i].w; }
;         LDS_WAIT(); asm volatile("" ::: "memory");
;         const int c8 = lane & 7; int d0 = n0;
;         if (ffnmap) { const int bj = n0 >= FFH ? 1 : 0, chn = n0 - FFH * bj; d0 = 256 * (chn >> 7) + 128 * bj + (chn & 127); }
; #pragma unroll
;         for (int j = 0; j < 8; ++j) { const int n = (lane >> 3) + 8 * j; const LAS float* sp = scr + (8 * c8) * 65 + n;
;             v4u o; o.x = pk2(sp[0 * 65], sp[1 * 65]); o.y = pk2(sp[2 * 65], sp[3 * 65]); o.z = pk2(sp[4 * 65], sp[5 * 65]); o.w = pk2(sp[6 * 65], sp[7 * 65]);
;             *(v4u*)(WT + (size_t)(d0 + n) * K + k0 + 8 * c8) = o; }
.LBB0_4611:
	s_or_b64 exec, exec, s[6:7]
	s_waitcnt vmcnt(0)
	ds_write2_b32 v79, v4, v5 offset1:1
	ds_write2_b32 v79, v6, v7 offset0:2 offset1:3
	v_add_u32_e32 v4, 0x410, v79
	ds_write2_b32 v4, v12, v13 offset1:1
	v_add_u32_e32 v4, 0x418, v79
	ds_write2_b32 v4, v14, v15 offset1:1
	v_add_u32_e32 v4, 0x820, v79
	ds_write2_b32 v4, v8, v9 offset1:1
	v_add_u32_e32 v4, 0x828, v79
	ds_write2_b32 v4, v10, v11 offset1:1
	v_add_u32_e32 v4, 0xc30, v79
	ds_write2_b32 v4, v20, v21 offset1:1
	v_add_u32_e32 v4, 0xc38, v79
	ds_write2_b32 v4, v22, v23 offset1:1
	v_add_u32_e32 v4, 0x1040, v79
	ds_write2_b32 v4, v16, v17 offset1:1
	v_add_u32_e32 v4, 0x1048, v79
	ds_write2_b32 v4, v18, v19 offset1:1
	v_add_u32_e32 v4, 0x1450, v79
	ds_write2_b32 v4, v28, v29 offset1:1
	v_add_u32_e32 v4, 0x1458, v79
	ds_write2_b32 v4, v30, v31 offset1:1
	v_add_u32_e32 v4, 0x1860, v79
	ds_write2_b32 v4, v24, v25 offset1:1
	v_add_u32_e32 v4, 0x1868, v79
	ds_write2_b32 v4, v26, v27 offset1:1
	v_add_u32_e32 v4, 0x1c70, v79
	ds_write2_b32 v4, v36, v37 offset1:1
	v_add_u32_e32 v4, 0x1c78, v79
	ds_write2_b32 v4, v38, v39 offset1:1
	v_add_u32_e32 v4, 0x2080, v79
	ds_write2_b32 v4, v32, v33 offset1:1
	v_add_u32_e32 v4, 0x2088, v79
	ds_write2_b32 v4, v34, v35 offset1:1
	v_add_u32_e32 v4, 0x2490, v79
	ds_write2_b32 v4, v44, v45 offset1:1
	v_add_u32_e32 v4, 0x2498, v79
	ds_write2_b32 v4, v46, v47 offset1:1
	v_add_u32_e32 v4, 0x28a0, v79
	ds_write2_b32 v4, v40, v41 offset1:1
	v_add_u32_e32 v4, 0x28a8, v79
	ds_write2_b32 v4, v42, v43 offset1:1
	v_add_u32_e32 v4, 0x2cb0, v79
	ds_write2_b32 v4, v52, v53 offset1:1
	v_add_u32_e32 v4, 0x2cb8, v79
	ds_write2_b32 v4, v54, v55 offset1:1
	v_add_u32_e32 v4, 0x30c0, v79
	ds_write2_b32 v4, v48, v49 offset1:1
	v_add_u32_e32 v4, 0x30c8, v79
	ds_write2_b32 v4, v50, v51 offset1:1
	v_add_u32_e32 v4, 0x34d0, v79
	ds_write2_b32 v4, v60, v61 offset1:1
	v_add_u32_e32 v4, 0x34d8, v79
	ds_write2_b32 v4, v62, v63 offset1:1
	v_add_u32_e32 v4, 0x38e0, v79
	ds_write2_b32 v4, v56, v57 offset1:1
	v_add_u32_e32 v4, 0x38e8, v79
	ds_write2_b32 v4, v58, v59 offset1:1
	v_add_u32_e32 v4, 0x3cf0, v79
	ds_write2_b32 v4, v64, v65 offset1:1
	v_add_u32_e32 v4, 0x3cf8, v79
	ds_write2_b32 v4, v66, v67 offset1:1
	s_waitcnt lgkmcnt(0)
	ds_read2_b32 v[12:13], v78 offset1:8
	ds_read2_b32 v[14:15], v78 offset0:65 offset1:73
	ds_read2_b32 v[16:17], v78 offset0:130 offset1:138
	ds_read2_b32 v[18:19], v78 offset0:195 offset1:203
	v_add_u32_e32 v30, 0x400, v78
	s_waitcnt lgkmcnt(3)
	s_nop 1
	s_waitcnt lgkmcnt(2)
	s_nop 0
	ds_read2_b32 v[20:21], v30 offset0:4 offset1:12
	s_nop 1
	ds_read2_b32 v[22:23], v30 offset0:69 offset1:77
	v_cvt_pk_bf16_f32 v8, v12, v14
	s_waitcnt lgkmcnt(3)
	s_nop 1
	s_waitcnt lgkmcnt(2)
	s_nop 0
	ds_read2_b32 v[24:25], v30 offset0:134 offset1:142
	s_nop 1
	ds_read2_b32 v[26:27], v30 offset0:199 offset1:207
	v_cvt_pk_bf16_f32 v9, v16, v18
	s_waitcnt lgkmcnt(3)
	s_nop 1
	s_waitcnt lgkmcnt(2)
	s_nop 2
	v_cvt_pk_bf16_f32 v10, v20, v22
	s_waitcnt lgkmcnt(1)
	s_nop 1
	s_waitcnt lgkmcnt(0)
	s_nop 2
	s_add_i32 s17, s17, s12
	v_cvt_pk_bf16_f32 v11, v24, v26
	v_add_u32_e32 v6, s17, v77
	s_ashr_i32 s3, s2, 31
	v_ashrrev_i32_e32 v7, 31, v6
	v_lshl_add_u64 v[4:5], s[2:3], 1, v[70:71]
	v_lshlrev_b64 v[28:29], 12, v[6:7]
	v_lshl_add_u64 v[28:29], v[4:5], 0, v[28:29]
	v_bfe_u32 v7, v13, 16, 1
	global_store_dwordx4 v[28:29], v[8:11], off
	v_add3_u32 v7, v13, v7, s15
	v_lshrrev_b32_e32 v7, 16, v7
	v_bfe_u32 v8, v15, 16, 1
	v_add3_u32 v8, v15, v8, s15
	v_and_or_b32 v8, v8, s16, v7
	s_nop 4
	v_cvt_pk_bf16_f32 v9, v17, v19
	s_nop 4
	v_cvt_pk_bf16_f32 v10, v21, v23
	s_nop 0
	v_add_u32_e32 v12, 8, v6
	s_nop 1
	v_ashrrev_i32_e32 v13, 31, v12
	s_nop 1
	v_lshlrev_b64 v[12:13], 12, v[12:13]
	v_cvt_pk_bf16_f32 v11, v25, v27
	ds_read2_b32 v[14:15], v78 offset0:16 offset1:24
	v_lshl_add_u64 v[12:13], v[4:5], 0, v[12:13]
	global_store_dwordx4 v[12:13], v[8:11], off
	ds_read2_b32 v[12:13], v78 offset0:81 offset1:89
	ds_read2_b32 v[16:17], v78 offset0:146 offset1:154
	ds_read2_b32 v[18:19], v78 offset0:211 offset1:219
	s_waitcnt lgkmcnt(3)
	s_nop 1
	s_waitcnt lgkmcnt(2)
	s_nop 0
	ds_read2_b32 v[20:21], v30 offset0:20 offset1:28
	s_nop 1
	ds_read2_b32 v[22:23], v30 offset0:85 offset1:93
	v_cvt_pk_bf16_f32 v8, v14, v12
	s_waitcnt lgkmcnt(3)
; #define LAS __attribute__((address_space(3)))
; #define LDS_WAIT() asm volatile("s_waitcnt lgkmcnt(0)" ::: "memory")
; __device__ __forceinline__ unsigned pk2(float lo, float hi) { return f2bf(lo) | (f2bf(hi) << 16); }
;     ...
; #pragma unroll
;         for (int j = 0; j < 8; ++j) { const int n = (lane >> 3) + 8 * j; const LAS float* sp = scr + (8 * c8) * 65 + n;
;             v4u o; o.x = pk2(sp[0 * 65], sp[1 * 65]); o.y = pk2(sp[2 * 65], sp[3 * 65]); o.z = pk2(sp[4 * 65], sp[5 * 65]); o.w = pk2(sp[6 * 65], sp[7 * 65]);
;             *(v4u*)(WT + (size_t)(d0 + n) * K + k0 + 8 * c8) = o; }
;         LDS_WAIT(); asm volatile("" ::: "memory");
	s_nop 1
	s_waitcnt lgkmcnt(2)
	s_nop 0
	ds_read2_b32 v[24:25], v30 offset0:150 offset1:158
	s_nop 1
	ds_read2_b32 v[26:27], v30 offset0:215 offset1:223
	v_cvt_pk_bf16_f32 v9, v16, v18
	s_waitcnt lgkmcnt(3)
	s_nop 1
	s_waitcnt lgkmcnt(2)
	s_nop 2
	v_cvt_pk_bf16_f32 v10, v20, v22
	s_waitcnt lgkmcnt(1)
	s_nop 0
	v_add_u32_e32 v28, 16, v6
	s_nop 0
	s_waitcnt lgkmcnt(0)
	s_nop 0
	v_ashrrev_i32_e32 v29, 31, v28
	s_nop 1
	v_lshlrev_b64 v[28:29], 12, v[28:29]
	v_cvt_pk_bf16_f32 v11, v24, v26
	v_lshl_add_u64 v[28:29], v[4:5], 0, v[28:29]
	v_bfe_u32 v7, v15, 16, 1
	global_store_dwordx4 v[28:29], v[8:11], off
	v_add3_u32 v7, v15, v7, s15
	v_lshrrev_b32_e32 v7, 16, v7
	v_bfe_u32 v8, v13, 16, 1
	v_add3_u32 v8, v13, v8, s15
	v_and_or_b32 v8, v8, s16, v7
	s_nop 4
	v_cvt_pk_bf16_f32 v9, v17, v19
	s_nop 4
	v_cvt_pk_bf16_f32 v10, v21, v23
	s_nop 0
	v_add_u32_e32 v12, 24, v6
	s_nop 1
	v_ashrrev_i32_e32 v13, 31, v12
	s_nop 1
	v_lshlrev_b64 v[12:13], 12, v[12:13]
	v_cvt_pk_bf16_f32 v11, v25, v27
	ds_read2_b32 v[14:15], v78 offset0:32 offset1:40
	v_lshl_add_u64 v[12:13], v[4:5], 0, v[12:13]
	global_store_dwordx4 v[12:13], v[8:11], off
	ds_read2_b32 v[12:13], v78 offset0:97 offset1:105
	ds_read2_b32 v[16:17], v78 offset0:162 offset1:170
	ds_read2_b32 v[18:19], v78 offset0:227 offset1:235
	s_waitcnt lgkmcnt(3)
	s_nop 1
	s_waitcnt lgkmcnt(2)
	s_nop 0
	ds_read2_b32 v[20:21], v30 offset0:36 offset1:44
	s_nop 1
	ds_read2_b32 v[22:23], v30 offset0:101 offset1:109
	v_cvt_pk_bf16_f32 v8, v14, v12
	s_waitcnt lgkmcnt(3)
	s_nop 1
	s_waitcnt lgkmcnt(2)
	s_nop 0
	ds_read2_b32 v[24:25], v30 offset0:166 offset1:174
	s_nop 1
	ds_read2_b32 v[26:27], v30 offset0:231 offset1:239
	v_cvt_pk_bf16_f32 v9, v16, v18
	s_waitcnt lgkmcnt(3)
	s_nop 1
	s_waitcnt lgkmcnt(2)
	s_nop 2
	v_cvt_pk_bf16_f32 v10, v20, v22
	s_waitcnt lgkmcnt(1)
	s_nop 0
	v_add_u32_e32 v28, 32, v6
	s_nop 0
	s_waitcnt lgkmcnt(0)
	s_nop 0
	v_ashrrev_i32_e32 v29, 31, v28
	s_nop 1
	v_lshlrev_b64 v[28:29], 12, v[28:29]
	v_cvt_pk_bf16_f32 v11, v24, v26
	v_lshl_add_u64 v[28:29], v[4:5], 0, v[28:29]
	v_bfe_u32 v7, v15, 16, 1
	global_store_dwordx4 v[28:29], v[8:11], off
	v_add3_u32 v7, v15, v7, s15
	v_lshrrev_b32_e32 v7, 16, v7
	v_bfe_u32 v8, v13, 16, 1
	v_add3_u32 v8, v13, v8, s15
	v_and_or_b32 v8, v8, s16, v7
	s_nop 4
	v_cvt_pk_bf16_f32 v9, v17, v19
	s_nop 4
	v_cvt_pk_bf16_f32 v10, v21, v23
	s_nop 0
	v_add_u32_e32 v12, 40, v6
	s_nop 1
	v_ashrrev_i32_e32 v13, 31, v12
	s_nop 1
	v_lshlrev_b64 v[12:13], 12, v[12:13]
	v_cvt_pk_bf16_f32 v11, v25, v27
	ds_read2_b32 v[14:15], v78 offset0:48 offset1:56
	v_lshl_add_u64 v[12:13], v[4:5], 0, v[12:13]
	global_store_dwordx4 v[12:13], v[8:11], off
	ds_read2_b32 v[12:13], v78 offset0:113 offset1:121
	ds_read2_b32 v[16:17], v78 offset0:178 offset1:186
	ds_read2_b32 v[18:19], v78 offset0:243 offset1:251
	s_waitcnt lgkmcnt(3)
	s_nop 1
	s_waitcnt lgkmcnt(2)
	s_nop 0
	ds_read2_b32 v[20:21], v30 offset0:52 offset1:60
	s_nop 1
	ds_read2_b32 v[22:23], v30 offset0:117 offset1:125
	v_cvt_pk_bf16_f32 v8, v14, v12
	s_waitcnt lgkmcnt(3)
	s_nop 1
	s_waitcnt lgkmcnt(2)
	s_nop 0
	ds_read2_b32 v[24:25], v30 offset0:182 offset1:190
	s_nop 1
	ds_read2_b32 v[26:27], v30 offset0:247 offset1:255
	v_cvt_pk_bf16_f32 v9, v16, v18
	s_waitcnt lgkmcnt(3)
	s_nop 1
	s_waitcnt lgkmcnt(2)
	s_nop 2
	v_cvt_pk_bf16_f32 v10, v20, v22
	s_waitcnt lgkmcnt(1)
	s_nop 0
	v_add_u32_e32 v28, 48, v6
	s_nop 0
	s_waitcnt lgkmcnt(0)
	s_nop 0
	v_ashrrev_i32_e32 v29, 31, v28
	s_nop 1
	v_lshlrev_b64 v[28:29], 12, v[28:29]
	v_cvt_pk_bf16_f32 v11, v24, v26
	v_lshl_add_u64 v[28:29], v[4:5], 0, v[28:29]
	v_bfe_u32 v7, v15, 16, 1
	global_store_dwordx4 v[28:29], v[8:11], off
	v_add3_u32 v7, v15, v7, s15
	v_lshrrev_b32_e32 v7, 16, v7
	v_bfe_u32 v8, v13, 16, 1
	v_add3_u32 v8, v13, v8, s15
	v_and_or_b32 v8, v8, s16, v7
	s_nop 4
	v_cvt_pk_bf16_f32 v9, v17, v19
	s_nop 4
	v_cvt_pk_bf16_f32 v10, v21, v23
	s_nop 4
	v_add_u32_e32 v6, 56, v6
	v_cvt_pk_bf16_f32 v11, v25, v27
	v_ashrrev_i32_e32 v7, 31, v6
	v_lshlrev_b64 v[6:7], 12, v[6:7]
	v_lshl_add_u64 v[4:5], v[4:5], 0, v[6:7]
	global_store_dwordx4 v[4:5], v[8:11], off
	s_waitcnt lgkmcnt(0)
	s_add_i32 s11, s11, s86
	s_add_i32 s12, s12, s13
	s_cmpk_lt_i32 s11, 0x200
	s_cbranch_scc0 .LBB0_4644

; #define LAS __attribute__((address_space(3)))
; #define LDS_WAIT() asm volatile("s_waitcnt lgkmcnt(0)" ::: "memory")
; __device__ __forceinline__ unsigned pk2(float lo, float hi) { return f2bf(lo) | (f2bf(hi) << 16); }
;     ...
; #pragma unroll
;         for (int i = 0; i < 16; ++i) { LAS float* d = scr + (4 * i + kr) * 65 + nq; d[0] = v[i].x; d[1] = v[i].y; d[2] = v[i].z; d[3] = v[i].w; }
;         LDS_WAIT(); asm volatile("" ::: "memory");
;         const int c8 = lane & 7; int d0 = n0;
;         if (ffnmap) { const int bj = n0 >= FFH ? 1 : 0, chn = n0 - FFH * bj; d0 = 256 * (chn >> 7) + 128 * bj + (chn & 127); }
; #pragma unroll
;         for (int j = 0; j < 8; ++j) { const int n = (lane >> 3) + 8 * j; const LAS float* sp = scr + (8 * c8) * 65 + n;
;             v4u o; o.x = pk2(sp[0 * 65], sp[1 * 65]); o.y = pk2(sp[2 * 65], sp[3 * 65]); o.z = pk2(sp[4 * 65], sp[5 * 65]); o.w = pk2(sp[6 * 65], sp[7 * 65]);
;             *(v4u*)(WT + (size_t)(d0 + n) * K + k0 + 8 * c8) = o; }
.LBB0_4646:
	s_or_b64 exec, exec, s[6:7]
	s_waitcnt vmcnt(0)
	ds_write2_b32 v79, v4, v5 offset1:1
	ds_write2_b32 v79, v6, v7 offset0:2 offset1:3
	v_add_u32_e32 v4, 0x410, v79
	ds_write2_b32 v4, v12, v13 offset1:1
	v_add_u32_e32 v4, 0x418, v79
	ds_write2_b32 v4, v14, v15 offset1:1
	v_add_u32_e32 v4, 0x820, v79
	ds_write2_b32 v4, v8, v9 offset1:1
	v_add_u32_e32 v4, 0x828, v79
	ds_write2_b32 v4, v10, v11 offset1:1
	v_add_u32_e32 v4, 0xc30, v79
	ds_write2_b32 v4, v20, v21 offset1:1
	v_add_u32_e32 v4, 0xc38, v79
	ds_write2_b32 v4, v22, v23 offset1:1
	v_add_u32_e32 v4, 0x1040, v79
	ds_write2_b32 v4, v16, v17 offset1:1
	v_add_u32_e32 v4, 0x1048, v79
	ds_write2_b32 v4, v18, v19 offset1:1
	v_add_u32_e32 v4, 0x1450, v79
	ds_write2_b32 v4, v28, v29 offset1:1
	v_add_u32_e32 v4, 0x1458, v79
	ds_write2_b32 v4, v30, v31 offset1:1
	v_add_u32_e32 v4, 0x1860, v79
	ds_write2_b32 v4, v24, v25 offset1:1
	v_add_u32_e32 v4, 0x1868, v79
	ds_write2_b32 v4, v26, v27 offset1:1
	v_add_u32_e32 v4, 0x1c70, v79
	ds_write2_b32 v4, v36, v37 offset1:1
	v_add_u32_e32 v4, 0x1c78, v79
	ds_write2_b32 v4, v38, v39 offset1:1
	v_add_u32_e32 v4, 0x2080, v79
	ds_write2_b32 v4, v32, v33 offset1:1
	v_add_u32_e32 v4, 0x2088, v79
	ds_write2_b32 v4, v34, v35 offset1:1
	v_add_u32_e32 v4, 0x2490, v79
	ds_write2_b32 v4, v44, v45 offset1:1
	v_add_u32_e32 v4, 0x2498, v79
	ds_write2_b32 v4, v46, v47 offset1:1
	v_add_u32_e32 v4, 0x28a0, v79
	ds_write2_b32 v4, v40, v41 offset1:1
	v_add_u32_e32 v4, 0x28a8, v79
	ds_write2_b32 v4, v42, v43 offset1:1
	v_add_u32_e32 v4, 0x2cb0, v79
	ds_write2_b32 v4, v52, v53 offset1:1
	v_add_u32_e32 v4, 0x2cb8, v79
	ds_write2_b32 v4, v54, v55 offset1:1
	v_add_u32_e32 v4, 0x30c0, v79
	ds_write2_b32 v4, v48, v49 offset1:1
	v_add_u32_e32 v4, 0x30c8, v79
	ds_write2_b32 v4, v50, v51 offset1:1
	v_add_u32_e32 v4, 0x34d0, v79
	ds_write2_b32 v4, v60, v61 offset1:1
	v_add_u32_e32 v4, 0x34d8, v79
	ds_write2_b32 v4, v62, v63 offset1:1
	v_add_u32_e32 v4, 0x38e0, v79
	ds_write2_b32 v4, v56, v57 offset1:1
	v_add_u32_e32 v4, 0x38e8, v79
	ds_write2_b32 v4, v58, v59 offset1:1
	v_add_u32_e32 v4, 0x3cf0, v79
	ds_write2_b32 v4, v64, v65 offset1:1
	v_add_u32_e32 v4, 0x3cf8, v79
	ds_write2_b32 v4, v66, v67 offset1:1
	s_waitcnt lgkmcnt(0)
	ds_read2_b32 v[12:13], v78 offset1:8
	ds_read2_b32 v[14:15], v78 offset0:65 offset1:73
	ds_read2_b32 v[16:17], v78 offset0:130 offset1:138
	ds_read2_b32 v[18:19], v78 offset0:195 offset1:203
	v_add_u32_e32 v30, 0x400, v78
	s_waitcnt lgkmcnt(3)
	s_nop 1
	s_waitcnt lgkmcnt(2)
	s_nop 0
	ds_read2_b32 v[20:21], v30 offset0:4 offset1:12
	s_nop 1
	ds_read2_b32 v[22:23], v30 offset0:69 offset1:77
	v_cvt_pk_bf16_f32 v8, v12, v14
	s_waitcnt lgkmcnt(3)
	s_nop 1
	s_waitcnt lgkmcnt(2)
	s_nop 0
	ds_read2_b32 v[24:25], v30 offset0:134 offset1:142
	s_nop 1
	ds_read2_b32 v[26:27], v30 offset0:199 offset1:207
	v_cvt_pk_bf16_f32 v9, v16, v18
	s_waitcnt lgkmcnt(3)
	s_nop 1
	s_waitcnt lgkmcnt(2)
	s_nop 2
	v_cvt_pk_bf16_f32 v10, v20, v22
	s_waitcnt lgkmcnt(1)
	s_nop 1
	s_waitcnt lgkmcnt(0)
	s_nop 2
	s_add_i32 s17, s17, s12
	v_cvt_pk_bf16_f32 v11, v24, v26
	v_add_u32_e32 v6, s17, v77
	s_ashr_i32 s3, s2, 31
	v_ashrrev_i32_e32 v7, 31, v6
	v_lshl_add_u64 v[4:5], s[2:3], 1, v[70:71]
	v_lshlrev_b64 v[28:29], 10, v[6:7]
	v_lshl_add_u64 v[28:29], v[4:5], 0, v[28:29]
	v_bfe_u32 v7, v13, 16, 1
	global_store_dwordx4 v[28:29], v[8:11], off
	v_add3_u32 v7, v13, v7, s15
	v_lshrrev_b32_e32 v7, 16, v7
	v_bfe_u32 v8, v15, 16, 1
	v_add3_u32 v8, v15, v8, s15
	v_and_or_b32 v8, v8, s16, v7
	s_nop 4
	v_cvt_pk_bf16_f32 v9, v17, v19
	s_nop 4
	v_cvt_pk_bf16_f32 v10, v21, v23
	s_nop 0
	v_add_u32_e32 v12, 8, v6
	s_nop 1
	v_ashrrev_i32_e32 v13, 31, v12
	s_nop 1
	v_lshlrev_b64 v[12:13], 10, v[12:13]
	v_cvt_pk_bf16_f32 v11, v25, v27
	ds_read2_b32 v[14:15], v78 offset0:16 offset1:24
	v_lshl_add_u64 v[12:13], v[4:5], 0, v[12:13]
	global_store_dwordx4 v[12:13], v[8:11], off
	ds_read2_b32 v[12:13], v78 offset0:81 offset1:89
	ds_read2_b32 v[16:17], v78 offset0:146 offset1:154
	ds_read2_b32 v[18:19], v78 offset0:211 offset1:219
	s_waitcnt lgkmcnt(3)
	s_nop 1
	s_waitcnt lgkmcnt(2)
	s_nop 0
	ds_read2_b32 v[20:21], v30 offset0:20 offset1:28
	s_nop 1
	ds_read2_b32 v[22:23], v30 offset0:85 offset1:93
	v_cvt_pk_bf16_f32 v8, v14, v12
	s_waitcnt lgkmcnt(3)
; #define LAS __attribute__((address_space(3)))
; #define LDS_WAIT() asm volatile("s_waitcnt lgkmcnt(0)" ::: "memory")
; __device__ __forceinline__ unsigned pk2(float lo, float hi) { return f2bf(lo) | (f2bf(hi) << 16); }
;     ...
;         for (int j = 0; j < 8; ++j) { const int n = (lane >> 3) + 8 * j; const LAS float* sp = scr + (8 * c8) * 65 + n;
;             v4u o; o.x = pk2(sp[0 * 65], sp[1 * 65]); o.y = pk2(sp[2 * 65], sp[3 * 65]); o.z = pk2(sp[4 * 65], sp[5 * 65]); o.w = pk2(sp[6 * 65], sp[7 * 65]);
;             *(v4u*)(WT + (size_t)(d0 + n) * K + k0 + 8 * c8) = o; }
;         LDS_WAIT(); asm volatile("" ::: "memory");
	s_nop 1
	s_waitcnt lgkmcnt(2)
	s_nop 0
	ds_read2_b32 v[24:25], v30 offset0:150 offset1:158
	s_nop 1
	ds_read2_b32 v[26:27], v30 offset0:215 offset1:223
	v_cvt_pk_bf16_f32 v9, v16, v18
	s_waitcnt lgkmcnt(3)
	s_nop 1
	s_waitcnt lgkmcnt(2)
	s_nop 2
	v_cvt_pk_bf16_f32 v10, v20, v22
	s_waitcnt lgkmcnt(1)
	s_nop 0
	v_add_u32_e32 v28, 16, v6
	s_nop 0
	s_waitcnt lgkmcnt(0)
	s_nop 0
	v_ashrrev_i32_e32 v29, 31, v28
	s_nop 1
	v_lshlrev_b64 v[28:29], 10, v[28:29]
	v_cvt_pk_bf16_f32 v11, v24, v26
	v_lshl_add_u64 v[28:29], v[4:5], 0, v[28:29]
	v_bfe_u32 v7, v15, 16, 1
	global_store_dwordx4 v[28:29], v[8:11], off
	v_add3_u32 v7, v15, v7, s15
	v_lshrrev_b32_e32 v7, 16, v7
	v_bfe_u32 v8, v13, 16, 1
	v_add3_u32 v8, v13, v8, s15
	v_and_or_b32 v8, v8, s16, v7
	s_nop 4
	v_cvt_pk_bf16_f32 v9, v17, v19
	s_nop 4
	v_cvt_pk_bf16_f32 v10, v21, v23
	s_nop 0
	v_add_u32_e32 v12, 24, v6
	s_nop 1
	v_ashrrev_i32_e32 v13, 31, v12
	s_nop 1
	v_lshlrev_b64 v[12:13], 10, v[12:13]
	v_cvt_pk_bf16_f32 v11, v25, v27
	ds_read2_b32 v[14:15], v78 offset0:32 offset1:40
	v_lshl_add_u64 v[12:13], v[4:5], 0, v[12:13]
	global_store_dwordx4 v[12:13], v[8:11], off
	ds_read2_b32 v[12:13], v78 offset0:97 offset1:105
	ds_read2_b32 v[16:17], v78 offset0:162 offset1:170
	ds_read2_b32 v[18:19], v78 offset0:227 offset1:235
	s_waitcnt lgkmcnt(3)
	s_nop 1
	s_waitcnt lgkmcnt(2)
	s_nop 0
	ds_read2_b32 v[20:21], v30 offset0:36 offset1:44
	s_nop 1
	ds_read2_b32 v[22:23], v30 offset0:101 offset1:109
	v_cvt_pk_bf16_f32 v8, v14, v12
	s_waitcnt lgkmcnt(3)
	s_nop 1
	s_waitcnt lgkmcnt(2)
	s_nop 0
	ds_read2_b32 v[24:25], v30 offset0:166 offset1:174
	s_nop 1
	ds_read2_b32 v[26:27], v30 offset0:231 offset1:239
	v_cvt_pk_bf16_f32 v9, v16, v18
	s_waitcnt lgkmcnt(3)
	s_nop 1
	s_waitcnt lgkmcnt(2)
	s_nop 2
	v_cvt_pk_bf16_f32 v10, v20, v22
	s_waitcnt lgkmcnt(1)
	s_nop 0
	v_add_u32_e32 v28, 32, v6
	s_nop 0
	s_waitcnt lgkmcnt(0)
	s_nop 0
	v_ashrrev_i32_e32 v29, 31, v28
	s_nop 1
	v_lshlrev_b64 v[28:29], 10, v[28:29]
	v_cvt_pk_bf16_f32 v11, v24, v26
	v_lshl_add_u64 v[28:29], v[4:5], 0, v[28:29]
	v_bfe_u32 v7, v15, 16, 1
	global_store_dwordx4 v[28:29], v[8:11], off
	v_add3_u32 v7, v15, v7, s15
	v_lshrrev_b32_e32 v7, 16, v7
	v_bfe_u32 v8, v13, 16, 1
	v_add3_u32 v8, v13, v8, s15
	v_and_or_b32 v8, v8, s16, v7
	s_nop 4
	v_cvt_pk_bf16_f32 v9, v17, v19
	s_nop 4
	v_cvt_pk_bf16_f32 v10, v21, v23
	s_nop 0
	v_add_u32_e32 v12, 40, v6
	s_nop 1
	v_ashrrev_i32_e32 v13, 31, v12
	s_nop 1
	v_lshlrev_b64 v[12:13], 10, v[12:13]
	v_cvt_pk_bf16_f32 v11, v25, v27
	ds_read2_b32 v[14:15], v78 offset0:48 offset1:56
	v_lshl_add_u64 v[12:13], v[4:5], 0, v[12:13]
	global_store_dwordx4 v[12:13], v[8:11], off
	ds_read2_b32 v[12:13], v78 offset0:113 offset1:121
	ds_read2_b32 v[16:17], v78 offset0:178 offset1:186
	ds_read2_b32 v[18:19], v78 offset0:243 offset1:251
	s_waitcnt lgkmcnt(3)
	s_nop 1
	s_waitcnt lgkmcnt(2)
	s_nop 0
	ds_read2_b32 v[20:21], v30 offset0:52 offset1:60
	s_nop 1
	ds_read2_b32 v[22:23], v30 offset0:117 offset1:125
	v_cvt_pk_bf16_f32 v8, v14, v12
	s_waitcnt lgkmcnt(3)
	s_nop 1
	s_waitcnt lgkmcnt(2)
	s_nop 0
	ds_read2_b32 v[24:25], v30 offset0:182 offset1:190
	s_nop 1
	ds_read2_b32 v[26:27], v30 offset0:247 offset1:255
	v_cvt_pk_bf16_f32 v9, v16, v18
	s_waitcnt lgkmcnt(3)
	s_nop 1
	s_waitcnt lgkmcnt(2)
	s_nop 2
	v_cvt_pk_bf16_f32 v10, v20, v22
	s_waitcnt lgkmcnt(1)
	s_nop 0
	v_add_u32_e32 v28, 48, v6
	s_nop 0
	s_waitcnt lgkmcnt(0)
	s_nop 0
	v_ashrrev_i32_e32 v29, 31, v28
	s_nop 1
	v_lshlrev_b64 v[28:29], 10, v[28:29]
	v_cvt_pk_bf16_f32 v11, v24, v26
	v_lshl_add_u64 v[28:29], v[4:5], 0, v[28:29]
	v_bfe_u32 v7, v15, 16, 1
	global_store_dwordx4 v[28:29], v[8:11], off
	v_add3_u32 v7, v15, v7, s15
	v_lshrrev_b32_e32 v7, 16, v7
	v_bfe_u32 v8, v13, 16, 1
	v_add3_u32 v8, v13, v8, s15
	v_and_or_b32 v8, v8, s16, v7
	s_nop 4
	v_cvt_pk_bf16_f32 v9, v17, v19
	s_nop 4
	v_cvt_pk_bf16_f32 v10, v21, v23
	s_nop 4
	v_add_u32_e32 v6, 56, v6
	v_cvt_pk_bf16_f32 v11, v25, v27
	v_ashrrev_i32_e32 v7, 31, v6
	v_lshlrev_b64 v[6:7], 10, v[6:7]
	v_lshl_add_u64 v[4:5], v[4:5], 0, v[6:7]
	global_store_dwordx4 v[4:5], v[8:11], off
	s_waitcnt lgkmcnt(0)
	s_add_i32 s11, s11, s86
	s_add_i32 s12, s12, s13
	s_cmpk_lt_i32 s11, 0x100
	s_cbranch_scc0 .LBB0_4679

; #define LAS __attribute__((address_space(3)))
; #define LDS_WAIT() asm volatile("s_waitcnt lgkmcnt(0)" ::: "memory")
;     ...
;         if (gain) {
; #pragma unroll
;             for (int i = 0; i < 16; ++i) v[i] *= gain[k0 + 4 * i + kr]; }
; #pragma unroll
;         for (int i = 0; i < 16; ++i) { LAS float* d = scr + (4 * i + kr) * 65 + nq; d[0] = v[i].x; d[1] = v[i].y; d[2] = v[i].z; d[3] = v[i].w; }
;         LDS_WAIT(); asm volatile("" ::: "memory");
;         const int c8 = lane & 7; int d0 = n0;
;         if (ffnmap) { const int bj = n0 >= FFH ? 1 : 0, chn = n0 - FFH * bj; d0 = 256 * (chn >> 7) + 128 * bj + (chn & 127); }
.LBB0_4740:
	s_or_b64 exec, exec, s[10:11]
	v_ashrrev_i32_e32 v73, 31, v72
	v_lshl_add_u64 v[72:73], v[72:73], 2, s[0:1]
	global_load_dword v74, v[72:73], off
	global_load_dword v90, v[72:73], off offset:16
	global_load_dword v92, v[72:73], off offset:32
	global_load_dword v94, v[72:73], off offset:48
	global_load_dword v96, v[72:73], off offset:64
	global_load_dword v98, v[72:73], off offset:80
	global_load_dword v100, v[72:73], off offset:96
	global_load_dword v102, v[72:73], off offset:112
	global_load_dword v104, v[72:73], off offset:128
	global_load_dword v106, v[72:73], off offset:144
	global_load_dword v108, v[72:73], off offset:160
	global_load_dword v110, v[72:73], off offset:176
	global_load_dword v112, v[72:73], off offset:192
	global_load_dword v114, v[72:73], off offset:208
	s_nop 0
	global_load_dword v72, v[72:73], off offset:224
	v_lshl_add_u64 v[76:77], v[76:77], 2, s[0:1]
	global_load_dword v76, v[76:77], off
	v_add_u32_e32 v75, 0x418, v88
	v_add_u32_e32 v91, 0xc30, v88
	v_add_u32_e32 v93, 0xc38, v88
	v_add_u32_e32 v95, 0x1040, v88
	s_waitcnt vmcnt(0)
	v_add_u32_e32 v97, 0x1048, v88
	v_add_u32_e32 v99, 0x1450, v88
	v_add_u32_e32 v101, 0x1458, v88
	v_add_u32_e32 v103, 0x1860, v88
	v_add_u32_e32 v105, 0x1868, v88
	v_add_u32_e32 v73, 0x410, v88
	v_add_u32_e32 v77, 0x820, v88
	v_add_u32_e32 v89, 0x828, v88
	v_add_u32_e32 v107, 0x1c70, v88
	v_add_u32_e32 v109, 0x1c78, v88
	v_add_u32_e32 v111, 0x2080, v88
	s_mulk_i32 s26, 0xff50
	s_add_i32 s9, s25, s26
	s_cmpk_gt_i32 s9, 0x57
	s_cselect_b32 s9, 0xffffea00, 0
	s_cselect_b32 s10, 0x80, 0
	s_add_i32 s9, s9, s19
	s_add_i32 s9, s9, s7
	s_lshl_b32 s7, s9, 1
	s_and_b32 s8, s8, 64
	s_and_b32 s7, s7, 0xffffff00
	s_or_b32 s8, s8, s10
	s_or_b32 s8, s8, s7
	s_ashr_i32 s7, s6, 31
	s_add_i32 s25, s25, s17
	s_add_i32 s19, s19, s20
	s_cmpk_lt_i32 s25, 0x1600
	v_pk_mul_f32 v[4:5], v[4:5], v[74:75] op_sel_hi:[1,0]
	v_pk_mul_f32 v[6:7], v[6:7], v[74:75] op_sel_hi:[1,0]
	v_pk_mul_f32 v[14:15], v[14:15], v[90:91] op_sel_hi:[1,0]
	v_pk_mul_f32 v[12:13], v[12:13], v[90:91] op_sel_hi:[1,0]
	v_pk_mul_f32 v[10:11], v[10:11], v[92:93] op_sel_hi:[1,0]
	v_pk_mul_f32 v[8:9], v[8:9], v[92:93] op_sel_hi:[1,0]
	v_pk_mul_f32 v[22:23], v[22:23], v[94:95] op_sel_hi:[1,0]
	v_pk_mul_f32 v[20:21], v[20:21], v[94:95] op_sel_hi:[1,0]
	v_pk_mul_f32 v[18:19], v[18:19], v[96:97] op_sel_hi:[1,0]
	v_pk_mul_f32 v[16:17], v[16:17], v[96:97] op_sel_hi:[1,0]
	v_pk_mul_f32 v[30:31], v[30:31], v[98:99] op_sel_hi:[1,0]
	v_pk_mul_f32 v[28:29], v[28:29], v[98:99] op_sel_hi:[1,0]
	v_pk_mul_f32 v[26:27], v[26:27], v[100:101] op_sel_hi:[1,0]
	v_pk_mul_f32 v[24:25], v[24:25], v[100:101] op_sel_hi:[1,0]
	v_pk_mul_f32 v[38:39], v[38:39], v[102:103] op_sel_hi:[1,0]
	v_pk_mul_f32 v[36:37], v[36:37], v[102:103] op_sel_hi:[1,0]
	v_pk_mul_f32 v[34:35], v[34:35], v[104:105] op_sel_hi:[1,0]
	v_pk_mul_f32 v[32:33], v[32:33], v[104:105] op_sel_hi:[1,0]
	ds_write2_b32 v88, v4, v5 offset1:1
	ds_write2_b32 v88, v6, v7 offset0:2 offset1:3
	ds_write2_b32 v73, v12, v13 offset1:1
	ds_write2_b32 v75, v14, v15 offset1:1
	ds_write2_b32 v77, v8, v9 offset1:1
	ds_write2_b32 v89, v10, v11 offset1:1
	ds_write2_b32 v91, v20, v21 offset1:1
	ds_write2_b32 v93, v22, v23 offset1:1
	ds_write2_b32 v95, v16, v17 offset1:1
	ds_write2_b32 v97, v18, v19 offset1:1
	ds_write2_b32 v99, v28, v29 offset1:1
	ds_write2_b32 v101, v30, v31 offset1:1
	ds_write2_b32 v103, v24, v25 offset1:1
	ds_write2_b32 v105, v26, v27 offset1:1
	ds_write2_b32 v107, v36, v37 offset1:1
	ds_write2_b32 v109, v38, v39 offset1:1
	ds_write2_b32 v111, v32, v33 offset1:1
	v_add_u32_e32 v4, 0x2088, v88
	v_pk_mul_f32 v[44:45], v[44:45], v[106:107] op_sel_hi:[1,0]
	ds_write2_b32 v4, v34, v35 offset1:1
	v_add_u32_e32 v4, 0x2490, v88
	v_pk_mul_f32 v[46:47], v[46:47], v[106:107] op_sel_hi:[1,0]
	ds_write2_b32 v4, v44, v45 offset1:1
	v_add_u32_e32 v4, 0x2498, v88
	v_pk_mul_f32 v[40:41], v[40:41], v[108:109] op_sel_hi:[1,0]
	ds_write2_b32 v4, v46, v47 offset1:1
	v_add_u32_e32 v4, 0x28a0, v88
	v_pk_mul_f32 v[42:43], v[42:43], v[108:109] op_sel_hi:[1,0]
	ds_write2_b32 v4, v40, v41 offset1:1
	v_add_u32_e32 v4, 0x28a8, v88
	v_pk_mul_f32 v[52:53], v[52:53], v[110:111] op_sel_hi:[1,0]
	ds_write2_b32 v4, v42, v43 offset1:1
	v_add_u32_e32 v4, 0x2cb0, v88
	v_pk_mul_f32 v[54:55], v[54:55], v[110:111] op_sel_hi:[1,0]
	ds_write2_b32 v4, v52, v53 offset1:1
	v_add_u32_e32 v4, 0x2cb8, v88
	v_pk_mul_f32 v[48:49], v[48:49], v[112:113] op_sel_hi:[1,0]
	ds_write2_b32 v4, v54, v55 offset1:1
	v_add_u32_e32 v4, 0x30c0, v88
	v_pk_mul_f32 v[50:51], v[50:51], v[112:113] op_sel_hi:[1,0]
	ds_write2_b32 v4, v48, v49 offset1:1
	v_add_u32_e32 v4, 0x30c8, v88
	v_pk_mul_f32 v[60:61], v[60:61], v[114:115] op_sel_hi:[1,0]
	ds_write2_b32 v4, v50, v51 offset1:1
	v_add_u32_e32 v4, 0x34d0, v88
	v_pk_mul_f32 v[62:63], v[62:63], v[114:115] op_sel_hi:[1,0]
	ds_write2_b32 v4, v60, v61 offset1:1
	v_add_u32_e32 v4, 0x34d8, v88
	v_pk_mul_f32 v[56:57], v[56:57], v[72:73] op_sel_hi:[1,0]
	ds_write2_b32 v4, v62, v63 offset1:1
	v_add_u32_e32 v4, 0x38e0, v88
	v_pk_mul_f32 v[58:59], v[58:59], v[72:73] op_sel_hi:[1,0]
	ds_write2_b32 v4, v56, v57 offset1:1
	v_add_u32_e32 v4, 0x38e8, v88
	v_pk_mul_f32 v[64:65], v[64:65], v[76:77] op_sel_hi:[1,0]
	ds_write2_b32 v4, v58, v59 offset1:1
	v_add_u32_e32 v4, 0x3cf0, v88
	v_pk_mul_f32 v[66:67], v[66:67], v[76:77] op_sel_hi:[1,0]
	ds_write2_b32 v4, v64, v65 offset1:1
	v_add_u32_e32 v4, 0x3cf8, v88
	ds_write2_b32 v4, v66, v67 offset1:1
	s_waitcnt lgkmcnt(0)
; #define LAS __attribute__((address_space(3)))
; #define LDS_WAIT() asm volatile("s_waitcnt lgkmcnt(0)" ::: "memory")
; __device__ __forceinline__ unsigned pk2(float lo, float hi) { return f2bf(lo) | (f2bf(hi) << 16); }
;     ...
;         const int c8 = lane & 7; int d0 = n0;
;         if (ffnmap) { const int bj = n0 >= FFH ? 1 : 0, chn = n0 - FFH * bj; d0 = 256 * (chn >> 7) + 128 * bj + (chn & 127); }
; #pragma unroll
;         for (int j = 0; j < 8; ++j) { const int n = (lane >> 3) + 8 * j; const LAS float* sp = scr + (8 * c8) * 65 + n;
;             v4u o; o.x = pk2(sp[0 * 65], sp[1 * 65]); o.y = pk2(sp[2 * 65], sp[3 * 65]); o.z = pk2(sp[4 * 65], sp[5 * 65]); o.w = pk2(sp[6 * 65], sp[7 * 65]);
;             *(v4u*)(WT + (size_t)(d0 + n) * K + k0 + 8 * c8) = o; }
;         LDS_WAIT(); asm volatile("" ::: "memory");
	ds_read2_b32 v[10:11], v80 offset1:8
	ds_read2_b32 v[12:13], v80 offset0:65 offset1:73
	ds_read2_b32 v[14:15], v80 offset0:130 offset1:138
	ds_read2_b32 v[16:17], v80 offset0:195 offset1:203
	v_add_u32_e32 v28, 0x400, v80
	s_waitcnt lgkmcnt(3)
	s_nop 1
	s_waitcnt lgkmcnt(2)
	s_nop 0
	ds_read2_b32 v[18:19], v28 offset0:4 offset1:12
	s_nop 1
	ds_read2_b32 v[20:21], v28 offset0:69 offset1:77
	v_cvt_pk_bf16_f32 v6, v10, v12
	s_waitcnt lgkmcnt(3)
	s_nop 1
	s_waitcnt lgkmcnt(2)
	s_nop 0
	ds_read2_b32 v[22:23], v28 offset0:134 offset1:142
	s_nop 1
	ds_read2_b32 v[24:25], v28 offset0:199 offset1:207
	v_cvt_pk_bf16_f32 v7, v14, v16
	s_waitcnt lgkmcnt(3)
	s_nop 1
	s_waitcnt lgkmcnt(2)
	s_nop 2
	v_cvt_pk_bf16_f32 v8, v18, v20
	s_waitcnt lgkmcnt(1)
	s_nop 0
	v_or_b32_e32 v26, s8, v78
	s_nop 0
	s_waitcnt lgkmcnt(0)
	s_nop 0
	v_ashrrev_i32_e32 v27, 31, v26
	v_lshl_add_u64 v[4:5], s[6:7], 1, v[70:71]
	s_nop 1
	v_lshlrev_b64 v[26:27], 12, v[26:27]
	v_cvt_pk_bf16_f32 v9, v22, v24
	v_lshl_add_u64 v[26:27], v[4:5], 0, v[26:27]
	global_store_dwordx4 v[26:27], v[6:9], off
	s_nop 6
	v_cvt_pk_bf16_f32 v6, v11, v13
	s_nop 4
	v_cvt_pk_bf16_f32 v7, v15, v17
	s_nop 4
	v_cvt_pk_bf16_f32 v8, v19, v21
	s_nop 2
	v_cvt_pk_bf16_f32 v9, v23, v25
	v_or_b32_e32 v10, s8, v81
	v_ashrrev_i32_e32 v11, 31, v10
	v_lshlrev_b64 v[10:11], 12, v[10:11]
	ds_read2_b32 v[12:13], v80 offset0:16 offset1:24
	v_lshl_add_u64 v[10:11], v[4:5], 0, v[10:11]
	global_store_dwordx4 v[10:11], v[6:9], off
	ds_read2_b32 v[10:11], v80 offset0:81 offset1:89
	ds_read2_b32 v[14:15], v80 offset0:146 offset1:154
	ds_read2_b32 v[16:17], v80 offset0:211 offset1:219
	s_waitcnt lgkmcnt(3)
	s_nop 1
	s_waitcnt lgkmcnt(2)
	s_nop 0
	ds_read2_b32 v[18:19], v28 offset0:20 offset1:28
	s_nop 1
	ds_read2_b32 v[20:21], v28 offset0:85 offset1:93
	v_cvt_pk_bf16_f32 v6, v12, v10
	s_waitcnt lgkmcnt(3)
	s_nop 1
	s_waitcnt lgkmcnt(2)
	s_nop 0
	ds_read2_b32 v[22:23], v28 offset0:150 offset1:158
	s_nop 1
	ds_read2_b32 v[24:25], v28 offset0:215 offset1:223
	v_cvt_pk_bf16_f32 v7, v14, v16
	s_waitcnt lgkmcnt(3)
	s_nop 1
	s_waitcnt lgkmcnt(2)
	s_nop 2
	v_cvt_pk_bf16_f32 v8, v18, v20
	s_waitcnt lgkmcnt(1)
	s_nop 0
	v_or_b32_e32 v26, s8, v82
	s_nop 0
	s_waitcnt lgkmcnt(0)
	s_nop 0
	v_ashrrev_i32_e32 v27, 31, v26
	s_nop 1
	v_lshlrev_b64 v[26:27], 12, v[26:27]
	v_cvt_pk_bf16_f32 v9, v22, v24
	v_lshl_add_u64 v[26:27], v[4:5], 0, v[26:27]
	global_store_dwordx4 v[26:27], v[6:9], off
	s_nop 6
	v_cvt_pk_bf16_f32 v6, v13, v11
	s_nop 4
	v_cvt_pk_bf16_f32 v7, v15, v17
	s_nop 4
	v_cvt_pk_bf16_f32 v8, v19, v21
	s_nop 2
	v_cvt_pk_bf16_f32 v9, v23, v25
	v_or_b32_e32 v10, s8, v83
	v_ashrrev_i32_e32 v11, 31, v10
	v_lshlrev_b64 v[10:11], 12, v[10:11]
	ds_read2_b32 v[12:13], v80 offset0:32 offset1:40
	v_lshl_add_u64 v[10:11], v[4:5], 0, v[10:11]
	global_store_dwordx4 v[10:11], v[6:9], off
	ds_read2_b32 v[10:11], v80 offset0:97 offset1:105
	ds_read2_b32 v[14:15], v80 offset0:162 offset1:170
	ds_read2_b32 v[16:17], v80 offset0:227 offset1:235
	s_waitcnt lgkmcnt(3)
	s_nop 1
	s_waitcnt lgkmcnt(2)
	s_nop 0
	ds_read2_b32 v[18:19], v28 offset0:36 offset1:44
	s_nop 1
	ds_read2_b32 v[20:21], v28 offset0:101 offset1:109
	v_cvt_pk_bf16_f32 v6, v12, v10
	s_waitcnt lgkmcnt(3)
	s_nop 1
	s_waitcnt lgkmcnt(2)
	s_nop 0
	ds_read2_b32 v[22:23], v28 offset0:166 offset1:174
	s_nop 1
	ds_read2_b32 v[24:25], v28 offset0:231 offset1:239
	v_cvt_pk_bf16_f32 v7, v14, v16
	s_waitcnt lgkmcnt(3)
	s_nop 1
	s_waitcnt lgkmcnt(2)
	s_nop 2
	v_cvt_pk_bf16_f32 v8, v18, v20
	s_waitcnt lgkmcnt(1)
	s_nop 0
	v_or_b32_e32 v26, s8, v84
	s_nop 0
	s_waitcnt lgkmcnt(0)
	s_nop 0
	v_ashrrev_i32_e32 v27, 31, v26
	s_nop 1
	v_lshlrev_b64 v[26:27], 12, v[26:27]
	v_cvt_pk_bf16_f32 v9, v22, v24
	v_lshl_add_u64 v[26:27], v[4:5], 0, v[26:27]
	global_store_dwordx4 v[26:27], v[6:9], off
	s_nop 6
	v_cvt_pk_bf16_f32 v6, v13, v11
	s_nop 4
	v_cvt_pk_bf16_f32 v7, v15, v17
	s_nop 4
	v_cvt_pk_bf16_f32 v8, v19, v21
	s_nop 2
	v_cvt_pk_bf16_f32 v9, v23, v25
	v_or_b32_e32 v10, s8, v85
	v_ashrrev_i32_e32 v11, 31, v10
	v_lshlrev_b64 v[10:11], 12, v[10:11]
	ds_read2_b32 v[12:13], v80 offset0:48 offset1:56
	v_lshl_add_u64 v[10:11], v[4:5], 0, v[10:11]
	global_store_dwordx4 v[10:11], v[6:9], off
	ds_read2_b32 v[10:11], v80 offset0:113 offset1:121
	ds_read2_b32 v[14:15], v80 offset0:178 offset1:186
	ds_read2_b32 v[16:17], v80 offset0:243 offset1:251
	s_waitcnt lgkmcnt(3)
	s_nop 1
	s_waitcnt lgkmcnt(2)
	s_nop 0
	ds_read2_b32 v[18:19], v28 offset0:52 offset1:60
	s_nop 1
	ds_read2_b32 v[20:21], v28 offset0:117 offset1:125
	v_cvt_pk_bf16_f32 v6, v12, v10
	s_waitcnt lgkmcnt(3)
	s_nop 1
	s_waitcnt lgkmcnt(2)
	s_nop 0
	ds_read2_b32 v[22:23], v28 offset0:182 offset1:190
	s_nop 1
	ds_read2_b32 v[24:25], v28 offset0:247 offset1:255
	v_cvt_pk_bf16_f32 v7, v14, v16
	s_waitcnt lgkmcnt(3)
	s_nop 1
	s_waitcnt lgkmcnt(2)
	s_nop 2
	v_cvt_pk_bf16_f32 v8, v18, v20
	s_waitcnt lgkmcnt(1)
	s_nop 0
	v_or_b32_e32 v26, s8, v86
	s_nop 0
	s_waitcnt lgkmcnt(0)
	s_nop 0
	v_ashrrev_i32_e32 v27, 31, v26
	s_nop 1
	v_lshlrev_b64 v[26:27], 12, v[26:27]
	v_cvt_pk_bf16_f32 v9, v22, v24
	v_lshl_add_u64 v[26:27], v[4:5], 0, v[26:27]
	global_store_dwordx4 v[26:27], v[6:9], off
	s_nop 6
	v_cvt_pk_bf16_f32 v6, v13, v11
	s_nop 4
	v_cvt_pk_bf16_f32 v7, v15, v17
	s_nop 4
	v_cvt_pk_bf16_f32 v8, v19, v21
	s_nop 2
	v_cvt_pk_bf16_f32 v9, v23, v25
	v_or_b32_e32 v10, s8, v87
	v_ashrrev_i32_e32 v11, 31, v10
	v_lshlrev_b64 v[10:11], 12, v[10:11]
	v_lshl_add_u64 v[4:5], v[4:5], 0, v[10:11]
	global_store_dwordx4 v[4:5], v[6:9], off
	s_waitcnt lgkmcnt(0)
	s_cbranch_scc0 .LBB0_4773

; #define LAS __attribute__((address_space(3)))
; #define LDS_WAIT() asm volatile("s_waitcnt lgkmcnt(0)" ::: "memory")
; __device__ __forceinline__ unsigned pk2(float lo, float hi) { return f2bf(lo) | (f2bf(hi) << 16); }
;     ...
;         for (int i = 0; i < 16; ++i) { LAS float* d = scr + (4 * i + kr) * 65 + nq; d[0] = v[i].x; d[1] = v[i].y; d[2] = v[i].z; d[3] = v[i].w; }
;         LDS_WAIT(); asm volatile("" ::: "memory");
;         const int c8 = lane & 7; int d0 = n0;
;         if (ffnmap) { const int bj = n0 >= FFH ? 1 : 0, chn = n0 - FFH * bj; d0 = 256 * (chn >> 7) + 128 * bj + (chn & 127); }
; #pragma unroll
;         for (int j = 0; j < 8; ++j) { const int n = (lane >> 3) + 8 * j; const LAS float* sp = scr + (8 * c8) * 65 + n;
;             v4u o; o.x = pk2(sp[0 * 65], sp[1 * 65]); o.y = pk2(sp[2 * 65], sp[3 * 65]); o.z = pk2(sp[4 * 65], sp[5 * 65]); o.w = pk2(sp[6 * 65], sp[7 * 65]);
;             *(v4u*)(WT + (size_t)(d0 + n) * K + k0 + 8 * c8) = o; }
.LBB0_4775:
	s_or_b64 exec, exec, s[6:7]
	s_waitcnt vmcnt(0)
	ds_write2_b32 v79, v4, v5 offset1:1
	ds_write2_b32 v79, v6, v7 offset0:2 offset1:3
	v_add_u32_e32 v4, 0x410, v79
	ds_write2_b32 v4, v12, v13 offset1:1
	v_add_u32_e32 v4, 0x418, v79
	ds_write2_b32 v4, v14, v15 offset1:1
	v_add_u32_e32 v4, 0x820, v79
	ds_write2_b32 v4, v8, v9 offset1:1
	v_add_u32_e32 v4, 0x828, v79
	ds_write2_b32 v4, v10, v11 offset1:1
	v_add_u32_e32 v4, 0xc30, v79
	ds_write2_b32 v4, v20, v21 offset1:1
	v_add_u32_e32 v4, 0xc38, v79
	ds_write2_b32 v4, v22, v23 offset1:1
	v_add_u32_e32 v4, 0x1040, v79
	ds_write2_b32 v4, v16, v17 offset1:1
	v_add_u32_e32 v4, 0x1048, v79
	ds_write2_b32 v4, v18, v19 offset1:1
	v_add_u32_e32 v4, 0x1450, v79
	ds_write2_b32 v4, v28, v29 offset1:1
	v_add_u32_e32 v4, 0x1458, v79
	ds_write2_b32 v4, v30, v31 offset1:1
	v_add_u32_e32 v4, 0x1860, v79
	ds_write2_b32 v4, v24, v25 offset1:1
	v_add_u32_e32 v4, 0x1868, v79
	ds_write2_b32 v4, v26, v27 offset1:1
	v_add_u32_e32 v4, 0x1c70, v79
	ds_write2_b32 v4, v36, v37 offset1:1
	v_add_u32_e32 v4, 0x1c78, v79
	ds_write2_b32 v4, v38, v39 offset1:1
	v_add_u32_e32 v4, 0x2080, v79
	ds_write2_b32 v4, v32, v33 offset1:1
	v_add_u32_e32 v4, 0x2088, v79
	ds_write2_b32 v4, v34, v35 offset1:1
	v_add_u32_e32 v4, 0x2490, v79
	ds_write2_b32 v4, v44, v45 offset1:1
	v_add_u32_e32 v4, 0x2498, v79
	ds_write2_b32 v4, v46, v47 offset1:1
	v_add_u32_e32 v4, 0x28a0, v79
	ds_write2_b32 v4, v40, v41 offset1:1
	v_add_u32_e32 v4, 0x28a8, v79
	ds_write2_b32 v4, v42, v43 offset1:1
	v_add_u32_e32 v4, 0x2cb0, v79
	ds_write2_b32 v4, v52, v53 offset1:1
	v_add_u32_e32 v4, 0x2cb8, v79
	ds_write2_b32 v4, v54, v55 offset1:1
	v_add_u32_e32 v4, 0x30c0, v79
	ds_write2_b32 v4, v48, v49 offset1:1
	v_add_u32_e32 v4, 0x30c8, v79
	ds_write2_b32 v4, v50, v51 offset1:1
	v_add_u32_e32 v4, 0x34d0, v79
	ds_write2_b32 v4, v60, v61 offset1:1
	v_add_u32_e32 v4, 0x34d8, v79
	ds_write2_b32 v4, v62, v63 offset1:1
	v_add_u32_e32 v4, 0x38e0, v79
	ds_write2_b32 v4, v56, v57 offset1:1
	v_add_u32_e32 v4, 0x38e8, v79
	ds_write2_b32 v4, v58, v59 offset1:1
	v_add_u32_e32 v4, 0x3cf0, v79
	ds_write2_b32 v4, v64, v65 offset1:1
	v_add_u32_e32 v4, 0x3cf8, v79
	ds_write2_b32 v4, v66, v67 offset1:1
	s_waitcnt lgkmcnt(0)
	ds_read2_b32 v[12:13], v77 offset1:8
	ds_read2_b32 v[14:15], v77 offset0:65 offset1:73
	ds_read2_b32 v[16:17], v77 offset0:130 offset1:138
	ds_read2_b32 v[18:19], v77 offset0:195 offset1:203
	v_add_u32_e32 v30, 0x400, v77
	s_waitcnt lgkmcnt(3)
	s_nop 1
	s_waitcnt lgkmcnt(2)
	s_nop 0
	ds_read2_b32 v[20:21], v30 offset0:4 offset1:12
	s_nop 1
	ds_read2_b32 v[22:23], v30 offset0:69 offset1:77
	v_cvt_pk_bf16_f32 v8, v12, v14
	s_waitcnt lgkmcnt(3)
	s_nop 1
	s_waitcnt lgkmcnt(2)
	s_nop 0
	ds_read2_b32 v[24:25], v30 offset0:134 offset1:142
	s_nop 1
	ds_read2_b32 v[26:27], v30 offset0:199 offset1:207
	v_cvt_pk_bf16_f32 v9, v16, v18
	s_waitcnt lgkmcnt(3)
	s_nop 1
	s_waitcnt lgkmcnt(2)
	s_nop 2
	v_cvt_pk_bf16_f32 v10, v20, v22
	s_waitcnt lgkmcnt(1)
	s_nop 1
	s_waitcnt lgkmcnt(0)
	s_nop 2
	s_mul_i32 s20, s20, 0xfea00000
	s_ashr_i32 s1, s0, 31
	v_cvt_pk_bf16_f32 v11, v24, v26
	v_add_u32_e32 v6, s20, v78
	v_lshl_add_u64 v[4:5], s[0:1], 1, v[70:71]
	v_ashrrev_i32_e32 v7, 31, v6
	v_lshl_add_u64 v[28:29], v[4:5], 0, v[6:7]
	v_bfe_u32 v7, v13, 16, 1
	global_store_dwordx4 v[28:29], v[8:11], off
	v_add3_u32 v7, v13, v7, s18
	v_lshrrev_b32_e32 v7, 16, v7
	v_bfe_u32 v8, v15, 16, 1
	v_add3_u32 v8, v15, v8, s18
	v_and_or_b32 v8, v8, s19, v7
	s_nop 4
	v_cvt_pk_bf16_f32 v9, v17, v19
	s_nop 4
	v_cvt_pk_bf16_f32 v10, v21, v23
	s_nop 2
	v_add_u32_e32 v12, 0x16000, v6
	s_nop 1
	v_ashrrev_i32_e32 v13, 31, v12
	v_cvt_pk_bf16_f32 v11, v25, v27
	ds_read2_b32 v[14:15], v77 offset0:16 offset1:24
	v_lshl_add_u64 v[12:13], v[4:5], 0, v[12:13]
	global_store_dwordx4 v[12:13], v[8:11], off
	ds_read2_b32 v[12:13], v77 offset0:81 offset1:89
	ds_read2_b32 v[16:17], v77 offset0:146 offset1:154
	ds_read2_b32 v[18:19], v77 offset0:211 offset1:219
	s_waitcnt lgkmcnt(3)
	s_nop 1
	s_waitcnt lgkmcnt(2)
; #define LAS __attribute__((address_space(3)))
; #define LDS_WAIT() asm volatile("s_waitcnt lgkmcnt(0)" ::: "memory")
; __device__ __forceinline__ unsigned pk2(float lo, float hi) { return f2bf(lo) | (f2bf(hi) << 16); }
;     ...
;         for (int j = 0; j < 8; ++j) { const int n = (lane >> 3) + 8 * j; const LAS float* sp = scr + (8 * c8) * 65 + n;
;             v4u o; o.x = pk2(sp[0 * 65], sp[1 * 65]); o.y = pk2(sp[2 * 65], sp[3 * 65]); o.z = pk2(sp[4 * 65], sp[5 * 65]); o.w = pk2(sp[6 * 65], sp[7 * 65]);
;             *(v4u*)(WT + (size_t)(d0 + n) * K + k0 + 8 * c8) = o; }
;         LDS_WAIT(); asm volatile("" ::: "memory");
	s_nop 0
	ds_read2_b32 v[20:21], v30 offset0:20 offset1:28
	s_nop 1
	ds_read2_b32 v[22:23], v30 offset0:85 offset1:93
	v_cvt_pk_bf16_f32 v8, v14, v12
	s_waitcnt lgkmcnt(3)
	s_nop 1
	s_waitcnt lgkmcnt(2)
	s_nop 0
	ds_read2_b32 v[24:25], v30 offset0:150 offset1:158
	s_nop 1
	ds_read2_b32 v[26:27], v30 offset0:215 offset1:223
	v_cvt_pk_bf16_f32 v9, v16, v18
	s_waitcnt lgkmcnt(3)
	s_nop 1
	s_waitcnt lgkmcnt(2)
	s_nop 2
	v_cvt_pk_bf16_f32 v10, v20, v22
	s_waitcnt lgkmcnt(1)
	s_nop 1
	s_waitcnt lgkmcnt(0)
	s_nop 0
	v_add_u32_e32 v28, 0x2c000, v6
	s_nop 1
	v_ashrrev_i32_e32 v29, 31, v28
	v_cvt_pk_bf16_f32 v11, v24, v26
	v_lshl_add_u64 v[28:29], v[4:5], 0, v[28:29]
	v_bfe_u32 v7, v15, 16, 1
	global_store_dwordx4 v[28:29], v[8:11], off
	v_add3_u32 v7, v15, v7, s18
	v_lshrrev_b32_e32 v7, 16, v7
	v_bfe_u32 v8, v13, 16, 1
	v_add3_u32 v8, v13, v8, s18
	v_and_or_b32 v8, v8, s19, v7
	s_nop 4
	v_cvt_pk_bf16_f32 v9, v17, v19
	s_nop 4
	v_cvt_pk_bf16_f32 v10, v21, v23
	s_nop 2
	v_add_u32_e32 v12, 0x42000, v6
	s_nop 1
	v_ashrrev_i32_e32 v13, 31, v12
	v_cvt_pk_bf16_f32 v11, v25, v27
	ds_read2_b32 v[14:15], v77 offset0:32 offset1:40
	v_lshl_add_u64 v[12:13], v[4:5], 0, v[12:13]
	global_store_dwordx4 v[12:13], v[8:11], off
	ds_read2_b32 v[12:13], v77 offset0:97 offset1:105
	ds_read2_b32 v[16:17], v77 offset0:162 offset1:170
	ds_read2_b32 v[18:19], v77 offset0:227 offset1:235
	s_waitcnt lgkmcnt(3)
	s_nop 1
	s_waitcnt lgkmcnt(2)
	s_nop 0
	ds_read2_b32 v[20:21], v30 offset0:36 offset1:44
	s_nop 1
	ds_read2_b32 v[22:23], v30 offset0:101 offset1:109
	v_cvt_pk_bf16_f32 v8, v14, v12
	s_waitcnt lgkmcnt(3)
	s_nop 1
	s_waitcnt lgkmcnt(2)
	s_nop 0
	ds_read2_b32 v[24:25], v30 offset0:166 offset1:174
	s_nop 1
	ds_read2_b32 v[26:27], v30 offset0:231 offset1:239
	v_cvt_pk_bf16_f32 v9, v16, v18
	s_waitcnt lgkmcnt(3)
	s_nop 1
	s_waitcnt lgkmcnt(2)
	s_nop 2
	v_cvt_pk_bf16_f32 v10, v20, v22
	s_waitcnt lgkmcnt(1)
	s_nop 1
	s_waitcnt lgkmcnt(0)
	s_nop 0
	v_add_u32_e32 v28, 0x58000, v6
	s_nop 1
	v_ashrrev_i32_e32 v29, 31, v28
	v_cvt_pk_bf16_f32 v11, v24, v26
	v_lshl_add_u64 v[28:29], v[4:5], 0, v[28:29]
	v_bfe_u32 v7, v15, 16, 1
	global_store_dwordx4 v[28:29], v[8:11], off
	v_add3_u32 v7, v15, v7, s18
	v_lshrrev_b32_e32 v7, 16, v7
	v_bfe_u32 v8, v13, 16, 1
	v_add3_u32 v8, v13, v8, s18
	v_and_or_b32 v8, v8, s19, v7
	s_nop 4
	v_cvt_pk_bf16_f32 v9, v17, v19
	s_nop 4
	v_cvt_pk_bf16_f32 v10, v21, v23
	s_nop 2
	v_add_u32_e32 v12, 0x6e000, v6
	s_nop 1
	v_ashrrev_i32_e32 v13, 31, v12
	v_cvt_pk_bf16_f32 v11, v25, v27
	ds_read2_b32 v[14:15], v77 offset0:48 offset1:56
	v_lshl_add_u64 v[12:13], v[4:5], 0, v[12:13]
	global_store_dwordx4 v[12:13], v[8:11], off
	ds_read2_b32 v[12:13], v77 offset0:113 offset1:121
	ds_read2_b32 v[16:17], v77 offset0:178 offset1:186
	ds_read2_b32 v[18:19], v77 offset0:243 offset1:251
	s_waitcnt lgkmcnt(3)
	s_nop 1
	s_waitcnt lgkmcnt(2)
	s_nop 0
	ds_read2_b32 v[20:21], v30 offset0:52 offset1:60
	s_nop 1
	ds_read2_b32 v[22:23], v30 offset0:117 offset1:125
	v_cvt_pk_bf16_f32 v8, v14, v12
	s_waitcnt lgkmcnt(3)
	s_nop 1
	s_waitcnt lgkmcnt(2)
	s_nop 0
	ds_read2_b32 v[24:25], v30 offset0:182 offset1:190
	s_nop 1
	ds_read2_b32 v[26:27], v30 offset0:247 offset1:255
	v_cvt_pk_bf16_f32 v9, v16, v18
	s_waitcnt lgkmcnt(3)
	s_nop 1
	s_waitcnt lgkmcnt(2)
	s_nop 2
	v_cvt_pk_bf16_f32 v10, v20, v22
	s_waitcnt lgkmcnt(1)
	s_nop 1
	s_waitcnt lgkmcnt(0)
	s_nop 0
	v_add_u32_e32 v28, 0x84000, v6
	s_nop 1
	v_ashrrev_i32_e32 v29, 31, v28
	v_cvt_pk_bf16_f32 v11, v24, v26
	v_lshl_add_u64 v[28:29], v[4:5], 0, v[28:29]
	v_bfe_u32 v7, v15, 16, 1
	global_store_dwordx4 v[28:29], v[8:11], off
	v_add3_u32 v7, v15, v7, s18
	v_lshrrev_b32_e32 v7, 16, v7
	v_bfe_u32 v8, v13, 16, 1
	v_add3_u32 v8, v13, v8, s18
	v_and_or_b32 v8, v8, s19, v7
	s_nop 4
	v_cvt_pk_bf16_f32 v9, v17, v19
	s_nop 4
	v_cvt_pk_bf16_f32 v10, v21, v23
	s_nop 4
	v_add_u32_e32 v6, 0x9a000, v6
	v_cvt_pk_bf16_f32 v11, v25, v27
	v_ashrrev_i32_e32 v7, 31, v6
	v_lshl_add_u64 v[4:5], v[4:5], 0, v[6:7]
	global_store_dwordx4 v[4:5], v[8:11], off
	s_waitcnt lgkmcnt(0)
	s_add_i32 s16, s16, s17
	s_add_i32 s9, s9, s10
	s_cmpk_lt_i32 s16, 0xb00
	v_add_u32_e32 v78, s8, v78
	s_cbranch_scc0 .LBB0_4808

; __device__ __forceinline__ unsigned pk2(float lo, float hi) { return f2bf(lo) | (f2bf(hi) << 16); }
; template <int MODE, class MaskF> ...
;     ...
;     if constexpr (MODE == 0) { l[0] = OL[0][0] * 0.25f; l[1] = OL[1][0] * 0.25f; }
; __device__ __forceinline__ void xa_attn_fa(const Ctx& c, const bf16* Q, const bf16* KV, const bf16* XVT, bf16* Oo) {
;     ...
;         for (int mi = 0; mi < 2; ++mi) { float lt = l[mi]; lt += __shfl_xor(lt, 16); lt += __shfl_xor(lt, 32); const float il = 1.f / lt;
; #pragma unroll
;             for (int dt = 0; dt < 8; ++dt) { const f32x4 o = O[dt][mi] * il; v2u w; w.x = pk2(o[0], o[1]); w.y = pk2(o[2], o[3]);
;                 *(v2u*)(Oo + grow[mi] * 512 + hd * 128 + 16 * dt + 4 * lg) = w; } }
.LBB0_5374:
	v_mul_f32_e32 v2, 0x3e800000, v126
	ds_bpermute_b32 v2, v192, v2
	s_lshl_b32 s8, s21, 1
	v_lshl_add_u64 v[4:5], v[170:171], 0, s[8:9]
	v_lshl_add_u64 v[28:29], v[4:5], 0, v[186:187]
	v_mul_f32_e32 v50, 0x3e800000, v26
	s_waitcnt lgkmcnt(0)
	v_fmac_f32_e32 v2, 0x3e800000, v126
	ds_bpermute_b32 v27, v193, v2
	v_lshl_add_u64 v[4:5], v[4:5], 0, v[184:185]
	s_add_i32 s20, s20, s33
	s_cmpk_lt_i32 s20, 0x100
	s_waitcnt lgkmcnt(0)
	v_add_f32_e32 v2, v2, v27
	v_div_scale_f32 v27, s[10:11], v2, v2, 1.0
	v_rcp_f32_e32 v46, v27
	v_div_scale_f32 v47, vcc, 1.0, v2, 1.0
	v_fma_f32 v48, -v27, v46, 1.0
	v_fmac_f32_e32 v46, v48, v46
	v_mul_f32_e32 v48, v47, v46
	v_fma_f32 v49, -v27, v48, v47
	v_fmac_f32_e32 v48, v49, v46
	v_fma_f32 v27, -v27, v48, v47
	v_div_fmas_f32 v27, v27, v46, v48
	v_div_fixup_f32 v2, v27, v2, 1.0
	v_pk_mul_f32 v[48:49], v[118:119], v[2:3] op_sel_hi:[1,0]
	v_pk_mul_f32 v[46:47], v[120:121], v[2:3] op_sel_hi:[1,0]
	s_nop 4
	v_cvt_pk_bf16_f32 v48, v48, v49
	v_bfe_u32 v27, v46, 16, 1
	v_add3_u32 v27, v46, v27, s18
	v_bfe_u32 v46, v47, 16, 1
	v_lshrrev_b32_e32 v27, 16, v27
	v_add3_u32 v46, v47, v46, s18
	v_and_or_b32 v49, v46, s19, v27
	global_store_dwordx2 v[28:29], v[48:49], off
	v_pk_mul_f32 v[48:49], v[114:115], v[2:3] op_sel_hi:[1,0]
	v_pk_mul_f32 v[46:47], v[116:117], v[2:3] op_sel_hi:[1,0]
	v_bfe_u32 v27, v48, 16, 1
	v_add3_u32 v27, v48, v27, s18
	v_bfe_u32 v48, v49, 16, 1
	v_lshrrev_b32_e32 v27, 16, v27
	v_add3_u32 v48, v49, v48, s18
	v_and_or_b32 v48, v48, s19, v27
	v_bfe_u32 v27, v46, 16, 1
	v_add3_u32 v27, v46, v27, s18
	v_bfe_u32 v46, v47, 16, 1
	v_lshrrev_b32_e32 v27, 16, v27
	v_add3_u32 v46, v47, v46, s18
	v_and_or_b32 v49, v46, s19, v27
	global_store_dwordx2 v[28:29], v[48:49], off offset:32
	v_pk_mul_f32 v[48:49], v[110:111], v[2:3] op_sel_hi:[1,0]
	v_pk_mul_f32 v[46:47], v[112:113], v[2:3] op_sel_hi:[1,0]
	v_bfe_u32 v27, v48, 16, 1
	v_add3_u32 v27, v48, v27, s18
	v_bfe_u32 v48, v49, 16, 1
	v_lshrrev_b32_e32 v27, 16, v27
	v_add3_u32 v48, v49, v48, s18
	v_and_or_b32 v48, v48, s19, v27
	v_bfe_u32 v27, v46, 16, 1
	v_add3_u32 v27, v46, v27, s18
	v_bfe_u32 v46, v47, 16, 1
	v_lshrrev_b32_e32 v27, 16, v27
	v_add3_u32 v46, v47, v46, s18
	v_and_or_b32 v49, v46, s19, v27
	global_store_dwordx2 v[28:29], v[48:49], off offset:64
	v_pk_mul_f32 v[48:49], v[90:91], v[2:3] op_sel_hi:[1,0]
	v_pk_mul_f32 v[46:47], v[92:93], v[2:3] op_sel_hi:[1,0]
	v_bfe_u32 v27, v48, 16, 1
	v_add3_u32 v27, v48, v27, s18
	v_bfe_u32 v48, v49, 16, 1
	v_lshrrev_b32_e32 v27, 16, v27
	v_add3_u32 v48, v49, v48, s18
	v_and_or_b32 v48, v48, s19, v27
	v_bfe_u32 v27, v46, 16, 1
	v_add3_u32 v27, v46, v27, s18
	v_bfe_u32 v46, v47, 16, 1
	v_lshrrev_b32_e32 v27, 16, v27
	v_add3_u32 v46, v47, v46, s18
	v_and_or_b32 v49, v46, s19, v27
	global_store_dwordx2 v[28:29], v[48:49], off offset:96
	v_pk_mul_f32 v[48:49], v[86:87], v[2:3] op_sel_hi:[1,0]
	v_pk_mul_f32 v[46:47], v[88:89], v[2:3] op_sel_hi:[1,0]
	v_bfe_u32 v27, v48, 16, 1
	v_add3_u32 v27, v48, v27, s18
	v_bfe_u32 v48, v49, 16, 1
	v_lshrrev_b32_e32 v27, 16, v27
	v_add3_u32 v48, v49, v48, s18
	v_and_or_b32 v48, v48, s19, v27
	v_bfe_u32 v27, v46, 16, 1
	v_add3_u32 v27, v46, v27, s18
	v_bfe_u32 v46, v47, 16, 1
	v_lshrrev_b32_e32 v27, 16, v27
	v_add3_u32 v46, v47, v46, s18
	v_and_or_b32 v49, v46, s19, v27
	global_store_dwordx2 v[28:29], v[48:49], off offset:128
	v_pk_mul_f32 v[48:49], v[82:83], v[2:3] op_sel_hi:[1,0]
	v_pk_mul_f32 v[46:47], v[84:85], v[2:3] op_sel_hi:[1,0]
	v_bfe_u32 v27, v48, 16, 1
	v_add3_u32 v27, v48, v27, s18
	v_bfe_u32 v48, v49, 16, 1
	v_lshrrev_b32_e32 v27, 16, v27
	v_add3_u32 v48, v49, v48, s18
	v_and_or_b32 v48, v48, s19, v27
	v_bfe_u32 v27, v46, 16, 1
	v_add3_u32 v27, v46, v27, s18
	v_bfe_u32 v46, v47, 16, 1
	v_lshrrev_b32_e32 v27, 16, v27
	v_add3_u32 v46, v47, v46, s18
	v_and_or_b32 v49, v46, s19, v27
	global_store_dwordx2 v[28:29], v[48:49], off offset:160
	v_pk_mul_f32 v[48:49], v[62:63], v[2:3] op_sel_hi:[1,0]
	v_pk_mul_f32 v[46:47], v[64:65], v[2:3] op_sel_hi:[1,0]
	v_bfe_u32 v27, v48, 16, 1
	v_add3_u32 v27, v48, v27, s18
	v_bfe_u32 v48, v49, 16, 1
	v_lshrrev_b32_e32 v27, 16, v27
	v_add3_u32 v48, v49, v48, s18
	v_and_or_b32 v48, v48, s19, v27
	v_bfe_u32 v27, v46, 16, 1
	v_add3_u32 v27, v46, v27, s18
	v_bfe_u32 v46, v47, 16, 1
	v_lshrrev_b32_e32 v27, 16, v27
	v_add3_u32 v46, v47, v46, s18
	v_and_or_b32 v49, v46, s19, v27
	ds_bpermute_b32 v27, v192, v50
	v_pk_mul_f32 v[42:43], v[42:43], v[2:3] op_sel_hi:[1,0]
	v_pk_mul_f32 v[44:45], v[44:45], v[2:3] op_sel_hi:[1,0]
	v_bfe_u32 v2, v42, 16, 1
	v_add3_u32 v2, v42, v2, s18
	v_bfe_u32 v42, v43, 16, 1
	v_lshrrev_b32_e32 v2, 16, v2
	v_add3_u32 v42, v43, v42, s18
	s_waitcnt lgkmcnt(0)
; __device__ __forceinline__ unsigned pk2(float lo, float hi) { return f2bf(lo) | (f2bf(hi) << 16); }
; __device__ __forceinline__ void xa_attn_fa(const Ctx& c, const bf16* Q, const bf16* KV, const bf16* XVT, bf16* Oo) {
;     ...
;         for (int mi = 0; mi < 2; ++mi) { float lt = l[mi]; lt += __shfl_xor(lt, 16); lt += __shfl_xor(lt, 32); const float il = 1.f / lt;
; #pragma unroll
;             for (int dt = 0; dt < 8; ++dt) { const f32x4 o = O[dt][mi] * il; v2u w; w.x = pk2(o[0], o[1]); w.y = pk2(o[2], o[3]);
;                 *(v2u*)(Oo + grow[mi] * 512 + hd * 128 + 16 * dt + 4 * lg) = w; } }
	v_fmac_f32_e32 v27, 0x3e800000, v26
	v_and_or_b32 v42, v42, s19, v2
	ds_bpermute_b32 v2, v193, v27
	v_bfe_u32 v26, v44, 16, 1
	v_add3_u32 v26, v44, v26, s18
	v_bfe_u32 v43, v45, 16, 1
	v_lshrrev_b32_e32 v26, 16, v26
	s_waitcnt lgkmcnt(0)
	v_add_f32_e32 v2, v27, v2
	v_div_scale_f32 v27, s[10:11], v2, v2, 1.0
	v_rcp_f32_e32 v44, v27
	v_add3_u32 v43, v45, v43, s18
	v_and_or_b32 v43, v43, s19, v26
	global_store_dwordx2 v[28:29], v[48:49], off offset:192
	v_fma_f32 v26, -v27, v44, 1.0
	v_fmac_f32_e32 v44, v26, v44
	v_div_scale_f32 v26, vcc, 1.0, v2, 1.0
	global_store_dwordx2 v[28:29], v[42:43], off offset:224
	v_mul_f32_e32 v28, v26, v44
	v_fma_f32 v29, -v27, v28, v26
	v_fmac_f32_e32 v28, v29, v44
	v_fma_f32 v26, -v27, v28, v26
	v_div_fmas_f32 v26, v26, v44, v28
	v_div_fixup_f32 v2, v26, v2, 1.0
	v_pk_mul_f32 v[28:29], v[38:39], v[2:3] op_sel_hi:[1,0]
	v_pk_mul_f32 v[26:27], v[40:41], v[2:3] op_sel_hi:[1,0]
	s_nop 4
	v_cvt_pk_bf16_f32 v28, v28, v29
	s_nop 4
	v_cvt_pk_bf16_f32 v29, v26, v27
	global_store_dwordx2 v[4:5], v[28:29], off
	v_pk_mul_f32 v[28:29], v[34:35], v[2:3] op_sel_hi:[1,0]
	v_pk_mul_f32 v[26:27], v[36:37], v[2:3] op_sel_hi:[1,0]
	s_nop 4
	v_cvt_pk_bf16_f32 v28, v28, v29
	s_nop 4
	v_cvt_pk_bf16_f32 v29, v26, v27
	global_store_dwordx2 v[4:5], v[28:29], off offset:32
	v_pk_mul_f32 v[28:29], v[30:31], v[2:3] op_sel_hi:[1,0]
	v_pk_mul_f32 v[26:27], v[32:33], v[2:3] op_sel_hi:[1,0]
	s_nop 4
	v_cvt_pk_bf16_f32 v28, v28, v29
	s_nop 4
	v_pk_mul_f32 v[22:23], v[22:23], v[2:3] op_sel_hi:[1,0]
	v_cvt_pk_bf16_f32 v29, v26, v27
	s_nop 2
	v_pk_mul_f32 v[24:25], v[24:25], v[2:3] op_sel_hi:[1,0]
	s_nop 1
	v_cvt_pk_bf16_f32 v22, v22, v23
	v_bfe_u32 v23, v24, 16, 1
	v_add3_u32 v23, v24, v23, s18
	v_bfe_u32 v24, v25, 16, 1
	v_lshrrev_b32_e32 v23, 16, v23
	v_add3_u32 v24, v25, v24, s18
	v_and_or_b32 v23, v24, s19, v23
	v_pk_mul_f32 v[18:19], v[18:19], v[2:3] op_sel_hi:[1,0]
	global_store_dwordx2 v[4:5], v[22:23], off offset:96
	s_nop 2
	v_pk_mul_f32 v[20:21], v[20:21], v[2:3] op_sel_hi:[1,0]
	s_nop 1
	v_cvt_pk_bf16_f32 v18, v18, v19
	v_bfe_u32 v19, v20, 16, 1
	v_add3_u32 v19, v20, v19, s18
	v_bfe_u32 v20, v21, 16, 1
	v_lshrrev_b32_e32 v19, 16, v19
	v_add3_u32 v20, v21, v20, s18
	v_and_or_b32 v19, v20, s19, v19
	v_pk_mul_f32 v[14:15], v[14:15], v[2:3] op_sel_hi:[1,0]
	global_store_dwordx2 v[4:5], v[18:19], off offset:128
	s_nop 2
	v_pk_mul_f32 v[16:17], v[16:17], v[2:3] op_sel_hi:[1,0]
	s_nop 1
	v_cvt_pk_bf16_f32 v14, v14, v15
	v_bfe_u32 v15, v16, 16, 1
	v_add3_u32 v15, v16, v15, s18
	v_bfe_u32 v16, v17, 16, 1
	v_lshrrev_b32_e32 v15, 16, v15
	v_add3_u32 v16, v17, v16, s18
	v_and_or_b32 v15, v16, s19, v15
	v_pk_mul_f32 v[10:11], v[10:11], v[2:3] op_sel_hi:[1,0]
	v_pk_mul_f32 v[6:7], v[6:7], v[2:3] op_sel_hi:[1,0]
	global_store_dwordx2 v[4:5], v[14:15], off offset:160
	v_pk_mul_f32 v[12:13], v[12:13], v[2:3] op_sel_hi:[1,0]
	s_nop 0
	v_pk_mul_f32 v[8:9], v[8:9], v[2:3] op_sel_hi:[1,0]
	v_bfe_u32 v2, v6, 16, 1
	s_nop 1
	v_add3_u32 v2, v6, v2, s18
	v_bfe_u32 v6, v7, 16, 1
	s_nop 1
	v_lshrrev_b32_e32 v2, 16, v2
	v_add3_u32 v6, v7, v6, s18
	v_cvt_pk_bf16_f32 v10, v10, v11
	v_bfe_u32 v11, v12, 16, 1
	v_and_or_b32 v6, v6, s19, v2
	s_nop 0
	v_add3_u32 v11, v12, v11, s18
	v_bfe_u32 v12, v13, 16, 1
	s_nop 1
	v_lshrrev_b32_e32 v11, 16, v11
	v_add3_u32 v12, v13, v12, s18
	s_nop 1
	v_and_or_b32 v11, v12, s19, v11
	v_cvt_pk_bf16_f32 v7, v8, v9
	global_store_dwordx2 v[4:5], v[28:29], off offset:64
	global_store_dwordx2 v[4:5], v[10:11], off offset:192
	global_store_dwordx2 v[4:5], v[6:7], off offset:224
	s_cbranch_scc0 .LBB0_5386
